# load segments: the LDS-read wait moved from before the barrier to its first consumer (first MFMA after the barrier); on top of the v54 stack
# speedup vs baseline: 1.0133x; 1.0026x over previous
; #define PG8_STAGE(bufoff, gbase, voff) do { _Pragma("unroll") for (int _i = 0; _i < 2; ++_i) \
;         __builtin_amdgcn_global_load_lds((const unsigned*)((const char*)(gbase) + (voff)[_i]), (LAS unsigned*)(lds + (bufoff) + ldsw + _i * 8192), 16, 0, 0); } while (0)
; #define PG8_LDA(dst, b, h) do { _Pragma("unroll") for (int m = 0; m < 4; ++m) _Pragma("unroll") for (int k = 0; k < 2; ++k) dst[m][k] = *(const LAS bf16x8*)(lds + PG8_SA(b, h) + aoff + m * 2048 + k * 1024); } while (0)
; #define PG8_LDB(dst, b, h) do { _Pragma("unroll") for (int n = 0; n < 2; ++n) _Pragma("unroll") for (int k = 0; k < 2; ++k) dst[n][k] = *(const LAS bf16x8*)(lds + PG8_SB(b, h) + boff + n * 2048 + k * 1024); } while (0)
; #define PG8_WAIT_V(n) asm volatile("s_waitcnt vmcnt(" #n ")" ::: "memory")
; #define PG8_WAIT_L(n) asm volatile("s_waitcnt lgkmcnt(" #n ")" ::: "memory")
; template <class Epi, class Sched, bool ABLK = false, bool ALIGN_EPI = true, bool SP2 = true, bool BBLK = true>
; __device__ __forceinline__ void gemm_phase(LAS unsigned char* lds, const Gemm g, const Sched& S, const Epi& E) {
;     ...
;         const bool has_next = S.next(ui + 1, nxt);
;         const int nt = cur.nt;
;         const char* nuA = has_next ? a_unit(nxt) : uA; const int ntbA = has_next ? nxt.k0 / BK : tbA; const char* nB = has_next ? (const char*)g.Bt + (size_t)nxt.pn * tstepB + b_k0(nxt.k0) : cB;
;         for (int t = 0; t < nt; t += 2) {
;             const bool last = (t == nt - 2);
;             const char* a1 = a_tile(uA, tbA + t + 1);
;             const char* a2 = last ? a_tile(nuA, ntbA) : a_tile(uA, tbA + t + 2); const char* b2 = last ? nB : cB + (size_t)(t + 2) * kstepB;
;             const char* a3 = last ? a_tile(nuA, ntbA + 1) : a_tile(uA, tbA + t + 3); const char* b3 = b2 + kstepB;
;             if (last && has_next) S.a_ready(nxt);
;             if constexpr (SP2) {
;             PG8_LDB(B0, 0, 0); PG8_LDB(B1, 0, 1); PG8_SCHED; PG8_LDA(At, 0, 0); PG8_STAGE(PG8_SA(1, 1), a1 + hstepA, voffA);
;             PG8_WAIT_V(8); PG8_WAIT_L(0); PG8_BAR; PG8_MMA(0, 0, At, B0); PG8_MMA(0, 1, At, B1); PG8_BAR; PG8_SCHED;
;             PG8_LDA(At, 0, 1); PG8_STAGE(PG8_SB(0, 0), b2, voffB); PG8_STAGE(PG8_SB(0, 1), b2 + hstepB, voffB); PG8_STAGE(PG8_SA(0, 0), a2, voffA);
;             PG8_WAIT_V(8); PG8_WAIT_L(0); PG8_BAR; PG8_MMA(1, 0, At, B0); PG8_MMA(1, 1, At, B1); PG8_BAR; PG8_SCHED;
.LBB0_349:
	s_ashr_i32 s9, s8, 31
	s_lshl_b64 s[4:5], s[8:9], 20
	s_add_u32 s12, s36, s4
	s_addc_u32 s13, s37, s5
	s_and_b64 s[4:5], s[14:15], exec
	s_cselect_b32 s4, s13, s25
	s_cselect_b32 s5, s12, s24
	s_ashr_i32 s11, s10, 31
	s_lshl_b64 s[18:19], s[10:11], 20
	s_add_u32 s18, s0, s18
	s_addc_u32 s19, s1, s19
	s_and_b64 s[28:29], s[14:15], exec
	s_cselect_b32 s9, s19, s27
	s_cselect_b32 s11, s18, s26
	s_add_u32 s50, s5, 0x80
	s_addc_u32 s51, s4, 0
	s_add_u32 s52, s26, 0x10000
	v_mov_b32_e32 v2, 0
	s_addc_u32 s53, s27, 0
	v_lshl_add_u64 v[142:143], s[24:25], 0, v[138:139]
	v_lshl_add_u64 v[144:145], s[24:25], 0, v[140:141]
	s_mov_b32 s54, -2
	s_mov_b64 s[26:27], 0
	ds_read_b128 v[152:155], v148
	ds_read_b128 v[156:159], v148 offset:1024
	ds_read_b128 v[160:163], v148 offset:2048
	ds_read_b128 v[164:167], v148 offset:3072
	ds_read_b128 v[168:171], v149
	ds_read_b128 v[172:175], v149 offset:1024
	ds_read_b128 v[176:179], v149 offset:2048
	ds_read_b128 v[180:183], v149 offset:3072
	s_add_u32 s28, s24, s26
	s_addc_u32 s29, s25, s27
	s_add_u32 s34, s28, 0x100
	s_addc_u32 s35, s29, 0
	s_add_u32 s28, s28, 0x180
	s_addc_u32 s29, s29, 0
	s_cmpk_eq_i32 s26, 0xf00
	s_cselect_b32 s29, s51, s29
	s_cselect_b32 s28, s50, s28
	s_cselect_b32 s31, s9, s53
	s_cselect_b32 s30, s11, s52
	s_cselect_b32 s35, s4, s35
	s_cselect_b32 s34, s5, s34
	s_mov_b32 m0, s49
	v_lshl_add_u64 v[216:217], v[142:143], 0, s[26:27]
	ds_read_b128 v[184:187], v150
	ds_read_b128 v[188:191], v150 offset:1024
	ds_read_b128 v[192:195], v150 offset:2048
	ds_read_b128 v[196:199], v150 offset:3072
	ds_read_b128 v[200:203], v150 offset:4096
	ds_read_b128 v[204:207], v150 offset:5120
	ds_read_b128 v[208:211], v150 offset:6144
	ds_read_b128 v[212:215], v150 offset:7168
	global_load_lds_dwordx4 v[216:217], off
	v_lshl_add_u64 v[216:217], v[144:145], 0, s[26:27]
	s_add_i32 m0, s21, 0xe000
	s_nop 0
	global_load_lds_dwordx4 v[216:217], off
	s_waitcnt vmcnt(8)
	s_barrier
	s_waitcnt lgkmcnt(0)
	v_mfma_f32_16x16x32_bf16 v[122:125], v[152:155], v[184:187], 0
	v_mfma_f32_16x16x32_bf16 v[118:121], v[160:163], v[184:187], 0
	v_mfma_f32_16x16x32_bf16 v[106:109], v[152:155], v[192:195], 0
	v_mfma_f32_16x16x32_bf16 v[102:105], v[160:163], v[192:195], 0
	v_mfma_f32_16x16x32_bf16 v[90:93], v[152:155], v[200:203], 0
	v_mfma_f32_16x16x32_bf16 v[86:89], v[160:163], v[200:203], 0
	v_mfma_f32_16x16x32_bf16 v[74:77], v[152:155], v[208:211], 0
	v_mfma_f32_16x16x32_bf16 v[70:73], v[160:163], v[208:211], 0
	v_mfma_f32_16x16x32_bf16 v[122:125], v[156:159], v[188:191], v[122:125]
	v_mfma_f32_16x16x32_bf16 v[118:121], v[164:167], v[188:191], v[118:121]
	v_mfma_f32_16x16x32_bf16 v[106:109], v[156:159], v[196:199], v[106:109]
	v_mfma_f32_16x16x32_bf16 v[102:105], v[164:167], v[196:199], v[102:105]
	v_mfma_f32_16x16x32_bf16 v[90:93], v[156:159], v[204:207], v[90:93]
	v_mfma_f32_16x16x32_bf16 v[86:89], v[164:167], v[204:207], v[86:89]
	v_mfma_f32_16x16x32_bf16 v[74:77], v[156:159], v[212:215], v[74:77]
	v_mfma_f32_16x16x32_bf16 v[70:73], v[164:167], v[212:215], v[70:73]
	v_mfma_f32_16x16x32_bf16 v[126:129], v[168:171], v[184:187], 0
	v_mfma_f32_16x16x32_bf16 v[114:117], v[176:179], v[184:187], 0
	v_mfma_f32_16x16x32_bf16 v[110:113], v[168:171], v[192:195], 0
	v_mfma_f32_16x16x32_bf16 v[98:101], v[176:179], v[192:195], 0
	v_mfma_f32_16x16x32_bf16 v[94:97], v[168:171], v[200:203], 0
	v_mfma_f32_16x16x32_bf16 v[82:85], v[176:179], v[200:203], 0
	v_mfma_f32_16x16x32_bf16 v[78:81], v[168:171], v[208:211], 0
	v_mfma_f32_16x16x32_bf16 v[66:69], v[176:179], v[208:211], 0
	v_mfma_f32_16x16x32_bf16 v[126:129], v[172:175], v[188:191], v[126:129]
	v_mfma_f32_16x16x32_bf16 v[114:117], v[180:183], v[188:191], v[114:117]
	v_mfma_f32_16x16x32_bf16 v[110:113], v[172:175], v[196:199], v[110:113]
	v_mfma_f32_16x16x32_bf16 v[98:101], v[180:183], v[196:199], v[98:101]
	v_mfma_f32_16x16x32_bf16 v[94:97], v[172:175], v[204:207], v[94:97]
	v_mfma_f32_16x16x32_bf16 v[82:85], v[180:183], v[204:207], v[82:85]
	v_mfma_f32_16x16x32_bf16 v[78:81], v[172:175], v[212:215], v[78:81]
	v_mfma_f32_16x16x32_bf16 v[66:69], v[180:183], v[212:215], v[66:69]
	s_barrier
	s_add_i32 s55, s44, s33
	s_mov_b32 m0, s55
	ds_read_b128 v[184:187], v150 offset:16384
	ds_read_b128 v[188:191], v150 offset:17408
	ds_read_b128 v[192:195], v150 offset:18432
	ds_read_b128 v[196:199], v150 offset:19456
	ds_read_b128 v[200:203], v150 offset:20480
	ds_read_b128 v[204:207], v150 offset:21504
	ds_read_b128 v[208:211], v150 offset:22528
	ds_read_b128 v[212:215], v150 offset:23552
	global_load_lds_dwordx4 v134, s[30:31]
	s_add_i32 m0, s55, 0x2000
	s_add_u32 s56, s30, 0x4000
	s_addc_u32 s57, s31, 0
	s_add_i32 s55, s45, s33
	global_load_lds_dwordx4 v130, s[30:31]
	s_mov_b32 m0, s55
	s_nop 0
	global_load_lds_dwordx4 v134, s[56:57]
	s_add_i32 m0, s55, 0x2000
	s_nop 0
	global_load_lds_dwordx4 v130, s[56:57]
	s_mov_b32 m0, s21
	s_nop 0
	global_load_lds_dwordx4 v136, s[34:35]
	s_mov_b32 m0, s23
	s_nop 0
	global_load_lds_dwordx4 v132, s[34:35]
	s_waitcnt vmcnt(8)
	s_barrier
; #define PG8_STAGE(bufoff, gbase, voff) do { _Pragma("unroll") for (int _i = 0; _i < 2; ++_i) \
;         __builtin_amdgcn_global_load_lds((const unsigned*)((const char*)(gbase) + (voff)[_i]), (LAS unsigned*)(lds + (bufoff) + ldsw + _i * 8192), 16, 0, 0); } while (0)
; #define PG8_LDA(dst, b, h) do { _Pragma("unroll") for (int m = 0; m < 4; ++m) _Pragma("unroll") for (int k = 0; k < 2; ++k) dst[m][k] = *(const LAS bf16x8*)(lds + PG8_SA(b, h) + aoff + m * 2048 + k * 1024); } while (0)
; #define PG8_LDB(dst, b, h) do { _Pragma("unroll") for (int n = 0; n < 2; ++n) _Pragma("unroll") for (int k = 0; k < 2; ++k) dst[n][k] = *(const LAS bf16x8*)(lds + PG8_SB(b, h) + boff + n * 2048 + k * 1024); } while (0)
; #define PG8_MMA(ai, bj, At, Bt) do { __builtin_amdgcn_s_setprio(1); _Pragma("unroll") for (int m = 0; m < 4; ++m) _Pragma("unroll") for (int n = 0; n < 2; ++n) _Pragma("unroll") for (int k = 0; k < 2; ++k) \
;         acc[ai][bj][m][n] = __builtin_amdgcn_mfma_f32_16x16x32_bf16(Bt[n][k], At[m][k], acc[ai][bj][m][n], 0, 0, 0); __builtin_amdgcn_s_setprio(0); } while (0)
; #define PG8_WAIT_V(n) asm volatile("s_waitcnt vmcnt(" #n ")" ::: "memory")
; #define PG8_WAIT_L(n) asm volatile("s_waitcnt lgkmcnt(" #n ")" ::: "memory")
; #define PG8_BAR __builtin_amdgcn_s_barrier()
; #define PG8_SCHED __builtin_amdgcn_sched_barrier(0)
; template <class Epi, class Sched, bool ABLK = false, bool ALIGN_EPI = true, bool SP2 = true, bool BBLK = true>
; __device__ __forceinline__ void gemm_phase(LAS unsigned char* lds, const Gemm g, const Sched& S, const Epi& E) {
;     ...
;             PG8_LDA(At, 0, 1); PG8_STAGE(PG8_SB(0, 0), b2, voffB); PG8_STAGE(PG8_SB(0, 1), b2 + hstepB, voffB); PG8_STAGE(PG8_SA(0, 0), a2, voffA);
;             PG8_WAIT_V(8); PG8_WAIT_L(0); PG8_BAR; PG8_MMA(1, 0, At, B0); PG8_MMA(1, 1, At, B1); PG8_BAR; PG8_SCHED;
;             PG8_LDB(B0, 1, 0); PG8_LDB(B1, 1, 1); PG8_SCHED; PG8_LDA(At, 1, 0); PG8_STAGE(PG8_SA(0, 1), a2 + hstepA, voffA);
;             PG8_WAIT_V(8); PG8_WAIT_L(0); PG8_BAR; PG8_MMA(0, 0, At, B0); PG8_MMA(0, 1, At, B1); PG8_BAR; PG8_SCHED;
	s_waitcnt lgkmcnt(0)
	v_mfma_f32_16x16x32_bf16 v[58:61], v[152:155], v[184:187], 0
	v_mfma_f32_16x16x32_bf16 v[54:57], v[160:163], v[184:187], 0
	v_mfma_f32_16x16x32_bf16 v[42:45], v[152:155], v[192:195], 0
	v_mfma_f32_16x16x32_bf16 v[38:41], v[160:163], v[192:195], 0
	v_mfma_f32_16x16x32_bf16 v[26:29], v[152:155], v[200:203], 0
	v_mfma_f32_16x16x32_bf16 v[22:25], v[160:163], v[200:203], 0
	v_mfma_f32_16x16x32_bf16 v[10:13], v[152:155], v[208:211], 0
	v_mfma_f32_16x16x32_bf16 v[6:9], v[160:163], v[208:211], 0
	v_mfma_f32_16x16x32_bf16 v[58:61], v[156:159], v[188:191], v[58:61]
	v_mfma_f32_16x16x32_bf16 v[54:57], v[164:167], v[188:191], v[54:57]
	v_mfma_f32_16x16x32_bf16 v[42:45], v[156:159], v[196:199], v[42:45]
	v_mfma_f32_16x16x32_bf16 v[38:41], v[164:167], v[196:199], v[38:41]
	v_mfma_f32_16x16x32_bf16 v[26:29], v[156:159], v[204:207], v[26:29]
	v_mfma_f32_16x16x32_bf16 v[22:25], v[164:167], v[204:207], v[22:25]
	v_mfma_f32_16x16x32_bf16 v[10:13], v[156:159], v[212:215], v[10:13]
	v_mfma_f32_16x16x32_bf16 v[6:9], v[164:167], v[212:215], v[6:9]
	v_mfma_f32_16x16x32_bf16 v[62:65], v[168:171], v[184:187], 0
	v_mfma_f32_16x16x32_bf16 v[50:53], v[176:179], v[184:187], 0
	v_mfma_f32_16x16x32_bf16 v[46:49], v[168:171], v[192:195], 0
	v_mfma_f32_16x16x32_bf16 v[34:37], v[176:179], v[192:195], 0
	v_mfma_f32_16x16x32_bf16 v[30:33], v[168:171], v[200:203], 0
	v_mfma_f32_16x16x32_bf16 v[18:21], v[176:179], v[200:203], 0
	v_mfma_f32_16x16x32_bf16 v[14:17], v[168:171], v[208:211], 0
	v_mfma_f32_16x16x32_bf16 v[2:5], v[176:179], v[208:211], 0
	v_mfma_f32_16x16x32_bf16 v[62:65], v[172:175], v[188:191], v[62:65]
	v_mfma_f32_16x16x32_bf16 v[50:53], v[180:183], v[188:191], v[50:53]
	v_mfma_f32_16x16x32_bf16 v[46:49], v[172:175], v[196:199], v[46:49]
	v_mfma_f32_16x16x32_bf16 v[34:37], v[180:183], v[196:199], v[34:37]
	v_mfma_f32_16x16x32_bf16 v[30:33], v[172:175], v[204:207], v[30:33]
	v_mfma_f32_16x16x32_bf16 v[18:21], v[180:183], v[204:207], v[18:21]
	v_mfma_f32_16x16x32_bf16 v[14:17], v[172:175], v[212:215], v[14:17]
	v_mfma_f32_16x16x32_bf16 v[2:5], v[180:183], v[212:215], v[2:5]
	s_barrier
	s_add_i32 s55, 0, 0x18000
	v_add_u32_e32 v151, s55, v146
	s_add_i32 s56, 0, 0x1c000
	ds_read_b128 v[152:155], v151
	ds_read_b128 v[156:159], v151 offset:1024
	ds_read_b128 v[160:163], v151 offset:2048
	ds_read_b128 v[164:167], v151 offset:3072
	v_add_u32_e32 v151, s56, v146
	ds_read_b128 v[168:171], v151
	ds_read_b128 v[172:175], v151 offset:1024
	ds_read_b128 v[176:179], v151 offset:2048
	ds_read_b128 v[180:183], v151 offset:3072
	s_add_u32 s34, s34, 0x80000
	s_addc_u32 s35, s35, 0
	s_mov_b32 m0, s39
	ds_read_b128 v[184:187], v150 offset:32768
	ds_read_b128 v[188:191], v150 offset:33792
	ds_read_b128 v[192:195], v150 offset:34816
	ds_read_b128 v[196:199], v150 offset:35840
	ds_read_b128 v[200:203], v150 offset:36864
	ds_read_b128 v[204:207], v150 offset:37888
	ds_read_b128 v[208:211], v150 offset:38912
	ds_read_b128 v[212:215], v150 offset:39936
	global_load_lds_dwordx4 v136, s[34:35]
	s_mov_b32 m0, s40
	s_nop 0
	global_load_lds_dwordx4 v132, s[34:35]
	s_waitcnt vmcnt(8)
	s_barrier
	s_waitcnt lgkmcnt(0)
	v_mfma_f32_16x16x32_bf16 v[122:125], v[152:155], v[184:187], v[122:125]
	v_mfma_f32_16x16x32_bf16 v[118:121], v[160:163], v[184:187], v[118:121]
	v_mfma_f32_16x16x32_bf16 v[106:109], v[152:155], v[192:195], v[106:109]
	v_mfma_f32_16x16x32_bf16 v[102:105], v[160:163], v[192:195], v[102:105]
	v_mfma_f32_16x16x32_bf16 v[90:93], v[152:155], v[200:203], v[90:93]
	v_mfma_f32_16x16x32_bf16 v[86:89], v[160:163], v[200:203], v[86:89]
	v_mfma_f32_16x16x32_bf16 v[74:77], v[152:155], v[208:211], v[74:77]
	v_mfma_f32_16x16x32_bf16 v[70:73], v[160:163], v[208:211], v[70:73]
	v_mfma_f32_16x16x32_bf16 v[122:125], v[156:159], v[188:191], v[122:125]
	v_mfma_f32_16x16x32_bf16 v[118:121], v[164:167], v[188:191], v[118:121]
	v_mfma_f32_16x16x32_bf16 v[106:109], v[156:159], v[196:199], v[106:109]
	v_mfma_f32_16x16x32_bf16 v[102:105], v[164:167], v[196:199], v[102:105]
	v_mfma_f32_16x16x32_bf16 v[90:93], v[156:159], v[204:207], v[90:93]
	v_mfma_f32_16x16x32_bf16 v[86:89], v[164:167], v[204:207], v[86:89]
	v_mfma_f32_16x16x32_bf16 v[74:77], v[156:159], v[212:215], v[74:77]
	v_mfma_f32_16x16x32_bf16 v[70:73], v[164:167], v[212:215], v[70:73]
	v_mfma_f32_16x16x32_bf16 v[126:129], v[168:171], v[184:187], v[126:129]
	v_mfma_f32_16x16x32_bf16 v[114:117], v[176:179], v[184:187], v[114:117]
	v_mfma_f32_16x16x32_bf16 v[110:113], v[168:171], v[192:195], v[110:113]
	v_mfma_f32_16x16x32_bf16 v[98:101], v[176:179], v[192:195], v[98:101]
	v_mfma_f32_16x16x32_bf16 v[94:97], v[168:171], v[200:203], v[94:97]
	v_mfma_f32_16x16x32_bf16 v[82:85], v[176:179], v[200:203], v[82:85]
	v_mfma_f32_16x16x32_bf16 v[78:81], v[168:171], v[208:211], v[78:81]
	v_mfma_f32_16x16x32_bf16 v[66:69], v[176:179], v[208:211], v[66:69]
	v_mfma_f32_16x16x32_bf16 v[126:129], v[172:175], v[188:191], v[126:129]
	v_mfma_f32_16x16x32_bf16 v[114:117], v[180:183], v[188:191], v[114:117]
	v_mfma_f32_16x16x32_bf16 v[110:113], v[172:175], v[196:199], v[110:113]
	v_mfma_f32_16x16x32_bf16 v[98:101], v[180:183], v[196:199], v[98:101]
	v_mfma_f32_16x16x32_bf16 v[94:97], v[172:175], v[204:207], v[94:97]
	v_mfma_f32_16x16x32_bf16 v[82:85], v[180:183], v[204:207], v[82:85]
	v_mfma_f32_16x16x32_bf16 v[78:81], v[172:175], v[212:215], v[78:81]
	v_mfma_f32_16x16x32_bf16 v[66:69], v[180:183], v[212:215], v[66:69]
	s_barrier
; #define PG8_STAGE(bufoff, gbase, voff) do { _Pragma("unroll") for (int _i = 0; _i < 2; ++_i) \
;         __builtin_amdgcn_global_load_lds((const unsigned*)((const char*)(gbase) + (voff)[_i]), (LAS unsigned*)(lds + (bufoff) + ldsw + _i * 8192), 16, 0, 0); } while (0)
; #define PG8_LDA(dst, b, h) do { _Pragma("unroll") for (int m = 0; m < 4; ++m) _Pragma("unroll") for (int k = 0; k < 2; ++k) dst[m][k] = *(const LAS bf16x8*)(lds + PG8_SA(b, h) + aoff + m * 2048 + k * 1024); } while (0)
; #define PG8_WAIT_V(n) asm volatile("s_waitcnt vmcnt(" #n ")" ::: "memory")
; #define PG8_WAIT_L(n) asm volatile("s_waitcnt lgkmcnt(" #n ")" ::: "memory")
; template <class Epi, class Sched, bool ABLK = false, bool ALIGN_EPI = true, bool SP2 = true, bool BBLK = true>
; __device__ __forceinline__ void gemm_phase(LAS unsigned char* lds, const Gemm g, const Sched& S, const Epi& E) {
;     ...
;         for (int t = 0; t < nt; t += 2) {
;             const bool last = (t == nt - 2);
;             const char* a1 = a_tile(uA, tbA + t + 1);
;             const char* a2 = last ? a_tile(nuA, ntbA) : a_tile(uA, tbA + t + 2); const char* b2 = last ? nB : cB + (size_t)(t + 2) * kstepB;
;             const char* a3 = last ? a_tile(nuA, ntbA + 1) : a_tile(uA, tbA + t + 3); const char* b3 = b2 + kstepB;
;             if (last && has_next) S.a_ready(nxt);
;             if constexpr (SP2) {
;             PG8_LDB(B0, 0, 0); PG8_LDB(B1, 0, 1); PG8_SCHED; PG8_LDA(At, 0, 0); PG8_STAGE(PG8_SA(1, 1), a1 + hstepA, voffA);
;             PG8_WAIT_V(8); PG8_WAIT_L(0); PG8_BAR; PG8_MMA(0, 0, At, B0); PG8_MMA(0, 1, At, B1); PG8_BAR; PG8_SCHED;
;             PG8_LDA(At, 0, 1); PG8_STAGE(PG8_SB(0, 0), b2, voffB); PG8_STAGE(PG8_SB(0, 1), b2 + hstepB, voffB); PG8_STAGE(PG8_SA(0, 0), a2, voffA);
;             PG8_WAIT_V(8); PG8_WAIT_L(0); PG8_BAR; PG8_MMA(1, 0, At, B0); PG8_MMA(1, 1, At, B1); PG8_BAR; PG8_SCHED;
;             PG8_LDB(B0, 1, 0); PG8_LDB(B1, 1, 1); PG8_SCHED; PG8_LDA(At, 1, 0); PG8_STAGE(PG8_SA(0, 1), a2 + hstepA, voffA);
;             PG8_WAIT_V(8); PG8_WAIT_L(0); PG8_BAR; PG8_MMA(0, 0, At, B0); PG8_MMA(0, 1, At, B1); PG8_BAR; PG8_SCHED;
;             PG8_LDA(At, 1, 1); PG8_STAGE(PG8_SB(1, 0), b3, voffB); PG8_STAGE(PG8_SB(1, 1), b3 + hstepB, voffB); PG8_STAGE(PG8_SA(1, 0), a3, voffA);
;             PG8_WAIT_V(8); PG8_WAIT_L(0); PG8_BAR; PG8_MMA(1, 0, At, B0); PG8_MMA(1, 1, At, B1); PG8_BAR; PG8_SCHED;
	s_add_u32 s34, s30, 0x8000
	s_addc_u32 s35, s31, 0
	s_add_i32 s55, s55, s33
	s_mov_b32 m0, s55
	ds_read_b128 v[184:187], v150 offset:49152
	ds_read_b128 v[188:191], v150 offset:50176
	ds_read_b128 v[192:195], v150 offset:51200
	ds_read_b128 v[196:199], v150 offset:52224
	ds_read_b128 v[200:203], v150 offset:53248
	ds_read_b128 v[204:207], v150 offset:54272
	ds_read_b128 v[208:211], v150 offset:55296
	ds_read_b128 v[212:215], v150 offset:56320
	global_load_lds_dwordx4 v134, s[34:35]
	s_add_i32 m0, s55, 0x2000
	s_add_u32 s30, s30, 0xc000
	v_lshl_add_u64 v[216:217], s[34:35], 0, v[130:131]
	s_addc_u32 s31, s31, 0
	s_add_i32 s34, s56, s33
	global_load_lds_dwordx4 v[216:217], off
	s_mov_b32 m0, s34
	s_nop 0
	global_load_lds_dwordx4 v134, s[30:31]
	s_add_i32 m0, s34, 0x2000
	s_nop 0
	global_load_lds_dwordx4 v130, s[30:31]
	s_mov_b32 m0, s42
	s_nop 0
	global_load_lds_dwordx4 v136, s[28:29]
	s_mov_b32 m0, s43
	s_nop 0
	global_load_lds_dwordx4 v132, s[28:29]
	s_waitcnt vmcnt(8)
	s_barrier
	s_waitcnt lgkmcnt(0)
	v_mfma_f32_16x16x32_bf16 v[58:61], v[152:155], v[184:187], v[58:61]
	v_mfma_f32_16x16x32_bf16 v[54:57], v[160:163], v[184:187], v[54:57]
	v_mfma_f32_16x16x32_bf16 v[42:45], v[152:155], v[192:195], v[42:45]
	v_mfma_f32_16x16x32_bf16 v[38:41], v[160:163], v[192:195], v[38:41]
	v_mfma_f32_16x16x32_bf16 v[26:29], v[152:155], v[200:203], v[26:29]
	v_mfma_f32_16x16x32_bf16 v[22:25], v[160:163], v[200:203], v[22:25]
	v_mfma_f32_16x16x32_bf16 v[10:13], v[152:155], v[208:211], v[10:13]
	v_mfma_f32_16x16x32_bf16 v[6:9], v[160:163], v[208:211], v[6:9]
	v_mfma_f32_16x16x32_bf16 v[58:61], v[156:159], v[188:191], v[58:61]
	v_mfma_f32_16x16x32_bf16 v[54:57], v[164:167], v[188:191], v[54:57]
	v_mfma_f32_16x16x32_bf16 v[42:45], v[156:159], v[196:199], v[42:45]
	v_mfma_f32_16x16x32_bf16 v[38:41], v[164:167], v[196:199], v[38:41]
	v_mfma_f32_16x16x32_bf16 v[26:29], v[156:159], v[204:207], v[26:29]
	v_mfma_f32_16x16x32_bf16 v[22:25], v[164:167], v[204:207], v[22:25]
	v_mfma_f32_16x16x32_bf16 v[10:13], v[156:159], v[212:215], v[10:13]
	v_mfma_f32_16x16x32_bf16 v[6:9], v[164:167], v[212:215], v[6:9]
	v_mfma_f32_16x16x32_bf16 v[62:65], v[168:171], v[184:187], v[62:65]
	v_mfma_f32_16x16x32_bf16 v[50:53], v[176:179], v[184:187], v[50:53]
	v_mfma_f32_16x16x32_bf16 v[46:49], v[168:171], v[192:195], v[46:49]
	v_mfma_f32_16x16x32_bf16 v[34:37], v[176:179], v[192:195], v[34:37]
	v_mfma_f32_16x16x32_bf16 v[30:33], v[168:171], v[200:203], v[30:33]
	v_mfma_f32_16x16x32_bf16 v[18:21], v[176:179], v[200:203], v[18:21]
	v_mfma_f32_16x16x32_bf16 v[14:17], v[168:171], v[208:211], v[14:17]
	v_mfma_f32_16x16x32_bf16 v[2:5], v[176:179], v[208:211], v[2:5]
	v_mfma_f32_16x16x32_bf16 v[62:65], v[172:175], v[188:191], v[62:65]
	v_mfma_f32_16x16x32_bf16 v[50:53], v[180:183], v[188:191], v[50:53]
	v_mfma_f32_16x16x32_bf16 v[46:49], v[172:175], v[196:199], v[46:49]
	v_mfma_f32_16x16x32_bf16 v[34:37], v[180:183], v[196:199], v[34:37]
	v_mfma_f32_16x16x32_bf16 v[30:33], v[172:175], v[204:207], v[30:33]
	v_mfma_f32_16x16x32_bf16 v[18:21], v[180:183], v[204:207], v[18:21]
	v_mfma_f32_16x16x32_bf16 v[14:17], v[172:175], v[212:215], v[14:17]
	v_mfma_f32_16x16x32_bf16 v[2:5], v[180:183], v[212:215], v[2:5]
	s_barrier
	s_add_i32 s54, s54, 2
	s_add_u32 s26, s26, 0x100
	s_addc_u32 s27, s27, 0
	s_add_u32 s52, s52, 0x10000
	s_addc_u32 s53, s53, 0
	s_cmp_gt_u32 s54, 29
.LBB0_350:
	ds_read_b128 v[152:155], v148
	ds_read_b128 v[156:159], v148 offset:1024
	ds_read_b128 v[160:163], v148 offset:2048
	ds_read_b128 v[164:167], v148 offset:3072
	ds_read_b128 v[168:171], v149
	ds_read_b128 v[172:175], v149 offset:1024
	ds_read_b128 v[176:179], v149 offset:2048
	ds_read_b128 v[180:183], v149 offset:3072
	s_add_u32 s28, s24, s26
	s_addc_u32 s29, s25, s27
	s_add_u32 s34, s28, 0x100
	s_addc_u32 s35, s29, 0
	s_add_u32 s28, s28, 0x180
	s_addc_u32 s29, s29, 0
	s_cmpk_eq_i32 s26, 0xf00
	s_cselect_b32 s29, s51, s29
	s_cselect_b32 s28, s50, s28
	s_cselect_b32 s31, s9, s53
	s_cselect_b32 s30, s11, s52
	s_cselect_b32 s35, s4, s35
	s_cselect_b32 s34, s5, s34
	s_mov_b32 m0, s49
	v_lshl_add_u64 v[216:217], v[142:143], 0, s[26:27]
	ds_read_b128 v[184:187], v150
	ds_read_b128 v[188:191], v150 offset:1024
	ds_read_b128 v[192:195], v150 offset:2048
	ds_read_b128 v[196:199], v150 offset:3072
	ds_read_b128 v[200:203], v150 offset:4096
	ds_read_b128 v[204:207], v150 offset:5120
	ds_read_b128 v[208:211], v150 offset:6144
	ds_read_b128 v[212:215], v150 offset:7168
	global_load_lds_dwordx4 v[216:217], off
	v_lshl_add_u64 v[216:217], v[144:145], 0, s[26:27]
	s_add_i32 m0, s21, 0xe000
	s_nop 0
	global_load_lds_dwordx4 v[216:217], off
	s_waitcnt vmcnt(8)
	s_barrier
; #define PG8_STAGE(bufoff, gbase, voff) do { _Pragma("unroll") for (int _i = 0; _i < 2; ++_i) \
;         __builtin_amdgcn_global_load_lds((const unsigned*)((const char*)(gbase) + (voff)[_i]), (LAS unsigned*)(lds + (bufoff) + ldsw + _i * 8192), 16, 0, 0); } while (0)
; #define PG8_LDA(dst, b, h) do { _Pragma("unroll") for (int m = 0; m < 4; ++m) _Pragma("unroll") for (int k = 0; k < 2; ++k) dst[m][k] = *(const LAS bf16x8*)(lds + PG8_SA(b, h) + aoff + m * 2048 + k * 1024); } while (0)
; #define PG8_LDB(dst, b, h) do { _Pragma("unroll") for (int n = 0; n < 2; ++n) _Pragma("unroll") for (int k = 0; k < 2; ++k) dst[n][k] = *(const LAS bf16x8*)(lds + PG8_SB(b, h) + boff + n * 2048 + k * 1024); } while (0)
; #define PG8_MMA(ai, bj, At, Bt) do { __builtin_amdgcn_s_setprio(1); _Pragma("unroll") for (int m = 0; m < 4; ++m) _Pragma("unroll") for (int n = 0; n < 2; ++n) _Pragma("unroll") for (int k = 0; k < 2; ++k) \
;         acc[ai][bj][m][n] = __builtin_amdgcn_mfma_f32_16x16x32_bf16(Bt[n][k], At[m][k], acc[ai][bj][m][n], 0, 0, 0); __builtin_amdgcn_s_setprio(0); } while (0)
; #define PG8_WAIT_V(n) asm volatile("s_waitcnt vmcnt(" #n ")" ::: "memory")
; #define PG8_WAIT_L(n) asm volatile("s_waitcnt lgkmcnt(" #n ")" ::: "memory")
; #define PG8_BAR __builtin_amdgcn_s_barrier()
; #define PG8_SCHED __builtin_amdgcn_sched_barrier(0)
; template <class Epi, class Sched, bool ABLK = false, bool ALIGN_EPI = true, bool SP2 = true, bool BBLK = true>
; __device__ __forceinline__ void gemm_phase(LAS unsigned char* lds, const Gemm g, const Sched& S, const Epi& E) {
;     ...
;             PG8_LDB(B0, 0, 0); PG8_LDB(B1, 0, 1); PG8_SCHED; PG8_LDA(At, 0, 0); PG8_STAGE(PG8_SA(1, 1), a1 + hstepA, voffA);
;             PG8_WAIT_V(8); PG8_WAIT_L(0); PG8_BAR; PG8_MMA(0, 0, At, B0); PG8_MMA(0, 1, At, B1); PG8_BAR; PG8_SCHED;
;             PG8_LDA(At, 0, 1); PG8_STAGE(PG8_SB(0, 0), b2, voffB); PG8_STAGE(PG8_SB(0, 1), b2 + hstepB, voffB); PG8_STAGE(PG8_SA(0, 0), a2, voffA);
;             PG8_WAIT_V(8); PG8_WAIT_L(0); PG8_BAR; PG8_MMA(1, 0, At, B0); PG8_MMA(1, 1, At, B1); PG8_BAR; PG8_SCHED;
	s_waitcnt lgkmcnt(0)
	v_mfma_f32_16x16x32_bf16 v[122:125], v[152:155], v[184:187], v[122:125]
	v_mfma_f32_16x16x32_bf16 v[118:121], v[160:163], v[184:187], v[118:121]
	v_mfma_f32_16x16x32_bf16 v[106:109], v[152:155], v[192:195], v[106:109]
	v_mfma_f32_16x16x32_bf16 v[102:105], v[160:163], v[192:195], v[102:105]
	v_mfma_f32_16x16x32_bf16 v[90:93], v[152:155], v[200:203], v[90:93]
	v_mfma_f32_16x16x32_bf16 v[86:89], v[160:163], v[200:203], v[86:89]
	v_mfma_f32_16x16x32_bf16 v[74:77], v[152:155], v[208:211], v[74:77]
	v_mfma_f32_16x16x32_bf16 v[70:73], v[160:163], v[208:211], v[70:73]
	v_mfma_f32_16x16x32_bf16 v[122:125], v[156:159], v[188:191], v[122:125]
	v_mfma_f32_16x16x32_bf16 v[118:121], v[164:167], v[188:191], v[118:121]
	v_mfma_f32_16x16x32_bf16 v[106:109], v[156:159], v[196:199], v[106:109]
	v_mfma_f32_16x16x32_bf16 v[102:105], v[164:167], v[196:199], v[102:105]
	v_mfma_f32_16x16x32_bf16 v[90:93], v[156:159], v[204:207], v[90:93]
	v_mfma_f32_16x16x32_bf16 v[86:89], v[164:167], v[204:207], v[86:89]
	v_mfma_f32_16x16x32_bf16 v[74:77], v[156:159], v[212:215], v[74:77]
	v_mfma_f32_16x16x32_bf16 v[70:73], v[164:167], v[212:215], v[70:73]
	v_mfma_f32_16x16x32_bf16 v[126:129], v[168:171], v[184:187], v[126:129]
	v_mfma_f32_16x16x32_bf16 v[114:117], v[176:179], v[184:187], v[114:117]
	v_mfma_f32_16x16x32_bf16 v[110:113], v[168:171], v[192:195], v[110:113]
	v_mfma_f32_16x16x32_bf16 v[98:101], v[176:179], v[192:195], v[98:101]
	v_mfma_f32_16x16x32_bf16 v[94:97], v[168:171], v[200:203], v[94:97]
	v_mfma_f32_16x16x32_bf16 v[82:85], v[176:179], v[200:203], v[82:85]
	v_mfma_f32_16x16x32_bf16 v[78:81], v[168:171], v[208:211], v[78:81]
	v_mfma_f32_16x16x32_bf16 v[66:69], v[176:179], v[208:211], v[66:69]
	v_mfma_f32_16x16x32_bf16 v[126:129], v[172:175], v[188:191], v[126:129]
	v_mfma_f32_16x16x32_bf16 v[114:117], v[180:183], v[188:191], v[114:117]
	v_mfma_f32_16x16x32_bf16 v[110:113], v[172:175], v[196:199], v[110:113]
	v_mfma_f32_16x16x32_bf16 v[98:101], v[180:183], v[196:199], v[98:101]
	v_mfma_f32_16x16x32_bf16 v[94:97], v[172:175], v[204:207], v[94:97]
	v_mfma_f32_16x16x32_bf16 v[82:85], v[180:183], v[204:207], v[82:85]
	v_mfma_f32_16x16x32_bf16 v[78:81], v[172:175], v[212:215], v[78:81]
	v_mfma_f32_16x16x32_bf16 v[66:69], v[180:183], v[212:215], v[66:69]
	s_barrier
	s_add_i32 s55, s44, s33
	s_mov_b32 m0, s55
	ds_read_b128 v[184:187], v150 offset:16384
	ds_read_b128 v[188:191], v150 offset:17408
	ds_read_b128 v[192:195], v150 offset:18432
	ds_read_b128 v[196:199], v150 offset:19456
	ds_read_b128 v[200:203], v150 offset:20480
	ds_read_b128 v[204:207], v150 offset:21504
	ds_read_b128 v[208:211], v150 offset:22528
	ds_read_b128 v[212:215], v150 offset:23552
	global_load_lds_dwordx4 v134, s[30:31]
	s_add_i32 m0, s55, 0x2000
	s_add_u32 s56, s30, 0x4000
	s_addc_u32 s57, s31, 0
	s_add_i32 s55, s45, s33
	global_load_lds_dwordx4 v130, s[30:31]
	s_mov_b32 m0, s55
	s_nop 0
	global_load_lds_dwordx4 v134, s[56:57]
	s_add_i32 m0, s55, 0x2000
	s_nop 0
	global_load_lds_dwordx4 v130, s[56:57]
	s_mov_b32 m0, s21
	s_nop 0
	global_load_lds_dwordx4 v136, s[34:35]
	s_mov_b32 m0, s23
	s_nop 0
	global_load_lds_dwordx4 v132, s[34:35]
	s_waitcnt vmcnt(8)
	s_barrier
	s_waitcnt lgkmcnt(0)
	v_mfma_f32_16x16x32_bf16 v[58:61], v[152:155], v[184:187], v[58:61]
	v_mfma_f32_16x16x32_bf16 v[54:57], v[160:163], v[184:187], v[54:57]
	v_mfma_f32_16x16x32_bf16 v[42:45], v[152:155], v[192:195], v[42:45]
	v_mfma_f32_16x16x32_bf16 v[38:41], v[160:163], v[192:195], v[38:41]
	v_mfma_f32_16x16x32_bf16 v[26:29], v[152:155], v[200:203], v[26:29]
	v_mfma_f32_16x16x32_bf16 v[22:25], v[160:163], v[200:203], v[22:25]
	v_mfma_f32_16x16x32_bf16 v[10:13], v[152:155], v[208:211], v[10:13]
	v_mfma_f32_16x16x32_bf16 v[6:9], v[160:163], v[208:211], v[6:9]
	v_mfma_f32_16x16x32_bf16 v[58:61], v[156:159], v[188:191], v[58:61]
	v_mfma_f32_16x16x32_bf16 v[54:57], v[164:167], v[188:191], v[54:57]
	v_mfma_f32_16x16x32_bf16 v[42:45], v[156:159], v[196:199], v[42:45]
	v_mfma_f32_16x16x32_bf16 v[38:41], v[164:167], v[196:199], v[38:41]
	v_mfma_f32_16x16x32_bf16 v[26:29], v[156:159], v[204:207], v[26:29]
	v_mfma_f32_16x16x32_bf16 v[22:25], v[164:167], v[204:207], v[22:25]
	v_mfma_f32_16x16x32_bf16 v[10:13], v[156:159], v[212:215], v[10:13]
	v_mfma_f32_16x16x32_bf16 v[6:9], v[164:167], v[212:215], v[6:9]
	v_mfma_f32_16x16x32_bf16 v[62:65], v[168:171], v[184:187], v[62:65]
	v_mfma_f32_16x16x32_bf16 v[50:53], v[176:179], v[184:187], v[50:53]
	v_mfma_f32_16x16x32_bf16 v[46:49], v[168:171], v[192:195], v[46:49]
	v_mfma_f32_16x16x32_bf16 v[34:37], v[176:179], v[192:195], v[34:37]
	v_mfma_f32_16x16x32_bf16 v[30:33], v[168:171], v[200:203], v[30:33]
	v_mfma_f32_16x16x32_bf16 v[18:21], v[176:179], v[200:203], v[18:21]
	v_mfma_f32_16x16x32_bf16 v[14:17], v[168:171], v[208:211], v[14:17]
	v_mfma_f32_16x16x32_bf16 v[2:5], v[176:179], v[208:211], v[2:5]
	v_mfma_f32_16x16x32_bf16 v[62:65], v[172:175], v[188:191], v[62:65]
	v_mfma_f32_16x16x32_bf16 v[50:53], v[180:183], v[188:191], v[50:53]
	v_mfma_f32_16x16x32_bf16 v[46:49], v[172:175], v[196:199], v[46:49]
	v_mfma_f32_16x16x32_bf16 v[34:37], v[180:183], v[196:199], v[34:37]
	v_mfma_f32_16x16x32_bf16 v[30:33], v[172:175], v[204:207], v[30:33]
	v_mfma_f32_16x16x32_bf16 v[18:21], v[180:183], v[204:207], v[18:21]
	v_mfma_f32_16x16x32_bf16 v[14:17], v[172:175], v[212:215], v[14:17]
	v_mfma_f32_16x16x32_bf16 v[2:5], v[180:183], v[212:215], v[2:5]
	s_barrier
; #define PG8_STAGE(bufoff, gbase, voff) do { _Pragma("unroll") for (int _i = 0; _i < 2; ++_i) \
;         __builtin_amdgcn_global_load_lds((const unsigned*)((const char*)(gbase) + (voff)[_i]), (LAS unsigned*)(lds + (bufoff) + ldsw + _i * 8192), 16, 0, 0); } while (0)
; #define PG8_LDA(dst, b, h) do { _Pragma("unroll") for (int m = 0; m < 4; ++m) _Pragma("unroll") for (int k = 0; k < 2; ++k) dst[m][k] = *(const LAS bf16x8*)(lds + PG8_SA(b, h) + aoff + m * 2048 + k * 1024); } while (0)
; #define PG8_LDB(dst, b, h) do { _Pragma("unroll") for (int n = 0; n < 2; ++n) _Pragma("unroll") for (int k = 0; k < 2; ++k) dst[n][k] = *(const LAS bf16x8*)(lds + PG8_SB(b, h) + boff + n * 2048 + k * 1024); } while (0)
; #define PG8_MMA(ai, bj, At, Bt) do { __builtin_amdgcn_s_setprio(1); _Pragma("unroll") for (int m = 0; m < 4; ++m) _Pragma("unroll") for (int n = 0; n < 2; ++n) _Pragma("unroll") for (int k = 0; k < 2; ++k) \
;         acc[ai][bj][m][n] = __builtin_amdgcn_mfma_f32_16x16x32_bf16(Bt[n][k], At[m][k], acc[ai][bj][m][n], 0, 0, 0); __builtin_amdgcn_s_setprio(0); } while (0)
; #define PG8_WAIT_V(n) asm volatile("s_waitcnt vmcnt(" #n ")" ::: "memory")
; #define PG8_WAIT_L(n) asm volatile("s_waitcnt lgkmcnt(" #n ")" ::: "memory")
; #define PG8_BAR __builtin_amdgcn_s_barrier()
; #define PG8_SCHED __builtin_amdgcn_sched_barrier(0)
; template <class Epi, class Sched, bool ABLK = false, bool ALIGN_EPI = true, bool SP2 = true, bool BBLK = true>
; __device__ __forceinline__ void gemm_phase(LAS unsigned char* lds, const Gemm g, const Sched& S, const Epi& E) {
;     ...
;             PG8_LDB(B0, 1, 0); PG8_LDB(B1, 1, 1); PG8_SCHED; PG8_LDA(At, 1, 0); PG8_STAGE(PG8_SA(0, 1), a2 + hstepA, voffA);
;             PG8_WAIT_V(8); PG8_WAIT_L(0); PG8_BAR; PG8_MMA(0, 0, At, B0); PG8_MMA(0, 1, At, B1); PG8_BAR; PG8_SCHED;
;             PG8_LDA(At, 1, 1); PG8_STAGE(PG8_SB(1, 0), b3, voffB); PG8_STAGE(PG8_SB(1, 1), b3 + hstepB, voffB); PG8_STAGE(PG8_SA(1, 0), a3, voffA);
;             PG8_WAIT_V(8); PG8_WAIT_L(0); PG8_BAR; PG8_MMA(1, 0, At, B0); PG8_MMA(1, 1, At, B1); PG8_BAR; PG8_SCHED;
;     ...
;         if constexpr (ALIGN_EPI) { if (wr == 0) PG8_BAR; }
	s_add_i32 s55, 0, 0x18000
	v_add_u32_e32 v151, s55, v146
	s_add_i32 s56, 0, 0x1c000
	ds_read_b128 v[152:155], v151
	ds_read_b128 v[156:159], v151 offset:1024
	ds_read_b128 v[160:163], v151 offset:2048
	ds_read_b128 v[164:167], v151 offset:3072
	v_add_u32_e32 v151, s56, v146
	ds_read_b128 v[168:171], v151
	ds_read_b128 v[172:175], v151 offset:1024
	ds_read_b128 v[176:179], v151 offset:2048
	ds_read_b128 v[180:183], v151 offset:3072
	s_add_u32 s34, s34, 0x80000
	s_addc_u32 s35, s35, 0
	s_mov_b32 m0, s39
	ds_read_b128 v[184:187], v150 offset:32768
	ds_read_b128 v[188:191], v150 offset:33792
	ds_read_b128 v[192:195], v150 offset:34816
	ds_read_b128 v[196:199], v150 offset:35840
	ds_read_b128 v[200:203], v150 offset:36864
	ds_read_b128 v[204:207], v150 offset:37888
	ds_read_b128 v[208:211], v150 offset:38912
	ds_read_b128 v[212:215], v150 offset:39936
	global_load_lds_dwordx4 v136, s[34:35]
	s_mov_b32 m0, s40
	s_nop 0
	global_load_lds_dwordx4 v132, s[34:35]
	s_waitcnt vmcnt(8)
	s_barrier
	s_waitcnt lgkmcnt(0)
	v_mfma_f32_16x16x32_bf16 v[122:125], v[152:155], v[184:187], v[122:125]
	v_mfma_f32_16x16x32_bf16 v[118:121], v[160:163], v[184:187], v[118:121]
	v_mfma_f32_16x16x32_bf16 v[106:109], v[152:155], v[192:195], v[106:109]
	v_mfma_f32_16x16x32_bf16 v[102:105], v[160:163], v[192:195], v[102:105]
	v_mfma_f32_16x16x32_bf16 v[90:93], v[152:155], v[200:203], v[90:93]
	v_mfma_f32_16x16x32_bf16 v[86:89], v[160:163], v[200:203], v[86:89]
	v_mfma_f32_16x16x32_bf16 v[74:77], v[152:155], v[208:211], v[74:77]
	v_mfma_f32_16x16x32_bf16 v[70:73], v[160:163], v[208:211], v[70:73]
	v_mfma_f32_16x16x32_bf16 v[122:125], v[156:159], v[188:191], v[122:125]
	v_mfma_f32_16x16x32_bf16 v[118:121], v[164:167], v[188:191], v[118:121]
	v_mfma_f32_16x16x32_bf16 v[106:109], v[156:159], v[196:199], v[106:109]
	v_mfma_f32_16x16x32_bf16 v[102:105], v[164:167], v[196:199], v[102:105]
	v_mfma_f32_16x16x32_bf16 v[90:93], v[156:159], v[204:207], v[90:93]
	v_mfma_f32_16x16x32_bf16 v[86:89], v[164:167], v[204:207], v[86:89]
	v_mfma_f32_16x16x32_bf16 v[74:77], v[156:159], v[212:215], v[74:77]
	v_mfma_f32_16x16x32_bf16 v[70:73], v[164:167], v[212:215], v[70:73]
	v_mfma_f32_16x16x32_bf16 v[126:129], v[168:171], v[184:187], v[126:129]
	v_mfma_f32_16x16x32_bf16 v[114:117], v[176:179], v[184:187], v[114:117]
	v_mfma_f32_16x16x32_bf16 v[110:113], v[168:171], v[192:195], v[110:113]
	v_mfma_f32_16x16x32_bf16 v[98:101], v[176:179], v[192:195], v[98:101]
	v_mfma_f32_16x16x32_bf16 v[94:97], v[168:171], v[200:203], v[94:97]
	v_mfma_f32_16x16x32_bf16 v[82:85], v[176:179], v[200:203], v[82:85]
	v_mfma_f32_16x16x32_bf16 v[78:81], v[168:171], v[208:211], v[78:81]
	v_mfma_f32_16x16x32_bf16 v[66:69], v[176:179], v[208:211], v[66:69]
	v_mfma_f32_16x16x32_bf16 v[126:129], v[172:175], v[188:191], v[126:129]
	v_mfma_f32_16x16x32_bf16 v[114:117], v[180:183], v[188:191], v[114:117]
	v_mfma_f32_16x16x32_bf16 v[110:113], v[172:175], v[196:199], v[110:113]
	v_mfma_f32_16x16x32_bf16 v[98:101], v[180:183], v[196:199], v[98:101]
	v_mfma_f32_16x16x32_bf16 v[94:97], v[172:175], v[204:207], v[94:97]
	v_mfma_f32_16x16x32_bf16 v[82:85], v[180:183], v[204:207], v[82:85]
	v_mfma_f32_16x16x32_bf16 v[78:81], v[172:175], v[212:215], v[78:81]
	v_mfma_f32_16x16x32_bf16 v[66:69], v[180:183], v[212:215], v[66:69]
	s_barrier
	s_add_u32 s34, s30, 0x8000
	s_addc_u32 s35, s31, 0
	s_add_i32 s55, s55, s33
	s_mov_b32 m0, s55
	ds_read_b128 v[184:187], v150 offset:49152
	ds_read_b128 v[188:191], v150 offset:50176
	ds_read_b128 v[192:195], v150 offset:51200
	ds_read_b128 v[196:199], v150 offset:52224
	ds_read_b128 v[200:203], v150 offset:53248
	ds_read_b128 v[204:207], v150 offset:54272
	ds_read_b128 v[208:211], v150 offset:55296
	ds_read_b128 v[212:215], v150 offset:56320
	global_load_lds_dwordx4 v134, s[34:35]
	s_add_i32 m0, s55, 0x2000
	s_add_u32 s30, s30, 0xc000
	v_lshl_add_u64 v[216:217], s[34:35], 0, v[130:131]
	s_addc_u32 s31, s31, 0
	s_add_i32 s34, s56, s33
	global_load_lds_dwordx4 v[216:217], off
	s_mov_b32 m0, s34
	s_nop 0
	global_load_lds_dwordx4 v134, s[30:31]
	s_add_i32 m0, s34, 0x2000
	s_nop 0
	global_load_lds_dwordx4 v130, s[30:31]
	s_mov_b32 m0, s42
	s_nop 0
	global_load_lds_dwordx4 v136, s[28:29]
	s_mov_b32 m0, s43
	s_nop 0
	global_load_lds_dwordx4 v132, s[28:29]
	s_waitcnt vmcnt(8)
	s_barrier
	s_waitcnt lgkmcnt(0)
	v_mfma_f32_16x16x32_bf16 v[58:61], v[152:155], v[184:187], v[58:61]
	v_mfma_f32_16x16x32_bf16 v[54:57], v[160:163], v[184:187], v[54:57]
	v_mfma_f32_16x16x32_bf16 v[42:45], v[152:155], v[192:195], v[42:45]
	v_mfma_f32_16x16x32_bf16 v[38:41], v[160:163], v[192:195], v[38:41]
	v_mfma_f32_16x16x32_bf16 v[26:29], v[152:155], v[200:203], v[26:29]
	v_mfma_f32_16x16x32_bf16 v[22:25], v[160:163], v[200:203], v[22:25]
	v_mfma_f32_16x16x32_bf16 v[10:13], v[152:155], v[208:211], v[10:13]
	v_mfma_f32_16x16x32_bf16 v[6:9], v[160:163], v[208:211], v[6:9]
	v_mfma_f32_16x16x32_bf16 v[58:61], v[156:159], v[188:191], v[58:61]
	v_mfma_f32_16x16x32_bf16 v[54:57], v[164:167], v[188:191], v[54:57]
	v_mfma_f32_16x16x32_bf16 v[42:45], v[156:159], v[196:199], v[42:45]
	v_mfma_f32_16x16x32_bf16 v[38:41], v[164:167], v[196:199], v[38:41]
	v_mfma_f32_16x16x32_bf16 v[26:29], v[156:159], v[204:207], v[26:29]
	v_mfma_f32_16x16x32_bf16 v[22:25], v[164:167], v[204:207], v[22:25]
	v_mfma_f32_16x16x32_bf16 v[10:13], v[156:159], v[212:215], v[10:13]
	v_mfma_f32_16x16x32_bf16 v[6:9], v[164:167], v[212:215], v[6:9]
	v_mfma_f32_16x16x32_bf16 v[62:65], v[168:171], v[184:187], v[62:65]
	v_mfma_f32_16x16x32_bf16 v[50:53], v[176:179], v[184:187], v[50:53]
	v_mfma_f32_16x16x32_bf16 v[46:49], v[168:171], v[192:195], v[46:49]
	v_mfma_f32_16x16x32_bf16 v[34:37], v[176:179], v[192:195], v[34:37]
	v_mfma_f32_16x16x32_bf16 v[30:33], v[168:171], v[200:203], v[30:33]
	v_mfma_f32_16x16x32_bf16 v[18:21], v[176:179], v[200:203], v[18:21]
	v_mfma_f32_16x16x32_bf16 v[14:17], v[168:171], v[208:211], v[14:17]
	v_mfma_f32_16x16x32_bf16 v[2:5], v[176:179], v[208:211], v[2:5]
	v_mfma_f32_16x16x32_bf16 v[62:65], v[172:175], v[188:191], v[62:65]
	v_mfma_f32_16x16x32_bf16 v[50:53], v[180:183], v[188:191], v[50:53]
	v_mfma_f32_16x16x32_bf16 v[46:49], v[172:175], v[196:199], v[46:49]
	v_mfma_f32_16x16x32_bf16 v[34:37], v[180:183], v[196:199], v[34:37]
	v_mfma_f32_16x16x32_bf16 v[30:33], v[172:175], v[204:207], v[30:33]
	v_mfma_f32_16x16x32_bf16 v[18:21], v[180:183], v[204:207], v[18:21]
	v_mfma_f32_16x16x32_bf16 v[14:17], v[172:175], v[212:215], v[14:17]
	v_mfma_f32_16x16x32_bf16 v[2:5], v[180:183], v[212:215], v[2:5]
	s_barrier
	s_add_i32 s54, s54, 2
	s_add_u32 s26, s26, 0x100
	s_addc_u32 s27, s27, 0
	s_add_u32 s52, s52, 0x10000
	s_addc_u32 s53, s53, 0
	s_cmp_gt_u32 s54, 29
	s_cbranch_scc0 .LBB0_350
	s_and_b64 vcc, exec, s[6:7]
	s_cbranch_vccz .LBB0_353
	s_barrier

; #define PG8_STAGE(bufoff, gbase, voff) do { _Pragma("unroll") for (int _i = 0; _i < 2; ++_i) \
;         __builtin_amdgcn_global_load_lds((const unsigned*)((const char*)(gbase) + (voff)[_i]), (LAS unsigned*)(lds + (bufoff) + ldsw + _i * 8192), 16, 0, 0); } while (0)
; #define PG8_LDA(dst, b, h) do { _Pragma("unroll") for (int m = 0; m < 4; ++m) _Pragma("unroll") for (int k = 0; k < 2; ++k) dst[m][k] = *(const LAS bf16x8*)(lds + PG8_SA(b, h) + aoff + m * 2048 + k * 1024); } while (0)
; #define PG8_LDB(dst, b, h) do { _Pragma("unroll") for (int n = 0; n < 2; ++n) _Pragma("unroll") for (int k = 0; k < 2; ++k) dst[n][k] = *(const LAS bf16x8*)(lds + PG8_SB(b, h) + boff + n * 2048 + k * 1024); } while (0)
; #define PG8_WAIT_V(n) asm volatile("s_waitcnt vmcnt(" #n ")" ::: "memory")
; #define PG8_WAIT_L(n) asm volatile("s_waitcnt lgkmcnt(" #n ")" ::: "memory")
; template <class Epi, class Sched, bool ABLK = false, bool ALIGN_EPI = true, bool SP2 = true, bool BBLK = true>
; __device__ __forceinline__ void gemm_phase(LAS unsigned char* lds, const Gemm g, const Sched& S, const Epi& E) {
;     ...
;         const bool has_next = S.next(ui + 1, nxt);
;         const int nt = cur.nt;
;         const char* nuA = has_next ? a_unit(nxt) : uA; const int ntbA = has_next ? nxt.k0 / BK : tbA; const char* nB = has_next ? (const char*)g.Bt + (size_t)nxt.pn * tstepB + b_k0(nxt.k0) : cB;
;         for (int t = 0; t < nt; t += 2) {
;             const bool last = (t == nt - 2);
;             const char* a1 = a_tile(uA, tbA + t + 1);
;             const char* a2 = last ? a_tile(nuA, ntbA) : a_tile(uA, tbA + t + 2); const char* b2 = last ? nB : cB + (size_t)(t + 2) * kstepB;
;             const char* a3 = last ? a_tile(nuA, ntbA + 1) : a_tile(uA, tbA + t + 3); const char* b3 = b2 + kstepB;
;             if (last && has_next) S.a_ready(nxt);
;             if constexpr (SP2) {
;             PG8_LDB(B0, 0, 0); PG8_LDB(B1, 0, 1); PG8_SCHED; PG8_LDA(At, 0, 0); PG8_STAGE(PG8_SA(1, 1), a1 + hstepA, voffA);
;             PG8_WAIT_V(8); PG8_WAIT_L(0); PG8_BAR; PG8_MMA(0, 0, At, B0); PG8_MMA(0, 1, At, B1); PG8_BAR; PG8_SCHED;
;             PG8_LDA(At, 0, 1); PG8_STAGE(PG8_SB(0, 0), b2, voffB); PG8_STAGE(PG8_SB(0, 1), b2 + hstepB, voffB); PG8_STAGE(PG8_SA(0, 0), a2, voffA);
;             PG8_WAIT_V(8); PG8_WAIT_L(0); PG8_BAR; PG8_MMA(1, 0, At, B0); PG8_MMA(1, 1, At, B1); PG8_BAR; PG8_SCHED;
.LBB0_474:
	s_ashr_i32 s11, s10, 31
	s_lshl_b64 s[4:5], s[10:11], 20
	s_add_u32 s14, s41, s4
	s_addc_u32 s15, s42, s5
	s_and_b64 s[4:5], s[18:19], exec
	s_cselect_b32 s4, s15, s27
	s_cselect_b32 s5, s14, s26
	s_ashr_i32 s13, s12, 31
	s_lshl_b64 s[20:21], s[12:13], 20
	s_add_u32 s20, s0, s20
	s_addc_u32 s21, s39, s21
	s_and_b64 s[30:31], s[18:19], exec
	s_cselect_b32 s11, s21, s29
	s_cselect_b32 s13, s20, s28
	s_add_u32 s23, s5, 0x80
	s_addc_u32 s57, s4, 0
	s_add_u32 s58, s28, 0x10000
	v_mov_b32_e32 v2, 0
	s_addc_u32 s59, s29, 0
	v_lshl_add_u64 v[164:165], s[26:27], 0, v[160:161]
	v_lshl_add_u64 v[166:167], s[26:27], 0, v[162:163]
	s_mov_b32 s60, -2
	s_mov_b64 s[28:29], 0
	ds_read_b128 v[172:175], v168
	ds_read_b128 v[176:179], v168 offset:1024
	ds_read_b128 v[180:183], v168 offset:2048
	ds_read_b128 v[184:187], v168 offset:3072
	ds_read_b128 v[188:191], v169
	ds_read_b128 v[192:195], v169 offset:1024
	ds_read_b128 v[196:199], v169 offset:2048
	ds_read_b128 v[200:203], v169 offset:3072
	s_add_u32 s30, s26, s28
	s_addc_u32 s31, s27, s29
	s_add_u32 s36, s30, 0x100
	s_addc_u32 s37, s31, 0
	s_add_u32 s30, s30, 0x180
	s_addc_u32 s31, s31, 0
	s_cmpk_eq_i32 s28, 0xf00
	s_cselect_b32 s31, s57, s31
	s_cselect_b32 s30, s23, s30
	s_cselect_b32 s35, s11, s59
	s_cselect_b32 s34, s13, s58
	s_cselect_b32 s37, s4, s37
	s_cselect_b32 s36, s5, s36
	s_mov_b32 m0, s53
	v_lshl_add_u64 v[236:237], v[164:165], 0, s[28:29]
	ds_read_b128 v[204:207], v170
	ds_read_b128 v[208:211], v170 offset:1024
	ds_read_b128 v[212:215], v170 offset:2048
	ds_read_b128 v[216:219], v170 offset:3072
	ds_read_b128 v[220:223], v170 offset:4096
	ds_read_b128 v[224:227], v170 offset:5120
	ds_read_b128 v[228:231], v170 offset:6144
	ds_read_b128 v[232:235], v170 offset:7168
	global_load_lds_dwordx4 v[236:237], off
	v_lshl_add_u64 v[236:237], v[166:167], 0, s[28:29]
	s_mov_b32 m0, s54
	s_nop 0
	global_load_lds_dwordx4 v[236:237], off
	s_waitcnt vmcnt(8)
	s_barrier
	s_waitcnt lgkmcnt(0)
	v_mfma_f32_16x16x32_bf16 v[126:129], v[172:175], v[204:207], 0
	v_mfma_f32_16x16x32_bf16 v[122:125], v[180:183], v[204:207], 0
	v_mfma_f32_16x16x32_bf16 v[110:113], v[172:175], v[212:215], 0
	v_mfma_f32_16x16x32_bf16 v[106:109], v[180:183], v[212:215], 0
	v_mfma_f32_16x16x32_bf16 v[94:97], v[172:175], v[220:223], 0
	v_mfma_f32_16x16x32_bf16 v[90:93], v[180:183], v[220:223], 0
	v_mfma_f32_16x16x32_bf16 v[78:81], v[172:175], v[228:231], 0
	v_mfma_f32_16x16x32_bf16 v[74:77], v[180:183], v[228:231], 0
	v_mfma_f32_16x16x32_bf16 v[126:129], v[176:179], v[208:211], v[126:129]
	v_mfma_f32_16x16x32_bf16 v[122:125], v[184:187], v[208:211], v[122:125]
	v_mfma_f32_16x16x32_bf16 v[110:113], v[176:179], v[216:219], v[110:113]
	v_mfma_f32_16x16x32_bf16 v[106:109], v[184:187], v[216:219], v[106:109]
	v_mfma_f32_16x16x32_bf16 v[94:97], v[176:179], v[224:227], v[94:97]
	v_mfma_f32_16x16x32_bf16 v[90:93], v[184:187], v[224:227], v[90:93]
	v_mfma_f32_16x16x32_bf16 v[78:81], v[176:179], v[232:235], v[78:81]
	v_mfma_f32_16x16x32_bf16 v[74:77], v[184:187], v[232:235], v[74:77]
	v_mfma_f32_16x16x32_bf16 v[118:121], v[188:191], v[204:207], 0
	v_mfma_f32_16x16x32_bf16 v[114:117], v[196:199], v[204:207], 0
	v_mfma_f32_16x16x32_bf16 v[102:105], v[188:191], v[212:215], 0
	v_mfma_f32_16x16x32_bf16 v[98:101], v[196:199], v[212:215], 0
	v_mfma_f32_16x16x32_bf16 v[86:89], v[188:191], v[220:223], 0
	v_mfma_f32_16x16x32_bf16 v[82:85], v[196:199], v[220:223], 0
	v_mfma_f32_16x16x32_bf16 v[70:73], v[188:191], v[228:231], 0
	v_mfma_f32_16x16x32_bf16 v[66:69], v[196:199], v[228:231], 0
	v_mfma_f32_16x16x32_bf16 v[118:121], v[192:195], v[208:211], v[118:121]
	v_mfma_f32_16x16x32_bf16 v[114:117], v[200:203], v[208:211], v[114:117]
	v_mfma_f32_16x16x32_bf16 v[102:105], v[192:195], v[216:219], v[102:105]
	v_mfma_f32_16x16x32_bf16 v[98:101], v[200:203], v[216:219], v[98:101]
	v_mfma_f32_16x16x32_bf16 v[86:89], v[192:195], v[224:227], v[86:89]
	v_mfma_f32_16x16x32_bf16 v[82:85], v[200:203], v[224:227], v[82:85]
	v_mfma_f32_16x16x32_bf16 v[70:73], v[192:195], v[232:235], v[70:73]
	v_mfma_f32_16x16x32_bf16 v[66:69], v[200:203], v[232:235], v[66:69]
	s_barrier
	s_mov_b32 m0, s55
	s_add_u32 s62, s34, 0x4000
	ds_read_b128 v[204:207], v170 offset:16384
	ds_read_b128 v[208:211], v170 offset:17408
	ds_read_b128 v[212:215], v170 offset:18432
	ds_read_b128 v[216:219], v170 offset:19456
	ds_read_b128 v[220:223], v170 offset:20480
	ds_read_b128 v[224:227], v170 offset:21504
	ds_read_b128 v[228:231], v170 offset:22528
	ds_read_b128 v[232:235], v170 offset:23552
	global_load_lds_dwordx4 v134, s[34:35]
	s_mov_b32 m0, s56
	s_addc_u32 s63, s35, 0
	s_add_i32 s61, s52, s40
	global_load_lds_dwordx4 v130, s[34:35]
	s_mov_b32 m0, s61
	s_nop 0
	global_load_lds_dwordx4 v134, s[62:63]
	s_add_i32 m0, s61, 0x2000
	s_nop 0
	global_load_lds_dwordx4 v130, s[62:63]
	s_mov_b32 m0, s25
	s_nop 0
	global_load_lds_dwordx4 v136, s[36:37]
	s_mov_b32 m0, s43
	s_nop 0
	global_load_lds_dwordx4 v132, s[36:37]
	s_waitcnt vmcnt(8)
	s_barrier
; #define PG8_STAGE(bufoff, gbase, voff) do { _Pragma("unroll") for (int _i = 0; _i < 2; ++_i) \
;         __builtin_amdgcn_global_load_lds((const unsigned*)((const char*)(gbase) + (voff)[_i]), (LAS unsigned*)(lds + (bufoff) + ldsw + _i * 8192), 16, 0, 0); } while (0)
; #define PG8_LDA(dst, b, h) do { _Pragma("unroll") for (int m = 0; m < 4; ++m) _Pragma("unroll") for (int k = 0; k < 2; ++k) dst[m][k] = *(const LAS bf16x8*)(lds + PG8_SA(b, h) + aoff + m * 2048 + k * 1024); } while (0)
; #define PG8_LDB(dst, b, h) do { _Pragma("unroll") for (int n = 0; n < 2; ++n) _Pragma("unroll") for (int k = 0; k < 2; ++k) dst[n][k] = *(const LAS bf16x8*)(lds + PG8_SB(b, h) + boff + n * 2048 + k * 1024); } while (0)
; #define PG8_MMA(ai, bj, At, Bt) do { __builtin_amdgcn_s_setprio(1); _Pragma("unroll") for (int m = 0; m < 4; ++m) _Pragma("unroll") for (int n = 0; n < 2; ++n) _Pragma("unroll") for (int k = 0; k < 2; ++k) \
;         acc[ai][bj][m][n] = __builtin_amdgcn_mfma_f32_16x16x32_bf16(Bt[n][k], At[m][k], acc[ai][bj][m][n], 0, 0, 0); __builtin_amdgcn_s_setprio(0); } while (0)
; #define PG8_WAIT_V(n) asm volatile("s_waitcnt vmcnt(" #n ")" ::: "memory")
; #define PG8_WAIT_L(n) asm volatile("s_waitcnt lgkmcnt(" #n ")" ::: "memory")
; #define PG8_BAR __builtin_amdgcn_s_barrier()
; #define PG8_SCHED __builtin_amdgcn_sched_barrier(0)
; template <class Epi, class Sched, bool ABLK = false, bool ALIGN_EPI = true, bool SP2 = true, bool BBLK = true>
; __device__ __forceinline__ void gemm_phase(LAS unsigned char* lds, const Gemm g, const Sched& S, const Epi& E) {
;     ...
;             PG8_LDA(At, 0, 1); PG8_STAGE(PG8_SB(0, 0), b2, voffB); PG8_STAGE(PG8_SB(0, 1), b2 + hstepB, voffB); PG8_STAGE(PG8_SA(0, 0), a2, voffA);
;             PG8_WAIT_V(8); PG8_WAIT_L(0); PG8_BAR; PG8_MMA(1, 0, At, B0); PG8_MMA(1, 1, At, B1); PG8_BAR; PG8_SCHED;
;             PG8_LDB(B0, 1, 0); PG8_LDB(B1, 1, 1); PG8_SCHED; PG8_LDA(At, 1, 0); PG8_STAGE(PG8_SA(0, 1), a2 + hstepA, voffA);
;             PG8_WAIT_V(8); PG8_WAIT_L(0); PG8_BAR; PG8_MMA(0, 0, At, B0); PG8_MMA(0, 1, At, B1); PG8_BAR; PG8_SCHED;
	s_waitcnt lgkmcnt(0)
	v_mfma_f32_16x16x32_bf16 v[62:65], v[172:175], v[204:207], 0
	v_mfma_f32_16x16x32_bf16 v[58:61], v[180:183], v[204:207], 0
	v_mfma_f32_16x16x32_bf16 v[46:49], v[172:175], v[212:215], 0
	v_mfma_f32_16x16x32_bf16 v[42:45], v[180:183], v[212:215], 0
	v_mfma_f32_16x16x32_bf16 v[30:33], v[172:175], v[220:223], 0
	v_mfma_f32_16x16x32_bf16 v[26:29], v[180:183], v[220:223], 0
	v_mfma_f32_16x16x32_bf16 v[14:17], v[172:175], v[228:231], 0
	v_mfma_f32_16x16x32_bf16 v[10:13], v[180:183], v[228:231], 0
	v_mfma_f32_16x16x32_bf16 v[62:65], v[176:179], v[208:211], v[62:65]
	v_mfma_f32_16x16x32_bf16 v[58:61], v[184:187], v[208:211], v[58:61]
	v_mfma_f32_16x16x32_bf16 v[46:49], v[176:179], v[216:219], v[46:49]
	v_mfma_f32_16x16x32_bf16 v[42:45], v[184:187], v[216:219], v[42:45]
	v_mfma_f32_16x16x32_bf16 v[30:33], v[176:179], v[224:227], v[30:33]
	v_mfma_f32_16x16x32_bf16 v[26:29], v[184:187], v[224:227], v[26:29]
	v_mfma_f32_16x16x32_bf16 v[14:17], v[176:179], v[232:235], v[14:17]
	v_mfma_f32_16x16x32_bf16 v[10:13], v[184:187], v[232:235], v[10:13]
	v_mfma_f32_16x16x32_bf16 v[54:57], v[188:191], v[204:207], 0
	v_mfma_f32_16x16x32_bf16 v[50:53], v[196:199], v[204:207], 0
	v_mfma_f32_16x16x32_bf16 v[38:41], v[188:191], v[212:215], 0
	v_mfma_f32_16x16x32_bf16 v[34:37], v[196:199], v[212:215], 0
	v_mfma_f32_16x16x32_bf16 v[22:25], v[188:191], v[220:223], 0
	v_mfma_f32_16x16x32_bf16 v[18:21], v[196:199], v[220:223], 0
	v_mfma_f32_16x16x32_bf16 v[6:9], v[188:191], v[228:231], 0
	v_mfma_f32_16x16x32_bf16 v[2:5], v[196:199], v[228:231], 0
	v_mfma_f32_16x16x32_bf16 v[54:57], v[192:195], v[208:211], v[54:57]
	v_mfma_f32_16x16x32_bf16 v[50:53], v[200:203], v[208:211], v[50:53]
	v_mfma_f32_16x16x32_bf16 v[38:41], v[192:195], v[216:219], v[38:41]
	v_mfma_f32_16x16x32_bf16 v[34:37], v[200:203], v[216:219], v[34:37]
	v_mfma_f32_16x16x32_bf16 v[22:25], v[192:195], v[224:227], v[22:25]
	v_mfma_f32_16x16x32_bf16 v[18:21], v[200:203], v[224:227], v[18:21]
	v_mfma_f32_16x16x32_bf16 v[6:9], v[192:195], v[232:235], v[6:9]
	v_mfma_f32_16x16x32_bf16 v[2:5], v[200:203], v[232:235], v[2:5]
	s_barrier
	s_add_i32 s61, 0, 0x18000
	v_add_u32_e32 v171, s61, v1
	s_add_i32 s62, 0, 0x1c000
	ds_read_b128 v[172:175], v171
	ds_read_b128 v[176:179], v171 offset:1024
	ds_read_b128 v[180:183], v171 offset:2048
	ds_read_b128 v[184:187], v171 offset:3072
	v_add_u32_e32 v171, s62, v1
	ds_read_b128 v[188:191], v171
	ds_read_b128 v[192:195], v171 offset:1024
	ds_read_b128 v[196:199], v171 offset:2048
	ds_read_b128 v[200:203], v171 offset:3072
	s_add_u32 s36, s36, 0x80000
	s_addc_u32 s37, s37, 0
	s_mov_b32 m0, s46
	ds_read_b128 v[204:207], v170 offset:32768
	ds_read_b128 v[208:211], v170 offset:33792
	ds_read_b128 v[212:215], v170 offset:34816
	ds_read_b128 v[216:219], v170 offset:35840
	ds_read_b128 v[220:223], v170 offset:36864
	ds_read_b128 v[224:227], v170 offset:37888
	ds_read_b128 v[228:231], v170 offset:38912
	ds_read_b128 v[232:235], v170 offset:39936
	global_load_lds_dwordx4 v136, s[36:37]
	s_mov_b32 m0, s47
	s_nop 0
	global_load_lds_dwordx4 v132, s[36:37]
	s_waitcnt vmcnt(8)
	s_barrier
	s_waitcnt lgkmcnt(0)
	v_mfma_f32_16x16x32_bf16 v[126:129], v[172:175], v[204:207], v[126:129]
	v_mfma_f32_16x16x32_bf16 v[122:125], v[180:183], v[204:207], v[122:125]
	v_mfma_f32_16x16x32_bf16 v[110:113], v[172:175], v[212:215], v[110:113]
	v_mfma_f32_16x16x32_bf16 v[106:109], v[180:183], v[212:215], v[106:109]
	v_mfma_f32_16x16x32_bf16 v[94:97], v[172:175], v[220:223], v[94:97]
	v_mfma_f32_16x16x32_bf16 v[90:93], v[180:183], v[220:223], v[90:93]
	v_mfma_f32_16x16x32_bf16 v[78:81], v[172:175], v[228:231], v[78:81]
	v_mfma_f32_16x16x32_bf16 v[74:77], v[180:183], v[228:231], v[74:77]
	v_mfma_f32_16x16x32_bf16 v[126:129], v[176:179], v[208:211], v[126:129]
	v_mfma_f32_16x16x32_bf16 v[122:125], v[184:187], v[208:211], v[122:125]
	v_mfma_f32_16x16x32_bf16 v[110:113], v[176:179], v[216:219], v[110:113]
	v_mfma_f32_16x16x32_bf16 v[106:109], v[184:187], v[216:219], v[106:109]
	v_mfma_f32_16x16x32_bf16 v[94:97], v[176:179], v[224:227], v[94:97]
	v_mfma_f32_16x16x32_bf16 v[90:93], v[184:187], v[224:227], v[90:93]
	v_mfma_f32_16x16x32_bf16 v[78:81], v[176:179], v[232:235], v[78:81]
	v_mfma_f32_16x16x32_bf16 v[74:77], v[184:187], v[232:235], v[74:77]
	v_mfma_f32_16x16x32_bf16 v[118:121], v[188:191], v[204:207], v[118:121]
	v_mfma_f32_16x16x32_bf16 v[114:117], v[196:199], v[204:207], v[114:117]
	v_mfma_f32_16x16x32_bf16 v[102:105], v[188:191], v[212:215], v[102:105]
	v_mfma_f32_16x16x32_bf16 v[98:101], v[196:199], v[212:215], v[98:101]
	v_mfma_f32_16x16x32_bf16 v[86:89], v[188:191], v[220:223], v[86:89]
	v_mfma_f32_16x16x32_bf16 v[82:85], v[196:199], v[220:223], v[82:85]
	v_mfma_f32_16x16x32_bf16 v[70:73], v[188:191], v[228:231], v[70:73]
	v_mfma_f32_16x16x32_bf16 v[66:69], v[196:199], v[228:231], v[66:69]
	v_mfma_f32_16x16x32_bf16 v[118:121], v[192:195], v[208:211], v[118:121]
	v_mfma_f32_16x16x32_bf16 v[114:117], v[200:203], v[208:211], v[114:117]
	v_mfma_f32_16x16x32_bf16 v[102:105], v[192:195], v[216:219], v[102:105]
	v_mfma_f32_16x16x32_bf16 v[98:101], v[200:203], v[216:219], v[98:101]
	v_mfma_f32_16x16x32_bf16 v[86:89], v[192:195], v[224:227], v[86:89]
	v_mfma_f32_16x16x32_bf16 v[82:85], v[200:203], v[224:227], v[82:85]
	v_mfma_f32_16x16x32_bf16 v[70:73], v[192:195], v[232:235], v[70:73]
	v_mfma_f32_16x16x32_bf16 v[66:69], v[200:203], v[232:235], v[66:69]
	s_barrier
; #define PG8_STAGE(bufoff, gbase, voff) do { _Pragma("unroll") for (int _i = 0; _i < 2; ++_i) \
;         __builtin_amdgcn_global_load_lds((const unsigned*)((const char*)(gbase) + (voff)[_i]), (LAS unsigned*)(lds + (bufoff) + ldsw + _i * 8192), 16, 0, 0); } while (0)
; #define PG8_LDA(dst, b, h) do { _Pragma("unroll") for (int m = 0; m < 4; ++m) _Pragma("unroll") for (int k = 0; k < 2; ++k) dst[m][k] = *(const LAS bf16x8*)(lds + PG8_SA(b, h) + aoff + m * 2048 + k * 1024); } while (0)
; #define PG8_WAIT_V(n) asm volatile("s_waitcnt vmcnt(" #n ")" ::: "memory")
; #define PG8_WAIT_L(n) asm volatile("s_waitcnt lgkmcnt(" #n ")" ::: "memory")
; template <class Epi, class Sched, bool ABLK = false, bool ALIGN_EPI = true, bool SP2 = true, bool BBLK = true>
; __device__ __forceinline__ void gemm_phase(LAS unsigned char* lds, const Gemm g, const Sched& S, const Epi& E) {
;     ...
;         for (int t = 0; t < nt; t += 2) {
;             const bool last = (t == nt - 2);
;             const char* a1 = a_tile(uA, tbA + t + 1);
;             const char* a2 = last ? a_tile(nuA, ntbA) : a_tile(uA, tbA + t + 2); const char* b2 = last ? nB : cB + (size_t)(t + 2) * kstepB;
;             const char* a3 = last ? a_tile(nuA, ntbA + 1) : a_tile(uA, tbA + t + 3); const char* b3 = b2 + kstepB;
;             if (last && has_next) S.a_ready(nxt);
;             if constexpr (SP2) {
;             PG8_LDB(B0, 0, 0); PG8_LDB(B1, 0, 1); PG8_SCHED; PG8_LDA(At, 0, 0); PG8_STAGE(PG8_SA(1, 1), a1 + hstepA, voffA);
;             PG8_WAIT_V(8); PG8_WAIT_L(0); PG8_BAR; PG8_MMA(0, 0, At, B0); PG8_MMA(0, 1, At, B1); PG8_BAR; PG8_SCHED;
;             PG8_LDA(At, 0, 1); PG8_STAGE(PG8_SB(0, 0), b2, voffB); PG8_STAGE(PG8_SB(0, 1), b2 + hstepB, voffB); PG8_STAGE(PG8_SA(0, 0), a2, voffA);
;             PG8_WAIT_V(8); PG8_WAIT_L(0); PG8_BAR; PG8_MMA(1, 0, At, B0); PG8_MMA(1, 1, At, B1); PG8_BAR; PG8_SCHED;
;             PG8_LDB(B0, 1, 0); PG8_LDB(B1, 1, 1); PG8_SCHED; PG8_LDA(At, 1, 0); PG8_STAGE(PG8_SA(0, 1), a2 + hstepA, voffA);
;             PG8_WAIT_V(8); PG8_WAIT_L(0); PG8_BAR; PG8_MMA(0, 0, At, B0); PG8_MMA(0, 1, At, B1); PG8_BAR; PG8_SCHED;
;             PG8_LDA(At, 1, 1); PG8_STAGE(PG8_SB(1, 0), b3, voffB); PG8_STAGE(PG8_SB(1, 1), b3 + hstepB, voffB); PG8_STAGE(PG8_SA(1, 0), a3, voffA);
;             PG8_WAIT_V(8); PG8_WAIT_L(0); PG8_BAR; PG8_MMA(1, 0, At, B0); PG8_MMA(1, 1, At, B1); PG8_BAR; PG8_SCHED;
	s_add_u32 s36, s34, 0x8000
	s_addc_u32 s37, s35, 0
	s_add_i32 s61, s61, s40
	s_mov_b32 m0, s61
	ds_read_b128 v[204:207], v170 offset:49152
	ds_read_b128 v[208:211], v170 offset:50176
	ds_read_b128 v[212:215], v170 offset:51200
	ds_read_b128 v[216:219], v170 offset:52224
	ds_read_b128 v[220:223], v170 offset:53248
	ds_read_b128 v[224:227], v170 offset:54272
	ds_read_b128 v[228:231], v170 offset:55296
	ds_read_b128 v[232:235], v170 offset:56320
	global_load_lds_dwordx4 v134, s[36:37]
	s_add_i32 m0, s61, 0x2000
	s_add_u32 s34, s34, 0xc000
	v_lshl_add_u64 v[236:237], s[36:37], 0, v[130:131]
	s_addc_u32 s35, s35, 0
	s_add_i32 s36, s62, s40
	global_load_lds_dwordx4 v[236:237], off
	s_mov_b32 m0, s36
	s_nop 0
	global_load_lds_dwordx4 v134, s[34:35]
	s_add_i32 m0, s36, 0x2000
	s_nop 0
	global_load_lds_dwordx4 v130, s[34:35]
	s_mov_b32 m0, s50
	s_nop 0
	global_load_lds_dwordx4 v136, s[30:31]
	s_mov_b32 m0, s51
	s_nop 0
	global_load_lds_dwordx4 v132, s[30:31]
	s_waitcnt vmcnt(8)
	s_barrier
	s_waitcnt lgkmcnt(0)
	v_mfma_f32_16x16x32_bf16 v[62:65], v[172:175], v[204:207], v[62:65]
	v_mfma_f32_16x16x32_bf16 v[58:61], v[180:183], v[204:207], v[58:61]
	v_mfma_f32_16x16x32_bf16 v[46:49], v[172:175], v[212:215], v[46:49]
	v_mfma_f32_16x16x32_bf16 v[42:45], v[180:183], v[212:215], v[42:45]
	v_mfma_f32_16x16x32_bf16 v[30:33], v[172:175], v[220:223], v[30:33]
	v_mfma_f32_16x16x32_bf16 v[26:29], v[180:183], v[220:223], v[26:29]
	v_mfma_f32_16x16x32_bf16 v[14:17], v[172:175], v[228:231], v[14:17]
	v_mfma_f32_16x16x32_bf16 v[10:13], v[180:183], v[228:231], v[10:13]
	v_mfma_f32_16x16x32_bf16 v[62:65], v[176:179], v[208:211], v[62:65]
	v_mfma_f32_16x16x32_bf16 v[58:61], v[184:187], v[208:211], v[58:61]
	v_mfma_f32_16x16x32_bf16 v[46:49], v[176:179], v[216:219], v[46:49]
	v_mfma_f32_16x16x32_bf16 v[42:45], v[184:187], v[216:219], v[42:45]
	v_mfma_f32_16x16x32_bf16 v[30:33], v[176:179], v[224:227], v[30:33]
	v_mfma_f32_16x16x32_bf16 v[26:29], v[184:187], v[224:227], v[26:29]
	v_mfma_f32_16x16x32_bf16 v[14:17], v[176:179], v[232:235], v[14:17]
	v_mfma_f32_16x16x32_bf16 v[10:13], v[184:187], v[232:235], v[10:13]
	v_mfma_f32_16x16x32_bf16 v[54:57], v[188:191], v[204:207], v[54:57]
	v_mfma_f32_16x16x32_bf16 v[50:53], v[196:199], v[204:207], v[50:53]
	v_mfma_f32_16x16x32_bf16 v[38:41], v[188:191], v[212:215], v[38:41]
	v_mfma_f32_16x16x32_bf16 v[34:37], v[196:199], v[212:215], v[34:37]
	v_mfma_f32_16x16x32_bf16 v[22:25], v[188:191], v[220:223], v[22:25]
	v_mfma_f32_16x16x32_bf16 v[18:21], v[196:199], v[220:223], v[18:21]
	v_mfma_f32_16x16x32_bf16 v[6:9], v[188:191], v[228:231], v[6:9]
	v_mfma_f32_16x16x32_bf16 v[2:5], v[196:199], v[228:231], v[2:5]
	v_mfma_f32_16x16x32_bf16 v[54:57], v[192:195], v[208:211], v[54:57]
	v_mfma_f32_16x16x32_bf16 v[50:53], v[200:203], v[208:211], v[50:53]
	v_mfma_f32_16x16x32_bf16 v[38:41], v[192:195], v[216:219], v[38:41]
	v_mfma_f32_16x16x32_bf16 v[34:37], v[200:203], v[216:219], v[34:37]
	v_mfma_f32_16x16x32_bf16 v[22:25], v[192:195], v[224:227], v[22:25]
	v_mfma_f32_16x16x32_bf16 v[18:21], v[200:203], v[224:227], v[18:21]
	v_mfma_f32_16x16x32_bf16 v[6:9], v[192:195], v[232:235], v[6:9]
	v_mfma_f32_16x16x32_bf16 v[2:5], v[200:203], v[232:235], v[2:5]
	s_barrier
	s_add_i32 s60, s60, 2
	s_add_u32 s28, s28, 0x100
	s_addc_u32 s29, s29, 0
	s_add_u32 s58, s58, 0x10000
	s_addc_u32 s59, s59, 0
	s_cmp_gt_u32 s60, 29
.LBB0_475:
	ds_read_b128 v[172:175], v168
	ds_read_b128 v[176:179], v168 offset:1024
	ds_read_b128 v[180:183], v168 offset:2048
	ds_read_b128 v[184:187], v168 offset:3072
	ds_read_b128 v[188:191], v169
	ds_read_b128 v[192:195], v169 offset:1024
	ds_read_b128 v[196:199], v169 offset:2048
	ds_read_b128 v[200:203], v169 offset:3072
	s_add_u32 s30, s26, s28
	s_addc_u32 s31, s27, s29
	s_add_u32 s36, s30, 0x100
	s_addc_u32 s37, s31, 0
	s_add_u32 s30, s30, 0x180
	s_addc_u32 s31, s31, 0
	s_cmpk_eq_i32 s28, 0xf00
	s_cselect_b32 s31, s57, s31
	s_cselect_b32 s30, s23, s30
	s_cselect_b32 s35, s11, s59
	s_cselect_b32 s34, s13, s58
	s_cselect_b32 s37, s4, s37
	s_cselect_b32 s36, s5, s36
	s_mov_b32 m0, s53
	v_lshl_add_u64 v[236:237], v[164:165], 0, s[28:29]
	ds_read_b128 v[204:207], v170
	ds_read_b128 v[208:211], v170 offset:1024
	ds_read_b128 v[212:215], v170 offset:2048
	ds_read_b128 v[216:219], v170 offset:3072
	ds_read_b128 v[220:223], v170 offset:4096
	ds_read_b128 v[224:227], v170 offset:5120
	ds_read_b128 v[228:231], v170 offset:6144
	ds_read_b128 v[232:235], v170 offset:7168
	global_load_lds_dwordx4 v[236:237], off
	v_lshl_add_u64 v[236:237], v[166:167], 0, s[28:29]
	s_mov_b32 m0, s54
	s_nop 0
	global_load_lds_dwordx4 v[236:237], off
	s_waitcnt vmcnt(8)
	s_barrier
; #define PG8_STAGE(bufoff, gbase, voff) do { _Pragma("unroll") for (int _i = 0; _i < 2; ++_i) \
;         __builtin_amdgcn_global_load_lds((const unsigned*)((const char*)(gbase) + (voff)[_i]), (LAS unsigned*)(lds + (bufoff) + ldsw + _i * 8192), 16, 0, 0); } while (0)
; #define PG8_LDA(dst, b, h) do { _Pragma("unroll") for (int m = 0; m < 4; ++m) _Pragma("unroll") for (int k = 0; k < 2; ++k) dst[m][k] = *(const LAS bf16x8*)(lds + PG8_SA(b, h) + aoff + m * 2048 + k * 1024); } while (0)
; #define PG8_LDB(dst, b, h) do { _Pragma("unroll") for (int n = 0; n < 2; ++n) _Pragma("unroll") for (int k = 0; k < 2; ++k) dst[n][k] = *(const LAS bf16x8*)(lds + PG8_SB(b, h) + boff + n * 2048 + k * 1024); } while (0)
; #define PG8_MMA(ai, bj, At, Bt) do { __builtin_amdgcn_s_setprio(1); _Pragma("unroll") for (int m = 0; m < 4; ++m) _Pragma("unroll") for (int n = 0; n < 2; ++n) _Pragma("unroll") for (int k = 0; k < 2; ++k) \
;         acc[ai][bj][m][n] = __builtin_amdgcn_mfma_f32_16x16x32_bf16(Bt[n][k], At[m][k], acc[ai][bj][m][n], 0, 0, 0); __builtin_amdgcn_s_setprio(0); } while (0)
; #define PG8_WAIT_V(n) asm volatile("s_waitcnt vmcnt(" #n ")" ::: "memory")
; #define PG8_WAIT_L(n) asm volatile("s_waitcnt lgkmcnt(" #n ")" ::: "memory")
; #define PG8_BAR __builtin_amdgcn_s_barrier()
; #define PG8_SCHED __builtin_amdgcn_sched_barrier(0)
; template <class Epi, class Sched, bool ABLK = false, bool ALIGN_EPI = true, bool SP2 = true, bool BBLK = true>
; __device__ __forceinline__ void gemm_phase(LAS unsigned char* lds, const Gemm g, const Sched& S, const Epi& E) {
;     ...
;             PG8_LDB(B0, 0, 0); PG8_LDB(B1, 0, 1); PG8_SCHED; PG8_LDA(At, 0, 0); PG8_STAGE(PG8_SA(1, 1), a1 + hstepA, voffA);
;             PG8_WAIT_V(8); PG8_WAIT_L(0); PG8_BAR; PG8_MMA(0, 0, At, B0); PG8_MMA(0, 1, At, B1); PG8_BAR; PG8_SCHED;
;             PG8_LDA(At, 0, 1); PG8_STAGE(PG8_SB(0, 0), b2, voffB); PG8_STAGE(PG8_SB(0, 1), b2 + hstepB, voffB); PG8_STAGE(PG8_SA(0, 0), a2, voffA);
;             PG8_WAIT_V(8); PG8_WAIT_L(0); PG8_BAR; PG8_MMA(1, 0, At, B0); PG8_MMA(1, 1, At, B1); PG8_BAR; PG8_SCHED;
	s_waitcnt lgkmcnt(0)
	v_mfma_f32_16x16x32_bf16 v[126:129], v[172:175], v[204:207], v[126:129]
	v_mfma_f32_16x16x32_bf16 v[122:125], v[180:183], v[204:207], v[122:125]
	v_mfma_f32_16x16x32_bf16 v[110:113], v[172:175], v[212:215], v[110:113]
	v_mfma_f32_16x16x32_bf16 v[106:109], v[180:183], v[212:215], v[106:109]
	v_mfma_f32_16x16x32_bf16 v[94:97], v[172:175], v[220:223], v[94:97]
	v_mfma_f32_16x16x32_bf16 v[90:93], v[180:183], v[220:223], v[90:93]
	v_mfma_f32_16x16x32_bf16 v[78:81], v[172:175], v[228:231], v[78:81]
	v_mfma_f32_16x16x32_bf16 v[74:77], v[180:183], v[228:231], v[74:77]
	v_mfma_f32_16x16x32_bf16 v[126:129], v[176:179], v[208:211], v[126:129]
	v_mfma_f32_16x16x32_bf16 v[122:125], v[184:187], v[208:211], v[122:125]
	v_mfma_f32_16x16x32_bf16 v[110:113], v[176:179], v[216:219], v[110:113]
	v_mfma_f32_16x16x32_bf16 v[106:109], v[184:187], v[216:219], v[106:109]
	v_mfma_f32_16x16x32_bf16 v[94:97], v[176:179], v[224:227], v[94:97]
	v_mfma_f32_16x16x32_bf16 v[90:93], v[184:187], v[224:227], v[90:93]
	v_mfma_f32_16x16x32_bf16 v[78:81], v[176:179], v[232:235], v[78:81]
	v_mfma_f32_16x16x32_bf16 v[74:77], v[184:187], v[232:235], v[74:77]
	v_mfma_f32_16x16x32_bf16 v[118:121], v[188:191], v[204:207], v[118:121]
	v_mfma_f32_16x16x32_bf16 v[114:117], v[196:199], v[204:207], v[114:117]
	v_mfma_f32_16x16x32_bf16 v[102:105], v[188:191], v[212:215], v[102:105]
	v_mfma_f32_16x16x32_bf16 v[98:101], v[196:199], v[212:215], v[98:101]
	v_mfma_f32_16x16x32_bf16 v[86:89], v[188:191], v[220:223], v[86:89]
	v_mfma_f32_16x16x32_bf16 v[82:85], v[196:199], v[220:223], v[82:85]
	v_mfma_f32_16x16x32_bf16 v[70:73], v[188:191], v[228:231], v[70:73]
	v_mfma_f32_16x16x32_bf16 v[66:69], v[196:199], v[228:231], v[66:69]
	v_mfma_f32_16x16x32_bf16 v[118:121], v[192:195], v[208:211], v[118:121]
	v_mfma_f32_16x16x32_bf16 v[114:117], v[200:203], v[208:211], v[114:117]
	v_mfma_f32_16x16x32_bf16 v[102:105], v[192:195], v[216:219], v[102:105]
	v_mfma_f32_16x16x32_bf16 v[98:101], v[200:203], v[216:219], v[98:101]
	v_mfma_f32_16x16x32_bf16 v[86:89], v[192:195], v[224:227], v[86:89]
	v_mfma_f32_16x16x32_bf16 v[82:85], v[200:203], v[224:227], v[82:85]
	v_mfma_f32_16x16x32_bf16 v[70:73], v[192:195], v[232:235], v[70:73]
	v_mfma_f32_16x16x32_bf16 v[66:69], v[200:203], v[232:235], v[66:69]
	s_barrier
	s_mov_b32 m0, s55
	s_add_u32 s62, s34, 0x4000
	ds_read_b128 v[204:207], v170 offset:16384
	ds_read_b128 v[208:211], v170 offset:17408
	ds_read_b128 v[212:215], v170 offset:18432
	ds_read_b128 v[216:219], v170 offset:19456
	ds_read_b128 v[220:223], v170 offset:20480
	ds_read_b128 v[224:227], v170 offset:21504
	ds_read_b128 v[228:231], v170 offset:22528
	ds_read_b128 v[232:235], v170 offset:23552
	global_load_lds_dwordx4 v134, s[34:35]
	s_mov_b32 m0, s56
	s_addc_u32 s63, s35, 0
	s_add_i32 s61, s52, s40
	global_load_lds_dwordx4 v130, s[34:35]
	s_mov_b32 m0, s61
	s_nop 0
	global_load_lds_dwordx4 v134, s[62:63]
	s_add_i32 m0, s61, 0x2000
	s_nop 0
	global_load_lds_dwordx4 v130, s[62:63]
	s_mov_b32 m0, s25
	s_nop 0
	global_load_lds_dwordx4 v136, s[36:37]
	s_mov_b32 m0, s43
	s_nop 0
	global_load_lds_dwordx4 v132, s[36:37]
	s_waitcnt vmcnt(8)
	s_barrier
	s_waitcnt lgkmcnt(0)
	v_mfma_f32_16x16x32_bf16 v[62:65], v[172:175], v[204:207], v[62:65]
	v_mfma_f32_16x16x32_bf16 v[58:61], v[180:183], v[204:207], v[58:61]
	v_mfma_f32_16x16x32_bf16 v[46:49], v[172:175], v[212:215], v[46:49]
	v_mfma_f32_16x16x32_bf16 v[42:45], v[180:183], v[212:215], v[42:45]
	v_mfma_f32_16x16x32_bf16 v[30:33], v[172:175], v[220:223], v[30:33]
	v_mfma_f32_16x16x32_bf16 v[26:29], v[180:183], v[220:223], v[26:29]
	v_mfma_f32_16x16x32_bf16 v[14:17], v[172:175], v[228:231], v[14:17]
	v_mfma_f32_16x16x32_bf16 v[10:13], v[180:183], v[228:231], v[10:13]
	v_mfma_f32_16x16x32_bf16 v[62:65], v[176:179], v[208:211], v[62:65]
	v_mfma_f32_16x16x32_bf16 v[58:61], v[184:187], v[208:211], v[58:61]
	v_mfma_f32_16x16x32_bf16 v[46:49], v[176:179], v[216:219], v[46:49]
	v_mfma_f32_16x16x32_bf16 v[42:45], v[184:187], v[216:219], v[42:45]
	v_mfma_f32_16x16x32_bf16 v[30:33], v[176:179], v[224:227], v[30:33]
	v_mfma_f32_16x16x32_bf16 v[26:29], v[184:187], v[224:227], v[26:29]
	v_mfma_f32_16x16x32_bf16 v[14:17], v[176:179], v[232:235], v[14:17]
	v_mfma_f32_16x16x32_bf16 v[10:13], v[184:187], v[232:235], v[10:13]
	v_mfma_f32_16x16x32_bf16 v[54:57], v[188:191], v[204:207], v[54:57]
	v_mfma_f32_16x16x32_bf16 v[50:53], v[196:199], v[204:207], v[50:53]
	v_mfma_f32_16x16x32_bf16 v[38:41], v[188:191], v[212:215], v[38:41]
	v_mfma_f32_16x16x32_bf16 v[34:37], v[196:199], v[212:215], v[34:37]
	v_mfma_f32_16x16x32_bf16 v[22:25], v[188:191], v[220:223], v[22:25]
	v_mfma_f32_16x16x32_bf16 v[18:21], v[196:199], v[220:223], v[18:21]
	v_mfma_f32_16x16x32_bf16 v[6:9], v[188:191], v[228:231], v[6:9]
	v_mfma_f32_16x16x32_bf16 v[2:5], v[196:199], v[228:231], v[2:5]
	v_mfma_f32_16x16x32_bf16 v[54:57], v[192:195], v[208:211], v[54:57]
	v_mfma_f32_16x16x32_bf16 v[50:53], v[200:203], v[208:211], v[50:53]
	v_mfma_f32_16x16x32_bf16 v[38:41], v[192:195], v[216:219], v[38:41]
	v_mfma_f32_16x16x32_bf16 v[34:37], v[200:203], v[216:219], v[34:37]
	v_mfma_f32_16x16x32_bf16 v[22:25], v[192:195], v[224:227], v[22:25]
	v_mfma_f32_16x16x32_bf16 v[18:21], v[200:203], v[224:227], v[18:21]
	v_mfma_f32_16x16x32_bf16 v[6:9], v[192:195], v[232:235], v[6:9]
	v_mfma_f32_16x16x32_bf16 v[2:5], v[200:203], v[232:235], v[2:5]
	s_barrier
; #define PG8_STAGE(bufoff, gbase, voff) do { _Pragma("unroll") for (int _i = 0; _i < 2; ++_i) \
;         __builtin_amdgcn_global_load_lds((const unsigned*)((const char*)(gbase) + (voff)[_i]), (LAS unsigned*)(lds + (bufoff) + ldsw + _i * 8192), 16, 0, 0); } while (0)
; #define PG8_LDA(dst, b, h) do { _Pragma("unroll") for (int m = 0; m < 4; ++m) _Pragma("unroll") for (int k = 0; k < 2; ++k) dst[m][k] = *(const LAS bf16x8*)(lds + PG8_SA(b, h) + aoff + m * 2048 + k * 1024); } while (0)
; #define PG8_LDB(dst, b, h) do { _Pragma("unroll") for (int n = 0; n < 2; ++n) _Pragma("unroll") for (int k = 0; k < 2; ++k) dst[n][k] = *(const LAS bf16x8*)(lds + PG8_SB(b, h) + boff + n * 2048 + k * 1024); } while (0)
; #define PG8_MMA(ai, bj, At, Bt) do { __builtin_amdgcn_s_setprio(1); _Pragma("unroll") for (int m = 0; m < 4; ++m) _Pragma("unroll") for (int n = 0; n < 2; ++n) _Pragma("unroll") for (int k = 0; k < 2; ++k) \
;         acc[ai][bj][m][n] = __builtin_amdgcn_mfma_f32_16x16x32_bf16(Bt[n][k], At[m][k], acc[ai][bj][m][n], 0, 0, 0); __builtin_amdgcn_s_setprio(0); } while (0)
; #define PG8_WAIT_V(n) asm volatile("s_waitcnt vmcnt(" #n ")" ::: "memory")
; #define PG8_WAIT_L(n) asm volatile("s_waitcnt lgkmcnt(" #n ")" ::: "memory")
; #define PG8_BAR __builtin_amdgcn_s_barrier()
; #define PG8_SCHED __builtin_amdgcn_sched_barrier(0)
; template <class Epi, class Sched, bool ABLK = false, bool ALIGN_EPI = true, bool SP2 = true, bool BBLK = true>
; __device__ __forceinline__ void gemm_phase(LAS unsigned char* lds, const Gemm g, const Sched& S, const Epi& E) {
;     ...
;             PG8_LDB(B0, 1, 0); PG8_LDB(B1, 1, 1); PG8_SCHED; PG8_LDA(At, 1, 0); PG8_STAGE(PG8_SA(0, 1), a2 + hstepA, voffA);
;             PG8_WAIT_V(8); PG8_WAIT_L(0); PG8_BAR; PG8_MMA(0, 0, At, B0); PG8_MMA(0, 1, At, B1); PG8_BAR; PG8_SCHED;
;             PG8_LDA(At, 1, 1); PG8_STAGE(PG8_SB(1, 0), b3, voffB); PG8_STAGE(PG8_SB(1, 1), b3 + hstepB, voffB); PG8_STAGE(PG8_SA(1, 0), a3, voffA);
;             PG8_WAIT_V(8); PG8_WAIT_L(0); PG8_BAR; PG8_MMA(1, 0, At, B0); PG8_MMA(1, 1, At, B1); PG8_BAR; PG8_SCHED;
;     ...
;         if constexpr (ALIGN_EPI) { if (wr == 0) PG8_BAR; }
	s_add_i32 s61, 0, 0x18000
	v_add_u32_e32 v171, s61, v1
	s_add_i32 s62, 0, 0x1c000
	ds_read_b128 v[172:175], v171
	ds_read_b128 v[176:179], v171 offset:1024
	ds_read_b128 v[180:183], v171 offset:2048
	ds_read_b128 v[184:187], v171 offset:3072
	v_add_u32_e32 v171, s62, v1
	ds_read_b128 v[188:191], v171
	ds_read_b128 v[192:195], v171 offset:1024
	ds_read_b128 v[196:199], v171 offset:2048
	ds_read_b128 v[200:203], v171 offset:3072
	s_add_u32 s36, s36, 0x80000
	s_addc_u32 s37, s37, 0
	s_mov_b32 m0, s46
	ds_read_b128 v[204:207], v170 offset:32768
	ds_read_b128 v[208:211], v170 offset:33792
	ds_read_b128 v[212:215], v170 offset:34816
	ds_read_b128 v[216:219], v170 offset:35840
	ds_read_b128 v[220:223], v170 offset:36864
	ds_read_b128 v[224:227], v170 offset:37888
	ds_read_b128 v[228:231], v170 offset:38912
	ds_read_b128 v[232:235], v170 offset:39936
	global_load_lds_dwordx4 v136, s[36:37]
	s_mov_b32 m0, s47
	s_nop 0
	global_load_lds_dwordx4 v132, s[36:37]
	s_waitcnt vmcnt(8)
	s_barrier
	s_waitcnt lgkmcnt(0)
	v_mfma_f32_16x16x32_bf16 v[126:129], v[172:175], v[204:207], v[126:129]
	v_mfma_f32_16x16x32_bf16 v[122:125], v[180:183], v[204:207], v[122:125]
	v_mfma_f32_16x16x32_bf16 v[110:113], v[172:175], v[212:215], v[110:113]
	v_mfma_f32_16x16x32_bf16 v[106:109], v[180:183], v[212:215], v[106:109]
	v_mfma_f32_16x16x32_bf16 v[94:97], v[172:175], v[220:223], v[94:97]
	v_mfma_f32_16x16x32_bf16 v[90:93], v[180:183], v[220:223], v[90:93]
	v_mfma_f32_16x16x32_bf16 v[78:81], v[172:175], v[228:231], v[78:81]
	v_mfma_f32_16x16x32_bf16 v[74:77], v[180:183], v[228:231], v[74:77]
	v_mfma_f32_16x16x32_bf16 v[126:129], v[176:179], v[208:211], v[126:129]
	v_mfma_f32_16x16x32_bf16 v[122:125], v[184:187], v[208:211], v[122:125]
	v_mfma_f32_16x16x32_bf16 v[110:113], v[176:179], v[216:219], v[110:113]
	v_mfma_f32_16x16x32_bf16 v[106:109], v[184:187], v[216:219], v[106:109]
	v_mfma_f32_16x16x32_bf16 v[94:97], v[176:179], v[224:227], v[94:97]
	v_mfma_f32_16x16x32_bf16 v[90:93], v[184:187], v[224:227], v[90:93]
	v_mfma_f32_16x16x32_bf16 v[78:81], v[176:179], v[232:235], v[78:81]
	v_mfma_f32_16x16x32_bf16 v[74:77], v[184:187], v[232:235], v[74:77]
	v_mfma_f32_16x16x32_bf16 v[118:121], v[188:191], v[204:207], v[118:121]
	v_mfma_f32_16x16x32_bf16 v[114:117], v[196:199], v[204:207], v[114:117]
	v_mfma_f32_16x16x32_bf16 v[102:105], v[188:191], v[212:215], v[102:105]
	v_mfma_f32_16x16x32_bf16 v[98:101], v[196:199], v[212:215], v[98:101]
	v_mfma_f32_16x16x32_bf16 v[86:89], v[188:191], v[220:223], v[86:89]
	v_mfma_f32_16x16x32_bf16 v[82:85], v[196:199], v[220:223], v[82:85]
	v_mfma_f32_16x16x32_bf16 v[70:73], v[188:191], v[228:231], v[70:73]
	v_mfma_f32_16x16x32_bf16 v[66:69], v[196:199], v[228:231], v[66:69]
	v_mfma_f32_16x16x32_bf16 v[118:121], v[192:195], v[208:211], v[118:121]
	v_mfma_f32_16x16x32_bf16 v[114:117], v[200:203], v[208:211], v[114:117]
	v_mfma_f32_16x16x32_bf16 v[102:105], v[192:195], v[216:219], v[102:105]
	v_mfma_f32_16x16x32_bf16 v[98:101], v[200:203], v[216:219], v[98:101]
	v_mfma_f32_16x16x32_bf16 v[86:89], v[192:195], v[224:227], v[86:89]
	v_mfma_f32_16x16x32_bf16 v[82:85], v[200:203], v[224:227], v[82:85]
	v_mfma_f32_16x16x32_bf16 v[70:73], v[192:195], v[232:235], v[70:73]
	v_mfma_f32_16x16x32_bf16 v[66:69], v[200:203], v[232:235], v[66:69]
	s_barrier
	s_add_u32 s36, s34, 0x8000
	s_addc_u32 s37, s35, 0
	s_add_i32 s61, s61, s40
	s_mov_b32 m0, s61
	ds_read_b128 v[204:207], v170 offset:49152
	ds_read_b128 v[208:211], v170 offset:50176
	ds_read_b128 v[212:215], v170 offset:51200
	ds_read_b128 v[216:219], v170 offset:52224
	ds_read_b128 v[220:223], v170 offset:53248
	ds_read_b128 v[224:227], v170 offset:54272
	ds_read_b128 v[228:231], v170 offset:55296
	ds_read_b128 v[232:235], v170 offset:56320
	global_load_lds_dwordx4 v134, s[36:37]
	s_add_i32 m0, s61, 0x2000
	s_add_u32 s34, s34, 0xc000
	v_lshl_add_u64 v[236:237], s[36:37], 0, v[130:131]
	s_addc_u32 s35, s35, 0
	s_add_i32 s36, s62, s40
	global_load_lds_dwordx4 v[236:237], off
	s_mov_b32 m0, s36
	s_nop 0
	global_load_lds_dwordx4 v134, s[34:35]
	s_add_i32 m0, s36, 0x2000
	s_nop 0
	global_load_lds_dwordx4 v130, s[34:35]
	s_mov_b32 m0, s50
	s_nop 0
	global_load_lds_dwordx4 v136, s[30:31]
	s_mov_b32 m0, s51
	s_nop 0
	global_load_lds_dwordx4 v132, s[30:31]
	s_waitcnt vmcnt(8)
	s_barrier
	s_waitcnt lgkmcnt(0)
	v_mfma_f32_16x16x32_bf16 v[62:65], v[172:175], v[204:207], v[62:65]
	v_mfma_f32_16x16x32_bf16 v[58:61], v[180:183], v[204:207], v[58:61]
	v_mfma_f32_16x16x32_bf16 v[46:49], v[172:175], v[212:215], v[46:49]
	v_mfma_f32_16x16x32_bf16 v[42:45], v[180:183], v[212:215], v[42:45]
	v_mfma_f32_16x16x32_bf16 v[30:33], v[172:175], v[220:223], v[30:33]
	v_mfma_f32_16x16x32_bf16 v[26:29], v[180:183], v[220:223], v[26:29]
	v_mfma_f32_16x16x32_bf16 v[14:17], v[172:175], v[228:231], v[14:17]
	v_mfma_f32_16x16x32_bf16 v[10:13], v[180:183], v[228:231], v[10:13]
	v_mfma_f32_16x16x32_bf16 v[62:65], v[176:179], v[208:211], v[62:65]
	v_mfma_f32_16x16x32_bf16 v[58:61], v[184:187], v[208:211], v[58:61]
	v_mfma_f32_16x16x32_bf16 v[46:49], v[176:179], v[216:219], v[46:49]
	v_mfma_f32_16x16x32_bf16 v[42:45], v[184:187], v[216:219], v[42:45]
	v_mfma_f32_16x16x32_bf16 v[30:33], v[176:179], v[224:227], v[30:33]
	v_mfma_f32_16x16x32_bf16 v[26:29], v[184:187], v[224:227], v[26:29]
	v_mfma_f32_16x16x32_bf16 v[14:17], v[176:179], v[232:235], v[14:17]
	v_mfma_f32_16x16x32_bf16 v[10:13], v[184:187], v[232:235], v[10:13]
	v_mfma_f32_16x16x32_bf16 v[54:57], v[188:191], v[204:207], v[54:57]
	v_mfma_f32_16x16x32_bf16 v[50:53], v[196:199], v[204:207], v[50:53]
	v_mfma_f32_16x16x32_bf16 v[38:41], v[188:191], v[212:215], v[38:41]
	v_mfma_f32_16x16x32_bf16 v[34:37], v[196:199], v[212:215], v[34:37]
	v_mfma_f32_16x16x32_bf16 v[22:25], v[188:191], v[220:223], v[22:25]
	v_mfma_f32_16x16x32_bf16 v[18:21], v[196:199], v[220:223], v[18:21]
	v_mfma_f32_16x16x32_bf16 v[6:9], v[188:191], v[228:231], v[6:9]
	v_mfma_f32_16x16x32_bf16 v[2:5], v[196:199], v[228:231], v[2:5]
	v_mfma_f32_16x16x32_bf16 v[54:57], v[192:195], v[208:211], v[54:57]
	v_mfma_f32_16x16x32_bf16 v[50:53], v[200:203], v[208:211], v[50:53]
	v_mfma_f32_16x16x32_bf16 v[38:41], v[192:195], v[216:219], v[38:41]
	v_mfma_f32_16x16x32_bf16 v[34:37], v[200:203], v[216:219], v[34:37]
	v_mfma_f32_16x16x32_bf16 v[22:25], v[192:195], v[224:227], v[22:25]
	v_mfma_f32_16x16x32_bf16 v[18:21], v[200:203], v[224:227], v[18:21]
	v_mfma_f32_16x16x32_bf16 v[6:9], v[192:195], v[232:235], v[6:9]
	v_mfma_f32_16x16x32_bf16 v[2:5], v[200:203], v[232:235], v[2:5]
	s_barrier
	s_add_i32 s60, s60, 2
	s_add_u32 s28, s28, 0x100
	s_addc_u32 s29, s29, 0
	s_add_u32 s58, s58, 0x10000
	s_addc_u32 s59, s59, 0
	s_cmp_gt_u32 s60, 29
	s_cbranch_scc0 .LBB0_475
	s_and_b64 vcc, exec, s[8:9]
	s_cbranch_vccz .LBB0_478
	s_barrier

; #define PG8_STAGE(bufoff, gbase, voff) do { _Pragma("unroll") for (int _i = 0; _i < 2; ++_i) \
;         __builtin_amdgcn_global_load_lds((const unsigned*)((const char*)(gbase) + (voff)[_i]), (LAS unsigned*)(lds + (bufoff) + ldsw + _i * 8192), 16, 0, 0); } while (0)
; #define PG8_LDA(dst, b, h) do { _Pragma("unroll") for (int m = 0; m < 4; ++m) _Pragma("unroll") for (int k = 0; k < 2; ++k) dst[m][k] = *(const LAS bf16x8*)(lds + PG8_SA(b, h) + aoff + m * 2048 + k * 1024); } while (0)
; #define PG8_LDB(dst, b, h) do { _Pragma("unroll") for (int n = 0; n < 2; ++n) _Pragma("unroll") for (int k = 0; k < 2; ++k) dst[n][k] = *(const LAS bf16x8*)(lds + PG8_SB(b, h) + boff + n * 2048 + k * 1024); } while (0)
; #define PG8_WAIT_V(n) asm volatile("s_waitcnt vmcnt(" #n ")" ::: "memory")
; #define PG8_WAIT_L(n) asm volatile("s_waitcnt lgkmcnt(" #n ")" ::: "memory")
; template <class Epi, class Sched, bool ABLK = false, bool ALIGN_EPI = true, bool SP2 = true, bool BBLK = true>
; __device__ __forceinline__ void gemm_phase(LAS unsigned char* lds, const Gemm g, const Sched& S, const Epi& E) {
;     ...
;         const bool has_next = S.next(ui + 1, nxt);
;         const int nt = cur.nt;
;         const char* nuA = has_next ? a_unit(nxt) : uA; const int ntbA = has_next ? nxt.k0 / BK : tbA; const char* nB = has_next ? (const char*)g.Bt + (size_t)nxt.pn * tstepB + b_k0(nxt.k0) : cB;
;         for (int t = 0; t < nt; t += 2) {
;             const bool last = (t == nt - 2);
;             const char* a1 = a_tile(uA, tbA + t + 1);
;             const char* a2 = last ? a_tile(nuA, ntbA) : a_tile(uA, tbA + t + 2); const char* b2 = last ? nB : cB + (size_t)(t + 2) * kstepB;
;             const char* a3 = last ? a_tile(nuA, ntbA + 1) : a_tile(uA, tbA + t + 3); const char* b3 = b2 + kstepB;
;             if (last && has_next) S.a_ready(nxt);
;             if constexpr (SP2) {
;             PG8_LDB(B0, 0, 0); PG8_LDB(B1, 0, 1); PG8_SCHED; PG8_LDA(At, 0, 0); PG8_STAGE(PG8_SA(1, 1), a1 + hstepA, voffA);
;             PG8_WAIT_V(8); PG8_WAIT_L(0); PG8_BAR; PG8_MMA(0, 0, At, B0); PG8_MMA(0, 1, At, B1); PG8_BAR; PG8_SCHED;
;             PG8_LDA(At, 0, 1); PG8_STAGE(PG8_SB(0, 0), b2, voffB); PG8_STAGE(PG8_SB(0, 1), b2 + hstepB, voffB); PG8_STAGE(PG8_SA(0, 0), a2, voffA);
;             PG8_WAIT_V(8); PG8_WAIT_L(0); PG8_BAR; PG8_MMA(1, 0, At, B0); PG8_MMA(1, 1, At, B1); PG8_BAR; PG8_SCHED;
.LBB0_539:
	s_ashr_i32 s81, s80, 31
	s_andn2_b64 vcc, exec, s[4:5]
	s_lshl_b64 s[30:31], s[80:81], 22
	s_add_u32 s30, s1, s30
	s_addc_u32 s31, s33, s31
	s_and_b64 s[34:35], s[4:5], exec
	s_cselect_b32 s47, s31, s43
	s_cselect_b32 s60, s30, s42
	s_ashr_i32 s34, s0, 31
	s_lshr_b32 s34, s34, 26
	s_add_i32 s34, s0, s34
	s_ashr_i32 s34, s34, 6
	s_and_b64 s[36:37], s[4:5], exec
	s_cselect_b32 s48, s34, s46
	s_ashr_i32 s79, s78, 31
	s_lshl_b64 s[36:37], s[78:79], 22
	s_add_u32 s49, s39, s36
	s_addc_u32 s61, s50, s37
	s_ashr_i32 s35, s34, 31
	s_lshl_b64 s[36:37], s[34:35], 15
	s_add_u32 s36, s49, s36
	s_addc_u32 s37, s61, s37
	v_cndmask_b32_e64 v2, 0, 1, s[4:5]
	s_and_b64 s[4:5], s[4:5], exec
	s_cselect_b32 s4, s37, s41
	s_cselect_b32 s5, s36, s40
	s_ashr_i32 s49, s48, 31
	s_lshl_b64 s[48:49], s[48:49], 15
	s_add_u32 s35, s60, s48
	s_addc_u32 s63, s47, s49
	s_add_u32 s64, s35, 0x8000
	s_addc_u32 s65, s63, 0
	s_add_u32 s66, s40, 0x10000
	s_addc_u32 s67, s41, 0
	s_ashr_i32 s47, s46, 31
	v_cmp_ne_u32_e64 s[8:9], 1, v2
	s_lshl_b64 s[40:41], s[46:47], 15
	v_lshl_add_u64 v[2:3], s[42:43], 0, v[138:139]
	s_add_u32 s75, s42, s40
	v_lshl_add_u64 v[142:143], v[2:3], 0, s[40:41]
	v_lshl_add_u64 v[2:3], s[42:43], 0, v[140:141]
	s_addc_u32 s76, s43, s41
	v_lshl_add_u64 v[144:145], v[2:3], 0, s[40:41]
	s_lshl_b32 s40, s59, 15
	s_add_i32 s40, s40, 0xfff00000
	v_mov_b32_e32 v2, 0
	s_add_u32 s77, s40, 0xf0000
	s_mov_b32 s79, 0
	s_mov_b64 s[40:41], 0
	ds_read_b128 v[152:155], v148
	ds_read_b128 v[156:159], v148 offset:1024
	ds_read_b128 v[160:163], v148 offset:2048
	ds_read_b128 v[164:167], v148 offset:3072
	ds_read_b128 v[168:171], v149
	ds_read_b128 v[172:175], v149 offset:1024
	ds_read_b128 v[176:179], v149 offset:2048
	ds_read_b128 v[180:183], v149 offset:3072
	s_add_u32 s42, s75, s40
	s_addc_u32 s43, s76, s41
	s_add_u32 s48, s42, 0x10000
	s_addc_u32 s49, s43, 0
	s_add_i32 s79, s79, 2
	s_add_u32 s46, s66, s40
	s_addc_u32 s47, s67, s41
	s_add_u32 s42, s42, 0x18000
	s_addc_u32 s43, s43, 0
	s_cmp_eq_u32 s77, s40
	s_cselect_b32 s43, s65, s43
	s_cselect_b32 s42, s64, s42
	s_cselect_b32 s47, s4, s47
	s_cselect_b32 s46, s5, s46
	s_cselect_b32 s49, s63, s49
	s_cselect_b32 s48, s35, s48
	v_lshl_add_u64 v[216:217], v[142:143], 0, s[40:41]
	s_add_i32 m0, s52, 0xc000
	ds_read_b128 v[184:187], v150
	ds_read_b128 v[188:191], v150 offset:1024
	ds_read_b128 v[192:195], v150 offset:2048
	ds_read_b128 v[196:199], v150 offset:3072
	ds_read_b128 v[200:203], v150 offset:4096
	ds_read_b128 v[204:207], v150 offset:5120
	ds_read_b128 v[208:211], v150 offset:6144
	ds_read_b128 v[212:215], v150 offset:7168
	global_load_lds_dwordx4 v[216:217], off
	v_lshl_add_u64 v[216:217], v[144:145], 0, s[40:41]
	s_add_i32 m0, s52, 0xe000
	s_nop 0
	global_load_lds_dwordx4 v[216:217], off
	s_waitcnt vmcnt(8)
	s_barrier
	s_waitcnt lgkmcnt(0)
	v_mfma_f32_16x16x32_bf16 v[126:129], v[152:155], v[184:187], 0
	v_mfma_f32_16x16x32_bf16 v[122:125], v[160:163], v[184:187], 0
	v_mfma_f32_16x16x32_bf16 v[110:113], v[152:155], v[192:195], 0
	v_mfma_f32_16x16x32_bf16 v[106:109], v[160:163], v[192:195], 0
	v_mfma_f32_16x16x32_bf16 v[94:97], v[152:155], v[200:203], 0
	v_mfma_f32_16x16x32_bf16 v[90:93], v[160:163], v[200:203], 0
	v_mfma_f32_16x16x32_bf16 v[78:81], v[152:155], v[208:211], 0
	v_mfma_f32_16x16x32_bf16 v[74:77], v[160:163], v[208:211], 0
	v_mfma_f32_16x16x32_bf16 v[126:129], v[156:159], v[188:191], v[126:129]
	v_mfma_f32_16x16x32_bf16 v[122:125], v[164:167], v[188:191], v[122:125]
	v_mfma_f32_16x16x32_bf16 v[110:113], v[156:159], v[196:199], v[110:113]
	v_mfma_f32_16x16x32_bf16 v[106:109], v[164:167], v[196:199], v[106:109]
	v_mfma_f32_16x16x32_bf16 v[94:97], v[156:159], v[204:207], v[94:97]
	v_mfma_f32_16x16x32_bf16 v[90:93], v[164:167], v[204:207], v[90:93]
	v_mfma_f32_16x16x32_bf16 v[78:81], v[156:159], v[212:215], v[78:81]
	v_mfma_f32_16x16x32_bf16 v[74:77], v[164:167], v[212:215], v[74:77]
	v_mfma_f32_16x16x32_bf16 v[118:121], v[168:171], v[184:187], 0
	v_mfma_f32_16x16x32_bf16 v[114:117], v[176:179], v[184:187], 0
	v_mfma_f32_16x16x32_bf16 v[102:105], v[168:171], v[192:195], 0
	v_mfma_f32_16x16x32_bf16 v[98:101], v[176:179], v[192:195], 0
	v_mfma_f32_16x16x32_bf16 v[86:89], v[168:171], v[200:203], 0
	v_mfma_f32_16x16x32_bf16 v[82:85], v[176:179], v[200:203], 0
	v_mfma_f32_16x16x32_bf16 v[70:73], v[168:171], v[208:211], 0
	v_mfma_f32_16x16x32_bf16 v[66:69], v[176:179], v[208:211], 0
	v_mfma_f32_16x16x32_bf16 v[118:121], v[172:175], v[188:191], v[118:121]
	v_mfma_f32_16x16x32_bf16 v[114:117], v[180:183], v[188:191], v[114:117]
	v_mfma_f32_16x16x32_bf16 v[102:105], v[172:175], v[196:199], v[102:105]
	v_mfma_f32_16x16x32_bf16 v[98:101], v[180:183], v[196:199], v[98:101]
	v_mfma_f32_16x16x32_bf16 v[86:89], v[172:175], v[204:207], v[86:89]
	v_mfma_f32_16x16x32_bf16 v[82:85], v[180:183], v[204:207], v[82:85]
	v_mfma_f32_16x16x32_bf16 v[70:73], v[172:175], v[212:215], v[70:73]
	v_mfma_f32_16x16x32_bf16 v[66:69], v[180:183], v[212:215], v[66:69]
	s_barrier
	s_add_i32 s60, s72, s51
	s_mov_b32 m0, s60
	ds_read_b128 v[184:187], v150 offset:16384
	ds_read_b128 v[188:191], v150 offset:17408
	ds_read_b128 v[192:195], v150 offset:18432
	ds_read_b128 v[196:199], v150 offset:19456
	ds_read_b128 v[200:203], v150 offset:20480
	ds_read_b128 v[204:207], v150 offset:21504
	ds_read_b128 v[208:211], v150 offset:22528
	ds_read_b128 v[212:215], v150 offset:23552
	global_load_lds_dwordx4 v130, s[46:47]
	s_add_i32 m0, s60, 0x2000
	s_add_u32 s60, s46, 0x4000
	s_addc_u32 s61, s47, 0
	s_add_i32 s81, s73, s51
	global_load_lds_dwordx4 v132, s[46:47]
	s_mov_b32 m0, s81
	s_nop 0
	global_load_lds_dwordx4 v130, s[60:61]
	s_add_i32 m0, s81, 0x2000
	s_nop 0
	global_load_lds_dwordx4 v132, s[60:61]
	s_mov_b32 m0, s52
	s_nop 0
	global_load_lds_dwordx4 v130, s[48:49]
	s_mov_b32 m0, s53
	s_nop 0
	global_load_lds_dwordx4 v132, s[48:49]
	s_waitcnt vmcnt(8)
	s_barrier
; #define PG8_STAGE(bufoff, gbase, voff) do { _Pragma("unroll") for (int _i = 0; _i < 2; ++_i) \
;         __builtin_amdgcn_global_load_lds((const unsigned*)((const char*)(gbase) + (voff)[_i]), (LAS unsigned*)(lds + (bufoff) + ldsw + _i * 8192), 16, 0, 0); } while (0)
; #define PG8_LDA(dst, b, h) do { _Pragma("unroll") for (int m = 0; m < 4; ++m) _Pragma("unroll") for (int k = 0; k < 2; ++k) dst[m][k] = *(const LAS bf16x8*)(lds + PG8_SA(b, h) + aoff + m * 2048 + k * 1024); } while (0)
; #define PG8_LDB(dst, b, h) do { _Pragma("unroll") for (int n = 0; n < 2; ++n) _Pragma("unroll") for (int k = 0; k < 2; ++k) dst[n][k] = *(const LAS bf16x8*)(lds + PG8_SB(b, h) + boff + n * 2048 + k * 1024); } while (0)
; #define PG8_MMA(ai, bj, At, Bt) do { __builtin_amdgcn_s_setprio(1); _Pragma("unroll") for (int m = 0; m < 4; ++m) _Pragma("unroll") for (int n = 0; n < 2; ++n) _Pragma("unroll") for (int k = 0; k < 2; ++k) \
;         acc[ai][bj][m][n] = __builtin_amdgcn_mfma_f32_16x16x32_bf16(Bt[n][k], At[m][k], acc[ai][bj][m][n], 0, 0, 0); __builtin_amdgcn_s_setprio(0); } while (0)
; #define PG8_WAIT_V(n) asm volatile("s_waitcnt vmcnt(" #n ")" ::: "memory")
; #define PG8_WAIT_L(n) asm volatile("s_waitcnt lgkmcnt(" #n ")" ::: "memory")
; #define PG8_BAR __builtin_amdgcn_s_barrier()
; #define PG8_SCHED __builtin_amdgcn_sched_barrier(0)
; template <class Epi, class Sched, bool ABLK = false, bool ALIGN_EPI = true, bool SP2 = true, bool BBLK = true>
; __device__ __forceinline__ void gemm_phase(LAS unsigned char* lds, const Gemm g, const Sched& S, const Epi& E) {
;     ...
;             PG8_LDA(At, 0, 1); PG8_STAGE(PG8_SB(0, 0), b2, voffB); PG8_STAGE(PG8_SB(0, 1), b2 + hstepB, voffB); PG8_STAGE(PG8_SA(0, 0), a2, voffA);
;             PG8_WAIT_V(8); PG8_WAIT_L(0); PG8_BAR; PG8_MMA(1, 0, At, B0); PG8_MMA(1, 1, At, B1); PG8_BAR; PG8_SCHED;
;             PG8_LDB(B0, 1, 0); PG8_LDB(B1, 1, 1); PG8_SCHED; PG8_LDA(At, 1, 0); PG8_STAGE(PG8_SA(0, 1), a2 + hstepA, voffA);
;             PG8_WAIT_V(8); PG8_WAIT_L(0); PG8_BAR; PG8_MMA(0, 0, At, B0); PG8_MMA(0, 1, At, B1); PG8_BAR; PG8_SCHED;
	s_waitcnt lgkmcnt(0)
	v_mfma_f32_16x16x32_bf16 v[62:65], v[152:155], v[184:187], 0
	v_mfma_f32_16x16x32_bf16 v[58:61], v[160:163], v[184:187], 0
	v_mfma_f32_16x16x32_bf16 v[46:49], v[152:155], v[192:195], 0
	v_mfma_f32_16x16x32_bf16 v[42:45], v[160:163], v[192:195], 0
	v_mfma_f32_16x16x32_bf16 v[30:33], v[152:155], v[200:203], 0
	v_mfma_f32_16x16x32_bf16 v[26:29], v[160:163], v[200:203], 0
	v_mfma_f32_16x16x32_bf16 v[14:17], v[152:155], v[208:211], 0
	v_mfma_f32_16x16x32_bf16 v[10:13], v[160:163], v[208:211], 0
	v_mfma_f32_16x16x32_bf16 v[62:65], v[156:159], v[188:191], v[62:65]
	v_mfma_f32_16x16x32_bf16 v[58:61], v[164:167], v[188:191], v[58:61]
	v_mfma_f32_16x16x32_bf16 v[46:49], v[156:159], v[196:199], v[46:49]
	v_mfma_f32_16x16x32_bf16 v[42:45], v[164:167], v[196:199], v[42:45]
	v_mfma_f32_16x16x32_bf16 v[30:33], v[156:159], v[204:207], v[30:33]
	v_mfma_f32_16x16x32_bf16 v[26:29], v[164:167], v[204:207], v[26:29]
	v_mfma_f32_16x16x32_bf16 v[14:17], v[156:159], v[212:215], v[14:17]
	v_mfma_f32_16x16x32_bf16 v[10:13], v[164:167], v[212:215], v[10:13]
	v_mfma_f32_16x16x32_bf16 v[54:57], v[168:171], v[184:187], 0
	v_mfma_f32_16x16x32_bf16 v[50:53], v[176:179], v[184:187], 0
	v_mfma_f32_16x16x32_bf16 v[38:41], v[168:171], v[192:195], 0
	v_mfma_f32_16x16x32_bf16 v[34:37], v[176:179], v[192:195], 0
	v_mfma_f32_16x16x32_bf16 v[22:25], v[168:171], v[200:203], 0
	v_mfma_f32_16x16x32_bf16 v[18:21], v[176:179], v[200:203], 0
	v_mfma_f32_16x16x32_bf16 v[6:9], v[168:171], v[208:211], 0
	v_mfma_f32_16x16x32_bf16 v[2:5], v[176:179], v[208:211], 0
	v_mfma_f32_16x16x32_bf16 v[54:57], v[172:175], v[188:191], v[54:57]
	v_mfma_f32_16x16x32_bf16 v[50:53], v[180:183], v[188:191], v[50:53]
	v_mfma_f32_16x16x32_bf16 v[38:41], v[172:175], v[196:199], v[38:41]
	v_mfma_f32_16x16x32_bf16 v[34:37], v[180:183], v[196:199], v[34:37]
	v_mfma_f32_16x16x32_bf16 v[22:25], v[172:175], v[204:207], v[22:25]
	v_mfma_f32_16x16x32_bf16 v[18:21], v[180:183], v[204:207], v[18:21]
	v_mfma_f32_16x16x32_bf16 v[6:9], v[172:175], v[212:215], v[6:9]
	v_mfma_f32_16x16x32_bf16 v[2:5], v[180:183], v[212:215], v[2:5]
	s_barrier
	s_add_i32 s60, 0, 0x18000
	v_add_u32_e32 v151, s60, v146
	s_add_i32 s61, 0, 0x1c000
	ds_read_b128 v[152:155], v151
	ds_read_b128 v[156:159], v151 offset:1024
	ds_read_b128 v[160:163], v151 offset:2048
	ds_read_b128 v[164:167], v151 offset:3072
	v_add_u32_e32 v151, s61, v146
	ds_read_b128 v[168:171], v151
	ds_read_b128 v[172:175], v151 offset:1024
	ds_read_b128 v[176:179], v151 offset:2048
	ds_read_b128 v[180:183], v151 offset:3072
	s_add_u32 s48, s48, 0x4000
	s_addc_u32 s49, s49, 0
	s_mov_b32 m0, s54
	ds_read_b128 v[184:187], v150 offset:32768
	ds_read_b128 v[188:191], v150 offset:33792
	ds_read_b128 v[192:195], v150 offset:34816
	ds_read_b128 v[196:199], v150 offset:35840
	ds_read_b128 v[200:203], v150 offset:36864
	ds_read_b128 v[204:207], v150 offset:37888
	ds_read_b128 v[208:211], v150 offset:38912
	ds_read_b128 v[212:215], v150 offset:39936
	global_load_lds_dwordx4 v130, s[48:49]
	s_mov_b32 m0, s55
	s_nop 0
	global_load_lds_dwordx4 v132, s[48:49]
	s_waitcnt vmcnt(8)
	s_barrier
	s_waitcnt lgkmcnt(0)
	v_mfma_f32_16x16x32_bf16 v[126:129], v[152:155], v[184:187], v[126:129]
	v_mfma_f32_16x16x32_bf16 v[122:125], v[160:163], v[184:187], v[122:125]
	v_mfma_f32_16x16x32_bf16 v[110:113], v[152:155], v[192:195], v[110:113]
	v_mfma_f32_16x16x32_bf16 v[106:109], v[160:163], v[192:195], v[106:109]
	v_mfma_f32_16x16x32_bf16 v[94:97], v[152:155], v[200:203], v[94:97]
	v_mfma_f32_16x16x32_bf16 v[90:93], v[160:163], v[200:203], v[90:93]
	v_mfma_f32_16x16x32_bf16 v[78:81], v[152:155], v[208:211], v[78:81]
	v_mfma_f32_16x16x32_bf16 v[74:77], v[160:163], v[208:211], v[74:77]
	v_mfma_f32_16x16x32_bf16 v[126:129], v[156:159], v[188:191], v[126:129]
	v_mfma_f32_16x16x32_bf16 v[122:125], v[164:167], v[188:191], v[122:125]
	v_mfma_f32_16x16x32_bf16 v[110:113], v[156:159], v[196:199], v[110:113]
	v_mfma_f32_16x16x32_bf16 v[106:109], v[164:167], v[196:199], v[106:109]
	v_mfma_f32_16x16x32_bf16 v[94:97], v[156:159], v[204:207], v[94:97]
	v_mfma_f32_16x16x32_bf16 v[90:93], v[164:167], v[204:207], v[90:93]
	v_mfma_f32_16x16x32_bf16 v[78:81], v[156:159], v[212:215], v[78:81]
	v_mfma_f32_16x16x32_bf16 v[74:77], v[164:167], v[212:215], v[74:77]
	v_mfma_f32_16x16x32_bf16 v[118:121], v[168:171], v[184:187], v[118:121]
	v_mfma_f32_16x16x32_bf16 v[114:117], v[176:179], v[184:187], v[114:117]
	v_mfma_f32_16x16x32_bf16 v[102:105], v[168:171], v[192:195], v[102:105]
	v_mfma_f32_16x16x32_bf16 v[98:101], v[176:179], v[192:195], v[98:101]
	v_mfma_f32_16x16x32_bf16 v[86:89], v[168:171], v[200:203], v[86:89]
	v_mfma_f32_16x16x32_bf16 v[82:85], v[176:179], v[200:203], v[82:85]
	v_mfma_f32_16x16x32_bf16 v[70:73], v[168:171], v[208:211], v[70:73]
	v_mfma_f32_16x16x32_bf16 v[66:69], v[176:179], v[208:211], v[66:69]
	v_mfma_f32_16x16x32_bf16 v[118:121], v[172:175], v[188:191], v[118:121]
	v_mfma_f32_16x16x32_bf16 v[114:117], v[180:183], v[188:191], v[114:117]
	v_mfma_f32_16x16x32_bf16 v[102:105], v[172:175], v[196:199], v[102:105]
	v_mfma_f32_16x16x32_bf16 v[98:101], v[180:183], v[196:199], v[98:101]
	v_mfma_f32_16x16x32_bf16 v[86:89], v[172:175], v[204:207], v[86:89]
	v_mfma_f32_16x16x32_bf16 v[82:85], v[180:183], v[204:207], v[82:85]
	v_mfma_f32_16x16x32_bf16 v[70:73], v[172:175], v[212:215], v[70:73]
	v_mfma_f32_16x16x32_bf16 v[66:69], v[180:183], v[212:215], v[66:69]
	s_barrier
; #define PG8_STAGE(bufoff, gbase, voff) do { _Pragma("unroll") for (int _i = 0; _i < 2; ++_i) \
;         __builtin_amdgcn_global_load_lds((const unsigned*)((const char*)(gbase) + (voff)[_i]), (LAS unsigned*)(lds + (bufoff) + ldsw + _i * 8192), 16, 0, 0); } while (0)
; #define PG8_LDA(dst, b, h) do { _Pragma("unroll") for (int m = 0; m < 4; ++m) _Pragma("unroll") for (int k = 0; k < 2; ++k) dst[m][k] = *(const LAS bf16x8*)(lds + PG8_SA(b, h) + aoff + m * 2048 + k * 1024); } while (0)
; #define PG8_WAIT_V(n) asm volatile("s_waitcnt vmcnt(" #n ")" ::: "memory")
; #define PG8_WAIT_L(n) asm volatile("s_waitcnt lgkmcnt(" #n ")" ::: "memory")
; template <class Epi, class Sched, bool ABLK = false, bool ALIGN_EPI = true, bool SP2 = true, bool BBLK = true>
; __device__ __forceinline__ void gemm_phase(LAS unsigned char* lds, const Gemm g, const Sched& S, const Epi& E) {
;     ...
;         for (int t = 0; t < nt; t += 2) {
;             const bool last = (t == nt - 2);
;             const char* a1 = a_tile(uA, tbA + t + 1);
;             const char* a2 = last ? a_tile(nuA, ntbA) : a_tile(uA, tbA + t + 2); const char* b2 = last ? nB : cB + (size_t)(t + 2) * kstepB;
;             const char* a3 = last ? a_tile(nuA, ntbA + 1) : a_tile(uA, tbA + t + 3); const char* b3 = b2 + kstepB;
;             if (last && has_next) S.a_ready(nxt);
;             if constexpr (SP2) {
;             PG8_LDB(B0, 0, 0); PG8_LDB(B1, 0, 1); PG8_SCHED; PG8_LDA(At, 0, 0); PG8_STAGE(PG8_SA(1, 1), a1 + hstepA, voffA);
;             PG8_WAIT_V(8); PG8_WAIT_L(0); PG8_BAR; PG8_MMA(0, 0, At, B0); PG8_MMA(0, 1, At, B1); PG8_BAR; PG8_SCHED;
;             PG8_LDA(At, 0, 1); PG8_STAGE(PG8_SB(0, 0), b2, voffB); PG8_STAGE(PG8_SB(0, 1), b2 + hstepB, voffB); PG8_STAGE(PG8_SA(0, 0), a2, voffA);
;             PG8_WAIT_V(8); PG8_WAIT_L(0); PG8_BAR; PG8_MMA(1, 0, At, B0); PG8_MMA(1, 1, At, B1); PG8_BAR; PG8_SCHED;
;             PG8_LDB(B0, 1, 0); PG8_LDB(B1, 1, 1); PG8_SCHED; PG8_LDA(At, 1, 0); PG8_STAGE(PG8_SA(0, 1), a2 + hstepA, voffA);
;             PG8_WAIT_V(8); PG8_WAIT_L(0); PG8_BAR; PG8_MMA(0, 0, At, B0); PG8_MMA(0, 1, At, B1); PG8_BAR; PG8_SCHED;
;             PG8_LDA(At, 1, 1); PG8_STAGE(PG8_SB(1, 0), b3, voffB); PG8_STAGE(PG8_SB(1, 1), b3 + hstepB, voffB); PG8_STAGE(PG8_SA(1, 0), a3, voffA);
;             PG8_WAIT_V(8); PG8_WAIT_L(0); PG8_BAR; PG8_MMA(1, 0, At, B0); PG8_MMA(1, 1, At, B1); PG8_BAR; PG8_SCHED;
	s_add_u32 s48, s46, 0x8000
	s_addc_u32 s49, s47, 0
	s_add_i32 s81, s60, s51
	s_mov_b32 m0, s81
	ds_read_b128 v[184:187], v150 offset:49152
	ds_read_b128 v[188:191], v150 offset:50176
	ds_read_b128 v[192:195], v150 offset:51200
	ds_read_b128 v[196:199], v150 offset:52224
	ds_read_b128 v[200:203], v150 offset:53248
	ds_read_b128 v[204:207], v150 offset:54272
	ds_read_b128 v[208:211], v150 offset:55296
	ds_read_b128 v[212:215], v150 offset:56320
	global_load_lds_dwordx4 v130, s[48:49]
	s_add_i32 m0, s81, 0x2000
	s_add_u32 s46, s46, 0xc000
	v_lshl_add_u64 v[216:217], s[48:49], 0, v[132:133]
	s_addc_u32 s47, s47, 0
	s_add_i32 s48, s61, s51
	global_load_lds_dwordx4 v[216:217], off
	s_mov_b32 m0, s48
	s_nop 0
	global_load_lds_dwordx4 v130, s[46:47]
	s_add_i32 m0, s48, 0x2000
	s_nop 0
	global_load_lds_dwordx4 v132, s[46:47]
	s_mov_b32 m0, s56
	s_nop 0
	global_load_lds_dwordx4 v130, s[42:43]
	s_mov_b32 m0, s57
	s_nop 0
	global_load_lds_dwordx4 v132, s[42:43]
	s_waitcnt vmcnt(8)
	s_barrier
	s_waitcnt lgkmcnt(0)
	v_mfma_f32_16x16x32_bf16 v[62:65], v[152:155], v[184:187], v[62:65]
	v_mfma_f32_16x16x32_bf16 v[58:61], v[160:163], v[184:187], v[58:61]
	v_mfma_f32_16x16x32_bf16 v[46:49], v[152:155], v[192:195], v[46:49]
	v_mfma_f32_16x16x32_bf16 v[42:45], v[160:163], v[192:195], v[42:45]
	v_mfma_f32_16x16x32_bf16 v[30:33], v[152:155], v[200:203], v[30:33]
	v_mfma_f32_16x16x32_bf16 v[26:29], v[160:163], v[200:203], v[26:29]
	v_mfma_f32_16x16x32_bf16 v[14:17], v[152:155], v[208:211], v[14:17]
	v_mfma_f32_16x16x32_bf16 v[10:13], v[160:163], v[208:211], v[10:13]
	v_mfma_f32_16x16x32_bf16 v[62:65], v[156:159], v[188:191], v[62:65]
	v_mfma_f32_16x16x32_bf16 v[58:61], v[164:167], v[188:191], v[58:61]
	v_mfma_f32_16x16x32_bf16 v[46:49], v[156:159], v[196:199], v[46:49]
	v_mfma_f32_16x16x32_bf16 v[42:45], v[164:167], v[196:199], v[42:45]
	v_mfma_f32_16x16x32_bf16 v[30:33], v[156:159], v[204:207], v[30:33]
	v_mfma_f32_16x16x32_bf16 v[26:29], v[164:167], v[204:207], v[26:29]
	v_mfma_f32_16x16x32_bf16 v[14:17], v[156:159], v[212:215], v[14:17]
	v_mfma_f32_16x16x32_bf16 v[10:13], v[164:167], v[212:215], v[10:13]
	v_mfma_f32_16x16x32_bf16 v[54:57], v[168:171], v[184:187], v[54:57]
	v_mfma_f32_16x16x32_bf16 v[50:53], v[176:179], v[184:187], v[50:53]
	v_mfma_f32_16x16x32_bf16 v[38:41], v[168:171], v[192:195], v[38:41]
	v_mfma_f32_16x16x32_bf16 v[34:37], v[176:179], v[192:195], v[34:37]
	v_mfma_f32_16x16x32_bf16 v[22:25], v[168:171], v[200:203], v[22:25]
	v_mfma_f32_16x16x32_bf16 v[18:21], v[176:179], v[200:203], v[18:21]
	v_mfma_f32_16x16x32_bf16 v[6:9], v[168:171], v[208:211], v[6:9]
	v_mfma_f32_16x16x32_bf16 v[2:5], v[176:179], v[208:211], v[2:5]
	v_mfma_f32_16x16x32_bf16 v[54:57], v[172:175], v[188:191], v[54:57]
	v_mfma_f32_16x16x32_bf16 v[50:53], v[180:183], v[188:191], v[50:53]
	v_mfma_f32_16x16x32_bf16 v[38:41], v[172:175], v[196:199], v[38:41]
	v_mfma_f32_16x16x32_bf16 v[34:37], v[180:183], v[196:199], v[34:37]
	v_mfma_f32_16x16x32_bf16 v[22:25], v[172:175], v[204:207], v[22:25]
	v_mfma_f32_16x16x32_bf16 v[18:21], v[180:183], v[204:207], v[18:21]
	v_mfma_f32_16x16x32_bf16 v[6:9], v[172:175], v[212:215], v[6:9]
	v_mfma_f32_16x16x32_bf16 v[2:5], v[180:183], v[212:215], v[2:5]
	s_barrier
	s_add_u32 s40, s40, 0x10000
	s_addc_u32 s41, s41, 0
	s_cmp_ge_u32 s79, s59
.LBB0_540:
	ds_read_b128 v[152:155], v148
	ds_read_b128 v[156:159], v148 offset:1024
	ds_read_b128 v[160:163], v148 offset:2048
	ds_read_b128 v[164:167], v148 offset:3072
	ds_read_b128 v[168:171], v149
	ds_read_b128 v[172:175], v149 offset:1024
	ds_read_b128 v[176:179], v149 offset:2048
	ds_read_b128 v[180:183], v149 offset:3072
	s_add_u32 s42, s75, s40
	s_addc_u32 s43, s76, s41
	s_add_u32 s48, s42, 0x10000
	s_addc_u32 s49, s43, 0
	s_add_i32 s79, s79, 2
	s_add_u32 s46, s66, s40
	s_addc_u32 s47, s67, s41
	s_add_u32 s42, s42, 0x18000
	s_addc_u32 s43, s43, 0
	s_cmp_eq_u32 s77, s40
	s_cselect_b32 s43, s65, s43
	s_cselect_b32 s42, s64, s42
	s_cselect_b32 s47, s4, s47
	s_cselect_b32 s46, s5, s46
	s_cselect_b32 s49, s63, s49
	s_cselect_b32 s48, s35, s48
	v_lshl_add_u64 v[216:217], v[142:143], 0, s[40:41]
	s_add_i32 m0, s52, 0xc000
	ds_read_b128 v[184:187], v150
	ds_read_b128 v[188:191], v150 offset:1024
	ds_read_b128 v[192:195], v150 offset:2048
	ds_read_b128 v[196:199], v150 offset:3072
	ds_read_b128 v[200:203], v150 offset:4096
	ds_read_b128 v[204:207], v150 offset:5120
	ds_read_b128 v[208:211], v150 offset:6144
	ds_read_b128 v[212:215], v150 offset:7168
	global_load_lds_dwordx4 v[216:217], off
	v_lshl_add_u64 v[216:217], v[144:145], 0, s[40:41]
	s_add_i32 m0, s52, 0xe000
	s_nop 0
	global_load_lds_dwordx4 v[216:217], off
	s_waitcnt vmcnt(8)
	s_barrier
; #define PG8_STAGE(bufoff, gbase, voff) do { _Pragma("unroll") for (int _i = 0; _i < 2; ++_i) \
;         __builtin_amdgcn_global_load_lds((const unsigned*)((const char*)(gbase) + (voff)[_i]), (LAS unsigned*)(lds + (bufoff) + ldsw + _i * 8192), 16, 0, 0); } while (0)
; #define PG8_LDA(dst, b, h) do { _Pragma("unroll") for (int m = 0; m < 4; ++m) _Pragma("unroll") for (int k = 0; k < 2; ++k) dst[m][k] = *(const LAS bf16x8*)(lds + PG8_SA(b, h) + aoff + m * 2048 + k * 1024); } while (0)
; #define PG8_LDB(dst, b, h) do { _Pragma("unroll") for (int n = 0; n < 2; ++n) _Pragma("unroll") for (int k = 0; k < 2; ++k) dst[n][k] = *(const LAS bf16x8*)(lds + PG8_SB(b, h) + boff + n * 2048 + k * 1024); } while (0)
; #define PG8_MMA(ai, bj, At, Bt) do { __builtin_amdgcn_s_setprio(1); _Pragma("unroll") for (int m = 0; m < 4; ++m) _Pragma("unroll") for (int n = 0; n < 2; ++n) _Pragma("unroll") for (int k = 0; k < 2; ++k) \
;         acc[ai][bj][m][n] = __builtin_amdgcn_mfma_f32_16x16x32_bf16(Bt[n][k], At[m][k], acc[ai][bj][m][n], 0, 0, 0); __builtin_amdgcn_s_setprio(0); } while (0)
; #define PG8_WAIT_V(n) asm volatile("s_waitcnt vmcnt(" #n ")" ::: "memory")
; #define PG8_WAIT_L(n) asm volatile("s_waitcnt lgkmcnt(" #n ")" ::: "memory")
; #define PG8_BAR __builtin_amdgcn_s_barrier()
; #define PG8_SCHED __builtin_amdgcn_sched_barrier(0)
; template <class Epi, class Sched, bool ABLK = false, bool ALIGN_EPI = true, bool SP2 = true, bool BBLK = true>
; __device__ __forceinline__ void gemm_phase(LAS unsigned char* lds, const Gemm g, const Sched& S, const Epi& E) {
;     ...
;             PG8_LDB(B0, 0, 0); PG8_LDB(B1, 0, 1); PG8_SCHED; PG8_LDA(At, 0, 0); PG8_STAGE(PG8_SA(1, 1), a1 + hstepA, voffA);
;             PG8_WAIT_V(8); PG8_WAIT_L(0); PG8_BAR; PG8_MMA(0, 0, At, B0); PG8_MMA(0, 1, At, B1); PG8_BAR; PG8_SCHED;
;             PG8_LDA(At, 0, 1); PG8_STAGE(PG8_SB(0, 0), b2, voffB); PG8_STAGE(PG8_SB(0, 1), b2 + hstepB, voffB); PG8_STAGE(PG8_SA(0, 0), a2, voffA);
;             PG8_WAIT_V(8); PG8_WAIT_L(0); PG8_BAR; PG8_MMA(1, 0, At, B0); PG8_MMA(1, 1, At, B1); PG8_BAR; PG8_SCHED;
	s_waitcnt lgkmcnt(0)
	v_mfma_f32_16x16x32_bf16 v[126:129], v[152:155], v[184:187], v[126:129]
	v_mfma_f32_16x16x32_bf16 v[122:125], v[160:163], v[184:187], v[122:125]
	v_mfma_f32_16x16x32_bf16 v[110:113], v[152:155], v[192:195], v[110:113]
	v_mfma_f32_16x16x32_bf16 v[106:109], v[160:163], v[192:195], v[106:109]
	v_mfma_f32_16x16x32_bf16 v[94:97], v[152:155], v[200:203], v[94:97]
	v_mfma_f32_16x16x32_bf16 v[90:93], v[160:163], v[200:203], v[90:93]
	v_mfma_f32_16x16x32_bf16 v[78:81], v[152:155], v[208:211], v[78:81]
	v_mfma_f32_16x16x32_bf16 v[74:77], v[160:163], v[208:211], v[74:77]
	v_mfma_f32_16x16x32_bf16 v[126:129], v[156:159], v[188:191], v[126:129]
	v_mfma_f32_16x16x32_bf16 v[122:125], v[164:167], v[188:191], v[122:125]
	v_mfma_f32_16x16x32_bf16 v[110:113], v[156:159], v[196:199], v[110:113]
	v_mfma_f32_16x16x32_bf16 v[106:109], v[164:167], v[196:199], v[106:109]
	v_mfma_f32_16x16x32_bf16 v[94:97], v[156:159], v[204:207], v[94:97]
	v_mfma_f32_16x16x32_bf16 v[90:93], v[164:167], v[204:207], v[90:93]
	v_mfma_f32_16x16x32_bf16 v[78:81], v[156:159], v[212:215], v[78:81]
	v_mfma_f32_16x16x32_bf16 v[74:77], v[164:167], v[212:215], v[74:77]
	v_mfma_f32_16x16x32_bf16 v[118:121], v[168:171], v[184:187], v[118:121]
	v_mfma_f32_16x16x32_bf16 v[114:117], v[176:179], v[184:187], v[114:117]
	v_mfma_f32_16x16x32_bf16 v[102:105], v[168:171], v[192:195], v[102:105]
	v_mfma_f32_16x16x32_bf16 v[98:101], v[176:179], v[192:195], v[98:101]
	v_mfma_f32_16x16x32_bf16 v[86:89], v[168:171], v[200:203], v[86:89]
	v_mfma_f32_16x16x32_bf16 v[82:85], v[176:179], v[200:203], v[82:85]
	v_mfma_f32_16x16x32_bf16 v[70:73], v[168:171], v[208:211], v[70:73]
	v_mfma_f32_16x16x32_bf16 v[66:69], v[176:179], v[208:211], v[66:69]
	v_mfma_f32_16x16x32_bf16 v[118:121], v[172:175], v[188:191], v[118:121]
	v_mfma_f32_16x16x32_bf16 v[114:117], v[180:183], v[188:191], v[114:117]
	v_mfma_f32_16x16x32_bf16 v[102:105], v[172:175], v[196:199], v[102:105]
	v_mfma_f32_16x16x32_bf16 v[98:101], v[180:183], v[196:199], v[98:101]
	v_mfma_f32_16x16x32_bf16 v[86:89], v[172:175], v[204:207], v[86:89]
	v_mfma_f32_16x16x32_bf16 v[82:85], v[180:183], v[204:207], v[82:85]
	v_mfma_f32_16x16x32_bf16 v[70:73], v[172:175], v[212:215], v[70:73]
	v_mfma_f32_16x16x32_bf16 v[66:69], v[180:183], v[212:215], v[66:69]
	s_barrier
	s_add_i32 s60, s72, s51
	s_mov_b32 m0, s60
	ds_read_b128 v[184:187], v150 offset:16384
	ds_read_b128 v[188:191], v150 offset:17408
	ds_read_b128 v[192:195], v150 offset:18432
	ds_read_b128 v[196:199], v150 offset:19456
	ds_read_b128 v[200:203], v150 offset:20480
	ds_read_b128 v[204:207], v150 offset:21504
	ds_read_b128 v[208:211], v150 offset:22528
	ds_read_b128 v[212:215], v150 offset:23552
	global_load_lds_dwordx4 v130, s[46:47]
	s_add_i32 m0, s60, 0x2000
	s_add_u32 s60, s46, 0x4000
	s_addc_u32 s61, s47, 0
	s_add_i32 s81, s73, s51
	global_load_lds_dwordx4 v132, s[46:47]
	s_mov_b32 m0, s81
	s_nop 0
	global_load_lds_dwordx4 v130, s[60:61]
	s_add_i32 m0, s81, 0x2000
	s_nop 0
	global_load_lds_dwordx4 v132, s[60:61]
	s_mov_b32 m0, s52
	s_nop 0
	global_load_lds_dwordx4 v130, s[48:49]
	s_mov_b32 m0, s53
	s_nop 0
	global_load_lds_dwordx4 v132, s[48:49]
	s_waitcnt vmcnt(8)
	s_barrier
	s_waitcnt lgkmcnt(0)
	v_mfma_f32_16x16x32_bf16 v[62:65], v[152:155], v[184:187], v[62:65]
	v_mfma_f32_16x16x32_bf16 v[58:61], v[160:163], v[184:187], v[58:61]
	v_mfma_f32_16x16x32_bf16 v[46:49], v[152:155], v[192:195], v[46:49]
	v_mfma_f32_16x16x32_bf16 v[42:45], v[160:163], v[192:195], v[42:45]
	v_mfma_f32_16x16x32_bf16 v[30:33], v[152:155], v[200:203], v[30:33]
	v_mfma_f32_16x16x32_bf16 v[26:29], v[160:163], v[200:203], v[26:29]
	v_mfma_f32_16x16x32_bf16 v[14:17], v[152:155], v[208:211], v[14:17]
	v_mfma_f32_16x16x32_bf16 v[10:13], v[160:163], v[208:211], v[10:13]
	v_mfma_f32_16x16x32_bf16 v[62:65], v[156:159], v[188:191], v[62:65]
	v_mfma_f32_16x16x32_bf16 v[58:61], v[164:167], v[188:191], v[58:61]
	v_mfma_f32_16x16x32_bf16 v[46:49], v[156:159], v[196:199], v[46:49]
	v_mfma_f32_16x16x32_bf16 v[42:45], v[164:167], v[196:199], v[42:45]
	v_mfma_f32_16x16x32_bf16 v[30:33], v[156:159], v[204:207], v[30:33]
	v_mfma_f32_16x16x32_bf16 v[26:29], v[164:167], v[204:207], v[26:29]
	v_mfma_f32_16x16x32_bf16 v[14:17], v[156:159], v[212:215], v[14:17]
	v_mfma_f32_16x16x32_bf16 v[10:13], v[164:167], v[212:215], v[10:13]
	v_mfma_f32_16x16x32_bf16 v[54:57], v[168:171], v[184:187], v[54:57]
	v_mfma_f32_16x16x32_bf16 v[50:53], v[176:179], v[184:187], v[50:53]
	v_mfma_f32_16x16x32_bf16 v[38:41], v[168:171], v[192:195], v[38:41]
	v_mfma_f32_16x16x32_bf16 v[34:37], v[176:179], v[192:195], v[34:37]
	v_mfma_f32_16x16x32_bf16 v[22:25], v[168:171], v[200:203], v[22:25]
	v_mfma_f32_16x16x32_bf16 v[18:21], v[176:179], v[200:203], v[18:21]
	v_mfma_f32_16x16x32_bf16 v[6:9], v[168:171], v[208:211], v[6:9]
	v_mfma_f32_16x16x32_bf16 v[2:5], v[176:179], v[208:211], v[2:5]
	v_mfma_f32_16x16x32_bf16 v[54:57], v[172:175], v[188:191], v[54:57]
	v_mfma_f32_16x16x32_bf16 v[50:53], v[180:183], v[188:191], v[50:53]
	v_mfma_f32_16x16x32_bf16 v[38:41], v[172:175], v[196:199], v[38:41]
	v_mfma_f32_16x16x32_bf16 v[34:37], v[180:183], v[196:199], v[34:37]
	v_mfma_f32_16x16x32_bf16 v[22:25], v[172:175], v[204:207], v[22:25]
	v_mfma_f32_16x16x32_bf16 v[18:21], v[180:183], v[204:207], v[18:21]
	v_mfma_f32_16x16x32_bf16 v[6:9], v[172:175], v[212:215], v[6:9]
	v_mfma_f32_16x16x32_bf16 v[2:5], v[180:183], v[212:215], v[2:5]
	s_barrier
; #define PG8_STAGE(bufoff, gbase, voff) do { _Pragma("unroll") for (int _i = 0; _i < 2; ++_i) \
;         __builtin_amdgcn_global_load_lds((const unsigned*)((const char*)(gbase) + (voff)[_i]), (LAS unsigned*)(lds + (bufoff) + ldsw + _i * 8192), 16, 0, 0); } while (0)
; #define PG8_LDA(dst, b, h) do { _Pragma("unroll") for (int m = 0; m < 4; ++m) _Pragma("unroll") for (int k = 0; k < 2; ++k) dst[m][k] = *(const LAS bf16x8*)(lds + PG8_SA(b, h) + aoff + m * 2048 + k * 1024); } while (0)
; #define PG8_WAIT_V(n) asm volatile("s_waitcnt vmcnt(" #n ")" ::: "memory")
; #define PG8_WAIT_L(n) asm volatile("s_waitcnt lgkmcnt(" #n ")" ::: "memory")
; template <class Epi, class Sched, bool ABLK = false, bool ALIGN_EPI = true, bool SP2 = true, bool BBLK = true>
; __device__ __forceinline__ void gemm_phase(LAS unsigned char* lds, const Gemm g, const Sched& S, const Epi& E) {
;     ...
;         for (int t = 0; t < nt; t += 2) {
;             const bool last = (t == nt - 2);
;             const char* a1 = a_tile(uA, tbA + t + 1);
;             const char* a2 = last ? a_tile(nuA, ntbA) : a_tile(uA, tbA + t + 2); const char* b2 = last ? nB : cB + (size_t)(t + 2) * kstepB;
;             const char* a3 = last ? a_tile(nuA, ntbA + 1) : a_tile(uA, tbA + t + 3); const char* b3 = b2 + kstepB;
;             if (last && has_next) S.a_ready(nxt);
;             if constexpr (SP2) {
;             PG8_LDB(B0, 0, 0); PG8_LDB(B1, 0, 1); PG8_SCHED; PG8_LDA(At, 0, 0); PG8_STAGE(PG8_SA(1, 1), a1 + hstepA, voffA);
;             PG8_WAIT_V(8); PG8_WAIT_L(0); PG8_BAR; PG8_MMA(0, 0, At, B0); PG8_MMA(0, 1, At, B1); PG8_BAR; PG8_SCHED;
;             PG8_LDA(At, 0, 1); PG8_STAGE(PG8_SB(0, 0), b2, voffB); PG8_STAGE(PG8_SB(0, 1), b2 + hstepB, voffB); PG8_STAGE(PG8_SA(0, 0), a2, voffA);
;             PG8_WAIT_V(8); PG8_WAIT_L(0); PG8_BAR; PG8_MMA(1, 0, At, B0); PG8_MMA(1, 1, At, B1); PG8_BAR; PG8_SCHED;
;             PG8_LDB(B0, 1, 0); PG8_LDB(B1, 1, 1); PG8_SCHED; PG8_LDA(At, 1, 0); PG8_STAGE(PG8_SA(0, 1), a2 + hstepA, voffA);
;             PG8_WAIT_V(8); PG8_WAIT_L(0); PG8_BAR; PG8_MMA(0, 0, At, B0); PG8_MMA(0, 1, At, B1); PG8_BAR; PG8_SCHED;
;             PG8_LDA(At, 1, 1); PG8_STAGE(PG8_SB(1, 0), b3, voffB); PG8_STAGE(PG8_SB(1, 1), b3 + hstepB, voffB); PG8_STAGE(PG8_SA(1, 0), a3, voffA);
;             PG8_WAIT_V(8); PG8_WAIT_L(0); PG8_BAR; PG8_MMA(1, 0, At, B0); PG8_MMA(1, 1, At, B1); PG8_BAR; PG8_SCHED;
	s_add_i32 s60, 0, 0x18000
	v_add_u32_e32 v151, s60, v146
	s_add_i32 s61, 0, 0x1c000
	ds_read_b128 v[152:155], v151
	ds_read_b128 v[156:159], v151 offset:1024
	ds_read_b128 v[160:163], v151 offset:2048
	ds_read_b128 v[164:167], v151 offset:3072
	v_add_u32_e32 v151, s61, v146
	ds_read_b128 v[168:171], v151
	ds_read_b128 v[172:175], v151 offset:1024
	ds_read_b128 v[176:179], v151 offset:2048
	ds_read_b128 v[180:183], v151 offset:3072
	s_add_u32 s48, s48, 0x4000
	s_addc_u32 s49, s49, 0
	s_mov_b32 m0, s54
	ds_read_b128 v[184:187], v150 offset:32768
	ds_read_b128 v[188:191], v150 offset:33792
	ds_read_b128 v[192:195], v150 offset:34816
	ds_read_b128 v[196:199], v150 offset:35840
	ds_read_b128 v[200:203], v150 offset:36864
	ds_read_b128 v[204:207], v150 offset:37888
	ds_read_b128 v[208:211], v150 offset:38912
	ds_read_b128 v[212:215], v150 offset:39936
	global_load_lds_dwordx4 v130, s[48:49]
	s_mov_b32 m0, s55
	s_nop 0
	global_load_lds_dwordx4 v132, s[48:49]
	s_waitcnt vmcnt(8)
	s_barrier
	s_waitcnt lgkmcnt(0)
	v_mfma_f32_16x16x32_bf16 v[126:129], v[152:155], v[184:187], v[126:129]
	v_mfma_f32_16x16x32_bf16 v[122:125], v[160:163], v[184:187], v[122:125]
	v_mfma_f32_16x16x32_bf16 v[110:113], v[152:155], v[192:195], v[110:113]
	v_mfma_f32_16x16x32_bf16 v[106:109], v[160:163], v[192:195], v[106:109]
	v_mfma_f32_16x16x32_bf16 v[94:97], v[152:155], v[200:203], v[94:97]
	v_mfma_f32_16x16x32_bf16 v[90:93], v[160:163], v[200:203], v[90:93]
	v_mfma_f32_16x16x32_bf16 v[78:81], v[152:155], v[208:211], v[78:81]
	v_mfma_f32_16x16x32_bf16 v[74:77], v[160:163], v[208:211], v[74:77]
	v_mfma_f32_16x16x32_bf16 v[126:129], v[156:159], v[188:191], v[126:129]
	v_mfma_f32_16x16x32_bf16 v[122:125], v[164:167], v[188:191], v[122:125]
	v_mfma_f32_16x16x32_bf16 v[110:113], v[156:159], v[196:199], v[110:113]
	v_mfma_f32_16x16x32_bf16 v[106:109], v[164:167], v[196:199], v[106:109]
	v_mfma_f32_16x16x32_bf16 v[94:97], v[156:159], v[204:207], v[94:97]
	v_mfma_f32_16x16x32_bf16 v[90:93], v[164:167], v[204:207], v[90:93]
	v_mfma_f32_16x16x32_bf16 v[78:81], v[156:159], v[212:215], v[78:81]
	v_mfma_f32_16x16x32_bf16 v[74:77], v[164:167], v[212:215], v[74:77]
	v_mfma_f32_16x16x32_bf16 v[118:121], v[168:171], v[184:187], v[118:121]
	v_mfma_f32_16x16x32_bf16 v[114:117], v[176:179], v[184:187], v[114:117]
	v_mfma_f32_16x16x32_bf16 v[102:105], v[168:171], v[192:195], v[102:105]
	v_mfma_f32_16x16x32_bf16 v[98:101], v[176:179], v[192:195], v[98:101]
	v_mfma_f32_16x16x32_bf16 v[86:89], v[168:171], v[200:203], v[86:89]
	v_mfma_f32_16x16x32_bf16 v[82:85], v[176:179], v[200:203], v[82:85]
	v_mfma_f32_16x16x32_bf16 v[70:73], v[168:171], v[208:211], v[70:73]
	v_mfma_f32_16x16x32_bf16 v[66:69], v[176:179], v[208:211], v[66:69]
	v_mfma_f32_16x16x32_bf16 v[118:121], v[172:175], v[188:191], v[118:121]
	v_mfma_f32_16x16x32_bf16 v[114:117], v[180:183], v[188:191], v[114:117]
	v_mfma_f32_16x16x32_bf16 v[102:105], v[172:175], v[196:199], v[102:105]
	v_mfma_f32_16x16x32_bf16 v[98:101], v[180:183], v[196:199], v[98:101]
	v_mfma_f32_16x16x32_bf16 v[86:89], v[172:175], v[204:207], v[86:89]
	v_mfma_f32_16x16x32_bf16 v[82:85], v[180:183], v[204:207], v[82:85]
	v_mfma_f32_16x16x32_bf16 v[70:73], v[172:175], v[212:215], v[70:73]
	v_mfma_f32_16x16x32_bf16 v[66:69], v[180:183], v[212:215], v[66:69]
	s_barrier
	s_add_u32 s48, s46, 0x8000
	s_addc_u32 s49, s47, 0
	s_add_i32 s81, s60, s51
	s_mov_b32 m0, s81
	ds_read_b128 v[184:187], v150 offset:49152
	ds_read_b128 v[188:191], v150 offset:50176
	ds_read_b128 v[192:195], v150 offset:51200
	ds_read_b128 v[196:199], v150 offset:52224
	ds_read_b128 v[200:203], v150 offset:53248
	ds_read_b128 v[204:207], v150 offset:54272
	ds_read_b128 v[208:211], v150 offset:55296
	ds_read_b128 v[212:215], v150 offset:56320
	global_load_lds_dwordx4 v130, s[48:49]
	s_add_i32 m0, s81, 0x2000
	s_add_u32 s46, s46, 0xc000
	v_lshl_add_u64 v[216:217], s[48:49], 0, v[132:133]
	s_addc_u32 s47, s47, 0
	s_add_i32 s48, s61, s51
	global_load_lds_dwordx4 v[216:217], off
	s_mov_b32 m0, s48
	s_nop 0
	global_load_lds_dwordx4 v130, s[46:47]
	s_add_i32 m0, s48, 0x2000
	s_nop 0
	global_load_lds_dwordx4 v132, s[46:47]
	s_mov_b32 m0, s56
	s_nop 0
	global_load_lds_dwordx4 v130, s[42:43]
	s_mov_b32 m0, s57
	s_nop 0
	global_load_lds_dwordx4 v132, s[42:43]
	s_waitcnt vmcnt(8)
	s_barrier
	s_waitcnt lgkmcnt(0)
	v_mfma_f32_16x16x32_bf16 v[62:65], v[152:155], v[184:187], v[62:65]
	v_mfma_f32_16x16x32_bf16 v[58:61], v[160:163], v[184:187], v[58:61]
	v_mfma_f32_16x16x32_bf16 v[46:49], v[152:155], v[192:195], v[46:49]
	v_mfma_f32_16x16x32_bf16 v[42:45], v[160:163], v[192:195], v[42:45]
	v_mfma_f32_16x16x32_bf16 v[30:33], v[152:155], v[200:203], v[30:33]
	v_mfma_f32_16x16x32_bf16 v[26:29], v[160:163], v[200:203], v[26:29]
	v_mfma_f32_16x16x32_bf16 v[14:17], v[152:155], v[208:211], v[14:17]
	v_mfma_f32_16x16x32_bf16 v[10:13], v[160:163], v[208:211], v[10:13]
	v_mfma_f32_16x16x32_bf16 v[62:65], v[156:159], v[188:191], v[62:65]
	v_mfma_f32_16x16x32_bf16 v[58:61], v[164:167], v[188:191], v[58:61]
	v_mfma_f32_16x16x32_bf16 v[46:49], v[156:159], v[196:199], v[46:49]
	v_mfma_f32_16x16x32_bf16 v[42:45], v[164:167], v[196:199], v[42:45]
	v_mfma_f32_16x16x32_bf16 v[30:33], v[156:159], v[204:207], v[30:33]
	v_mfma_f32_16x16x32_bf16 v[26:29], v[164:167], v[204:207], v[26:29]
	v_mfma_f32_16x16x32_bf16 v[14:17], v[156:159], v[212:215], v[14:17]
	v_mfma_f32_16x16x32_bf16 v[10:13], v[164:167], v[212:215], v[10:13]
	v_mfma_f32_16x16x32_bf16 v[54:57], v[168:171], v[184:187], v[54:57]
	v_mfma_f32_16x16x32_bf16 v[50:53], v[176:179], v[184:187], v[50:53]
	v_mfma_f32_16x16x32_bf16 v[38:41], v[168:171], v[192:195], v[38:41]
	v_mfma_f32_16x16x32_bf16 v[34:37], v[176:179], v[192:195], v[34:37]
	v_mfma_f32_16x16x32_bf16 v[22:25], v[168:171], v[200:203], v[22:25]
	v_mfma_f32_16x16x32_bf16 v[18:21], v[176:179], v[200:203], v[18:21]
	v_mfma_f32_16x16x32_bf16 v[6:9], v[168:171], v[208:211], v[6:9]
	v_mfma_f32_16x16x32_bf16 v[2:5], v[176:179], v[208:211], v[2:5]
	v_mfma_f32_16x16x32_bf16 v[54:57], v[172:175], v[188:191], v[54:57]
	v_mfma_f32_16x16x32_bf16 v[50:53], v[180:183], v[188:191], v[50:53]
	v_mfma_f32_16x16x32_bf16 v[38:41], v[172:175], v[196:199], v[38:41]
	v_mfma_f32_16x16x32_bf16 v[34:37], v[180:183], v[196:199], v[34:37]
	v_mfma_f32_16x16x32_bf16 v[22:25], v[172:175], v[204:207], v[22:25]
	v_mfma_f32_16x16x32_bf16 v[18:21], v[180:183], v[204:207], v[18:21]
	v_mfma_f32_16x16x32_bf16 v[6:9], v[172:175], v[212:215], v[6:9]
	v_mfma_f32_16x16x32_bf16 v[2:5], v[180:183], v[212:215], v[2:5]
	s_barrier
	s_add_u32 s40, s40, 0x10000
	s_addc_u32 s41, s41, 0
	s_cmp_ge_u32 s79, s59
	s_cbranch_scc0 .LBB0_540
	s_and_b64 vcc, exec, s[12:13]
	s_cbranch_vccz .LBB0_543
	s_barrier

; #define PG8_STAGE(bufoff, gbase, voff) do { _Pragma("unroll") for (int _i = 0; _i < 2; ++_i) \
;         __builtin_amdgcn_global_load_lds((const unsigned*)((const char*)(gbase) + (voff)[_i]), (LAS unsigned*)(lds + (bufoff) + ldsw + _i * 8192), 16, 0, 0); } while (0)
; #define PG8_LDA(dst, b, h) do { _Pragma("unroll") for (int m = 0; m < 4; ++m) _Pragma("unroll") for (int k = 0; k < 2; ++k) dst[m][k] = *(const LAS bf16x8*)(lds + PG8_SA(b, h) + aoff + m * 2048 + k * 1024); } while (0)
; #define PG8_LDB(dst, b, h) do { _Pragma("unroll") for (int n = 0; n < 2; ++n) _Pragma("unroll") for (int k = 0; k < 2; ++k) dst[n][k] = *(const LAS bf16x8*)(lds + PG8_SB(b, h) + boff + n * 2048 + k * 1024); } while (0)
; #define PG8_WAIT_V(n) asm volatile("s_waitcnt vmcnt(" #n ")" ::: "memory")
; #define PG8_WAIT_L(n) asm volatile("s_waitcnt lgkmcnt(" #n ")" ::: "memory")
; template <class Epi, class Sched, bool ABLK = false, bool ALIGN_EPI = true, bool SP2 = true, bool BBLK = true>
; __device__ __forceinline__ void gemm_phase(LAS unsigned char* lds, const Gemm g, const Sched& S, const Epi& E) {
;     ...
;         const bool has_next = S.next(ui + 1, nxt);
;         const int nt = cur.nt;
;         const char* nuA = has_next ? a_unit(nxt) : uA; const int ntbA = has_next ? nxt.k0 / BK : tbA; const char* nB = has_next ? (const char*)g.Bt + (size_t)nxt.pn * tstepB + b_k0(nxt.k0) : cB;
;         for (int t = 0; t < nt; t += 2) {
;             const bool last = (t == nt - 2);
;             const char* a1 = a_tile(uA, tbA + t + 1);
;             const char* a2 = last ? a_tile(nuA, ntbA) : a_tile(uA, tbA + t + 2); const char* b2 = last ? nB : cB + (size_t)(t + 2) * kstepB;
;             const char* a3 = last ? a_tile(nuA, ntbA + 1) : a_tile(uA, tbA + t + 3); const char* b3 = b2 + kstepB;
;             if (last && has_next) S.a_ready(nxt);
;             if constexpr (SP2) {
;             PG8_LDB(B0, 0, 0); PG8_LDB(B1, 0, 1); PG8_SCHED; PG8_LDA(At, 0, 0); PG8_STAGE(PG8_SA(1, 1), a1 + hstepA, voffA);
;             PG8_WAIT_V(8); PG8_WAIT_L(0); PG8_BAR; PG8_MMA(0, 0, At, B0); PG8_MMA(0, 1, At, B1); PG8_BAR; PG8_SCHED;
;             PG8_LDA(At, 0, 1); PG8_STAGE(PG8_SB(0, 0), b2, voffB); PG8_STAGE(PG8_SB(0, 1), b2 + hstepB, voffB); PG8_STAGE(PG8_SA(0, 0), a2, voffA);
;             PG8_WAIT_V(8); PG8_WAIT_L(0); PG8_BAR; PG8_MMA(1, 0, At, B0); PG8_MMA(1, 1, At, B1); PG8_BAR; PG8_SCHED;
.LBB0_667:
	s_ashr_i32 s15, s14, 31
	s_lshl_b64 s[4:5], s[14:15], 20
	s_add_u32 s18, s59, s4
	s_addc_u32 s19, s62, s5
	s_and_b64 s[4:5], s[20:21], exec
	s_cselect_b32 s2, s19, s27
	s_cselect_b32 s4, s18, s26
	s_ashr_i32 s17, s16, 31
	s_lshl_b64 s[22:23], s[16:17], 20
	s_add_u32 s22, s39, s22
	s_addc_u32 s23, s40, s23
	s_and_b64 s[30:31], s[20:21], exec
	s_cselect_b32 s5, s23, s29
	s_cselect_b32 s9, s22, s28
	s_add_u32 s15, s4, 0x80
	s_addc_u32 s17, s2, 0
	s_add_u32 s52, s28, 0x10000
	v_mov_b32_e32 v2, 0
	s_addc_u32 s53, s29, 0
	v_lshl_add_u64 v[180:181], s[26:27], 0, v[176:177]
	v_lshl_add_u64 v[182:183], s[26:27], 0, v[178:179]
	s_mov_b32 s54, -2
	s_mov_b64 s[28:29], 0
	ds_read_b128 v[184:187], v153
	ds_read_b128 v[188:191], v153 offset:1024
	ds_read_b128 v[192:195], v153 offset:2048
	ds_read_b128 v[196:199], v153 offset:3072
	ds_read_b128 v[200:203], v157
	ds_read_b128 v[204:207], v157 offset:1024
	ds_read_b128 v[208:211], v157 offset:2048
	ds_read_b128 v[212:215], v157 offset:3072
	s_add_u32 s30, s26, s28
	s_addc_u32 s31, s27, s29
	s_add_u32 s36, s30, 0x100
	s_addc_u32 s37, s31, 0
	s_add_u32 s30, s30, 0x180
	s_addc_u32 s31, s31, 0
	s_cmpk_eq_i32 s28, 0xf00
	s_cselect_b32 s31, s17, s31
	s_cselect_b32 s30, s15, s30
	s_cselect_b32 s35, s5, s53
	s_cselect_b32 s34, s9, s52
	s_cselect_b32 s37, s2, s37
	s_cselect_b32 s36, s4, s36
	v_lshl_add_u64 v[248:249], v[180:181], 0, s[28:29]
	s_add_i32 m0, s25, 0xc000
	ds_read_b128 v[216:219], v149
	ds_read_b128 v[220:223], v149 offset:1024
	ds_read_b128 v[224:227], v149 offset:2048
	ds_read_b128 v[228:231], v149 offset:3072
	ds_read_b128 v[232:235], v149 offset:4096
	ds_read_b128 v[236:239], v149 offset:5120
	ds_read_b128 v[240:243], v149 offset:6144
	ds_read_b128 v[244:247], v149 offset:7168
	global_load_lds_dwordx4 v[248:249], off
	v_lshl_add_u64 v[248:249], v[182:183], 0, s[28:29]
	s_add_i32 m0, s25, 0xe000
	s_nop 0
	global_load_lds_dwordx4 v[248:249], off
	s_waitcnt vmcnt(8)
	s_barrier
	s_waitcnt lgkmcnt(0)
	v_mfma_f32_16x16x32_bf16 v[126:129], v[184:187], v[216:219], 0
	v_mfma_f32_16x16x32_bf16 v[122:125], v[192:195], v[216:219], 0
	v_mfma_f32_16x16x32_bf16 v[110:113], v[184:187], v[224:227], 0
	v_mfma_f32_16x16x32_bf16 v[106:109], v[192:195], v[224:227], 0
	v_mfma_f32_16x16x32_bf16 v[94:97], v[184:187], v[232:235], 0
	v_mfma_f32_16x16x32_bf16 v[90:93], v[192:195], v[232:235], 0
	v_mfma_f32_16x16x32_bf16 v[78:81], v[184:187], v[240:243], 0
	v_mfma_f32_16x16x32_bf16 v[74:77], v[192:195], v[240:243], 0
	v_mfma_f32_16x16x32_bf16 v[126:129], v[188:191], v[220:223], v[126:129]
	v_mfma_f32_16x16x32_bf16 v[122:125], v[196:199], v[220:223], v[122:125]
	v_mfma_f32_16x16x32_bf16 v[110:113], v[188:191], v[228:231], v[110:113]
	v_mfma_f32_16x16x32_bf16 v[106:109], v[196:199], v[228:231], v[106:109]
	v_mfma_f32_16x16x32_bf16 v[94:97], v[188:191], v[236:239], v[94:97]
	v_mfma_f32_16x16x32_bf16 v[90:93], v[196:199], v[236:239], v[90:93]
	v_mfma_f32_16x16x32_bf16 v[78:81], v[188:191], v[244:247], v[78:81]
	v_mfma_f32_16x16x32_bf16 v[74:77], v[196:199], v[244:247], v[74:77]
	v_mfma_f32_16x16x32_bf16 v[118:121], v[200:203], v[216:219], 0
	v_mfma_f32_16x16x32_bf16 v[114:117], v[208:211], v[216:219], 0
	v_mfma_f32_16x16x32_bf16 v[102:105], v[200:203], v[224:227], 0
	v_mfma_f32_16x16x32_bf16 v[98:101], v[208:211], v[224:227], 0
	v_mfma_f32_16x16x32_bf16 v[86:89], v[200:203], v[232:235], 0
	v_mfma_f32_16x16x32_bf16 v[82:85], v[208:211], v[232:235], 0
	v_mfma_f32_16x16x32_bf16 v[70:73], v[200:203], v[240:243], 0
	v_mfma_f32_16x16x32_bf16 v[66:69], v[208:211], v[240:243], 0
	v_mfma_f32_16x16x32_bf16 v[118:121], v[204:207], v[220:223], v[118:121]
	v_mfma_f32_16x16x32_bf16 v[114:117], v[212:215], v[220:223], v[114:117]
	v_mfma_f32_16x16x32_bf16 v[102:105], v[204:207], v[228:231], v[102:105]
	v_mfma_f32_16x16x32_bf16 v[98:101], v[212:215], v[228:231], v[98:101]
	v_mfma_f32_16x16x32_bf16 v[86:89], v[204:207], v[236:239], v[86:89]
	v_mfma_f32_16x16x32_bf16 v[82:85], v[212:215], v[236:239], v[82:85]
	v_mfma_f32_16x16x32_bf16 v[70:73], v[204:207], v[244:247], v[70:73]
	v_mfma_f32_16x16x32_bf16 v[66:69], v[212:215], v[244:247], v[66:69]
	s_barrier
	s_add_i32 s55, s72, s41
	s_mov_b32 m0, s55
	ds_read_b128 v[216:219], v149 offset:16384
	ds_read_b128 v[220:223], v149 offset:17408
	ds_read_b128 v[224:227], v149 offset:18432
	ds_read_b128 v[228:231], v149 offset:19456
	ds_read_b128 v[232:235], v149 offset:20480
	ds_read_b128 v[236:239], v149 offset:21504
	ds_read_b128 v[240:243], v149 offset:22528
	ds_read_b128 v[244:247], v149 offset:23552
	global_load_lds_dwordx4 v132, s[34:35]
	s_add_i32 m0, s55, 0x2000
	s_add_u32 s56, s34, 0x4000
	s_addc_u32 s57, s35, 0
	s_add_i32 s55, s73, s41
	global_load_lds_dwordx4 v136, s[34:35]
	s_mov_b32 m0, s55
	s_nop 0
	global_load_lds_dwordx4 v132, s[56:57]
	s_add_i32 m0, s55, 0x2000
	s_nop 0
	global_load_lds_dwordx4 v136, s[56:57]
	s_mov_b32 m0, s25
	s_nop 0
	global_load_lds_dwordx4 v130, s[36:37]
	s_mov_b32 m0, s42
	s_nop 0
	global_load_lds_dwordx4 v134, s[36:37]
	s_waitcnt vmcnt(8)
	s_barrier
; #define PG8_STAGE(bufoff, gbase, voff) do { _Pragma("unroll") for (int _i = 0; _i < 2; ++_i) \
;         __builtin_amdgcn_global_load_lds((const unsigned*)((const char*)(gbase) + (voff)[_i]), (LAS unsigned*)(lds + (bufoff) + ldsw + _i * 8192), 16, 0, 0); } while (0)
; #define PG8_LDA(dst, b, h) do { _Pragma("unroll") for (int m = 0; m < 4; ++m) _Pragma("unroll") for (int k = 0; k < 2; ++k) dst[m][k] = *(const LAS bf16x8*)(lds + PG8_SA(b, h) + aoff + m * 2048 + k * 1024); } while (0)
; #define PG8_LDB(dst, b, h) do { _Pragma("unroll") for (int n = 0; n < 2; ++n) _Pragma("unroll") for (int k = 0; k < 2; ++k) dst[n][k] = *(const LAS bf16x8*)(lds + PG8_SB(b, h) + boff + n * 2048 + k * 1024); } while (0)
; #define PG8_MMA(ai, bj, At, Bt) do { __builtin_amdgcn_s_setprio(1); _Pragma("unroll") for (int m = 0; m < 4; ++m) _Pragma("unroll") for (int n = 0; n < 2; ++n) _Pragma("unroll") for (int k = 0; k < 2; ++k) \
;         acc[ai][bj][m][n] = __builtin_amdgcn_mfma_f32_16x16x32_bf16(Bt[n][k], At[m][k], acc[ai][bj][m][n], 0, 0, 0); __builtin_amdgcn_s_setprio(0); } while (0)
; #define PG8_WAIT_V(n) asm volatile("s_waitcnt vmcnt(" #n ")" ::: "memory")
; #define PG8_WAIT_L(n) asm volatile("s_waitcnt lgkmcnt(" #n ")" ::: "memory")
; #define PG8_BAR __builtin_amdgcn_s_barrier()
; #define PG8_SCHED __builtin_amdgcn_sched_barrier(0)
; template <class Epi, class Sched, bool ABLK = false, bool ALIGN_EPI = true, bool SP2 = true, bool BBLK = true>
; __device__ __forceinline__ void gemm_phase(LAS unsigned char* lds, const Gemm g, const Sched& S, const Epi& E) {
;     ...
;             PG8_WAIT_V(8); PG8_WAIT_L(0); PG8_BAR; PG8_MMA(1, 0, At, B0); PG8_MMA(1, 1, At, B1); PG8_BAR; PG8_SCHED;
;             PG8_LDB(B0, 1, 0); PG8_LDB(B1, 1, 1); PG8_SCHED; PG8_LDA(At, 1, 0); PG8_STAGE(PG8_SA(0, 1), a2 + hstepA, voffA);
;             PG8_WAIT_V(8); PG8_WAIT_L(0); PG8_BAR; PG8_MMA(0, 0, At, B0); PG8_MMA(0, 1, At, B1); PG8_BAR; PG8_SCHED;
	s_waitcnt lgkmcnt(0)
	v_mfma_f32_16x16x32_bf16 v[62:65], v[184:187], v[216:219], 0
	v_mfma_f32_16x16x32_bf16 v[58:61], v[192:195], v[216:219], 0
	v_mfma_f32_16x16x32_bf16 v[46:49], v[184:187], v[224:227], 0
	v_mfma_f32_16x16x32_bf16 v[42:45], v[192:195], v[224:227], 0
	v_mfma_f32_16x16x32_bf16 v[30:33], v[184:187], v[232:235], 0
	v_mfma_f32_16x16x32_bf16 v[26:29], v[192:195], v[232:235], 0
	v_mfma_f32_16x16x32_bf16 v[14:17], v[184:187], v[240:243], 0
	v_mfma_f32_16x16x32_bf16 v[10:13], v[192:195], v[240:243], 0
	v_mfma_f32_16x16x32_bf16 v[62:65], v[188:191], v[220:223], v[62:65]
	v_mfma_f32_16x16x32_bf16 v[58:61], v[196:199], v[220:223], v[58:61]
	v_mfma_f32_16x16x32_bf16 v[46:49], v[188:191], v[228:231], v[46:49]
	v_mfma_f32_16x16x32_bf16 v[42:45], v[196:199], v[228:231], v[42:45]
	v_mfma_f32_16x16x32_bf16 v[30:33], v[188:191], v[236:239], v[30:33]
	v_mfma_f32_16x16x32_bf16 v[26:29], v[196:199], v[236:239], v[26:29]
	v_mfma_f32_16x16x32_bf16 v[14:17], v[188:191], v[244:247], v[14:17]
	v_mfma_f32_16x16x32_bf16 v[10:13], v[196:199], v[244:247], v[10:13]
	v_mfma_f32_16x16x32_bf16 v[54:57], v[200:203], v[216:219], 0
	v_mfma_f32_16x16x32_bf16 v[50:53], v[208:211], v[216:219], 0
	v_mfma_f32_16x16x32_bf16 v[38:41], v[200:203], v[224:227], 0
	v_mfma_f32_16x16x32_bf16 v[34:37], v[208:211], v[224:227], 0
	v_mfma_f32_16x16x32_bf16 v[22:25], v[200:203], v[232:235], 0
	v_mfma_f32_16x16x32_bf16 v[18:21], v[208:211], v[232:235], 0
	v_mfma_f32_16x16x32_bf16 v[6:9], v[200:203], v[240:243], 0
	v_mfma_f32_16x16x32_bf16 v[2:5], v[208:211], v[240:243], 0
	v_mfma_f32_16x16x32_bf16 v[54:57], v[204:207], v[220:223], v[54:57]
	v_mfma_f32_16x16x32_bf16 v[50:53], v[212:215], v[220:223], v[50:53]
	v_mfma_f32_16x16x32_bf16 v[38:41], v[204:207], v[228:231], v[38:41]
	v_mfma_f32_16x16x32_bf16 v[34:37], v[212:215], v[228:231], v[34:37]
	v_mfma_f32_16x16x32_bf16 v[22:25], v[204:207], v[236:239], v[22:25]
	v_mfma_f32_16x16x32_bf16 v[18:21], v[212:215], v[236:239], v[18:21]
	v_mfma_f32_16x16x32_bf16 v[6:9], v[204:207], v[244:247], v[6:9]
	v_mfma_f32_16x16x32_bf16 v[2:5], v[212:215], v[244:247], v[2:5]
	s_barrier
	v_add_u32_e32 v138, s60, v1
	ds_read_b128 v[184:187], v138
	ds_read_b128 v[188:191], v138 offset:1024
	ds_read_b128 v[192:195], v138 offset:2048
	ds_read_b128 v[196:199], v138 offset:3072
	v_add_u32_e32 v138, s61, v1
	ds_read_b128 v[200:203], v138
	ds_read_b128 v[204:207], v138 offset:1024
	ds_read_b128 v[208:211], v138 offset:2048
	ds_read_b128 v[212:215], v138 offset:3072
	s_add_u32 s36, s36, 0x80000
	s_addc_u32 s37, s37, 0
	s_mov_b32 m0, s43
	ds_read_b128 v[216:219], v149 offset:32768
	ds_read_b128 v[220:223], v149 offset:33792
	ds_read_b128 v[224:227], v149 offset:34816
	ds_read_b128 v[228:231], v149 offset:35840
	ds_read_b128 v[232:235], v149 offset:36864
	ds_read_b128 v[236:239], v149 offset:37888
	ds_read_b128 v[240:243], v149 offset:38912
	ds_read_b128 v[244:247], v149 offset:39936
	global_load_lds_dwordx4 v130, s[36:37]
	s_mov_b32 m0, s46
	s_nop 0
	global_load_lds_dwordx4 v134, s[36:37]
	s_waitcnt vmcnt(8)
	s_barrier
	s_waitcnt lgkmcnt(0)
	v_mfma_f32_16x16x32_bf16 v[126:129], v[184:187], v[216:219], v[126:129]
	v_mfma_f32_16x16x32_bf16 v[122:125], v[192:195], v[216:219], v[122:125]
	v_mfma_f32_16x16x32_bf16 v[110:113], v[184:187], v[224:227], v[110:113]
	v_mfma_f32_16x16x32_bf16 v[106:109], v[192:195], v[224:227], v[106:109]
	v_mfma_f32_16x16x32_bf16 v[94:97], v[184:187], v[232:235], v[94:97]
	v_mfma_f32_16x16x32_bf16 v[90:93], v[192:195], v[232:235], v[90:93]
	v_mfma_f32_16x16x32_bf16 v[78:81], v[184:187], v[240:243], v[78:81]
	v_mfma_f32_16x16x32_bf16 v[74:77], v[192:195], v[240:243], v[74:77]
	v_mfma_f32_16x16x32_bf16 v[126:129], v[188:191], v[220:223], v[126:129]
	v_mfma_f32_16x16x32_bf16 v[122:125], v[196:199], v[220:223], v[122:125]
	v_mfma_f32_16x16x32_bf16 v[110:113], v[188:191], v[228:231], v[110:113]
	v_mfma_f32_16x16x32_bf16 v[106:109], v[196:199], v[228:231], v[106:109]
	v_mfma_f32_16x16x32_bf16 v[94:97], v[188:191], v[236:239], v[94:97]
	v_mfma_f32_16x16x32_bf16 v[90:93], v[196:199], v[236:239], v[90:93]
	v_mfma_f32_16x16x32_bf16 v[78:81], v[188:191], v[244:247], v[78:81]
	v_mfma_f32_16x16x32_bf16 v[74:77], v[196:199], v[244:247], v[74:77]
	v_mfma_f32_16x16x32_bf16 v[118:121], v[200:203], v[216:219], v[118:121]
	v_mfma_f32_16x16x32_bf16 v[114:117], v[208:211], v[216:219], v[114:117]
	v_mfma_f32_16x16x32_bf16 v[102:105], v[200:203], v[224:227], v[102:105]
	v_mfma_f32_16x16x32_bf16 v[98:101], v[208:211], v[224:227], v[98:101]
	v_mfma_f32_16x16x32_bf16 v[86:89], v[200:203], v[232:235], v[86:89]
	v_mfma_f32_16x16x32_bf16 v[82:85], v[208:211], v[232:235], v[82:85]
	v_mfma_f32_16x16x32_bf16 v[70:73], v[200:203], v[240:243], v[70:73]
	v_mfma_f32_16x16x32_bf16 v[66:69], v[208:211], v[240:243], v[66:69]
	v_mfma_f32_16x16x32_bf16 v[118:121], v[204:207], v[220:223], v[118:121]
	v_mfma_f32_16x16x32_bf16 v[114:117], v[212:215], v[220:223], v[114:117]
	v_mfma_f32_16x16x32_bf16 v[102:105], v[204:207], v[228:231], v[102:105]
	v_mfma_f32_16x16x32_bf16 v[98:101], v[212:215], v[228:231], v[98:101]
	v_mfma_f32_16x16x32_bf16 v[86:89], v[204:207], v[236:239], v[86:89]
	v_mfma_f32_16x16x32_bf16 v[82:85], v[212:215], v[236:239], v[82:85]
	v_mfma_f32_16x16x32_bf16 v[70:73], v[204:207], v[244:247], v[70:73]
	v_mfma_f32_16x16x32_bf16 v[66:69], v[212:215], v[244:247], v[66:69]
	s_barrier
; #define PG8_STAGE(bufoff, gbase, voff) do { _Pragma("unroll") for (int _i = 0; _i < 2; ++_i) \
;         __builtin_amdgcn_global_load_lds((const unsigned*)((const char*)(gbase) + (voff)[_i]), (LAS unsigned*)(lds + (bufoff) + ldsw + _i * 8192), 16, 0, 0); } while (0)
; #define PG8_LDA(dst, b, h) do { _Pragma("unroll") for (int m = 0; m < 4; ++m) _Pragma("unroll") for (int k = 0; k < 2; ++k) dst[m][k] = *(const LAS bf16x8*)(lds + PG8_SA(b, h) + aoff + m * 2048 + k * 1024); } while (0)
; #define PG8_WAIT_V(n) asm volatile("s_waitcnt vmcnt(" #n ")" ::: "memory")
; #define PG8_WAIT_L(n) asm volatile("s_waitcnt lgkmcnt(" #n ")" ::: "memory")
; template <class Epi, class Sched, bool ABLK = false, bool ALIGN_EPI = true, bool SP2 = true, bool BBLK = true>
; __device__ __forceinline__ void gemm_phase(LAS unsigned char* lds, const Gemm g, const Sched& S, const Epi& E) {
;     ...
;         for (int t = 0; t < nt; t += 2) {
;             const bool last = (t == nt - 2);
;             const char* a1 = a_tile(uA, tbA + t + 1);
;             const char* a2 = last ? a_tile(nuA, ntbA) : a_tile(uA, tbA + t + 2); const char* b2 = last ? nB : cB + (size_t)(t + 2) * kstepB;
;             const char* a3 = last ? a_tile(nuA, ntbA + 1) : a_tile(uA, tbA + t + 3); const char* b3 = b2 + kstepB;
;             if (last && has_next) S.a_ready(nxt);
;             if constexpr (SP2) {
;             PG8_LDB(B0, 0, 0); PG8_LDB(B1, 0, 1); PG8_SCHED; PG8_LDA(At, 0, 0); PG8_STAGE(PG8_SA(1, 1), a1 + hstepA, voffA);
;             PG8_WAIT_V(8); PG8_WAIT_L(0); PG8_BAR; PG8_MMA(0, 0, At, B0); PG8_MMA(0, 1, At, B1); PG8_BAR; PG8_SCHED;
;             PG8_LDA(At, 0, 1); PG8_STAGE(PG8_SB(0, 0), b2, voffB); PG8_STAGE(PG8_SB(0, 1), b2 + hstepB, voffB); PG8_STAGE(PG8_SA(0, 0), a2, voffA);
;             PG8_WAIT_V(8); PG8_WAIT_L(0); PG8_BAR; PG8_MMA(1, 0, At, B0); PG8_MMA(1, 1, At, B1); PG8_BAR; PG8_SCHED;
;             PG8_LDB(B0, 1, 0); PG8_LDB(B1, 1, 1); PG8_SCHED; PG8_LDA(At, 1, 0); PG8_STAGE(PG8_SA(0, 1), a2 + hstepA, voffA);
;             PG8_WAIT_V(8); PG8_WAIT_L(0); PG8_BAR; PG8_MMA(0, 0, At, B0); PG8_MMA(0, 1, At, B1); PG8_BAR; PG8_SCHED;
;             PG8_LDA(At, 1, 1); PG8_STAGE(PG8_SB(1, 0), b3, voffB); PG8_STAGE(PG8_SB(1, 1), b3 + hstepB, voffB); PG8_STAGE(PG8_SA(1, 0), a3, voffA);
;             PG8_WAIT_V(8); PG8_WAIT_L(0); PG8_BAR; PG8_MMA(1, 0, At, B0); PG8_MMA(1, 1, At, B1); PG8_BAR; PG8_SCHED;
	s_add_u32 s36, s34, 0x8000
	s_addc_u32 s37, s35, 0
	s_add_i32 s55, s60, s41
	s_mov_b32 m0, s55
	ds_read_b128 v[216:219], v149 offset:49152
	ds_read_b128 v[220:223], v149 offset:50176
	ds_read_b128 v[224:227], v149 offset:51200
	ds_read_b128 v[228:231], v149 offset:52224
	ds_read_b128 v[232:235], v149 offset:53248
	ds_read_b128 v[236:239], v149 offset:54272
	ds_read_b128 v[240:243], v149 offset:55296
	ds_read_b128 v[244:247], v149 offset:56320
	global_load_lds_dwordx4 v132, s[36:37]
	s_add_i32 m0, s55, 0x2000
	s_add_u32 s34, s34, 0xc000
	v_lshl_add_u64 v[248:249], s[36:37], 0, v[136:137]
	s_addc_u32 s35, s35, 0
	s_add_i32 s36, s61, s41
	global_load_lds_dwordx4 v[248:249], off
	s_mov_b32 m0, s36
	s_nop 0
	global_load_lds_dwordx4 v132, s[34:35]
	s_add_i32 m0, s36, 0x2000
	s_nop 0
	global_load_lds_dwordx4 v136, s[34:35]
	s_mov_b32 m0, s47
	s_nop 0
	global_load_lds_dwordx4 v130, s[30:31]
	s_mov_b32 m0, s48
	s_nop 0
	global_load_lds_dwordx4 v134, s[30:31]
	s_waitcnt vmcnt(8)
	s_barrier
	s_waitcnt lgkmcnt(0)
	v_mfma_f32_16x16x32_bf16 v[62:65], v[184:187], v[216:219], v[62:65]
	v_mfma_f32_16x16x32_bf16 v[58:61], v[192:195], v[216:219], v[58:61]
	v_mfma_f32_16x16x32_bf16 v[46:49], v[184:187], v[224:227], v[46:49]
	v_mfma_f32_16x16x32_bf16 v[42:45], v[192:195], v[224:227], v[42:45]
	v_mfma_f32_16x16x32_bf16 v[30:33], v[184:187], v[232:235], v[30:33]
	v_mfma_f32_16x16x32_bf16 v[26:29], v[192:195], v[232:235], v[26:29]
	v_mfma_f32_16x16x32_bf16 v[14:17], v[184:187], v[240:243], v[14:17]
	v_mfma_f32_16x16x32_bf16 v[10:13], v[192:195], v[240:243], v[10:13]
	v_mfma_f32_16x16x32_bf16 v[62:65], v[188:191], v[220:223], v[62:65]
	v_mfma_f32_16x16x32_bf16 v[58:61], v[196:199], v[220:223], v[58:61]
	v_mfma_f32_16x16x32_bf16 v[46:49], v[188:191], v[228:231], v[46:49]
	v_mfma_f32_16x16x32_bf16 v[42:45], v[196:199], v[228:231], v[42:45]
	v_mfma_f32_16x16x32_bf16 v[30:33], v[188:191], v[236:239], v[30:33]
	v_mfma_f32_16x16x32_bf16 v[26:29], v[196:199], v[236:239], v[26:29]
	v_mfma_f32_16x16x32_bf16 v[14:17], v[188:191], v[244:247], v[14:17]
	v_mfma_f32_16x16x32_bf16 v[10:13], v[196:199], v[244:247], v[10:13]
	v_mfma_f32_16x16x32_bf16 v[54:57], v[200:203], v[216:219], v[54:57]
	v_mfma_f32_16x16x32_bf16 v[50:53], v[208:211], v[216:219], v[50:53]
	v_mfma_f32_16x16x32_bf16 v[38:41], v[200:203], v[224:227], v[38:41]
	v_mfma_f32_16x16x32_bf16 v[34:37], v[208:211], v[224:227], v[34:37]
	v_mfma_f32_16x16x32_bf16 v[22:25], v[200:203], v[232:235], v[22:25]
	v_mfma_f32_16x16x32_bf16 v[18:21], v[208:211], v[232:235], v[18:21]
	v_mfma_f32_16x16x32_bf16 v[6:9], v[200:203], v[240:243], v[6:9]
	v_mfma_f32_16x16x32_bf16 v[2:5], v[208:211], v[240:243], v[2:5]
	v_mfma_f32_16x16x32_bf16 v[54:57], v[204:207], v[220:223], v[54:57]
	v_mfma_f32_16x16x32_bf16 v[50:53], v[212:215], v[220:223], v[50:53]
	v_mfma_f32_16x16x32_bf16 v[38:41], v[204:207], v[228:231], v[38:41]
	v_mfma_f32_16x16x32_bf16 v[34:37], v[212:215], v[228:231], v[34:37]
	v_mfma_f32_16x16x32_bf16 v[22:25], v[204:207], v[236:239], v[22:25]
	v_mfma_f32_16x16x32_bf16 v[18:21], v[212:215], v[236:239], v[18:21]
	v_mfma_f32_16x16x32_bf16 v[6:9], v[204:207], v[244:247], v[6:9]
	v_mfma_f32_16x16x32_bf16 v[2:5], v[212:215], v[244:247], v[2:5]
	s_barrier
	s_add_i32 s54, s54, 2
	s_add_u32 s28, s28, 0x100
	s_addc_u32 s29, s29, 0
	s_add_u32 s52, s52, 0x10000
	s_addc_u32 s53, s53, 0
	s_cmp_gt_u32 s54, 29
.LBB0_668:
	ds_read_b128 v[184:187], v153
	ds_read_b128 v[188:191], v153 offset:1024
	ds_read_b128 v[192:195], v153 offset:2048
	ds_read_b128 v[196:199], v153 offset:3072
	ds_read_b128 v[200:203], v157
	ds_read_b128 v[204:207], v157 offset:1024
	ds_read_b128 v[208:211], v157 offset:2048
	ds_read_b128 v[212:215], v157 offset:3072
	s_add_u32 s30, s26, s28
	s_addc_u32 s31, s27, s29
	s_add_u32 s36, s30, 0x100
	s_addc_u32 s37, s31, 0
	s_add_u32 s30, s30, 0x180
	s_addc_u32 s31, s31, 0
	s_cmpk_eq_i32 s28, 0xf00
	s_cselect_b32 s31, s17, s31
	s_cselect_b32 s30, s15, s30
	s_cselect_b32 s35, s5, s53
	s_cselect_b32 s34, s9, s52
	s_cselect_b32 s37, s2, s37
	s_cselect_b32 s36, s4, s36
	v_lshl_add_u64 v[248:249], v[180:181], 0, s[28:29]
	s_add_i32 m0, s25, 0xc000
	ds_read_b128 v[216:219], v149
	ds_read_b128 v[220:223], v149 offset:1024
	ds_read_b128 v[224:227], v149 offset:2048
	ds_read_b128 v[228:231], v149 offset:3072
	ds_read_b128 v[232:235], v149 offset:4096
	ds_read_b128 v[236:239], v149 offset:5120
	ds_read_b128 v[240:243], v149 offset:6144
	ds_read_b128 v[244:247], v149 offset:7168
	global_load_lds_dwordx4 v[248:249], off
	v_lshl_add_u64 v[248:249], v[182:183], 0, s[28:29]
	s_add_i32 m0, s25, 0xe000
	s_nop 0
	global_load_lds_dwordx4 v[248:249], off
	s_waitcnt vmcnt(8)
	s_barrier
; #define PG8_STAGE(bufoff, gbase, voff) do { _Pragma("unroll") for (int _i = 0; _i < 2; ++_i) \
;         __builtin_amdgcn_global_load_lds((const unsigned*)((const char*)(gbase) + (voff)[_i]), (LAS unsigned*)(lds + (bufoff) + ldsw + _i * 8192), 16, 0, 0); } while (0)
; #define PG8_LDA(dst, b, h) do { _Pragma("unroll") for (int m = 0; m < 4; ++m) _Pragma("unroll") for (int k = 0; k < 2; ++k) dst[m][k] = *(const LAS bf16x8*)(lds + PG8_SA(b, h) + aoff + m * 2048 + k * 1024); } while (0)
; #define PG8_MMA(ai, bj, At, Bt) do { __builtin_amdgcn_s_setprio(1); _Pragma("unroll") for (int m = 0; m < 4; ++m) _Pragma("unroll") for (int n = 0; n < 2; ++n) _Pragma("unroll") for (int k = 0; k < 2; ++k) \
;         acc[ai][bj][m][n] = __builtin_amdgcn_mfma_f32_16x16x32_bf16(Bt[n][k], At[m][k], acc[ai][bj][m][n], 0, 0, 0); __builtin_amdgcn_s_setprio(0); } while (0)
; #define PG8_WAIT_V(n) asm volatile("s_waitcnt vmcnt(" #n ")" ::: "memory")
; #define PG8_WAIT_L(n) asm volatile("s_waitcnt lgkmcnt(" #n ")" ::: "memory")
; #define PG8_BAR __builtin_amdgcn_s_barrier()
; #define PG8_SCHED __builtin_amdgcn_sched_barrier(0)
; template <class Epi, class Sched, bool ABLK = false, bool ALIGN_EPI = true, bool SP2 = true, bool BBLK = true>
; __device__ __forceinline__ void gemm_phase(LAS unsigned char* lds, const Gemm g, const Sched& S, const Epi& E) {
;     ...
;             PG8_WAIT_V(8); PG8_WAIT_L(0); PG8_BAR; PG8_MMA(0, 0, At, B0); PG8_MMA(0, 1, At, B1); PG8_BAR; PG8_SCHED;
;             PG8_LDA(At, 0, 1); PG8_STAGE(PG8_SB(0, 0), b2, voffB); PG8_STAGE(PG8_SB(0, 1), b2 + hstepB, voffB); PG8_STAGE(PG8_SA(0, 0), a2, voffA);
;             PG8_WAIT_V(8); PG8_WAIT_L(0); PG8_BAR; PG8_MMA(1, 0, At, B0); PG8_MMA(1, 1, At, B1); PG8_BAR; PG8_SCHED;
	s_waitcnt lgkmcnt(0)
	v_mfma_f32_16x16x32_bf16 v[126:129], v[184:187], v[216:219], v[126:129]
	v_mfma_f32_16x16x32_bf16 v[122:125], v[192:195], v[216:219], v[122:125]
	v_mfma_f32_16x16x32_bf16 v[110:113], v[184:187], v[224:227], v[110:113]
	v_mfma_f32_16x16x32_bf16 v[106:109], v[192:195], v[224:227], v[106:109]
	v_mfma_f32_16x16x32_bf16 v[94:97], v[184:187], v[232:235], v[94:97]
	v_mfma_f32_16x16x32_bf16 v[90:93], v[192:195], v[232:235], v[90:93]
	v_mfma_f32_16x16x32_bf16 v[78:81], v[184:187], v[240:243], v[78:81]
	v_mfma_f32_16x16x32_bf16 v[74:77], v[192:195], v[240:243], v[74:77]
	v_mfma_f32_16x16x32_bf16 v[126:129], v[188:191], v[220:223], v[126:129]
	v_mfma_f32_16x16x32_bf16 v[122:125], v[196:199], v[220:223], v[122:125]
	v_mfma_f32_16x16x32_bf16 v[110:113], v[188:191], v[228:231], v[110:113]
	v_mfma_f32_16x16x32_bf16 v[106:109], v[196:199], v[228:231], v[106:109]
	v_mfma_f32_16x16x32_bf16 v[94:97], v[188:191], v[236:239], v[94:97]
	v_mfma_f32_16x16x32_bf16 v[90:93], v[196:199], v[236:239], v[90:93]
	v_mfma_f32_16x16x32_bf16 v[78:81], v[188:191], v[244:247], v[78:81]
	v_mfma_f32_16x16x32_bf16 v[74:77], v[196:199], v[244:247], v[74:77]
	v_mfma_f32_16x16x32_bf16 v[118:121], v[200:203], v[216:219], v[118:121]
	v_mfma_f32_16x16x32_bf16 v[114:117], v[208:211], v[216:219], v[114:117]
	v_mfma_f32_16x16x32_bf16 v[102:105], v[200:203], v[224:227], v[102:105]
	v_mfma_f32_16x16x32_bf16 v[98:101], v[208:211], v[224:227], v[98:101]
	v_mfma_f32_16x16x32_bf16 v[86:89], v[200:203], v[232:235], v[86:89]
	v_mfma_f32_16x16x32_bf16 v[82:85], v[208:211], v[232:235], v[82:85]
	v_mfma_f32_16x16x32_bf16 v[70:73], v[200:203], v[240:243], v[70:73]
	v_mfma_f32_16x16x32_bf16 v[66:69], v[208:211], v[240:243], v[66:69]
	v_mfma_f32_16x16x32_bf16 v[118:121], v[204:207], v[220:223], v[118:121]
	v_mfma_f32_16x16x32_bf16 v[114:117], v[212:215], v[220:223], v[114:117]
	v_mfma_f32_16x16x32_bf16 v[102:105], v[204:207], v[228:231], v[102:105]
	v_mfma_f32_16x16x32_bf16 v[98:101], v[212:215], v[228:231], v[98:101]
	v_mfma_f32_16x16x32_bf16 v[86:89], v[204:207], v[236:239], v[86:89]
	v_mfma_f32_16x16x32_bf16 v[82:85], v[212:215], v[236:239], v[82:85]
	v_mfma_f32_16x16x32_bf16 v[70:73], v[204:207], v[244:247], v[70:73]
	v_mfma_f32_16x16x32_bf16 v[66:69], v[212:215], v[244:247], v[66:69]
	s_barrier
	s_add_i32 s55, s72, s41
	s_mov_b32 m0, s55
	ds_read_b128 v[216:219], v149 offset:16384
	ds_read_b128 v[220:223], v149 offset:17408
	ds_read_b128 v[224:227], v149 offset:18432
	ds_read_b128 v[228:231], v149 offset:19456
	ds_read_b128 v[232:235], v149 offset:20480
	ds_read_b128 v[236:239], v149 offset:21504
	ds_read_b128 v[240:243], v149 offset:22528
	ds_read_b128 v[244:247], v149 offset:23552
	global_load_lds_dwordx4 v132, s[34:35]
	s_add_i32 m0, s55, 0x2000
	s_add_u32 s56, s34, 0x4000
	s_addc_u32 s57, s35, 0
	s_add_i32 s55, s73, s41
	global_load_lds_dwordx4 v136, s[34:35]
	s_mov_b32 m0, s55
	s_nop 0
	global_load_lds_dwordx4 v132, s[56:57]
	s_add_i32 m0, s55, 0x2000
	s_nop 0
	global_load_lds_dwordx4 v136, s[56:57]
	s_mov_b32 m0, s25
	s_nop 0
	global_load_lds_dwordx4 v130, s[36:37]
	s_mov_b32 m0, s42
	s_nop 0
	global_load_lds_dwordx4 v134, s[36:37]
	s_waitcnt vmcnt(8)
	s_barrier
	s_waitcnt lgkmcnt(0)
	v_mfma_f32_16x16x32_bf16 v[62:65], v[184:187], v[216:219], v[62:65]
	v_mfma_f32_16x16x32_bf16 v[58:61], v[192:195], v[216:219], v[58:61]
	v_mfma_f32_16x16x32_bf16 v[46:49], v[184:187], v[224:227], v[46:49]
	v_mfma_f32_16x16x32_bf16 v[42:45], v[192:195], v[224:227], v[42:45]
	v_mfma_f32_16x16x32_bf16 v[30:33], v[184:187], v[232:235], v[30:33]
	v_mfma_f32_16x16x32_bf16 v[26:29], v[192:195], v[232:235], v[26:29]
	v_mfma_f32_16x16x32_bf16 v[14:17], v[184:187], v[240:243], v[14:17]
	v_mfma_f32_16x16x32_bf16 v[10:13], v[192:195], v[240:243], v[10:13]
	v_mfma_f32_16x16x32_bf16 v[62:65], v[188:191], v[220:223], v[62:65]
	v_mfma_f32_16x16x32_bf16 v[58:61], v[196:199], v[220:223], v[58:61]
	v_mfma_f32_16x16x32_bf16 v[46:49], v[188:191], v[228:231], v[46:49]
	v_mfma_f32_16x16x32_bf16 v[42:45], v[196:199], v[228:231], v[42:45]
	v_mfma_f32_16x16x32_bf16 v[30:33], v[188:191], v[236:239], v[30:33]
	v_mfma_f32_16x16x32_bf16 v[26:29], v[196:199], v[236:239], v[26:29]
	v_mfma_f32_16x16x32_bf16 v[14:17], v[188:191], v[244:247], v[14:17]
	v_mfma_f32_16x16x32_bf16 v[10:13], v[196:199], v[244:247], v[10:13]
	v_mfma_f32_16x16x32_bf16 v[54:57], v[200:203], v[216:219], v[54:57]
	v_mfma_f32_16x16x32_bf16 v[50:53], v[208:211], v[216:219], v[50:53]
	v_mfma_f32_16x16x32_bf16 v[38:41], v[200:203], v[224:227], v[38:41]
	v_mfma_f32_16x16x32_bf16 v[34:37], v[208:211], v[224:227], v[34:37]
	v_mfma_f32_16x16x32_bf16 v[22:25], v[200:203], v[232:235], v[22:25]
	v_mfma_f32_16x16x32_bf16 v[18:21], v[208:211], v[232:235], v[18:21]
	v_mfma_f32_16x16x32_bf16 v[6:9], v[200:203], v[240:243], v[6:9]
	v_mfma_f32_16x16x32_bf16 v[2:5], v[208:211], v[240:243], v[2:5]
	v_mfma_f32_16x16x32_bf16 v[54:57], v[204:207], v[220:223], v[54:57]
	v_mfma_f32_16x16x32_bf16 v[50:53], v[212:215], v[220:223], v[50:53]
	v_mfma_f32_16x16x32_bf16 v[38:41], v[204:207], v[228:231], v[38:41]
	v_mfma_f32_16x16x32_bf16 v[34:37], v[212:215], v[228:231], v[34:37]
	v_mfma_f32_16x16x32_bf16 v[22:25], v[204:207], v[236:239], v[22:25]
	v_mfma_f32_16x16x32_bf16 v[18:21], v[212:215], v[236:239], v[18:21]
	v_mfma_f32_16x16x32_bf16 v[6:9], v[204:207], v[244:247], v[6:9]
	v_mfma_f32_16x16x32_bf16 v[2:5], v[212:215], v[244:247], v[2:5]
	s_barrier
; #define PG8_STAGE(bufoff, gbase, voff) do { _Pragma("unroll") for (int _i = 0; _i < 2; ++_i) \
;         __builtin_amdgcn_global_load_lds((const unsigned*)((const char*)(gbase) + (voff)[_i]), (LAS unsigned*)(lds + (bufoff) + ldsw + _i * 8192), 16, 0, 0); } while (0)
; #define PG8_LDA(dst, b, h) do { _Pragma("unroll") for (int m = 0; m < 4; ++m) _Pragma("unroll") for (int k = 0; k < 2; ++k) dst[m][k] = *(const LAS bf16x8*)(lds + PG8_SA(b, h) + aoff + m * 2048 + k * 1024); } while (0)
; #define PG8_LDB(dst, b, h) do { _Pragma("unroll") for (int n = 0; n < 2; ++n) _Pragma("unroll") for (int k = 0; k < 2; ++k) dst[n][k] = *(const LAS bf16x8*)(lds + PG8_SB(b, h) + boff + n * 2048 + k * 1024); } while (0)
; #define PG8_MMA(ai, bj, At, Bt) do { __builtin_amdgcn_s_setprio(1); _Pragma("unroll") for (int m = 0; m < 4; ++m) _Pragma("unroll") for (int n = 0; n < 2; ++n) _Pragma("unroll") for (int k = 0; k < 2; ++k) \
;         acc[ai][bj][m][n] = __builtin_amdgcn_mfma_f32_16x16x32_bf16(Bt[n][k], At[m][k], acc[ai][bj][m][n], 0, 0, 0); __builtin_amdgcn_s_setprio(0); } while (0)
; #define PG8_WAIT_V(n) asm volatile("s_waitcnt vmcnt(" #n ")" ::: "memory")
; #define PG8_WAIT_L(n) asm volatile("s_waitcnt lgkmcnt(" #n ")" ::: "memory")
; #define PG8_BAR __builtin_amdgcn_s_barrier()
; #define PG8_SCHED __builtin_amdgcn_sched_barrier(0)
; template <class Epi, class Sched, bool ABLK = false, bool ALIGN_EPI = true, bool SP2 = true, bool BBLK = true>
; __device__ __forceinline__ void gemm_phase(LAS unsigned char* lds, const Gemm g, const Sched& S, const Epi& E) {
;     ...
;             PG8_LDB(B0, 1, 0); PG8_LDB(B1, 1, 1); PG8_SCHED; PG8_LDA(At, 1, 0); PG8_STAGE(PG8_SA(0, 1), a2 + hstepA, voffA);
;             PG8_WAIT_V(8); PG8_WAIT_L(0); PG8_BAR; PG8_MMA(0, 0, At, B0); PG8_MMA(0, 1, At, B1); PG8_BAR; PG8_SCHED;
;             PG8_LDA(At, 1, 1); PG8_STAGE(PG8_SB(1, 0), b3, voffB); PG8_STAGE(PG8_SB(1, 1), b3 + hstepB, voffB); PG8_STAGE(PG8_SA(1, 0), a3, voffA);
;             PG8_WAIT_V(8); PG8_WAIT_L(0); PG8_BAR; PG8_MMA(1, 0, At, B0); PG8_MMA(1, 1, At, B1); PG8_BAR; PG8_SCHED;
	v_add_u32_e32 v138, s60, v1
	ds_read_b128 v[184:187], v138
	ds_read_b128 v[188:191], v138 offset:1024
	ds_read_b128 v[192:195], v138 offset:2048
	ds_read_b128 v[196:199], v138 offset:3072
	v_add_u32_e32 v138, s61, v1
	ds_read_b128 v[200:203], v138
	ds_read_b128 v[204:207], v138 offset:1024
	ds_read_b128 v[208:211], v138 offset:2048
	ds_read_b128 v[212:215], v138 offset:3072
	s_add_u32 s36, s36, 0x80000
	s_addc_u32 s37, s37, 0
	s_mov_b32 m0, s43
	ds_read_b128 v[216:219], v149 offset:32768
	ds_read_b128 v[220:223], v149 offset:33792
	ds_read_b128 v[224:227], v149 offset:34816
	ds_read_b128 v[228:231], v149 offset:35840
	ds_read_b128 v[232:235], v149 offset:36864
	ds_read_b128 v[236:239], v149 offset:37888
	ds_read_b128 v[240:243], v149 offset:38912
	ds_read_b128 v[244:247], v149 offset:39936
	global_load_lds_dwordx4 v130, s[36:37]
	s_mov_b32 m0, s46
	s_nop 0
	global_load_lds_dwordx4 v134, s[36:37]
	s_waitcnt vmcnt(8)
	s_barrier
	s_waitcnt lgkmcnt(0)
	v_mfma_f32_16x16x32_bf16 v[126:129], v[184:187], v[216:219], v[126:129]
	v_mfma_f32_16x16x32_bf16 v[122:125], v[192:195], v[216:219], v[122:125]
	v_mfma_f32_16x16x32_bf16 v[110:113], v[184:187], v[224:227], v[110:113]
	v_mfma_f32_16x16x32_bf16 v[106:109], v[192:195], v[224:227], v[106:109]
	v_mfma_f32_16x16x32_bf16 v[94:97], v[184:187], v[232:235], v[94:97]
	v_mfma_f32_16x16x32_bf16 v[90:93], v[192:195], v[232:235], v[90:93]
	v_mfma_f32_16x16x32_bf16 v[78:81], v[184:187], v[240:243], v[78:81]
	v_mfma_f32_16x16x32_bf16 v[74:77], v[192:195], v[240:243], v[74:77]
	v_mfma_f32_16x16x32_bf16 v[126:129], v[188:191], v[220:223], v[126:129]
	v_mfma_f32_16x16x32_bf16 v[122:125], v[196:199], v[220:223], v[122:125]
	v_mfma_f32_16x16x32_bf16 v[110:113], v[188:191], v[228:231], v[110:113]
	v_mfma_f32_16x16x32_bf16 v[106:109], v[196:199], v[228:231], v[106:109]
	v_mfma_f32_16x16x32_bf16 v[94:97], v[188:191], v[236:239], v[94:97]
	v_mfma_f32_16x16x32_bf16 v[90:93], v[196:199], v[236:239], v[90:93]
	v_mfma_f32_16x16x32_bf16 v[78:81], v[188:191], v[244:247], v[78:81]
	v_mfma_f32_16x16x32_bf16 v[74:77], v[196:199], v[244:247], v[74:77]
	v_mfma_f32_16x16x32_bf16 v[118:121], v[200:203], v[216:219], v[118:121]
	v_mfma_f32_16x16x32_bf16 v[114:117], v[208:211], v[216:219], v[114:117]
	v_mfma_f32_16x16x32_bf16 v[102:105], v[200:203], v[224:227], v[102:105]
	v_mfma_f32_16x16x32_bf16 v[98:101], v[208:211], v[224:227], v[98:101]
	v_mfma_f32_16x16x32_bf16 v[86:89], v[200:203], v[232:235], v[86:89]
	v_mfma_f32_16x16x32_bf16 v[82:85], v[208:211], v[232:235], v[82:85]
	v_mfma_f32_16x16x32_bf16 v[70:73], v[200:203], v[240:243], v[70:73]
	v_mfma_f32_16x16x32_bf16 v[66:69], v[208:211], v[240:243], v[66:69]
	v_mfma_f32_16x16x32_bf16 v[118:121], v[204:207], v[220:223], v[118:121]
	v_mfma_f32_16x16x32_bf16 v[114:117], v[212:215], v[220:223], v[114:117]
	v_mfma_f32_16x16x32_bf16 v[102:105], v[204:207], v[228:231], v[102:105]
	v_mfma_f32_16x16x32_bf16 v[98:101], v[212:215], v[228:231], v[98:101]
	v_mfma_f32_16x16x32_bf16 v[86:89], v[204:207], v[236:239], v[86:89]
	v_mfma_f32_16x16x32_bf16 v[82:85], v[212:215], v[236:239], v[82:85]
	v_mfma_f32_16x16x32_bf16 v[70:73], v[204:207], v[244:247], v[70:73]
	v_mfma_f32_16x16x32_bf16 v[66:69], v[212:215], v[244:247], v[66:69]
	s_barrier
	s_add_u32 s36, s34, 0x8000
	s_addc_u32 s37, s35, 0
	s_add_i32 s55, s60, s41
	s_mov_b32 m0, s55
	ds_read_b128 v[216:219], v149 offset:49152
	ds_read_b128 v[220:223], v149 offset:50176
	ds_read_b128 v[224:227], v149 offset:51200
	ds_read_b128 v[228:231], v149 offset:52224
	ds_read_b128 v[232:235], v149 offset:53248
	ds_read_b128 v[236:239], v149 offset:54272
	ds_read_b128 v[240:243], v149 offset:55296
	ds_read_b128 v[244:247], v149 offset:56320
	global_load_lds_dwordx4 v132, s[36:37]
	s_add_i32 m0, s55, 0x2000
	s_add_u32 s34, s34, 0xc000
	v_lshl_add_u64 v[248:249], s[36:37], 0, v[136:137]
	s_addc_u32 s35, s35, 0
	s_add_i32 s36, s61, s41
	global_load_lds_dwordx4 v[248:249], off
	s_mov_b32 m0, s36
	s_nop 0
	global_load_lds_dwordx4 v132, s[34:35]
	s_add_i32 m0, s36, 0x2000
	s_nop 0
	global_load_lds_dwordx4 v136, s[34:35]
	s_mov_b32 m0, s47
	s_nop 0
	global_load_lds_dwordx4 v130, s[30:31]
	s_mov_b32 m0, s48
	s_nop 0
	global_load_lds_dwordx4 v134, s[30:31]
	s_waitcnt vmcnt(8)
	s_barrier
	s_waitcnt lgkmcnt(0)
	v_mfma_f32_16x16x32_bf16 v[62:65], v[184:187], v[216:219], v[62:65]
	v_mfma_f32_16x16x32_bf16 v[58:61], v[192:195], v[216:219], v[58:61]
	v_mfma_f32_16x16x32_bf16 v[46:49], v[184:187], v[224:227], v[46:49]
	v_mfma_f32_16x16x32_bf16 v[42:45], v[192:195], v[224:227], v[42:45]
	v_mfma_f32_16x16x32_bf16 v[30:33], v[184:187], v[232:235], v[30:33]
	v_mfma_f32_16x16x32_bf16 v[26:29], v[192:195], v[232:235], v[26:29]
	v_mfma_f32_16x16x32_bf16 v[14:17], v[184:187], v[240:243], v[14:17]
	v_mfma_f32_16x16x32_bf16 v[10:13], v[192:195], v[240:243], v[10:13]
	v_mfma_f32_16x16x32_bf16 v[62:65], v[188:191], v[220:223], v[62:65]
	v_mfma_f32_16x16x32_bf16 v[58:61], v[196:199], v[220:223], v[58:61]
	v_mfma_f32_16x16x32_bf16 v[46:49], v[188:191], v[228:231], v[46:49]
	v_mfma_f32_16x16x32_bf16 v[42:45], v[196:199], v[228:231], v[42:45]
	v_mfma_f32_16x16x32_bf16 v[30:33], v[188:191], v[236:239], v[30:33]
	v_mfma_f32_16x16x32_bf16 v[26:29], v[196:199], v[236:239], v[26:29]
	v_mfma_f32_16x16x32_bf16 v[14:17], v[188:191], v[244:247], v[14:17]
	v_mfma_f32_16x16x32_bf16 v[10:13], v[196:199], v[244:247], v[10:13]
	v_mfma_f32_16x16x32_bf16 v[54:57], v[200:203], v[216:219], v[54:57]
	v_mfma_f32_16x16x32_bf16 v[50:53], v[208:211], v[216:219], v[50:53]
	v_mfma_f32_16x16x32_bf16 v[38:41], v[200:203], v[224:227], v[38:41]
	v_mfma_f32_16x16x32_bf16 v[34:37], v[208:211], v[224:227], v[34:37]
	v_mfma_f32_16x16x32_bf16 v[22:25], v[200:203], v[232:235], v[22:25]
	v_mfma_f32_16x16x32_bf16 v[18:21], v[208:211], v[232:235], v[18:21]
	v_mfma_f32_16x16x32_bf16 v[6:9], v[200:203], v[240:243], v[6:9]
	v_mfma_f32_16x16x32_bf16 v[2:5], v[208:211], v[240:243], v[2:5]
	v_mfma_f32_16x16x32_bf16 v[54:57], v[204:207], v[220:223], v[54:57]
	v_mfma_f32_16x16x32_bf16 v[50:53], v[212:215], v[220:223], v[50:53]
	v_mfma_f32_16x16x32_bf16 v[38:41], v[204:207], v[228:231], v[38:41]
	v_mfma_f32_16x16x32_bf16 v[34:37], v[212:215], v[228:231], v[34:37]
	v_mfma_f32_16x16x32_bf16 v[22:25], v[204:207], v[236:239], v[22:25]
	v_mfma_f32_16x16x32_bf16 v[18:21], v[212:215], v[236:239], v[18:21]
	v_mfma_f32_16x16x32_bf16 v[6:9], v[204:207], v[244:247], v[6:9]
	v_mfma_f32_16x16x32_bf16 v[2:5], v[212:215], v[244:247], v[2:5]
	s_barrier
	s_add_i32 s54, s54, 2
	s_add_u32 s28, s28, 0x100
	s_addc_u32 s29, s29, 0
	s_add_u32 s52, s52, 0x10000
	s_addc_u32 s53, s53, 0
	s_cmp_gt_u32 s54, 29
	s_cbranch_scc0 .LBB0_668
	s_and_b64 vcc, exec, s[12:13]
	s_cbranch_vccz .LBB0_671
	s_barrier

; #define PG8_STAGE(bufoff, gbase, voff) do { _Pragma("unroll") for (int _i = 0; _i < 2; ++_i) \
;         __builtin_amdgcn_global_load_lds((const unsigned*)((const char*)(gbase) + (voff)[_i]), (LAS unsigned*)(lds + (bufoff) + ldsw + _i * 8192), 16, 0, 0); } while (0)
; #define PG8_LDA(dst, b, h) do { _Pragma("unroll") for (int m = 0; m < 4; ++m) _Pragma("unroll") for (int k = 0; k < 2; ++k) dst[m][k] = *(const LAS bf16x8*)(lds + PG8_SA(b, h) + aoff + m * 2048 + k * 1024); } while (0)
; #define PG8_LDB(dst, b, h) do { _Pragma("unroll") for (int n = 0; n < 2; ++n) _Pragma("unroll") for (int k = 0; k < 2; ++k) dst[n][k] = *(const LAS bf16x8*)(lds + PG8_SB(b, h) + boff + n * 2048 + k * 1024); } while (0)
; #define PG8_WAIT_V(n) asm volatile("s_waitcnt vmcnt(" #n ")" ::: "memory")
; #define PG8_WAIT_L(n) asm volatile("s_waitcnt lgkmcnt(" #n ")" ::: "memory")
; template <class Epi, class Sched, bool ABLK = false, bool ALIGN_EPI = true, bool SP2 = true, bool BBLK = true>
; __device__ __forceinline__ void gemm_phase(LAS unsigned char* lds, const Gemm g, const Sched& S, const Epi& E) {
;     ...
;         const bool has_next = S.next(ui + 1, nxt);
;         const int nt = cur.nt;
;         const char* nuA = has_next ? a_unit(nxt) : uA; const int ntbA = has_next ? nxt.k0 / BK : tbA; const char* nB = has_next ? (const char*)g.Bt + (size_t)nxt.pn * tstepB + b_k0(nxt.k0) : cB;
;         for (int t = 0; t < nt; t += 2) {
;             const bool last = (t == nt - 2);
;             const char* a1 = a_tile(uA, tbA + t + 1);
;             const char* a2 = last ? a_tile(nuA, ntbA) : a_tile(uA, tbA + t + 2); const char* b2 = last ? nB : cB + (size_t)(t + 2) * kstepB;
;             const char* a3 = last ? a_tile(nuA, ntbA + 1) : a_tile(uA, tbA + t + 3); const char* b3 = b2 + kstepB;
;             if (last && has_next) S.a_ready(nxt);
;             if constexpr (SP2) {
;             PG8_LDB(B0, 0, 0); PG8_LDB(B1, 0, 1); PG8_SCHED; PG8_LDA(At, 0, 0); PG8_STAGE(PG8_SA(1, 1), a1 + hstepA, voffA);
;             PG8_WAIT_V(8); PG8_WAIT_L(0); PG8_BAR; PG8_MMA(0, 0, At, B0); PG8_MMA(0, 1, At, B1); PG8_BAR; PG8_SCHED;
;             PG8_LDA(At, 0, 1); PG8_STAGE(PG8_SB(0, 0), b2, voffB); PG8_STAGE(PG8_SB(0, 1), b2 + hstepB, voffB); PG8_STAGE(PG8_SA(0, 0), a2, voffA);
;             PG8_WAIT_V(8); PG8_WAIT_L(0); PG8_BAR; PG8_MMA(1, 0, At, B0); PG8_MMA(1, 1, At, B1); PG8_BAR; PG8_SCHED;
.LBB0_1037:
	s_ashr_i32 s81, s80, 31
	s_andn2_b64 vcc, exec, s[4:5]
	s_lshl_b64 s[14:15], s[80:81], 20
	s_add_u32 s14, s28, s14
	s_addc_u32 s15, s29, s15
	s_and_b64 s[16:17], s[4:5], exec
	s_cselect_b32 s25, s15, s23
	s_cselect_b32 s48, s14, s22
	s_ashr_i32 s16, s63, 31
	s_lshr_b32 s16, s16, 26
	s_add_i32 s16, s63, s16
	s_ashr_i32 s16, s16, 6
	s_and_b64 s[18:19], s[4:5], exec
	s_cselect_b32 s26, s16, s24
	s_ashr_i32 s79, s78, 31
	s_lshl_b64 s[18:19], s[78:79], 20
	s_add_u32 s27, s30, s18
	s_addc_u32 s49, s31, s19
	s_ashr_i32 s17, s16, 31
	s_lshl_b64 s[18:19], s[16:17], 15
	s_add_u32 s18, s27, s18
	s_addc_u32 s19, s49, s19
	v_cndmask_b32_e64 v2, 0, 1, s[4:5]
	s_and_b64 s[4:5], s[4:5], exec
	s_cselect_b32 s4, s19, s21
	s_cselect_b32 s5, s18, s20
	s_ashr_i32 s27, s26, 31
	s_lshl_b64 s[26:27], s[26:27], 7
	s_add_u32 s17, s48, s26
	s_addc_u32 s48, s25, s27
	s_add_u32 s49, s17, 0x80
	s_addc_u32 s50, s48, 0
	s_add_u32 s51, s20, 0x10000
	s_addc_u32 s55, s21, 0
	s_ashr_i32 s25, s24, 31
	v_cmp_ne_u32_e64 s[8:9], 1, v2
	s_lshl_b64 s[20:21], s[24:25], 7
	v_lshl_add_u64 v[2:3], s[22:23], 0, v[142:143]
	s_add_u32 s56, s22, s20
	v_lshl_add_u64 v[146:147], v[2:3], 0, s[20:21]
	v_lshl_add_u64 v[2:3], s[22:23], 0, v[144:145]
	s_addc_u32 s57, s23, s21
	v_lshl_add_u64 v[148:149], v[2:3], 0, s[20:21]
	s_lshl_b32 s20, s46, 7
	s_addk_i32 s20, 0xfc00
	v_mov_b32_e32 v2, 0
	s_add_u32 s64, s20, 0x300
	s_mov_b32 s65, 0
	s_mov_b64 s[20:21], 0
	ds_read_b128 v[156:159], v153
	ds_read_b128 v[160:163], v153 offset:1024
	ds_read_b128 v[164:167], v153 offset:2048
	ds_read_b128 v[168:171], v153 offset:3072
	ds_read_b128 v[172:175], v154
	ds_read_b128 v[176:179], v154 offset:1024
	ds_read_b128 v[180:183], v154 offset:2048
	ds_read_b128 v[184:187], v154 offset:3072
	s_add_u32 s22, s56, s20
	s_addc_u32 s23, s57, s21
	s_add_u32 s26, s22, 0x100
	s_addc_u32 s27, s23, 0
	s_add_i32 s65, s65, 2
	s_add_u32 s22, s22, 0x180
	s_addc_u32 s23, s23, 0
	s_cmp_eq_u32 s64, s20
	s_cselect_b32 s23, s50, s23
	s_cselect_b32 s22, s49, s22
	s_cselect_b32 s25, s4, s55
	s_cselect_b32 s24, s5, s51
	s_cselect_b32 s27, s48, s27
	s_cselect_b32 s26, s17, s26
	v_lshl_add_u64 v[220:221], v[146:147], 0, s[20:21]
	s_add_i32 m0, s35, 0xc000
	ds_read_b128 v[188:191], v155
	ds_read_b128 v[192:195], v155 offset:1024
	ds_read_b128 v[196:199], v155 offset:2048
	ds_read_b128 v[200:203], v155 offset:3072
	ds_read_b128 v[204:207], v155 offset:4096
	ds_read_b128 v[208:211], v155 offset:5120
	ds_read_b128 v[212:215], v155 offset:6144
	ds_read_b128 v[216:219], v155 offset:7168
	global_load_lds_dwordx4 v[220:221], off
	v_lshl_add_u64 v[220:221], v[148:149], 0, s[20:21]
	s_add_i32 m0, s35, 0xe000
	s_nop 0
	global_load_lds_dwordx4 v[220:221], off
	s_waitcnt vmcnt(8)
	s_barrier
	s_waitcnt lgkmcnt(0)
	v_mfma_f32_16x16x32_bf16 v[126:129], v[156:159], v[188:191], 0
	v_mfma_f32_16x16x32_bf16 v[122:125], v[164:167], v[188:191], 0
	v_mfma_f32_16x16x32_bf16 v[110:113], v[156:159], v[196:199], 0
	v_mfma_f32_16x16x32_bf16 v[106:109], v[164:167], v[196:199], 0
	v_mfma_f32_16x16x32_bf16 v[94:97], v[156:159], v[204:207], 0
	v_mfma_f32_16x16x32_bf16 v[90:93], v[164:167], v[204:207], 0
	v_mfma_f32_16x16x32_bf16 v[78:81], v[156:159], v[212:215], 0
	v_mfma_f32_16x16x32_bf16 v[74:77], v[164:167], v[212:215], 0
	v_mfma_f32_16x16x32_bf16 v[126:129], v[160:163], v[192:195], v[126:129]
	v_mfma_f32_16x16x32_bf16 v[122:125], v[168:171], v[192:195], v[122:125]
	v_mfma_f32_16x16x32_bf16 v[110:113], v[160:163], v[200:203], v[110:113]
	v_mfma_f32_16x16x32_bf16 v[106:109], v[168:171], v[200:203], v[106:109]
	v_mfma_f32_16x16x32_bf16 v[94:97], v[160:163], v[208:211], v[94:97]
	v_mfma_f32_16x16x32_bf16 v[90:93], v[168:171], v[208:211], v[90:93]
	v_mfma_f32_16x16x32_bf16 v[78:81], v[160:163], v[216:219], v[78:81]
	v_mfma_f32_16x16x32_bf16 v[74:77], v[168:171], v[216:219], v[74:77]
	v_mfma_f32_16x16x32_bf16 v[118:121], v[172:175], v[188:191], 0
	v_mfma_f32_16x16x32_bf16 v[114:117], v[180:183], v[188:191], 0
	v_mfma_f32_16x16x32_bf16 v[102:105], v[172:175], v[196:199], 0
	v_mfma_f32_16x16x32_bf16 v[98:101], v[180:183], v[196:199], 0
	v_mfma_f32_16x16x32_bf16 v[86:89], v[172:175], v[204:207], 0
	v_mfma_f32_16x16x32_bf16 v[82:85], v[180:183], v[204:207], 0
	v_mfma_f32_16x16x32_bf16 v[70:73], v[172:175], v[212:215], 0
	v_mfma_f32_16x16x32_bf16 v[66:69], v[180:183], v[212:215], 0
	v_mfma_f32_16x16x32_bf16 v[118:121], v[176:179], v[192:195], v[118:121]
	v_mfma_f32_16x16x32_bf16 v[114:117], v[184:187], v[192:195], v[114:117]
	v_mfma_f32_16x16x32_bf16 v[102:105], v[176:179], v[200:203], v[102:105]
	v_mfma_f32_16x16x32_bf16 v[98:101], v[184:187], v[200:203], v[98:101]
	v_mfma_f32_16x16x32_bf16 v[86:89], v[176:179], v[208:211], v[86:89]
	v_mfma_f32_16x16x32_bf16 v[82:85], v[184:187], v[208:211], v[82:85]
	v_mfma_f32_16x16x32_bf16 v[70:73], v[176:179], v[216:219], v[70:73]
	v_mfma_f32_16x16x32_bf16 v[66:69], v[184:187], v[216:219], v[66:69]
	s_barrier
	s_add_i32 s66, s72, s34
	s_mov_b32 m0, s66
	ds_read_b128 v[188:191], v155 offset:16384
	ds_read_b128 v[192:195], v155 offset:17408
	ds_read_b128 v[196:199], v155 offset:18432
	ds_read_b128 v[200:203], v155 offset:19456
	ds_read_b128 v[204:207], v155 offset:20480
	ds_read_b128 v[208:211], v155 offset:21504
	ds_read_b128 v[212:215], v155 offset:22528
	ds_read_b128 v[216:219], v155 offset:23552
	global_load_lds_dwordx4 v132, s[24:25]
	s_add_i32 m0, s66, 0x2000
	s_add_u32 s66, s24, 0x4000
	s_addc_u32 s67, s25, 0
	s_add_i32 s75, s73, s34
	global_load_lds_dwordx4 v136, s[24:25]
	s_mov_b32 m0, s75
	s_nop 0
	global_load_lds_dwordx4 v132, s[66:67]
	s_add_i32 m0, s75, 0x2000
	s_nop 0
	global_load_lds_dwordx4 v136, s[66:67]
	s_mov_b32 m0, s35
	s_nop 0
	global_load_lds_dwordx4 v130, s[26:27]
	s_mov_b32 m0, s36
	s_nop 0
	global_load_lds_dwordx4 v134, s[26:27]
	s_waitcnt vmcnt(8)
	s_barrier
; #define PG8_STAGE(bufoff, gbase, voff) do { _Pragma("unroll") for (int _i = 0; _i < 2; ++_i) \
;         __builtin_amdgcn_global_load_lds((const unsigned*)((const char*)(gbase) + (voff)[_i]), (LAS unsigned*)(lds + (bufoff) + ldsw + _i * 8192), 16, 0, 0); } while (0)
; #define PG8_LDA(dst, b, h) do { _Pragma("unroll") for (int m = 0; m < 4; ++m) _Pragma("unroll") for (int k = 0; k < 2; ++k) dst[m][k] = *(const LAS bf16x8*)(lds + PG8_SA(b, h) + aoff + m * 2048 + k * 1024); } while (0)
; #define PG8_LDB(dst, b, h) do { _Pragma("unroll") for (int n = 0; n < 2; ++n) _Pragma("unroll") for (int k = 0; k < 2; ++k) dst[n][k] = *(const LAS bf16x8*)(lds + PG8_SB(b, h) + boff + n * 2048 + k * 1024); } while (0)
; #define PG8_MMA(ai, bj, At, Bt) do { __builtin_amdgcn_s_setprio(1); _Pragma("unroll") for (int m = 0; m < 4; ++m) _Pragma("unroll") for (int n = 0; n < 2; ++n) _Pragma("unroll") for (int k = 0; k < 2; ++k) \
;         acc[ai][bj][m][n] = __builtin_amdgcn_mfma_f32_16x16x32_bf16(Bt[n][k], At[m][k], acc[ai][bj][m][n], 0, 0, 0); __builtin_amdgcn_s_setprio(0); } while (0)
; #define PG8_WAIT_V(n) asm volatile("s_waitcnt vmcnt(" #n ")" ::: "memory")
; #define PG8_WAIT_L(n) asm volatile("s_waitcnt lgkmcnt(" #n ")" ::: "memory")
; #define PG8_BAR __builtin_amdgcn_s_barrier()
; #define PG8_SCHED __builtin_amdgcn_sched_barrier(0)
; template <class Epi, class Sched, bool ABLK = false, bool ALIGN_EPI = true, bool SP2 = true, bool BBLK = true>
; __device__ __forceinline__ void gemm_phase(LAS unsigned char* lds, const Gemm g, const Sched& S, const Epi& E) {
;     ...
;             PG8_WAIT_V(8); PG8_WAIT_L(0); PG8_BAR; PG8_MMA(1, 0, At, B0); PG8_MMA(1, 1, At, B1); PG8_BAR; PG8_SCHED;
;             PG8_LDB(B0, 1, 0); PG8_LDB(B1, 1, 1); PG8_SCHED; PG8_LDA(At, 1, 0); PG8_STAGE(PG8_SA(0, 1), a2 + hstepA, voffA);
;             PG8_WAIT_V(8); PG8_WAIT_L(0); PG8_BAR; PG8_MMA(0, 0, At, B0); PG8_MMA(0, 1, At, B1); PG8_BAR; PG8_SCHED;
	s_waitcnt lgkmcnt(0)
	v_mfma_f32_16x16x32_bf16 v[62:65], v[156:159], v[188:191], 0
	v_mfma_f32_16x16x32_bf16 v[58:61], v[164:167], v[188:191], 0
	v_mfma_f32_16x16x32_bf16 v[46:49], v[156:159], v[196:199], 0
	v_mfma_f32_16x16x32_bf16 v[42:45], v[164:167], v[196:199], 0
	v_mfma_f32_16x16x32_bf16 v[30:33], v[156:159], v[204:207], 0
	v_mfma_f32_16x16x32_bf16 v[26:29], v[164:167], v[204:207], 0
	v_mfma_f32_16x16x32_bf16 v[14:17], v[156:159], v[212:215], 0
	v_mfma_f32_16x16x32_bf16 v[10:13], v[164:167], v[212:215], 0
	v_mfma_f32_16x16x32_bf16 v[62:65], v[160:163], v[192:195], v[62:65]
	v_mfma_f32_16x16x32_bf16 v[58:61], v[168:171], v[192:195], v[58:61]
	v_mfma_f32_16x16x32_bf16 v[46:49], v[160:163], v[200:203], v[46:49]
	v_mfma_f32_16x16x32_bf16 v[42:45], v[168:171], v[200:203], v[42:45]
	v_mfma_f32_16x16x32_bf16 v[30:33], v[160:163], v[208:211], v[30:33]
	v_mfma_f32_16x16x32_bf16 v[26:29], v[168:171], v[208:211], v[26:29]
	v_mfma_f32_16x16x32_bf16 v[14:17], v[160:163], v[216:219], v[14:17]
	v_mfma_f32_16x16x32_bf16 v[10:13], v[168:171], v[216:219], v[10:13]
	v_mfma_f32_16x16x32_bf16 v[54:57], v[172:175], v[188:191], 0
	v_mfma_f32_16x16x32_bf16 v[50:53], v[180:183], v[188:191], 0
	v_mfma_f32_16x16x32_bf16 v[38:41], v[172:175], v[196:199], 0
	v_mfma_f32_16x16x32_bf16 v[34:37], v[180:183], v[196:199], 0
	v_mfma_f32_16x16x32_bf16 v[22:25], v[172:175], v[204:207], 0
	v_mfma_f32_16x16x32_bf16 v[18:21], v[180:183], v[204:207], 0
	v_mfma_f32_16x16x32_bf16 v[6:9], v[172:175], v[212:215], 0
	v_mfma_f32_16x16x32_bf16 v[2:5], v[180:183], v[212:215], 0
	v_mfma_f32_16x16x32_bf16 v[54:57], v[176:179], v[192:195], v[54:57]
	v_mfma_f32_16x16x32_bf16 v[50:53], v[184:187], v[192:195], v[50:53]
	v_mfma_f32_16x16x32_bf16 v[38:41], v[176:179], v[200:203], v[38:41]
	v_mfma_f32_16x16x32_bf16 v[34:37], v[184:187], v[200:203], v[34:37]
	v_mfma_f32_16x16x32_bf16 v[22:25], v[176:179], v[208:211], v[22:25]
	v_mfma_f32_16x16x32_bf16 v[18:21], v[184:187], v[208:211], v[18:21]
	v_mfma_f32_16x16x32_bf16 v[6:9], v[176:179], v[216:219], v[6:9]
	v_mfma_f32_16x16x32_bf16 v[2:5], v[184:187], v[216:219], v[2:5]
	s_barrier
	v_add_u32_e32 v168, s60, v151
	v_add_u32_e32 v184, s61, v151
	ds_read_b128 v[156:159], v168
	ds_read_b128 v[160:163], v168 offset:1024
	ds_read_b128 v[164:167], v168 offset:2048
	ds_read_b128 v[168:171], v168 offset:3072
	ds_read_b128 v[172:175], v184
	ds_read_b128 v[176:179], v184 offset:1024
	ds_read_b128 v[180:183], v184 offset:2048
	ds_read_b128 v[184:187], v184 offset:3072
	s_add_u32 s26, s26, 0x80000
	s_addc_u32 s27, s27, 0
	s_mov_b32 m0, s37
	ds_read_b128 v[188:191], v155 offset:32768
	ds_read_b128 v[192:195], v155 offset:33792
	ds_read_b128 v[196:199], v155 offset:34816
	ds_read_b128 v[200:203], v155 offset:35840
	ds_read_b128 v[204:207], v155 offset:36864
	ds_read_b128 v[208:211], v155 offset:37888
	ds_read_b128 v[212:215], v155 offset:38912
	ds_read_b128 v[216:219], v155 offset:39936
	global_load_lds_dwordx4 v130, s[26:27]
	s_mov_b32 m0, s40
	s_nop 0
	global_load_lds_dwordx4 v134, s[26:27]
	s_waitcnt vmcnt(8)
	s_barrier
	s_waitcnt lgkmcnt(0)
	v_mfma_f32_16x16x32_bf16 v[126:129], v[156:159], v[188:191], v[126:129]
	v_mfma_f32_16x16x32_bf16 v[122:125], v[164:167], v[188:191], v[122:125]
	v_mfma_f32_16x16x32_bf16 v[110:113], v[156:159], v[196:199], v[110:113]
	v_mfma_f32_16x16x32_bf16 v[106:109], v[164:167], v[196:199], v[106:109]
	v_mfma_f32_16x16x32_bf16 v[94:97], v[156:159], v[204:207], v[94:97]
	v_mfma_f32_16x16x32_bf16 v[90:93], v[164:167], v[204:207], v[90:93]
	v_mfma_f32_16x16x32_bf16 v[78:81], v[156:159], v[212:215], v[78:81]
	v_mfma_f32_16x16x32_bf16 v[74:77], v[164:167], v[212:215], v[74:77]
	v_mfma_f32_16x16x32_bf16 v[126:129], v[160:163], v[192:195], v[126:129]
	v_mfma_f32_16x16x32_bf16 v[122:125], v[168:171], v[192:195], v[122:125]
	v_mfma_f32_16x16x32_bf16 v[110:113], v[160:163], v[200:203], v[110:113]
	v_mfma_f32_16x16x32_bf16 v[106:109], v[168:171], v[200:203], v[106:109]
	v_mfma_f32_16x16x32_bf16 v[94:97], v[160:163], v[208:211], v[94:97]
	v_mfma_f32_16x16x32_bf16 v[90:93], v[168:171], v[208:211], v[90:93]
	v_mfma_f32_16x16x32_bf16 v[78:81], v[160:163], v[216:219], v[78:81]
	v_mfma_f32_16x16x32_bf16 v[74:77], v[168:171], v[216:219], v[74:77]
	v_mfma_f32_16x16x32_bf16 v[118:121], v[172:175], v[188:191], v[118:121]
	v_mfma_f32_16x16x32_bf16 v[114:117], v[180:183], v[188:191], v[114:117]
	v_mfma_f32_16x16x32_bf16 v[102:105], v[172:175], v[196:199], v[102:105]
	v_mfma_f32_16x16x32_bf16 v[98:101], v[180:183], v[196:199], v[98:101]
	v_mfma_f32_16x16x32_bf16 v[86:89], v[172:175], v[204:207], v[86:89]
	v_mfma_f32_16x16x32_bf16 v[82:85], v[180:183], v[204:207], v[82:85]
	v_mfma_f32_16x16x32_bf16 v[70:73], v[172:175], v[212:215], v[70:73]
	v_mfma_f32_16x16x32_bf16 v[66:69], v[180:183], v[212:215], v[66:69]
	v_mfma_f32_16x16x32_bf16 v[118:121], v[176:179], v[192:195], v[118:121]
	v_mfma_f32_16x16x32_bf16 v[114:117], v[184:187], v[192:195], v[114:117]
	v_mfma_f32_16x16x32_bf16 v[102:105], v[176:179], v[200:203], v[102:105]
	v_mfma_f32_16x16x32_bf16 v[98:101], v[184:187], v[200:203], v[98:101]
	v_mfma_f32_16x16x32_bf16 v[86:89], v[176:179], v[208:211], v[86:89]
	v_mfma_f32_16x16x32_bf16 v[82:85], v[184:187], v[208:211], v[82:85]
	v_mfma_f32_16x16x32_bf16 v[70:73], v[176:179], v[216:219], v[70:73]
	v_mfma_f32_16x16x32_bf16 v[66:69], v[184:187], v[216:219], v[66:69]
	s_barrier
; #define PG8_STAGE(bufoff, gbase, voff) do { _Pragma("unroll") for (int _i = 0; _i < 2; ++_i) \
;         __builtin_amdgcn_global_load_lds((const unsigned*)((const char*)(gbase) + (voff)[_i]), (LAS unsigned*)(lds + (bufoff) + ldsw + _i * 8192), 16, 0, 0); } while (0)
; #define PG8_LDA(dst, b, h) do { _Pragma("unroll") for (int m = 0; m < 4; ++m) _Pragma("unroll") for (int k = 0; k < 2; ++k) dst[m][k] = *(const LAS bf16x8*)(lds + PG8_SA(b, h) + aoff + m * 2048 + k * 1024); } while (0)
; #define PG8_WAIT_V(n) asm volatile("s_waitcnt vmcnt(" #n ")" ::: "memory")
; #define PG8_WAIT_L(n) asm volatile("s_waitcnt lgkmcnt(" #n ")" ::: "memory")
; template <class Epi, class Sched, bool ABLK = false, bool ALIGN_EPI = true, bool SP2 = true, bool BBLK = true>
; __device__ __forceinline__ void gemm_phase(LAS unsigned char* lds, const Gemm g, const Sched& S, const Epi& E) {
;     ...
;         for (int t = 0; t < nt; t += 2) {
;             const bool last = (t == nt - 2);
;             const char* a1 = a_tile(uA, tbA + t + 1);
;             const char* a2 = last ? a_tile(nuA, ntbA) : a_tile(uA, tbA + t + 2); const char* b2 = last ? nB : cB + (size_t)(t + 2) * kstepB;
;             const char* a3 = last ? a_tile(nuA, ntbA + 1) : a_tile(uA, tbA + t + 3); const char* b3 = b2 + kstepB;
;             if (last && has_next) S.a_ready(nxt);
;             if constexpr (SP2) {
;             PG8_LDB(B0, 0, 0); PG8_LDB(B1, 0, 1); PG8_SCHED; PG8_LDA(At, 0, 0); PG8_STAGE(PG8_SA(1, 1), a1 + hstepA, voffA);
;             PG8_WAIT_V(8); PG8_WAIT_L(0); PG8_BAR; PG8_MMA(0, 0, At, B0); PG8_MMA(0, 1, At, B1); PG8_BAR; PG8_SCHED;
;             PG8_LDA(At, 0, 1); PG8_STAGE(PG8_SB(0, 0), b2, voffB); PG8_STAGE(PG8_SB(0, 1), b2 + hstepB, voffB); PG8_STAGE(PG8_SA(0, 0), a2, voffA);
;             PG8_WAIT_V(8); PG8_WAIT_L(0); PG8_BAR; PG8_MMA(1, 0, At, B0); PG8_MMA(1, 1, At, B1); PG8_BAR; PG8_SCHED;
;             PG8_LDB(B0, 1, 0); PG8_LDB(B1, 1, 1); PG8_SCHED; PG8_LDA(At, 1, 0); PG8_STAGE(PG8_SA(0, 1), a2 + hstepA, voffA);
;             PG8_WAIT_V(8); PG8_WAIT_L(0); PG8_BAR; PG8_MMA(0, 0, At, B0); PG8_MMA(0, 1, At, B1); PG8_BAR; PG8_SCHED;
;             PG8_LDA(At, 1, 1); PG8_STAGE(PG8_SB(1, 0), b3, voffB); PG8_STAGE(PG8_SB(1, 1), b3 + hstepB, voffB); PG8_STAGE(PG8_SA(1, 0), a3, voffA);
;             PG8_WAIT_V(8); PG8_WAIT_L(0); PG8_BAR; PG8_MMA(1, 0, At, B0); PG8_MMA(1, 1, At, B1); PG8_BAR; PG8_SCHED;
	s_add_u32 s26, s24, 0x8000
	s_addc_u32 s27, s25, 0
	s_add_i32 s66, s60, s34
	s_mov_b32 m0, s66
	ds_read_b128 v[188:191], v155 offset:49152
	ds_read_b128 v[192:195], v155 offset:50176
	ds_read_b128 v[196:199], v155 offset:51200
	ds_read_b128 v[200:203], v155 offset:52224
	ds_read_b128 v[204:207], v155 offset:53248
	ds_read_b128 v[208:211], v155 offset:54272
	ds_read_b128 v[212:215], v155 offset:55296
	ds_read_b128 v[216:219], v155 offset:56320
	global_load_lds_dwordx4 v132, s[26:27]
	s_add_i32 m0, s66, 0x2000
	s_add_u32 s24, s24, 0xc000
	v_lshl_add_u64 v[220:221], s[26:27], 0, v[136:137]
	s_addc_u32 s25, s25, 0
	s_add_i32 s26, s61, s34
	global_load_lds_dwordx4 v[220:221], off
	s_mov_b32 m0, s26
	s_nop 0
	global_load_lds_dwordx4 v132, s[24:25]
	s_add_i32 m0, s26, 0x2000
	s_nop 0
	global_load_lds_dwordx4 v136, s[24:25]
	s_mov_b32 m0, s41
	s_nop 0
	global_load_lds_dwordx4 v130, s[22:23]
	s_mov_b32 m0, s42
	s_nop 0
	global_load_lds_dwordx4 v134, s[22:23]
	s_waitcnt vmcnt(8)
	s_barrier
	s_waitcnt lgkmcnt(0)
	v_mfma_f32_16x16x32_bf16 v[62:65], v[156:159], v[188:191], v[62:65]
	v_mfma_f32_16x16x32_bf16 v[58:61], v[164:167], v[188:191], v[58:61]
	v_mfma_f32_16x16x32_bf16 v[46:49], v[156:159], v[196:199], v[46:49]
	v_mfma_f32_16x16x32_bf16 v[42:45], v[164:167], v[196:199], v[42:45]
	v_mfma_f32_16x16x32_bf16 v[30:33], v[156:159], v[204:207], v[30:33]
	v_mfma_f32_16x16x32_bf16 v[26:29], v[164:167], v[204:207], v[26:29]
	v_mfma_f32_16x16x32_bf16 v[14:17], v[156:159], v[212:215], v[14:17]
	v_mfma_f32_16x16x32_bf16 v[10:13], v[164:167], v[212:215], v[10:13]
	v_mfma_f32_16x16x32_bf16 v[62:65], v[160:163], v[192:195], v[62:65]
	v_mfma_f32_16x16x32_bf16 v[58:61], v[168:171], v[192:195], v[58:61]
	v_mfma_f32_16x16x32_bf16 v[46:49], v[160:163], v[200:203], v[46:49]
	v_mfma_f32_16x16x32_bf16 v[42:45], v[168:171], v[200:203], v[42:45]
	v_mfma_f32_16x16x32_bf16 v[30:33], v[160:163], v[208:211], v[30:33]
	v_mfma_f32_16x16x32_bf16 v[26:29], v[168:171], v[208:211], v[26:29]
	v_mfma_f32_16x16x32_bf16 v[14:17], v[160:163], v[216:219], v[14:17]
	v_mfma_f32_16x16x32_bf16 v[10:13], v[168:171], v[216:219], v[10:13]
	v_mfma_f32_16x16x32_bf16 v[54:57], v[172:175], v[188:191], v[54:57]
	v_mfma_f32_16x16x32_bf16 v[50:53], v[180:183], v[188:191], v[50:53]
	v_mfma_f32_16x16x32_bf16 v[38:41], v[172:175], v[196:199], v[38:41]
	v_mfma_f32_16x16x32_bf16 v[34:37], v[180:183], v[196:199], v[34:37]
	v_mfma_f32_16x16x32_bf16 v[22:25], v[172:175], v[204:207], v[22:25]
	v_mfma_f32_16x16x32_bf16 v[18:21], v[180:183], v[204:207], v[18:21]
	v_mfma_f32_16x16x32_bf16 v[6:9], v[172:175], v[212:215], v[6:9]
	v_mfma_f32_16x16x32_bf16 v[2:5], v[180:183], v[212:215], v[2:5]
	v_mfma_f32_16x16x32_bf16 v[54:57], v[176:179], v[192:195], v[54:57]
	v_mfma_f32_16x16x32_bf16 v[50:53], v[184:187], v[192:195], v[50:53]
	v_mfma_f32_16x16x32_bf16 v[38:41], v[176:179], v[200:203], v[38:41]
	v_mfma_f32_16x16x32_bf16 v[34:37], v[184:187], v[200:203], v[34:37]
	v_mfma_f32_16x16x32_bf16 v[22:25], v[176:179], v[208:211], v[22:25]
	v_mfma_f32_16x16x32_bf16 v[18:21], v[184:187], v[208:211], v[18:21]
	v_mfma_f32_16x16x32_bf16 v[6:9], v[176:179], v[216:219], v[6:9]
	v_mfma_f32_16x16x32_bf16 v[2:5], v[184:187], v[216:219], v[2:5]
	s_barrier
	s_add_u32 s51, s51, 0x10000
	s_addc_u32 s55, s55, 0
	s_add_u32 s20, s20, 0x100
	s_addc_u32 s21, s21, 0
	s_cmp_ge_u32 s65, s46
.LBB0_1038:
	ds_read_b128 v[156:159], v153
	ds_read_b128 v[160:163], v153 offset:1024
	ds_read_b128 v[164:167], v153 offset:2048
	ds_read_b128 v[168:171], v153 offset:3072
	ds_read_b128 v[172:175], v154
	ds_read_b128 v[176:179], v154 offset:1024
	ds_read_b128 v[180:183], v154 offset:2048
	ds_read_b128 v[184:187], v154 offset:3072
	s_add_u32 s22, s56, s20
	s_addc_u32 s23, s57, s21
	s_add_u32 s26, s22, 0x100
	s_addc_u32 s27, s23, 0
	s_add_i32 s65, s65, 2
	s_add_u32 s22, s22, 0x180
	s_addc_u32 s23, s23, 0
	s_cmp_eq_u32 s64, s20
	s_cselect_b32 s23, s50, s23
	s_cselect_b32 s22, s49, s22
	s_cselect_b32 s25, s4, s55
	s_cselect_b32 s24, s5, s51
	s_cselect_b32 s27, s48, s27
	s_cselect_b32 s26, s17, s26
	v_lshl_add_u64 v[220:221], v[146:147], 0, s[20:21]
	s_add_i32 m0, s35, 0xc000
	ds_read_b128 v[188:191], v155
	ds_read_b128 v[192:195], v155 offset:1024
	ds_read_b128 v[196:199], v155 offset:2048
	ds_read_b128 v[200:203], v155 offset:3072
	ds_read_b128 v[204:207], v155 offset:4096
	ds_read_b128 v[208:211], v155 offset:5120
	ds_read_b128 v[212:215], v155 offset:6144
	ds_read_b128 v[216:219], v155 offset:7168
	global_load_lds_dwordx4 v[220:221], off
	v_lshl_add_u64 v[220:221], v[148:149], 0, s[20:21]
	s_add_i32 m0, s35, 0xe000
	s_nop 0
	global_load_lds_dwordx4 v[220:221], off
	s_waitcnt vmcnt(8)
	s_barrier
; #define PG8_STAGE(bufoff, gbase, voff) do { _Pragma("unroll") for (int _i = 0; _i < 2; ++_i) \
;         __builtin_amdgcn_global_load_lds((const unsigned*)((const char*)(gbase) + (voff)[_i]), (LAS unsigned*)(lds + (bufoff) + ldsw + _i * 8192), 16, 0, 0); } while (0)
; #define PG8_LDA(dst, b, h) do { _Pragma("unroll") for (int m = 0; m < 4; ++m) _Pragma("unroll") for (int k = 0; k < 2; ++k) dst[m][k] = *(const LAS bf16x8*)(lds + PG8_SA(b, h) + aoff + m * 2048 + k * 1024); } while (0)
; #define PG8_MMA(ai, bj, At, Bt) do { __builtin_amdgcn_s_setprio(1); _Pragma("unroll") for (int m = 0; m < 4; ++m) _Pragma("unroll") for (int n = 0; n < 2; ++n) _Pragma("unroll") for (int k = 0; k < 2; ++k) \
;         acc[ai][bj][m][n] = __builtin_amdgcn_mfma_f32_16x16x32_bf16(Bt[n][k], At[m][k], acc[ai][bj][m][n], 0, 0, 0); __builtin_amdgcn_s_setprio(0); } while (0)
; #define PG8_WAIT_V(n) asm volatile("s_waitcnt vmcnt(" #n ")" ::: "memory")
; #define PG8_WAIT_L(n) asm volatile("s_waitcnt lgkmcnt(" #n ")" ::: "memory")
; #define PG8_BAR __builtin_amdgcn_s_barrier()
; #define PG8_SCHED __builtin_amdgcn_sched_barrier(0)
; template <class Epi, class Sched, bool ABLK = false, bool ALIGN_EPI = true, bool SP2 = true, bool BBLK = true>
; __device__ __forceinline__ void gemm_phase(LAS unsigned char* lds, const Gemm g, const Sched& S, const Epi& E) {
;     ...
;             PG8_WAIT_V(8); PG8_WAIT_L(0); PG8_BAR; PG8_MMA(0, 0, At, B0); PG8_MMA(0, 1, At, B1); PG8_BAR; PG8_SCHED;
;             PG8_LDA(At, 0, 1); PG8_STAGE(PG8_SB(0, 0), b2, voffB); PG8_STAGE(PG8_SB(0, 1), b2 + hstepB, voffB); PG8_STAGE(PG8_SA(0, 0), a2, voffA);
;             PG8_WAIT_V(8); PG8_WAIT_L(0); PG8_BAR; PG8_MMA(1, 0, At, B0); PG8_MMA(1, 1, At, B1); PG8_BAR; PG8_SCHED;
	s_waitcnt lgkmcnt(0)
	v_mfma_f32_16x16x32_bf16 v[126:129], v[156:159], v[188:191], v[126:129]
	v_mfma_f32_16x16x32_bf16 v[122:125], v[164:167], v[188:191], v[122:125]
	v_mfma_f32_16x16x32_bf16 v[110:113], v[156:159], v[196:199], v[110:113]
	v_mfma_f32_16x16x32_bf16 v[106:109], v[164:167], v[196:199], v[106:109]
	v_mfma_f32_16x16x32_bf16 v[94:97], v[156:159], v[204:207], v[94:97]
	v_mfma_f32_16x16x32_bf16 v[90:93], v[164:167], v[204:207], v[90:93]
	v_mfma_f32_16x16x32_bf16 v[78:81], v[156:159], v[212:215], v[78:81]
	v_mfma_f32_16x16x32_bf16 v[74:77], v[164:167], v[212:215], v[74:77]
	v_mfma_f32_16x16x32_bf16 v[126:129], v[160:163], v[192:195], v[126:129]
	v_mfma_f32_16x16x32_bf16 v[122:125], v[168:171], v[192:195], v[122:125]
	v_mfma_f32_16x16x32_bf16 v[110:113], v[160:163], v[200:203], v[110:113]
	v_mfma_f32_16x16x32_bf16 v[106:109], v[168:171], v[200:203], v[106:109]
	v_mfma_f32_16x16x32_bf16 v[94:97], v[160:163], v[208:211], v[94:97]
	v_mfma_f32_16x16x32_bf16 v[90:93], v[168:171], v[208:211], v[90:93]
	v_mfma_f32_16x16x32_bf16 v[78:81], v[160:163], v[216:219], v[78:81]
	v_mfma_f32_16x16x32_bf16 v[74:77], v[168:171], v[216:219], v[74:77]
	v_mfma_f32_16x16x32_bf16 v[118:121], v[172:175], v[188:191], v[118:121]
	v_mfma_f32_16x16x32_bf16 v[114:117], v[180:183], v[188:191], v[114:117]
	v_mfma_f32_16x16x32_bf16 v[102:105], v[172:175], v[196:199], v[102:105]
	v_mfma_f32_16x16x32_bf16 v[98:101], v[180:183], v[196:199], v[98:101]
	v_mfma_f32_16x16x32_bf16 v[86:89], v[172:175], v[204:207], v[86:89]
	v_mfma_f32_16x16x32_bf16 v[82:85], v[180:183], v[204:207], v[82:85]
	v_mfma_f32_16x16x32_bf16 v[70:73], v[172:175], v[212:215], v[70:73]
	v_mfma_f32_16x16x32_bf16 v[66:69], v[180:183], v[212:215], v[66:69]
	v_mfma_f32_16x16x32_bf16 v[118:121], v[176:179], v[192:195], v[118:121]
	v_mfma_f32_16x16x32_bf16 v[114:117], v[184:187], v[192:195], v[114:117]
	v_mfma_f32_16x16x32_bf16 v[102:105], v[176:179], v[200:203], v[102:105]
	v_mfma_f32_16x16x32_bf16 v[98:101], v[184:187], v[200:203], v[98:101]
	v_mfma_f32_16x16x32_bf16 v[86:89], v[176:179], v[208:211], v[86:89]
	v_mfma_f32_16x16x32_bf16 v[82:85], v[184:187], v[208:211], v[82:85]
	v_mfma_f32_16x16x32_bf16 v[70:73], v[176:179], v[216:219], v[70:73]
	v_mfma_f32_16x16x32_bf16 v[66:69], v[184:187], v[216:219], v[66:69]
	s_barrier
	s_add_i32 s66, s72, s34
	s_mov_b32 m0, s66
	ds_read_b128 v[188:191], v155 offset:16384
	ds_read_b128 v[192:195], v155 offset:17408
	ds_read_b128 v[196:199], v155 offset:18432
	ds_read_b128 v[200:203], v155 offset:19456
	ds_read_b128 v[204:207], v155 offset:20480
	ds_read_b128 v[208:211], v155 offset:21504
	ds_read_b128 v[212:215], v155 offset:22528
	ds_read_b128 v[216:219], v155 offset:23552
	global_load_lds_dwordx4 v132, s[24:25]
	s_add_i32 m0, s66, 0x2000
	s_add_u32 s66, s24, 0x4000
	s_addc_u32 s67, s25, 0
	s_add_i32 s75, s73, s34
	global_load_lds_dwordx4 v136, s[24:25]
	s_mov_b32 m0, s75
	s_nop 0
	global_load_lds_dwordx4 v132, s[66:67]
	s_add_i32 m0, s75, 0x2000
	s_nop 0
	global_load_lds_dwordx4 v136, s[66:67]
	s_mov_b32 m0, s35
	s_nop 0
	global_load_lds_dwordx4 v130, s[26:27]
	s_mov_b32 m0, s36
	s_nop 0
	global_load_lds_dwordx4 v134, s[26:27]
	s_waitcnt vmcnt(8)
	s_barrier
	s_waitcnt lgkmcnt(0)
	v_mfma_f32_16x16x32_bf16 v[62:65], v[156:159], v[188:191], v[62:65]
	v_mfma_f32_16x16x32_bf16 v[58:61], v[164:167], v[188:191], v[58:61]
	v_mfma_f32_16x16x32_bf16 v[46:49], v[156:159], v[196:199], v[46:49]
	v_mfma_f32_16x16x32_bf16 v[42:45], v[164:167], v[196:199], v[42:45]
	v_mfma_f32_16x16x32_bf16 v[30:33], v[156:159], v[204:207], v[30:33]
	v_mfma_f32_16x16x32_bf16 v[26:29], v[164:167], v[204:207], v[26:29]
	v_mfma_f32_16x16x32_bf16 v[14:17], v[156:159], v[212:215], v[14:17]
	v_mfma_f32_16x16x32_bf16 v[10:13], v[164:167], v[212:215], v[10:13]
	v_mfma_f32_16x16x32_bf16 v[62:65], v[160:163], v[192:195], v[62:65]
	v_mfma_f32_16x16x32_bf16 v[58:61], v[168:171], v[192:195], v[58:61]
	v_mfma_f32_16x16x32_bf16 v[46:49], v[160:163], v[200:203], v[46:49]
	v_mfma_f32_16x16x32_bf16 v[42:45], v[168:171], v[200:203], v[42:45]
	v_mfma_f32_16x16x32_bf16 v[30:33], v[160:163], v[208:211], v[30:33]
	v_mfma_f32_16x16x32_bf16 v[26:29], v[168:171], v[208:211], v[26:29]
	v_mfma_f32_16x16x32_bf16 v[14:17], v[160:163], v[216:219], v[14:17]
	v_mfma_f32_16x16x32_bf16 v[10:13], v[168:171], v[216:219], v[10:13]
	v_mfma_f32_16x16x32_bf16 v[54:57], v[172:175], v[188:191], v[54:57]
	v_mfma_f32_16x16x32_bf16 v[50:53], v[180:183], v[188:191], v[50:53]
	v_mfma_f32_16x16x32_bf16 v[38:41], v[172:175], v[196:199], v[38:41]
	v_mfma_f32_16x16x32_bf16 v[34:37], v[180:183], v[196:199], v[34:37]
	v_mfma_f32_16x16x32_bf16 v[22:25], v[172:175], v[204:207], v[22:25]
	v_mfma_f32_16x16x32_bf16 v[18:21], v[180:183], v[204:207], v[18:21]
	v_mfma_f32_16x16x32_bf16 v[6:9], v[172:175], v[212:215], v[6:9]
	v_mfma_f32_16x16x32_bf16 v[2:5], v[180:183], v[212:215], v[2:5]
	v_mfma_f32_16x16x32_bf16 v[54:57], v[176:179], v[192:195], v[54:57]
	v_mfma_f32_16x16x32_bf16 v[50:53], v[184:187], v[192:195], v[50:53]
	v_mfma_f32_16x16x32_bf16 v[38:41], v[176:179], v[200:203], v[38:41]
	v_mfma_f32_16x16x32_bf16 v[34:37], v[184:187], v[200:203], v[34:37]
	v_mfma_f32_16x16x32_bf16 v[22:25], v[176:179], v[208:211], v[22:25]
	v_mfma_f32_16x16x32_bf16 v[18:21], v[184:187], v[208:211], v[18:21]
	v_mfma_f32_16x16x32_bf16 v[6:9], v[176:179], v[216:219], v[6:9]
	v_mfma_f32_16x16x32_bf16 v[2:5], v[184:187], v[216:219], v[2:5]
	s_barrier
; #define PG8_STAGE(bufoff, gbase, voff) do { _Pragma("unroll") for (int _i = 0; _i < 2; ++_i) \
;         __builtin_amdgcn_global_load_lds((const unsigned*)((const char*)(gbase) + (voff)[_i]), (LAS unsigned*)(lds + (bufoff) + ldsw + _i * 8192), 16, 0, 0); } while (0)
; #define PG8_LDA(dst, b, h) do { _Pragma("unroll") for (int m = 0; m < 4; ++m) _Pragma("unroll") for (int k = 0; k < 2; ++k) dst[m][k] = *(const LAS bf16x8*)(lds + PG8_SA(b, h) + aoff + m * 2048 + k * 1024); } while (0)
; #define PG8_LDB(dst, b, h) do { _Pragma("unroll") for (int n = 0; n < 2; ++n) _Pragma("unroll") for (int k = 0; k < 2; ++k) dst[n][k] = *(const LAS bf16x8*)(lds + PG8_SB(b, h) + boff + n * 2048 + k * 1024); } while (0)
; #define PG8_MMA(ai, bj, At, Bt) do { __builtin_amdgcn_s_setprio(1); _Pragma("unroll") for (int m = 0; m < 4; ++m) _Pragma("unroll") for (int n = 0; n < 2; ++n) _Pragma("unroll") for (int k = 0; k < 2; ++k) \
;         acc[ai][bj][m][n] = __builtin_amdgcn_mfma_f32_16x16x32_bf16(Bt[n][k], At[m][k], acc[ai][bj][m][n], 0, 0, 0); __builtin_amdgcn_s_setprio(0); } while (0)
; #define PG8_WAIT_V(n) asm volatile("s_waitcnt vmcnt(" #n ")" ::: "memory")
; #define PG8_WAIT_L(n) asm volatile("s_waitcnt lgkmcnt(" #n ")" ::: "memory")
; #define PG8_BAR __builtin_amdgcn_s_barrier()
; #define PG8_SCHED __builtin_amdgcn_sched_barrier(0)
; template <class Epi, class Sched, bool ABLK = false, bool ALIGN_EPI = true, bool SP2 = true, bool BBLK = true>
; __device__ __forceinline__ void gemm_phase(LAS unsigned char* lds, const Gemm g, const Sched& S, const Epi& E) {
;     ...
;             PG8_LDB(B0, 1, 0); PG8_LDB(B1, 1, 1); PG8_SCHED; PG8_LDA(At, 1, 0); PG8_STAGE(PG8_SA(0, 1), a2 + hstepA, voffA);
;             PG8_WAIT_V(8); PG8_WAIT_L(0); PG8_BAR; PG8_MMA(0, 0, At, B0); PG8_MMA(0, 1, At, B1); PG8_BAR; PG8_SCHED;
;             PG8_LDA(At, 1, 1); PG8_STAGE(PG8_SB(1, 0), b3, voffB); PG8_STAGE(PG8_SB(1, 1), b3 + hstepB, voffB); PG8_STAGE(PG8_SA(1, 0), a3, voffA);
;             PG8_WAIT_V(8); PG8_WAIT_L(0); PG8_BAR; PG8_MMA(1, 0, At, B0); PG8_MMA(1, 1, At, B1); PG8_BAR; PG8_SCHED;
	v_add_u32_e32 v168, s60, v151
	v_add_u32_e32 v184, s61, v151
	ds_read_b128 v[156:159], v168
	ds_read_b128 v[160:163], v168 offset:1024
	ds_read_b128 v[164:167], v168 offset:2048
	ds_read_b128 v[168:171], v168 offset:3072
	ds_read_b128 v[172:175], v184
	ds_read_b128 v[176:179], v184 offset:1024
	ds_read_b128 v[180:183], v184 offset:2048
	ds_read_b128 v[184:187], v184 offset:3072
	s_add_u32 s26, s26, 0x80000
	s_addc_u32 s27, s27, 0
	s_mov_b32 m0, s37
	ds_read_b128 v[188:191], v155 offset:32768
	ds_read_b128 v[192:195], v155 offset:33792
	ds_read_b128 v[196:199], v155 offset:34816
	ds_read_b128 v[200:203], v155 offset:35840
	ds_read_b128 v[204:207], v155 offset:36864
	ds_read_b128 v[208:211], v155 offset:37888
	ds_read_b128 v[212:215], v155 offset:38912
	ds_read_b128 v[216:219], v155 offset:39936
	global_load_lds_dwordx4 v130, s[26:27]
	s_mov_b32 m0, s40
	s_nop 0
	global_load_lds_dwordx4 v134, s[26:27]
	s_waitcnt vmcnt(8)
	s_barrier
	s_waitcnt lgkmcnt(0)
	v_mfma_f32_16x16x32_bf16 v[126:129], v[156:159], v[188:191], v[126:129]
	v_mfma_f32_16x16x32_bf16 v[122:125], v[164:167], v[188:191], v[122:125]
	v_mfma_f32_16x16x32_bf16 v[110:113], v[156:159], v[196:199], v[110:113]
	v_mfma_f32_16x16x32_bf16 v[106:109], v[164:167], v[196:199], v[106:109]
	v_mfma_f32_16x16x32_bf16 v[94:97], v[156:159], v[204:207], v[94:97]
	v_mfma_f32_16x16x32_bf16 v[90:93], v[164:167], v[204:207], v[90:93]
	v_mfma_f32_16x16x32_bf16 v[78:81], v[156:159], v[212:215], v[78:81]
	v_mfma_f32_16x16x32_bf16 v[74:77], v[164:167], v[212:215], v[74:77]
	v_mfma_f32_16x16x32_bf16 v[126:129], v[160:163], v[192:195], v[126:129]
	v_mfma_f32_16x16x32_bf16 v[122:125], v[168:171], v[192:195], v[122:125]
	v_mfma_f32_16x16x32_bf16 v[110:113], v[160:163], v[200:203], v[110:113]
	v_mfma_f32_16x16x32_bf16 v[106:109], v[168:171], v[200:203], v[106:109]
	v_mfma_f32_16x16x32_bf16 v[94:97], v[160:163], v[208:211], v[94:97]
	v_mfma_f32_16x16x32_bf16 v[90:93], v[168:171], v[208:211], v[90:93]
	v_mfma_f32_16x16x32_bf16 v[78:81], v[160:163], v[216:219], v[78:81]
	v_mfma_f32_16x16x32_bf16 v[74:77], v[168:171], v[216:219], v[74:77]
	v_mfma_f32_16x16x32_bf16 v[118:121], v[172:175], v[188:191], v[118:121]
	v_mfma_f32_16x16x32_bf16 v[114:117], v[180:183], v[188:191], v[114:117]
	v_mfma_f32_16x16x32_bf16 v[102:105], v[172:175], v[196:199], v[102:105]
	v_mfma_f32_16x16x32_bf16 v[98:101], v[180:183], v[196:199], v[98:101]
	v_mfma_f32_16x16x32_bf16 v[86:89], v[172:175], v[204:207], v[86:89]
	v_mfma_f32_16x16x32_bf16 v[82:85], v[180:183], v[204:207], v[82:85]
	v_mfma_f32_16x16x32_bf16 v[70:73], v[172:175], v[212:215], v[70:73]
	v_mfma_f32_16x16x32_bf16 v[66:69], v[180:183], v[212:215], v[66:69]
	v_mfma_f32_16x16x32_bf16 v[118:121], v[176:179], v[192:195], v[118:121]
	v_mfma_f32_16x16x32_bf16 v[114:117], v[184:187], v[192:195], v[114:117]
	v_mfma_f32_16x16x32_bf16 v[102:105], v[176:179], v[200:203], v[102:105]
	v_mfma_f32_16x16x32_bf16 v[98:101], v[184:187], v[200:203], v[98:101]
	v_mfma_f32_16x16x32_bf16 v[86:89], v[176:179], v[208:211], v[86:89]
	v_mfma_f32_16x16x32_bf16 v[82:85], v[184:187], v[208:211], v[82:85]
	v_mfma_f32_16x16x32_bf16 v[70:73], v[176:179], v[216:219], v[70:73]
	v_mfma_f32_16x16x32_bf16 v[66:69], v[184:187], v[216:219], v[66:69]
	s_barrier
	s_add_u32 s26, s24, 0x8000
	s_addc_u32 s27, s25, 0
	s_add_i32 s66, s60, s34
	s_mov_b32 m0, s66
	ds_read_b128 v[188:191], v155 offset:49152
	ds_read_b128 v[192:195], v155 offset:50176
	ds_read_b128 v[196:199], v155 offset:51200
	ds_read_b128 v[200:203], v155 offset:52224
	ds_read_b128 v[204:207], v155 offset:53248
	ds_read_b128 v[208:211], v155 offset:54272
	ds_read_b128 v[212:215], v155 offset:55296
	ds_read_b128 v[216:219], v155 offset:56320
	global_load_lds_dwordx4 v132, s[26:27]
	s_add_i32 m0, s66, 0x2000
	s_add_u32 s24, s24, 0xc000
	v_lshl_add_u64 v[220:221], s[26:27], 0, v[136:137]
	s_addc_u32 s25, s25, 0
	s_add_i32 s26, s61, s34
	global_load_lds_dwordx4 v[220:221], off
	s_mov_b32 m0, s26
	s_nop 0
	global_load_lds_dwordx4 v132, s[24:25]
	s_add_i32 m0, s26, 0x2000
	s_nop 0
	global_load_lds_dwordx4 v136, s[24:25]
	s_mov_b32 m0, s41
	s_nop 0
	global_load_lds_dwordx4 v130, s[22:23]
	s_mov_b32 m0, s42
	s_nop 0
	global_load_lds_dwordx4 v134, s[22:23]
	s_waitcnt vmcnt(8)
	s_barrier
	s_waitcnt lgkmcnt(0)
	v_mfma_f32_16x16x32_bf16 v[62:65], v[156:159], v[188:191], v[62:65]
	v_mfma_f32_16x16x32_bf16 v[58:61], v[164:167], v[188:191], v[58:61]
	v_mfma_f32_16x16x32_bf16 v[46:49], v[156:159], v[196:199], v[46:49]
	v_mfma_f32_16x16x32_bf16 v[42:45], v[164:167], v[196:199], v[42:45]
	v_mfma_f32_16x16x32_bf16 v[30:33], v[156:159], v[204:207], v[30:33]
	v_mfma_f32_16x16x32_bf16 v[26:29], v[164:167], v[204:207], v[26:29]
	v_mfma_f32_16x16x32_bf16 v[14:17], v[156:159], v[212:215], v[14:17]
	v_mfma_f32_16x16x32_bf16 v[10:13], v[164:167], v[212:215], v[10:13]
	v_mfma_f32_16x16x32_bf16 v[62:65], v[160:163], v[192:195], v[62:65]
	v_mfma_f32_16x16x32_bf16 v[58:61], v[168:171], v[192:195], v[58:61]
	v_mfma_f32_16x16x32_bf16 v[46:49], v[160:163], v[200:203], v[46:49]
	v_mfma_f32_16x16x32_bf16 v[42:45], v[168:171], v[200:203], v[42:45]
	v_mfma_f32_16x16x32_bf16 v[30:33], v[160:163], v[208:211], v[30:33]
	v_mfma_f32_16x16x32_bf16 v[26:29], v[168:171], v[208:211], v[26:29]
	v_mfma_f32_16x16x32_bf16 v[14:17], v[160:163], v[216:219], v[14:17]
	v_mfma_f32_16x16x32_bf16 v[10:13], v[168:171], v[216:219], v[10:13]
	v_mfma_f32_16x16x32_bf16 v[54:57], v[172:175], v[188:191], v[54:57]
	v_mfma_f32_16x16x32_bf16 v[50:53], v[180:183], v[188:191], v[50:53]
	v_mfma_f32_16x16x32_bf16 v[38:41], v[172:175], v[196:199], v[38:41]
	v_mfma_f32_16x16x32_bf16 v[34:37], v[180:183], v[196:199], v[34:37]
	v_mfma_f32_16x16x32_bf16 v[22:25], v[172:175], v[204:207], v[22:25]
	v_mfma_f32_16x16x32_bf16 v[18:21], v[180:183], v[204:207], v[18:21]
	v_mfma_f32_16x16x32_bf16 v[6:9], v[172:175], v[212:215], v[6:9]
	v_mfma_f32_16x16x32_bf16 v[2:5], v[180:183], v[212:215], v[2:5]
	v_mfma_f32_16x16x32_bf16 v[54:57], v[176:179], v[192:195], v[54:57]
	v_mfma_f32_16x16x32_bf16 v[50:53], v[184:187], v[192:195], v[50:53]
	v_mfma_f32_16x16x32_bf16 v[38:41], v[176:179], v[200:203], v[38:41]
	v_mfma_f32_16x16x32_bf16 v[34:37], v[184:187], v[200:203], v[34:37]
	v_mfma_f32_16x16x32_bf16 v[22:25], v[176:179], v[208:211], v[22:25]
	v_mfma_f32_16x16x32_bf16 v[18:21], v[184:187], v[208:211], v[18:21]
	v_mfma_f32_16x16x32_bf16 v[6:9], v[176:179], v[216:219], v[6:9]
	v_mfma_f32_16x16x32_bf16 v[2:5], v[184:187], v[216:219], v[2:5]
	s_barrier
	s_add_u32 s51, s51, 0x10000
	s_addc_u32 s55, s55, 0
	s_add_u32 s20, s20, 0x100
	s_addc_u32 s21, s21, 0
	s_cmp_ge_u32 s65, s46
	s_cbranch_scc0 .LBB0_1038
	s_and_b64 vcc, exec, s[10:11]
	s_cbranch_vccz .LBB0_1041
	s_barrier

; #define PG8_STAGE(bufoff, gbase, voff) do { _Pragma("unroll") for (int _i = 0; _i < 2; ++_i) \
;         __builtin_amdgcn_global_load_lds((const unsigned*)((const char*)(gbase) + (voff)[_i]), (LAS unsigned*)(lds + (bufoff) + ldsw + _i * 8192), 16, 0, 0); } while (0)
; #define PG8_LDA(dst, b, h) do { _Pragma("unroll") for (int m = 0; m < 4; ++m) _Pragma("unroll") for (int k = 0; k < 2; ++k) dst[m][k] = *(const LAS bf16x8*)(lds + PG8_SA(b, h) + aoff + m * 2048 + k * 1024); } while (0)
; #define PG8_LDB(dst, b, h) do { _Pragma("unroll") for (int n = 0; n < 2; ++n) _Pragma("unroll") for (int k = 0; k < 2; ++k) dst[n][k] = *(const LAS bf16x8*)(lds + PG8_SB(b, h) + boff + n * 2048 + k * 1024); } while (0)
; #define PG8_WAIT_V(n) asm volatile("s_waitcnt vmcnt(" #n ")" ::: "memory")
; #define PG8_WAIT_L(n) asm volatile("s_waitcnt lgkmcnt(" #n ")" ::: "memory")
; template <class Epi, class Sched, bool ABLK = false, bool ALIGN_EPI = true, bool SP2 = true, bool BBLK = true>
; __device__ __forceinline__ void gemm_phase(LAS unsigned char* lds, const Gemm g, const Sched& S, const Epi& E) {
;     ...
;         const bool has_next = S.next(ui + 1, nxt);
;         const int nt = cur.nt;
;         const char* nuA = has_next ? a_unit(nxt) : uA; const int ntbA = has_next ? nxt.k0 / BK : tbA; const char* nB = has_next ? (const char*)g.Bt + (size_t)nxt.pn * tstepB + b_k0(nxt.k0) : cB;
;         for (int t = 0; t < nt; t += 2) {
;             const bool last = (t == nt - 2);
;             const char* a1 = a_tile(uA, tbA + t + 1);
;             const char* a2 = last ? a_tile(nuA, ntbA) : a_tile(uA, tbA + t + 2); const char* b2 = last ? nB : cB + (size_t)(t + 2) * kstepB;
;             const char* a3 = last ? a_tile(nuA, ntbA + 1) : a_tile(uA, tbA + t + 3); const char* b3 = b2 + kstepB;
;             if (last && has_next) S.a_ready(nxt);
;             if constexpr (SP2) {
;             PG8_LDB(B0, 0, 0); PG8_LDB(B1, 0, 1); PG8_SCHED; PG8_LDA(At, 0, 0); PG8_STAGE(PG8_SA(1, 1), a1 + hstepA, voffA);
;             PG8_WAIT_V(8); PG8_WAIT_L(0); PG8_BAR; PG8_MMA(0, 0, At, B0); PG8_MMA(0, 1, At, B1); PG8_BAR; PG8_SCHED;
;             PG8_LDA(At, 0, 1); PG8_STAGE(PG8_SB(0, 0), b2, voffB); PG8_STAGE(PG8_SB(0, 1), b2 + hstepB, voffB); PG8_STAGE(PG8_SA(0, 0), a2, voffA);
;             PG8_WAIT_V(8); PG8_WAIT_L(0); PG8_BAR; PG8_MMA(1, 0, At, B0); PG8_MMA(1, 1, At, B1); PG8_BAR; PG8_SCHED;
.LBB0_1163:
	s_ashr_i32 s11, s10, 31
	s_lshl_b64 s[4:5], s[10:11], 20
	s_add_u32 s16, s59, s4
	s_addc_u32 s17, s62, s5
	s_and_b64 s[4:5], s[18:19], exec
	s_cselect_b32 s4, s17, s27
	s_cselect_b32 s5, s16, s26
	s_ashr_i32 s15, s14, 31
	s_lshl_b64 s[20:21], s[14:15], 20
	s_add_u32 s20, s40, s20
	s_addc_u32 s21, s41, s21
	s_and_b64 s[30:31], s[18:19], exec
	s_cselect_b32 s11, s21, s29
	s_cselect_b32 s15, s20, s28
	s_add_u32 s23, s5, 0x80
	s_addc_u32 s57, s4, 0
	s_add_u32 s64, s28, 0x10000
	v_mov_b32_e32 v2, 0
	s_addc_u32 s65, s29, 0
	v_lshl_add_u64 v[164:165], s[26:27], 0, v[160:161]
	v_lshl_add_u64 v[166:167], s[26:27], 0, v[162:163]
	s_mov_b32 s66, -2
	s_mov_b64 s[28:29], 0
	ds_read_b128 v[172:175], v169
	ds_read_b128 v[176:179], v169 offset:1024
	ds_read_b128 v[180:183], v169 offset:2048
	ds_read_b128 v[184:187], v169 offset:3072
	ds_read_b128 v[188:191], v170
	ds_read_b128 v[192:195], v170 offset:1024
	ds_read_b128 v[196:199], v170 offset:2048
	ds_read_b128 v[200:203], v170 offset:3072
	s_add_u32 s30, s26, s28
	s_addc_u32 s31, s27, s29
	s_add_u32 s36, s30, 0x100
	s_addc_u32 s37, s31, 0
	s_add_u32 s30, s30, 0x180
	s_addc_u32 s31, s31, 0
	s_cmpk_eq_i32 s28, 0xf00
	s_cselect_b32 s31, s57, s31
	s_cselect_b32 s30, s23, s30
	s_cselect_b32 s35, s11, s65
	s_cselect_b32 s34, s15, s64
	s_cselect_b32 s37, s4, s37
	s_cselect_b32 s36, s5, s36
	s_mov_b32 m0, s50
	v_lshl_add_u64 v[236:237], v[164:165], 0, s[28:29]
	ds_read_b128 v[204:207], v171
	ds_read_b128 v[208:211], v171 offset:1024
	ds_read_b128 v[212:215], v171 offset:2048
	ds_read_b128 v[216:219], v171 offset:3072
	ds_read_b128 v[220:223], v171 offset:4096
	ds_read_b128 v[224:227], v171 offset:5120
	ds_read_b128 v[228:231], v171 offset:6144
	ds_read_b128 v[232:235], v171 offset:7168
	global_load_lds_dwordx4 v[236:237], off
	v_lshl_add_u64 v[236:237], v[166:167], 0, s[28:29]
	s_mov_b32 m0, s51
	s_nop 0
	global_load_lds_dwordx4 v[236:237], off
	s_waitcnt vmcnt(8)
	s_barrier
	s_waitcnt lgkmcnt(0)
	v_mfma_f32_16x16x32_bf16 v[126:129], v[172:175], v[204:207], 0
	v_mfma_f32_16x16x32_bf16 v[122:125], v[180:183], v[204:207], 0
	v_mfma_f32_16x16x32_bf16 v[110:113], v[172:175], v[212:215], 0
	v_mfma_f32_16x16x32_bf16 v[106:109], v[180:183], v[212:215], 0
	v_mfma_f32_16x16x32_bf16 v[94:97], v[172:175], v[220:223], 0
	v_mfma_f32_16x16x32_bf16 v[90:93], v[180:183], v[220:223], 0
	v_mfma_f32_16x16x32_bf16 v[78:81], v[172:175], v[228:231], 0
	v_mfma_f32_16x16x32_bf16 v[74:77], v[180:183], v[228:231], 0
	v_mfma_f32_16x16x32_bf16 v[126:129], v[176:179], v[208:211], v[126:129]
	v_mfma_f32_16x16x32_bf16 v[122:125], v[184:187], v[208:211], v[122:125]
	v_mfma_f32_16x16x32_bf16 v[110:113], v[176:179], v[216:219], v[110:113]
	v_mfma_f32_16x16x32_bf16 v[106:109], v[184:187], v[216:219], v[106:109]
	v_mfma_f32_16x16x32_bf16 v[94:97], v[176:179], v[224:227], v[94:97]
	v_mfma_f32_16x16x32_bf16 v[90:93], v[184:187], v[224:227], v[90:93]
	v_mfma_f32_16x16x32_bf16 v[78:81], v[176:179], v[232:235], v[78:81]
	v_mfma_f32_16x16x32_bf16 v[74:77], v[184:187], v[232:235], v[74:77]
	v_mfma_f32_16x16x32_bf16 v[118:121], v[188:191], v[204:207], 0
	v_mfma_f32_16x16x32_bf16 v[114:117], v[196:199], v[204:207], 0
	v_mfma_f32_16x16x32_bf16 v[102:105], v[188:191], v[212:215], 0
	v_mfma_f32_16x16x32_bf16 v[98:101], v[196:199], v[212:215], 0
	v_mfma_f32_16x16x32_bf16 v[86:89], v[188:191], v[220:223], 0
	v_mfma_f32_16x16x32_bf16 v[82:85], v[196:199], v[220:223], 0
	v_mfma_f32_16x16x32_bf16 v[70:73], v[188:191], v[228:231], 0
	v_mfma_f32_16x16x32_bf16 v[66:69], v[196:199], v[228:231], 0
	v_mfma_f32_16x16x32_bf16 v[118:121], v[192:195], v[208:211], v[118:121]
	v_mfma_f32_16x16x32_bf16 v[114:117], v[200:203], v[208:211], v[114:117]
	v_mfma_f32_16x16x32_bf16 v[102:105], v[192:195], v[216:219], v[102:105]
	v_mfma_f32_16x16x32_bf16 v[98:101], v[200:203], v[216:219], v[98:101]
	v_mfma_f32_16x16x32_bf16 v[86:89], v[192:195], v[224:227], v[86:89]
	v_mfma_f32_16x16x32_bf16 v[82:85], v[200:203], v[224:227], v[82:85]
	v_mfma_f32_16x16x32_bf16 v[70:73], v[192:195], v[232:235], v[70:73]
	v_mfma_f32_16x16x32_bf16 v[66:69], v[200:203], v[232:235], v[66:69]
	s_barrier
	s_mov_b32 m0, s55
	s_add_u32 s76, s34, 0x4000
	ds_read_b128 v[204:207], v171 offset:16384
	ds_read_b128 v[208:211], v171 offset:17408
	ds_read_b128 v[212:215], v171 offset:18432
	ds_read_b128 v[216:219], v171 offset:19456
	ds_read_b128 v[220:223], v171 offset:20480
	ds_read_b128 v[224:227], v171 offset:21504
	ds_read_b128 v[228:231], v171 offset:22528
	ds_read_b128 v[232:235], v171 offset:23552
	global_load_lds_dwordx4 v134, s[34:35]
	s_mov_b32 m0, s56
	s_addc_u32 s77, s35, 0
	s_add_i32 s67, s73, s42
	global_load_lds_dwordx4 v130, s[34:35]
	s_mov_b32 m0, s67
	s_nop 0
	global_load_lds_dwordx4 v134, s[76:77]
	s_add_i32 m0, s67, 0x2000
	s_nop 0
	global_load_lds_dwordx4 v130, s[76:77]
	s_mov_b32 m0, s25
	s_nop 0
	global_load_lds_dwordx4 v136, s[36:37]
	s_mov_b32 m0, s43
	s_nop 0
	global_load_lds_dwordx4 v132, s[36:37]
	s_waitcnt vmcnt(8)
	s_barrier
; #define PG8_STAGE(bufoff, gbase, voff) do { _Pragma("unroll") for (int _i = 0; _i < 2; ++_i) \
;         __builtin_amdgcn_global_load_lds((const unsigned*)((const char*)(gbase) + (voff)[_i]), (LAS unsigned*)(lds + (bufoff) + ldsw + _i * 8192), 16, 0, 0); } while (0)
; #define PG8_LDA(dst, b, h) do { _Pragma("unroll") for (int m = 0; m < 4; ++m) _Pragma("unroll") for (int k = 0; k < 2; ++k) dst[m][k] = *(const LAS bf16x8*)(lds + PG8_SA(b, h) + aoff + m * 2048 + k * 1024); } while (0)
; #define PG8_LDB(dst, b, h) do { _Pragma("unroll") for (int n = 0; n < 2; ++n) _Pragma("unroll") for (int k = 0; k < 2; ++k) dst[n][k] = *(const LAS bf16x8*)(lds + PG8_SB(b, h) + boff + n * 2048 + k * 1024); } while (0)
; #define PG8_MMA(ai, bj, At, Bt) do { __builtin_amdgcn_s_setprio(1); _Pragma("unroll") for (int m = 0; m < 4; ++m) _Pragma("unroll") for (int n = 0; n < 2; ++n) _Pragma("unroll") for (int k = 0; k < 2; ++k) \
;         acc[ai][bj][m][n] = __builtin_amdgcn_mfma_f32_16x16x32_bf16(Bt[n][k], At[m][k], acc[ai][bj][m][n], 0, 0, 0); __builtin_amdgcn_s_setprio(0); } while (0)
; #define PG8_WAIT_V(n) asm volatile("s_waitcnt vmcnt(" #n ")" ::: "memory")
; #define PG8_WAIT_L(n) asm volatile("s_waitcnt lgkmcnt(" #n ")" ::: "memory")
; #define PG8_BAR __builtin_amdgcn_s_barrier()
; #define PG8_SCHED __builtin_amdgcn_sched_barrier(0)
; template <class Epi, class Sched, bool ABLK = false, bool ALIGN_EPI = true, bool SP2 = true, bool BBLK = true>
; __device__ __forceinline__ void gemm_phase(LAS unsigned char* lds, const Gemm g, const Sched& S, const Epi& E) {
;     ...
;             PG8_WAIT_V(8); PG8_WAIT_L(0); PG8_BAR; PG8_MMA(1, 0, At, B0); PG8_MMA(1, 1, At, B1); PG8_BAR; PG8_SCHED;
;             PG8_LDB(B0, 1, 0); PG8_LDB(B1, 1, 1); PG8_SCHED; PG8_LDA(At, 1, 0); PG8_STAGE(PG8_SA(0, 1), a2 + hstepA, voffA);
;             PG8_WAIT_V(8); PG8_WAIT_L(0); PG8_BAR; PG8_MMA(0, 0, At, B0); PG8_MMA(0, 1, At, B1); PG8_BAR; PG8_SCHED;
	s_waitcnt lgkmcnt(0)
	v_mfma_f32_16x16x32_bf16 v[62:65], v[172:175], v[204:207], 0
	v_mfma_f32_16x16x32_bf16 v[58:61], v[180:183], v[204:207], 0
	v_mfma_f32_16x16x32_bf16 v[46:49], v[172:175], v[212:215], 0
	v_mfma_f32_16x16x32_bf16 v[42:45], v[180:183], v[212:215], 0
	v_mfma_f32_16x16x32_bf16 v[30:33], v[172:175], v[220:223], 0
	v_mfma_f32_16x16x32_bf16 v[26:29], v[180:183], v[220:223], 0
	v_mfma_f32_16x16x32_bf16 v[14:17], v[172:175], v[228:231], 0
	v_mfma_f32_16x16x32_bf16 v[10:13], v[180:183], v[228:231], 0
	v_mfma_f32_16x16x32_bf16 v[62:65], v[176:179], v[208:211], v[62:65]
	v_mfma_f32_16x16x32_bf16 v[58:61], v[184:187], v[208:211], v[58:61]
	v_mfma_f32_16x16x32_bf16 v[46:49], v[176:179], v[216:219], v[46:49]
	v_mfma_f32_16x16x32_bf16 v[42:45], v[184:187], v[216:219], v[42:45]
	v_mfma_f32_16x16x32_bf16 v[30:33], v[176:179], v[224:227], v[30:33]
	v_mfma_f32_16x16x32_bf16 v[26:29], v[184:187], v[224:227], v[26:29]
	v_mfma_f32_16x16x32_bf16 v[14:17], v[176:179], v[232:235], v[14:17]
	v_mfma_f32_16x16x32_bf16 v[10:13], v[184:187], v[232:235], v[10:13]
	v_mfma_f32_16x16x32_bf16 v[54:57], v[188:191], v[204:207], 0
	v_mfma_f32_16x16x32_bf16 v[50:53], v[196:199], v[204:207], 0
	v_mfma_f32_16x16x32_bf16 v[38:41], v[188:191], v[212:215], 0
	v_mfma_f32_16x16x32_bf16 v[34:37], v[196:199], v[212:215], 0
	v_mfma_f32_16x16x32_bf16 v[22:25], v[188:191], v[220:223], 0
	v_mfma_f32_16x16x32_bf16 v[18:21], v[196:199], v[220:223], 0
	v_mfma_f32_16x16x32_bf16 v[6:9], v[188:191], v[228:231], 0
	v_mfma_f32_16x16x32_bf16 v[2:5], v[196:199], v[228:231], 0
	v_mfma_f32_16x16x32_bf16 v[54:57], v[192:195], v[208:211], v[54:57]
	v_mfma_f32_16x16x32_bf16 v[50:53], v[200:203], v[208:211], v[50:53]
	v_mfma_f32_16x16x32_bf16 v[38:41], v[192:195], v[216:219], v[38:41]
	v_mfma_f32_16x16x32_bf16 v[34:37], v[200:203], v[216:219], v[34:37]
	v_mfma_f32_16x16x32_bf16 v[22:25], v[192:195], v[224:227], v[22:25]
	v_mfma_f32_16x16x32_bf16 v[18:21], v[200:203], v[224:227], v[18:21]
	v_mfma_f32_16x16x32_bf16 v[6:9], v[192:195], v[232:235], v[6:9]
	v_mfma_f32_16x16x32_bf16 v[2:5], v[200:203], v[232:235], v[2:5]
	s_barrier
	v_add_u32_e32 v184, s60, v168
	v_add_u32_e32 v200, s61, v168
	ds_read_b128 v[172:175], v184
	ds_read_b128 v[176:179], v184 offset:1024
	ds_read_b128 v[180:183], v184 offset:2048
	ds_read_b128 v[184:187], v184 offset:3072
	ds_read_b128 v[188:191], v200
	ds_read_b128 v[192:195], v200 offset:1024
	ds_read_b128 v[196:199], v200 offset:2048
	ds_read_b128 v[200:203], v200 offset:3072
	s_add_u32 s36, s36, 0x80000
	s_addc_u32 s37, s37, 0
	s_mov_b32 m0, s44
	ds_read_b128 v[204:207], v171 offset:32768
	ds_read_b128 v[208:211], v171 offset:33792
	ds_read_b128 v[212:215], v171 offset:34816
	ds_read_b128 v[216:219], v171 offset:35840
	ds_read_b128 v[220:223], v171 offset:36864
	ds_read_b128 v[224:227], v171 offset:37888
	ds_read_b128 v[228:231], v171 offset:38912
	ds_read_b128 v[232:235], v171 offset:39936
	global_load_lds_dwordx4 v136, s[36:37]
	s_mov_b32 m0, s45
	s_nop 0
	global_load_lds_dwordx4 v132, s[36:37]
	s_waitcnt vmcnt(8)
	s_barrier
	s_waitcnt lgkmcnt(0)
	v_mfma_f32_16x16x32_bf16 v[126:129], v[172:175], v[204:207], v[126:129]
	v_mfma_f32_16x16x32_bf16 v[122:125], v[180:183], v[204:207], v[122:125]
	v_mfma_f32_16x16x32_bf16 v[110:113], v[172:175], v[212:215], v[110:113]
	v_mfma_f32_16x16x32_bf16 v[106:109], v[180:183], v[212:215], v[106:109]
	v_mfma_f32_16x16x32_bf16 v[94:97], v[172:175], v[220:223], v[94:97]
	v_mfma_f32_16x16x32_bf16 v[90:93], v[180:183], v[220:223], v[90:93]
	v_mfma_f32_16x16x32_bf16 v[78:81], v[172:175], v[228:231], v[78:81]
	v_mfma_f32_16x16x32_bf16 v[74:77], v[180:183], v[228:231], v[74:77]
	v_mfma_f32_16x16x32_bf16 v[126:129], v[176:179], v[208:211], v[126:129]
	v_mfma_f32_16x16x32_bf16 v[122:125], v[184:187], v[208:211], v[122:125]
	v_mfma_f32_16x16x32_bf16 v[110:113], v[176:179], v[216:219], v[110:113]
	v_mfma_f32_16x16x32_bf16 v[106:109], v[184:187], v[216:219], v[106:109]
	v_mfma_f32_16x16x32_bf16 v[94:97], v[176:179], v[224:227], v[94:97]
	v_mfma_f32_16x16x32_bf16 v[90:93], v[184:187], v[224:227], v[90:93]
	v_mfma_f32_16x16x32_bf16 v[78:81], v[176:179], v[232:235], v[78:81]
	v_mfma_f32_16x16x32_bf16 v[74:77], v[184:187], v[232:235], v[74:77]
	v_mfma_f32_16x16x32_bf16 v[118:121], v[188:191], v[204:207], v[118:121]
	v_mfma_f32_16x16x32_bf16 v[114:117], v[196:199], v[204:207], v[114:117]
	v_mfma_f32_16x16x32_bf16 v[102:105], v[188:191], v[212:215], v[102:105]
	v_mfma_f32_16x16x32_bf16 v[98:101], v[196:199], v[212:215], v[98:101]
	v_mfma_f32_16x16x32_bf16 v[86:89], v[188:191], v[220:223], v[86:89]
	v_mfma_f32_16x16x32_bf16 v[82:85], v[196:199], v[220:223], v[82:85]
	v_mfma_f32_16x16x32_bf16 v[70:73], v[188:191], v[228:231], v[70:73]
	v_mfma_f32_16x16x32_bf16 v[66:69], v[196:199], v[228:231], v[66:69]
	v_mfma_f32_16x16x32_bf16 v[118:121], v[192:195], v[208:211], v[118:121]
	v_mfma_f32_16x16x32_bf16 v[114:117], v[200:203], v[208:211], v[114:117]
	v_mfma_f32_16x16x32_bf16 v[102:105], v[192:195], v[216:219], v[102:105]
	v_mfma_f32_16x16x32_bf16 v[98:101], v[200:203], v[216:219], v[98:101]
	v_mfma_f32_16x16x32_bf16 v[86:89], v[192:195], v[224:227], v[86:89]
	v_mfma_f32_16x16x32_bf16 v[82:85], v[200:203], v[224:227], v[82:85]
	v_mfma_f32_16x16x32_bf16 v[70:73], v[192:195], v[232:235], v[70:73]
	v_mfma_f32_16x16x32_bf16 v[66:69], v[200:203], v[232:235], v[66:69]
	s_barrier
; #define PG8_STAGE(bufoff, gbase, voff) do { _Pragma("unroll") for (int _i = 0; _i < 2; ++_i) \
;         __builtin_amdgcn_global_load_lds((const unsigned*)((const char*)(gbase) + (voff)[_i]), (LAS unsigned*)(lds + (bufoff) + ldsw + _i * 8192), 16, 0, 0); } while (0)
; #define PG8_LDA(dst, b, h) do { _Pragma("unroll") for (int m = 0; m < 4; ++m) _Pragma("unroll") for (int k = 0; k < 2; ++k) dst[m][k] = *(const LAS bf16x8*)(lds + PG8_SA(b, h) + aoff + m * 2048 + k * 1024); } while (0)
; #define PG8_WAIT_V(n) asm volatile("s_waitcnt vmcnt(" #n ")" ::: "memory")
; #define PG8_WAIT_L(n) asm volatile("s_waitcnt lgkmcnt(" #n ")" ::: "memory")
; template <class Epi, class Sched, bool ABLK = false, bool ALIGN_EPI = true, bool SP2 = true, bool BBLK = true>
; __device__ __forceinline__ void gemm_phase(LAS unsigned char* lds, const Gemm g, const Sched& S, const Epi& E) {
;     ...
;         for (int t = 0; t < nt; t += 2) {
;             const bool last = (t == nt - 2);
;             const char* a1 = a_tile(uA, tbA + t + 1);
;             const char* a2 = last ? a_tile(nuA, ntbA) : a_tile(uA, tbA + t + 2); const char* b2 = last ? nB : cB + (size_t)(t + 2) * kstepB;
;             const char* a3 = last ? a_tile(nuA, ntbA + 1) : a_tile(uA, tbA + t + 3); const char* b3 = b2 + kstepB;
;             if (last && has_next) S.a_ready(nxt);
;             if constexpr (SP2) {
;             PG8_LDB(B0, 0, 0); PG8_LDB(B1, 0, 1); PG8_SCHED; PG8_LDA(At, 0, 0); PG8_STAGE(PG8_SA(1, 1), a1 + hstepA, voffA);
;             PG8_WAIT_V(8); PG8_WAIT_L(0); PG8_BAR; PG8_MMA(0, 0, At, B0); PG8_MMA(0, 1, At, B1); PG8_BAR; PG8_SCHED;
;             PG8_LDA(At, 0, 1); PG8_STAGE(PG8_SB(0, 0), b2, voffB); PG8_STAGE(PG8_SB(0, 1), b2 + hstepB, voffB); PG8_STAGE(PG8_SA(0, 0), a2, voffA);
;             PG8_WAIT_V(8); PG8_WAIT_L(0); PG8_BAR; PG8_MMA(1, 0, At, B0); PG8_MMA(1, 1, At, B1); PG8_BAR; PG8_SCHED;
;             PG8_LDB(B0, 1, 0); PG8_LDB(B1, 1, 1); PG8_SCHED; PG8_LDA(At, 1, 0); PG8_STAGE(PG8_SA(0, 1), a2 + hstepA, voffA);
;             PG8_WAIT_V(8); PG8_WAIT_L(0); PG8_BAR; PG8_MMA(0, 0, At, B0); PG8_MMA(0, 1, At, B1); PG8_BAR; PG8_SCHED;
;             PG8_LDA(At, 1, 1); PG8_STAGE(PG8_SB(1, 0), b3, voffB); PG8_STAGE(PG8_SB(1, 1), b3 + hstepB, voffB); PG8_STAGE(PG8_SA(1, 0), a3, voffA);
;             PG8_WAIT_V(8); PG8_WAIT_L(0); PG8_BAR; PG8_MMA(1, 0, At, B0); PG8_MMA(1, 1, At, B1); PG8_BAR; PG8_SCHED;
	s_add_u32 s36, s34, 0x8000
	s_addc_u32 s37, s35, 0
	s_add_i32 s67, s60, s42
	s_mov_b32 m0, s67
	ds_read_b128 v[204:207], v171 offset:49152
	ds_read_b128 v[208:211], v171 offset:50176
	ds_read_b128 v[212:215], v171 offset:51200
	ds_read_b128 v[216:219], v171 offset:52224
	ds_read_b128 v[220:223], v171 offset:53248
	ds_read_b128 v[224:227], v171 offset:54272
	ds_read_b128 v[228:231], v171 offset:55296
	ds_read_b128 v[232:235], v171 offset:56320
	global_load_lds_dwordx4 v134, s[36:37]
	s_add_i32 m0, s67, 0x2000
	s_add_u32 s34, s34, 0xc000
	v_lshl_add_u64 v[236:237], s[36:37], 0, v[130:131]
	s_addc_u32 s35, s35, 0
	s_add_i32 s36, s61, s42
	global_load_lds_dwordx4 v[236:237], off
	s_mov_b32 m0, s36
	s_nop 0
	global_load_lds_dwordx4 v134, s[34:35]
	s_add_i32 m0, s36, 0x2000
	s_nop 0
	global_load_lds_dwordx4 v130, s[34:35]
	s_mov_b32 m0, s48
	s_nop 0
	global_load_lds_dwordx4 v136, s[30:31]
	s_mov_b32 m0, s49
	s_nop 0
	global_load_lds_dwordx4 v132, s[30:31]
	s_waitcnt vmcnt(8)
	s_barrier
	s_waitcnt lgkmcnt(0)
	v_mfma_f32_16x16x32_bf16 v[62:65], v[172:175], v[204:207], v[62:65]
	v_mfma_f32_16x16x32_bf16 v[58:61], v[180:183], v[204:207], v[58:61]
	v_mfma_f32_16x16x32_bf16 v[46:49], v[172:175], v[212:215], v[46:49]
	v_mfma_f32_16x16x32_bf16 v[42:45], v[180:183], v[212:215], v[42:45]
	v_mfma_f32_16x16x32_bf16 v[30:33], v[172:175], v[220:223], v[30:33]
	v_mfma_f32_16x16x32_bf16 v[26:29], v[180:183], v[220:223], v[26:29]
	v_mfma_f32_16x16x32_bf16 v[14:17], v[172:175], v[228:231], v[14:17]
	v_mfma_f32_16x16x32_bf16 v[10:13], v[180:183], v[228:231], v[10:13]
	v_mfma_f32_16x16x32_bf16 v[62:65], v[176:179], v[208:211], v[62:65]
	v_mfma_f32_16x16x32_bf16 v[58:61], v[184:187], v[208:211], v[58:61]
	v_mfma_f32_16x16x32_bf16 v[46:49], v[176:179], v[216:219], v[46:49]
	v_mfma_f32_16x16x32_bf16 v[42:45], v[184:187], v[216:219], v[42:45]
	v_mfma_f32_16x16x32_bf16 v[30:33], v[176:179], v[224:227], v[30:33]
	v_mfma_f32_16x16x32_bf16 v[26:29], v[184:187], v[224:227], v[26:29]
	v_mfma_f32_16x16x32_bf16 v[14:17], v[176:179], v[232:235], v[14:17]
	v_mfma_f32_16x16x32_bf16 v[10:13], v[184:187], v[232:235], v[10:13]
	v_mfma_f32_16x16x32_bf16 v[54:57], v[188:191], v[204:207], v[54:57]
	v_mfma_f32_16x16x32_bf16 v[50:53], v[196:199], v[204:207], v[50:53]
	v_mfma_f32_16x16x32_bf16 v[38:41], v[188:191], v[212:215], v[38:41]
	v_mfma_f32_16x16x32_bf16 v[34:37], v[196:199], v[212:215], v[34:37]
	v_mfma_f32_16x16x32_bf16 v[22:25], v[188:191], v[220:223], v[22:25]
	v_mfma_f32_16x16x32_bf16 v[18:21], v[196:199], v[220:223], v[18:21]
	v_mfma_f32_16x16x32_bf16 v[6:9], v[188:191], v[228:231], v[6:9]
	v_mfma_f32_16x16x32_bf16 v[2:5], v[196:199], v[228:231], v[2:5]
	v_mfma_f32_16x16x32_bf16 v[54:57], v[192:195], v[208:211], v[54:57]
	v_mfma_f32_16x16x32_bf16 v[50:53], v[200:203], v[208:211], v[50:53]
	v_mfma_f32_16x16x32_bf16 v[38:41], v[192:195], v[216:219], v[38:41]
	v_mfma_f32_16x16x32_bf16 v[34:37], v[200:203], v[216:219], v[34:37]
	v_mfma_f32_16x16x32_bf16 v[22:25], v[192:195], v[224:227], v[22:25]
	v_mfma_f32_16x16x32_bf16 v[18:21], v[200:203], v[224:227], v[18:21]
	v_mfma_f32_16x16x32_bf16 v[6:9], v[192:195], v[232:235], v[6:9]
	v_mfma_f32_16x16x32_bf16 v[2:5], v[200:203], v[232:235], v[2:5]
	s_barrier
	s_add_i32 s66, s66, 2
	s_add_u32 s28, s28, 0x100
	s_addc_u32 s29, s29, 0
	s_add_u32 s64, s64, 0x10000
	s_addc_u32 s65, s65, 0
	s_cmp_gt_u32 s66, 29
.LBB0_1164:
	ds_read_b128 v[172:175], v169
	ds_read_b128 v[176:179], v169 offset:1024
	ds_read_b128 v[180:183], v169 offset:2048
	ds_read_b128 v[184:187], v169 offset:3072
	ds_read_b128 v[188:191], v170
	ds_read_b128 v[192:195], v170 offset:1024
	ds_read_b128 v[196:199], v170 offset:2048
	ds_read_b128 v[200:203], v170 offset:3072
	s_add_u32 s30, s26, s28
	s_addc_u32 s31, s27, s29
	s_add_u32 s36, s30, 0x100
	s_addc_u32 s37, s31, 0
	s_add_u32 s30, s30, 0x180
	s_addc_u32 s31, s31, 0
	s_cmpk_eq_i32 s28, 0xf00
	s_cselect_b32 s31, s57, s31
	s_cselect_b32 s30, s23, s30
	s_cselect_b32 s35, s11, s65
	s_cselect_b32 s34, s15, s64
	s_cselect_b32 s37, s4, s37
	s_cselect_b32 s36, s5, s36
	s_mov_b32 m0, s50
	v_lshl_add_u64 v[236:237], v[164:165], 0, s[28:29]
	ds_read_b128 v[204:207], v171
	ds_read_b128 v[208:211], v171 offset:1024
	ds_read_b128 v[212:215], v171 offset:2048
	ds_read_b128 v[216:219], v171 offset:3072
	ds_read_b128 v[220:223], v171 offset:4096
	ds_read_b128 v[224:227], v171 offset:5120
	ds_read_b128 v[228:231], v171 offset:6144
	ds_read_b128 v[232:235], v171 offset:7168
	global_load_lds_dwordx4 v[236:237], off
	v_lshl_add_u64 v[236:237], v[166:167], 0, s[28:29]
	s_mov_b32 m0, s51
	s_nop 0
	global_load_lds_dwordx4 v[236:237], off
	s_waitcnt vmcnt(8)
	s_barrier
; #define PG8_STAGE(bufoff, gbase, voff) do { _Pragma("unroll") for (int _i = 0; _i < 2; ++_i) \
;         __builtin_amdgcn_global_load_lds((const unsigned*)((const char*)(gbase) + (voff)[_i]), (LAS unsigned*)(lds + (bufoff) + ldsw + _i * 8192), 16, 0, 0); } while (0)
; #define PG8_LDA(dst, b, h) do { _Pragma("unroll") for (int m = 0; m < 4; ++m) _Pragma("unroll") for (int k = 0; k < 2; ++k) dst[m][k] = *(const LAS bf16x8*)(lds + PG8_SA(b, h) + aoff + m * 2048 + k * 1024); } while (0)
; #define PG8_MMA(ai, bj, At, Bt) do { __builtin_amdgcn_s_setprio(1); _Pragma("unroll") for (int m = 0; m < 4; ++m) _Pragma("unroll") for (int n = 0; n < 2; ++n) _Pragma("unroll") for (int k = 0; k < 2; ++k) \
;         acc[ai][bj][m][n] = __builtin_amdgcn_mfma_f32_16x16x32_bf16(Bt[n][k], At[m][k], acc[ai][bj][m][n], 0, 0, 0); __builtin_amdgcn_s_setprio(0); } while (0)
; #define PG8_WAIT_V(n) asm volatile("s_waitcnt vmcnt(" #n ")" ::: "memory")
; #define PG8_WAIT_L(n) asm volatile("s_waitcnt lgkmcnt(" #n ")" ::: "memory")
; #define PG8_BAR __builtin_amdgcn_s_barrier()
; #define PG8_SCHED __builtin_amdgcn_sched_barrier(0)
; template <class Epi, class Sched, bool ABLK = false, bool ALIGN_EPI = true, bool SP2 = true, bool BBLK = true>
; __device__ __forceinline__ void gemm_phase(LAS unsigned char* lds, const Gemm g, const Sched& S, const Epi& E) {
;     ...
;             PG8_WAIT_V(8); PG8_WAIT_L(0); PG8_BAR; PG8_MMA(0, 0, At, B0); PG8_MMA(0, 1, At, B1); PG8_BAR; PG8_SCHED;
;             PG8_LDA(At, 0, 1); PG8_STAGE(PG8_SB(0, 0), b2, voffB); PG8_STAGE(PG8_SB(0, 1), b2 + hstepB, voffB); PG8_STAGE(PG8_SA(0, 0), a2, voffA);
;             PG8_WAIT_V(8); PG8_WAIT_L(0); PG8_BAR; PG8_MMA(1, 0, At, B0); PG8_MMA(1, 1, At, B1); PG8_BAR; PG8_SCHED;
	s_waitcnt lgkmcnt(0)
	v_mfma_f32_16x16x32_bf16 v[126:129], v[172:175], v[204:207], v[126:129]
	v_mfma_f32_16x16x32_bf16 v[122:125], v[180:183], v[204:207], v[122:125]
	v_mfma_f32_16x16x32_bf16 v[110:113], v[172:175], v[212:215], v[110:113]
	v_mfma_f32_16x16x32_bf16 v[106:109], v[180:183], v[212:215], v[106:109]
	v_mfma_f32_16x16x32_bf16 v[94:97], v[172:175], v[220:223], v[94:97]
	v_mfma_f32_16x16x32_bf16 v[90:93], v[180:183], v[220:223], v[90:93]
	v_mfma_f32_16x16x32_bf16 v[78:81], v[172:175], v[228:231], v[78:81]
	v_mfma_f32_16x16x32_bf16 v[74:77], v[180:183], v[228:231], v[74:77]
	v_mfma_f32_16x16x32_bf16 v[126:129], v[176:179], v[208:211], v[126:129]
	v_mfma_f32_16x16x32_bf16 v[122:125], v[184:187], v[208:211], v[122:125]
	v_mfma_f32_16x16x32_bf16 v[110:113], v[176:179], v[216:219], v[110:113]
	v_mfma_f32_16x16x32_bf16 v[106:109], v[184:187], v[216:219], v[106:109]
	v_mfma_f32_16x16x32_bf16 v[94:97], v[176:179], v[224:227], v[94:97]
	v_mfma_f32_16x16x32_bf16 v[90:93], v[184:187], v[224:227], v[90:93]
	v_mfma_f32_16x16x32_bf16 v[78:81], v[176:179], v[232:235], v[78:81]
	v_mfma_f32_16x16x32_bf16 v[74:77], v[184:187], v[232:235], v[74:77]
	v_mfma_f32_16x16x32_bf16 v[118:121], v[188:191], v[204:207], v[118:121]
	v_mfma_f32_16x16x32_bf16 v[114:117], v[196:199], v[204:207], v[114:117]
	v_mfma_f32_16x16x32_bf16 v[102:105], v[188:191], v[212:215], v[102:105]
	v_mfma_f32_16x16x32_bf16 v[98:101], v[196:199], v[212:215], v[98:101]
	v_mfma_f32_16x16x32_bf16 v[86:89], v[188:191], v[220:223], v[86:89]
	v_mfma_f32_16x16x32_bf16 v[82:85], v[196:199], v[220:223], v[82:85]
	v_mfma_f32_16x16x32_bf16 v[70:73], v[188:191], v[228:231], v[70:73]
	v_mfma_f32_16x16x32_bf16 v[66:69], v[196:199], v[228:231], v[66:69]
	v_mfma_f32_16x16x32_bf16 v[118:121], v[192:195], v[208:211], v[118:121]
	v_mfma_f32_16x16x32_bf16 v[114:117], v[200:203], v[208:211], v[114:117]
	v_mfma_f32_16x16x32_bf16 v[102:105], v[192:195], v[216:219], v[102:105]
	v_mfma_f32_16x16x32_bf16 v[98:101], v[200:203], v[216:219], v[98:101]
	v_mfma_f32_16x16x32_bf16 v[86:89], v[192:195], v[224:227], v[86:89]
	v_mfma_f32_16x16x32_bf16 v[82:85], v[200:203], v[224:227], v[82:85]
	v_mfma_f32_16x16x32_bf16 v[70:73], v[192:195], v[232:235], v[70:73]
	v_mfma_f32_16x16x32_bf16 v[66:69], v[200:203], v[232:235], v[66:69]
	s_barrier
	s_mov_b32 m0, s55
	s_add_u32 s76, s34, 0x4000
	ds_read_b128 v[204:207], v171 offset:16384
	ds_read_b128 v[208:211], v171 offset:17408
	ds_read_b128 v[212:215], v171 offset:18432
	ds_read_b128 v[216:219], v171 offset:19456
	ds_read_b128 v[220:223], v171 offset:20480
	ds_read_b128 v[224:227], v171 offset:21504
	ds_read_b128 v[228:231], v171 offset:22528
	ds_read_b128 v[232:235], v171 offset:23552
	global_load_lds_dwordx4 v134, s[34:35]
	s_mov_b32 m0, s56
	s_addc_u32 s77, s35, 0
	s_add_i32 s67, s73, s42
	global_load_lds_dwordx4 v130, s[34:35]
	s_mov_b32 m0, s67
	s_nop 0
	global_load_lds_dwordx4 v134, s[76:77]
	s_add_i32 m0, s67, 0x2000
	s_nop 0
	global_load_lds_dwordx4 v130, s[76:77]
	s_mov_b32 m0, s25
	s_nop 0
	global_load_lds_dwordx4 v136, s[36:37]
	s_mov_b32 m0, s43
	s_nop 0
	global_load_lds_dwordx4 v132, s[36:37]
	s_waitcnt vmcnt(8)
	s_barrier
	s_waitcnt lgkmcnt(0)
	v_mfma_f32_16x16x32_bf16 v[62:65], v[172:175], v[204:207], v[62:65]
	v_mfma_f32_16x16x32_bf16 v[58:61], v[180:183], v[204:207], v[58:61]
	v_mfma_f32_16x16x32_bf16 v[46:49], v[172:175], v[212:215], v[46:49]
	v_mfma_f32_16x16x32_bf16 v[42:45], v[180:183], v[212:215], v[42:45]
	v_mfma_f32_16x16x32_bf16 v[30:33], v[172:175], v[220:223], v[30:33]
	v_mfma_f32_16x16x32_bf16 v[26:29], v[180:183], v[220:223], v[26:29]
	v_mfma_f32_16x16x32_bf16 v[14:17], v[172:175], v[228:231], v[14:17]
	v_mfma_f32_16x16x32_bf16 v[10:13], v[180:183], v[228:231], v[10:13]
	v_mfma_f32_16x16x32_bf16 v[62:65], v[176:179], v[208:211], v[62:65]
	v_mfma_f32_16x16x32_bf16 v[58:61], v[184:187], v[208:211], v[58:61]
	v_mfma_f32_16x16x32_bf16 v[46:49], v[176:179], v[216:219], v[46:49]
	v_mfma_f32_16x16x32_bf16 v[42:45], v[184:187], v[216:219], v[42:45]
	v_mfma_f32_16x16x32_bf16 v[30:33], v[176:179], v[224:227], v[30:33]
	v_mfma_f32_16x16x32_bf16 v[26:29], v[184:187], v[224:227], v[26:29]
	v_mfma_f32_16x16x32_bf16 v[14:17], v[176:179], v[232:235], v[14:17]
	v_mfma_f32_16x16x32_bf16 v[10:13], v[184:187], v[232:235], v[10:13]
	v_mfma_f32_16x16x32_bf16 v[54:57], v[188:191], v[204:207], v[54:57]
	v_mfma_f32_16x16x32_bf16 v[50:53], v[196:199], v[204:207], v[50:53]
	v_mfma_f32_16x16x32_bf16 v[38:41], v[188:191], v[212:215], v[38:41]
	v_mfma_f32_16x16x32_bf16 v[34:37], v[196:199], v[212:215], v[34:37]
	v_mfma_f32_16x16x32_bf16 v[22:25], v[188:191], v[220:223], v[22:25]
	v_mfma_f32_16x16x32_bf16 v[18:21], v[196:199], v[220:223], v[18:21]
	v_mfma_f32_16x16x32_bf16 v[6:9], v[188:191], v[228:231], v[6:9]
	v_mfma_f32_16x16x32_bf16 v[2:5], v[196:199], v[228:231], v[2:5]
	v_mfma_f32_16x16x32_bf16 v[54:57], v[192:195], v[208:211], v[54:57]
	v_mfma_f32_16x16x32_bf16 v[50:53], v[200:203], v[208:211], v[50:53]
	v_mfma_f32_16x16x32_bf16 v[38:41], v[192:195], v[216:219], v[38:41]
	v_mfma_f32_16x16x32_bf16 v[34:37], v[200:203], v[216:219], v[34:37]
	v_mfma_f32_16x16x32_bf16 v[22:25], v[192:195], v[224:227], v[22:25]
	v_mfma_f32_16x16x32_bf16 v[18:21], v[200:203], v[224:227], v[18:21]
	v_mfma_f32_16x16x32_bf16 v[6:9], v[192:195], v[232:235], v[6:9]
	v_mfma_f32_16x16x32_bf16 v[2:5], v[200:203], v[232:235], v[2:5]
	s_barrier
; #define PG8_STAGE(bufoff, gbase, voff) do { _Pragma("unroll") for (int _i = 0; _i < 2; ++_i) \
;         __builtin_amdgcn_global_load_lds((const unsigned*)((const char*)(gbase) + (voff)[_i]), (LAS unsigned*)(lds + (bufoff) + ldsw + _i * 8192), 16, 0, 0); } while (0)
; #define PG8_LDA(dst, b, h) do { _Pragma("unroll") for (int m = 0; m < 4; ++m) _Pragma("unroll") for (int k = 0; k < 2; ++k) dst[m][k] = *(const LAS bf16x8*)(lds + PG8_SA(b, h) + aoff + m * 2048 + k * 1024); } while (0)
; #define PG8_LDB(dst, b, h) do { _Pragma("unroll") for (int n = 0; n < 2; ++n) _Pragma("unroll") for (int k = 0; k < 2; ++k) dst[n][k] = *(const LAS bf16x8*)(lds + PG8_SB(b, h) + boff + n * 2048 + k * 1024); } while (0)
; #define PG8_MMA(ai, bj, At, Bt) do { __builtin_amdgcn_s_setprio(1); _Pragma("unroll") for (int m = 0; m < 4; ++m) _Pragma("unroll") for (int n = 0; n < 2; ++n) _Pragma("unroll") for (int k = 0; k < 2; ++k) \
;         acc[ai][bj][m][n] = __builtin_amdgcn_mfma_f32_16x16x32_bf16(Bt[n][k], At[m][k], acc[ai][bj][m][n], 0, 0, 0); __builtin_amdgcn_s_setprio(0); } while (0)
; #define PG8_WAIT_V(n) asm volatile("s_waitcnt vmcnt(" #n ")" ::: "memory")
; #define PG8_WAIT_L(n) asm volatile("s_waitcnt lgkmcnt(" #n ")" ::: "memory")
; #define PG8_BAR __builtin_amdgcn_s_barrier()
; #define PG8_SCHED __builtin_amdgcn_sched_barrier(0)
; template <class Epi, class Sched, bool ABLK = false, bool ALIGN_EPI = true, bool SP2 = true, bool BBLK = true>
; __device__ __forceinline__ void gemm_phase(LAS unsigned char* lds, const Gemm g, const Sched& S, const Epi& E) {
;     ...
;             PG8_LDB(B0, 1, 0); PG8_LDB(B1, 1, 1); PG8_SCHED; PG8_LDA(At, 1, 0); PG8_STAGE(PG8_SA(0, 1), a2 + hstepA, voffA);
;             PG8_WAIT_V(8); PG8_WAIT_L(0); PG8_BAR; PG8_MMA(0, 0, At, B0); PG8_MMA(0, 1, At, B1); PG8_BAR; PG8_SCHED;
;             PG8_LDA(At, 1, 1); PG8_STAGE(PG8_SB(1, 0), b3, voffB); PG8_STAGE(PG8_SB(1, 1), b3 + hstepB, voffB); PG8_STAGE(PG8_SA(1, 0), a3, voffA);
;             PG8_WAIT_V(8); PG8_WAIT_L(0); PG8_BAR; PG8_MMA(1, 0, At, B0); PG8_MMA(1, 1, At, B1); PG8_BAR; PG8_SCHED;
	v_add_u32_e32 v184, s60, v168
	v_add_u32_e32 v200, s61, v168
	ds_read_b128 v[172:175], v184
	ds_read_b128 v[176:179], v184 offset:1024
	ds_read_b128 v[180:183], v184 offset:2048
	ds_read_b128 v[184:187], v184 offset:3072
	ds_read_b128 v[188:191], v200
	ds_read_b128 v[192:195], v200 offset:1024
	ds_read_b128 v[196:199], v200 offset:2048
	ds_read_b128 v[200:203], v200 offset:3072
	s_add_u32 s36, s36, 0x80000
	s_addc_u32 s37, s37, 0
	s_mov_b32 m0, s44
	ds_read_b128 v[204:207], v171 offset:32768
	ds_read_b128 v[208:211], v171 offset:33792
	ds_read_b128 v[212:215], v171 offset:34816
	ds_read_b128 v[216:219], v171 offset:35840
	ds_read_b128 v[220:223], v171 offset:36864
	ds_read_b128 v[224:227], v171 offset:37888
	ds_read_b128 v[228:231], v171 offset:38912
	ds_read_b128 v[232:235], v171 offset:39936
	global_load_lds_dwordx4 v136, s[36:37]
	s_mov_b32 m0, s45
	s_nop 0
	global_load_lds_dwordx4 v132, s[36:37]
	s_waitcnt vmcnt(8)
	s_barrier
	s_waitcnt lgkmcnt(0)
	v_mfma_f32_16x16x32_bf16 v[126:129], v[172:175], v[204:207], v[126:129]
	v_mfma_f32_16x16x32_bf16 v[122:125], v[180:183], v[204:207], v[122:125]
	v_mfma_f32_16x16x32_bf16 v[110:113], v[172:175], v[212:215], v[110:113]
	v_mfma_f32_16x16x32_bf16 v[106:109], v[180:183], v[212:215], v[106:109]
	v_mfma_f32_16x16x32_bf16 v[94:97], v[172:175], v[220:223], v[94:97]
	v_mfma_f32_16x16x32_bf16 v[90:93], v[180:183], v[220:223], v[90:93]
	v_mfma_f32_16x16x32_bf16 v[78:81], v[172:175], v[228:231], v[78:81]
	v_mfma_f32_16x16x32_bf16 v[74:77], v[180:183], v[228:231], v[74:77]
	v_mfma_f32_16x16x32_bf16 v[126:129], v[176:179], v[208:211], v[126:129]
	v_mfma_f32_16x16x32_bf16 v[122:125], v[184:187], v[208:211], v[122:125]
	v_mfma_f32_16x16x32_bf16 v[110:113], v[176:179], v[216:219], v[110:113]
	v_mfma_f32_16x16x32_bf16 v[106:109], v[184:187], v[216:219], v[106:109]
	v_mfma_f32_16x16x32_bf16 v[94:97], v[176:179], v[224:227], v[94:97]
	v_mfma_f32_16x16x32_bf16 v[90:93], v[184:187], v[224:227], v[90:93]
	v_mfma_f32_16x16x32_bf16 v[78:81], v[176:179], v[232:235], v[78:81]
	v_mfma_f32_16x16x32_bf16 v[74:77], v[184:187], v[232:235], v[74:77]
	v_mfma_f32_16x16x32_bf16 v[118:121], v[188:191], v[204:207], v[118:121]
	v_mfma_f32_16x16x32_bf16 v[114:117], v[196:199], v[204:207], v[114:117]
	v_mfma_f32_16x16x32_bf16 v[102:105], v[188:191], v[212:215], v[102:105]
	v_mfma_f32_16x16x32_bf16 v[98:101], v[196:199], v[212:215], v[98:101]
	v_mfma_f32_16x16x32_bf16 v[86:89], v[188:191], v[220:223], v[86:89]
	v_mfma_f32_16x16x32_bf16 v[82:85], v[196:199], v[220:223], v[82:85]
	v_mfma_f32_16x16x32_bf16 v[70:73], v[188:191], v[228:231], v[70:73]
	v_mfma_f32_16x16x32_bf16 v[66:69], v[196:199], v[228:231], v[66:69]
	v_mfma_f32_16x16x32_bf16 v[118:121], v[192:195], v[208:211], v[118:121]
	v_mfma_f32_16x16x32_bf16 v[114:117], v[200:203], v[208:211], v[114:117]
	v_mfma_f32_16x16x32_bf16 v[102:105], v[192:195], v[216:219], v[102:105]
	v_mfma_f32_16x16x32_bf16 v[98:101], v[200:203], v[216:219], v[98:101]
	v_mfma_f32_16x16x32_bf16 v[86:89], v[192:195], v[224:227], v[86:89]
	v_mfma_f32_16x16x32_bf16 v[82:85], v[200:203], v[224:227], v[82:85]
	v_mfma_f32_16x16x32_bf16 v[70:73], v[192:195], v[232:235], v[70:73]
	v_mfma_f32_16x16x32_bf16 v[66:69], v[200:203], v[232:235], v[66:69]
	s_barrier
	s_add_u32 s36, s34, 0x8000
	s_addc_u32 s37, s35, 0
	s_add_i32 s67, s60, s42
	s_mov_b32 m0, s67
	ds_read_b128 v[204:207], v171 offset:49152
	ds_read_b128 v[208:211], v171 offset:50176
	ds_read_b128 v[212:215], v171 offset:51200
	ds_read_b128 v[216:219], v171 offset:52224
	ds_read_b128 v[220:223], v171 offset:53248
	ds_read_b128 v[224:227], v171 offset:54272
	ds_read_b128 v[228:231], v171 offset:55296
	ds_read_b128 v[232:235], v171 offset:56320
	global_load_lds_dwordx4 v134, s[36:37]
	s_add_i32 m0, s67, 0x2000
	s_add_u32 s34, s34, 0xc000
	v_lshl_add_u64 v[236:237], s[36:37], 0, v[130:131]
	s_addc_u32 s35, s35, 0
	s_add_i32 s36, s61, s42
	global_load_lds_dwordx4 v[236:237], off
	s_mov_b32 m0, s36
	s_nop 0
	global_load_lds_dwordx4 v134, s[34:35]
	s_add_i32 m0, s36, 0x2000
	s_nop 0
	global_load_lds_dwordx4 v130, s[34:35]
	s_mov_b32 m0, s48
	s_nop 0
	global_load_lds_dwordx4 v136, s[30:31]
	s_mov_b32 m0, s49
	s_nop 0
	global_load_lds_dwordx4 v132, s[30:31]
	s_waitcnt vmcnt(8)
	s_barrier
	s_waitcnt lgkmcnt(0)
	v_mfma_f32_16x16x32_bf16 v[62:65], v[172:175], v[204:207], v[62:65]
	v_mfma_f32_16x16x32_bf16 v[58:61], v[180:183], v[204:207], v[58:61]
	v_mfma_f32_16x16x32_bf16 v[46:49], v[172:175], v[212:215], v[46:49]
	v_mfma_f32_16x16x32_bf16 v[42:45], v[180:183], v[212:215], v[42:45]
	v_mfma_f32_16x16x32_bf16 v[30:33], v[172:175], v[220:223], v[30:33]
	v_mfma_f32_16x16x32_bf16 v[26:29], v[180:183], v[220:223], v[26:29]
	v_mfma_f32_16x16x32_bf16 v[14:17], v[172:175], v[228:231], v[14:17]
	v_mfma_f32_16x16x32_bf16 v[10:13], v[180:183], v[228:231], v[10:13]
	v_mfma_f32_16x16x32_bf16 v[62:65], v[176:179], v[208:211], v[62:65]
	v_mfma_f32_16x16x32_bf16 v[58:61], v[184:187], v[208:211], v[58:61]
	v_mfma_f32_16x16x32_bf16 v[46:49], v[176:179], v[216:219], v[46:49]
	v_mfma_f32_16x16x32_bf16 v[42:45], v[184:187], v[216:219], v[42:45]
	v_mfma_f32_16x16x32_bf16 v[30:33], v[176:179], v[224:227], v[30:33]
	v_mfma_f32_16x16x32_bf16 v[26:29], v[184:187], v[224:227], v[26:29]
	v_mfma_f32_16x16x32_bf16 v[14:17], v[176:179], v[232:235], v[14:17]
	v_mfma_f32_16x16x32_bf16 v[10:13], v[184:187], v[232:235], v[10:13]
	v_mfma_f32_16x16x32_bf16 v[54:57], v[188:191], v[204:207], v[54:57]
	v_mfma_f32_16x16x32_bf16 v[50:53], v[196:199], v[204:207], v[50:53]
	v_mfma_f32_16x16x32_bf16 v[38:41], v[188:191], v[212:215], v[38:41]
	v_mfma_f32_16x16x32_bf16 v[34:37], v[196:199], v[212:215], v[34:37]
	v_mfma_f32_16x16x32_bf16 v[22:25], v[188:191], v[220:223], v[22:25]
	v_mfma_f32_16x16x32_bf16 v[18:21], v[196:199], v[220:223], v[18:21]
	v_mfma_f32_16x16x32_bf16 v[6:9], v[188:191], v[228:231], v[6:9]
	v_mfma_f32_16x16x32_bf16 v[2:5], v[196:199], v[228:231], v[2:5]
	v_mfma_f32_16x16x32_bf16 v[54:57], v[192:195], v[208:211], v[54:57]
	v_mfma_f32_16x16x32_bf16 v[50:53], v[200:203], v[208:211], v[50:53]
	v_mfma_f32_16x16x32_bf16 v[38:41], v[192:195], v[216:219], v[38:41]
	v_mfma_f32_16x16x32_bf16 v[34:37], v[200:203], v[216:219], v[34:37]
	v_mfma_f32_16x16x32_bf16 v[22:25], v[192:195], v[224:227], v[22:25]
	v_mfma_f32_16x16x32_bf16 v[18:21], v[200:203], v[224:227], v[18:21]
	v_mfma_f32_16x16x32_bf16 v[6:9], v[192:195], v[232:235], v[6:9]
	v_mfma_f32_16x16x32_bf16 v[2:5], v[200:203], v[232:235], v[2:5]
	s_barrier
	s_add_i32 s66, s66, 2
	s_add_u32 s28, s28, 0x100
	s_addc_u32 s29, s29, 0
	s_add_u32 s64, s64, 0x10000
	s_addc_u32 s65, s65, 0
	s_cmp_gt_u32 s66, 29
	s_cbranch_scc0 .LBB0_1164
	s_and_b64 vcc, exec, s[6:7]
	s_cbranch_vccz .LBB0_1167
	s_barrier

; #define PG8_STAGE(bufoff, gbase, voff) do { _Pragma("unroll") for (int _i = 0; _i < 2; ++_i) \
;         __builtin_amdgcn_global_load_lds((const unsigned*)((const char*)(gbase) + (voff)[_i]), (LAS unsigned*)(lds + (bufoff) + ldsw + _i * 8192), 16, 0, 0); } while (0)
; #define PG8_LDA(dst, b, h) do { _Pragma("unroll") for (int m = 0; m < 4; ++m) _Pragma("unroll") for (int k = 0; k < 2; ++k) dst[m][k] = *(const LAS bf16x8*)(lds + PG8_SA(b, h) + aoff + m * 2048 + k * 1024); } while (0)
; #define PG8_LDB(dst, b, h) do { _Pragma("unroll") for (int n = 0; n < 2; ++n) _Pragma("unroll") for (int k = 0; k < 2; ++k) dst[n][k] = *(const LAS bf16x8*)(lds + PG8_SB(b, h) + boff + n * 2048 + k * 1024); } while (0)
; #define PG8_WAIT_V(n) asm volatile("s_waitcnt vmcnt(" #n ")" ::: "memory")
; #define PG8_WAIT_L(n) asm volatile("s_waitcnt lgkmcnt(" #n ")" ::: "memory")
; template <class Epi, class Sched, bool ABLK = false, bool ALIGN_EPI = true, bool SP2 = true, bool BBLK = true>
; __device__ __forceinline__ void gemm_phase(LAS unsigned char* lds, const Gemm g, const Sched& S, const Epi& E) {
;     ...
;         const bool has_next = S.next(ui + 1, nxt);
;         const int nt = cur.nt;
;         const char* nuA = has_next ? a_unit(nxt) : uA; const int ntbA = has_next ? nxt.k0 / BK : tbA; const char* nB = has_next ? (const char*)g.Bt + (size_t)nxt.pn * tstepB + b_k0(nxt.k0) : cB;
;         for (int t = 0; t < nt; t += 2) {
;             const bool last = (t == nt - 2);
;             const char* a1 = a_tile(uA, tbA + t + 1);
;             const char* a2 = last ? a_tile(nuA, ntbA) : a_tile(uA, tbA + t + 2); const char* b2 = last ? nB : cB + (size_t)(t + 2) * kstepB;
;             const char* a3 = last ? a_tile(nuA, ntbA + 1) : a_tile(uA, tbA + t + 3); const char* b3 = b2 + kstepB;
;             if (last && has_next) S.a_ready(nxt);
;             if constexpr (SP2) {
;             PG8_LDB(B0, 0, 0); PG8_LDB(B1, 0, 1); PG8_SCHED; PG8_LDA(At, 0, 0); PG8_STAGE(PG8_SA(1, 1), a1 + hstepA, voffA);
;             PG8_WAIT_V(8); PG8_WAIT_L(0); PG8_BAR; PG8_MMA(0, 0, At, B0); PG8_MMA(0, 1, At, B1); PG8_BAR; PG8_SCHED;
;             PG8_LDA(At, 0, 1); PG8_STAGE(PG8_SB(0, 0), b2, voffB); PG8_STAGE(PG8_SB(0, 1), b2 + hstepB, voffB); PG8_STAGE(PG8_SA(0, 0), a2, voffA);
;             PG8_WAIT_V(8); PG8_WAIT_L(0); PG8_BAR; PG8_MMA(1, 0, At, B0); PG8_MMA(1, 1, At, B1); PG8_BAR; PG8_SCHED;
.LBB0_1228:
	s_ashr_i32 s81, s80, 31
	s_andn2_b64 vcc, exec, s[4:5]
	s_lshl_b64 s[16:17], s[80:81], 22
	s_add_u32 s16, s1, s16
	s_addc_u32 s17, s33, s17
	s_and_b64 s[18:19], s[4:5], exec
	s_cselect_b32 s27, s17, s25
	s_cselect_b32 s46, s16, s24
	s_ashr_i32 s18, s0, 31
	s_lshr_b32 s18, s18, 26
	s_add_i32 s18, s0, s18
	s_ashr_i32 s18, s18, 6
	s_and_b64 s[20:21], s[4:5], exec
	s_cselect_b32 s28, s18, s26
	s_ashr_i32 s79, s78, 31
	s_lshl_b64 s[20:21], s[78:79], 22
	s_add_u32 s29, s30, s20
	s_addc_u32 s47, s31, s21
	s_ashr_i32 s19, s18, 31
	s_lshl_b64 s[20:21], s[18:19], 15
	s_add_u32 s20, s29, s20
	s_addc_u32 s21, s47, s21
	v_cndmask_b32_e64 v2, 0, 1, s[4:5]
	s_and_b64 s[4:5], s[4:5], exec
	s_cselect_b32 s4, s21, s23
	s_cselect_b32 s5, s20, s22
	s_ashr_i32 s29, s28, 31
	s_lshl_b64 s[28:29], s[28:29], 15
	s_add_u32 s19, s46, s28
	s_addc_u32 s46, s27, s29
	s_add_u32 s47, s19, 0x8000
	s_addc_u32 s48, s46, 0
	s_add_u32 s49, s22, 0x10000
	s_addc_u32 s50, s23, 0
	s_ashr_i32 s27, s26, 31
	v_cmp_ne_u32_e64 s[10:11], 1, v2
	s_lshl_b64 s[22:23], s[26:27], 15
	v_lshl_add_u64 v[2:3], s[24:25], 0, v[138:139]
	s_add_u32 s51, s24, s22
	v_lshl_add_u64 v[142:143], v[2:3], 0, s[22:23]
	v_lshl_add_u64 v[2:3], s[24:25], 0, v[140:141]
	s_addc_u32 s55, s25, s23
	v_lshl_add_u64 v[144:145], v[2:3], 0, s[22:23]
	s_lshl_b32 s22, s44, 15
	s_add_i32 s22, s22, 0xfff00000
	v_mov_b32_e32 v2, 0
	s_add_u32 s56, s22, 0xf0000
	s_mov_b32 s57, 0
	s_mov_b64 s[22:23], 0
	ds_read_b128 v[152:155], v149
	ds_read_b128 v[156:159], v149 offset:1024
	ds_read_b128 v[160:163], v149 offset:2048
	ds_read_b128 v[164:167], v149 offset:3072
	ds_read_b128 v[168:171], v150
	ds_read_b128 v[172:175], v150 offset:1024
	ds_read_b128 v[176:179], v150 offset:2048
	ds_read_b128 v[180:183], v150 offset:3072
	s_add_u32 s24, s51, s22
	s_addc_u32 s25, s55, s23
	s_add_u32 s28, s24, 0x10000
	s_addc_u32 s29, s25, 0
	s_add_i32 s57, s57, 2
	s_add_u32 s26, s49, s22
	s_addc_u32 s27, s50, s23
	s_add_u32 s24, s24, 0x18000
	s_addc_u32 s25, s25, 0
	s_cmp_eq_u32 s56, s22
	s_cselect_b32 s25, s48, s25
	s_cselect_b32 s24, s47, s24
	s_cselect_b32 s27, s4, s27
	s_cselect_b32 s26, s5, s26
	s_cselect_b32 s29, s46, s29
	s_cselect_b32 s28, s19, s28
	v_lshl_add_u64 v[216:217], v[142:143], 0, s[22:23]
	s_add_i32 m0, s35, 0xc000
	ds_read_b128 v[184:187], v151
	ds_read_b128 v[188:191], v151 offset:1024
	ds_read_b128 v[192:195], v151 offset:2048
	ds_read_b128 v[196:199], v151 offset:3072
	ds_read_b128 v[200:203], v151 offset:4096
	ds_read_b128 v[204:207], v151 offset:5120
	ds_read_b128 v[208:211], v151 offset:6144
	ds_read_b128 v[212:215], v151 offset:7168
	global_load_lds_dwordx4 v[216:217], off
	v_lshl_add_u64 v[216:217], v[144:145], 0, s[22:23]
	s_add_i32 m0, s35, 0xe000
	s_nop 0
	global_load_lds_dwordx4 v[216:217], off
	s_waitcnt vmcnt(8)
	s_barrier
	s_waitcnt lgkmcnt(0)
	v_mfma_f32_16x16x32_bf16 v[126:129], v[152:155], v[184:187], 0
	v_mfma_f32_16x16x32_bf16 v[122:125], v[160:163], v[184:187], 0
	v_mfma_f32_16x16x32_bf16 v[110:113], v[152:155], v[192:195], 0
	v_mfma_f32_16x16x32_bf16 v[106:109], v[160:163], v[192:195], 0
	v_mfma_f32_16x16x32_bf16 v[94:97], v[152:155], v[200:203], 0
	v_mfma_f32_16x16x32_bf16 v[90:93], v[160:163], v[200:203], 0
	v_mfma_f32_16x16x32_bf16 v[78:81], v[152:155], v[208:211], 0
	v_mfma_f32_16x16x32_bf16 v[74:77], v[160:163], v[208:211], 0
	v_mfma_f32_16x16x32_bf16 v[126:129], v[156:159], v[188:191], v[126:129]
	v_mfma_f32_16x16x32_bf16 v[122:125], v[164:167], v[188:191], v[122:125]
	v_mfma_f32_16x16x32_bf16 v[110:113], v[156:159], v[196:199], v[110:113]
	v_mfma_f32_16x16x32_bf16 v[106:109], v[164:167], v[196:199], v[106:109]
	v_mfma_f32_16x16x32_bf16 v[94:97], v[156:159], v[204:207], v[94:97]
	v_mfma_f32_16x16x32_bf16 v[90:93], v[164:167], v[204:207], v[90:93]
	v_mfma_f32_16x16x32_bf16 v[78:81], v[156:159], v[212:215], v[78:81]
	v_mfma_f32_16x16x32_bf16 v[74:77], v[164:167], v[212:215], v[74:77]
	v_mfma_f32_16x16x32_bf16 v[118:121], v[168:171], v[184:187], 0
	v_mfma_f32_16x16x32_bf16 v[114:117], v[176:179], v[184:187], 0
	v_mfma_f32_16x16x32_bf16 v[102:105], v[168:171], v[192:195], 0
	v_mfma_f32_16x16x32_bf16 v[98:101], v[176:179], v[192:195], 0
	v_mfma_f32_16x16x32_bf16 v[86:89], v[168:171], v[200:203], 0
	v_mfma_f32_16x16x32_bf16 v[82:85], v[176:179], v[200:203], 0
	v_mfma_f32_16x16x32_bf16 v[70:73], v[168:171], v[208:211], 0
	v_mfma_f32_16x16x32_bf16 v[66:69], v[176:179], v[208:211], 0
	v_mfma_f32_16x16x32_bf16 v[118:121], v[172:175], v[188:191], v[118:121]
	v_mfma_f32_16x16x32_bf16 v[114:117], v[180:183], v[188:191], v[114:117]
	v_mfma_f32_16x16x32_bf16 v[102:105], v[172:175], v[196:199], v[102:105]
	v_mfma_f32_16x16x32_bf16 v[98:101], v[180:183], v[196:199], v[98:101]
	v_mfma_f32_16x16x32_bf16 v[86:89], v[172:175], v[204:207], v[86:89]
	v_mfma_f32_16x16x32_bf16 v[82:85], v[180:183], v[204:207], v[82:85]
	v_mfma_f32_16x16x32_bf16 v[70:73], v[172:175], v[212:215], v[70:73]
	v_mfma_f32_16x16x32_bf16 v[66:69], v[180:183], v[212:215], v[66:69]
	s_barrier
	s_add_i32 s59, s72, s34
	s_mov_b32 m0, s59
	ds_read_b128 v[184:187], v151 offset:16384
	ds_read_b128 v[188:191], v151 offset:17408
	ds_read_b128 v[192:195], v151 offset:18432
	ds_read_b128 v[196:199], v151 offset:19456
	ds_read_b128 v[200:203], v151 offset:20480
	ds_read_b128 v[204:207], v151 offset:21504
	ds_read_b128 v[208:211], v151 offset:22528
	ds_read_b128 v[212:215], v151 offset:23552
	global_load_lds_dwordx4 v130, s[26:27]
	s_add_i32 m0, s59, 0x2000
	s_add_u32 s64, s26, 0x4000
	s_addc_u32 s65, s27, 0
	s_add_i32 s59, s73, s34
	global_load_lds_dwordx4 v132, s[26:27]
	s_mov_b32 m0, s59
	s_nop 0
	global_load_lds_dwordx4 v130, s[64:65]
	s_add_i32 m0, s59, 0x2000
	s_nop 0
	global_load_lds_dwordx4 v132, s[64:65]
	s_mov_b32 m0, s35
	s_nop 0
	global_load_lds_dwordx4 v130, s[28:29]
	s_mov_b32 m0, s36
	s_nop 0
	global_load_lds_dwordx4 v132, s[28:29]
	s_waitcnt vmcnt(8)
	s_barrier
; #define PG8_STAGE(bufoff, gbase, voff) do { _Pragma("unroll") for (int _i = 0; _i < 2; ++_i) \
;         __builtin_amdgcn_global_load_lds((const unsigned*)((const char*)(gbase) + (voff)[_i]), (LAS unsigned*)(lds + (bufoff) + ldsw + _i * 8192), 16, 0, 0); } while (0)
; #define PG8_LDA(dst, b, h) do { _Pragma("unroll") for (int m = 0; m < 4; ++m) _Pragma("unroll") for (int k = 0; k < 2; ++k) dst[m][k] = *(const LAS bf16x8*)(lds + PG8_SA(b, h) + aoff + m * 2048 + k * 1024); } while (0)
; #define PG8_LDB(dst, b, h) do { _Pragma("unroll") for (int n = 0; n < 2; ++n) _Pragma("unroll") for (int k = 0; k < 2; ++k) dst[n][k] = *(const LAS bf16x8*)(lds + PG8_SB(b, h) + boff + n * 2048 + k * 1024); } while (0)
; #define PG8_MMA(ai, bj, At, Bt) do { __builtin_amdgcn_s_setprio(1); _Pragma("unroll") for (int m = 0; m < 4; ++m) _Pragma("unroll") for (int n = 0; n < 2; ++n) _Pragma("unroll") for (int k = 0; k < 2; ++k) \
;         acc[ai][bj][m][n] = __builtin_amdgcn_mfma_f32_16x16x32_bf16(Bt[n][k], At[m][k], acc[ai][bj][m][n], 0, 0, 0); __builtin_amdgcn_s_setprio(0); } while (0)
; #define PG8_WAIT_V(n) asm volatile("s_waitcnt vmcnt(" #n ")" ::: "memory")
; #define PG8_WAIT_L(n) asm volatile("s_waitcnt lgkmcnt(" #n ")" ::: "memory")
; #define PG8_BAR __builtin_amdgcn_s_barrier()
; #define PG8_SCHED __builtin_amdgcn_sched_barrier(0)
; template <class Epi, class Sched, bool ABLK = false, bool ALIGN_EPI = true, bool SP2 = true, bool BBLK = true>
; __device__ __forceinline__ void gemm_phase(LAS unsigned char* lds, const Gemm g, const Sched& S, const Epi& E) {
;     ...
;             PG8_WAIT_V(8); PG8_WAIT_L(0); PG8_BAR; PG8_MMA(1, 0, At, B0); PG8_MMA(1, 1, At, B1); PG8_BAR; PG8_SCHED;
;             PG8_LDB(B0, 1, 0); PG8_LDB(B1, 1, 1); PG8_SCHED; PG8_LDA(At, 1, 0); PG8_STAGE(PG8_SA(0, 1), a2 + hstepA, voffA);
;             PG8_WAIT_V(8); PG8_WAIT_L(0); PG8_BAR; PG8_MMA(0, 0, At, B0); PG8_MMA(0, 1, At, B1); PG8_BAR; PG8_SCHED;
	s_waitcnt lgkmcnt(0)
	v_mfma_f32_16x16x32_bf16 v[62:65], v[152:155], v[184:187], 0
	v_mfma_f32_16x16x32_bf16 v[58:61], v[160:163], v[184:187], 0
	v_mfma_f32_16x16x32_bf16 v[46:49], v[152:155], v[192:195], 0
	v_mfma_f32_16x16x32_bf16 v[42:45], v[160:163], v[192:195], 0
	v_mfma_f32_16x16x32_bf16 v[30:33], v[152:155], v[200:203], 0
	v_mfma_f32_16x16x32_bf16 v[26:29], v[160:163], v[200:203], 0
	v_mfma_f32_16x16x32_bf16 v[14:17], v[152:155], v[208:211], 0
	v_mfma_f32_16x16x32_bf16 v[10:13], v[160:163], v[208:211], 0
	v_mfma_f32_16x16x32_bf16 v[62:65], v[156:159], v[188:191], v[62:65]
	v_mfma_f32_16x16x32_bf16 v[58:61], v[164:167], v[188:191], v[58:61]
	v_mfma_f32_16x16x32_bf16 v[46:49], v[156:159], v[196:199], v[46:49]
	v_mfma_f32_16x16x32_bf16 v[42:45], v[164:167], v[196:199], v[42:45]
	v_mfma_f32_16x16x32_bf16 v[30:33], v[156:159], v[204:207], v[30:33]
	v_mfma_f32_16x16x32_bf16 v[26:29], v[164:167], v[204:207], v[26:29]
	v_mfma_f32_16x16x32_bf16 v[14:17], v[156:159], v[212:215], v[14:17]
	v_mfma_f32_16x16x32_bf16 v[10:13], v[164:167], v[212:215], v[10:13]
	v_mfma_f32_16x16x32_bf16 v[54:57], v[168:171], v[184:187], 0
	v_mfma_f32_16x16x32_bf16 v[50:53], v[176:179], v[184:187], 0
	v_mfma_f32_16x16x32_bf16 v[38:41], v[168:171], v[192:195], 0
	v_mfma_f32_16x16x32_bf16 v[34:37], v[176:179], v[192:195], 0
	v_mfma_f32_16x16x32_bf16 v[22:25], v[168:171], v[200:203], 0
	v_mfma_f32_16x16x32_bf16 v[18:21], v[176:179], v[200:203], 0
	v_mfma_f32_16x16x32_bf16 v[6:9], v[168:171], v[208:211], 0
	v_mfma_f32_16x16x32_bf16 v[2:5], v[176:179], v[208:211], 0
	v_mfma_f32_16x16x32_bf16 v[54:57], v[172:175], v[188:191], v[54:57]
	v_mfma_f32_16x16x32_bf16 v[50:53], v[180:183], v[188:191], v[50:53]
	v_mfma_f32_16x16x32_bf16 v[38:41], v[172:175], v[196:199], v[38:41]
	v_mfma_f32_16x16x32_bf16 v[34:37], v[180:183], v[196:199], v[34:37]
	v_mfma_f32_16x16x32_bf16 v[22:25], v[172:175], v[204:207], v[22:25]
	v_mfma_f32_16x16x32_bf16 v[18:21], v[180:183], v[204:207], v[18:21]
	v_mfma_f32_16x16x32_bf16 v[6:9], v[172:175], v[212:215], v[6:9]
	v_mfma_f32_16x16x32_bf16 v[2:5], v[180:183], v[212:215], v[2:5]
	s_barrier
	v_add_u32_e32 v164, s60, v147
	v_add_u32_e32 v180, s61, v147
	ds_read_b128 v[152:155], v164
	ds_read_b128 v[156:159], v164 offset:1024
	ds_read_b128 v[160:163], v164 offset:2048
	ds_read_b128 v[164:167], v164 offset:3072
	ds_read_b128 v[168:171], v180
	ds_read_b128 v[172:175], v180 offset:1024
	ds_read_b128 v[176:179], v180 offset:2048
	ds_read_b128 v[180:183], v180 offset:3072
	s_add_u32 s28, s28, 0x4000
	s_addc_u32 s29, s29, 0
	s_mov_b32 m0, s37
	ds_read_b128 v[184:187], v151 offset:32768
	ds_read_b128 v[188:191], v151 offset:33792
	ds_read_b128 v[192:195], v151 offset:34816
	ds_read_b128 v[196:199], v151 offset:35840
	ds_read_b128 v[200:203], v151 offset:36864
	ds_read_b128 v[204:207], v151 offset:37888
	ds_read_b128 v[208:211], v151 offset:38912
	ds_read_b128 v[212:215], v151 offset:39936
	global_load_lds_dwordx4 v130, s[28:29]
	s_mov_b32 m0, s40
	s_nop 0
	global_load_lds_dwordx4 v132, s[28:29]
	s_waitcnt vmcnt(8)
	s_barrier
	s_waitcnt lgkmcnt(0)
	v_mfma_f32_16x16x32_bf16 v[126:129], v[152:155], v[184:187], v[126:129]
	v_mfma_f32_16x16x32_bf16 v[122:125], v[160:163], v[184:187], v[122:125]
	v_mfma_f32_16x16x32_bf16 v[110:113], v[152:155], v[192:195], v[110:113]
	v_mfma_f32_16x16x32_bf16 v[106:109], v[160:163], v[192:195], v[106:109]
	v_mfma_f32_16x16x32_bf16 v[94:97], v[152:155], v[200:203], v[94:97]
	v_mfma_f32_16x16x32_bf16 v[90:93], v[160:163], v[200:203], v[90:93]
	v_mfma_f32_16x16x32_bf16 v[78:81], v[152:155], v[208:211], v[78:81]
	v_mfma_f32_16x16x32_bf16 v[74:77], v[160:163], v[208:211], v[74:77]
	v_mfma_f32_16x16x32_bf16 v[126:129], v[156:159], v[188:191], v[126:129]
	v_mfma_f32_16x16x32_bf16 v[122:125], v[164:167], v[188:191], v[122:125]
	v_mfma_f32_16x16x32_bf16 v[110:113], v[156:159], v[196:199], v[110:113]
	v_mfma_f32_16x16x32_bf16 v[106:109], v[164:167], v[196:199], v[106:109]
	v_mfma_f32_16x16x32_bf16 v[94:97], v[156:159], v[204:207], v[94:97]
	v_mfma_f32_16x16x32_bf16 v[90:93], v[164:167], v[204:207], v[90:93]
	v_mfma_f32_16x16x32_bf16 v[78:81], v[156:159], v[212:215], v[78:81]
	v_mfma_f32_16x16x32_bf16 v[74:77], v[164:167], v[212:215], v[74:77]
	v_mfma_f32_16x16x32_bf16 v[118:121], v[168:171], v[184:187], v[118:121]
	v_mfma_f32_16x16x32_bf16 v[114:117], v[176:179], v[184:187], v[114:117]
	v_mfma_f32_16x16x32_bf16 v[102:105], v[168:171], v[192:195], v[102:105]
	v_mfma_f32_16x16x32_bf16 v[98:101], v[176:179], v[192:195], v[98:101]
	v_mfma_f32_16x16x32_bf16 v[86:89], v[168:171], v[200:203], v[86:89]
	v_mfma_f32_16x16x32_bf16 v[82:85], v[176:179], v[200:203], v[82:85]
	v_mfma_f32_16x16x32_bf16 v[70:73], v[168:171], v[208:211], v[70:73]
	v_mfma_f32_16x16x32_bf16 v[66:69], v[176:179], v[208:211], v[66:69]
	v_mfma_f32_16x16x32_bf16 v[118:121], v[172:175], v[188:191], v[118:121]
	v_mfma_f32_16x16x32_bf16 v[114:117], v[180:183], v[188:191], v[114:117]
	v_mfma_f32_16x16x32_bf16 v[102:105], v[172:175], v[196:199], v[102:105]
	v_mfma_f32_16x16x32_bf16 v[98:101], v[180:183], v[196:199], v[98:101]
	v_mfma_f32_16x16x32_bf16 v[86:89], v[172:175], v[204:207], v[86:89]
	v_mfma_f32_16x16x32_bf16 v[82:85], v[180:183], v[204:207], v[82:85]
	v_mfma_f32_16x16x32_bf16 v[70:73], v[172:175], v[212:215], v[70:73]
	v_mfma_f32_16x16x32_bf16 v[66:69], v[180:183], v[212:215], v[66:69]
	s_barrier
; #define PG8_STAGE(bufoff, gbase, voff) do { _Pragma("unroll") for (int _i = 0; _i < 2; ++_i) \
;         __builtin_amdgcn_global_load_lds((const unsigned*)((const char*)(gbase) + (voff)[_i]), (LAS unsigned*)(lds + (bufoff) + ldsw + _i * 8192), 16, 0, 0); } while (0)
; #define PG8_LDA(dst, b, h) do { _Pragma("unroll") for (int m = 0; m < 4; ++m) _Pragma("unroll") for (int k = 0; k < 2; ++k) dst[m][k] = *(const LAS bf16x8*)(lds + PG8_SA(b, h) + aoff + m * 2048 + k * 1024); } while (0)
; #define PG8_WAIT_V(n) asm volatile("s_waitcnt vmcnt(" #n ")" ::: "memory")
; #define PG8_WAIT_L(n) asm volatile("s_waitcnt lgkmcnt(" #n ")" ::: "memory")
; template <class Epi, class Sched, bool ABLK = false, bool ALIGN_EPI = true, bool SP2 = true, bool BBLK = true>
; __device__ __forceinline__ void gemm_phase(LAS unsigned char* lds, const Gemm g, const Sched& S, const Epi& E) {
;     ...
;         for (int t = 0; t < nt; t += 2) {
;             const bool last = (t == nt - 2);
;             const char* a1 = a_tile(uA, tbA + t + 1);
;             const char* a2 = last ? a_tile(nuA, ntbA) : a_tile(uA, tbA + t + 2); const char* b2 = last ? nB : cB + (size_t)(t + 2) * kstepB;
;             const char* a3 = last ? a_tile(nuA, ntbA + 1) : a_tile(uA, tbA + t + 3); const char* b3 = b2 + kstepB;
;             if (last && has_next) S.a_ready(nxt);
;             if constexpr (SP2) {
;             PG8_LDB(B0, 0, 0); PG8_LDB(B1, 0, 1); PG8_SCHED; PG8_LDA(At, 0, 0); PG8_STAGE(PG8_SA(1, 1), a1 + hstepA, voffA);
;             PG8_WAIT_V(8); PG8_WAIT_L(0); PG8_BAR; PG8_MMA(0, 0, At, B0); PG8_MMA(0, 1, At, B1); PG8_BAR; PG8_SCHED;
;             PG8_LDA(At, 0, 1); PG8_STAGE(PG8_SB(0, 0), b2, voffB); PG8_STAGE(PG8_SB(0, 1), b2 + hstepB, voffB); PG8_STAGE(PG8_SA(0, 0), a2, voffA);
;             PG8_WAIT_V(8); PG8_WAIT_L(0); PG8_BAR; PG8_MMA(1, 0, At, B0); PG8_MMA(1, 1, At, B1); PG8_BAR; PG8_SCHED;
;             PG8_LDB(B0, 1, 0); PG8_LDB(B1, 1, 1); PG8_SCHED; PG8_LDA(At, 1, 0); PG8_STAGE(PG8_SA(0, 1), a2 + hstepA, voffA);
;             PG8_WAIT_V(8); PG8_WAIT_L(0); PG8_BAR; PG8_MMA(0, 0, At, B0); PG8_MMA(0, 1, At, B1); PG8_BAR; PG8_SCHED;
;             PG8_LDA(At, 1, 1); PG8_STAGE(PG8_SB(1, 0), b3, voffB); PG8_STAGE(PG8_SB(1, 1), b3 + hstepB, voffB); PG8_STAGE(PG8_SA(1, 0), a3, voffA);
;             PG8_WAIT_V(8); PG8_WAIT_L(0); PG8_BAR; PG8_MMA(1, 0, At, B0); PG8_MMA(1, 1, At, B1); PG8_BAR; PG8_SCHED;
	s_add_u32 s28, s26, 0x8000
	s_addc_u32 s29, s27, 0
	s_add_i32 s59, s60, s34
	s_mov_b32 m0, s59
	ds_read_b128 v[184:187], v151 offset:49152
	ds_read_b128 v[188:191], v151 offset:50176
	ds_read_b128 v[192:195], v151 offset:51200
	ds_read_b128 v[196:199], v151 offset:52224
	ds_read_b128 v[200:203], v151 offset:53248
	ds_read_b128 v[204:207], v151 offset:54272
	ds_read_b128 v[208:211], v151 offset:55296
	ds_read_b128 v[212:215], v151 offset:56320
	global_load_lds_dwordx4 v130, s[28:29]
	s_add_i32 m0, s59, 0x2000
	s_add_u32 s26, s26, 0xc000
	v_lshl_add_u64 v[216:217], s[28:29], 0, v[132:133]
	s_addc_u32 s27, s27, 0
	s_add_i32 s28, s61, s34
	global_load_lds_dwordx4 v[216:217], off
	s_mov_b32 m0, s28
	s_nop 0
	global_load_lds_dwordx4 v130, s[26:27]
	s_add_i32 m0, s28, 0x2000
	s_nop 0
	global_load_lds_dwordx4 v132, s[26:27]
	s_mov_b32 m0, s41
	s_nop 0
	global_load_lds_dwordx4 v130, s[24:25]
	s_mov_b32 m0, s42
	s_nop 0
	global_load_lds_dwordx4 v132, s[24:25]
	s_waitcnt vmcnt(8)
	s_barrier
	s_waitcnt lgkmcnt(0)
	v_mfma_f32_16x16x32_bf16 v[62:65], v[152:155], v[184:187], v[62:65]
	v_mfma_f32_16x16x32_bf16 v[58:61], v[160:163], v[184:187], v[58:61]
	v_mfma_f32_16x16x32_bf16 v[46:49], v[152:155], v[192:195], v[46:49]
	v_mfma_f32_16x16x32_bf16 v[42:45], v[160:163], v[192:195], v[42:45]
	v_mfma_f32_16x16x32_bf16 v[30:33], v[152:155], v[200:203], v[30:33]
	v_mfma_f32_16x16x32_bf16 v[26:29], v[160:163], v[200:203], v[26:29]
	v_mfma_f32_16x16x32_bf16 v[14:17], v[152:155], v[208:211], v[14:17]
	v_mfma_f32_16x16x32_bf16 v[10:13], v[160:163], v[208:211], v[10:13]
	v_mfma_f32_16x16x32_bf16 v[62:65], v[156:159], v[188:191], v[62:65]
	v_mfma_f32_16x16x32_bf16 v[58:61], v[164:167], v[188:191], v[58:61]
	v_mfma_f32_16x16x32_bf16 v[46:49], v[156:159], v[196:199], v[46:49]
	v_mfma_f32_16x16x32_bf16 v[42:45], v[164:167], v[196:199], v[42:45]
	v_mfma_f32_16x16x32_bf16 v[30:33], v[156:159], v[204:207], v[30:33]
	v_mfma_f32_16x16x32_bf16 v[26:29], v[164:167], v[204:207], v[26:29]
	v_mfma_f32_16x16x32_bf16 v[14:17], v[156:159], v[212:215], v[14:17]
	v_mfma_f32_16x16x32_bf16 v[10:13], v[164:167], v[212:215], v[10:13]
	v_mfma_f32_16x16x32_bf16 v[54:57], v[168:171], v[184:187], v[54:57]
	v_mfma_f32_16x16x32_bf16 v[50:53], v[176:179], v[184:187], v[50:53]
	v_mfma_f32_16x16x32_bf16 v[38:41], v[168:171], v[192:195], v[38:41]
	v_mfma_f32_16x16x32_bf16 v[34:37], v[176:179], v[192:195], v[34:37]
	v_mfma_f32_16x16x32_bf16 v[22:25], v[168:171], v[200:203], v[22:25]
	v_mfma_f32_16x16x32_bf16 v[18:21], v[176:179], v[200:203], v[18:21]
	v_mfma_f32_16x16x32_bf16 v[6:9], v[168:171], v[208:211], v[6:9]
	v_mfma_f32_16x16x32_bf16 v[2:5], v[176:179], v[208:211], v[2:5]
	v_mfma_f32_16x16x32_bf16 v[54:57], v[172:175], v[188:191], v[54:57]
	v_mfma_f32_16x16x32_bf16 v[50:53], v[180:183], v[188:191], v[50:53]
	v_mfma_f32_16x16x32_bf16 v[38:41], v[172:175], v[196:199], v[38:41]
	v_mfma_f32_16x16x32_bf16 v[34:37], v[180:183], v[196:199], v[34:37]
	v_mfma_f32_16x16x32_bf16 v[22:25], v[172:175], v[204:207], v[22:25]
	v_mfma_f32_16x16x32_bf16 v[18:21], v[180:183], v[204:207], v[18:21]
	v_mfma_f32_16x16x32_bf16 v[6:9], v[172:175], v[212:215], v[6:9]
	v_mfma_f32_16x16x32_bf16 v[2:5], v[180:183], v[212:215], v[2:5]
	s_barrier
	s_add_u32 s22, s22, 0x10000
	s_addc_u32 s23, s23, 0
	s_cmp_ge_u32 s57, s44
.LBB0_1229:
	ds_read_b128 v[152:155], v149
	ds_read_b128 v[156:159], v149 offset:1024
	ds_read_b128 v[160:163], v149 offset:2048
	ds_read_b128 v[164:167], v149 offset:3072
	ds_read_b128 v[168:171], v150
	ds_read_b128 v[172:175], v150 offset:1024
	ds_read_b128 v[176:179], v150 offset:2048
	ds_read_b128 v[180:183], v150 offset:3072
	s_add_u32 s24, s51, s22
	s_addc_u32 s25, s55, s23
	s_add_u32 s28, s24, 0x10000
	s_addc_u32 s29, s25, 0
	s_add_i32 s57, s57, 2
	s_add_u32 s26, s49, s22
	s_addc_u32 s27, s50, s23
	s_add_u32 s24, s24, 0x18000
	s_addc_u32 s25, s25, 0
	s_cmp_eq_u32 s56, s22
	s_cselect_b32 s25, s48, s25
	s_cselect_b32 s24, s47, s24
	s_cselect_b32 s27, s4, s27
	s_cselect_b32 s26, s5, s26
	s_cselect_b32 s29, s46, s29
	s_cselect_b32 s28, s19, s28
	v_lshl_add_u64 v[216:217], v[142:143], 0, s[22:23]
	s_add_i32 m0, s35, 0xc000
	ds_read_b128 v[184:187], v151
	ds_read_b128 v[188:191], v151 offset:1024
	ds_read_b128 v[192:195], v151 offset:2048
	ds_read_b128 v[196:199], v151 offset:3072
	ds_read_b128 v[200:203], v151 offset:4096
	ds_read_b128 v[204:207], v151 offset:5120
	ds_read_b128 v[208:211], v151 offset:6144
	ds_read_b128 v[212:215], v151 offset:7168
	global_load_lds_dwordx4 v[216:217], off
	v_lshl_add_u64 v[216:217], v[144:145], 0, s[22:23]
	s_add_i32 m0, s35, 0xe000
	s_nop 0
	global_load_lds_dwordx4 v[216:217], off
	s_waitcnt vmcnt(8)
	s_barrier
; #define PG8_STAGE(bufoff, gbase, voff) do { _Pragma("unroll") for (int _i = 0; _i < 2; ++_i) \
;         __builtin_amdgcn_global_load_lds((const unsigned*)((const char*)(gbase) + (voff)[_i]), (LAS unsigned*)(lds + (bufoff) + ldsw + _i * 8192), 16, 0, 0); } while (0)
; #define PG8_LDA(dst, b, h) do { _Pragma("unroll") for (int m = 0; m < 4; ++m) _Pragma("unroll") for (int k = 0; k < 2; ++k) dst[m][k] = *(const LAS bf16x8*)(lds + PG8_SA(b, h) + aoff + m * 2048 + k * 1024); } while (0)
; #define PG8_MMA(ai, bj, At, Bt) do { __builtin_amdgcn_s_setprio(1); _Pragma("unroll") for (int m = 0; m < 4; ++m) _Pragma("unroll") for (int n = 0; n < 2; ++n) _Pragma("unroll") for (int k = 0; k < 2; ++k) \
;         acc[ai][bj][m][n] = __builtin_amdgcn_mfma_f32_16x16x32_bf16(Bt[n][k], At[m][k], acc[ai][bj][m][n], 0, 0, 0); __builtin_amdgcn_s_setprio(0); } while (0)
; #define PG8_WAIT_V(n) asm volatile("s_waitcnt vmcnt(" #n ")" ::: "memory")
; #define PG8_WAIT_L(n) asm volatile("s_waitcnt lgkmcnt(" #n ")" ::: "memory")
; #define PG8_BAR __builtin_amdgcn_s_barrier()
; #define PG8_SCHED __builtin_amdgcn_sched_barrier(0)
; template <class Epi, class Sched, bool ABLK = false, bool ALIGN_EPI = true, bool SP2 = true, bool BBLK = true>
; __device__ __forceinline__ void gemm_phase(LAS unsigned char* lds, const Gemm g, const Sched& S, const Epi& E) {
;     ...
;             PG8_WAIT_V(8); PG8_WAIT_L(0); PG8_BAR; PG8_MMA(0, 0, At, B0); PG8_MMA(0, 1, At, B1); PG8_BAR; PG8_SCHED;
;             PG8_LDA(At, 0, 1); PG8_STAGE(PG8_SB(0, 0), b2, voffB); PG8_STAGE(PG8_SB(0, 1), b2 + hstepB, voffB); PG8_STAGE(PG8_SA(0, 0), a2, voffA);
;             PG8_WAIT_V(8); PG8_WAIT_L(0); PG8_BAR; PG8_MMA(1, 0, At, B0); PG8_MMA(1, 1, At, B1); PG8_BAR; PG8_SCHED;
	s_waitcnt lgkmcnt(0)
	v_mfma_f32_16x16x32_bf16 v[126:129], v[152:155], v[184:187], v[126:129]
	v_mfma_f32_16x16x32_bf16 v[122:125], v[160:163], v[184:187], v[122:125]
	v_mfma_f32_16x16x32_bf16 v[110:113], v[152:155], v[192:195], v[110:113]
	v_mfma_f32_16x16x32_bf16 v[106:109], v[160:163], v[192:195], v[106:109]
	v_mfma_f32_16x16x32_bf16 v[94:97], v[152:155], v[200:203], v[94:97]
	v_mfma_f32_16x16x32_bf16 v[90:93], v[160:163], v[200:203], v[90:93]
	v_mfma_f32_16x16x32_bf16 v[78:81], v[152:155], v[208:211], v[78:81]
	v_mfma_f32_16x16x32_bf16 v[74:77], v[160:163], v[208:211], v[74:77]
	v_mfma_f32_16x16x32_bf16 v[126:129], v[156:159], v[188:191], v[126:129]
	v_mfma_f32_16x16x32_bf16 v[122:125], v[164:167], v[188:191], v[122:125]
	v_mfma_f32_16x16x32_bf16 v[110:113], v[156:159], v[196:199], v[110:113]
	v_mfma_f32_16x16x32_bf16 v[106:109], v[164:167], v[196:199], v[106:109]
	v_mfma_f32_16x16x32_bf16 v[94:97], v[156:159], v[204:207], v[94:97]
	v_mfma_f32_16x16x32_bf16 v[90:93], v[164:167], v[204:207], v[90:93]
	v_mfma_f32_16x16x32_bf16 v[78:81], v[156:159], v[212:215], v[78:81]
	v_mfma_f32_16x16x32_bf16 v[74:77], v[164:167], v[212:215], v[74:77]
	v_mfma_f32_16x16x32_bf16 v[118:121], v[168:171], v[184:187], v[118:121]
	v_mfma_f32_16x16x32_bf16 v[114:117], v[176:179], v[184:187], v[114:117]
	v_mfma_f32_16x16x32_bf16 v[102:105], v[168:171], v[192:195], v[102:105]
	v_mfma_f32_16x16x32_bf16 v[98:101], v[176:179], v[192:195], v[98:101]
	v_mfma_f32_16x16x32_bf16 v[86:89], v[168:171], v[200:203], v[86:89]
	v_mfma_f32_16x16x32_bf16 v[82:85], v[176:179], v[200:203], v[82:85]
	v_mfma_f32_16x16x32_bf16 v[70:73], v[168:171], v[208:211], v[70:73]
	v_mfma_f32_16x16x32_bf16 v[66:69], v[176:179], v[208:211], v[66:69]
	v_mfma_f32_16x16x32_bf16 v[118:121], v[172:175], v[188:191], v[118:121]
	v_mfma_f32_16x16x32_bf16 v[114:117], v[180:183], v[188:191], v[114:117]
	v_mfma_f32_16x16x32_bf16 v[102:105], v[172:175], v[196:199], v[102:105]
	v_mfma_f32_16x16x32_bf16 v[98:101], v[180:183], v[196:199], v[98:101]
	v_mfma_f32_16x16x32_bf16 v[86:89], v[172:175], v[204:207], v[86:89]
	v_mfma_f32_16x16x32_bf16 v[82:85], v[180:183], v[204:207], v[82:85]
	v_mfma_f32_16x16x32_bf16 v[70:73], v[172:175], v[212:215], v[70:73]
	v_mfma_f32_16x16x32_bf16 v[66:69], v[180:183], v[212:215], v[66:69]
	s_barrier
	s_add_i32 s59, s72, s34
	s_mov_b32 m0, s59
	ds_read_b128 v[184:187], v151 offset:16384
	ds_read_b128 v[188:191], v151 offset:17408
	ds_read_b128 v[192:195], v151 offset:18432
	ds_read_b128 v[196:199], v151 offset:19456
	ds_read_b128 v[200:203], v151 offset:20480
	ds_read_b128 v[204:207], v151 offset:21504
	ds_read_b128 v[208:211], v151 offset:22528
	ds_read_b128 v[212:215], v151 offset:23552
	global_load_lds_dwordx4 v130, s[26:27]
	s_add_i32 m0, s59, 0x2000
	s_add_u32 s64, s26, 0x4000
	s_addc_u32 s65, s27, 0
	s_add_i32 s59, s73, s34
	global_load_lds_dwordx4 v132, s[26:27]
	s_mov_b32 m0, s59
	s_nop 0
	global_load_lds_dwordx4 v130, s[64:65]
	s_add_i32 m0, s59, 0x2000
	s_nop 0
	global_load_lds_dwordx4 v132, s[64:65]
	s_mov_b32 m0, s35
	s_nop 0
	global_load_lds_dwordx4 v130, s[28:29]
	s_mov_b32 m0, s36
	s_nop 0
	global_load_lds_dwordx4 v132, s[28:29]
	s_waitcnt vmcnt(8)
	s_barrier
	s_waitcnt lgkmcnt(0)
	v_mfma_f32_16x16x32_bf16 v[62:65], v[152:155], v[184:187], v[62:65]
	v_mfma_f32_16x16x32_bf16 v[58:61], v[160:163], v[184:187], v[58:61]
	v_mfma_f32_16x16x32_bf16 v[46:49], v[152:155], v[192:195], v[46:49]
	v_mfma_f32_16x16x32_bf16 v[42:45], v[160:163], v[192:195], v[42:45]
	v_mfma_f32_16x16x32_bf16 v[30:33], v[152:155], v[200:203], v[30:33]
	v_mfma_f32_16x16x32_bf16 v[26:29], v[160:163], v[200:203], v[26:29]
	v_mfma_f32_16x16x32_bf16 v[14:17], v[152:155], v[208:211], v[14:17]
	v_mfma_f32_16x16x32_bf16 v[10:13], v[160:163], v[208:211], v[10:13]
	v_mfma_f32_16x16x32_bf16 v[62:65], v[156:159], v[188:191], v[62:65]
	v_mfma_f32_16x16x32_bf16 v[58:61], v[164:167], v[188:191], v[58:61]
	v_mfma_f32_16x16x32_bf16 v[46:49], v[156:159], v[196:199], v[46:49]
	v_mfma_f32_16x16x32_bf16 v[42:45], v[164:167], v[196:199], v[42:45]
	v_mfma_f32_16x16x32_bf16 v[30:33], v[156:159], v[204:207], v[30:33]
	v_mfma_f32_16x16x32_bf16 v[26:29], v[164:167], v[204:207], v[26:29]
	v_mfma_f32_16x16x32_bf16 v[14:17], v[156:159], v[212:215], v[14:17]
	v_mfma_f32_16x16x32_bf16 v[10:13], v[164:167], v[212:215], v[10:13]
	v_mfma_f32_16x16x32_bf16 v[54:57], v[168:171], v[184:187], v[54:57]
	v_mfma_f32_16x16x32_bf16 v[50:53], v[176:179], v[184:187], v[50:53]
	v_mfma_f32_16x16x32_bf16 v[38:41], v[168:171], v[192:195], v[38:41]
	v_mfma_f32_16x16x32_bf16 v[34:37], v[176:179], v[192:195], v[34:37]
	v_mfma_f32_16x16x32_bf16 v[22:25], v[168:171], v[200:203], v[22:25]
	v_mfma_f32_16x16x32_bf16 v[18:21], v[176:179], v[200:203], v[18:21]
	v_mfma_f32_16x16x32_bf16 v[6:9], v[168:171], v[208:211], v[6:9]
	v_mfma_f32_16x16x32_bf16 v[2:5], v[176:179], v[208:211], v[2:5]
	v_mfma_f32_16x16x32_bf16 v[54:57], v[172:175], v[188:191], v[54:57]
	v_mfma_f32_16x16x32_bf16 v[50:53], v[180:183], v[188:191], v[50:53]
	v_mfma_f32_16x16x32_bf16 v[38:41], v[172:175], v[196:199], v[38:41]
	v_mfma_f32_16x16x32_bf16 v[34:37], v[180:183], v[196:199], v[34:37]
	v_mfma_f32_16x16x32_bf16 v[22:25], v[172:175], v[204:207], v[22:25]
	v_mfma_f32_16x16x32_bf16 v[18:21], v[180:183], v[204:207], v[18:21]
	v_mfma_f32_16x16x32_bf16 v[6:9], v[172:175], v[212:215], v[6:9]
	v_mfma_f32_16x16x32_bf16 v[2:5], v[180:183], v[212:215], v[2:5]
	s_barrier
; #define PG8_STAGE(bufoff, gbase, voff) do { _Pragma("unroll") for (int _i = 0; _i < 2; ++_i) \
;         __builtin_amdgcn_global_load_lds((const unsigned*)((const char*)(gbase) + (voff)[_i]), (LAS unsigned*)(lds + (bufoff) + ldsw + _i * 8192), 16, 0, 0); } while (0)
; #define PG8_LDA(dst, b, h) do { _Pragma("unroll") for (int m = 0; m < 4; ++m) _Pragma("unroll") for (int k = 0; k < 2; ++k) dst[m][k] = *(const LAS bf16x8*)(lds + PG8_SA(b, h) + aoff + m * 2048 + k * 1024); } while (0)
; #define PG8_LDB(dst, b, h) do { _Pragma("unroll") for (int n = 0; n < 2; ++n) _Pragma("unroll") for (int k = 0; k < 2; ++k) dst[n][k] = *(const LAS bf16x8*)(lds + PG8_SB(b, h) + boff + n * 2048 + k * 1024); } while (0)
; #define PG8_MMA(ai, bj, At, Bt) do { __builtin_amdgcn_s_setprio(1); _Pragma("unroll") for (int m = 0; m < 4; ++m) _Pragma("unroll") for (int n = 0; n < 2; ++n) _Pragma("unroll") for (int k = 0; k < 2; ++k) \
;         acc[ai][bj][m][n] = __builtin_amdgcn_mfma_f32_16x16x32_bf16(Bt[n][k], At[m][k], acc[ai][bj][m][n], 0, 0, 0); __builtin_amdgcn_s_setprio(0); } while (0)
; #define PG8_WAIT_V(n) asm volatile("s_waitcnt vmcnt(" #n ")" ::: "memory")
; #define PG8_WAIT_L(n) asm volatile("s_waitcnt lgkmcnt(" #n ")" ::: "memory")
; #define PG8_BAR __builtin_amdgcn_s_barrier()
; #define PG8_SCHED __builtin_amdgcn_sched_barrier(0)
; template <class Epi, class Sched, bool ABLK = false, bool ALIGN_EPI = true, bool SP2 = true, bool BBLK = true>
; __device__ __forceinline__ void gemm_phase(LAS unsigned char* lds, const Gemm g, const Sched& S, const Epi& E) {
;     ...
;             PG8_LDB(B0, 1, 0); PG8_LDB(B1, 1, 1); PG8_SCHED; PG8_LDA(At, 1, 0); PG8_STAGE(PG8_SA(0, 1), a2 + hstepA, voffA);
;             PG8_WAIT_V(8); PG8_WAIT_L(0); PG8_BAR; PG8_MMA(0, 0, At, B0); PG8_MMA(0, 1, At, B1); PG8_BAR; PG8_SCHED;
;             PG8_LDA(At, 1, 1); PG8_STAGE(PG8_SB(1, 0), b3, voffB); PG8_STAGE(PG8_SB(1, 1), b3 + hstepB, voffB); PG8_STAGE(PG8_SA(1, 0), a3, voffA);
;             PG8_WAIT_V(8); PG8_WAIT_L(0); PG8_BAR; PG8_MMA(1, 0, At, B0); PG8_MMA(1, 1, At, B1); PG8_BAR; PG8_SCHED;
	v_add_u32_e32 v164, s60, v147
	v_add_u32_e32 v180, s61, v147
	ds_read_b128 v[152:155], v164
	ds_read_b128 v[156:159], v164 offset:1024
	ds_read_b128 v[160:163], v164 offset:2048
	ds_read_b128 v[164:167], v164 offset:3072
	ds_read_b128 v[168:171], v180
	ds_read_b128 v[172:175], v180 offset:1024
	ds_read_b128 v[176:179], v180 offset:2048
	ds_read_b128 v[180:183], v180 offset:3072
	s_add_u32 s28, s28, 0x4000
	s_addc_u32 s29, s29, 0
	s_mov_b32 m0, s37
	ds_read_b128 v[184:187], v151 offset:32768
	ds_read_b128 v[188:191], v151 offset:33792
	ds_read_b128 v[192:195], v151 offset:34816
	ds_read_b128 v[196:199], v151 offset:35840
	ds_read_b128 v[200:203], v151 offset:36864
	ds_read_b128 v[204:207], v151 offset:37888
	ds_read_b128 v[208:211], v151 offset:38912
	ds_read_b128 v[212:215], v151 offset:39936
	global_load_lds_dwordx4 v130, s[28:29]
	s_mov_b32 m0, s40
	s_nop 0
	global_load_lds_dwordx4 v132, s[28:29]
	s_waitcnt vmcnt(8)
	s_barrier
	s_waitcnt lgkmcnt(0)
	v_mfma_f32_16x16x32_bf16 v[126:129], v[152:155], v[184:187], v[126:129]
	v_mfma_f32_16x16x32_bf16 v[122:125], v[160:163], v[184:187], v[122:125]
	v_mfma_f32_16x16x32_bf16 v[110:113], v[152:155], v[192:195], v[110:113]
	v_mfma_f32_16x16x32_bf16 v[106:109], v[160:163], v[192:195], v[106:109]
	v_mfma_f32_16x16x32_bf16 v[94:97], v[152:155], v[200:203], v[94:97]
	v_mfma_f32_16x16x32_bf16 v[90:93], v[160:163], v[200:203], v[90:93]
	v_mfma_f32_16x16x32_bf16 v[78:81], v[152:155], v[208:211], v[78:81]
	v_mfma_f32_16x16x32_bf16 v[74:77], v[160:163], v[208:211], v[74:77]
	v_mfma_f32_16x16x32_bf16 v[126:129], v[156:159], v[188:191], v[126:129]
	v_mfma_f32_16x16x32_bf16 v[122:125], v[164:167], v[188:191], v[122:125]
	v_mfma_f32_16x16x32_bf16 v[110:113], v[156:159], v[196:199], v[110:113]
	v_mfma_f32_16x16x32_bf16 v[106:109], v[164:167], v[196:199], v[106:109]
	v_mfma_f32_16x16x32_bf16 v[94:97], v[156:159], v[204:207], v[94:97]
	v_mfma_f32_16x16x32_bf16 v[90:93], v[164:167], v[204:207], v[90:93]
	v_mfma_f32_16x16x32_bf16 v[78:81], v[156:159], v[212:215], v[78:81]
	v_mfma_f32_16x16x32_bf16 v[74:77], v[164:167], v[212:215], v[74:77]
	v_mfma_f32_16x16x32_bf16 v[118:121], v[168:171], v[184:187], v[118:121]
	v_mfma_f32_16x16x32_bf16 v[114:117], v[176:179], v[184:187], v[114:117]
	v_mfma_f32_16x16x32_bf16 v[102:105], v[168:171], v[192:195], v[102:105]
	v_mfma_f32_16x16x32_bf16 v[98:101], v[176:179], v[192:195], v[98:101]
	v_mfma_f32_16x16x32_bf16 v[86:89], v[168:171], v[200:203], v[86:89]
	v_mfma_f32_16x16x32_bf16 v[82:85], v[176:179], v[200:203], v[82:85]
	v_mfma_f32_16x16x32_bf16 v[70:73], v[168:171], v[208:211], v[70:73]
	v_mfma_f32_16x16x32_bf16 v[66:69], v[176:179], v[208:211], v[66:69]
	v_mfma_f32_16x16x32_bf16 v[118:121], v[172:175], v[188:191], v[118:121]
	v_mfma_f32_16x16x32_bf16 v[114:117], v[180:183], v[188:191], v[114:117]
	v_mfma_f32_16x16x32_bf16 v[102:105], v[172:175], v[196:199], v[102:105]
	v_mfma_f32_16x16x32_bf16 v[98:101], v[180:183], v[196:199], v[98:101]
	v_mfma_f32_16x16x32_bf16 v[86:89], v[172:175], v[204:207], v[86:89]
	v_mfma_f32_16x16x32_bf16 v[82:85], v[180:183], v[204:207], v[82:85]
	v_mfma_f32_16x16x32_bf16 v[70:73], v[172:175], v[212:215], v[70:73]
	v_mfma_f32_16x16x32_bf16 v[66:69], v[180:183], v[212:215], v[66:69]
	s_barrier
	s_add_u32 s28, s26, 0x8000
	s_addc_u32 s29, s27, 0
	s_add_i32 s59, s60, s34
	s_mov_b32 m0, s59
	ds_read_b128 v[184:187], v151 offset:49152
	ds_read_b128 v[188:191], v151 offset:50176
	ds_read_b128 v[192:195], v151 offset:51200
	ds_read_b128 v[196:199], v151 offset:52224
	ds_read_b128 v[200:203], v151 offset:53248
	ds_read_b128 v[204:207], v151 offset:54272
	ds_read_b128 v[208:211], v151 offset:55296
	ds_read_b128 v[212:215], v151 offset:56320
	global_load_lds_dwordx4 v130, s[28:29]
	s_add_i32 m0, s59, 0x2000
	s_add_u32 s26, s26, 0xc000
	v_lshl_add_u64 v[216:217], s[28:29], 0, v[132:133]
	s_addc_u32 s27, s27, 0
	s_add_i32 s28, s61, s34
	global_load_lds_dwordx4 v[216:217], off
	s_mov_b32 m0, s28
	s_nop 0
	global_load_lds_dwordx4 v130, s[26:27]
	s_add_i32 m0, s28, 0x2000
	s_nop 0
	global_load_lds_dwordx4 v132, s[26:27]
	s_mov_b32 m0, s41
	s_nop 0
	global_load_lds_dwordx4 v130, s[24:25]
	s_mov_b32 m0, s42
	s_nop 0
	global_load_lds_dwordx4 v132, s[24:25]
	s_waitcnt vmcnt(8)
	s_barrier
	s_waitcnt lgkmcnt(0)
	v_mfma_f32_16x16x32_bf16 v[62:65], v[152:155], v[184:187], v[62:65]
	v_mfma_f32_16x16x32_bf16 v[58:61], v[160:163], v[184:187], v[58:61]
	v_mfma_f32_16x16x32_bf16 v[46:49], v[152:155], v[192:195], v[46:49]
	v_mfma_f32_16x16x32_bf16 v[42:45], v[160:163], v[192:195], v[42:45]
	v_mfma_f32_16x16x32_bf16 v[30:33], v[152:155], v[200:203], v[30:33]
	v_mfma_f32_16x16x32_bf16 v[26:29], v[160:163], v[200:203], v[26:29]
	v_mfma_f32_16x16x32_bf16 v[14:17], v[152:155], v[208:211], v[14:17]
	v_mfma_f32_16x16x32_bf16 v[10:13], v[160:163], v[208:211], v[10:13]
	v_mfma_f32_16x16x32_bf16 v[62:65], v[156:159], v[188:191], v[62:65]
	v_mfma_f32_16x16x32_bf16 v[58:61], v[164:167], v[188:191], v[58:61]
	v_mfma_f32_16x16x32_bf16 v[46:49], v[156:159], v[196:199], v[46:49]
	v_mfma_f32_16x16x32_bf16 v[42:45], v[164:167], v[196:199], v[42:45]
	v_mfma_f32_16x16x32_bf16 v[30:33], v[156:159], v[204:207], v[30:33]
	v_mfma_f32_16x16x32_bf16 v[26:29], v[164:167], v[204:207], v[26:29]
	v_mfma_f32_16x16x32_bf16 v[14:17], v[156:159], v[212:215], v[14:17]
	v_mfma_f32_16x16x32_bf16 v[10:13], v[164:167], v[212:215], v[10:13]
	v_mfma_f32_16x16x32_bf16 v[54:57], v[168:171], v[184:187], v[54:57]
	v_mfma_f32_16x16x32_bf16 v[50:53], v[176:179], v[184:187], v[50:53]
	v_mfma_f32_16x16x32_bf16 v[38:41], v[168:171], v[192:195], v[38:41]
	v_mfma_f32_16x16x32_bf16 v[34:37], v[176:179], v[192:195], v[34:37]
	v_mfma_f32_16x16x32_bf16 v[22:25], v[168:171], v[200:203], v[22:25]
	v_mfma_f32_16x16x32_bf16 v[18:21], v[176:179], v[200:203], v[18:21]
	v_mfma_f32_16x16x32_bf16 v[6:9], v[168:171], v[208:211], v[6:9]
	v_mfma_f32_16x16x32_bf16 v[2:5], v[176:179], v[208:211], v[2:5]
	v_mfma_f32_16x16x32_bf16 v[54:57], v[172:175], v[188:191], v[54:57]
	v_mfma_f32_16x16x32_bf16 v[50:53], v[180:183], v[188:191], v[50:53]
	v_mfma_f32_16x16x32_bf16 v[38:41], v[172:175], v[196:199], v[38:41]
	v_mfma_f32_16x16x32_bf16 v[34:37], v[180:183], v[196:199], v[34:37]
	v_mfma_f32_16x16x32_bf16 v[22:25], v[172:175], v[204:207], v[22:25]
	v_mfma_f32_16x16x32_bf16 v[18:21], v[180:183], v[204:207], v[18:21]
	v_mfma_f32_16x16x32_bf16 v[6:9], v[172:175], v[212:215], v[6:9]
	v_mfma_f32_16x16x32_bf16 v[2:5], v[180:183], v[212:215], v[2:5]
	s_barrier
	s_add_u32 s22, s22, 0x10000
	s_addc_u32 s23, s23, 0
	s_cmp_ge_u32 s57, s44
	s_cbranch_scc0 .LBB0_1229
	s_and_b64 vcc, exec, s[6:7]
	s_cbranch_vccz .LBB0_1232
	s_barrier

; #define PG8_STAGE(bufoff, gbase, voff) do { _Pragma("unroll") for (int _i = 0; _i < 2; ++_i) \
;         __builtin_amdgcn_global_load_lds((const unsigned*)((const char*)(gbase) + (voff)[_i]), (LAS unsigned*)(lds + (bufoff) + ldsw + _i * 8192), 16, 0, 0); } while (0)
; #define PG8_LDA(dst, b, h) do { _Pragma("unroll") for (int m = 0; m < 4; ++m) _Pragma("unroll") for (int k = 0; k < 2; ++k) dst[m][k] = *(const LAS bf16x8*)(lds + PG8_SA(b, h) + aoff + m * 2048 + k * 1024); } while (0)
; #define PG8_LDB(dst, b, h) do { _Pragma("unroll") for (int n = 0; n < 2; ++n) _Pragma("unroll") for (int k = 0; k < 2; ++k) dst[n][k] = *(const LAS bf16x8*)(lds + PG8_SB(b, h) + boff + n * 2048 + k * 1024); } while (0)
; #define PG8_WAIT_V(n) asm volatile("s_waitcnt vmcnt(" #n ")" ::: "memory")
; #define PG8_WAIT_L(n) asm volatile("s_waitcnt lgkmcnt(" #n ")" ::: "memory")
; #define PG8_BAR __builtin_amdgcn_s_barrier()
; #define PG8_SCHED __builtin_amdgcn_sched_barrier(0)
; template <class Epi, class Sched, bool ABLK = false, bool ALIGN_EPI = true, bool SP2 = true, bool BBLK = true>
; __device__ __forceinline__ void gemm_phase(LAS unsigned char* lds, const Gemm g, const Sched& S, const Epi& E) {
;     ...
;         const bool has_next = S.next(ui + 1, nxt);
;         const int nt = cur.nt;
;         const char* nuA = has_next ? a_unit(nxt) : uA; const int ntbA = has_next ? nxt.k0 / BK : tbA; const char* nB = has_next ? (const char*)g.Bt + (size_t)nxt.pn * tstepB + b_k0(nxt.k0) : cB;
;         for (int t = 0; t < nt; t += 2) {
;             const bool last = (t == nt - 2);
;             const char* a1 = a_tile(uA, tbA + t + 1);
;             const char* a2 = last ? a_tile(nuA, ntbA) : a_tile(uA, tbA + t + 2); const char* b2 = last ? nB : cB + (size_t)(t + 2) * kstepB;
;             const char* a3 = last ? a_tile(nuA, ntbA + 1) : a_tile(uA, tbA + t + 3); const char* b3 = b2 + kstepB;
;             if (last && has_next) S.a_ready(nxt);
;             if constexpr (SP2) {
;             PG8_LDB(B0, 0, 0); PG8_LDB(B1, 0, 1); PG8_SCHED; PG8_LDA(At, 0, 0); PG8_STAGE(PG8_SA(1, 1), a1 + hstepA, voffA);
;             PG8_WAIT_V(8); PG8_WAIT_L(0); PG8_BAR; PG8_MMA(0, 0, At, B0); PG8_MMA(0, 1, At, B1); PG8_BAR; PG8_SCHED;
;             PG8_LDA(At, 0, 1); PG8_STAGE(PG8_SB(0, 0), b2, voffB); PG8_STAGE(PG8_SB(0, 1), b2 + hstepB, voffB); PG8_STAGE(PG8_SA(0, 0), a2, voffA);
.LBB0_1354:
	s_ashr_i32 s21, s20, 31
	s_lshl_b64 s[4:5], s[20:21], 20
	s_add_u32 s24, s76, s4
	s_addc_u32 s25, s33, s5
	s_and_b64 s[4:5], s[26:27], exec
	s_cselect_b32 s4, s25, s37
	s_cselect_b32 s5, s24, s36
	s_ashr_i32 s23, s22, 31
	s_lshl_b64 s[28:29], s[22:23], 20
	s_add_u32 s28, s1, s28
	s_addc_u32 s29, s48, s29
	s_and_b64 s[42:43], s[26:27], exec
	s_cselect_b32 s21, s29, s41
	s_cselect_b32 s23, s28, s40
	s_add_u32 s56, s5, 0x80
	s_addc_u32 s57, s4, 0
	s_add_u32 s59, s40, 0x10000
	v_mov_b32_e32 v2, 0
	s_addc_u32 s64, s41, 0
	v_lshl_add_u64 v[148:149], s[36:37], 0, v[144:145]
	v_lshl_add_u64 v[150:151], s[36:37], 0, v[146:147]
	s_mov_b32 s65, -2
	s_mov_b64 s[40:41], 0
	ds_read_b128 v[152:155], v163
	ds_read_b128 v[156:159], v163 offset:1024
	ds_read_b128 v[166:169], v163 offset:2048
	ds_read_b128 v[170:173], v163 offset:3072
	ds_read_b128 v[174:177], v164
	ds_read_b128 v[178:181], v164 offset:1024
	ds_read_b128 v[182:185], v164 offset:2048
	ds_read_b128 v[186:189], v164 offset:3072
	s_add_u32 s42, s36, s40
	s_addc_u32 s43, s37, s41
	s_add_u32 s46, s42, 0x100
	s_addc_u32 s47, s43, 0
	s_add_u32 s42, s42, 0x180
	s_addc_u32 s43, s43, 0
	s_cmpk_eq_i32 s40, 0xf00
	s_cselect_b32 s43, s57, s43
	s_cselect_b32 s42, s56, s42
	s_cselect_b32 s45, s21, s64
	s_cselect_b32 s44, s23, s59
	s_cselect_b32 s47, s4, s47
	s_cselect_b32 s46, s5, s46
	v_lshl_add_u64 v[222:223], v[148:149], 0, s[40:41]
	s_add_i32 m0, s31, 0xc000
	ds_read_b128 v[190:193], v165
	ds_read_b128 v[194:197], v165 offset:1024
	ds_read_b128 v[198:201], v165 offset:2048
	ds_read_b128 v[202:205], v165 offset:3072
	ds_read_b128 v[206:209], v165 offset:4096
	ds_read_b128 v[210:213], v165 offset:5120
	ds_read_b128 v[214:217], v165 offset:6144
	ds_read_b128 v[218:221], v165 offset:7168
	global_load_lds_dwordx4 v[222:223], off
	v_lshl_add_u64 v[222:223], v[150:151], 0, s[40:41]
	s_add_i32 m0, s31, 0xe000
	s_nop 0
	global_load_lds_dwordx4 v[222:223], off
	s_waitcnt vmcnt(8)
	s_barrier
	s_waitcnt lgkmcnt(0)
	v_mfma_f32_16x16x32_bf16 v[126:129], v[152:155], v[190:193], 0
	v_mfma_f32_16x16x32_bf16 v[122:125], v[166:169], v[190:193], 0
	v_mfma_f32_16x16x32_bf16 v[110:113], v[152:155], v[198:201], 0
	v_mfma_f32_16x16x32_bf16 v[106:109], v[166:169], v[198:201], 0
	v_mfma_f32_16x16x32_bf16 v[94:97], v[152:155], v[206:209], 0
	v_mfma_f32_16x16x32_bf16 v[90:93], v[166:169], v[206:209], 0
	v_mfma_f32_16x16x32_bf16 v[78:81], v[152:155], v[214:217], 0
	v_mfma_f32_16x16x32_bf16 v[74:77], v[166:169], v[214:217], 0
	v_mfma_f32_16x16x32_bf16 v[126:129], v[156:159], v[194:197], v[126:129]
	v_mfma_f32_16x16x32_bf16 v[122:125], v[170:173], v[194:197], v[122:125]
	v_mfma_f32_16x16x32_bf16 v[110:113], v[156:159], v[202:205], v[110:113]
	v_mfma_f32_16x16x32_bf16 v[106:109], v[170:173], v[202:205], v[106:109]
	v_mfma_f32_16x16x32_bf16 v[94:97], v[156:159], v[210:213], v[94:97]
	v_mfma_f32_16x16x32_bf16 v[90:93], v[170:173], v[210:213], v[90:93]
	v_mfma_f32_16x16x32_bf16 v[78:81], v[156:159], v[218:221], v[78:81]
	v_mfma_f32_16x16x32_bf16 v[74:77], v[170:173], v[218:221], v[74:77]
	v_mfma_f32_16x16x32_bf16 v[118:121], v[174:177], v[190:193], 0
	v_mfma_f32_16x16x32_bf16 v[114:117], v[182:185], v[190:193], 0
	v_mfma_f32_16x16x32_bf16 v[102:105], v[174:177], v[198:201], 0
	v_mfma_f32_16x16x32_bf16 v[98:101], v[182:185], v[198:201], 0
	v_mfma_f32_16x16x32_bf16 v[86:89], v[174:177], v[206:209], 0
	v_mfma_f32_16x16x32_bf16 v[82:85], v[182:185], v[206:209], 0
	v_mfma_f32_16x16x32_bf16 v[70:73], v[174:177], v[214:217], 0
	v_mfma_f32_16x16x32_bf16 v[66:69], v[182:185], v[214:217], 0
	v_mfma_f32_16x16x32_bf16 v[118:121], v[178:181], v[194:197], v[118:121]
	v_mfma_f32_16x16x32_bf16 v[114:117], v[186:189], v[194:197], v[114:117]
	v_mfma_f32_16x16x32_bf16 v[102:105], v[178:181], v[202:205], v[102:105]
	v_mfma_f32_16x16x32_bf16 v[98:101], v[186:189], v[202:205], v[98:101]
	v_mfma_f32_16x16x32_bf16 v[86:89], v[178:181], v[210:213], v[86:89]
	v_mfma_f32_16x16x32_bf16 v[82:85], v[186:189], v[210:213], v[82:85]
	v_mfma_f32_16x16x32_bf16 v[70:73], v[178:181], v[218:221], v[70:73]
	v_mfma_f32_16x16x32_bf16 v[66:69], v[186:189], v[218:221], v[66:69]
	s_barrier
	s_add_i32 s66, s72, s49
	s_mov_b32 m0, s66
	ds_read_b128 v[190:193], v165 offset:16384
	ds_read_b128 v[194:197], v165 offset:17408
	ds_read_b128 v[198:201], v165 offset:18432
	ds_read_b128 v[202:205], v165 offset:19456
	ds_read_b128 v[206:209], v165 offset:20480
	ds_read_b128 v[210:213], v165 offset:21504
	ds_read_b128 v[214:217], v165 offset:22528
	ds_read_b128 v[218:221], v165 offset:23552
	global_load_lds_dwordx4 v134, s[44:45]
	s_add_i32 m0, s66, 0x2000
	s_add_u32 s66, s44, 0x4000
	s_addc_u32 s67, s45, 0
	s_add_i32 s75, s73, s49
	global_load_lds_dwordx4 v130, s[44:45]
	s_mov_b32 m0, s75
	s_nop 0
	global_load_lds_dwordx4 v134, s[66:67]
	s_add_i32 m0, s75, 0x2000
	s_nop 0
	global_load_lds_dwordx4 v130, s[66:67]
	s_mov_b32 m0, s31
	s_nop 0
	global_load_lds_dwordx4 v136, s[46:47]
	s_mov_b32 m0, s35
	s_nop 0
	global_load_lds_dwordx4 v132, s[46:47]
	s_waitcnt vmcnt(8)
	s_barrier
; #define PG8_STAGE(bufoff, gbase, voff) do { _Pragma("unroll") for (int _i = 0; _i < 2; ++_i) \
;         __builtin_amdgcn_global_load_lds((const unsigned*)((const char*)(gbase) + (voff)[_i]), (LAS unsigned*)(lds + (bufoff) + ldsw + _i * 8192), 16, 0, 0); } while (0)
; #define PG8_LDA(dst, b, h) do { _Pragma("unroll") for (int m = 0; m < 4; ++m) _Pragma("unroll") for (int k = 0; k < 2; ++k) dst[m][k] = *(const LAS bf16x8*)(lds + PG8_SA(b, h) + aoff + m * 2048 + k * 1024); } while (0)
; #define PG8_LDB(dst, b, h) do { _Pragma("unroll") for (int n = 0; n < 2; ++n) _Pragma("unroll") for (int k = 0; k < 2; ++k) dst[n][k] = *(const LAS bf16x8*)(lds + PG8_SB(b, h) + boff + n * 2048 + k * 1024); } while (0)
; #define PG8_MMA(ai, bj, At, Bt) do { __builtin_amdgcn_s_setprio(1); _Pragma("unroll") for (int m = 0; m < 4; ++m) _Pragma("unroll") for (int n = 0; n < 2; ++n) _Pragma("unroll") for (int k = 0; k < 2; ++k) \
;         acc[ai][bj][m][n] = __builtin_amdgcn_mfma_f32_16x16x32_bf16(Bt[n][k], At[m][k], acc[ai][bj][m][n], 0, 0, 0); __builtin_amdgcn_s_setprio(0); } while (0)
; #define PG8_WAIT_V(n) asm volatile("s_waitcnt vmcnt(" #n ")" ::: "memory")
; #define PG8_WAIT_L(n) asm volatile("s_waitcnt lgkmcnt(" #n ")" ::: "memory")
; #define PG8_BAR __builtin_amdgcn_s_barrier()
; #define PG8_SCHED __builtin_amdgcn_sched_barrier(0)
; template <class Epi, class Sched, bool ABLK = false, bool ALIGN_EPI = true, bool SP2 = true, bool BBLK = true>
; __device__ __forceinline__ void gemm_phase(LAS unsigned char* lds, const Gemm g, const Sched& S, const Epi& E) {
;     ...
;             PG8_WAIT_V(8); PG8_WAIT_L(0); PG8_BAR; PG8_MMA(1, 0, At, B0); PG8_MMA(1, 1, At, B1); PG8_BAR; PG8_SCHED;
;             PG8_LDB(B0, 1, 0); PG8_LDB(B1, 1, 1); PG8_SCHED; PG8_LDA(At, 1, 0); PG8_STAGE(PG8_SA(0, 1), a2 + hstepA, voffA);
;             PG8_WAIT_V(8); PG8_WAIT_L(0); PG8_BAR; PG8_MMA(0, 0, At, B0); PG8_MMA(0, 1, At, B1); PG8_BAR; PG8_SCHED;
	s_waitcnt lgkmcnt(0)
	v_mfma_f32_16x16x32_bf16 v[62:65], v[152:155], v[190:193], 0
	v_mfma_f32_16x16x32_bf16 v[58:61], v[166:169], v[190:193], 0
	v_mfma_f32_16x16x32_bf16 v[46:49], v[152:155], v[198:201], 0
	v_mfma_f32_16x16x32_bf16 v[42:45], v[166:169], v[198:201], 0
	v_mfma_f32_16x16x32_bf16 v[30:33], v[152:155], v[206:209], 0
	v_mfma_f32_16x16x32_bf16 v[26:29], v[166:169], v[206:209], 0
	v_mfma_f32_16x16x32_bf16 v[14:17], v[152:155], v[214:217], 0
	v_mfma_f32_16x16x32_bf16 v[10:13], v[166:169], v[214:217], 0
	v_mfma_f32_16x16x32_bf16 v[62:65], v[156:159], v[194:197], v[62:65]
	v_mfma_f32_16x16x32_bf16 v[58:61], v[170:173], v[194:197], v[58:61]
	v_mfma_f32_16x16x32_bf16 v[46:49], v[156:159], v[202:205], v[46:49]
	v_mfma_f32_16x16x32_bf16 v[42:45], v[170:173], v[202:205], v[42:45]
	v_mfma_f32_16x16x32_bf16 v[30:33], v[156:159], v[210:213], v[30:33]
	v_mfma_f32_16x16x32_bf16 v[26:29], v[170:173], v[210:213], v[26:29]
	v_mfma_f32_16x16x32_bf16 v[14:17], v[156:159], v[218:221], v[14:17]
	v_mfma_f32_16x16x32_bf16 v[10:13], v[170:173], v[218:221], v[10:13]
	v_mfma_f32_16x16x32_bf16 v[54:57], v[174:177], v[190:193], 0
	v_mfma_f32_16x16x32_bf16 v[50:53], v[182:185], v[190:193], 0
	v_mfma_f32_16x16x32_bf16 v[38:41], v[174:177], v[198:201], 0
	v_mfma_f32_16x16x32_bf16 v[34:37], v[182:185], v[198:201], 0
	v_mfma_f32_16x16x32_bf16 v[22:25], v[174:177], v[206:209], 0
	v_mfma_f32_16x16x32_bf16 v[18:21], v[182:185], v[206:209], 0
	v_mfma_f32_16x16x32_bf16 v[6:9], v[174:177], v[214:217], 0
	v_mfma_f32_16x16x32_bf16 v[2:5], v[182:185], v[214:217], 0
	v_mfma_f32_16x16x32_bf16 v[54:57], v[178:181], v[194:197], v[54:57]
	v_mfma_f32_16x16x32_bf16 v[50:53], v[186:189], v[194:197], v[50:53]
	v_mfma_f32_16x16x32_bf16 v[38:41], v[178:181], v[202:205], v[38:41]
	v_mfma_f32_16x16x32_bf16 v[34:37], v[186:189], v[202:205], v[34:37]
	v_mfma_f32_16x16x32_bf16 v[22:25], v[178:181], v[210:213], v[22:25]
	v_mfma_f32_16x16x32_bf16 v[18:21], v[186:189], v[210:213], v[18:21]
	v_mfma_f32_16x16x32_bf16 v[6:9], v[178:181], v[218:221], v[6:9]
	v_mfma_f32_16x16x32_bf16 v[2:5], v[186:189], v[218:221], v[2:5]
	s_barrier
	v_add_u32_e32 v138, s60, v161
	ds_read_b128 v[152:155], v138
	ds_read_b128 v[156:159], v138 offset:1024
	ds_read_b128 v[166:169], v138 offset:2048
	ds_read_b128 v[170:173], v138 offset:3072
	v_add_u32_e32 v138, s61, v161
	ds_read_b128 v[174:177], v138
	ds_read_b128 v[178:181], v138 offset:1024
	ds_read_b128 v[182:185], v138 offset:2048
	ds_read_b128 v[186:189], v138 offset:3072
	s_add_u32 s46, s46, 0x80000
	s_addc_u32 s47, s47, 0
	s_mov_b32 m0, s50
	ds_read_b128 v[190:193], v165 offset:32768
	ds_read_b128 v[194:197], v165 offset:33792
	ds_read_b128 v[198:201], v165 offset:34816
	ds_read_b128 v[202:205], v165 offset:35840
	ds_read_b128 v[206:209], v165 offset:36864
	ds_read_b128 v[210:213], v165 offset:37888
	ds_read_b128 v[214:217], v165 offset:38912
	ds_read_b128 v[218:221], v165 offset:39936
	global_load_lds_dwordx4 v136, s[46:47]
	s_mov_b32 m0, s51
	s_nop 0
	global_load_lds_dwordx4 v132, s[46:47]
	s_waitcnt vmcnt(8)
	s_barrier
	s_waitcnt lgkmcnt(0)
	v_mfma_f32_16x16x32_bf16 v[126:129], v[152:155], v[190:193], v[126:129]
	v_mfma_f32_16x16x32_bf16 v[122:125], v[166:169], v[190:193], v[122:125]
	v_mfma_f32_16x16x32_bf16 v[110:113], v[152:155], v[198:201], v[110:113]
	v_mfma_f32_16x16x32_bf16 v[106:109], v[166:169], v[198:201], v[106:109]
	v_mfma_f32_16x16x32_bf16 v[94:97], v[152:155], v[206:209], v[94:97]
	v_mfma_f32_16x16x32_bf16 v[90:93], v[166:169], v[206:209], v[90:93]
	v_mfma_f32_16x16x32_bf16 v[78:81], v[152:155], v[214:217], v[78:81]
	v_mfma_f32_16x16x32_bf16 v[74:77], v[166:169], v[214:217], v[74:77]
	v_mfma_f32_16x16x32_bf16 v[126:129], v[156:159], v[194:197], v[126:129]
	v_mfma_f32_16x16x32_bf16 v[122:125], v[170:173], v[194:197], v[122:125]
	v_mfma_f32_16x16x32_bf16 v[110:113], v[156:159], v[202:205], v[110:113]
	v_mfma_f32_16x16x32_bf16 v[106:109], v[170:173], v[202:205], v[106:109]
	v_mfma_f32_16x16x32_bf16 v[94:97], v[156:159], v[210:213], v[94:97]
	v_mfma_f32_16x16x32_bf16 v[90:93], v[170:173], v[210:213], v[90:93]
	v_mfma_f32_16x16x32_bf16 v[78:81], v[156:159], v[218:221], v[78:81]
	v_mfma_f32_16x16x32_bf16 v[74:77], v[170:173], v[218:221], v[74:77]
	v_mfma_f32_16x16x32_bf16 v[118:121], v[174:177], v[190:193], v[118:121]
	v_mfma_f32_16x16x32_bf16 v[114:117], v[182:185], v[190:193], v[114:117]
	v_mfma_f32_16x16x32_bf16 v[102:105], v[174:177], v[198:201], v[102:105]
	v_mfma_f32_16x16x32_bf16 v[98:101], v[182:185], v[198:201], v[98:101]
	v_mfma_f32_16x16x32_bf16 v[86:89], v[174:177], v[206:209], v[86:89]
	v_mfma_f32_16x16x32_bf16 v[82:85], v[182:185], v[206:209], v[82:85]
	v_mfma_f32_16x16x32_bf16 v[70:73], v[174:177], v[214:217], v[70:73]
	v_mfma_f32_16x16x32_bf16 v[66:69], v[182:185], v[214:217], v[66:69]
	v_mfma_f32_16x16x32_bf16 v[118:121], v[178:181], v[194:197], v[118:121]
	v_mfma_f32_16x16x32_bf16 v[114:117], v[186:189], v[194:197], v[114:117]
	v_mfma_f32_16x16x32_bf16 v[102:105], v[178:181], v[202:205], v[102:105]
	v_mfma_f32_16x16x32_bf16 v[98:101], v[186:189], v[202:205], v[98:101]
	v_mfma_f32_16x16x32_bf16 v[86:89], v[178:181], v[210:213], v[86:89]
	v_mfma_f32_16x16x32_bf16 v[82:85], v[186:189], v[210:213], v[82:85]
	v_mfma_f32_16x16x32_bf16 v[70:73], v[178:181], v[218:221], v[70:73]
	v_mfma_f32_16x16x32_bf16 v[66:69], v[186:189], v[218:221], v[66:69]
	s_barrier
; #define PG8_STAGE(bufoff, gbase, voff) do { _Pragma("unroll") for (int _i = 0; _i < 2; ++_i) \
;         __builtin_amdgcn_global_load_lds((const unsigned*)((const char*)(gbase) + (voff)[_i]), (LAS unsigned*)(lds + (bufoff) + ldsw + _i * 8192), 16, 0, 0); } while (0)
; #define PG8_LDA(dst, b, h) do { _Pragma("unroll") for (int m = 0; m < 4; ++m) _Pragma("unroll") for (int k = 0; k < 2; ++k) dst[m][k] = *(const LAS bf16x8*)(lds + PG8_SA(b, h) + aoff + m * 2048 + k * 1024); } while (0)
; #define PG8_LDB(dst, b, h) do { _Pragma("unroll") for (int n = 0; n < 2; ++n) _Pragma("unroll") for (int k = 0; k < 2; ++k) dst[n][k] = *(const LAS bf16x8*)(lds + PG8_SB(b, h) + boff + n * 2048 + k * 1024); } while (0)
; #define PG8_MMA(ai, bj, At, Bt) do { __builtin_amdgcn_s_setprio(1); _Pragma("unroll") for (int m = 0; m < 4; ++m) _Pragma("unroll") for (int n = 0; n < 2; ++n) _Pragma("unroll") for (int k = 0; k < 2; ++k) \
;         acc[ai][bj][m][n] = __builtin_amdgcn_mfma_f32_16x16x32_bf16(Bt[n][k], At[m][k], acc[ai][bj][m][n], 0, 0, 0); __builtin_amdgcn_s_setprio(0); } while (0)
; #define PG8_WAIT_V(n) asm volatile("s_waitcnt vmcnt(" #n ")" ::: "memory")
; #define PG8_WAIT_L(n) asm volatile("s_waitcnt lgkmcnt(" #n ")" ::: "memory")
; #define PG8_BAR __builtin_amdgcn_s_barrier()
; #define PG8_SCHED __builtin_amdgcn_sched_barrier(0)
; template <class Epi, class Sched, bool ABLK = false, bool ALIGN_EPI = true, bool SP2 = true, bool BBLK = true>
; __device__ __forceinline__ void gemm_phase(LAS unsigned char* lds, const Gemm g, const Sched& S, const Epi& E) {
;     ...
;             PG8_LDB(B0, 0, 0); PG8_LDB(B1, 0, 1); PG8_SCHED; PG8_LDA(At, 0, 0); PG8_STAGE(PG8_SA(1, 1), a1 + hstepA, voffA);
;             PG8_WAIT_V(8); PG8_WAIT_L(0); PG8_BAR; PG8_MMA(0, 0, At, B0); PG8_MMA(0, 1, At, B1); PG8_BAR; PG8_SCHED;
;     ...
;             PG8_LDA(At, 1, 1); PG8_STAGE(PG8_SB(1, 0), b3, voffB); PG8_STAGE(PG8_SB(1, 1), b3 + hstepB, voffB); PG8_STAGE(PG8_SA(1, 0), a3, voffA);
;             PG8_WAIT_V(8); PG8_WAIT_L(0); PG8_BAR; PG8_MMA(1, 0, At, B0); PG8_MMA(1, 1, At, B1); PG8_BAR; PG8_SCHED;
	s_add_u32 s46, s44, 0x8000
	s_addc_u32 s47, s45, 0
	s_add_i32 s66, s60, s49
	s_mov_b32 m0, s66
	ds_read_b128 v[190:193], v165 offset:49152
	ds_read_b128 v[194:197], v165 offset:50176
	ds_read_b128 v[198:201], v165 offset:51200
	ds_read_b128 v[202:205], v165 offset:52224
	ds_read_b128 v[206:209], v165 offset:53248
	ds_read_b128 v[210:213], v165 offset:54272
	ds_read_b128 v[214:217], v165 offset:55296
	ds_read_b128 v[218:221], v165 offset:56320
	global_load_lds_dwordx4 v134, s[46:47]
	s_add_i32 m0, s66, 0x2000
	s_add_u32 s44, s44, 0xc000
	v_lshl_add_u64 v[222:223], s[46:47], 0, v[130:131]
	s_addc_u32 s45, s45, 0
	s_add_i32 s46, s61, s49
	global_load_lds_dwordx4 v[222:223], off
	s_mov_b32 m0, s46
	s_nop 0
	global_load_lds_dwordx4 v134, s[44:45]
	s_add_i32 m0, s46, 0x2000
	s_nop 0
	global_load_lds_dwordx4 v130, s[44:45]
	s_mov_b32 m0, s54
	s_nop 0
	global_load_lds_dwordx4 v136, s[42:43]
	s_mov_b32 m0, s55
	s_nop 0
	global_load_lds_dwordx4 v132, s[42:43]
	s_waitcnt vmcnt(8)
	s_barrier
	s_waitcnt lgkmcnt(0)
	v_mfma_f32_16x16x32_bf16 v[62:65], v[152:155], v[190:193], v[62:65]
	v_mfma_f32_16x16x32_bf16 v[58:61], v[166:169], v[190:193], v[58:61]
	v_mfma_f32_16x16x32_bf16 v[46:49], v[152:155], v[198:201], v[46:49]
	v_mfma_f32_16x16x32_bf16 v[42:45], v[166:169], v[198:201], v[42:45]
	v_mfma_f32_16x16x32_bf16 v[30:33], v[152:155], v[206:209], v[30:33]
	v_mfma_f32_16x16x32_bf16 v[26:29], v[166:169], v[206:209], v[26:29]
	v_mfma_f32_16x16x32_bf16 v[14:17], v[152:155], v[214:217], v[14:17]
	v_mfma_f32_16x16x32_bf16 v[10:13], v[166:169], v[214:217], v[10:13]
	v_mfma_f32_16x16x32_bf16 v[62:65], v[156:159], v[194:197], v[62:65]
	v_mfma_f32_16x16x32_bf16 v[58:61], v[170:173], v[194:197], v[58:61]
	v_mfma_f32_16x16x32_bf16 v[46:49], v[156:159], v[202:205], v[46:49]
	v_mfma_f32_16x16x32_bf16 v[42:45], v[170:173], v[202:205], v[42:45]
	v_mfma_f32_16x16x32_bf16 v[30:33], v[156:159], v[210:213], v[30:33]
	v_mfma_f32_16x16x32_bf16 v[26:29], v[170:173], v[210:213], v[26:29]
	v_mfma_f32_16x16x32_bf16 v[14:17], v[156:159], v[218:221], v[14:17]
	v_mfma_f32_16x16x32_bf16 v[10:13], v[170:173], v[218:221], v[10:13]
	v_mfma_f32_16x16x32_bf16 v[54:57], v[174:177], v[190:193], v[54:57]
	v_mfma_f32_16x16x32_bf16 v[50:53], v[182:185], v[190:193], v[50:53]
	v_mfma_f32_16x16x32_bf16 v[38:41], v[174:177], v[198:201], v[38:41]
	v_mfma_f32_16x16x32_bf16 v[34:37], v[182:185], v[198:201], v[34:37]
	v_mfma_f32_16x16x32_bf16 v[22:25], v[174:177], v[206:209], v[22:25]
	v_mfma_f32_16x16x32_bf16 v[18:21], v[182:185], v[206:209], v[18:21]
	v_mfma_f32_16x16x32_bf16 v[6:9], v[174:177], v[214:217], v[6:9]
	v_mfma_f32_16x16x32_bf16 v[2:5], v[182:185], v[214:217], v[2:5]
	v_mfma_f32_16x16x32_bf16 v[54:57], v[178:181], v[194:197], v[54:57]
	v_mfma_f32_16x16x32_bf16 v[50:53], v[186:189], v[194:197], v[50:53]
	v_mfma_f32_16x16x32_bf16 v[38:41], v[178:181], v[202:205], v[38:41]
	v_mfma_f32_16x16x32_bf16 v[34:37], v[186:189], v[202:205], v[34:37]
	v_mfma_f32_16x16x32_bf16 v[22:25], v[178:181], v[210:213], v[22:25]
	v_mfma_f32_16x16x32_bf16 v[18:21], v[186:189], v[210:213], v[18:21]
	v_mfma_f32_16x16x32_bf16 v[6:9], v[178:181], v[218:221], v[6:9]
	v_mfma_f32_16x16x32_bf16 v[2:5], v[186:189], v[218:221], v[2:5]
	s_barrier
	s_add_i32 s65, s65, 2
	s_add_u32 s40, s40, 0x100
	s_addc_u32 s41, s41, 0
	s_add_u32 s59, s59, 0x10000
	s_addc_u32 s64, s64, 0
	s_cmp_gt_u32 s65, 29
.LBB0_1355:
	ds_read_b128 v[152:155], v163
	ds_read_b128 v[156:159], v163 offset:1024
	ds_read_b128 v[166:169], v163 offset:2048
	ds_read_b128 v[170:173], v163 offset:3072
	ds_read_b128 v[174:177], v164
	ds_read_b128 v[178:181], v164 offset:1024
	ds_read_b128 v[182:185], v164 offset:2048
	ds_read_b128 v[186:189], v164 offset:3072
	s_add_u32 s42, s36, s40
	s_addc_u32 s43, s37, s41
	s_add_u32 s46, s42, 0x100
	s_addc_u32 s47, s43, 0
	s_add_u32 s42, s42, 0x180
	s_addc_u32 s43, s43, 0
	s_cmpk_eq_i32 s40, 0xf00
	s_cselect_b32 s43, s57, s43
	s_cselect_b32 s42, s56, s42
	s_cselect_b32 s45, s21, s64
	s_cselect_b32 s44, s23, s59
	s_cselect_b32 s47, s4, s47
	s_cselect_b32 s46, s5, s46
	v_lshl_add_u64 v[222:223], v[148:149], 0, s[40:41]
	s_add_i32 m0, s31, 0xc000
	ds_read_b128 v[190:193], v165
	ds_read_b128 v[194:197], v165 offset:1024
	ds_read_b128 v[198:201], v165 offset:2048
	ds_read_b128 v[202:205], v165 offset:3072
	ds_read_b128 v[206:209], v165 offset:4096
	ds_read_b128 v[210:213], v165 offset:5120
	ds_read_b128 v[214:217], v165 offset:6144
	ds_read_b128 v[218:221], v165 offset:7168
	global_load_lds_dwordx4 v[222:223], off
	v_lshl_add_u64 v[222:223], v[150:151], 0, s[40:41]
	s_add_i32 m0, s31, 0xe000
	s_nop 0
	global_load_lds_dwordx4 v[222:223], off
	s_waitcnt vmcnt(8)
	s_barrier
; #define PG8_STAGE(bufoff, gbase, voff) do { _Pragma("unroll") for (int _i = 0; _i < 2; ++_i) \
;         __builtin_amdgcn_global_load_lds((const unsigned*)((const char*)(gbase) + (voff)[_i]), (LAS unsigned*)(lds + (bufoff) + ldsw + _i * 8192), 16, 0, 0); } while (0)
; #define PG8_LDA(dst, b, h) do { _Pragma("unroll") for (int m = 0; m < 4; ++m) _Pragma("unroll") for (int k = 0; k < 2; ++k) dst[m][k] = *(const LAS bf16x8*)(lds + PG8_SA(b, h) + aoff + m * 2048 + k * 1024); } while (0)
; #define PG8_MMA(ai, bj, At, Bt) do { __builtin_amdgcn_s_setprio(1); _Pragma("unroll") for (int m = 0; m < 4; ++m) _Pragma("unroll") for (int n = 0; n < 2; ++n) _Pragma("unroll") for (int k = 0; k < 2; ++k) \
;         acc[ai][bj][m][n] = __builtin_amdgcn_mfma_f32_16x16x32_bf16(Bt[n][k], At[m][k], acc[ai][bj][m][n], 0, 0, 0); __builtin_amdgcn_s_setprio(0); } while (0)
; #define PG8_WAIT_V(n) asm volatile("s_waitcnt vmcnt(" #n ")" ::: "memory")
; #define PG8_WAIT_L(n) asm volatile("s_waitcnt lgkmcnt(" #n ")" ::: "memory")
; #define PG8_BAR __builtin_amdgcn_s_barrier()
; #define PG8_SCHED __builtin_amdgcn_sched_barrier(0)
; template <class Epi, class Sched, bool ABLK = false, bool ALIGN_EPI = true, bool SP2 = true, bool BBLK = true>
; __device__ __forceinline__ void gemm_phase(LAS unsigned char* lds, const Gemm g, const Sched& S, const Epi& E) {
;     ...
;             PG8_WAIT_V(8); PG8_WAIT_L(0); PG8_BAR; PG8_MMA(0, 0, At, B0); PG8_MMA(0, 1, At, B1); PG8_BAR; PG8_SCHED;
;             PG8_LDA(At, 0, 1); PG8_STAGE(PG8_SB(0, 0), b2, voffB); PG8_STAGE(PG8_SB(0, 1), b2 + hstepB, voffB); PG8_STAGE(PG8_SA(0, 0), a2, voffA);
;             PG8_WAIT_V(8); PG8_WAIT_L(0); PG8_BAR; PG8_MMA(1, 0, At, B0); PG8_MMA(1, 1, At, B1); PG8_BAR; PG8_SCHED;
	s_waitcnt lgkmcnt(0)
	v_mfma_f32_16x16x32_bf16 v[126:129], v[152:155], v[190:193], v[126:129]
	v_mfma_f32_16x16x32_bf16 v[122:125], v[166:169], v[190:193], v[122:125]
	v_mfma_f32_16x16x32_bf16 v[110:113], v[152:155], v[198:201], v[110:113]
	v_mfma_f32_16x16x32_bf16 v[106:109], v[166:169], v[198:201], v[106:109]
	v_mfma_f32_16x16x32_bf16 v[94:97], v[152:155], v[206:209], v[94:97]
	v_mfma_f32_16x16x32_bf16 v[90:93], v[166:169], v[206:209], v[90:93]
	v_mfma_f32_16x16x32_bf16 v[78:81], v[152:155], v[214:217], v[78:81]
	v_mfma_f32_16x16x32_bf16 v[74:77], v[166:169], v[214:217], v[74:77]
	v_mfma_f32_16x16x32_bf16 v[126:129], v[156:159], v[194:197], v[126:129]
	v_mfma_f32_16x16x32_bf16 v[122:125], v[170:173], v[194:197], v[122:125]
	v_mfma_f32_16x16x32_bf16 v[110:113], v[156:159], v[202:205], v[110:113]
	v_mfma_f32_16x16x32_bf16 v[106:109], v[170:173], v[202:205], v[106:109]
	v_mfma_f32_16x16x32_bf16 v[94:97], v[156:159], v[210:213], v[94:97]
	v_mfma_f32_16x16x32_bf16 v[90:93], v[170:173], v[210:213], v[90:93]
	v_mfma_f32_16x16x32_bf16 v[78:81], v[156:159], v[218:221], v[78:81]
	v_mfma_f32_16x16x32_bf16 v[74:77], v[170:173], v[218:221], v[74:77]
	v_mfma_f32_16x16x32_bf16 v[118:121], v[174:177], v[190:193], v[118:121]
	v_mfma_f32_16x16x32_bf16 v[114:117], v[182:185], v[190:193], v[114:117]
	v_mfma_f32_16x16x32_bf16 v[102:105], v[174:177], v[198:201], v[102:105]
	v_mfma_f32_16x16x32_bf16 v[98:101], v[182:185], v[198:201], v[98:101]
	v_mfma_f32_16x16x32_bf16 v[86:89], v[174:177], v[206:209], v[86:89]
	v_mfma_f32_16x16x32_bf16 v[82:85], v[182:185], v[206:209], v[82:85]
	v_mfma_f32_16x16x32_bf16 v[70:73], v[174:177], v[214:217], v[70:73]
	v_mfma_f32_16x16x32_bf16 v[66:69], v[182:185], v[214:217], v[66:69]
	v_mfma_f32_16x16x32_bf16 v[118:121], v[178:181], v[194:197], v[118:121]
	v_mfma_f32_16x16x32_bf16 v[114:117], v[186:189], v[194:197], v[114:117]
	v_mfma_f32_16x16x32_bf16 v[102:105], v[178:181], v[202:205], v[102:105]
	v_mfma_f32_16x16x32_bf16 v[98:101], v[186:189], v[202:205], v[98:101]
	v_mfma_f32_16x16x32_bf16 v[86:89], v[178:181], v[210:213], v[86:89]
	v_mfma_f32_16x16x32_bf16 v[82:85], v[186:189], v[210:213], v[82:85]
	v_mfma_f32_16x16x32_bf16 v[70:73], v[178:181], v[218:221], v[70:73]
	v_mfma_f32_16x16x32_bf16 v[66:69], v[186:189], v[218:221], v[66:69]
	s_barrier
	s_add_i32 s66, s72, s49
	s_mov_b32 m0, s66
	ds_read_b128 v[190:193], v165 offset:16384
	ds_read_b128 v[194:197], v165 offset:17408
	ds_read_b128 v[198:201], v165 offset:18432
	ds_read_b128 v[202:205], v165 offset:19456
	ds_read_b128 v[206:209], v165 offset:20480
	ds_read_b128 v[210:213], v165 offset:21504
	ds_read_b128 v[214:217], v165 offset:22528
	ds_read_b128 v[218:221], v165 offset:23552
	global_load_lds_dwordx4 v134, s[44:45]
	s_add_i32 m0, s66, 0x2000
	s_add_u32 s66, s44, 0x4000
	s_addc_u32 s67, s45, 0
	s_add_i32 s75, s73, s49
	global_load_lds_dwordx4 v130, s[44:45]
	s_mov_b32 m0, s75
	s_nop 0
	global_load_lds_dwordx4 v134, s[66:67]
	s_add_i32 m0, s75, 0x2000
	s_nop 0
	global_load_lds_dwordx4 v130, s[66:67]
	s_mov_b32 m0, s31
	s_nop 0
	global_load_lds_dwordx4 v136, s[46:47]
	s_mov_b32 m0, s35
	s_nop 0
	global_load_lds_dwordx4 v132, s[46:47]
	s_waitcnt vmcnt(8)
	s_barrier
	s_waitcnt lgkmcnt(0)
	v_mfma_f32_16x16x32_bf16 v[62:65], v[152:155], v[190:193], v[62:65]
	v_mfma_f32_16x16x32_bf16 v[58:61], v[166:169], v[190:193], v[58:61]
	v_mfma_f32_16x16x32_bf16 v[46:49], v[152:155], v[198:201], v[46:49]
	v_mfma_f32_16x16x32_bf16 v[42:45], v[166:169], v[198:201], v[42:45]
	v_mfma_f32_16x16x32_bf16 v[30:33], v[152:155], v[206:209], v[30:33]
	v_mfma_f32_16x16x32_bf16 v[26:29], v[166:169], v[206:209], v[26:29]
	v_mfma_f32_16x16x32_bf16 v[14:17], v[152:155], v[214:217], v[14:17]
	v_mfma_f32_16x16x32_bf16 v[10:13], v[166:169], v[214:217], v[10:13]
	v_mfma_f32_16x16x32_bf16 v[62:65], v[156:159], v[194:197], v[62:65]
	v_mfma_f32_16x16x32_bf16 v[58:61], v[170:173], v[194:197], v[58:61]
	v_mfma_f32_16x16x32_bf16 v[46:49], v[156:159], v[202:205], v[46:49]
	v_mfma_f32_16x16x32_bf16 v[42:45], v[170:173], v[202:205], v[42:45]
	v_mfma_f32_16x16x32_bf16 v[30:33], v[156:159], v[210:213], v[30:33]
	v_mfma_f32_16x16x32_bf16 v[26:29], v[170:173], v[210:213], v[26:29]
	v_mfma_f32_16x16x32_bf16 v[14:17], v[156:159], v[218:221], v[14:17]
	v_mfma_f32_16x16x32_bf16 v[10:13], v[170:173], v[218:221], v[10:13]
	v_mfma_f32_16x16x32_bf16 v[54:57], v[174:177], v[190:193], v[54:57]
	v_mfma_f32_16x16x32_bf16 v[50:53], v[182:185], v[190:193], v[50:53]
	v_mfma_f32_16x16x32_bf16 v[38:41], v[174:177], v[198:201], v[38:41]
	v_mfma_f32_16x16x32_bf16 v[34:37], v[182:185], v[198:201], v[34:37]
	v_mfma_f32_16x16x32_bf16 v[22:25], v[174:177], v[206:209], v[22:25]
	v_mfma_f32_16x16x32_bf16 v[18:21], v[182:185], v[206:209], v[18:21]
	v_mfma_f32_16x16x32_bf16 v[6:9], v[174:177], v[214:217], v[6:9]
	v_mfma_f32_16x16x32_bf16 v[2:5], v[182:185], v[214:217], v[2:5]
	v_mfma_f32_16x16x32_bf16 v[54:57], v[178:181], v[194:197], v[54:57]
	v_mfma_f32_16x16x32_bf16 v[50:53], v[186:189], v[194:197], v[50:53]
	v_mfma_f32_16x16x32_bf16 v[38:41], v[178:181], v[202:205], v[38:41]
	v_mfma_f32_16x16x32_bf16 v[34:37], v[186:189], v[202:205], v[34:37]
	v_mfma_f32_16x16x32_bf16 v[22:25], v[178:181], v[210:213], v[22:25]
	v_mfma_f32_16x16x32_bf16 v[18:21], v[186:189], v[210:213], v[18:21]
	v_mfma_f32_16x16x32_bf16 v[6:9], v[178:181], v[218:221], v[6:9]
	v_mfma_f32_16x16x32_bf16 v[2:5], v[186:189], v[218:221], v[2:5]
	s_barrier
; #define PG8_STAGE(bufoff, gbase, voff) do { _Pragma("unroll") for (int _i = 0; _i < 2; ++_i) \
;         __builtin_amdgcn_global_load_lds((const unsigned*)((const char*)(gbase) + (voff)[_i]), (LAS unsigned*)(lds + (bufoff) + ldsw + _i * 8192), 16, 0, 0); } while (0)
; #define PG8_LDA(dst, b, h) do { _Pragma("unroll") for (int m = 0; m < 4; ++m) _Pragma("unroll") for (int k = 0; k < 2; ++k) dst[m][k] = *(const LAS bf16x8*)(lds + PG8_SA(b, h) + aoff + m * 2048 + k * 1024); } while (0)
; #define PG8_LDB(dst, b, h) do { _Pragma("unroll") for (int n = 0; n < 2; ++n) _Pragma("unroll") for (int k = 0; k < 2; ++k) dst[n][k] = *(const LAS bf16x8*)(lds + PG8_SB(b, h) + boff + n * 2048 + k * 1024); } while (0)
; #define PG8_MMA(ai, bj, At, Bt) do { __builtin_amdgcn_s_setprio(1); _Pragma("unroll") for (int m = 0; m < 4; ++m) _Pragma("unroll") for (int n = 0; n < 2; ++n) _Pragma("unroll") for (int k = 0; k < 2; ++k) \
;         acc[ai][bj][m][n] = __builtin_amdgcn_mfma_f32_16x16x32_bf16(Bt[n][k], At[m][k], acc[ai][bj][m][n], 0, 0, 0); __builtin_amdgcn_s_setprio(0); } while (0)
; #define PG8_WAIT_V(n) asm volatile("s_waitcnt vmcnt(" #n ")" ::: "memory")
; #define PG8_WAIT_L(n) asm volatile("s_waitcnt lgkmcnt(" #n ")" ::: "memory")
; #define PG8_BAR __builtin_amdgcn_s_barrier()
; #define PG8_SCHED __builtin_amdgcn_sched_barrier(0)
; template <class Epi, class Sched, bool ABLK = false, bool ALIGN_EPI = true, bool SP2 = true, bool BBLK = true>
; __device__ __forceinline__ void gemm_phase(LAS unsigned char* lds, const Gemm g, const Sched& S, const Epi& E) {
;     ...
;             PG8_LDB(B0, 1, 0); PG8_LDB(B1, 1, 1); PG8_SCHED; PG8_LDA(At, 1, 0); PG8_STAGE(PG8_SA(0, 1), a2 + hstepA, voffA);
;             PG8_WAIT_V(8); PG8_WAIT_L(0); PG8_BAR; PG8_MMA(0, 0, At, B0); PG8_MMA(0, 1, At, B1); PG8_BAR; PG8_SCHED;
;             PG8_LDA(At, 1, 1); PG8_STAGE(PG8_SB(1, 0), b3, voffB); PG8_STAGE(PG8_SB(1, 1), b3 + hstepB, voffB); PG8_STAGE(PG8_SA(1, 0), a3, voffA);
;             PG8_WAIT_V(8); PG8_WAIT_L(0); PG8_BAR; PG8_MMA(1, 0, At, B0); PG8_MMA(1, 1, At, B1); PG8_BAR; PG8_SCHED;
;     ...
;         if constexpr (ALIGN_EPI) { if (wr == 0) PG8_BAR; }
	v_add_u32_e32 v138, s60, v161
	ds_read_b128 v[152:155], v138
	ds_read_b128 v[156:159], v138 offset:1024
	ds_read_b128 v[166:169], v138 offset:2048
	ds_read_b128 v[170:173], v138 offset:3072
	v_add_u32_e32 v138, s61, v161
	ds_read_b128 v[174:177], v138
	ds_read_b128 v[178:181], v138 offset:1024
	ds_read_b128 v[182:185], v138 offset:2048
	ds_read_b128 v[186:189], v138 offset:3072
	s_add_u32 s46, s46, 0x80000
	s_addc_u32 s47, s47, 0
	s_mov_b32 m0, s50
	ds_read_b128 v[190:193], v165 offset:32768
	ds_read_b128 v[194:197], v165 offset:33792
	ds_read_b128 v[198:201], v165 offset:34816
	ds_read_b128 v[202:205], v165 offset:35840
	ds_read_b128 v[206:209], v165 offset:36864
	ds_read_b128 v[210:213], v165 offset:37888
	ds_read_b128 v[214:217], v165 offset:38912
	ds_read_b128 v[218:221], v165 offset:39936
	global_load_lds_dwordx4 v136, s[46:47]
	s_mov_b32 m0, s51
	s_nop 0
	global_load_lds_dwordx4 v132, s[46:47]
	s_waitcnt vmcnt(8)
	s_barrier
	s_waitcnt lgkmcnt(0)
	v_mfma_f32_16x16x32_bf16 v[126:129], v[152:155], v[190:193], v[126:129]
	v_mfma_f32_16x16x32_bf16 v[122:125], v[166:169], v[190:193], v[122:125]
	v_mfma_f32_16x16x32_bf16 v[110:113], v[152:155], v[198:201], v[110:113]
	v_mfma_f32_16x16x32_bf16 v[106:109], v[166:169], v[198:201], v[106:109]
	v_mfma_f32_16x16x32_bf16 v[94:97], v[152:155], v[206:209], v[94:97]
	v_mfma_f32_16x16x32_bf16 v[90:93], v[166:169], v[206:209], v[90:93]
	v_mfma_f32_16x16x32_bf16 v[78:81], v[152:155], v[214:217], v[78:81]
	v_mfma_f32_16x16x32_bf16 v[74:77], v[166:169], v[214:217], v[74:77]
	v_mfma_f32_16x16x32_bf16 v[126:129], v[156:159], v[194:197], v[126:129]
	v_mfma_f32_16x16x32_bf16 v[122:125], v[170:173], v[194:197], v[122:125]
	v_mfma_f32_16x16x32_bf16 v[110:113], v[156:159], v[202:205], v[110:113]
	v_mfma_f32_16x16x32_bf16 v[106:109], v[170:173], v[202:205], v[106:109]
	v_mfma_f32_16x16x32_bf16 v[94:97], v[156:159], v[210:213], v[94:97]
	v_mfma_f32_16x16x32_bf16 v[90:93], v[170:173], v[210:213], v[90:93]
	v_mfma_f32_16x16x32_bf16 v[78:81], v[156:159], v[218:221], v[78:81]
	v_mfma_f32_16x16x32_bf16 v[74:77], v[170:173], v[218:221], v[74:77]
	v_mfma_f32_16x16x32_bf16 v[118:121], v[174:177], v[190:193], v[118:121]
	v_mfma_f32_16x16x32_bf16 v[114:117], v[182:185], v[190:193], v[114:117]
	v_mfma_f32_16x16x32_bf16 v[102:105], v[174:177], v[198:201], v[102:105]
	v_mfma_f32_16x16x32_bf16 v[98:101], v[182:185], v[198:201], v[98:101]
	v_mfma_f32_16x16x32_bf16 v[86:89], v[174:177], v[206:209], v[86:89]
	v_mfma_f32_16x16x32_bf16 v[82:85], v[182:185], v[206:209], v[82:85]
	v_mfma_f32_16x16x32_bf16 v[70:73], v[174:177], v[214:217], v[70:73]
	v_mfma_f32_16x16x32_bf16 v[66:69], v[182:185], v[214:217], v[66:69]
	v_mfma_f32_16x16x32_bf16 v[118:121], v[178:181], v[194:197], v[118:121]
	v_mfma_f32_16x16x32_bf16 v[114:117], v[186:189], v[194:197], v[114:117]
	v_mfma_f32_16x16x32_bf16 v[102:105], v[178:181], v[202:205], v[102:105]
	v_mfma_f32_16x16x32_bf16 v[98:101], v[186:189], v[202:205], v[98:101]
	v_mfma_f32_16x16x32_bf16 v[86:89], v[178:181], v[210:213], v[86:89]
	v_mfma_f32_16x16x32_bf16 v[82:85], v[186:189], v[210:213], v[82:85]
	v_mfma_f32_16x16x32_bf16 v[70:73], v[178:181], v[218:221], v[70:73]
	v_mfma_f32_16x16x32_bf16 v[66:69], v[186:189], v[218:221], v[66:69]
	s_barrier
	s_add_u32 s46, s44, 0x8000
	s_addc_u32 s47, s45, 0
	s_add_i32 s66, s60, s49
	s_mov_b32 m0, s66
	ds_read_b128 v[190:193], v165 offset:49152
	ds_read_b128 v[194:197], v165 offset:50176
	ds_read_b128 v[198:201], v165 offset:51200
	ds_read_b128 v[202:205], v165 offset:52224
	ds_read_b128 v[206:209], v165 offset:53248
	ds_read_b128 v[210:213], v165 offset:54272
	ds_read_b128 v[214:217], v165 offset:55296
	ds_read_b128 v[218:221], v165 offset:56320
	global_load_lds_dwordx4 v134, s[46:47]
	s_add_i32 m0, s66, 0x2000
	s_add_u32 s44, s44, 0xc000
	v_lshl_add_u64 v[222:223], s[46:47], 0, v[130:131]
	s_addc_u32 s45, s45, 0
	s_add_i32 s46, s61, s49
	global_load_lds_dwordx4 v[222:223], off
	s_mov_b32 m0, s46
	s_nop 0
	global_load_lds_dwordx4 v134, s[44:45]
	s_add_i32 m0, s46, 0x2000
	s_nop 0
	global_load_lds_dwordx4 v130, s[44:45]
	s_mov_b32 m0, s54
	s_nop 0
	global_load_lds_dwordx4 v136, s[42:43]
	s_mov_b32 m0, s55
	s_nop 0
	global_load_lds_dwordx4 v132, s[42:43]
	s_waitcnt vmcnt(8)
	s_barrier
	s_waitcnt lgkmcnt(0)
	v_mfma_f32_16x16x32_bf16 v[62:65], v[152:155], v[190:193], v[62:65]
	v_mfma_f32_16x16x32_bf16 v[58:61], v[166:169], v[190:193], v[58:61]
	v_mfma_f32_16x16x32_bf16 v[46:49], v[152:155], v[198:201], v[46:49]
	v_mfma_f32_16x16x32_bf16 v[42:45], v[166:169], v[198:201], v[42:45]
	v_mfma_f32_16x16x32_bf16 v[30:33], v[152:155], v[206:209], v[30:33]
	v_mfma_f32_16x16x32_bf16 v[26:29], v[166:169], v[206:209], v[26:29]
	v_mfma_f32_16x16x32_bf16 v[14:17], v[152:155], v[214:217], v[14:17]
	v_mfma_f32_16x16x32_bf16 v[10:13], v[166:169], v[214:217], v[10:13]
	v_mfma_f32_16x16x32_bf16 v[62:65], v[156:159], v[194:197], v[62:65]
	v_mfma_f32_16x16x32_bf16 v[58:61], v[170:173], v[194:197], v[58:61]
	v_mfma_f32_16x16x32_bf16 v[46:49], v[156:159], v[202:205], v[46:49]
	v_mfma_f32_16x16x32_bf16 v[42:45], v[170:173], v[202:205], v[42:45]
	v_mfma_f32_16x16x32_bf16 v[30:33], v[156:159], v[210:213], v[30:33]
	v_mfma_f32_16x16x32_bf16 v[26:29], v[170:173], v[210:213], v[26:29]
	v_mfma_f32_16x16x32_bf16 v[14:17], v[156:159], v[218:221], v[14:17]
	v_mfma_f32_16x16x32_bf16 v[10:13], v[170:173], v[218:221], v[10:13]
	v_mfma_f32_16x16x32_bf16 v[54:57], v[174:177], v[190:193], v[54:57]
	v_mfma_f32_16x16x32_bf16 v[50:53], v[182:185], v[190:193], v[50:53]
	v_mfma_f32_16x16x32_bf16 v[38:41], v[174:177], v[198:201], v[38:41]
	v_mfma_f32_16x16x32_bf16 v[34:37], v[182:185], v[198:201], v[34:37]
	v_mfma_f32_16x16x32_bf16 v[22:25], v[174:177], v[206:209], v[22:25]
	v_mfma_f32_16x16x32_bf16 v[18:21], v[182:185], v[206:209], v[18:21]
	v_mfma_f32_16x16x32_bf16 v[6:9], v[174:177], v[214:217], v[6:9]
	v_mfma_f32_16x16x32_bf16 v[2:5], v[182:185], v[214:217], v[2:5]
	v_mfma_f32_16x16x32_bf16 v[54:57], v[178:181], v[194:197], v[54:57]
	v_mfma_f32_16x16x32_bf16 v[50:53], v[186:189], v[194:197], v[50:53]
	v_mfma_f32_16x16x32_bf16 v[38:41], v[178:181], v[202:205], v[38:41]
	v_mfma_f32_16x16x32_bf16 v[34:37], v[186:189], v[202:205], v[34:37]
	v_mfma_f32_16x16x32_bf16 v[22:25], v[178:181], v[210:213], v[22:25]
	v_mfma_f32_16x16x32_bf16 v[18:21], v[186:189], v[210:213], v[18:21]
	v_mfma_f32_16x16x32_bf16 v[6:9], v[178:181], v[218:221], v[6:9]
	v_mfma_f32_16x16x32_bf16 v[2:5], v[186:189], v[218:221], v[2:5]
	s_barrier
	s_add_i32 s65, s65, 2
	s_add_u32 s40, s40, 0x100
	s_addc_u32 s41, s41, 0
	s_add_u32 s59, s59, 0x10000
	s_addc_u32 s64, s64, 0
	s_cmp_gt_u32 s65, 29
	s_cbranch_scc0 .LBB0_1355
	s_and_b64 vcc, exec, s[12:13]
	s_cbranch_vccz .LBB0_1358
	s_barrier

; #define PG8_STAGE(bufoff, gbase, voff) do { _Pragma("unroll") for (int _i = 0; _i < 2; ++_i) \
;         __builtin_amdgcn_global_load_lds((const unsigned*)((const char*)(gbase) + (voff)[_i]), (LAS unsigned*)(lds + (bufoff) + ldsw + _i * 8192), 16, 0, 0); } while (0)
; #define PG8_LDA(dst, b, h) do { _Pragma("unroll") for (int m = 0; m < 4; ++m) _Pragma("unroll") for (int k = 0; k < 2; ++k) dst[m][k] = *(const LAS bf16x8*)(lds + PG8_SA(b, h) + aoff + m * 2048 + k * 1024); } while (0)
; #define PG8_LDB(dst, b, h) do { _Pragma("unroll") for (int n = 0; n < 2; ++n) _Pragma("unroll") for (int k = 0; k < 2; ++k) dst[n][k] = *(const LAS bf16x8*)(lds + PG8_SB(b, h) + boff + n * 2048 + k * 1024); } while (0)
; #define PG8_WAIT_V(n) asm volatile("s_waitcnt vmcnt(" #n ")" ::: "memory")
; #define PG8_WAIT_L(n) asm volatile("s_waitcnt lgkmcnt(" #n ")" ::: "memory")
; #define PG8_BAR __builtin_amdgcn_s_barrier()
; #define PG8_SCHED __builtin_amdgcn_sched_barrier(0)
; template <class Epi, class Sched, bool ABLK = false, bool ALIGN_EPI = true, bool SP2 = true, bool BBLK = true>
; __device__ __forceinline__ void gemm_phase(LAS unsigned char* lds, const Gemm g, const Sched& S, const Epi& E) {
;     ...
;         const bool has_next = S.next(ui + 1, nxt);
;         const int nt = cur.nt;
;         const char* nuA = has_next ? a_unit(nxt) : uA; const int ntbA = has_next ? nxt.k0 / BK : tbA; const char* nB = has_next ? (const char*)g.Bt + (size_t)nxt.pn * tstepB + b_k0(nxt.k0) : cB;
;         for (int t = 0; t < nt; t += 2) {
;             const bool last = (t == nt - 2);
;             const char* a1 = a_tile(uA, tbA + t + 1);
;             const char* a2 = last ? a_tile(nuA, ntbA) : a_tile(uA, tbA + t + 2); const char* b2 = last ? nB : cB + (size_t)(t + 2) * kstepB;
;             const char* a3 = last ? a_tile(nuA, ntbA + 1) : a_tile(uA, tbA + t + 3); const char* b3 = b2 + kstepB;
;             if (last && has_next) S.a_ready(nxt);
;             if constexpr (SP2) {
;             PG8_LDB(B0, 0, 0); PG8_LDB(B1, 0, 1); PG8_SCHED; PG8_LDA(At, 0, 0); PG8_STAGE(PG8_SA(1, 1), a1 + hstepA, voffA);
;             PG8_WAIT_V(8); PG8_WAIT_L(0); PG8_BAR; PG8_MMA(0, 0, At, B0); PG8_MMA(0, 1, At, B1); PG8_BAR; PG8_SCHED;
;             PG8_LDA(At, 0, 1); PG8_STAGE(PG8_SB(0, 0), b2, voffB); PG8_STAGE(PG8_SB(0, 1), b2 + hstepB, voffB); PG8_STAGE(PG8_SA(0, 0), a2, voffA);
.LBB0_1715:
	s_ashr_i32 s81, s80, 31
	s_andn2_b64 vcc, exec, s[4:5]
	s_lshl_b64 s[20:21], s[80:81], 20
	s_add_u32 s20, s1, s20
	s_addc_u32 s21, s36, s21
	s_and_b64 s[22:23], s[4:5], exec
	s_cselect_b32 s31, s21, s29
	s_cselect_b32 s49, s20, s28
	s_ashr_i32 s22, s63, 31
	s_lshr_b32 s22, s22, 26
	s_add_i32 s22, s63, s22
	s_ashr_i32 s22, s22, 6
	s_and_b64 s[24:25], s[4:5], exec
	s_cselect_b32 s34, s22, s30
	s_ashr_i32 s79, s78, 31
	s_lshl_b64 s[24:25], s[78:79], 20
	s_add_u32 s35, s37, s24
	s_addc_u32 s50, s38, s25
	s_ashr_i32 s23, s22, 31
	s_lshl_b64 s[24:25], s[22:23], 15
	s_add_u32 s24, s35, s24
	s_addc_u32 s25, s50, s25
	v_cndmask_b32_e64 v2, 0, 1, s[4:5]
	s_and_b64 s[4:5], s[4:5], exec
	s_cselect_b32 s4, s25, s27
	s_cselect_b32 s5, s24, s26
	s_ashr_i32 s35, s34, 31
	s_lshl_b64 s[34:35], s[34:35], 7
	s_add_u32 s23, s49, s34
	s_addc_u32 s49, s31, s35
	s_add_u32 s50, s23, 0x80
	s_addc_u32 s51, s49, 0
	s_add_u32 s52, s26, 0x10000
	s_addc_u32 s53, s27, 0
	s_ashr_i32 s31, s30, 31
	v_cmp_ne_u32_e64 s[10:11], 1, v2
	s_lshl_b64 s[26:27], s[30:31], 7
	v_lshl_add_u64 v[2:3], s[28:29], 0, v[142:143]
	s_add_u32 s54, s28, s26
	v_lshl_add_u64 v[146:147], v[2:3], 0, s[26:27]
	v_lshl_add_u64 v[2:3], s[28:29], 0, v[144:145]
	s_addc_u32 s55, s29, s27
	v_lshl_add_u64 v[148:149], v[2:3], 0, s[26:27]
	s_lshl_b32 s26, s47, 7
	s_addk_i32 s26, 0xfc00
	v_mov_b32_e32 v2, 0
	s_add_u32 s56, s26, 0x300
	s_mov_b32 s57, 0
	s_mov_b64 s[26:27], 0
	ds_read_b128 v[156:159], v152
	ds_read_b128 v[160:163], v152 offset:1024
	ds_read_b128 v[164:167], v152 offset:2048
	ds_read_b128 v[168:171], v152 offset:3072
	ds_read_b128 v[172:175], v153
	ds_read_b128 v[176:179], v153 offset:1024
	ds_read_b128 v[180:183], v153 offset:2048
	ds_read_b128 v[184:187], v153 offset:3072
	s_add_u32 s28, s54, s26
	s_addc_u32 s29, s55, s27
	s_add_u32 s34, s28, 0x100
	s_addc_u32 s35, s29, 0
	s_add_i32 s57, s57, 2
	s_add_u32 s28, s28, 0x180
	s_addc_u32 s29, s29, 0
	s_cmp_eq_u32 s56, s26
	s_cselect_b32 s29, s51, s29
	s_cselect_b32 s28, s50, s28
	s_cselect_b32 s31, s4, s53
	s_cselect_b32 s30, s5, s52
	s_cselect_b32 s35, s49, s35
	s_cselect_b32 s34, s23, s34
	v_lshl_add_u64 v[220:221], v[146:147], 0, s[26:27]
	s_add_i32 m0, s40, 0xc000
	ds_read_b128 v[188:191], v154
	ds_read_b128 v[192:195], v154 offset:1024
	ds_read_b128 v[196:199], v154 offset:2048
	ds_read_b128 v[200:203], v154 offset:3072
	ds_read_b128 v[204:207], v154 offset:4096
	ds_read_b128 v[208:211], v154 offset:5120
	ds_read_b128 v[212:215], v154 offset:6144
	ds_read_b128 v[216:219], v154 offset:7168
	global_load_lds_dwordx4 v[220:221], off
	v_lshl_add_u64 v[220:221], v[148:149], 0, s[26:27]
	s_add_i32 m0, s40, 0xe000
	s_nop 0
	global_load_lds_dwordx4 v[220:221], off
	s_waitcnt vmcnt(8)
	s_barrier
	s_waitcnt lgkmcnt(0)
	v_mfma_f32_16x16x32_bf16 v[126:129], v[156:159], v[188:191], 0
	v_mfma_f32_16x16x32_bf16 v[122:125], v[164:167], v[188:191], 0
	v_mfma_f32_16x16x32_bf16 v[110:113], v[156:159], v[196:199], 0
	v_mfma_f32_16x16x32_bf16 v[106:109], v[164:167], v[196:199], 0
	v_mfma_f32_16x16x32_bf16 v[94:97], v[156:159], v[204:207], 0
	v_mfma_f32_16x16x32_bf16 v[90:93], v[164:167], v[204:207], 0
	v_mfma_f32_16x16x32_bf16 v[78:81], v[156:159], v[212:215], 0
	v_mfma_f32_16x16x32_bf16 v[74:77], v[164:167], v[212:215], 0
	v_mfma_f32_16x16x32_bf16 v[126:129], v[160:163], v[192:195], v[126:129]
	v_mfma_f32_16x16x32_bf16 v[122:125], v[168:171], v[192:195], v[122:125]
	v_mfma_f32_16x16x32_bf16 v[110:113], v[160:163], v[200:203], v[110:113]
	v_mfma_f32_16x16x32_bf16 v[106:109], v[168:171], v[200:203], v[106:109]
	v_mfma_f32_16x16x32_bf16 v[94:97], v[160:163], v[208:211], v[94:97]
	v_mfma_f32_16x16x32_bf16 v[90:93], v[168:171], v[208:211], v[90:93]
	v_mfma_f32_16x16x32_bf16 v[78:81], v[160:163], v[216:219], v[78:81]
	v_mfma_f32_16x16x32_bf16 v[74:77], v[168:171], v[216:219], v[74:77]
	v_mfma_f32_16x16x32_bf16 v[118:121], v[172:175], v[188:191], 0
	v_mfma_f32_16x16x32_bf16 v[114:117], v[180:183], v[188:191], 0
	v_mfma_f32_16x16x32_bf16 v[102:105], v[172:175], v[196:199], 0
	v_mfma_f32_16x16x32_bf16 v[98:101], v[180:183], v[196:199], 0
	v_mfma_f32_16x16x32_bf16 v[86:89], v[172:175], v[204:207], 0
	v_mfma_f32_16x16x32_bf16 v[82:85], v[180:183], v[204:207], 0
	v_mfma_f32_16x16x32_bf16 v[70:73], v[172:175], v[212:215], 0
	v_mfma_f32_16x16x32_bf16 v[66:69], v[180:183], v[212:215], 0
	v_mfma_f32_16x16x32_bf16 v[118:121], v[176:179], v[192:195], v[118:121]
	v_mfma_f32_16x16x32_bf16 v[114:117], v[184:187], v[192:195], v[114:117]
	v_mfma_f32_16x16x32_bf16 v[102:105], v[176:179], v[200:203], v[102:105]
	v_mfma_f32_16x16x32_bf16 v[98:101], v[184:187], v[200:203], v[98:101]
	v_mfma_f32_16x16x32_bf16 v[86:89], v[176:179], v[208:211], v[86:89]
	v_mfma_f32_16x16x32_bf16 v[82:85], v[184:187], v[208:211], v[82:85]
	v_mfma_f32_16x16x32_bf16 v[70:73], v[176:179], v[216:219], v[70:73]
	v_mfma_f32_16x16x32_bf16 v[66:69], v[184:187], v[216:219], v[66:69]
	s_barrier
	s_add_i32 s58, s72, s39
	s_mov_b32 m0, s58
	ds_read_b128 v[188:191], v154 offset:16384
	ds_read_b128 v[192:195], v154 offset:17408
	ds_read_b128 v[196:199], v154 offset:18432
	ds_read_b128 v[200:203], v154 offset:19456
	ds_read_b128 v[204:207], v154 offset:20480
	ds_read_b128 v[208:211], v154 offset:21504
	ds_read_b128 v[212:215], v154 offset:22528
	ds_read_b128 v[216:219], v154 offset:23552
	global_load_lds_dwordx4 v132, s[30:31]
	s_add_i32 m0, s58, 0x2000
	s_add_u32 s58, s30, 0x4000
	s_addc_u32 s59, s31, 0
	s_add_i32 s64, s73, s39
	global_load_lds_dwordx4 v136, s[30:31]
	s_mov_b32 m0, s64
	s_nop 0
	global_load_lds_dwordx4 v132, s[58:59]
	s_add_i32 m0, s64, 0x2000
	s_nop 0
	global_load_lds_dwordx4 v136, s[58:59]
	s_mov_b32 m0, s40
	s_nop 0
	global_load_lds_dwordx4 v130, s[34:35]
	s_mov_b32 m0, s41
	s_nop 0
	global_load_lds_dwordx4 v134, s[34:35]
	s_waitcnt vmcnt(8)
	s_barrier
; #define PG8_STAGE(bufoff, gbase, voff) do { _Pragma("unroll") for (int _i = 0; _i < 2; ++_i) \
;         __builtin_amdgcn_global_load_lds((const unsigned*)((const char*)(gbase) + (voff)[_i]), (LAS unsigned*)(lds + (bufoff) + ldsw + _i * 8192), 16, 0, 0); } while (0)
; #define PG8_LDA(dst, b, h) do { _Pragma("unroll") for (int m = 0; m < 4; ++m) _Pragma("unroll") for (int k = 0; k < 2; ++k) dst[m][k] = *(const LAS bf16x8*)(lds + PG8_SA(b, h) + aoff + m * 2048 + k * 1024); } while (0)
; #define PG8_LDB(dst, b, h) do { _Pragma("unroll") for (int n = 0; n < 2; ++n) _Pragma("unroll") for (int k = 0; k < 2; ++k) dst[n][k] = *(const LAS bf16x8*)(lds + PG8_SB(b, h) + boff + n * 2048 + k * 1024); } while (0)
; #define PG8_MMA(ai, bj, At, Bt) do { __builtin_amdgcn_s_setprio(1); _Pragma("unroll") for (int m = 0; m < 4; ++m) _Pragma("unroll") for (int n = 0; n < 2; ++n) _Pragma("unroll") for (int k = 0; k < 2; ++k) \
;         acc[ai][bj][m][n] = __builtin_amdgcn_mfma_f32_16x16x32_bf16(Bt[n][k], At[m][k], acc[ai][bj][m][n], 0, 0, 0); __builtin_amdgcn_s_setprio(0); } while (0)
; #define PG8_WAIT_V(n) asm volatile("s_waitcnt vmcnt(" #n ")" ::: "memory")
; #define PG8_WAIT_L(n) asm volatile("s_waitcnt lgkmcnt(" #n ")" ::: "memory")
; #define PG8_BAR __builtin_amdgcn_s_barrier()
; #define PG8_SCHED __builtin_amdgcn_sched_barrier(0)
; template <class Epi, class Sched, bool ABLK = false, bool ALIGN_EPI = true, bool SP2 = true, bool BBLK = true>
; __device__ __forceinline__ void gemm_phase(LAS unsigned char* lds, const Gemm g, const Sched& S, const Epi& E) {
;     ...
;             PG8_WAIT_V(8); PG8_WAIT_L(0); PG8_BAR; PG8_MMA(1, 0, At, B0); PG8_MMA(1, 1, At, B1); PG8_BAR; PG8_SCHED;
;             PG8_LDB(B0, 1, 0); PG8_LDB(B1, 1, 1); PG8_SCHED; PG8_LDA(At, 1, 0); PG8_STAGE(PG8_SA(0, 1), a2 + hstepA, voffA);
;             PG8_WAIT_V(8); PG8_WAIT_L(0); PG8_BAR; PG8_MMA(0, 0, At, B0); PG8_MMA(0, 1, At, B1); PG8_BAR; PG8_SCHED;
	s_waitcnt lgkmcnt(0)
	v_mfma_f32_16x16x32_bf16 v[62:65], v[156:159], v[188:191], 0
	v_mfma_f32_16x16x32_bf16 v[58:61], v[164:167], v[188:191], 0
	v_mfma_f32_16x16x32_bf16 v[46:49], v[156:159], v[196:199], 0
	v_mfma_f32_16x16x32_bf16 v[42:45], v[164:167], v[196:199], 0
	v_mfma_f32_16x16x32_bf16 v[30:33], v[156:159], v[204:207], 0
	v_mfma_f32_16x16x32_bf16 v[26:29], v[164:167], v[204:207], 0
	v_mfma_f32_16x16x32_bf16 v[14:17], v[156:159], v[212:215], 0
	v_mfma_f32_16x16x32_bf16 v[10:13], v[164:167], v[212:215], 0
	v_mfma_f32_16x16x32_bf16 v[62:65], v[160:163], v[192:195], v[62:65]
	v_mfma_f32_16x16x32_bf16 v[58:61], v[168:171], v[192:195], v[58:61]
	v_mfma_f32_16x16x32_bf16 v[46:49], v[160:163], v[200:203], v[46:49]
	v_mfma_f32_16x16x32_bf16 v[42:45], v[168:171], v[200:203], v[42:45]
	v_mfma_f32_16x16x32_bf16 v[30:33], v[160:163], v[208:211], v[30:33]
	v_mfma_f32_16x16x32_bf16 v[26:29], v[168:171], v[208:211], v[26:29]
	v_mfma_f32_16x16x32_bf16 v[14:17], v[160:163], v[216:219], v[14:17]
	v_mfma_f32_16x16x32_bf16 v[10:13], v[168:171], v[216:219], v[10:13]
	v_mfma_f32_16x16x32_bf16 v[54:57], v[172:175], v[188:191], 0
	v_mfma_f32_16x16x32_bf16 v[50:53], v[180:183], v[188:191], 0
	v_mfma_f32_16x16x32_bf16 v[38:41], v[172:175], v[196:199], 0
	v_mfma_f32_16x16x32_bf16 v[34:37], v[180:183], v[196:199], 0
	v_mfma_f32_16x16x32_bf16 v[22:25], v[172:175], v[204:207], 0
	v_mfma_f32_16x16x32_bf16 v[18:21], v[180:183], v[204:207], 0
	v_mfma_f32_16x16x32_bf16 v[6:9], v[172:175], v[212:215], 0
	v_mfma_f32_16x16x32_bf16 v[2:5], v[180:183], v[212:215], 0
	v_mfma_f32_16x16x32_bf16 v[54:57], v[176:179], v[192:195], v[54:57]
	v_mfma_f32_16x16x32_bf16 v[50:53], v[184:187], v[192:195], v[50:53]
	v_mfma_f32_16x16x32_bf16 v[38:41], v[176:179], v[200:203], v[38:41]
	v_mfma_f32_16x16x32_bf16 v[34:37], v[184:187], v[200:203], v[34:37]
	v_mfma_f32_16x16x32_bf16 v[22:25], v[176:179], v[208:211], v[22:25]
	v_mfma_f32_16x16x32_bf16 v[18:21], v[184:187], v[208:211], v[18:21]
	v_mfma_f32_16x16x32_bf16 v[6:9], v[176:179], v[216:219], v[6:9]
	v_mfma_f32_16x16x32_bf16 v[2:5], v[184:187], v[216:219], v[2:5]
	s_barrier
	v_add_u32_e32 v155, s60, v150
	ds_read_b128 v[156:159], v155
	ds_read_b128 v[160:163], v155 offset:1024
	ds_read_b128 v[164:167], v155 offset:2048
	ds_read_b128 v[168:171], v155 offset:3072
	v_add_u32_e32 v155, s61, v150
	ds_read_b128 v[172:175], v155
	ds_read_b128 v[176:179], v155 offset:1024
	ds_read_b128 v[180:183], v155 offset:2048
	ds_read_b128 v[184:187], v155 offset:3072
	s_add_u32 s34, s34, 0x80000
	s_addc_u32 s35, s35, 0
	s_mov_b32 m0, s42
	ds_read_b128 v[188:191], v154 offset:32768
	ds_read_b128 v[192:195], v154 offset:33792
	ds_read_b128 v[196:199], v154 offset:34816
	ds_read_b128 v[200:203], v154 offset:35840
	ds_read_b128 v[204:207], v154 offset:36864
	ds_read_b128 v[208:211], v154 offset:37888
	ds_read_b128 v[212:215], v154 offset:38912
	ds_read_b128 v[216:219], v154 offset:39936
	global_load_lds_dwordx4 v130, s[34:35]
	s_mov_b32 m0, s43
	s_nop 0
	global_load_lds_dwordx4 v134, s[34:35]
	s_waitcnt vmcnt(8)
	s_barrier
	s_waitcnt lgkmcnt(0)
	v_mfma_f32_16x16x32_bf16 v[126:129], v[156:159], v[188:191], v[126:129]
	v_mfma_f32_16x16x32_bf16 v[122:125], v[164:167], v[188:191], v[122:125]
	v_mfma_f32_16x16x32_bf16 v[110:113], v[156:159], v[196:199], v[110:113]
	v_mfma_f32_16x16x32_bf16 v[106:109], v[164:167], v[196:199], v[106:109]
	v_mfma_f32_16x16x32_bf16 v[94:97], v[156:159], v[204:207], v[94:97]
	v_mfma_f32_16x16x32_bf16 v[90:93], v[164:167], v[204:207], v[90:93]
	v_mfma_f32_16x16x32_bf16 v[78:81], v[156:159], v[212:215], v[78:81]
	v_mfma_f32_16x16x32_bf16 v[74:77], v[164:167], v[212:215], v[74:77]
	v_mfma_f32_16x16x32_bf16 v[126:129], v[160:163], v[192:195], v[126:129]
	v_mfma_f32_16x16x32_bf16 v[122:125], v[168:171], v[192:195], v[122:125]
	v_mfma_f32_16x16x32_bf16 v[110:113], v[160:163], v[200:203], v[110:113]
	v_mfma_f32_16x16x32_bf16 v[106:109], v[168:171], v[200:203], v[106:109]
	v_mfma_f32_16x16x32_bf16 v[94:97], v[160:163], v[208:211], v[94:97]
	v_mfma_f32_16x16x32_bf16 v[90:93], v[168:171], v[208:211], v[90:93]
	v_mfma_f32_16x16x32_bf16 v[78:81], v[160:163], v[216:219], v[78:81]
	v_mfma_f32_16x16x32_bf16 v[74:77], v[168:171], v[216:219], v[74:77]
	v_mfma_f32_16x16x32_bf16 v[118:121], v[172:175], v[188:191], v[118:121]
	v_mfma_f32_16x16x32_bf16 v[114:117], v[180:183], v[188:191], v[114:117]
	v_mfma_f32_16x16x32_bf16 v[102:105], v[172:175], v[196:199], v[102:105]
	v_mfma_f32_16x16x32_bf16 v[98:101], v[180:183], v[196:199], v[98:101]
	v_mfma_f32_16x16x32_bf16 v[86:89], v[172:175], v[204:207], v[86:89]
	v_mfma_f32_16x16x32_bf16 v[82:85], v[180:183], v[204:207], v[82:85]
	v_mfma_f32_16x16x32_bf16 v[70:73], v[172:175], v[212:215], v[70:73]
	v_mfma_f32_16x16x32_bf16 v[66:69], v[180:183], v[212:215], v[66:69]
	v_mfma_f32_16x16x32_bf16 v[118:121], v[176:179], v[192:195], v[118:121]
	v_mfma_f32_16x16x32_bf16 v[114:117], v[184:187], v[192:195], v[114:117]
	v_mfma_f32_16x16x32_bf16 v[102:105], v[176:179], v[200:203], v[102:105]
	v_mfma_f32_16x16x32_bf16 v[98:101], v[184:187], v[200:203], v[98:101]
	v_mfma_f32_16x16x32_bf16 v[86:89], v[176:179], v[208:211], v[86:89]
	v_mfma_f32_16x16x32_bf16 v[82:85], v[184:187], v[208:211], v[82:85]
	v_mfma_f32_16x16x32_bf16 v[70:73], v[176:179], v[216:219], v[70:73]
	v_mfma_f32_16x16x32_bf16 v[66:69], v[184:187], v[216:219], v[66:69]
	s_barrier
; #define PG8_STAGE(bufoff, gbase, voff) do { _Pragma("unroll") for (int _i = 0; _i < 2; ++_i) \
;         __builtin_amdgcn_global_load_lds((const unsigned*)((const char*)(gbase) + (voff)[_i]), (LAS unsigned*)(lds + (bufoff) + ldsw + _i * 8192), 16, 0, 0); } while (0)
; #define PG8_LDA(dst, b, h) do { _Pragma("unroll") for (int m = 0; m < 4; ++m) _Pragma("unroll") for (int k = 0; k < 2; ++k) dst[m][k] = *(const LAS bf16x8*)(lds + PG8_SA(b, h) + aoff + m * 2048 + k * 1024); } while (0)
; #define PG8_LDB(dst, b, h) do { _Pragma("unroll") for (int n = 0; n < 2; ++n) _Pragma("unroll") for (int k = 0; k < 2; ++k) dst[n][k] = *(const LAS bf16x8*)(lds + PG8_SB(b, h) + boff + n * 2048 + k * 1024); } while (0)
; #define PG8_MMA(ai, bj, At, Bt) do { __builtin_amdgcn_s_setprio(1); _Pragma("unroll") for (int m = 0; m < 4; ++m) _Pragma("unroll") for (int n = 0; n < 2; ++n) _Pragma("unroll") for (int k = 0; k < 2; ++k) \
;         acc[ai][bj][m][n] = __builtin_amdgcn_mfma_f32_16x16x32_bf16(Bt[n][k], At[m][k], acc[ai][bj][m][n], 0, 0, 0); __builtin_amdgcn_s_setprio(0); } while (0)
; #define PG8_WAIT_V(n) asm volatile("s_waitcnt vmcnt(" #n ")" ::: "memory")
; #define PG8_WAIT_L(n) asm volatile("s_waitcnt lgkmcnt(" #n ")" ::: "memory")
; #define PG8_BAR __builtin_amdgcn_s_barrier()
; #define PG8_SCHED __builtin_amdgcn_sched_barrier(0)
; template <class Epi, class Sched, bool ABLK = false, bool ALIGN_EPI = true, bool SP2 = true, bool BBLK = true>
; __device__ __forceinline__ void gemm_phase(LAS unsigned char* lds, const Gemm g, const Sched& S, const Epi& E) {
;     ...
;             PG8_LDB(B0, 0, 0); PG8_LDB(B1, 0, 1); PG8_SCHED; PG8_LDA(At, 0, 0); PG8_STAGE(PG8_SA(1, 1), a1 + hstepA, voffA);
;             PG8_WAIT_V(8); PG8_WAIT_L(0); PG8_BAR; PG8_MMA(0, 0, At, B0); PG8_MMA(0, 1, At, B1); PG8_BAR; PG8_SCHED;
;     ...
;             PG8_LDA(At, 1, 1); PG8_STAGE(PG8_SB(1, 0), b3, voffB); PG8_STAGE(PG8_SB(1, 1), b3 + hstepB, voffB); PG8_STAGE(PG8_SA(1, 0), a3, voffA);
;             PG8_WAIT_V(8); PG8_WAIT_L(0); PG8_BAR; PG8_MMA(1, 0, At, B0); PG8_MMA(1, 1, At, B1); PG8_BAR; PG8_SCHED;
	s_add_u32 s34, s30, 0x8000
	s_addc_u32 s35, s31, 0
	s_add_i32 s58, s60, s39
	s_mov_b32 m0, s58
	ds_read_b128 v[188:191], v154 offset:49152
	ds_read_b128 v[192:195], v154 offset:50176
	ds_read_b128 v[196:199], v154 offset:51200
	ds_read_b128 v[200:203], v154 offset:52224
	ds_read_b128 v[204:207], v154 offset:53248
	ds_read_b128 v[208:211], v154 offset:54272
	ds_read_b128 v[212:215], v154 offset:55296
	ds_read_b128 v[216:219], v154 offset:56320
	global_load_lds_dwordx4 v132, s[34:35]
	s_add_i32 m0, s58, 0x2000
	s_add_u32 s30, s30, 0xc000
	v_lshl_add_u64 v[220:221], s[34:35], 0, v[136:137]
	s_addc_u32 s31, s31, 0
	s_add_i32 s34, s61, s39
	global_load_lds_dwordx4 v[220:221], off
	s_mov_b32 m0, s34
	s_nop 0
	global_load_lds_dwordx4 v132, s[30:31]
	s_add_i32 m0, s34, 0x2000
	s_nop 0
	global_load_lds_dwordx4 v136, s[30:31]
	s_mov_b32 m0, s44
	s_nop 0
	global_load_lds_dwordx4 v130, s[28:29]
	s_mov_b32 m0, s45
	s_nop 0
	global_load_lds_dwordx4 v134, s[28:29]
	s_waitcnt vmcnt(8)
	s_barrier
	s_waitcnt lgkmcnt(0)
	v_mfma_f32_16x16x32_bf16 v[62:65], v[156:159], v[188:191], v[62:65]
	v_mfma_f32_16x16x32_bf16 v[58:61], v[164:167], v[188:191], v[58:61]
	v_mfma_f32_16x16x32_bf16 v[46:49], v[156:159], v[196:199], v[46:49]
	v_mfma_f32_16x16x32_bf16 v[42:45], v[164:167], v[196:199], v[42:45]
	v_mfma_f32_16x16x32_bf16 v[30:33], v[156:159], v[204:207], v[30:33]
	v_mfma_f32_16x16x32_bf16 v[26:29], v[164:167], v[204:207], v[26:29]
	v_mfma_f32_16x16x32_bf16 v[14:17], v[156:159], v[212:215], v[14:17]
	v_mfma_f32_16x16x32_bf16 v[10:13], v[164:167], v[212:215], v[10:13]
	v_mfma_f32_16x16x32_bf16 v[62:65], v[160:163], v[192:195], v[62:65]
	v_mfma_f32_16x16x32_bf16 v[58:61], v[168:171], v[192:195], v[58:61]
	v_mfma_f32_16x16x32_bf16 v[46:49], v[160:163], v[200:203], v[46:49]
	v_mfma_f32_16x16x32_bf16 v[42:45], v[168:171], v[200:203], v[42:45]
	v_mfma_f32_16x16x32_bf16 v[30:33], v[160:163], v[208:211], v[30:33]
	v_mfma_f32_16x16x32_bf16 v[26:29], v[168:171], v[208:211], v[26:29]
	v_mfma_f32_16x16x32_bf16 v[14:17], v[160:163], v[216:219], v[14:17]
	v_mfma_f32_16x16x32_bf16 v[10:13], v[168:171], v[216:219], v[10:13]
	v_mfma_f32_16x16x32_bf16 v[54:57], v[172:175], v[188:191], v[54:57]
	v_mfma_f32_16x16x32_bf16 v[50:53], v[180:183], v[188:191], v[50:53]
	v_mfma_f32_16x16x32_bf16 v[38:41], v[172:175], v[196:199], v[38:41]
	v_mfma_f32_16x16x32_bf16 v[34:37], v[180:183], v[196:199], v[34:37]
	v_mfma_f32_16x16x32_bf16 v[22:25], v[172:175], v[204:207], v[22:25]
	v_mfma_f32_16x16x32_bf16 v[18:21], v[180:183], v[204:207], v[18:21]
	v_mfma_f32_16x16x32_bf16 v[6:9], v[172:175], v[212:215], v[6:9]
	v_mfma_f32_16x16x32_bf16 v[2:5], v[180:183], v[212:215], v[2:5]
	v_mfma_f32_16x16x32_bf16 v[54:57], v[176:179], v[192:195], v[54:57]
	v_mfma_f32_16x16x32_bf16 v[50:53], v[184:187], v[192:195], v[50:53]
	v_mfma_f32_16x16x32_bf16 v[38:41], v[176:179], v[200:203], v[38:41]
	v_mfma_f32_16x16x32_bf16 v[34:37], v[184:187], v[200:203], v[34:37]
	v_mfma_f32_16x16x32_bf16 v[22:25], v[176:179], v[208:211], v[22:25]
	v_mfma_f32_16x16x32_bf16 v[18:21], v[184:187], v[208:211], v[18:21]
	v_mfma_f32_16x16x32_bf16 v[6:9], v[176:179], v[216:219], v[6:9]
	v_mfma_f32_16x16x32_bf16 v[2:5], v[184:187], v[216:219], v[2:5]
	s_barrier
	s_add_u32 s52, s52, 0x10000
	s_addc_u32 s53, s53, 0
	s_add_u32 s26, s26, 0x100
	s_addc_u32 s27, s27, 0
	s_cmp_ge_u32 s57, s47
.LBB0_1716:
	ds_read_b128 v[156:159], v152
	ds_read_b128 v[160:163], v152 offset:1024
	ds_read_b128 v[164:167], v152 offset:2048
	ds_read_b128 v[168:171], v152 offset:3072
	ds_read_b128 v[172:175], v153
	ds_read_b128 v[176:179], v153 offset:1024
	ds_read_b128 v[180:183], v153 offset:2048
	ds_read_b128 v[184:187], v153 offset:3072
	s_add_u32 s28, s54, s26
	s_addc_u32 s29, s55, s27
	s_add_u32 s34, s28, 0x100
	s_addc_u32 s35, s29, 0
	s_add_i32 s57, s57, 2
	s_add_u32 s28, s28, 0x180
	s_addc_u32 s29, s29, 0
	s_cmp_eq_u32 s56, s26
	s_cselect_b32 s29, s51, s29
	s_cselect_b32 s28, s50, s28
	s_cselect_b32 s31, s4, s53
	s_cselect_b32 s30, s5, s52
	s_cselect_b32 s35, s49, s35
	s_cselect_b32 s34, s23, s34
	v_lshl_add_u64 v[220:221], v[146:147], 0, s[26:27]
	s_add_i32 m0, s40, 0xc000
	ds_read_b128 v[188:191], v154
	ds_read_b128 v[192:195], v154 offset:1024
	ds_read_b128 v[196:199], v154 offset:2048
	ds_read_b128 v[200:203], v154 offset:3072
	ds_read_b128 v[204:207], v154 offset:4096
	ds_read_b128 v[208:211], v154 offset:5120
	ds_read_b128 v[212:215], v154 offset:6144
	ds_read_b128 v[216:219], v154 offset:7168
	global_load_lds_dwordx4 v[220:221], off
	v_lshl_add_u64 v[220:221], v[148:149], 0, s[26:27]
	s_add_i32 m0, s40, 0xe000
	s_nop 0
	global_load_lds_dwordx4 v[220:221], off
	s_waitcnt vmcnt(8)
	s_barrier
; #define PG8_STAGE(bufoff, gbase, voff) do { _Pragma("unroll") for (int _i = 0; _i < 2; ++_i) \
;         __builtin_amdgcn_global_load_lds((const unsigned*)((const char*)(gbase) + (voff)[_i]), (LAS unsigned*)(lds + (bufoff) + ldsw + _i * 8192), 16, 0, 0); } while (0)
; #define PG8_LDA(dst, b, h) do { _Pragma("unroll") for (int m = 0; m < 4; ++m) _Pragma("unroll") for (int k = 0; k < 2; ++k) dst[m][k] = *(const LAS bf16x8*)(lds + PG8_SA(b, h) + aoff + m * 2048 + k * 1024); } while (0)
; #define PG8_MMA(ai, bj, At, Bt) do { __builtin_amdgcn_s_setprio(1); _Pragma("unroll") for (int m = 0; m < 4; ++m) _Pragma("unroll") for (int n = 0; n < 2; ++n) _Pragma("unroll") for (int k = 0; k < 2; ++k) \
;         acc[ai][bj][m][n] = __builtin_amdgcn_mfma_f32_16x16x32_bf16(Bt[n][k], At[m][k], acc[ai][bj][m][n], 0, 0, 0); __builtin_amdgcn_s_setprio(0); } while (0)
; #define PG8_WAIT_V(n) asm volatile("s_waitcnt vmcnt(" #n ")" ::: "memory")
; #define PG8_WAIT_L(n) asm volatile("s_waitcnt lgkmcnt(" #n ")" ::: "memory")
; #define PG8_BAR __builtin_amdgcn_s_barrier()
; #define PG8_SCHED __builtin_amdgcn_sched_barrier(0)
; template <class Epi, class Sched, bool ABLK = false, bool ALIGN_EPI = true, bool SP2 = true, bool BBLK = true>
; __device__ __forceinline__ void gemm_phase(LAS unsigned char* lds, const Gemm g, const Sched& S, const Epi& E) {
;     ...
;             PG8_WAIT_V(8); PG8_WAIT_L(0); PG8_BAR; PG8_MMA(0, 0, At, B0); PG8_MMA(0, 1, At, B1); PG8_BAR; PG8_SCHED;
;             PG8_LDA(At, 0, 1); PG8_STAGE(PG8_SB(0, 0), b2, voffB); PG8_STAGE(PG8_SB(0, 1), b2 + hstepB, voffB); PG8_STAGE(PG8_SA(0, 0), a2, voffA);
;             PG8_WAIT_V(8); PG8_WAIT_L(0); PG8_BAR; PG8_MMA(1, 0, At, B0); PG8_MMA(1, 1, At, B1); PG8_BAR; PG8_SCHED;
	s_waitcnt lgkmcnt(0)
	v_mfma_f32_16x16x32_bf16 v[126:129], v[156:159], v[188:191], v[126:129]
	v_mfma_f32_16x16x32_bf16 v[122:125], v[164:167], v[188:191], v[122:125]
	v_mfma_f32_16x16x32_bf16 v[110:113], v[156:159], v[196:199], v[110:113]
	v_mfma_f32_16x16x32_bf16 v[106:109], v[164:167], v[196:199], v[106:109]
	v_mfma_f32_16x16x32_bf16 v[94:97], v[156:159], v[204:207], v[94:97]
	v_mfma_f32_16x16x32_bf16 v[90:93], v[164:167], v[204:207], v[90:93]
	v_mfma_f32_16x16x32_bf16 v[78:81], v[156:159], v[212:215], v[78:81]
	v_mfma_f32_16x16x32_bf16 v[74:77], v[164:167], v[212:215], v[74:77]
	v_mfma_f32_16x16x32_bf16 v[126:129], v[160:163], v[192:195], v[126:129]
	v_mfma_f32_16x16x32_bf16 v[122:125], v[168:171], v[192:195], v[122:125]
	v_mfma_f32_16x16x32_bf16 v[110:113], v[160:163], v[200:203], v[110:113]
	v_mfma_f32_16x16x32_bf16 v[106:109], v[168:171], v[200:203], v[106:109]
	v_mfma_f32_16x16x32_bf16 v[94:97], v[160:163], v[208:211], v[94:97]
	v_mfma_f32_16x16x32_bf16 v[90:93], v[168:171], v[208:211], v[90:93]
	v_mfma_f32_16x16x32_bf16 v[78:81], v[160:163], v[216:219], v[78:81]
	v_mfma_f32_16x16x32_bf16 v[74:77], v[168:171], v[216:219], v[74:77]
	v_mfma_f32_16x16x32_bf16 v[118:121], v[172:175], v[188:191], v[118:121]
	v_mfma_f32_16x16x32_bf16 v[114:117], v[180:183], v[188:191], v[114:117]
	v_mfma_f32_16x16x32_bf16 v[102:105], v[172:175], v[196:199], v[102:105]
	v_mfma_f32_16x16x32_bf16 v[98:101], v[180:183], v[196:199], v[98:101]
	v_mfma_f32_16x16x32_bf16 v[86:89], v[172:175], v[204:207], v[86:89]
	v_mfma_f32_16x16x32_bf16 v[82:85], v[180:183], v[204:207], v[82:85]
	v_mfma_f32_16x16x32_bf16 v[70:73], v[172:175], v[212:215], v[70:73]
	v_mfma_f32_16x16x32_bf16 v[66:69], v[180:183], v[212:215], v[66:69]
	v_mfma_f32_16x16x32_bf16 v[118:121], v[176:179], v[192:195], v[118:121]
	v_mfma_f32_16x16x32_bf16 v[114:117], v[184:187], v[192:195], v[114:117]
	v_mfma_f32_16x16x32_bf16 v[102:105], v[176:179], v[200:203], v[102:105]
	v_mfma_f32_16x16x32_bf16 v[98:101], v[184:187], v[200:203], v[98:101]
	v_mfma_f32_16x16x32_bf16 v[86:89], v[176:179], v[208:211], v[86:89]
	v_mfma_f32_16x16x32_bf16 v[82:85], v[184:187], v[208:211], v[82:85]
	v_mfma_f32_16x16x32_bf16 v[70:73], v[176:179], v[216:219], v[70:73]
	v_mfma_f32_16x16x32_bf16 v[66:69], v[184:187], v[216:219], v[66:69]
	s_barrier
	s_add_i32 s58, s72, s39
	s_mov_b32 m0, s58
	ds_read_b128 v[188:191], v154 offset:16384
	ds_read_b128 v[192:195], v154 offset:17408
	ds_read_b128 v[196:199], v154 offset:18432
	ds_read_b128 v[200:203], v154 offset:19456
	ds_read_b128 v[204:207], v154 offset:20480
	ds_read_b128 v[208:211], v154 offset:21504
	ds_read_b128 v[212:215], v154 offset:22528
	ds_read_b128 v[216:219], v154 offset:23552
	global_load_lds_dwordx4 v132, s[30:31]
	s_add_i32 m0, s58, 0x2000
	s_add_u32 s58, s30, 0x4000
	s_addc_u32 s59, s31, 0
	s_add_i32 s64, s73, s39
	global_load_lds_dwordx4 v136, s[30:31]
	s_mov_b32 m0, s64
	s_nop 0
	global_load_lds_dwordx4 v132, s[58:59]
	s_add_i32 m0, s64, 0x2000
	s_nop 0
	global_load_lds_dwordx4 v136, s[58:59]
	s_mov_b32 m0, s40
	s_nop 0
	global_load_lds_dwordx4 v130, s[34:35]
	s_mov_b32 m0, s41
	s_nop 0
	global_load_lds_dwordx4 v134, s[34:35]
	s_waitcnt vmcnt(8)
	s_barrier
	s_waitcnt lgkmcnt(0)
	v_mfma_f32_16x16x32_bf16 v[62:65], v[156:159], v[188:191], v[62:65]
	v_mfma_f32_16x16x32_bf16 v[58:61], v[164:167], v[188:191], v[58:61]
	v_mfma_f32_16x16x32_bf16 v[46:49], v[156:159], v[196:199], v[46:49]
	v_mfma_f32_16x16x32_bf16 v[42:45], v[164:167], v[196:199], v[42:45]
	v_mfma_f32_16x16x32_bf16 v[30:33], v[156:159], v[204:207], v[30:33]
	v_mfma_f32_16x16x32_bf16 v[26:29], v[164:167], v[204:207], v[26:29]
	v_mfma_f32_16x16x32_bf16 v[14:17], v[156:159], v[212:215], v[14:17]
	v_mfma_f32_16x16x32_bf16 v[10:13], v[164:167], v[212:215], v[10:13]
	v_mfma_f32_16x16x32_bf16 v[62:65], v[160:163], v[192:195], v[62:65]
	v_mfma_f32_16x16x32_bf16 v[58:61], v[168:171], v[192:195], v[58:61]
	v_mfma_f32_16x16x32_bf16 v[46:49], v[160:163], v[200:203], v[46:49]
	v_mfma_f32_16x16x32_bf16 v[42:45], v[168:171], v[200:203], v[42:45]
	v_mfma_f32_16x16x32_bf16 v[30:33], v[160:163], v[208:211], v[30:33]
	v_mfma_f32_16x16x32_bf16 v[26:29], v[168:171], v[208:211], v[26:29]
	v_mfma_f32_16x16x32_bf16 v[14:17], v[160:163], v[216:219], v[14:17]
	v_mfma_f32_16x16x32_bf16 v[10:13], v[168:171], v[216:219], v[10:13]
	v_mfma_f32_16x16x32_bf16 v[54:57], v[172:175], v[188:191], v[54:57]
	v_mfma_f32_16x16x32_bf16 v[50:53], v[180:183], v[188:191], v[50:53]
	v_mfma_f32_16x16x32_bf16 v[38:41], v[172:175], v[196:199], v[38:41]
	v_mfma_f32_16x16x32_bf16 v[34:37], v[180:183], v[196:199], v[34:37]
	v_mfma_f32_16x16x32_bf16 v[22:25], v[172:175], v[204:207], v[22:25]
	v_mfma_f32_16x16x32_bf16 v[18:21], v[180:183], v[204:207], v[18:21]
	v_mfma_f32_16x16x32_bf16 v[6:9], v[172:175], v[212:215], v[6:9]
	v_mfma_f32_16x16x32_bf16 v[2:5], v[180:183], v[212:215], v[2:5]
	v_mfma_f32_16x16x32_bf16 v[54:57], v[176:179], v[192:195], v[54:57]
	v_mfma_f32_16x16x32_bf16 v[50:53], v[184:187], v[192:195], v[50:53]
	v_mfma_f32_16x16x32_bf16 v[38:41], v[176:179], v[200:203], v[38:41]
	v_mfma_f32_16x16x32_bf16 v[34:37], v[184:187], v[200:203], v[34:37]
	v_mfma_f32_16x16x32_bf16 v[22:25], v[176:179], v[208:211], v[22:25]
	v_mfma_f32_16x16x32_bf16 v[18:21], v[184:187], v[208:211], v[18:21]
	v_mfma_f32_16x16x32_bf16 v[6:9], v[176:179], v[216:219], v[6:9]
	v_mfma_f32_16x16x32_bf16 v[2:5], v[184:187], v[216:219], v[2:5]
	s_barrier
; #define PG8_STAGE(bufoff, gbase, voff) do { _Pragma("unroll") for (int _i = 0; _i < 2; ++_i) \
;         __builtin_amdgcn_global_load_lds((const unsigned*)((const char*)(gbase) + (voff)[_i]), (LAS unsigned*)(lds + (bufoff) + ldsw + _i * 8192), 16, 0, 0); } while (0)
; #define PG8_LDA(dst, b, h) do { _Pragma("unroll") for (int m = 0; m < 4; ++m) _Pragma("unroll") for (int k = 0; k < 2; ++k) dst[m][k] = *(const LAS bf16x8*)(lds + PG8_SA(b, h) + aoff + m * 2048 + k * 1024); } while (0)
; #define PG8_LDB(dst, b, h) do { _Pragma("unroll") for (int n = 0; n < 2; ++n) _Pragma("unroll") for (int k = 0; k < 2; ++k) dst[n][k] = *(const LAS bf16x8*)(lds + PG8_SB(b, h) + boff + n * 2048 + k * 1024); } while (0)
; #define PG8_MMA(ai, bj, At, Bt) do { __builtin_amdgcn_s_setprio(1); _Pragma("unroll") for (int m = 0; m < 4; ++m) _Pragma("unroll") for (int n = 0; n < 2; ++n) _Pragma("unroll") for (int k = 0; k < 2; ++k) \
;         acc[ai][bj][m][n] = __builtin_amdgcn_mfma_f32_16x16x32_bf16(Bt[n][k], At[m][k], acc[ai][bj][m][n], 0, 0, 0); __builtin_amdgcn_s_setprio(0); } while (0)
; #define PG8_WAIT_V(n) asm volatile("s_waitcnt vmcnt(" #n ")" ::: "memory")
; #define PG8_WAIT_L(n) asm volatile("s_waitcnt lgkmcnt(" #n ")" ::: "memory")
; #define PG8_BAR __builtin_amdgcn_s_barrier()
; #define PG8_SCHED __builtin_amdgcn_sched_barrier(0)
; template <class Epi, class Sched, bool ABLK = false, bool ALIGN_EPI = true, bool SP2 = true, bool BBLK = true>
; __device__ __forceinline__ void gemm_phase(LAS unsigned char* lds, const Gemm g, const Sched& S, const Epi& E) {
;     ...
;             PG8_LDB(B0, 1, 0); PG8_LDB(B1, 1, 1); PG8_SCHED; PG8_LDA(At, 1, 0); PG8_STAGE(PG8_SA(0, 1), a2 + hstepA, voffA);
;             PG8_WAIT_V(8); PG8_WAIT_L(0); PG8_BAR; PG8_MMA(0, 0, At, B0); PG8_MMA(0, 1, At, B1); PG8_BAR; PG8_SCHED;
;             PG8_LDA(At, 1, 1); PG8_STAGE(PG8_SB(1, 0), b3, voffB); PG8_STAGE(PG8_SB(1, 1), b3 + hstepB, voffB); PG8_STAGE(PG8_SA(1, 0), a3, voffA);
;             PG8_WAIT_V(8); PG8_WAIT_L(0); PG8_BAR; PG8_MMA(1, 0, At, B0); PG8_MMA(1, 1, At, B1); PG8_BAR; PG8_SCHED;
;     ...
;         if constexpr (ALIGN_EPI) { if (wr == 0) PG8_BAR; }
	v_add_u32_e32 v155, s60, v150
	ds_read_b128 v[156:159], v155
	ds_read_b128 v[160:163], v155 offset:1024
	ds_read_b128 v[164:167], v155 offset:2048
	ds_read_b128 v[168:171], v155 offset:3072
	v_add_u32_e32 v155, s61, v150
	ds_read_b128 v[172:175], v155
	ds_read_b128 v[176:179], v155 offset:1024
	ds_read_b128 v[180:183], v155 offset:2048
	ds_read_b128 v[184:187], v155 offset:3072
	s_add_u32 s34, s34, 0x80000
	s_addc_u32 s35, s35, 0
	s_mov_b32 m0, s42
	ds_read_b128 v[188:191], v154 offset:32768
	ds_read_b128 v[192:195], v154 offset:33792
	ds_read_b128 v[196:199], v154 offset:34816
	ds_read_b128 v[200:203], v154 offset:35840
	ds_read_b128 v[204:207], v154 offset:36864
	ds_read_b128 v[208:211], v154 offset:37888
	ds_read_b128 v[212:215], v154 offset:38912
	ds_read_b128 v[216:219], v154 offset:39936
	global_load_lds_dwordx4 v130, s[34:35]
	s_mov_b32 m0, s43
	s_nop 0
	global_load_lds_dwordx4 v134, s[34:35]
	s_waitcnt vmcnt(8)
	s_barrier
	s_waitcnt lgkmcnt(0)
	v_mfma_f32_16x16x32_bf16 v[126:129], v[156:159], v[188:191], v[126:129]
	v_mfma_f32_16x16x32_bf16 v[122:125], v[164:167], v[188:191], v[122:125]
	v_mfma_f32_16x16x32_bf16 v[110:113], v[156:159], v[196:199], v[110:113]
	v_mfma_f32_16x16x32_bf16 v[106:109], v[164:167], v[196:199], v[106:109]
	v_mfma_f32_16x16x32_bf16 v[94:97], v[156:159], v[204:207], v[94:97]
	v_mfma_f32_16x16x32_bf16 v[90:93], v[164:167], v[204:207], v[90:93]
	v_mfma_f32_16x16x32_bf16 v[78:81], v[156:159], v[212:215], v[78:81]
	v_mfma_f32_16x16x32_bf16 v[74:77], v[164:167], v[212:215], v[74:77]
	v_mfma_f32_16x16x32_bf16 v[126:129], v[160:163], v[192:195], v[126:129]
	v_mfma_f32_16x16x32_bf16 v[122:125], v[168:171], v[192:195], v[122:125]
	v_mfma_f32_16x16x32_bf16 v[110:113], v[160:163], v[200:203], v[110:113]
	v_mfma_f32_16x16x32_bf16 v[106:109], v[168:171], v[200:203], v[106:109]
	v_mfma_f32_16x16x32_bf16 v[94:97], v[160:163], v[208:211], v[94:97]
	v_mfma_f32_16x16x32_bf16 v[90:93], v[168:171], v[208:211], v[90:93]
	v_mfma_f32_16x16x32_bf16 v[78:81], v[160:163], v[216:219], v[78:81]
	v_mfma_f32_16x16x32_bf16 v[74:77], v[168:171], v[216:219], v[74:77]
	v_mfma_f32_16x16x32_bf16 v[118:121], v[172:175], v[188:191], v[118:121]
	v_mfma_f32_16x16x32_bf16 v[114:117], v[180:183], v[188:191], v[114:117]
	v_mfma_f32_16x16x32_bf16 v[102:105], v[172:175], v[196:199], v[102:105]
	v_mfma_f32_16x16x32_bf16 v[98:101], v[180:183], v[196:199], v[98:101]
	v_mfma_f32_16x16x32_bf16 v[86:89], v[172:175], v[204:207], v[86:89]
	v_mfma_f32_16x16x32_bf16 v[82:85], v[180:183], v[204:207], v[82:85]
	v_mfma_f32_16x16x32_bf16 v[70:73], v[172:175], v[212:215], v[70:73]
	v_mfma_f32_16x16x32_bf16 v[66:69], v[180:183], v[212:215], v[66:69]
	v_mfma_f32_16x16x32_bf16 v[118:121], v[176:179], v[192:195], v[118:121]
	v_mfma_f32_16x16x32_bf16 v[114:117], v[184:187], v[192:195], v[114:117]
	v_mfma_f32_16x16x32_bf16 v[102:105], v[176:179], v[200:203], v[102:105]
	v_mfma_f32_16x16x32_bf16 v[98:101], v[184:187], v[200:203], v[98:101]
	v_mfma_f32_16x16x32_bf16 v[86:89], v[176:179], v[208:211], v[86:89]
	v_mfma_f32_16x16x32_bf16 v[82:85], v[184:187], v[208:211], v[82:85]
	v_mfma_f32_16x16x32_bf16 v[70:73], v[176:179], v[216:219], v[70:73]
	v_mfma_f32_16x16x32_bf16 v[66:69], v[184:187], v[216:219], v[66:69]
	s_barrier
	s_add_u32 s34, s30, 0x8000
	s_addc_u32 s35, s31, 0
	s_add_i32 s58, s60, s39
	s_mov_b32 m0, s58
	ds_read_b128 v[188:191], v154 offset:49152
	ds_read_b128 v[192:195], v154 offset:50176
	ds_read_b128 v[196:199], v154 offset:51200
	ds_read_b128 v[200:203], v154 offset:52224
	ds_read_b128 v[204:207], v154 offset:53248
	ds_read_b128 v[208:211], v154 offset:54272
	ds_read_b128 v[212:215], v154 offset:55296
	ds_read_b128 v[216:219], v154 offset:56320
	global_load_lds_dwordx4 v132, s[34:35]
	s_add_i32 m0, s58, 0x2000
	s_add_u32 s30, s30, 0xc000
	v_lshl_add_u64 v[220:221], s[34:35], 0, v[136:137]
	s_addc_u32 s31, s31, 0
	s_add_i32 s34, s61, s39
	global_load_lds_dwordx4 v[220:221], off
	s_mov_b32 m0, s34
	s_nop 0
	global_load_lds_dwordx4 v132, s[30:31]
	s_add_i32 m0, s34, 0x2000
	s_nop 0
	global_load_lds_dwordx4 v136, s[30:31]
	s_mov_b32 m0, s44
	s_nop 0
	global_load_lds_dwordx4 v130, s[28:29]
	s_mov_b32 m0, s45
	s_nop 0
	global_load_lds_dwordx4 v134, s[28:29]
	s_waitcnt vmcnt(8)
	s_barrier
	s_waitcnt lgkmcnt(0)
	v_mfma_f32_16x16x32_bf16 v[62:65], v[156:159], v[188:191], v[62:65]
	v_mfma_f32_16x16x32_bf16 v[58:61], v[164:167], v[188:191], v[58:61]
	v_mfma_f32_16x16x32_bf16 v[46:49], v[156:159], v[196:199], v[46:49]
	v_mfma_f32_16x16x32_bf16 v[42:45], v[164:167], v[196:199], v[42:45]
	v_mfma_f32_16x16x32_bf16 v[30:33], v[156:159], v[204:207], v[30:33]
	v_mfma_f32_16x16x32_bf16 v[26:29], v[164:167], v[204:207], v[26:29]
	v_mfma_f32_16x16x32_bf16 v[14:17], v[156:159], v[212:215], v[14:17]
	v_mfma_f32_16x16x32_bf16 v[10:13], v[164:167], v[212:215], v[10:13]
	v_mfma_f32_16x16x32_bf16 v[62:65], v[160:163], v[192:195], v[62:65]
	v_mfma_f32_16x16x32_bf16 v[58:61], v[168:171], v[192:195], v[58:61]
	v_mfma_f32_16x16x32_bf16 v[46:49], v[160:163], v[200:203], v[46:49]
	v_mfma_f32_16x16x32_bf16 v[42:45], v[168:171], v[200:203], v[42:45]
	v_mfma_f32_16x16x32_bf16 v[30:33], v[160:163], v[208:211], v[30:33]
	v_mfma_f32_16x16x32_bf16 v[26:29], v[168:171], v[208:211], v[26:29]
	v_mfma_f32_16x16x32_bf16 v[14:17], v[160:163], v[216:219], v[14:17]
	v_mfma_f32_16x16x32_bf16 v[10:13], v[168:171], v[216:219], v[10:13]
	v_mfma_f32_16x16x32_bf16 v[54:57], v[172:175], v[188:191], v[54:57]
	v_mfma_f32_16x16x32_bf16 v[50:53], v[180:183], v[188:191], v[50:53]
	v_mfma_f32_16x16x32_bf16 v[38:41], v[172:175], v[196:199], v[38:41]
	v_mfma_f32_16x16x32_bf16 v[34:37], v[180:183], v[196:199], v[34:37]
	v_mfma_f32_16x16x32_bf16 v[22:25], v[172:175], v[204:207], v[22:25]
	v_mfma_f32_16x16x32_bf16 v[18:21], v[180:183], v[204:207], v[18:21]
	v_mfma_f32_16x16x32_bf16 v[6:9], v[172:175], v[212:215], v[6:9]
	v_mfma_f32_16x16x32_bf16 v[2:5], v[180:183], v[212:215], v[2:5]
	v_mfma_f32_16x16x32_bf16 v[54:57], v[176:179], v[192:195], v[54:57]
	v_mfma_f32_16x16x32_bf16 v[50:53], v[184:187], v[192:195], v[50:53]
	v_mfma_f32_16x16x32_bf16 v[38:41], v[176:179], v[200:203], v[38:41]
	v_mfma_f32_16x16x32_bf16 v[34:37], v[184:187], v[200:203], v[34:37]
	v_mfma_f32_16x16x32_bf16 v[22:25], v[176:179], v[208:211], v[22:25]
	v_mfma_f32_16x16x32_bf16 v[18:21], v[184:187], v[208:211], v[18:21]
	v_mfma_f32_16x16x32_bf16 v[6:9], v[176:179], v[216:219], v[6:9]
	v_mfma_f32_16x16x32_bf16 v[2:5], v[184:187], v[216:219], v[2:5]
	s_barrier
	s_add_u32 s52, s52, 0x10000
	s_addc_u32 s53, s53, 0
	s_add_u32 s26, s26, 0x100
	s_addc_u32 s27, s27, 0
	s_cmp_ge_u32 s57, s47
	s_cbranch_scc0 .LBB0_1716
	s_and_b64 vcc, exec, s[6:7]
	s_cbranch_vccz .LBB0_1719
	s_barrier

; #define PG8_STAGE(bufoff, gbase, voff) do { _Pragma("unroll") for (int _i = 0; _i < 2; ++_i) \
;         __builtin_amdgcn_global_load_lds((const unsigned*)((const char*)(gbase) + (voff)[_i]), (LAS unsigned*)(lds + (bufoff) + ldsw + _i * 8192), 16, 0, 0); } while (0)
; #define PG8_LDA(dst, b, h) do { _Pragma("unroll") for (int m = 0; m < 4; ++m) _Pragma("unroll") for (int k = 0; k < 2; ++k) dst[m][k] = *(const LAS bf16x8*)(lds + PG8_SA(b, h) + aoff + m * 2048 + k * 1024); } while (0)
; #define PG8_LDB(dst, b, h) do { _Pragma("unroll") for (int n = 0; n < 2; ++n) _Pragma("unroll") for (int k = 0; k < 2; ++k) dst[n][k] = *(const LAS bf16x8*)(lds + PG8_SB(b, h) + boff + n * 2048 + k * 1024); } while (0)
; #define PG8_WAIT_V(n) asm volatile("s_waitcnt vmcnt(" #n ")" ::: "memory")
; #define PG8_WAIT_L(n) asm volatile("s_waitcnt lgkmcnt(" #n ")" ::: "memory")
; #define PG8_BAR __builtin_amdgcn_s_barrier()
; #define PG8_SCHED __builtin_amdgcn_sched_barrier(0)
; template <class Epi, class Sched, bool ABLK = false, bool ALIGN_EPI = true, bool SP2 = true, bool BBLK = true>
; __device__ __forceinline__ void gemm_phase(LAS unsigned char* lds, const Gemm g, const Sched& S, const Epi& E) {
;     ...
;         const bool has_next = S.next(ui + 1, nxt);
;         const int nt = cur.nt;
;         const char* nuA = has_next ? a_unit(nxt) : uA; const int ntbA = has_next ? nxt.k0 / BK : tbA; const char* nB = has_next ? (const char*)g.Bt + (size_t)nxt.pn * tstepB + b_k0(nxt.k0) : cB;
;         for (int t = 0; t < nt; t += 2) {
;             const bool last = (t == nt - 2);
;             const char* a1 = a_tile(uA, tbA + t + 1);
;             const char* a2 = last ? a_tile(nuA, ntbA) : a_tile(uA, tbA + t + 2); const char* b2 = last ? nB : cB + (size_t)(t + 2) * kstepB;
;             const char* a3 = last ? a_tile(nuA, ntbA + 1) : a_tile(uA, tbA + t + 3); const char* b3 = b2 + kstepB;
;             if (last && has_next) S.a_ready(nxt);
;             if constexpr (SP2) {
;             PG8_LDB(B0, 0, 0); PG8_LDB(B1, 0, 1); PG8_SCHED; PG8_LDA(At, 0, 0); PG8_STAGE(PG8_SA(1, 1), a1 + hstepA, voffA);
;             PG8_WAIT_V(8); PG8_WAIT_L(0); PG8_BAR; PG8_MMA(0, 0, At, B0); PG8_MMA(0, 1, At, B1); PG8_BAR; PG8_SCHED;
;             PG8_LDA(At, 0, 1); PG8_STAGE(PG8_SB(0, 0), b2, voffB); PG8_STAGE(PG8_SB(0, 1), b2 + hstepB, voffB); PG8_STAGE(PG8_SA(0, 0), a2, voffA);
.LBB0_1841:
	s_ashr_i32 s11, s10, 31
	s_lshl_b64 s[4:5], s[10:11], 20
	s_add_u32 s16, s76, s4
	s_addc_u32 s17, s33, s5
	s_and_b64 s[4:5], s[18:19], exec
	s_cselect_b32 s4, s17, s27
	s_cselect_b32 s5, s16, s26
	s_ashr_i32 s15, s14, 31
	s_lshl_b64 s[20:21], s[14:15], 20
	s_add_u32 s20, s1, s20
	s_addc_u32 s21, s38, s21
	s_and_b64 s[30:31], s[18:19], exec
	s_cselect_b32 s11, s21, s29
	s_cselect_b32 s15, s20, s28
	s_add_u32 s23, s5, 0x80
	s_addc_u32 s51, s4, 0
	s_add_u32 s52, s28, 0x10000
	v_mov_b32_e32 v2, 0
	s_addc_u32 s53, s29, 0
	v_lshl_add_u64 v[164:165], s[26:27], 0, v[160:161]
	v_lshl_add_u64 v[166:167], s[26:27], 0, v[162:163]
	s_mov_b32 s54, -2
	s_mov_b64 s[28:29], 0
	ds_read_b128 v[172:175], v168
	ds_read_b128 v[176:179], v168 offset:1024
	ds_read_b128 v[180:183], v168 offset:2048
	ds_read_b128 v[184:187], v168 offset:3072
	ds_read_b128 v[188:191], v169
	ds_read_b128 v[192:195], v169 offset:1024
	ds_read_b128 v[196:199], v169 offset:2048
	ds_read_b128 v[200:203], v169 offset:3072
	s_add_u32 s30, s26, s28
	s_addc_u32 s31, s27, s29
	s_add_u32 s36, s30, 0x100
	s_addc_u32 s37, s31, 0
	s_add_u32 s30, s30, 0x180
	s_addc_u32 s31, s31, 0
	s_cmpk_eq_i32 s28, 0xf00
	s_cselect_b32 s31, s51, s31
	s_cselect_b32 s30, s23, s30
	s_cselect_b32 s35, s11, s53
	s_cselect_b32 s34, s15, s52
	s_cselect_b32 s37, s4, s37
	s_cselect_b32 s36, s5, s36
	s_mov_b32 m0, s47
	v_lshl_add_u64 v[236:237], v[164:165], 0, s[28:29]
	ds_read_b128 v[204:207], v170
	ds_read_b128 v[208:211], v170 offset:1024
	ds_read_b128 v[212:215], v170 offset:2048
	ds_read_b128 v[216:219], v170 offset:3072
	ds_read_b128 v[220:223], v170 offset:4096
	ds_read_b128 v[224:227], v170 offset:5120
	ds_read_b128 v[228:231], v170 offset:6144
	ds_read_b128 v[232:235], v170 offset:7168
	global_load_lds_dwordx4 v[236:237], off
	v_lshl_add_u64 v[236:237], v[166:167], 0, s[28:29]
	s_mov_b32 m0, s48
	s_nop 0
	global_load_lds_dwordx4 v[236:237], off
	s_waitcnt vmcnt(8)
	s_barrier
	s_waitcnt lgkmcnt(0)
	v_mfma_f32_16x16x32_bf16 v[126:129], v[172:175], v[204:207], 0
	v_mfma_f32_16x16x32_bf16 v[122:125], v[180:183], v[204:207], 0
	v_mfma_f32_16x16x32_bf16 v[110:113], v[172:175], v[212:215], 0
	v_mfma_f32_16x16x32_bf16 v[106:109], v[180:183], v[212:215], 0
	v_mfma_f32_16x16x32_bf16 v[94:97], v[172:175], v[220:223], 0
	v_mfma_f32_16x16x32_bf16 v[90:93], v[180:183], v[220:223], 0
	v_mfma_f32_16x16x32_bf16 v[78:81], v[172:175], v[228:231], 0
	v_mfma_f32_16x16x32_bf16 v[74:77], v[180:183], v[228:231], 0
	v_mfma_f32_16x16x32_bf16 v[126:129], v[176:179], v[208:211], v[126:129]
	v_mfma_f32_16x16x32_bf16 v[122:125], v[184:187], v[208:211], v[122:125]
	v_mfma_f32_16x16x32_bf16 v[110:113], v[176:179], v[216:219], v[110:113]
	v_mfma_f32_16x16x32_bf16 v[106:109], v[184:187], v[216:219], v[106:109]
	v_mfma_f32_16x16x32_bf16 v[94:97], v[176:179], v[224:227], v[94:97]
	v_mfma_f32_16x16x32_bf16 v[90:93], v[184:187], v[224:227], v[90:93]
	v_mfma_f32_16x16x32_bf16 v[78:81], v[176:179], v[232:235], v[78:81]
	v_mfma_f32_16x16x32_bf16 v[74:77], v[184:187], v[232:235], v[74:77]
	v_mfma_f32_16x16x32_bf16 v[118:121], v[188:191], v[204:207], 0
	v_mfma_f32_16x16x32_bf16 v[114:117], v[196:199], v[204:207], 0
	v_mfma_f32_16x16x32_bf16 v[102:105], v[188:191], v[212:215], 0
	v_mfma_f32_16x16x32_bf16 v[98:101], v[196:199], v[212:215], 0
	v_mfma_f32_16x16x32_bf16 v[86:89], v[188:191], v[220:223], 0
	v_mfma_f32_16x16x32_bf16 v[82:85], v[196:199], v[220:223], 0
	v_mfma_f32_16x16x32_bf16 v[70:73], v[188:191], v[228:231], 0
	v_mfma_f32_16x16x32_bf16 v[66:69], v[196:199], v[228:231], 0
	v_mfma_f32_16x16x32_bf16 v[118:121], v[192:195], v[208:211], v[118:121]
	v_mfma_f32_16x16x32_bf16 v[114:117], v[200:203], v[208:211], v[114:117]
	v_mfma_f32_16x16x32_bf16 v[102:105], v[192:195], v[216:219], v[102:105]
	v_mfma_f32_16x16x32_bf16 v[98:101], v[200:203], v[216:219], v[98:101]
	v_mfma_f32_16x16x32_bf16 v[86:89], v[192:195], v[224:227], v[86:89]
	v_mfma_f32_16x16x32_bf16 v[82:85], v[200:203], v[224:227], v[82:85]
	v_mfma_f32_16x16x32_bf16 v[70:73], v[192:195], v[232:235], v[70:73]
	v_mfma_f32_16x16x32_bf16 v[66:69], v[200:203], v[232:235], v[66:69]
	s_barrier
	s_mov_b32 m0, s49
	s_add_u32 s56, s34, 0x4000
	ds_read_b128 v[204:207], v170 offset:16384
	ds_read_b128 v[208:211], v170 offset:17408
	ds_read_b128 v[212:215], v170 offset:18432
	ds_read_b128 v[216:219], v170 offset:19456
	ds_read_b128 v[220:223], v170 offset:20480
	ds_read_b128 v[224:227], v170 offset:21504
	ds_read_b128 v[228:231], v170 offset:22528
	ds_read_b128 v[232:235], v170 offset:23552
	global_load_lds_dwordx4 v134, s[34:35]
	s_mov_b32 m0, s50
	s_addc_u32 s57, s35, 0
	s_add_i32 s55, s73, s39
	global_load_lds_dwordx4 v130, s[34:35]
	s_mov_b32 m0, s55
	s_nop 0
	global_load_lds_dwordx4 v134, s[56:57]
	s_add_i32 m0, s55, 0x2000
	s_nop 0
	global_load_lds_dwordx4 v130, s[56:57]
	s_mov_b32 m0, s25
	s_nop 0
	global_load_lds_dwordx4 v136, s[36:37]
	s_mov_b32 m0, s40
	s_nop 0
	global_load_lds_dwordx4 v132, s[36:37]
	s_waitcnt vmcnt(8)
	s_barrier
; #define PG8_STAGE(bufoff, gbase, voff) do { _Pragma("unroll") for (int _i = 0; _i < 2; ++_i) \
;         __builtin_amdgcn_global_load_lds((const unsigned*)((const char*)(gbase) + (voff)[_i]), (LAS unsigned*)(lds + (bufoff) + ldsw + _i * 8192), 16, 0, 0); } while (0)
; #define PG8_LDA(dst, b, h) do { _Pragma("unroll") for (int m = 0; m < 4; ++m) _Pragma("unroll") for (int k = 0; k < 2; ++k) dst[m][k] = *(const LAS bf16x8*)(lds + PG8_SA(b, h) + aoff + m * 2048 + k * 1024); } while (0)
; #define PG8_LDB(dst, b, h) do { _Pragma("unroll") for (int n = 0; n < 2; ++n) _Pragma("unroll") for (int k = 0; k < 2; ++k) dst[n][k] = *(const LAS bf16x8*)(lds + PG8_SB(b, h) + boff + n * 2048 + k * 1024); } while (0)
; #define PG8_MMA(ai, bj, At, Bt) do { __builtin_amdgcn_s_setprio(1); _Pragma("unroll") for (int m = 0; m < 4; ++m) _Pragma("unroll") for (int n = 0; n < 2; ++n) _Pragma("unroll") for (int k = 0; k < 2; ++k) \
;         acc[ai][bj][m][n] = __builtin_amdgcn_mfma_f32_16x16x32_bf16(Bt[n][k], At[m][k], acc[ai][bj][m][n], 0, 0, 0); __builtin_amdgcn_s_setprio(0); } while (0)
; #define PG8_WAIT_V(n) asm volatile("s_waitcnt vmcnt(" #n ")" ::: "memory")
; #define PG8_WAIT_L(n) asm volatile("s_waitcnt lgkmcnt(" #n ")" ::: "memory")
; #define PG8_BAR __builtin_amdgcn_s_barrier()
; #define PG8_SCHED __builtin_amdgcn_sched_barrier(0)
; template <class Epi, class Sched, bool ABLK = false, bool ALIGN_EPI = true, bool SP2 = true, bool BBLK = true>
; __device__ __forceinline__ void gemm_phase(LAS unsigned char* lds, const Gemm g, const Sched& S, const Epi& E) {
;     ...
;             PG8_WAIT_V(8); PG8_WAIT_L(0); PG8_BAR; PG8_MMA(1, 0, At, B0); PG8_MMA(1, 1, At, B1); PG8_BAR; PG8_SCHED;
;             PG8_LDB(B0, 1, 0); PG8_LDB(B1, 1, 1); PG8_SCHED; PG8_LDA(At, 1, 0); PG8_STAGE(PG8_SA(0, 1), a2 + hstepA, voffA);
;             PG8_WAIT_V(8); PG8_WAIT_L(0); PG8_BAR; PG8_MMA(0, 0, At, B0); PG8_MMA(0, 1, At, B1); PG8_BAR; PG8_SCHED;
	s_waitcnt lgkmcnt(0)
	v_mfma_f32_16x16x32_bf16 v[62:65], v[172:175], v[204:207], 0
	v_mfma_f32_16x16x32_bf16 v[58:61], v[180:183], v[204:207], 0
	v_mfma_f32_16x16x32_bf16 v[46:49], v[172:175], v[212:215], 0
	v_mfma_f32_16x16x32_bf16 v[42:45], v[180:183], v[212:215], 0
	v_mfma_f32_16x16x32_bf16 v[30:33], v[172:175], v[220:223], 0
	v_mfma_f32_16x16x32_bf16 v[26:29], v[180:183], v[220:223], 0
	v_mfma_f32_16x16x32_bf16 v[14:17], v[172:175], v[228:231], 0
	v_mfma_f32_16x16x32_bf16 v[10:13], v[180:183], v[228:231], 0
	v_mfma_f32_16x16x32_bf16 v[62:65], v[176:179], v[208:211], v[62:65]
	v_mfma_f32_16x16x32_bf16 v[58:61], v[184:187], v[208:211], v[58:61]
	v_mfma_f32_16x16x32_bf16 v[46:49], v[176:179], v[216:219], v[46:49]
	v_mfma_f32_16x16x32_bf16 v[42:45], v[184:187], v[216:219], v[42:45]
	v_mfma_f32_16x16x32_bf16 v[30:33], v[176:179], v[224:227], v[30:33]
	v_mfma_f32_16x16x32_bf16 v[26:29], v[184:187], v[224:227], v[26:29]
	v_mfma_f32_16x16x32_bf16 v[14:17], v[176:179], v[232:235], v[14:17]
	v_mfma_f32_16x16x32_bf16 v[10:13], v[184:187], v[232:235], v[10:13]
	v_mfma_f32_16x16x32_bf16 v[54:57], v[188:191], v[204:207], 0
	v_mfma_f32_16x16x32_bf16 v[50:53], v[196:199], v[204:207], 0
	v_mfma_f32_16x16x32_bf16 v[38:41], v[188:191], v[212:215], 0
	v_mfma_f32_16x16x32_bf16 v[34:37], v[196:199], v[212:215], 0
	v_mfma_f32_16x16x32_bf16 v[22:25], v[188:191], v[220:223], 0
	v_mfma_f32_16x16x32_bf16 v[18:21], v[196:199], v[220:223], 0
	v_mfma_f32_16x16x32_bf16 v[6:9], v[188:191], v[228:231], 0
	v_mfma_f32_16x16x32_bf16 v[2:5], v[196:199], v[228:231], 0
	v_mfma_f32_16x16x32_bf16 v[54:57], v[192:195], v[208:211], v[54:57]
	v_mfma_f32_16x16x32_bf16 v[50:53], v[200:203], v[208:211], v[50:53]
	v_mfma_f32_16x16x32_bf16 v[38:41], v[192:195], v[216:219], v[38:41]
	v_mfma_f32_16x16x32_bf16 v[34:37], v[200:203], v[216:219], v[34:37]
	v_mfma_f32_16x16x32_bf16 v[22:25], v[192:195], v[224:227], v[22:25]
	v_mfma_f32_16x16x32_bf16 v[18:21], v[200:203], v[224:227], v[18:21]
	v_mfma_f32_16x16x32_bf16 v[6:9], v[192:195], v[232:235], v[6:9]
	v_mfma_f32_16x16x32_bf16 v[2:5], v[200:203], v[232:235], v[2:5]
	s_barrier
	v_add_u32_e32 v171, s60, v1
	ds_read_b128 v[172:175], v171
	ds_read_b128 v[176:179], v171 offset:1024
	ds_read_b128 v[180:183], v171 offset:2048
	ds_read_b128 v[184:187], v171 offset:3072
	v_add_u32_e32 v171, s61, v1
	ds_read_b128 v[188:191], v171
	ds_read_b128 v[192:195], v171 offset:1024
	ds_read_b128 v[196:199], v171 offset:2048
	ds_read_b128 v[200:203], v171 offset:3072
	s_add_u32 s36, s36, 0x80000
	s_addc_u32 s37, s37, 0
	s_mov_b32 m0, s41
	ds_read_b128 v[204:207], v170 offset:32768
	ds_read_b128 v[208:211], v170 offset:33792
	ds_read_b128 v[212:215], v170 offset:34816
	ds_read_b128 v[216:219], v170 offset:35840
	ds_read_b128 v[220:223], v170 offset:36864
	ds_read_b128 v[224:227], v170 offset:37888
	ds_read_b128 v[228:231], v170 offset:38912
	ds_read_b128 v[232:235], v170 offset:39936
	global_load_lds_dwordx4 v136, s[36:37]
	s_mov_b32 m0, s42
	s_nop 0
	global_load_lds_dwordx4 v132, s[36:37]
	s_waitcnt vmcnt(8)
	s_barrier
	s_waitcnt lgkmcnt(0)
	v_mfma_f32_16x16x32_bf16 v[126:129], v[172:175], v[204:207], v[126:129]
	v_mfma_f32_16x16x32_bf16 v[122:125], v[180:183], v[204:207], v[122:125]
	v_mfma_f32_16x16x32_bf16 v[110:113], v[172:175], v[212:215], v[110:113]
	v_mfma_f32_16x16x32_bf16 v[106:109], v[180:183], v[212:215], v[106:109]
	v_mfma_f32_16x16x32_bf16 v[94:97], v[172:175], v[220:223], v[94:97]
	v_mfma_f32_16x16x32_bf16 v[90:93], v[180:183], v[220:223], v[90:93]
	v_mfma_f32_16x16x32_bf16 v[78:81], v[172:175], v[228:231], v[78:81]
	v_mfma_f32_16x16x32_bf16 v[74:77], v[180:183], v[228:231], v[74:77]
	v_mfma_f32_16x16x32_bf16 v[126:129], v[176:179], v[208:211], v[126:129]
	v_mfma_f32_16x16x32_bf16 v[122:125], v[184:187], v[208:211], v[122:125]
	v_mfma_f32_16x16x32_bf16 v[110:113], v[176:179], v[216:219], v[110:113]
	v_mfma_f32_16x16x32_bf16 v[106:109], v[184:187], v[216:219], v[106:109]
	v_mfma_f32_16x16x32_bf16 v[94:97], v[176:179], v[224:227], v[94:97]
	v_mfma_f32_16x16x32_bf16 v[90:93], v[184:187], v[224:227], v[90:93]
	v_mfma_f32_16x16x32_bf16 v[78:81], v[176:179], v[232:235], v[78:81]
	v_mfma_f32_16x16x32_bf16 v[74:77], v[184:187], v[232:235], v[74:77]
	v_mfma_f32_16x16x32_bf16 v[118:121], v[188:191], v[204:207], v[118:121]
	v_mfma_f32_16x16x32_bf16 v[114:117], v[196:199], v[204:207], v[114:117]
	v_mfma_f32_16x16x32_bf16 v[102:105], v[188:191], v[212:215], v[102:105]
	v_mfma_f32_16x16x32_bf16 v[98:101], v[196:199], v[212:215], v[98:101]
	v_mfma_f32_16x16x32_bf16 v[86:89], v[188:191], v[220:223], v[86:89]
	v_mfma_f32_16x16x32_bf16 v[82:85], v[196:199], v[220:223], v[82:85]
	v_mfma_f32_16x16x32_bf16 v[70:73], v[188:191], v[228:231], v[70:73]
	v_mfma_f32_16x16x32_bf16 v[66:69], v[196:199], v[228:231], v[66:69]
	v_mfma_f32_16x16x32_bf16 v[118:121], v[192:195], v[208:211], v[118:121]
	v_mfma_f32_16x16x32_bf16 v[114:117], v[200:203], v[208:211], v[114:117]
	v_mfma_f32_16x16x32_bf16 v[102:105], v[192:195], v[216:219], v[102:105]
	v_mfma_f32_16x16x32_bf16 v[98:101], v[200:203], v[216:219], v[98:101]
	v_mfma_f32_16x16x32_bf16 v[86:89], v[192:195], v[224:227], v[86:89]
	v_mfma_f32_16x16x32_bf16 v[82:85], v[200:203], v[224:227], v[82:85]
	v_mfma_f32_16x16x32_bf16 v[70:73], v[192:195], v[232:235], v[70:73]
	v_mfma_f32_16x16x32_bf16 v[66:69], v[200:203], v[232:235], v[66:69]
	s_barrier
; #define PG8_STAGE(bufoff, gbase, voff) do { _Pragma("unroll") for (int _i = 0; _i < 2; ++_i) \
;         __builtin_amdgcn_global_load_lds((const unsigned*)((const char*)(gbase) + (voff)[_i]), (LAS unsigned*)(lds + (bufoff) + ldsw + _i * 8192), 16, 0, 0); } while (0)
; #define PG8_LDA(dst, b, h) do { _Pragma("unroll") for (int m = 0; m < 4; ++m) _Pragma("unroll") for (int k = 0; k < 2; ++k) dst[m][k] = *(const LAS bf16x8*)(lds + PG8_SA(b, h) + aoff + m * 2048 + k * 1024); } while (0)
; #define PG8_LDB(dst, b, h) do { _Pragma("unroll") for (int n = 0; n < 2; ++n) _Pragma("unroll") for (int k = 0; k < 2; ++k) dst[n][k] = *(const LAS bf16x8*)(lds + PG8_SB(b, h) + boff + n * 2048 + k * 1024); } while (0)
; #define PG8_MMA(ai, bj, At, Bt) do { __builtin_amdgcn_s_setprio(1); _Pragma("unroll") for (int m = 0; m < 4; ++m) _Pragma("unroll") for (int n = 0; n < 2; ++n) _Pragma("unroll") for (int k = 0; k < 2; ++k) \
;         acc[ai][bj][m][n] = __builtin_amdgcn_mfma_f32_16x16x32_bf16(Bt[n][k], At[m][k], acc[ai][bj][m][n], 0, 0, 0); __builtin_amdgcn_s_setprio(0); } while (0)
; #define PG8_WAIT_V(n) asm volatile("s_waitcnt vmcnt(" #n ")" ::: "memory")
; #define PG8_WAIT_L(n) asm volatile("s_waitcnt lgkmcnt(" #n ")" ::: "memory")
; #define PG8_BAR __builtin_amdgcn_s_barrier()
; #define PG8_SCHED __builtin_amdgcn_sched_barrier(0)
; template <class Epi, class Sched, bool ABLK = false, bool ALIGN_EPI = true, bool SP2 = true, bool BBLK = true>
; __device__ __forceinline__ void gemm_phase(LAS unsigned char* lds, const Gemm g, const Sched& S, const Epi& E) {
;     ...
;             PG8_LDB(B0, 0, 0); PG8_LDB(B1, 0, 1); PG8_SCHED; PG8_LDA(At, 0, 0); PG8_STAGE(PG8_SA(1, 1), a1 + hstepA, voffA);
;             PG8_WAIT_V(8); PG8_WAIT_L(0); PG8_BAR; PG8_MMA(0, 0, At, B0); PG8_MMA(0, 1, At, B1); PG8_BAR; PG8_SCHED;
;     ...
;             PG8_LDA(At, 1, 1); PG8_STAGE(PG8_SB(1, 0), b3, voffB); PG8_STAGE(PG8_SB(1, 1), b3 + hstepB, voffB); PG8_STAGE(PG8_SA(1, 0), a3, voffA);
;             PG8_WAIT_V(8); PG8_WAIT_L(0); PG8_BAR; PG8_MMA(1, 0, At, B0); PG8_MMA(1, 1, At, B1); PG8_BAR; PG8_SCHED;
	s_add_u32 s36, s34, 0x8000
	s_addc_u32 s37, s35, 0
	s_add_i32 s55, s60, s39
	s_mov_b32 m0, s55
	ds_read_b128 v[204:207], v170 offset:49152
	ds_read_b128 v[208:211], v170 offset:50176
	ds_read_b128 v[212:215], v170 offset:51200
	ds_read_b128 v[216:219], v170 offset:52224
	ds_read_b128 v[220:223], v170 offset:53248
	ds_read_b128 v[224:227], v170 offset:54272
	ds_read_b128 v[228:231], v170 offset:55296
	ds_read_b128 v[232:235], v170 offset:56320
	global_load_lds_dwordx4 v134, s[36:37]
	s_add_i32 m0, s55, 0x2000
	s_add_u32 s34, s34, 0xc000
	v_lshl_add_u64 v[236:237], s[36:37], 0, v[130:131]
	s_addc_u32 s35, s35, 0
	s_add_i32 s36, s61, s39
	global_load_lds_dwordx4 v[236:237], off
	s_mov_b32 m0, s36
	s_nop 0
	global_load_lds_dwordx4 v134, s[34:35]
	s_add_i32 m0, s36, 0x2000
	s_nop 0
	global_load_lds_dwordx4 v130, s[34:35]
	s_mov_b32 m0, s45
	s_nop 0
	global_load_lds_dwordx4 v136, s[30:31]
	s_mov_b32 m0, s46
	s_nop 0
	global_load_lds_dwordx4 v132, s[30:31]
	s_waitcnt vmcnt(8)
	s_barrier
	s_waitcnt lgkmcnt(0)
	v_mfma_f32_16x16x32_bf16 v[62:65], v[172:175], v[204:207], v[62:65]
	v_mfma_f32_16x16x32_bf16 v[58:61], v[180:183], v[204:207], v[58:61]
	v_mfma_f32_16x16x32_bf16 v[46:49], v[172:175], v[212:215], v[46:49]
	v_mfma_f32_16x16x32_bf16 v[42:45], v[180:183], v[212:215], v[42:45]
	v_mfma_f32_16x16x32_bf16 v[30:33], v[172:175], v[220:223], v[30:33]
	v_mfma_f32_16x16x32_bf16 v[26:29], v[180:183], v[220:223], v[26:29]
	v_mfma_f32_16x16x32_bf16 v[14:17], v[172:175], v[228:231], v[14:17]
	v_mfma_f32_16x16x32_bf16 v[10:13], v[180:183], v[228:231], v[10:13]
	v_mfma_f32_16x16x32_bf16 v[62:65], v[176:179], v[208:211], v[62:65]
	v_mfma_f32_16x16x32_bf16 v[58:61], v[184:187], v[208:211], v[58:61]
	v_mfma_f32_16x16x32_bf16 v[46:49], v[176:179], v[216:219], v[46:49]
	v_mfma_f32_16x16x32_bf16 v[42:45], v[184:187], v[216:219], v[42:45]
	v_mfma_f32_16x16x32_bf16 v[30:33], v[176:179], v[224:227], v[30:33]
	v_mfma_f32_16x16x32_bf16 v[26:29], v[184:187], v[224:227], v[26:29]
	v_mfma_f32_16x16x32_bf16 v[14:17], v[176:179], v[232:235], v[14:17]
	v_mfma_f32_16x16x32_bf16 v[10:13], v[184:187], v[232:235], v[10:13]
	v_mfma_f32_16x16x32_bf16 v[54:57], v[188:191], v[204:207], v[54:57]
	v_mfma_f32_16x16x32_bf16 v[50:53], v[196:199], v[204:207], v[50:53]
	v_mfma_f32_16x16x32_bf16 v[38:41], v[188:191], v[212:215], v[38:41]
	v_mfma_f32_16x16x32_bf16 v[34:37], v[196:199], v[212:215], v[34:37]
	v_mfma_f32_16x16x32_bf16 v[22:25], v[188:191], v[220:223], v[22:25]
	v_mfma_f32_16x16x32_bf16 v[18:21], v[196:199], v[220:223], v[18:21]
	v_mfma_f32_16x16x32_bf16 v[6:9], v[188:191], v[228:231], v[6:9]
	v_mfma_f32_16x16x32_bf16 v[2:5], v[196:199], v[228:231], v[2:5]
	v_mfma_f32_16x16x32_bf16 v[54:57], v[192:195], v[208:211], v[54:57]
	v_mfma_f32_16x16x32_bf16 v[50:53], v[200:203], v[208:211], v[50:53]
	v_mfma_f32_16x16x32_bf16 v[38:41], v[192:195], v[216:219], v[38:41]
	v_mfma_f32_16x16x32_bf16 v[34:37], v[200:203], v[216:219], v[34:37]
	v_mfma_f32_16x16x32_bf16 v[22:25], v[192:195], v[224:227], v[22:25]
	v_mfma_f32_16x16x32_bf16 v[18:21], v[200:203], v[224:227], v[18:21]
	v_mfma_f32_16x16x32_bf16 v[6:9], v[192:195], v[232:235], v[6:9]
	v_mfma_f32_16x16x32_bf16 v[2:5], v[200:203], v[232:235], v[2:5]
	s_barrier
	s_add_i32 s54, s54, 2
	s_add_u32 s28, s28, 0x100
	s_addc_u32 s29, s29, 0
	s_add_u32 s52, s52, 0x10000
	s_addc_u32 s53, s53, 0
	s_cmp_gt_u32 s54, 29
.LBB0_1842:
	ds_read_b128 v[172:175], v168
	ds_read_b128 v[176:179], v168 offset:1024
	ds_read_b128 v[180:183], v168 offset:2048
	ds_read_b128 v[184:187], v168 offset:3072
	ds_read_b128 v[188:191], v169
	ds_read_b128 v[192:195], v169 offset:1024
	ds_read_b128 v[196:199], v169 offset:2048
	ds_read_b128 v[200:203], v169 offset:3072
	s_add_u32 s30, s26, s28
	s_addc_u32 s31, s27, s29
	s_add_u32 s36, s30, 0x100
	s_addc_u32 s37, s31, 0
	s_add_u32 s30, s30, 0x180
	s_addc_u32 s31, s31, 0
	s_cmpk_eq_i32 s28, 0xf00
	s_cselect_b32 s31, s51, s31
	s_cselect_b32 s30, s23, s30
	s_cselect_b32 s35, s11, s53
	s_cselect_b32 s34, s15, s52
	s_cselect_b32 s37, s4, s37
	s_cselect_b32 s36, s5, s36
	s_mov_b32 m0, s47
	v_lshl_add_u64 v[236:237], v[164:165], 0, s[28:29]
	ds_read_b128 v[204:207], v170
	ds_read_b128 v[208:211], v170 offset:1024
	ds_read_b128 v[212:215], v170 offset:2048
	ds_read_b128 v[216:219], v170 offset:3072
	ds_read_b128 v[220:223], v170 offset:4096
	ds_read_b128 v[224:227], v170 offset:5120
	ds_read_b128 v[228:231], v170 offset:6144
	ds_read_b128 v[232:235], v170 offset:7168
	global_load_lds_dwordx4 v[236:237], off
	v_lshl_add_u64 v[236:237], v[166:167], 0, s[28:29]
	s_mov_b32 m0, s48
	s_nop 0
	global_load_lds_dwordx4 v[236:237], off
	s_waitcnt vmcnt(8)
	s_barrier
; #define PG8_STAGE(bufoff, gbase, voff) do { _Pragma("unroll") for (int _i = 0; _i < 2; ++_i) \
;         __builtin_amdgcn_global_load_lds((const unsigned*)((const char*)(gbase) + (voff)[_i]), (LAS unsigned*)(lds + (bufoff) + ldsw + _i * 8192), 16, 0, 0); } while (0)
; #define PG8_LDA(dst, b, h) do { _Pragma("unroll") for (int m = 0; m < 4; ++m) _Pragma("unroll") for (int k = 0; k < 2; ++k) dst[m][k] = *(const LAS bf16x8*)(lds + PG8_SA(b, h) + aoff + m * 2048 + k * 1024); } while (0)
; #define PG8_MMA(ai, bj, At, Bt) do { __builtin_amdgcn_s_setprio(1); _Pragma("unroll") for (int m = 0; m < 4; ++m) _Pragma("unroll") for (int n = 0; n < 2; ++n) _Pragma("unroll") for (int k = 0; k < 2; ++k) \
;         acc[ai][bj][m][n] = __builtin_amdgcn_mfma_f32_16x16x32_bf16(Bt[n][k], At[m][k], acc[ai][bj][m][n], 0, 0, 0); __builtin_amdgcn_s_setprio(0); } while (0)
; #define PG8_WAIT_V(n) asm volatile("s_waitcnt vmcnt(" #n ")" ::: "memory")
; #define PG8_WAIT_L(n) asm volatile("s_waitcnt lgkmcnt(" #n ")" ::: "memory")
; #define PG8_BAR __builtin_amdgcn_s_barrier()
; #define PG8_SCHED __builtin_amdgcn_sched_barrier(0)
; template <class Epi, class Sched, bool ABLK = false, bool ALIGN_EPI = true, bool SP2 = true, bool BBLK = true>
; __device__ __forceinline__ void gemm_phase(LAS unsigned char* lds, const Gemm g, const Sched& S, const Epi& E) {
;     ...
;             PG8_WAIT_V(8); PG8_WAIT_L(0); PG8_BAR; PG8_MMA(0, 0, At, B0); PG8_MMA(0, 1, At, B1); PG8_BAR; PG8_SCHED;
;             PG8_LDA(At, 0, 1); PG8_STAGE(PG8_SB(0, 0), b2, voffB); PG8_STAGE(PG8_SB(0, 1), b2 + hstepB, voffB); PG8_STAGE(PG8_SA(0, 0), a2, voffA);
;             PG8_WAIT_V(8); PG8_WAIT_L(0); PG8_BAR; PG8_MMA(1, 0, At, B0); PG8_MMA(1, 1, At, B1); PG8_BAR; PG8_SCHED;
	s_waitcnt lgkmcnt(0)
	v_mfma_f32_16x16x32_bf16 v[126:129], v[172:175], v[204:207], v[126:129]
	v_mfma_f32_16x16x32_bf16 v[122:125], v[180:183], v[204:207], v[122:125]
	v_mfma_f32_16x16x32_bf16 v[110:113], v[172:175], v[212:215], v[110:113]
	v_mfma_f32_16x16x32_bf16 v[106:109], v[180:183], v[212:215], v[106:109]
	v_mfma_f32_16x16x32_bf16 v[94:97], v[172:175], v[220:223], v[94:97]
	v_mfma_f32_16x16x32_bf16 v[90:93], v[180:183], v[220:223], v[90:93]
	v_mfma_f32_16x16x32_bf16 v[78:81], v[172:175], v[228:231], v[78:81]
	v_mfma_f32_16x16x32_bf16 v[74:77], v[180:183], v[228:231], v[74:77]
	v_mfma_f32_16x16x32_bf16 v[126:129], v[176:179], v[208:211], v[126:129]
	v_mfma_f32_16x16x32_bf16 v[122:125], v[184:187], v[208:211], v[122:125]
	v_mfma_f32_16x16x32_bf16 v[110:113], v[176:179], v[216:219], v[110:113]
	v_mfma_f32_16x16x32_bf16 v[106:109], v[184:187], v[216:219], v[106:109]
	v_mfma_f32_16x16x32_bf16 v[94:97], v[176:179], v[224:227], v[94:97]
	v_mfma_f32_16x16x32_bf16 v[90:93], v[184:187], v[224:227], v[90:93]
	v_mfma_f32_16x16x32_bf16 v[78:81], v[176:179], v[232:235], v[78:81]
	v_mfma_f32_16x16x32_bf16 v[74:77], v[184:187], v[232:235], v[74:77]
	v_mfma_f32_16x16x32_bf16 v[118:121], v[188:191], v[204:207], v[118:121]
	v_mfma_f32_16x16x32_bf16 v[114:117], v[196:199], v[204:207], v[114:117]
	v_mfma_f32_16x16x32_bf16 v[102:105], v[188:191], v[212:215], v[102:105]
	v_mfma_f32_16x16x32_bf16 v[98:101], v[196:199], v[212:215], v[98:101]
	v_mfma_f32_16x16x32_bf16 v[86:89], v[188:191], v[220:223], v[86:89]
	v_mfma_f32_16x16x32_bf16 v[82:85], v[196:199], v[220:223], v[82:85]
	v_mfma_f32_16x16x32_bf16 v[70:73], v[188:191], v[228:231], v[70:73]
	v_mfma_f32_16x16x32_bf16 v[66:69], v[196:199], v[228:231], v[66:69]
	v_mfma_f32_16x16x32_bf16 v[118:121], v[192:195], v[208:211], v[118:121]
	v_mfma_f32_16x16x32_bf16 v[114:117], v[200:203], v[208:211], v[114:117]
	v_mfma_f32_16x16x32_bf16 v[102:105], v[192:195], v[216:219], v[102:105]
	v_mfma_f32_16x16x32_bf16 v[98:101], v[200:203], v[216:219], v[98:101]
	v_mfma_f32_16x16x32_bf16 v[86:89], v[192:195], v[224:227], v[86:89]
	v_mfma_f32_16x16x32_bf16 v[82:85], v[200:203], v[224:227], v[82:85]
	v_mfma_f32_16x16x32_bf16 v[70:73], v[192:195], v[232:235], v[70:73]
	v_mfma_f32_16x16x32_bf16 v[66:69], v[200:203], v[232:235], v[66:69]
	s_barrier
	s_mov_b32 m0, s49
	s_add_u32 s56, s34, 0x4000
	ds_read_b128 v[204:207], v170 offset:16384
	ds_read_b128 v[208:211], v170 offset:17408
	ds_read_b128 v[212:215], v170 offset:18432
	ds_read_b128 v[216:219], v170 offset:19456
	ds_read_b128 v[220:223], v170 offset:20480
	ds_read_b128 v[224:227], v170 offset:21504
	ds_read_b128 v[228:231], v170 offset:22528
	ds_read_b128 v[232:235], v170 offset:23552
	global_load_lds_dwordx4 v134, s[34:35]
	s_mov_b32 m0, s50
	s_addc_u32 s57, s35, 0
	s_add_i32 s55, s73, s39
	global_load_lds_dwordx4 v130, s[34:35]
	s_mov_b32 m0, s55
	s_nop 0
	global_load_lds_dwordx4 v134, s[56:57]
	s_add_i32 m0, s55, 0x2000
	s_nop 0
	global_load_lds_dwordx4 v130, s[56:57]
	s_mov_b32 m0, s25
	s_nop 0
	global_load_lds_dwordx4 v136, s[36:37]
	s_mov_b32 m0, s40
	s_nop 0
	global_load_lds_dwordx4 v132, s[36:37]
	s_waitcnt vmcnt(8)
	s_barrier
	s_waitcnt lgkmcnt(0)
	v_mfma_f32_16x16x32_bf16 v[62:65], v[172:175], v[204:207], v[62:65]
	v_mfma_f32_16x16x32_bf16 v[58:61], v[180:183], v[204:207], v[58:61]
	v_mfma_f32_16x16x32_bf16 v[46:49], v[172:175], v[212:215], v[46:49]
	v_mfma_f32_16x16x32_bf16 v[42:45], v[180:183], v[212:215], v[42:45]
	v_mfma_f32_16x16x32_bf16 v[30:33], v[172:175], v[220:223], v[30:33]
	v_mfma_f32_16x16x32_bf16 v[26:29], v[180:183], v[220:223], v[26:29]
	v_mfma_f32_16x16x32_bf16 v[14:17], v[172:175], v[228:231], v[14:17]
	v_mfma_f32_16x16x32_bf16 v[10:13], v[180:183], v[228:231], v[10:13]
	v_mfma_f32_16x16x32_bf16 v[62:65], v[176:179], v[208:211], v[62:65]
	v_mfma_f32_16x16x32_bf16 v[58:61], v[184:187], v[208:211], v[58:61]
	v_mfma_f32_16x16x32_bf16 v[46:49], v[176:179], v[216:219], v[46:49]
	v_mfma_f32_16x16x32_bf16 v[42:45], v[184:187], v[216:219], v[42:45]
	v_mfma_f32_16x16x32_bf16 v[30:33], v[176:179], v[224:227], v[30:33]
	v_mfma_f32_16x16x32_bf16 v[26:29], v[184:187], v[224:227], v[26:29]
	v_mfma_f32_16x16x32_bf16 v[14:17], v[176:179], v[232:235], v[14:17]
	v_mfma_f32_16x16x32_bf16 v[10:13], v[184:187], v[232:235], v[10:13]
	v_mfma_f32_16x16x32_bf16 v[54:57], v[188:191], v[204:207], v[54:57]
	v_mfma_f32_16x16x32_bf16 v[50:53], v[196:199], v[204:207], v[50:53]
	v_mfma_f32_16x16x32_bf16 v[38:41], v[188:191], v[212:215], v[38:41]
	v_mfma_f32_16x16x32_bf16 v[34:37], v[196:199], v[212:215], v[34:37]
	v_mfma_f32_16x16x32_bf16 v[22:25], v[188:191], v[220:223], v[22:25]
	v_mfma_f32_16x16x32_bf16 v[18:21], v[196:199], v[220:223], v[18:21]
	v_mfma_f32_16x16x32_bf16 v[6:9], v[188:191], v[228:231], v[6:9]
	v_mfma_f32_16x16x32_bf16 v[2:5], v[196:199], v[228:231], v[2:5]
	v_mfma_f32_16x16x32_bf16 v[54:57], v[192:195], v[208:211], v[54:57]
	v_mfma_f32_16x16x32_bf16 v[50:53], v[200:203], v[208:211], v[50:53]
	v_mfma_f32_16x16x32_bf16 v[38:41], v[192:195], v[216:219], v[38:41]
	v_mfma_f32_16x16x32_bf16 v[34:37], v[200:203], v[216:219], v[34:37]
	v_mfma_f32_16x16x32_bf16 v[22:25], v[192:195], v[224:227], v[22:25]
	v_mfma_f32_16x16x32_bf16 v[18:21], v[200:203], v[224:227], v[18:21]
	v_mfma_f32_16x16x32_bf16 v[6:9], v[192:195], v[232:235], v[6:9]
	v_mfma_f32_16x16x32_bf16 v[2:5], v[200:203], v[232:235], v[2:5]
	s_barrier
; #define PG8_STAGE(bufoff, gbase, voff) do { _Pragma("unroll") for (int _i = 0; _i < 2; ++_i) \
;         __builtin_amdgcn_global_load_lds((const unsigned*)((const char*)(gbase) + (voff)[_i]), (LAS unsigned*)(lds + (bufoff) + ldsw + _i * 8192), 16, 0, 0); } while (0)
; #define PG8_LDA(dst, b, h) do { _Pragma("unroll") for (int m = 0; m < 4; ++m) _Pragma("unroll") for (int k = 0; k < 2; ++k) dst[m][k] = *(const LAS bf16x8*)(lds + PG8_SA(b, h) + aoff + m * 2048 + k * 1024); } while (0)
; #define PG8_LDB(dst, b, h) do { _Pragma("unroll") for (int n = 0; n < 2; ++n) _Pragma("unroll") for (int k = 0; k < 2; ++k) dst[n][k] = *(const LAS bf16x8*)(lds + PG8_SB(b, h) + boff + n * 2048 + k * 1024); } while (0)
; #define PG8_MMA(ai, bj, At, Bt) do { __builtin_amdgcn_s_setprio(1); _Pragma("unroll") for (int m = 0; m < 4; ++m) _Pragma("unroll") for (int n = 0; n < 2; ++n) _Pragma("unroll") for (int k = 0; k < 2; ++k) \
;         acc[ai][bj][m][n] = __builtin_amdgcn_mfma_f32_16x16x32_bf16(Bt[n][k], At[m][k], acc[ai][bj][m][n], 0, 0, 0); __builtin_amdgcn_s_setprio(0); } while (0)
; #define PG8_WAIT_V(n) asm volatile("s_waitcnt vmcnt(" #n ")" ::: "memory")
; #define PG8_WAIT_L(n) asm volatile("s_waitcnt lgkmcnt(" #n ")" ::: "memory")
; #define PG8_BAR __builtin_amdgcn_s_barrier()
; #define PG8_SCHED __builtin_amdgcn_sched_barrier(0)
; template <class Epi, class Sched, bool ABLK = false, bool ALIGN_EPI = true, bool SP2 = true, bool BBLK = true>
; __device__ __forceinline__ void gemm_phase(LAS unsigned char* lds, const Gemm g, const Sched& S, const Epi& E) {
;     ...
;             PG8_LDB(B0, 1, 0); PG8_LDB(B1, 1, 1); PG8_SCHED; PG8_LDA(At, 1, 0); PG8_STAGE(PG8_SA(0, 1), a2 + hstepA, voffA);
;             PG8_WAIT_V(8); PG8_WAIT_L(0); PG8_BAR; PG8_MMA(0, 0, At, B0); PG8_MMA(0, 1, At, B1); PG8_BAR; PG8_SCHED;
;             PG8_LDA(At, 1, 1); PG8_STAGE(PG8_SB(1, 0), b3, voffB); PG8_STAGE(PG8_SB(1, 1), b3 + hstepB, voffB); PG8_STAGE(PG8_SA(1, 0), a3, voffA);
;             PG8_WAIT_V(8); PG8_WAIT_L(0); PG8_BAR; PG8_MMA(1, 0, At, B0); PG8_MMA(1, 1, At, B1); PG8_BAR; PG8_SCHED;
;     ...
;         if constexpr (ALIGN_EPI) { if (wr == 0) PG8_BAR; }
	v_add_u32_e32 v171, s60, v1
	ds_read_b128 v[172:175], v171
	ds_read_b128 v[176:179], v171 offset:1024
	ds_read_b128 v[180:183], v171 offset:2048
	ds_read_b128 v[184:187], v171 offset:3072
	v_add_u32_e32 v171, s61, v1
	ds_read_b128 v[188:191], v171
	ds_read_b128 v[192:195], v171 offset:1024
	ds_read_b128 v[196:199], v171 offset:2048
	ds_read_b128 v[200:203], v171 offset:3072
	s_add_u32 s36, s36, 0x80000
	s_addc_u32 s37, s37, 0
	s_mov_b32 m0, s41
	ds_read_b128 v[204:207], v170 offset:32768
	ds_read_b128 v[208:211], v170 offset:33792
	ds_read_b128 v[212:215], v170 offset:34816
	ds_read_b128 v[216:219], v170 offset:35840
	ds_read_b128 v[220:223], v170 offset:36864
	ds_read_b128 v[224:227], v170 offset:37888
	ds_read_b128 v[228:231], v170 offset:38912
	ds_read_b128 v[232:235], v170 offset:39936
	global_load_lds_dwordx4 v136, s[36:37]
	s_mov_b32 m0, s42
	s_nop 0
	global_load_lds_dwordx4 v132, s[36:37]
	s_waitcnt vmcnt(8)
	s_barrier
	s_waitcnt lgkmcnt(0)
	v_mfma_f32_16x16x32_bf16 v[126:129], v[172:175], v[204:207], v[126:129]
	v_mfma_f32_16x16x32_bf16 v[122:125], v[180:183], v[204:207], v[122:125]
	v_mfma_f32_16x16x32_bf16 v[110:113], v[172:175], v[212:215], v[110:113]
	v_mfma_f32_16x16x32_bf16 v[106:109], v[180:183], v[212:215], v[106:109]
	v_mfma_f32_16x16x32_bf16 v[94:97], v[172:175], v[220:223], v[94:97]
	v_mfma_f32_16x16x32_bf16 v[90:93], v[180:183], v[220:223], v[90:93]
	v_mfma_f32_16x16x32_bf16 v[78:81], v[172:175], v[228:231], v[78:81]
	v_mfma_f32_16x16x32_bf16 v[74:77], v[180:183], v[228:231], v[74:77]
	v_mfma_f32_16x16x32_bf16 v[126:129], v[176:179], v[208:211], v[126:129]
	v_mfma_f32_16x16x32_bf16 v[122:125], v[184:187], v[208:211], v[122:125]
	v_mfma_f32_16x16x32_bf16 v[110:113], v[176:179], v[216:219], v[110:113]
	v_mfma_f32_16x16x32_bf16 v[106:109], v[184:187], v[216:219], v[106:109]
	v_mfma_f32_16x16x32_bf16 v[94:97], v[176:179], v[224:227], v[94:97]
	v_mfma_f32_16x16x32_bf16 v[90:93], v[184:187], v[224:227], v[90:93]
	v_mfma_f32_16x16x32_bf16 v[78:81], v[176:179], v[232:235], v[78:81]
	v_mfma_f32_16x16x32_bf16 v[74:77], v[184:187], v[232:235], v[74:77]
	v_mfma_f32_16x16x32_bf16 v[118:121], v[188:191], v[204:207], v[118:121]
	v_mfma_f32_16x16x32_bf16 v[114:117], v[196:199], v[204:207], v[114:117]
	v_mfma_f32_16x16x32_bf16 v[102:105], v[188:191], v[212:215], v[102:105]
	v_mfma_f32_16x16x32_bf16 v[98:101], v[196:199], v[212:215], v[98:101]
	v_mfma_f32_16x16x32_bf16 v[86:89], v[188:191], v[220:223], v[86:89]
	v_mfma_f32_16x16x32_bf16 v[82:85], v[196:199], v[220:223], v[82:85]
	v_mfma_f32_16x16x32_bf16 v[70:73], v[188:191], v[228:231], v[70:73]
	v_mfma_f32_16x16x32_bf16 v[66:69], v[196:199], v[228:231], v[66:69]
	v_mfma_f32_16x16x32_bf16 v[118:121], v[192:195], v[208:211], v[118:121]
	v_mfma_f32_16x16x32_bf16 v[114:117], v[200:203], v[208:211], v[114:117]
	v_mfma_f32_16x16x32_bf16 v[102:105], v[192:195], v[216:219], v[102:105]
	v_mfma_f32_16x16x32_bf16 v[98:101], v[200:203], v[216:219], v[98:101]
	v_mfma_f32_16x16x32_bf16 v[86:89], v[192:195], v[224:227], v[86:89]
	v_mfma_f32_16x16x32_bf16 v[82:85], v[200:203], v[224:227], v[82:85]
	v_mfma_f32_16x16x32_bf16 v[70:73], v[192:195], v[232:235], v[70:73]
	v_mfma_f32_16x16x32_bf16 v[66:69], v[200:203], v[232:235], v[66:69]
	s_barrier
	s_add_u32 s36, s34, 0x8000
	s_addc_u32 s37, s35, 0
	s_add_i32 s55, s60, s39
	s_mov_b32 m0, s55
	ds_read_b128 v[204:207], v170 offset:49152
	ds_read_b128 v[208:211], v170 offset:50176
	ds_read_b128 v[212:215], v170 offset:51200
	ds_read_b128 v[216:219], v170 offset:52224
	ds_read_b128 v[220:223], v170 offset:53248
	ds_read_b128 v[224:227], v170 offset:54272
	ds_read_b128 v[228:231], v170 offset:55296
	ds_read_b128 v[232:235], v170 offset:56320
	global_load_lds_dwordx4 v134, s[36:37]
	s_add_i32 m0, s55, 0x2000
	s_add_u32 s34, s34, 0xc000
	v_lshl_add_u64 v[236:237], s[36:37], 0, v[130:131]
	s_addc_u32 s35, s35, 0
	s_add_i32 s36, s61, s39
	global_load_lds_dwordx4 v[236:237], off
	s_mov_b32 m0, s36
	s_nop 0
	global_load_lds_dwordx4 v134, s[34:35]
	s_add_i32 m0, s36, 0x2000
	s_nop 0
	global_load_lds_dwordx4 v130, s[34:35]
	s_mov_b32 m0, s45
	s_nop 0
	global_load_lds_dwordx4 v136, s[30:31]
	s_mov_b32 m0, s46
	s_nop 0
	global_load_lds_dwordx4 v132, s[30:31]
	s_waitcnt vmcnt(8)
	s_barrier
	s_waitcnt lgkmcnt(0)
	v_mfma_f32_16x16x32_bf16 v[62:65], v[172:175], v[204:207], v[62:65]
	v_mfma_f32_16x16x32_bf16 v[58:61], v[180:183], v[204:207], v[58:61]
	v_mfma_f32_16x16x32_bf16 v[46:49], v[172:175], v[212:215], v[46:49]
	v_mfma_f32_16x16x32_bf16 v[42:45], v[180:183], v[212:215], v[42:45]
	v_mfma_f32_16x16x32_bf16 v[30:33], v[172:175], v[220:223], v[30:33]
	v_mfma_f32_16x16x32_bf16 v[26:29], v[180:183], v[220:223], v[26:29]
	v_mfma_f32_16x16x32_bf16 v[14:17], v[172:175], v[228:231], v[14:17]
	v_mfma_f32_16x16x32_bf16 v[10:13], v[180:183], v[228:231], v[10:13]
	v_mfma_f32_16x16x32_bf16 v[62:65], v[176:179], v[208:211], v[62:65]
	v_mfma_f32_16x16x32_bf16 v[58:61], v[184:187], v[208:211], v[58:61]
	v_mfma_f32_16x16x32_bf16 v[46:49], v[176:179], v[216:219], v[46:49]
	v_mfma_f32_16x16x32_bf16 v[42:45], v[184:187], v[216:219], v[42:45]
	v_mfma_f32_16x16x32_bf16 v[30:33], v[176:179], v[224:227], v[30:33]
	v_mfma_f32_16x16x32_bf16 v[26:29], v[184:187], v[224:227], v[26:29]
	v_mfma_f32_16x16x32_bf16 v[14:17], v[176:179], v[232:235], v[14:17]
	v_mfma_f32_16x16x32_bf16 v[10:13], v[184:187], v[232:235], v[10:13]
	v_mfma_f32_16x16x32_bf16 v[54:57], v[188:191], v[204:207], v[54:57]
	v_mfma_f32_16x16x32_bf16 v[50:53], v[196:199], v[204:207], v[50:53]
	v_mfma_f32_16x16x32_bf16 v[38:41], v[188:191], v[212:215], v[38:41]
	v_mfma_f32_16x16x32_bf16 v[34:37], v[196:199], v[212:215], v[34:37]
	v_mfma_f32_16x16x32_bf16 v[22:25], v[188:191], v[220:223], v[22:25]
	v_mfma_f32_16x16x32_bf16 v[18:21], v[196:199], v[220:223], v[18:21]
	v_mfma_f32_16x16x32_bf16 v[6:9], v[188:191], v[228:231], v[6:9]
	v_mfma_f32_16x16x32_bf16 v[2:5], v[196:199], v[228:231], v[2:5]
	v_mfma_f32_16x16x32_bf16 v[54:57], v[192:195], v[208:211], v[54:57]
	v_mfma_f32_16x16x32_bf16 v[50:53], v[200:203], v[208:211], v[50:53]
	v_mfma_f32_16x16x32_bf16 v[38:41], v[192:195], v[216:219], v[38:41]
	v_mfma_f32_16x16x32_bf16 v[34:37], v[200:203], v[216:219], v[34:37]
	v_mfma_f32_16x16x32_bf16 v[22:25], v[192:195], v[224:227], v[22:25]
	v_mfma_f32_16x16x32_bf16 v[18:21], v[200:203], v[224:227], v[18:21]
	v_mfma_f32_16x16x32_bf16 v[6:9], v[192:195], v[232:235], v[6:9]
	v_mfma_f32_16x16x32_bf16 v[2:5], v[200:203], v[232:235], v[2:5]
	s_barrier
	s_add_i32 s54, s54, 2
	s_add_u32 s28, s28, 0x100
	s_addc_u32 s29, s29, 0
	s_add_u32 s52, s52, 0x10000
	s_addc_u32 s53, s53, 0
	s_cmp_gt_u32 s54, 29
	s_cbranch_scc0 .LBB0_1842
	s_and_b64 vcc, exec, s[6:7]
	s_cbranch_vccz .LBB0_1845
	s_barrier

; #define PG8_STAGE(bufoff, gbase, voff) do { _Pragma("unroll") for (int _i = 0; _i < 2; ++_i) \
;         __builtin_amdgcn_global_load_lds((const unsigned*)((const char*)(gbase) + (voff)[_i]), (LAS unsigned*)(lds + (bufoff) + ldsw + _i * 8192), 16, 0, 0); } while (0)
; #define PG8_LDA(dst, b, h) do { _Pragma("unroll") for (int m = 0; m < 4; ++m) _Pragma("unroll") for (int k = 0; k < 2; ++k) dst[m][k] = *(const LAS bf16x8*)(lds + PG8_SA(b, h) + aoff + m * 2048 + k * 1024); } while (0)
; #define PG8_LDB(dst, b, h) do { _Pragma("unroll") for (int n = 0; n < 2; ++n) _Pragma("unroll") for (int k = 0; k < 2; ++k) dst[n][k] = *(const LAS bf16x8*)(lds + PG8_SB(b, h) + boff + n * 2048 + k * 1024); } while (0)
; #define PG8_WAIT_V(n) asm volatile("s_waitcnt vmcnt(" #n ")" ::: "memory")
; #define PG8_WAIT_L(n) asm volatile("s_waitcnt lgkmcnt(" #n ")" ::: "memory")
; #define PG8_BAR __builtin_amdgcn_s_barrier()
; #define PG8_SCHED __builtin_amdgcn_sched_barrier(0)
; template <class Epi, class Sched, bool ABLK = false, bool ALIGN_EPI = true, bool SP2 = true, bool BBLK = true>
; __device__ __forceinline__ void gemm_phase(LAS unsigned char* lds, const Gemm g, const Sched& S, const Epi& E) {
;     ...
;         const bool has_next = S.next(ui + 1, nxt);
;         const int nt = cur.nt;
;         const char* nuA = has_next ? a_unit(nxt) : uA; const int ntbA = has_next ? nxt.k0 / BK : tbA; const char* nB = has_next ? (const char*)g.Bt + (size_t)nxt.pn * tstepB + b_k0(nxt.k0) : cB;
;         for (int t = 0; t < nt; t += 2) {
;             const bool last = (t == nt - 2);
;             const char* a1 = a_tile(uA, tbA + t + 1);
;             const char* a2 = last ? a_tile(nuA, ntbA) : a_tile(uA, tbA + t + 2); const char* b2 = last ? nB : cB + (size_t)(t + 2) * kstepB;
;             const char* a3 = last ? a_tile(nuA, ntbA + 1) : a_tile(uA, tbA + t + 3); const char* b3 = b2 + kstepB;
;             if (last && has_next) S.a_ready(nxt);
;             if constexpr (SP2) {
;             PG8_LDB(B0, 0, 0); PG8_LDB(B1, 0, 1); PG8_SCHED; PG8_LDA(At, 0, 0); PG8_STAGE(PG8_SA(1, 1), a1 + hstepA, voffA);
;             PG8_WAIT_V(8); PG8_WAIT_L(0); PG8_BAR; PG8_MMA(0, 0, At, B0); PG8_MMA(0, 1, At, B1); PG8_BAR; PG8_SCHED;
;             PG8_LDA(At, 0, 1); PG8_STAGE(PG8_SB(0, 0), b2, voffB); PG8_STAGE(PG8_SB(0, 1), b2 + hstepB, voffB); PG8_STAGE(PG8_SA(0, 0), a2, voffA);
.LBB0_1906:
	s_ashr_i32 s81, s80, 31
	s_andn2_b64 vcc, exec, s[4:5]
	s_lshl_b64 s[24:25], s[80:81], 22
	s_add_u32 s24, s62, s24
	s_addc_u32 s25, s83, s25
	s_and_b64 s[26:27], s[4:5], exec
	s_cselect_b32 s37, s25, s35
	s_cselect_b32 s50, s24, s34
	s_ashr_i32 s26, s0, 31
	s_lshr_b32 s26, s26, 26
	s_add_i32 s26, s0, s26
	s_ashr_i32 s26, s26, 6
	s_and_b64 s[28:29], s[4:5], exec
	s_cselect_b32 s38, s26, s36
	s_ashr_i32 s79, s78, 31
	s_lshl_b64 s[28:29], s[78:79], 22
	s_add_u32 s39, s1, s28
	s_addc_u32 s51, s33, s29
	s_ashr_i32 s27, s26, 31
	s_lshl_b64 s[28:29], s[26:27], 15
	s_add_u32 s28, s39, s28
	s_addc_u32 s29, s51, s29
	v_cndmask_b32_e64 v2, 0, 1, s[4:5]
	s_and_b64 s[4:5], s[4:5], exec
	s_cselect_b32 s4, s29, s31
	s_cselect_b32 s5, s28, s30
	s_ashr_i32 s39, s38, 31
	s_lshl_b64 s[38:39], s[38:39], 15
	s_add_u32 s27, s50, s38
	s_addc_u32 s50, s37, s39
	s_add_u32 s51, s27, 0x8000
	s_addc_u32 s52, s50, 0
	s_add_u32 s53, s30, 0x10000
	s_addc_u32 s54, s31, 0
	s_ashr_i32 s37, s36, 31
	v_cmp_ne_u32_e64 s[10:11], 1, v2
	s_lshl_b64 s[30:31], s[36:37], 15
	v_lshl_add_u64 v[2:3], s[34:35], 0, v[138:139]
	s_add_u32 s55, s34, s30
	v_lshl_add_u64 v[142:143], v[2:3], 0, s[30:31]
	v_lshl_add_u64 v[2:3], s[34:35], 0, v[140:141]
	s_addc_u32 s56, s35, s31
	v_lshl_add_u64 v[144:145], v[2:3], 0, s[30:31]
	s_lshl_b32 s30, s48, 15
	s_add_i32 s30, s30, 0xfff00000
	v_mov_b32_e32 v2, 0
	s_add_u32 s57, s30, 0xf0000
	s_mov_b32 s58, 0
	s_mov_b64 s[30:31], 0
	ds_read_b128 v[152:155], v148
	ds_read_b128 v[156:159], v148 offset:1024
	ds_read_b128 v[160:163], v148 offset:2048
	ds_read_b128 v[164:167], v148 offset:3072
	ds_read_b128 v[168:171], v149
	ds_read_b128 v[172:175], v149 offset:1024
	ds_read_b128 v[176:179], v149 offset:2048
	ds_read_b128 v[180:183], v149 offset:3072
	s_add_u32 s34, s55, s30
	s_addc_u32 s35, s56, s31
	s_add_u32 s38, s34, 0x10000
	s_addc_u32 s39, s35, 0
	s_add_i32 s58, s58, 2
	s_add_u32 s36, s53, s30
	s_addc_u32 s37, s54, s31
	s_add_u32 s34, s34, 0x18000
	s_addc_u32 s35, s35, 0
	s_cmp_eq_u32 s57, s30
	s_cselect_b32 s35, s52, s35
	s_cselect_b32 s34, s51, s34
	s_cselect_b32 s37, s4, s37
	s_cselect_b32 s36, s5, s36
	s_cselect_b32 s39, s50, s39
	s_cselect_b32 s38, s27, s38
	v_lshl_add_u64 v[216:217], v[142:143], 0, s[30:31]
	s_add_i32 m0, s41, 0xc000
	ds_read_b128 v[184:187], v150
	ds_read_b128 v[188:191], v150 offset:1024
	ds_read_b128 v[192:195], v150 offset:2048
	ds_read_b128 v[196:199], v150 offset:3072
	ds_read_b128 v[200:203], v150 offset:4096
	ds_read_b128 v[204:207], v150 offset:5120
	ds_read_b128 v[208:211], v150 offset:6144
	ds_read_b128 v[212:215], v150 offset:7168
	global_load_lds_dwordx4 v[216:217], off
	v_lshl_add_u64 v[216:217], v[144:145], 0, s[30:31]
	s_add_i32 m0, s41, 0xe000
	s_nop 0
	global_load_lds_dwordx4 v[216:217], off
	s_waitcnt vmcnt(8)
	s_barrier
	s_waitcnt lgkmcnt(0)
	v_mfma_f32_16x16x32_bf16 v[126:129], v[152:155], v[184:187], 0
	v_mfma_f32_16x16x32_bf16 v[122:125], v[160:163], v[184:187], 0
	v_mfma_f32_16x16x32_bf16 v[110:113], v[152:155], v[192:195], 0
	v_mfma_f32_16x16x32_bf16 v[106:109], v[160:163], v[192:195], 0
	v_mfma_f32_16x16x32_bf16 v[94:97], v[152:155], v[200:203], 0
	v_mfma_f32_16x16x32_bf16 v[90:93], v[160:163], v[200:203], 0
	v_mfma_f32_16x16x32_bf16 v[78:81], v[152:155], v[208:211], 0
	v_mfma_f32_16x16x32_bf16 v[74:77], v[160:163], v[208:211], 0
	v_mfma_f32_16x16x32_bf16 v[126:129], v[156:159], v[188:191], v[126:129]
	v_mfma_f32_16x16x32_bf16 v[122:125], v[164:167], v[188:191], v[122:125]
	v_mfma_f32_16x16x32_bf16 v[110:113], v[156:159], v[196:199], v[110:113]
	v_mfma_f32_16x16x32_bf16 v[106:109], v[164:167], v[196:199], v[106:109]
	v_mfma_f32_16x16x32_bf16 v[94:97], v[156:159], v[204:207], v[94:97]
	v_mfma_f32_16x16x32_bf16 v[90:93], v[164:167], v[204:207], v[90:93]
	v_mfma_f32_16x16x32_bf16 v[78:81], v[156:159], v[212:215], v[78:81]
	v_mfma_f32_16x16x32_bf16 v[74:77], v[164:167], v[212:215], v[74:77]
	v_mfma_f32_16x16x32_bf16 v[118:121], v[168:171], v[184:187], 0
	v_mfma_f32_16x16x32_bf16 v[114:117], v[176:179], v[184:187], 0
	v_mfma_f32_16x16x32_bf16 v[102:105], v[168:171], v[192:195], 0
	v_mfma_f32_16x16x32_bf16 v[98:101], v[176:179], v[192:195], 0
	v_mfma_f32_16x16x32_bf16 v[86:89], v[168:171], v[200:203], 0
	v_mfma_f32_16x16x32_bf16 v[82:85], v[176:179], v[200:203], 0
	v_mfma_f32_16x16x32_bf16 v[70:73], v[168:171], v[208:211], 0
	v_mfma_f32_16x16x32_bf16 v[66:69], v[176:179], v[208:211], 0
	v_mfma_f32_16x16x32_bf16 v[118:121], v[172:175], v[188:191], v[118:121]
	v_mfma_f32_16x16x32_bf16 v[114:117], v[180:183], v[188:191], v[114:117]
	v_mfma_f32_16x16x32_bf16 v[102:105], v[172:175], v[196:199], v[102:105]
	v_mfma_f32_16x16x32_bf16 v[98:101], v[180:183], v[196:199], v[98:101]
	v_mfma_f32_16x16x32_bf16 v[86:89], v[172:175], v[204:207], v[86:89]
	v_mfma_f32_16x16x32_bf16 v[82:85], v[180:183], v[204:207], v[82:85]
	v_mfma_f32_16x16x32_bf16 v[70:73], v[172:175], v[212:215], v[70:73]
	v_mfma_f32_16x16x32_bf16 v[66:69], v[180:183], v[212:215], v[66:69]
	s_barrier
	s_add_i32 s59, s72, s40
	s_mov_b32 m0, s59
	ds_read_b128 v[184:187], v150 offset:16384
	ds_read_b128 v[188:191], v150 offset:17408
	ds_read_b128 v[192:195], v150 offset:18432
	ds_read_b128 v[196:199], v150 offset:19456
	ds_read_b128 v[200:203], v150 offset:20480
	ds_read_b128 v[204:207], v150 offset:21504
	ds_read_b128 v[208:211], v150 offset:22528
	ds_read_b128 v[212:215], v150 offset:23552
	global_load_lds_dwordx4 v130, s[36:37]
	s_add_i32 m0, s59, 0x2000
	s_add_u32 s64, s36, 0x4000
	s_addc_u32 s65, s37, 0
	s_add_i32 s59, s73, s40
	global_load_lds_dwordx4 v132, s[36:37]
	s_mov_b32 m0, s59
	s_nop 0
	global_load_lds_dwordx4 v130, s[64:65]
	s_add_i32 m0, s59, 0x2000
	s_nop 0
	global_load_lds_dwordx4 v132, s[64:65]
	s_mov_b32 m0, s41
	s_nop 0
	global_load_lds_dwordx4 v130, s[38:39]
	s_mov_b32 m0, s42
	s_nop 0
	global_load_lds_dwordx4 v132, s[38:39]
	s_waitcnt vmcnt(8)
	s_barrier
; #define PG8_STAGE(bufoff, gbase, voff) do { _Pragma("unroll") for (int _i = 0; _i < 2; ++_i) \
;         __builtin_amdgcn_global_load_lds((const unsigned*)((const char*)(gbase) + (voff)[_i]), (LAS unsigned*)(lds + (bufoff) + ldsw + _i * 8192), 16, 0, 0); } while (0)
; #define PG8_LDA(dst, b, h) do { _Pragma("unroll") for (int m = 0; m < 4; ++m) _Pragma("unroll") for (int k = 0; k < 2; ++k) dst[m][k] = *(const LAS bf16x8*)(lds + PG8_SA(b, h) + aoff + m * 2048 + k * 1024); } while (0)
; #define PG8_LDB(dst, b, h) do { _Pragma("unroll") for (int n = 0; n < 2; ++n) _Pragma("unroll") for (int k = 0; k < 2; ++k) dst[n][k] = *(const LAS bf16x8*)(lds + PG8_SB(b, h) + boff + n * 2048 + k * 1024); } while (0)
; #define PG8_MMA(ai, bj, At, Bt) do { __builtin_amdgcn_s_setprio(1); _Pragma("unroll") for (int m = 0; m < 4; ++m) _Pragma("unroll") for (int n = 0; n < 2; ++n) _Pragma("unroll") for (int k = 0; k < 2; ++k) \
;         acc[ai][bj][m][n] = __builtin_amdgcn_mfma_f32_16x16x32_bf16(Bt[n][k], At[m][k], acc[ai][bj][m][n], 0, 0, 0); __builtin_amdgcn_s_setprio(0); } while (0)
; #define PG8_WAIT_V(n) asm volatile("s_waitcnt vmcnt(" #n ")" ::: "memory")
; #define PG8_WAIT_L(n) asm volatile("s_waitcnt lgkmcnt(" #n ")" ::: "memory")
; #define PG8_BAR __builtin_amdgcn_s_barrier()
; #define PG8_SCHED __builtin_amdgcn_sched_barrier(0)
; template <class Epi, class Sched, bool ABLK = false, bool ALIGN_EPI = true, bool SP2 = true, bool BBLK = true>
; __device__ __forceinline__ void gemm_phase(LAS unsigned char* lds, const Gemm g, const Sched& S, const Epi& E) {
;     ...
;             PG8_WAIT_V(8); PG8_WAIT_L(0); PG8_BAR; PG8_MMA(1, 0, At, B0); PG8_MMA(1, 1, At, B1); PG8_BAR; PG8_SCHED;
;             PG8_LDB(B0, 1, 0); PG8_LDB(B1, 1, 1); PG8_SCHED; PG8_LDA(At, 1, 0); PG8_STAGE(PG8_SA(0, 1), a2 + hstepA, voffA);
;             PG8_WAIT_V(8); PG8_WAIT_L(0); PG8_BAR; PG8_MMA(0, 0, At, B0); PG8_MMA(0, 1, At, B1); PG8_BAR; PG8_SCHED;
	s_waitcnt lgkmcnt(0)
	v_mfma_f32_16x16x32_bf16 v[62:65], v[152:155], v[184:187], 0
	v_mfma_f32_16x16x32_bf16 v[58:61], v[160:163], v[184:187], 0
	v_mfma_f32_16x16x32_bf16 v[46:49], v[152:155], v[192:195], 0
	v_mfma_f32_16x16x32_bf16 v[42:45], v[160:163], v[192:195], 0
	v_mfma_f32_16x16x32_bf16 v[30:33], v[152:155], v[200:203], 0
	v_mfma_f32_16x16x32_bf16 v[26:29], v[160:163], v[200:203], 0
	v_mfma_f32_16x16x32_bf16 v[14:17], v[152:155], v[208:211], 0
	v_mfma_f32_16x16x32_bf16 v[10:13], v[160:163], v[208:211], 0
	v_mfma_f32_16x16x32_bf16 v[62:65], v[156:159], v[188:191], v[62:65]
	v_mfma_f32_16x16x32_bf16 v[58:61], v[164:167], v[188:191], v[58:61]
	v_mfma_f32_16x16x32_bf16 v[46:49], v[156:159], v[196:199], v[46:49]
	v_mfma_f32_16x16x32_bf16 v[42:45], v[164:167], v[196:199], v[42:45]
	v_mfma_f32_16x16x32_bf16 v[30:33], v[156:159], v[204:207], v[30:33]
	v_mfma_f32_16x16x32_bf16 v[26:29], v[164:167], v[204:207], v[26:29]
	v_mfma_f32_16x16x32_bf16 v[14:17], v[156:159], v[212:215], v[14:17]
	v_mfma_f32_16x16x32_bf16 v[10:13], v[164:167], v[212:215], v[10:13]
	v_mfma_f32_16x16x32_bf16 v[54:57], v[168:171], v[184:187], 0
	v_mfma_f32_16x16x32_bf16 v[50:53], v[176:179], v[184:187], 0
	v_mfma_f32_16x16x32_bf16 v[38:41], v[168:171], v[192:195], 0
	v_mfma_f32_16x16x32_bf16 v[34:37], v[176:179], v[192:195], 0
	v_mfma_f32_16x16x32_bf16 v[22:25], v[168:171], v[200:203], 0
	v_mfma_f32_16x16x32_bf16 v[18:21], v[176:179], v[200:203], 0
	v_mfma_f32_16x16x32_bf16 v[6:9], v[168:171], v[208:211], 0
	v_mfma_f32_16x16x32_bf16 v[2:5], v[176:179], v[208:211], 0
	v_mfma_f32_16x16x32_bf16 v[54:57], v[172:175], v[188:191], v[54:57]
	v_mfma_f32_16x16x32_bf16 v[50:53], v[180:183], v[188:191], v[50:53]
	v_mfma_f32_16x16x32_bf16 v[38:41], v[172:175], v[196:199], v[38:41]
	v_mfma_f32_16x16x32_bf16 v[34:37], v[180:183], v[196:199], v[34:37]
	v_mfma_f32_16x16x32_bf16 v[22:25], v[172:175], v[204:207], v[22:25]
	v_mfma_f32_16x16x32_bf16 v[18:21], v[180:183], v[204:207], v[18:21]
	v_mfma_f32_16x16x32_bf16 v[6:9], v[172:175], v[212:215], v[6:9]
	v_mfma_f32_16x16x32_bf16 v[2:5], v[180:183], v[212:215], v[2:5]
	s_barrier
	v_add_u32_e32 v151, s60, v146
	ds_read_b128 v[152:155], v151
	ds_read_b128 v[156:159], v151 offset:1024
	ds_read_b128 v[160:163], v151 offset:2048
	ds_read_b128 v[164:167], v151 offset:3072
	v_add_u32_e32 v151, s61, v146
	ds_read_b128 v[168:171], v151
	ds_read_b128 v[172:175], v151 offset:1024
	ds_read_b128 v[176:179], v151 offset:2048
	ds_read_b128 v[180:183], v151 offset:3072
	s_add_u32 s38, s38, 0x4000
	s_addc_u32 s39, s39, 0
	s_mov_b32 m0, s43
	ds_read_b128 v[184:187], v150 offset:32768
	ds_read_b128 v[188:191], v150 offset:33792
	ds_read_b128 v[192:195], v150 offset:34816
	ds_read_b128 v[196:199], v150 offset:35840
	ds_read_b128 v[200:203], v150 offset:36864
	ds_read_b128 v[204:207], v150 offset:37888
	ds_read_b128 v[208:211], v150 offset:38912
	ds_read_b128 v[212:215], v150 offset:39936
	global_load_lds_dwordx4 v130, s[38:39]
	s_mov_b32 m0, s44
	s_nop 0
	global_load_lds_dwordx4 v132, s[38:39]
	s_waitcnt vmcnt(8)
	s_barrier
	s_waitcnt lgkmcnt(0)
	v_mfma_f32_16x16x32_bf16 v[126:129], v[152:155], v[184:187], v[126:129]
	v_mfma_f32_16x16x32_bf16 v[122:125], v[160:163], v[184:187], v[122:125]
	v_mfma_f32_16x16x32_bf16 v[110:113], v[152:155], v[192:195], v[110:113]
	v_mfma_f32_16x16x32_bf16 v[106:109], v[160:163], v[192:195], v[106:109]
	v_mfma_f32_16x16x32_bf16 v[94:97], v[152:155], v[200:203], v[94:97]
	v_mfma_f32_16x16x32_bf16 v[90:93], v[160:163], v[200:203], v[90:93]
	v_mfma_f32_16x16x32_bf16 v[78:81], v[152:155], v[208:211], v[78:81]
	v_mfma_f32_16x16x32_bf16 v[74:77], v[160:163], v[208:211], v[74:77]
	v_mfma_f32_16x16x32_bf16 v[126:129], v[156:159], v[188:191], v[126:129]
	v_mfma_f32_16x16x32_bf16 v[122:125], v[164:167], v[188:191], v[122:125]
	v_mfma_f32_16x16x32_bf16 v[110:113], v[156:159], v[196:199], v[110:113]
	v_mfma_f32_16x16x32_bf16 v[106:109], v[164:167], v[196:199], v[106:109]
	v_mfma_f32_16x16x32_bf16 v[94:97], v[156:159], v[204:207], v[94:97]
	v_mfma_f32_16x16x32_bf16 v[90:93], v[164:167], v[204:207], v[90:93]
	v_mfma_f32_16x16x32_bf16 v[78:81], v[156:159], v[212:215], v[78:81]
	v_mfma_f32_16x16x32_bf16 v[74:77], v[164:167], v[212:215], v[74:77]
	v_mfma_f32_16x16x32_bf16 v[118:121], v[168:171], v[184:187], v[118:121]
	v_mfma_f32_16x16x32_bf16 v[114:117], v[176:179], v[184:187], v[114:117]
	v_mfma_f32_16x16x32_bf16 v[102:105], v[168:171], v[192:195], v[102:105]
	v_mfma_f32_16x16x32_bf16 v[98:101], v[176:179], v[192:195], v[98:101]
	v_mfma_f32_16x16x32_bf16 v[86:89], v[168:171], v[200:203], v[86:89]
	v_mfma_f32_16x16x32_bf16 v[82:85], v[176:179], v[200:203], v[82:85]
	v_mfma_f32_16x16x32_bf16 v[70:73], v[168:171], v[208:211], v[70:73]
	v_mfma_f32_16x16x32_bf16 v[66:69], v[176:179], v[208:211], v[66:69]
	v_mfma_f32_16x16x32_bf16 v[118:121], v[172:175], v[188:191], v[118:121]
	v_mfma_f32_16x16x32_bf16 v[114:117], v[180:183], v[188:191], v[114:117]
	v_mfma_f32_16x16x32_bf16 v[102:105], v[172:175], v[196:199], v[102:105]
	v_mfma_f32_16x16x32_bf16 v[98:101], v[180:183], v[196:199], v[98:101]
	v_mfma_f32_16x16x32_bf16 v[86:89], v[172:175], v[204:207], v[86:89]
	v_mfma_f32_16x16x32_bf16 v[82:85], v[180:183], v[204:207], v[82:85]
	v_mfma_f32_16x16x32_bf16 v[70:73], v[172:175], v[212:215], v[70:73]
	v_mfma_f32_16x16x32_bf16 v[66:69], v[180:183], v[212:215], v[66:69]
	s_barrier
; #define PG8_STAGE(bufoff, gbase, voff) do { _Pragma("unroll") for (int _i = 0; _i < 2; ++_i) \
;         __builtin_amdgcn_global_load_lds((const unsigned*)((const char*)(gbase) + (voff)[_i]), (LAS unsigned*)(lds + (bufoff) + ldsw + _i * 8192), 16, 0, 0); } while (0)
; #define PG8_LDA(dst, b, h) do { _Pragma("unroll") for (int m = 0; m < 4; ++m) _Pragma("unroll") for (int k = 0; k < 2; ++k) dst[m][k] = *(const LAS bf16x8*)(lds + PG8_SA(b, h) + aoff + m * 2048 + k * 1024); } while (0)
; #define PG8_LDB(dst, b, h) do { _Pragma("unroll") for (int n = 0; n < 2; ++n) _Pragma("unroll") for (int k = 0; k < 2; ++k) dst[n][k] = *(const LAS bf16x8*)(lds + PG8_SB(b, h) + boff + n * 2048 + k * 1024); } while (0)
; #define PG8_MMA(ai, bj, At, Bt) do { __builtin_amdgcn_s_setprio(1); _Pragma("unroll") for (int m = 0; m < 4; ++m) _Pragma("unroll") for (int n = 0; n < 2; ++n) _Pragma("unroll") for (int k = 0; k < 2; ++k) \
;         acc[ai][bj][m][n] = __builtin_amdgcn_mfma_f32_16x16x32_bf16(Bt[n][k], At[m][k], acc[ai][bj][m][n], 0, 0, 0); __builtin_amdgcn_s_setprio(0); } while (0)
; #define PG8_WAIT_V(n) asm volatile("s_waitcnt vmcnt(" #n ")" ::: "memory")
; #define PG8_WAIT_L(n) asm volatile("s_waitcnt lgkmcnt(" #n ")" ::: "memory")
; #define PG8_BAR __builtin_amdgcn_s_barrier()
; #define PG8_SCHED __builtin_amdgcn_sched_barrier(0)
; template <class Epi, class Sched, bool ABLK = false, bool ALIGN_EPI = true, bool SP2 = true, bool BBLK = true>
; __device__ __forceinline__ void gemm_phase(LAS unsigned char* lds, const Gemm g, const Sched& S, const Epi& E) {
;     ...
;             PG8_LDB(B0, 0, 0); PG8_LDB(B1, 0, 1); PG8_SCHED; PG8_LDA(At, 0, 0); PG8_STAGE(PG8_SA(1, 1), a1 + hstepA, voffA);
;             PG8_WAIT_V(8); PG8_WAIT_L(0); PG8_BAR; PG8_MMA(0, 0, At, B0); PG8_MMA(0, 1, At, B1); PG8_BAR; PG8_SCHED;
;     ...
;             PG8_LDA(At, 1, 1); PG8_STAGE(PG8_SB(1, 0), b3, voffB); PG8_STAGE(PG8_SB(1, 1), b3 + hstepB, voffB); PG8_STAGE(PG8_SA(1, 0), a3, voffA);
;             PG8_WAIT_V(8); PG8_WAIT_L(0); PG8_BAR; PG8_MMA(1, 0, At, B0); PG8_MMA(1, 1, At, B1); PG8_BAR; PG8_SCHED;
	s_add_u32 s38, s36, 0x8000
	s_addc_u32 s39, s37, 0
	s_add_i32 s59, s60, s40
	s_mov_b32 m0, s59
	ds_read_b128 v[184:187], v150 offset:49152
	ds_read_b128 v[188:191], v150 offset:50176
	ds_read_b128 v[192:195], v150 offset:51200
	ds_read_b128 v[196:199], v150 offset:52224
	ds_read_b128 v[200:203], v150 offset:53248
	ds_read_b128 v[204:207], v150 offset:54272
	ds_read_b128 v[208:211], v150 offset:55296
	ds_read_b128 v[212:215], v150 offset:56320
	global_load_lds_dwordx4 v130, s[38:39]
	s_add_i32 m0, s59, 0x2000
	s_add_u32 s36, s36, 0xc000
	v_lshl_add_u64 v[216:217], s[38:39], 0, v[132:133]
	s_addc_u32 s37, s37, 0
	s_add_i32 s38, s61, s40
	global_load_lds_dwordx4 v[216:217], off
	s_mov_b32 m0, s38
	s_nop 0
	global_load_lds_dwordx4 v130, s[36:37]
	s_add_i32 m0, s38, 0x2000
	s_nop 0
	global_load_lds_dwordx4 v132, s[36:37]
	s_mov_b32 m0, s45
	s_nop 0
	global_load_lds_dwordx4 v130, s[34:35]
	s_mov_b32 m0, s46
	s_nop 0
	global_load_lds_dwordx4 v132, s[34:35]
	s_waitcnt vmcnt(8)
	s_barrier
	s_waitcnt lgkmcnt(0)
	v_mfma_f32_16x16x32_bf16 v[62:65], v[152:155], v[184:187], v[62:65]
	v_mfma_f32_16x16x32_bf16 v[58:61], v[160:163], v[184:187], v[58:61]
	v_mfma_f32_16x16x32_bf16 v[46:49], v[152:155], v[192:195], v[46:49]
	v_mfma_f32_16x16x32_bf16 v[42:45], v[160:163], v[192:195], v[42:45]
	v_mfma_f32_16x16x32_bf16 v[30:33], v[152:155], v[200:203], v[30:33]
	v_mfma_f32_16x16x32_bf16 v[26:29], v[160:163], v[200:203], v[26:29]
	v_mfma_f32_16x16x32_bf16 v[14:17], v[152:155], v[208:211], v[14:17]
	v_mfma_f32_16x16x32_bf16 v[10:13], v[160:163], v[208:211], v[10:13]
	v_mfma_f32_16x16x32_bf16 v[62:65], v[156:159], v[188:191], v[62:65]
	v_mfma_f32_16x16x32_bf16 v[58:61], v[164:167], v[188:191], v[58:61]
	v_mfma_f32_16x16x32_bf16 v[46:49], v[156:159], v[196:199], v[46:49]
	v_mfma_f32_16x16x32_bf16 v[42:45], v[164:167], v[196:199], v[42:45]
	v_mfma_f32_16x16x32_bf16 v[30:33], v[156:159], v[204:207], v[30:33]
	v_mfma_f32_16x16x32_bf16 v[26:29], v[164:167], v[204:207], v[26:29]
	v_mfma_f32_16x16x32_bf16 v[14:17], v[156:159], v[212:215], v[14:17]
	v_mfma_f32_16x16x32_bf16 v[10:13], v[164:167], v[212:215], v[10:13]
	v_mfma_f32_16x16x32_bf16 v[54:57], v[168:171], v[184:187], v[54:57]
	v_mfma_f32_16x16x32_bf16 v[50:53], v[176:179], v[184:187], v[50:53]
	v_mfma_f32_16x16x32_bf16 v[38:41], v[168:171], v[192:195], v[38:41]
	v_mfma_f32_16x16x32_bf16 v[34:37], v[176:179], v[192:195], v[34:37]
	v_mfma_f32_16x16x32_bf16 v[22:25], v[168:171], v[200:203], v[22:25]
	v_mfma_f32_16x16x32_bf16 v[18:21], v[176:179], v[200:203], v[18:21]
	v_mfma_f32_16x16x32_bf16 v[6:9], v[168:171], v[208:211], v[6:9]
	v_mfma_f32_16x16x32_bf16 v[2:5], v[176:179], v[208:211], v[2:5]
	v_mfma_f32_16x16x32_bf16 v[54:57], v[172:175], v[188:191], v[54:57]
	v_mfma_f32_16x16x32_bf16 v[50:53], v[180:183], v[188:191], v[50:53]
	v_mfma_f32_16x16x32_bf16 v[38:41], v[172:175], v[196:199], v[38:41]
	v_mfma_f32_16x16x32_bf16 v[34:37], v[180:183], v[196:199], v[34:37]
	v_mfma_f32_16x16x32_bf16 v[22:25], v[172:175], v[204:207], v[22:25]
	v_mfma_f32_16x16x32_bf16 v[18:21], v[180:183], v[204:207], v[18:21]
	v_mfma_f32_16x16x32_bf16 v[6:9], v[172:175], v[212:215], v[6:9]
	v_mfma_f32_16x16x32_bf16 v[2:5], v[180:183], v[212:215], v[2:5]
	s_barrier
	s_add_u32 s30, s30, 0x10000
	s_addc_u32 s31, s31, 0
	s_cmp_ge_u32 s58, s48
.LBB0_1907:
	ds_read_b128 v[152:155], v148
	ds_read_b128 v[156:159], v148 offset:1024
	ds_read_b128 v[160:163], v148 offset:2048
	ds_read_b128 v[164:167], v148 offset:3072
	ds_read_b128 v[168:171], v149
	ds_read_b128 v[172:175], v149 offset:1024
	ds_read_b128 v[176:179], v149 offset:2048
	ds_read_b128 v[180:183], v149 offset:3072
	s_add_u32 s34, s55, s30
	s_addc_u32 s35, s56, s31
	s_add_u32 s38, s34, 0x10000
	s_addc_u32 s39, s35, 0
	s_add_i32 s58, s58, 2
	s_add_u32 s36, s53, s30
	s_addc_u32 s37, s54, s31
	s_add_u32 s34, s34, 0x18000
	s_addc_u32 s35, s35, 0
	s_cmp_eq_u32 s57, s30
	s_cselect_b32 s35, s52, s35
	s_cselect_b32 s34, s51, s34
	s_cselect_b32 s37, s4, s37
	s_cselect_b32 s36, s5, s36
	s_cselect_b32 s39, s50, s39
	s_cselect_b32 s38, s27, s38
	v_lshl_add_u64 v[216:217], v[142:143], 0, s[30:31]
	s_add_i32 m0, s41, 0xc000
	ds_read_b128 v[184:187], v150
	ds_read_b128 v[188:191], v150 offset:1024
	ds_read_b128 v[192:195], v150 offset:2048
	ds_read_b128 v[196:199], v150 offset:3072
	ds_read_b128 v[200:203], v150 offset:4096
	ds_read_b128 v[204:207], v150 offset:5120
	ds_read_b128 v[208:211], v150 offset:6144
	ds_read_b128 v[212:215], v150 offset:7168
	global_load_lds_dwordx4 v[216:217], off
	v_lshl_add_u64 v[216:217], v[144:145], 0, s[30:31]
	s_add_i32 m0, s41, 0xe000
	s_nop 0
	global_load_lds_dwordx4 v[216:217], off
	s_waitcnt vmcnt(8)
	s_barrier
; #define PG8_STAGE(bufoff, gbase, voff) do { _Pragma("unroll") for (int _i = 0; _i < 2; ++_i) \
;         __builtin_amdgcn_global_load_lds((const unsigned*)((const char*)(gbase) + (voff)[_i]), (LAS unsigned*)(lds + (bufoff) + ldsw + _i * 8192), 16, 0, 0); } while (0)
; #define PG8_LDA(dst, b, h) do { _Pragma("unroll") for (int m = 0; m < 4; ++m) _Pragma("unroll") for (int k = 0; k < 2; ++k) dst[m][k] = *(const LAS bf16x8*)(lds + PG8_SA(b, h) + aoff + m * 2048 + k * 1024); } while (0)
; #define PG8_MMA(ai, bj, At, Bt) do { __builtin_amdgcn_s_setprio(1); _Pragma("unroll") for (int m = 0; m < 4; ++m) _Pragma("unroll") for (int n = 0; n < 2; ++n) _Pragma("unroll") for (int k = 0; k < 2; ++k) \
;         acc[ai][bj][m][n] = __builtin_amdgcn_mfma_f32_16x16x32_bf16(Bt[n][k], At[m][k], acc[ai][bj][m][n], 0, 0, 0); __builtin_amdgcn_s_setprio(0); } while (0)
; #define PG8_WAIT_V(n) asm volatile("s_waitcnt vmcnt(" #n ")" ::: "memory")
; #define PG8_WAIT_L(n) asm volatile("s_waitcnt lgkmcnt(" #n ")" ::: "memory")
; #define PG8_BAR __builtin_amdgcn_s_barrier()
; #define PG8_SCHED __builtin_amdgcn_sched_barrier(0)
; template <class Epi, class Sched, bool ABLK = false, bool ALIGN_EPI = true, bool SP2 = true, bool BBLK = true>
; __device__ __forceinline__ void gemm_phase(LAS unsigned char* lds, const Gemm g, const Sched& S, const Epi& E) {
;     ...
;             PG8_WAIT_V(8); PG8_WAIT_L(0); PG8_BAR; PG8_MMA(0, 0, At, B0); PG8_MMA(0, 1, At, B1); PG8_BAR; PG8_SCHED;
;             PG8_LDA(At, 0, 1); PG8_STAGE(PG8_SB(0, 0), b2, voffB); PG8_STAGE(PG8_SB(0, 1), b2 + hstepB, voffB); PG8_STAGE(PG8_SA(0, 0), a2, voffA);
;             PG8_WAIT_V(8); PG8_WAIT_L(0); PG8_BAR; PG8_MMA(1, 0, At, B0); PG8_MMA(1, 1, At, B1); PG8_BAR; PG8_SCHED;
	s_waitcnt lgkmcnt(0)
	v_mfma_f32_16x16x32_bf16 v[126:129], v[152:155], v[184:187], v[126:129]
	v_mfma_f32_16x16x32_bf16 v[122:125], v[160:163], v[184:187], v[122:125]
	v_mfma_f32_16x16x32_bf16 v[110:113], v[152:155], v[192:195], v[110:113]
	v_mfma_f32_16x16x32_bf16 v[106:109], v[160:163], v[192:195], v[106:109]
	v_mfma_f32_16x16x32_bf16 v[94:97], v[152:155], v[200:203], v[94:97]
	v_mfma_f32_16x16x32_bf16 v[90:93], v[160:163], v[200:203], v[90:93]
	v_mfma_f32_16x16x32_bf16 v[78:81], v[152:155], v[208:211], v[78:81]
	v_mfma_f32_16x16x32_bf16 v[74:77], v[160:163], v[208:211], v[74:77]
	v_mfma_f32_16x16x32_bf16 v[126:129], v[156:159], v[188:191], v[126:129]
	v_mfma_f32_16x16x32_bf16 v[122:125], v[164:167], v[188:191], v[122:125]
	v_mfma_f32_16x16x32_bf16 v[110:113], v[156:159], v[196:199], v[110:113]
	v_mfma_f32_16x16x32_bf16 v[106:109], v[164:167], v[196:199], v[106:109]
	v_mfma_f32_16x16x32_bf16 v[94:97], v[156:159], v[204:207], v[94:97]
	v_mfma_f32_16x16x32_bf16 v[90:93], v[164:167], v[204:207], v[90:93]
	v_mfma_f32_16x16x32_bf16 v[78:81], v[156:159], v[212:215], v[78:81]
	v_mfma_f32_16x16x32_bf16 v[74:77], v[164:167], v[212:215], v[74:77]
	v_mfma_f32_16x16x32_bf16 v[118:121], v[168:171], v[184:187], v[118:121]
	v_mfma_f32_16x16x32_bf16 v[114:117], v[176:179], v[184:187], v[114:117]
	v_mfma_f32_16x16x32_bf16 v[102:105], v[168:171], v[192:195], v[102:105]
	v_mfma_f32_16x16x32_bf16 v[98:101], v[176:179], v[192:195], v[98:101]
	v_mfma_f32_16x16x32_bf16 v[86:89], v[168:171], v[200:203], v[86:89]
	v_mfma_f32_16x16x32_bf16 v[82:85], v[176:179], v[200:203], v[82:85]
	v_mfma_f32_16x16x32_bf16 v[70:73], v[168:171], v[208:211], v[70:73]
	v_mfma_f32_16x16x32_bf16 v[66:69], v[176:179], v[208:211], v[66:69]
	v_mfma_f32_16x16x32_bf16 v[118:121], v[172:175], v[188:191], v[118:121]
	v_mfma_f32_16x16x32_bf16 v[114:117], v[180:183], v[188:191], v[114:117]
	v_mfma_f32_16x16x32_bf16 v[102:105], v[172:175], v[196:199], v[102:105]
	v_mfma_f32_16x16x32_bf16 v[98:101], v[180:183], v[196:199], v[98:101]
	v_mfma_f32_16x16x32_bf16 v[86:89], v[172:175], v[204:207], v[86:89]
	v_mfma_f32_16x16x32_bf16 v[82:85], v[180:183], v[204:207], v[82:85]
	v_mfma_f32_16x16x32_bf16 v[70:73], v[172:175], v[212:215], v[70:73]
	v_mfma_f32_16x16x32_bf16 v[66:69], v[180:183], v[212:215], v[66:69]
	s_barrier
	s_add_i32 s59, s72, s40
	s_mov_b32 m0, s59
	ds_read_b128 v[184:187], v150 offset:16384
	ds_read_b128 v[188:191], v150 offset:17408
	ds_read_b128 v[192:195], v150 offset:18432
	ds_read_b128 v[196:199], v150 offset:19456
	ds_read_b128 v[200:203], v150 offset:20480
	ds_read_b128 v[204:207], v150 offset:21504
	ds_read_b128 v[208:211], v150 offset:22528
	ds_read_b128 v[212:215], v150 offset:23552
	global_load_lds_dwordx4 v130, s[36:37]
	s_add_i32 m0, s59, 0x2000
	s_add_u32 s64, s36, 0x4000
	s_addc_u32 s65, s37, 0
	s_add_i32 s59, s73, s40
	global_load_lds_dwordx4 v132, s[36:37]
	s_mov_b32 m0, s59
	s_nop 0
	global_load_lds_dwordx4 v130, s[64:65]
	s_add_i32 m0, s59, 0x2000
	s_nop 0
	global_load_lds_dwordx4 v132, s[64:65]
	s_mov_b32 m0, s41
	s_nop 0
	global_load_lds_dwordx4 v130, s[38:39]
	s_mov_b32 m0, s42
	s_nop 0
	global_load_lds_dwordx4 v132, s[38:39]
	s_waitcnt vmcnt(8)
	s_barrier
	s_waitcnt lgkmcnt(0)
	v_mfma_f32_16x16x32_bf16 v[62:65], v[152:155], v[184:187], v[62:65]
	v_mfma_f32_16x16x32_bf16 v[58:61], v[160:163], v[184:187], v[58:61]
	v_mfma_f32_16x16x32_bf16 v[46:49], v[152:155], v[192:195], v[46:49]
	v_mfma_f32_16x16x32_bf16 v[42:45], v[160:163], v[192:195], v[42:45]
	v_mfma_f32_16x16x32_bf16 v[30:33], v[152:155], v[200:203], v[30:33]
	v_mfma_f32_16x16x32_bf16 v[26:29], v[160:163], v[200:203], v[26:29]
	v_mfma_f32_16x16x32_bf16 v[14:17], v[152:155], v[208:211], v[14:17]
	v_mfma_f32_16x16x32_bf16 v[10:13], v[160:163], v[208:211], v[10:13]
	v_mfma_f32_16x16x32_bf16 v[62:65], v[156:159], v[188:191], v[62:65]
	v_mfma_f32_16x16x32_bf16 v[58:61], v[164:167], v[188:191], v[58:61]
	v_mfma_f32_16x16x32_bf16 v[46:49], v[156:159], v[196:199], v[46:49]
	v_mfma_f32_16x16x32_bf16 v[42:45], v[164:167], v[196:199], v[42:45]
	v_mfma_f32_16x16x32_bf16 v[30:33], v[156:159], v[204:207], v[30:33]
	v_mfma_f32_16x16x32_bf16 v[26:29], v[164:167], v[204:207], v[26:29]
	v_mfma_f32_16x16x32_bf16 v[14:17], v[156:159], v[212:215], v[14:17]
	v_mfma_f32_16x16x32_bf16 v[10:13], v[164:167], v[212:215], v[10:13]
	v_mfma_f32_16x16x32_bf16 v[54:57], v[168:171], v[184:187], v[54:57]
	v_mfma_f32_16x16x32_bf16 v[50:53], v[176:179], v[184:187], v[50:53]
	v_mfma_f32_16x16x32_bf16 v[38:41], v[168:171], v[192:195], v[38:41]
	v_mfma_f32_16x16x32_bf16 v[34:37], v[176:179], v[192:195], v[34:37]
	v_mfma_f32_16x16x32_bf16 v[22:25], v[168:171], v[200:203], v[22:25]
	v_mfma_f32_16x16x32_bf16 v[18:21], v[176:179], v[200:203], v[18:21]
	v_mfma_f32_16x16x32_bf16 v[6:9], v[168:171], v[208:211], v[6:9]
	v_mfma_f32_16x16x32_bf16 v[2:5], v[176:179], v[208:211], v[2:5]
	v_mfma_f32_16x16x32_bf16 v[54:57], v[172:175], v[188:191], v[54:57]
	v_mfma_f32_16x16x32_bf16 v[50:53], v[180:183], v[188:191], v[50:53]
	v_mfma_f32_16x16x32_bf16 v[38:41], v[172:175], v[196:199], v[38:41]
	v_mfma_f32_16x16x32_bf16 v[34:37], v[180:183], v[196:199], v[34:37]
	v_mfma_f32_16x16x32_bf16 v[22:25], v[172:175], v[204:207], v[22:25]
	v_mfma_f32_16x16x32_bf16 v[18:21], v[180:183], v[204:207], v[18:21]
	v_mfma_f32_16x16x32_bf16 v[6:9], v[172:175], v[212:215], v[6:9]
	v_mfma_f32_16x16x32_bf16 v[2:5], v[180:183], v[212:215], v[2:5]
	s_barrier
; #define PG8_STAGE(bufoff, gbase, voff) do { _Pragma("unroll") for (int _i = 0; _i < 2; ++_i) \
;         __builtin_amdgcn_global_load_lds((const unsigned*)((const char*)(gbase) + (voff)[_i]), (LAS unsigned*)(lds + (bufoff) + ldsw + _i * 8192), 16, 0, 0); } while (0)
; #define PG8_LDA(dst, b, h) do { _Pragma("unroll") for (int m = 0; m < 4; ++m) _Pragma("unroll") for (int k = 0; k < 2; ++k) dst[m][k] = *(const LAS bf16x8*)(lds + PG8_SA(b, h) + aoff + m * 2048 + k * 1024); } while (0)
; #define PG8_LDB(dst, b, h) do { _Pragma("unroll") for (int n = 0; n < 2; ++n) _Pragma("unroll") for (int k = 0; k < 2; ++k) dst[n][k] = *(const LAS bf16x8*)(lds + PG8_SB(b, h) + boff + n * 2048 + k * 1024); } while (0)
; #define PG8_MMA(ai, bj, At, Bt) do { __builtin_amdgcn_s_setprio(1); _Pragma("unroll") for (int m = 0; m < 4; ++m) _Pragma("unroll") for (int n = 0; n < 2; ++n) _Pragma("unroll") for (int k = 0; k < 2; ++k) \
;         acc[ai][bj][m][n] = __builtin_amdgcn_mfma_f32_16x16x32_bf16(Bt[n][k], At[m][k], acc[ai][bj][m][n], 0, 0, 0); __builtin_amdgcn_s_setprio(0); } while (0)
; #define PG8_WAIT_V(n) asm volatile("s_waitcnt vmcnt(" #n ")" ::: "memory")
; #define PG8_WAIT_L(n) asm volatile("s_waitcnt lgkmcnt(" #n ")" ::: "memory")
; #define PG8_BAR __builtin_amdgcn_s_barrier()
; #define PG8_SCHED __builtin_amdgcn_sched_barrier(0)
; template <class Epi, class Sched, bool ABLK = false, bool ALIGN_EPI = true, bool SP2 = true, bool BBLK = true>
; __device__ __forceinline__ void gemm_phase(LAS unsigned char* lds, const Gemm g, const Sched& S, const Epi& E) {
;     ...
;             PG8_LDB(B0, 1, 0); PG8_LDB(B1, 1, 1); PG8_SCHED; PG8_LDA(At, 1, 0); PG8_STAGE(PG8_SA(0, 1), a2 + hstepA, voffA);
;             PG8_WAIT_V(8); PG8_WAIT_L(0); PG8_BAR; PG8_MMA(0, 0, At, B0); PG8_MMA(0, 1, At, B1); PG8_BAR; PG8_SCHED;
;             PG8_LDA(At, 1, 1); PG8_STAGE(PG8_SB(1, 0), b3, voffB); PG8_STAGE(PG8_SB(1, 1), b3 + hstepB, voffB); PG8_STAGE(PG8_SA(1, 0), a3, voffA);
;             PG8_WAIT_V(8); PG8_WAIT_L(0); PG8_BAR; PG8_MMA(1, 0, At, B0); PG8_MMA(1, 1, At, B1); PG8_BAR; PG8_SCHED;
;     ...
;         if constexpr (ALIGN_EPI) { if (wr == 0) PG8_BAR; }
	v_add_u32_e32 v151, s60, v146
	ds_read_b128 v[152:155], v151
	ds_read_b128 v[156:159], v151 offset:1024
	ds_read_b128 v[160:163], v151 offset:2048
	ds_read_b128 v[164:167], v151 offset:3072
	v_add_u32_e32 v151, s61, v146
	ds_read_b128 v[168:171], v151
	ds_read_b128 v[172:175], v151 offset:1024
	ds_read_b128 v[176:179], v151 offset:2048
	ds_read_b128 v[180:183], v151 offset:3072
	s_add_u32 s38, s38, 0x4000
	s_addc_u32 s39, s39, 0
	s_mov_b32 m0, s43
	ds_read_b128 v[184:187], v150 offset:32768
	ds_read_b128 v[188:191], v150 offset:33792
	ds_read_b128 v[192:195], v150 offset:34816
	ds_read_b128 v[196:199], v150 offset:35840
	ds_read_b128 v[200:203], v150 offset:36864
	ds_read_b128 v[204:207], v150 offset:37888
	ds_read_b128 v[208:211], v150 offset:38912
	ds_read_b128 v[212:215], v150 offset:39936
	global_load_lds_dwordx4 v130, s[38:39]
	s_mov_b32 m0, s44
	s_nop 0
	global_load_lds_dwordx4 v132, s[38:39]
	s_waitcnt vmcnt(8)
	s_barrier
	s_waitcnt lgkmcnt(0)
	v_mfma_f32_16x16x32_bf16 v[126:129], v[152:155], v[184:187], v[126:129]
	v_mfma_f32_16x16x32_bf16 v[122:125], v[160:163], v[184:187], v[122:125]
	v_mfma_f32_16x16x32_bf16 v[110:113], v[152:155], v[192:195], v[110:113]
	v_mfma_f32_16x16x32_bf16 v[106:109], v[160:163], v[192:195], v[106:109]
	v_mfma_f32_16x16x32_bf16 v[94:97], v[152:155], v[200:203], v[94:97]
	v_mfma_f32_16x16x32_bf16 v[90:93], v[160:163], v[200:203], v[90:93]
	v_mfma_f32_16x16x32_bf16 v[78:81], v[152:155], v[208:211], v[78:81]
	v_mfma_f32_16x16x32_bf16 v[74:77], v[160:163], v[208:211], v[74:77]
	v_mfma_f32_16x16x32_bf16 v[126:129], v[156:159], v[188:191], v[126:129]
	v_mfma_f32_16x16x32_bf16 v[122:125], v[164:167], v[188:191], v[122:125]
	v_mfma_f32_16x16x32_bf16 v[110:113], v[156:159], v[196:199], v[110:113]
	v_mfma_f32_16x16x32_bf16 v[106:109], v[164:167], v[196:199], v[106:109]
	v_mfma_f32_16x16x32_bf16 v[94:97], v[156:159], v[204:207], v[94:97]
	v_mfma_f32_16x16x32_bf16 v[90:93], v[164:167], v[204:207], v[90:93]
	v_mfma_f32_16x16x32_bf16 v[78:81], v[156:159], v[212:215], v[78:81]
	v_mfma_f32_16x16x32_bf16 v[74:77], v[164:167], v[212:215], v[74:77]
	v_mfma_f32_16x16x32_bf16 v[118:121], v[168:171], v[184:187], v[118:121]
	v_mfma_f32_16x16x32_bf16 v[114:117], v[176:179], v[184:187], v[114:117]
	v_mfma_f32_16x16x32_bf16 v[102:105], v[168:171], v[192:195], v[102:105]
	v_mfma_f32_16x16x32_bf16 v[98:101], v[176:179], v[192:195], v[98:101]
	v_mfma_f32_16x16x32_bf16 v[86:89], v[168:171], v[200:203], v[86:89]
	v_mfma_f32_16x16x32_bf16 v[82:85], v[176:179], v[200:203], v[82:85]
	v_mfma_f32_16x16x32_bf16 v[70:73], v[168:171], v[208:211], v[70:73]
	v_mfma_f32_16x16x32_bf16 v[66:69], v[176:179], v[208:211], v[66:69]
	v_mfma_f32_16x16x32_bf16 v[118:121], v[172:175], v[188:191], v[118:121]
	v_mfma_f32_16x16x32_bf16 v[114:117], v[180:183], v[188:191], v[114:117]
	v_mfma_f32_16x16x32_bf16 v[102:105], v[172:175], v[196:199], v[102:105]
	v_mfma_f32_16x16x32_bf16 v[98:101], v[180:183], v[196:199], v[98:101]
	v_mfma_f32_16x16x32_bf16 v[86:89], v[172:175], v[204:207], v[86:89]
	v_mfma_f32_16x16x32_bf16 v[82:85], v[180:183], v[204:207], v[82:85]
	v_mfma_f32_16x16x32_bf16 v[70:73], v[172:175], v[212:215], v[70:73]
	v_mfma_f32_16x16x32_bf16 v[66:69], v[180:183], v[212:215], v[66:69]
	s_barrier
	s_add_u32 s38, s36, 0x8000
	s_addc_u32 s39, s37, 0
	s_add_i32 s59, s60, s40
	s_mov_b32 m0, s59
	ds_read_b128 v[184:187], v150 offset:49152
	ds_read_b128 v[188:191], v150 offset:50176
	ds_read_b128 v[192:195], v150 offset:51200
	ds_read_b128 v[196:199], v150 offset:52224
	ds_read_b128 v[200:203], v150 offset:53248
	ds_read_b128 v[204:207], v150 offset:54272
	ds_read_b128 v[208:211], v150 offset:55296
	ds_read_b128 v[212:215], v150 offset:56320
	global_load_lds_dwordx4 v130, s[38:39]
	s_add_i32 m0, s59, 0x2000
	s_add_u32 s36, s36, 0xc000
	v_lshl_add_u64 v[216:217], s[38:39], 0, v[132:133]
	s_addc_u32 s37, s37, 0
	s_add_i32 s38, s61, s40
	global_load_lds_dwordx4 v[216:217], off
	s_mov_b32 m0, s38
	s_nop 0
	global_load_lds_dwordx4 v130, s[36:37]
	s_add_i32 m0, s38, 0x2000
	s_nop 0
	global_load_lds_dwordx4 v132, s[36:37]
	s_mov_b32 m0, s45
	s_nop 0
	global_load_lds_dwordx4 v130, s[34:35]
	s_mov_b32 m0, s46
	s_nop 0
	global_load_lds_dwordx4 v132, s[34:35]
	s_waitcnt vmcnt(8)
	s_barrier
	s_waitcnt lgkmcnt(0)
	v_mfma_f32_16x16x32_bf16 v[62:65], v[152:155], v[184:187], v[62:65]
	v_mfma_f32_16x16x32_bf16 v[58:61], v[160:163], v[184:187], v[58:61]
	v_mfma_f32_16x16x32_bf16 v[46:49], v[152:155], v[192:195], v[46:49]
	v_mfma_f32_16x16x32_bf16 v[42:45], v[160:163], v[192:195], v[42:45]
	v_mfma_f32_16x16x32_bf16 v[30:33], v[152:155], v[200:203], v[30:33]
	v_mfma_f32_16x16x32_bf16 v[26:29], v[160:163], v[200:203], v[26:29]
	v_mfma_f32_16x16x32_bf16 v[14:17], v[152:155], v[208:211], v[14:17]
	v_mfma_f32_16x16x32_bf16 v[10:13], v[160:163], v[208:211], v[10:13]
	v_mfma_f32_16x16x32_bf16 v[62:65], v[156:159], v[188:191], v[62:65]
	v_mfma_f32_16x16x32_bf16 v[58:61], v[164:167], v[188:191], v[58:61]
	v_mfma_f32_16x16x32_bf16 v[46:49], v[156:159], v[196:199], v[46:49]
	v_mfma_f32_16x16x32_bf16 v[42:45], v[164:167], v[196:199], v[42:45]
	v_mfma_f32_16x16x32_bf16 v[30:33], v[156:159], v[204:207], v[30:33]
	v_mfma_f32_16x16x32_bf16 v[26:29], v[164:167], v[204:207], v[26:29]
	v_mfma_f32_16x16x32_bf16 v[14:17], v[156:159], v[212:215], v[14:17]
	v_mfma_f32_16x16x32_bf16 v[10:13], v[164:167], v[212:215], v[10:13]
	v_mfma_f32_16x16x32_bf16 v[54:57], v[168:171], v[184:187], v[54:57]
	v_mfma_f32_16x16x32_bf16 v[50:53], v[176:179], v[184:187], v[50:53]
	v_mfma_f32_16x16x32_bf16 v[38:41], v[168:171], v[192:195], v[38:41]
	v_mfma_f32_16x16x32_bf16 v[34:37], v[176:179], v[192:195], v[34:37]
	v_mfma_f32_16x16x32_bf16 v[22:25], v[168:171], v[200:203], v[22:25]
	v_mfma_f32_16x16x32_bf16 v[18:21], v[176:179], v[200:203], v[18:21]
	v_mfma_f32_16x16x32_bf16 v[6:9], v[168:171], v[208:211], v[6:9]
	v_mfma_f32_16x16x32_bf16 v[2:5], v[176:179], v[208:211], v[2:5]
	v_mfma_f32_16x16x32_bf16 v[54:57], v[172:175], v[188:191], v[54:57]
	v_mfma_f32_16x16x32_bf16 v[50:53], v[180:183], v[188:191], v[50:53]
	v_mfma_f32_16x16x32_bf16 v[38:41], v[172:175], v[196:199], v[38:41]
	v_mfma_f32_16x16x32_bf16 v[34:37], v[180:183], v[196:199], v[34:37]
	v_mfma_f32_16x16x32_bf16 v[22:25], v[172:175], v[204:207], v[22:25]
	v_mfma_f32_16x16x32_bf16 v[18:21], v[180:183], v[204:207], v[18:21]
	v_mfma_f32_16x16x32_bf16 v[6:9], v[172:175], v[212:215], v[6:9]
	v_mfma_f32_16x16x32_bf16 v[2:5], v[180:183], v[212:215], v[2:5]
	s_barrier
	s_add_u32 s30, s30, 0x10000
	s_addc_u32 s31, s31, 0
	s_cmp_ge_u32 s58, s48
	s_cbranch_scc0 .LBB0_1907
	s_and_b64 vcc, exec, s[6:7]
	s_cbranch_vccz .LBB0_1910
	s_barrier

; #define PG8_STAGE(bufoff, gbase, voff) do { _Pragma("unroll") for (int _i = 0; _i < 2; ++_i) \
;         __builtin_amdgcn_global_load_lds((const unsigned*)((const char*)(gbase) + (voff)[_i]), (LAS unsigned*)(lds + (bufoff) + ldsw + _i * 8192), 16, 0, 0); } while (0)
; #define PG8_LDA(dst, b, h) do { _Pragma("unroll") for (int m = 0; m < 4; ++m) _Pragma("unroll") for (int k = 0; k < 2; ++k) dst[m][k] = *(const LAS bf16x8*)(lds + PG8_SA(b, h) + aoff + m * 2048 + k * 1024); } while (0)
; #define PG8_LDB(dst, b, h) do { _Pragma("unroll") for (int n = 0; n < 2; ++n) _Pragma("unroll") for (int k = 0; k < 2; ++k) dst[n][k] = *(const LAS bf16x8*)(lds + PG8_SB(b, h) + boff + n * 2048 + k * 1024); } while (0)
; #define PG8_WAIT_V(n) asm volatile("s_waitcnt vmcnt(" #n ")" ::: "memory")
; #define PG8_WAIT_L(n) asm volatile("s_waitcnt lgkmcnt(" #n ")" ::: "memory")
; #define PG8_BAR __builtin_amdgcn_s_barrier()
; #define PG8_SCHED __builtin_amdgcn_sched_barrier(0)
; template <class Epi, class Sched, bool ABLK = false, bool ALIGN_EPI = true, bool SP2 = true, bool BBLK = true>
; __device__ __forceinline__ void gemm_phase(LAS unsigned char* lds, const Gemm g, const Sched& S, const Epi& E) {
;     ...
;         const bool has_next = S.next(ui + 1, nxt);
;         const int nt = cur.nt;
;         const char* nuA = has_next ? a_unit(nxt) : uA; const int ntbA = has_next ? nxt.k0 / BK : tbA; const char* nB = has_next ? (const char*)g.Bt + (size_t)nxt.pn * tstepB + b_k0(nxt.k0) : cB;
;         for (int t = 0; t < nt; t += 2) {
;             const bool last = (t == nt - 2);
;             const char* a1 = a_tile(uA, tbA + t + 1);
;             const char* a2 = last ? a_tile(nuA, ntbA) : a_tile(uA, tbA + t + 2); const char* b2 = last ? nB : cB + (size_t)(t + 2) * kstepB;
;             const char* a3 = last ? a_tile(nuA, ntbA + 1) : a_tile(uA, tbA + t + 3); const char* b3 = b2 + kstepB;
;             if (last && has_next) S.a_ready(nxt);
;             if constexpr (SP2) {
;             PG8_LDB(B0, 0, 0); PG8_LDB(B1, 0, 1); PG8_SCHED; PG8_LDA(At, 0, 0); PG8_STAGE(PG8_SA(1, 1), a1 + hstepA, voffA);
;             PG8_WAIT_V(8); PG8_WAIT_L(0); PG8_BAR; PG8_MMA(0, 0, At, B0); PG8_MMA(0, 1, At, B1); PG8_BAR; PG8_SCHED;
;             PG8_LDA(At, 0, 1); PG8_STAGE(PG8_SB(0, 0), b2, voffB); PG8_STAGE(PG8_SB(0, 1), b2 + hstepB, voffB); PG8_STAGE(PG8_SA(0, 0), a2, voffA);
.LBB0_2137:
	s_ashr_i32 s11, s10, 31
	s_lshl_b64 s[4:5], s[10:11], 20
	s_add_u32 s14, s37, s4
	s_addc_u32 s15, s38, s5
	s_and_b64 s[4:5], s[16:17], exec
	s_cselect_b32 s4, s15, s25
	s_cselect_b32 s5, s14, s24
	s_ashr_i32 s13, s12, 31
	s_lshl_b64 s[18:19], s[12:13], 20
	s_add_u32 s18, s1, s18
	s_addc_u32 s19, s33, s19
	s_and_b64 s[28:29], s[16:17], exec
	s_cselect_b32 s11, s19, s27
	s_cselect_b32 s13, s18, s26
	s_add_u32 s48, s5, 0x80
	s_addc_u32 s49, s4, 0
	s_add_u32 s50, s26, 0x10000
	v_mov_b32_e32 v2, 0
	s_addc_u32 s51, s27, 0
	v_lshl_add_u64 v[142:143], s[24:25], 0, v[138:139]
	v_lshl_add_u64 v[144:145], s[24:25], 0, v[140:141]
	s_mov_b32 s52, -2
	s_mov_b64 s[26:27], 0
	ds_read_b128 v[152:155], v148
	ds_read_b128 v[156:159], v148 offset:1024
	ds_read_b128 v[160:163], v148 offset:2048
	ds_read_b128 v[164:167], v148 offset:3072
	ds_read_b128 v[168:171], v149
	ds_read_b128 v[172:175], v149 offset:1024
	ds_read_b128 v[176:179], v149 offset:2048
	ds_read_b128 v[180:183], v149 offset:3072
	s_add_u32 s28, s24, s26
	s_addc_u32 s29, s25, s27
	s_add_u32 s34, s28, 0x100
	s_addc_u32 s35, s29, 0
	s_add_u32 s28, s28, 0x180
	s_addc_u32 s29, s29, 0
	s_cmpk_eq_i32 s26, 0xf00
	s_cselect_b32 s29, s49, s29
	s_cselect_b32 s28, s48, s28
	s_cselect_b32 s31, s11, s51
	s_cselect_b32 s30, s13, s50
	s_cselect_b32 s35, s4, s35
	s_cselect_b32 s34, s5, s34
	s_mov_b32 m0, s47
	v_lshl_add_u64 v[216:217], v[142:143], 0, s[26:27]
	ds_read_b128 v[184:187], v150
	ds_read_b128 v[188:191], v150 offset:1024
	ds_read_b128 v[192:195], v150 offset:2048
	ds_read_b128 v[196:199], v150 offset:3072
	ds_read_b128 v[200:203], v150 offset:4096
	ds_read_b128 v[204:207], v150 offset:5120
	ds_read_b128 v[208:211], v150 offset:6144
	ds_read_b128 v[212:215], v150 offset:7168
	global_load_lds_dwordx4 v[216:217], off
	v_lshl_add_u64 v[216:217], v[144:145], 0, s[26:27]
	s_add_i32 m0, s21, 0xe000
	s_nop 0
	global_load_lds_dwordx4 v[216:217], off
	s_waitcnt vmcnt(8)
	s_barrier
	s_waitcnt lgkmcnt(0)
	v_mfma_f32_16x16x32_bf16 v[122:125], v[152:155], v[184:187], 0
	v_mfma_f32_16x16x32_bf16 v[118:121], v[160:163], v[184:187], 0
	v_mfma_f32_16x16x32_bf16 v[106:109], v[152:155], v[192:195], 0
	v_mfma_f32_16x16x32_bf16 v[102:105], v[160:163], v[192:195], 0
	v_mfma_f32_16x16x32_bf16 v[90:93], v[152:155], v[200:203], 0
	v_mfma_f32_16x16x32_bf16 v[86:89], v[160:163], v[200:203], 0
	v_mfma_f32_16x16x32_bf16 v[74:77], v[152:155], v[208:211], 0
	v_mfma_f32_16x16x32_bf16 v[70:73], v[160:163], v[208:211], 0
	v_mfma_f32_16x16x32_bf16 v[122:125], v[156:159], v[188:191], v[122:125]
	v_mfma_f32_16x16x32_bf16 v[118:121], v[164:167], v[188:191], v[118:121]
	v_mfma_f32_16x16x32_bf16 v[106:109], v[156:159], v[196:199], v[106:109]
	v_mfma_f32_16x16x32_bf16 v[102:105], v[164:167], v[196:199], v[102:105]
	v_mfma_f32_16x16x32_bf16 v[90:93], v[156:159], v[204:207], v[90:93]
	v_mfma_f32_16x16x32_bf16 v[86:89], v[164:167], v[204:207], v[86:89]
	v_mfma_f32_16x16x32_bf16 v[74:77], v[156:159], v[212:215], v[74:77]
	v_mfma_f32_16x16x32_bf16 v[70:73], v[164:167], v[212:215], v[70:73]
	v_mfma_f32_16x16x32_bf16 v[126:129], v[168:171], v[184:187], 0
	v_mfma_f32_16x16x32_bf16 v[114:117], v[176:179], v[184:187], 0
	v_mfma_f32_16x16x32_bf16 v[110:113], v[168:171], v[192:195], 0
	v_mfma_f32_16x16x32_bf16 v[98:101], v[176:179], v[192:195], 0
	v_mfma_f32_16x16x32_bf16 v[94:97], v[168:171], v[200:203], 0
	v_mfma_f32_16x16x32_bf16 v[82:85], v[176:179], v[200:203], 0
	v_mfma_f32_16x16x32_bf16 v[78:81], v[168:171], v[208:211], 0
	v_mfma_f32_16x16x32_bf16 v[66:69], v[176:179], v[208:211], 0
	v_mfma_f32_16x16x32_bf16 v[126:129], v[172:175], v[188:191], v[126:129]
	v_mfma_f32_16x16x32_bf16 v[114:117], v[180:183], v[188:191], v[114:117]
	v_mfma_f32_16x16x32_bf16 v[110:113], v[172:175], v[196:199], v[110:113]
	v_mfma_f32_16x16x32_bf16 v[98:101], v[180:183], v[196:199], v[98:101]
	v_mfma_f32_16x16x32_bf16 v[94:97], v[172:175], v[204:207], v[94:97]
	v_mfma_f32_16x16x32_bf16 v[82:85], v[180:183], v[204:207], v[82:85]
	v_mfma_f32_16x16x32_bf16 v[78:81], v[172:175], v[212:215], v[78:81]
	v_mfma_f32_16x16x32_bf16 v[66:69], v[180:183], v[212:215], v[66:69]
	s_barrier
	s_add_i32 s53, s72, s36
	s_mov_b32 m0, s53
	ds_read_b128 v[184:187], v150 offset:16384
	ds_read_b128 v[188:191], v150 offset:17408
	ds_read_b128 v[192:195], v150 offset:18432
	ds_read_b128 v[196:199], v150 offset:19456
	ds_read_b128 v[200:203], v150 offset:20480
	ds_read_b128 v[204:207], v150 offset:21504
	ds_read_b128 v[208:211], v150 offset:22528
	ds_read_b128 v[212:215], v150 offset:23552
	global_load_lds_dwordx4 v134, s[30:31]
	s_add_i32 m0, s53, 0x2000
	s_add_u32 s54, s30, 0x4000
	s_addc_u32 s55, s31, 0
	s_add_i32 s53, s73, s36
	global_load_lds_dwordx4 v130, s[30:31]
	s_mov_b32 m0, s53
	s_nop 0
	global_load_lds_dwordx4 v134, s[54:55]
	s_add_i32 m0, s53, 0x2000
	s_nop 0
	global_load_lds_dwordx4 v130, s[54:55]
	s_mov_b32 m0, s21
	s_nop 0
	global_load_lds_dwordx4 v136, s[34:35]
	s_mov_b32 m0, s23
	s_nop 0
	global_load_lds_dwordx4 v132, s[34:35]
	s_waitcnt vmcnt(8)
	s_barrier
; #define PG8_STAGE(bufoff, gbase, voff) do { _Pragma("unroll") for (int _i = 0; _i < 2; ++_i) \
;         __builtin_amdgcn_global_load_lds((const unsigned*)((const char*)(gbase) + (voff)[_i]), (LAS unsigned*)(lds + (bufoff) + ldsw + _i * 8192), 16, 0, 0); } while (0)
; #define PG8_LDA(dst, b, h) do { _Pragma("unroll") for (int m = 0; m < 4; ++m) _Pragma("unroll") for (int k = 0; k < 2; ++k) dst[m][k] = *(const LAS bf16x8*)(lds + PG8_SA(b, h) + aoff + m * 2048 + k * 1024); } while (0)
; #define PG8_LDB(dst, b, h) do { _Pragma("unroll") for (int n = 0; n < 2; ++n) _Pragma("unroll") for (int k = 0; k < 2; ++k) dst[n][k] = *(const LAS bf16x8*)(lds + PG8_SB(b, h) + boff + n * 2048 + k * 1024); } while (0)
; #define PG8_MMA(ai, bj, At, Bt) do { __builtin_amdgcn_s_setprio(1); _Pragma("unroll") for (int m = 0; m < 4; ++m) _Pragma("unroll") for (int n = 0; n < 2; ++n) _Pragma("unroll") for (int k = 0; k < 2; ++k) \
;         acc[ai][bj][m][n] = __builtin_amdgcn_mfma_f32_16x16x32_bf16(Bt[n][k], At[m][k], acc[ai][bj][m][n], 0, 0, 0); __builtin_amdgcn_s_setprio(0); } while (0)
; #define PG8_WAIT_V(n) asm volatile("s_waitcnt vmcnt(" #n ")" ::: "memory")
; #define PG8_WAIT_L(n) asm volatile("s_waitcnt lgkmcnt(" #n ")" ::: "memory")
; #define PG8_BAR __builtin_amdgcn_s_barrier()
; #define PG8_SCHED __builtin_amdgcn_sched_barrier(0)
; template <class Epi, class Sched, bool ABLK = false, bool ALIGN_EPI = true, bool SP2 = true, bool BBLK = true>
; __device__ __forceinline__ void gemm_phase(LAS unsigned char* lds, const Gemm g, const Sched& S, const Epi& E) {
;     ...
;             PG8_WAIT_V(8); PG8_WAIT_L(0); PG8_BAR; PG8_MMA(1, 0, At, B0); PG8_MMA(1, 1, At, B1); PG8_BAR; PG8_SCHED;
;             PG8_LDB(B0, 1, 0); PG8_LDB(B1, 1, 1); PG8_SCHED; PG8_LDA(At, 1, 0); PG8_STAGE(PG8_SA(0, 1), a2 + hstepA, voffA);
;             PG8_WAIT_V(8); PG8_WAIT_L(0); PG8_BAR; PG8_MMA(0, 0, At, B0); PG8_MMA(0, 1, At, B1); PG8_BAR; PG8_SCHED;
	s_waitcnt lgkmcnt(0)
	v_mfma_f32_16x16x32_bf16 v[58:61], v[152:155], v[184:187], 0
	v_mfma_f32_16x16x32_bf16 v[54:57], v[160:163], v[184:187], 0
	v_mfma_f32_16x16x32_bf16 v[42:45], v[152:155], v[192:195], 0
	v_mfma_f32_16x16x32_bf16 v[38:41], v[160:163], v[192:195], 0
	v_mfma_f32_16x16x32_bf16 v[26:29], v[152:155], v[200:203], 0
	v_mfma_f32_16x16x32_bf16 v[22:25], v[160:163], v[200:203], 0
	v_mfma_f32_16x16x32_bf16 v[10:13], v[152:155], v[208:211], 0
	v_mfma_f32_16x16x32_bf16 v[6:9], v[160:163], v[208:211], 0
	v_mfma_f32_16x16x32_bf16 v[58:61], v[156:159], v[188:191], v[58:61]
	v_mfma_f32_16x16x32_bf16 v[54:57], v[164:167], v[188:191], v[54:57]
	v_mfma_f32_16x16x32_bf16 v[42:45], v[156:159], v[196:199], v[42:45]
	v_mfma_f32_16x16x32_bf16 v[38:41], v[164:167], v[196:199], v[38:41]
	v_mfma_f32_16x16x32_bf16 v[26:29], v[156:159], v[204:207], v[26:29]
	v_mfma_f32_16x16x32_bf16 v[22:25], v[164:167], v[204:207], v[22:25]
	v_mfma_f32_16x16x32_bf16 v[10:13], v[156:159], v[212:215], v[10:13]
	v_mfma_f32_16x16x32_bf16 v[6:9], v[164:167], v[212:215], v[6:9]
	v_mfma_f32_16x16x32_bf16 v[62:65], v[168:171], v[184:187], 0
	v_mfma_f32_16x16x32_bf16 v[50:53], v[176:179], v[184:187], 0
	v_mfma_f32_16x16x32_bf16 v[46:49], v[168:171], v[192:195], 0
	v_mfma_f32_16x16x32_bf16 v[34:37], v[176:179], v[192:195], 0
	v_mfma_f32_16x16x32_bf16 v[30:33], v[168:171], v[200:203], 0
	v_mfma_f32_16x16x32_bf16 v[18:21], v[176:179], v[200:203], 0
	v_mfma_f32_16x16x32_bf16 v[14:17], v[168:171], v[208:211], 0
	v_mfma_f32_16x16x32_bf16 v[2:5], v[176:179], v[208:211], 0
	v_mfma_f32_16x16x32_bf16 v[62:65], v[172:175], v[188:191], v[62:65]
	v_mfma_f32_16x16x32_bf16 v[50:53], v[180:183], v[188:191], v[50:53]
	v_mfma_f32_16x16x32_bf16 v[46:49], v[172:175], v[196:199], v[46:49]
	v_mfma_f32_16x16x32_bf16 v[34:37], v[180:183], v[196:199], v[34:37]
	v_mfma_f32_16x16x32_bf16 v[30:33], v[172:175], v[204:207], v[30:33]
	v_mfma_f32_16x16x32_bf16 v[18:21], v[180:183], v[204:207], v[18:21]
	v_mfma_f32_16x16x32_bf16 v[14:17], v[172:175], v[212:215], v[14:17]
	v_mfma_f32_16x16x32_bf16 v[2:5], v[180:183], v[212:215], v[2:5]
	s_barrier
	v_add_u32_e32 v151, s60, v146
	ds_read_b128 v[152:155], v151
	ds_read_b128 v[156:159], v151 offset:1024
	ds_read_b128 v[160:163], v151 offset:2048
	ds_read_b128 v[164:167], v151 offset:3072
	v_add_u32_e32 v151, s61, v146
	ds_read_b128 v[168:171], v151
	ds_read_b128 v[172:175], v151 offset:1024
	ds_read_b128 v[176:179], v151 offset:2048
	ds_read_b128 v[180:183], v151 offset:3072
	s_add_u32 s34, s34, 0x80000
	s_addc_u32 s35, s35, 0
	s_mov_b32 m0, s39
	ds_read_b128 v[184:187], v150 offset:32768
	ds_read_b128 v[188:191], v150 offset:33792
	ds_read_b128 v[192:195], v150 offset:34816
	ds_read_b128 v[196:199], v150 offset:35840
	ds_read_b128 v[200:203], v150 offset:36864
	ds_read_b128 v[204:207], v150 offset:37888
	ds_read_b128 v[208:211], v150 offset:38912
	ds_read_b128 v[212:215], v150 offset:39936
	global_load_lds_dwordx4 v136, s[34:35]
	s_mov_b32 m0, s40
	s_nop 0
	global_load_lds_dwordx4 v132, s[34:35]
	s_waitcnt vmcnt(8)
	s_barrier
	s_waitcnt lgkmcnt(0)
	v_mfma_f32_16x16x32_bf16 v[122:125], v[152:155], v[184:187], v[122:125]
	v_mfma_f32_16x16x32_bf16 v[118:121], v[160:163], v[184:187], v[118:121]
	v_mfma_f32_16x16x32_bf16 v[106:109], v[152:155], v[192:195], v[106:109]
	v_mfma_f32_16x16x32_bf16 v[102:105], v[160:163], v[192:195], v[102:105]
	v_mfma_f32_16x16x32_bf16 v[90:93], v[152:155], v[200:203], v[90:93]
	v_mfma_f32_16x16x32_bf16 v[86:89], v[160:163], v[200:203], v[86:89]
	v_mfma_f32_16x16x32_bf16 v[74:77], v[152:155], v[208:211], v[74:77]
	v_mfma_f32_16x16x32_bf16 v[70:73], v[160:163], v[208:211], v[70:73]
	v_mfma_f32_16x16x32_bf16 v[122:125], v[156:159], v[188:191], v[122:125]
	v_mfma_f32_16x16x32_bf16 v[118:121], v[164:167], v[188:191], v[118:121]
	v_mfma_f32_16x16x32_bf16 v[106:109], v[156:159], v[196:199], v[106:109]
	v_mfma_f32_16x16x32_bf16 v[102:105], v[164:167], v[196:199], v[102:105]
	v_mfma_f32_16x16x32_bf16 v[90:93], v[156:159], v[204:207], v[90:93]
	v_mfma_f32_16x16x32_bf16 v[86:89], v[164:167], v[204:207], v[86:89]
	v_mfma_f32_16x16x32_bf16 v[74:77], v[156:159], v[212:215], v[74:77]
	v_mfma_f32_16x16x32_bf16 v[70:73], v[164:167], v[212:215], v[70:73]
	v_mfma_f32_16x16x32_bf16 v[126:129], v[168:171], v[184:187], v[126:129]
	v_mfma_f32_16x16x32_bf16 v[114:117], v[176:179], v[184:187], v[114:117]
	v_mfma_f32_16x16x32_bf16 v[110:113], v[168:171], v[192:195], v[110:113]
	v_mfma_f32_16x16x32_bf16 v[98:101], v[176:179], v[192:195], v[98:101]
	v_mfma_f32_16x16x32_bf16 v[94:97], v[168:171], v[200:203], v[94:97]
	v_mfma_f32_16x16x32_bf16 v[82:85], v[176:179], v[200:203], v[82:85]
	v_mfma_f32_16x16x32_bf16 v[78:81], v[168:171], v[208:211], v[78:81]
	v_mfma_f32_16x16x32_bf16 v[66:69], v[176:179], v[208:211], v[66:69]
	v_mfma_f32_16x16x32_bf16 v[126:129], v[172:175], v[188:191], v[126:129]
	v_mfma_f32_16x16x32_bf16 v[114:117], v[180:183], v[188:191], v[114:117]
	v_mfma_f32_16x16x32_bf16 v[110:113], v[172:175], v[196:199], v[110:113]
	v_mfma_f32_16x16x32_bf16 v[98:101], v[180:183], v[196:199], v[98:101]
	v_mfma_f32_16x16x32_bf16 v[94:97], v[172:175], v[204:207], v[94:97]
	v_mfma_f32_16x16x32_bf16 v[82:85], v[180:183], v[204:207], v[82:85]
	v_mfma_f32_16x16x32_bf16 v[78:81], v[172:175], v[212:215], v[78:81]
	v_mfma_f32_16x16x32_bf16 v[66:69], v[180:183], v[212:215], v[66:69]
	s_barrier
; #define PG8_STAGE(bufoff, gbase, voff) do { _Pragma("unroll") for (int _i = 0; _i < 2; ++_i) \
;         __builtin_amdgcn_global_load_lds((const unsigned*)((const char*)(gbase) + (voff)[_i]), (LAS unsigned*)(lds + (bufoff) + ldsw + _i * 8192), 16, 0, 0); } while (0)
; #define PG8_LDA(dst, b, h) do { _Pragma("unroll") for (int m = 0; m < 4; ++m) _Pragma("unroll") for (int k = 0; k < 2; ++k) dst[m][k] = *(const LAS bf16x8*)(lds + PG8_SA(b, h) + aoff + m * 2048 + k * 1024); } while (0)
; #define PG8_LDB(dst, b, h) do { _Pragma("unroll") for (int n = 0; n < 2; ++n) _Pragma("unroll") for (int k = 0; k < 2; ++k) dst[n][k] = *(const LAS bf16x8*)(lds + PG8_SB(b, h) + boff + n * 2048 + k * 1024); } while (0)
; #define PG8_WAIT_V(n) asm volatile("s_waitcnt vmcnt(" #n ")" ::: "memory")
; #define PG8_WAIT_L(n) asm volatile("s_waitcnt lgkmcnt(" #n ")" ::: "memory")
; #define PG8_BAR __builtin_amdgcn_s_barrier()
; #define PG8_SCHED __builtin_amdgcn_sched_barrier(0)
; template <class Epi, class Sched, bool ABLK = false, bool ALIGN_EPI = true, bool SP2 = true, bool BBLK = true>
; __device__ __forceinline__ void gemm_phase(LAS unsigned char* lds, const Gemm g, const Sched& S, const Epi& E) {
;     ...
;         for (int t = 0; t < nt; t += 2) {
;             const bool last = (t == nt - 2);
;             const char* a1 = a_tile(uA, tbA + t + 1);
;             const char* a2 = last ? a_tile(nuA, ntbA) : a_tile(uA, tbA + t + 2); const char* b2 = last ? nB : cB + (size_t)(t + 2) * kstepB;
;             const char* a3 = last ? a_tile(nuA, ntbA + 1) : a_tile(uA, tbA + t + 3); const char* b3 = b2 + kstepB;
;             if (last && has_next) S.a_ready(nxt);
;             if constexpr (SP2) {
;             PG8_LDB(B0, 0, 0); PG8_LDB(B1, 0, 1); PG8_SCHED; PG8_LDA(At, 0, 0); PG8_STAGE(PG8_SA(1, 1), a1 + hstepA, voffA);
;             PG8_WAIT_V(8); PG8_WAIT_L(0); PG8_BAR; PG8_MMA(0, 0, At, B0); PG8_MMA(0, 1, At, B1); PG8_BAR; PG8_SCHED;
;     ...
;             PG8_WAIT_V(8); PG8_WAIT_L(0); PG8_BAR; PG8_MMA(0, 0, At, B0); PG8_MMA(0, 1, At, B1); PG8_BAR; PG8_SCHED;
;             PG8_LDA(At, 1, 1); PG8_STAGE(PG8_SB(1, 0), b3, voffB); PG8_STAGE(PG8_SB(1, 1), b3 + hstepB, voffB); PG8_STAGE(PG8_SA(1, 0), a3, voffA);
;             PG8_WAIT_V(8); PG8_WAIT_L(0); PG8_BAR; PG8_MMA(1, 0, At, B0); PG8_MMA(1, 1, At, B1); PG8_BAR; PG8_SCHED;
	s_add_u32 s34, s30, 0x8000
	s_addc_u32 s35, s31, 0
	s_add_i32 s53, s60, s36
	s_mov_b32 m0, s53
	ds_read_b128 v[184:187], v150 offset:49152
	ds_read_b128 v[188:191], v150 offset:50176
	ds_read_b128 v[192:195], v150 offset:51200
	ds_read_b128 v[196:199], v150 offset:52224
	ds_read_b128 v[200:203], v150 offset:53248
	ds_read_b128 v[204:207], v150 offset:54272
	ds_read_b128 v[208:211], v150 offset:55296
	ds_read_b128 v[212:215], v150 offset:56320
	global_load_lds_dwordx4 v134, s[34:35]
	s_add_i32 m0, s53, 0x2000
	s_add_u32 s30, s30, 0xc000
	v_lshl_add_u64 v[216:217], s[34:35], 0, v[130:131]
	s_addc_u32 s31, s31, 0
	s_add_i32 s34, s61, s36
	global_load_lds_dwordx4 v[216:217], off
	s_mov_b32 m0, s34
	s_nop 0
	global_load_lds_dwordx4 v134, s[30:31]
	s_add_i32 m0, s34, 0x2000
	s_nop 0
	global_load_lds_dwordx4 v130, s[30:31]
	s_mov_b32 m0, s42
	s_nop 0
	global_load_lds_dwordx4 v136, s[28:29]
	s_mov_b32 m0, s43
	s_nop 0
	global_load_lds_dwordx4 v132, s[28:29]
	s_waitcnt vmcnt(8)
	s_barrier
	s_waitcnt lgkmcnt(0)
	v_mfma_f32_16x16x32_bf16 v[58:61], v[152:155], v[184:187], v[58:61]
	v_mfma_f32_16x16x32_bf16 v[54:57], v[160:163], v[184:187], v[54:57]
	v_mfma_f32_16x16x32_bf16 v[42:45], v[152:155], v[192:195], v[42:45]
	v_mfma_f32_16x16x32_bf16 v[38:41], v[160:163], v[192:195], v[38:41]
	v_mfma_f32_16x16x32_bf16 v[26:29], v[152:155], v[200:203], v[26:29]
	v_mfma_f32_16x16x32_bf16 v[22:25], v[160:163], v[200:203], v[22:25]
	v_mfma_f32_16x16x32_bf16 v[10:13], v[152:155], v[208:211], v[10:13]
	v_mfma_f32_16x16x32_bf16 v[6:9], v[160:163], v[208:211], v[6:9]
	v_mfma_f32_16x16x32_bf16 v[58:61], v[156:159], v[188:191], v[58:61]
	v_mfma_f32_16x16x32_bf16 v[54:57], v[164:167], v[188:191], v[54:57]
	v_mfma_f32_16x16x32_bf16 v[42:45], v[156:159], v[196:199], v[42:45]
	v_mfma_f32_16x16x32_bf16 v[38:41], v[164:167], v[196:199], v[38:41]
	v_mfma_f32_16x16x32_bf16 v[26:29], v[156:159], v[204:207], v[26:29]
	v_mfma_f32_16x16x32_bf16 v[22:25], v[164:167], v[204:207], v[22:25]
	v_mfma_f32_16x16x32_bf16 v[10:13], v[156:159], v[212:215], v[10:13]
	v_mfma_f32_16x16x32_bf16 v[6:9], v[164:167], v[212:215], v[6:9]
	v_mfma_f32_16x16x32_bf16 v[62:65], v[168:171], v[184:187], v[62:65]
	v_mfma_f32_16x16x32_bf16 v[50:53], v[176:179], v[184:187], v[50:53]
	v_mfma_f32_16x16x32_bf16 v[46:49], v[168:171], v[192:195], v[46:49]
	v_mfma_f32_16x16x32_bf16 v[34:37], v[176:179], v[192:195], v[34:37]
	v_mfma_f32_16x16x32_bf16 v[30:33], v[168:171], v[200:203], v[30:33]
	v_mfma_f32_16x16x32_bf16 v[18:21], v[176:179], v[200:203], v[18:21]
	v_mfma_f32_16x16x32_bf16 v[14:17], v[168:171], v[208:211], v[14:17]
	v_mfma_f32_16x16x32_bf16 v[2:5], v[176:179], v[208:211], v[2:5]
	v_mfma_f32_16x16x32_bf16 v[62:65], v[172:175], v[188:191], v[62:65]
	v_mfma_f32_16x16x32_bf16 v[50:53], v[180:183], v[188:191], v[50:53]
	v_mfma_f32_16x16x32_bf16 v[46:49], v[172:175], v[196:199], v[46:49]
	v_mfma_f32_16x16x32_bf16 v[34:37], v[180:183], v[196:199], v[34:37]
	v_mfma_f32_16x16x32_bf16 v[30:33], v[172:175], v[204:207], v[30:33]
	v_mfma_f32_16x16x32_bf16 v[18:21], v[180:183], v[204:207], v[18:21]
	v_mfma_f32_16x16x32_bf16 v[14:17], v[172:175], v[212:215], v[14:17]
	v_mfma_f32_16x16x32_bf16 v[2:5], v[180:183], v[212:215], v[2:5]
	s_barrier
	s_add_i32 s52, s52, 2
	s_add_u32 s26, s26, 0x100
	s_addc_u32 s27, s27, 0
	s_add_u32 s50, s50, 0x10000
	s_addc_u32 s51, s51, 0
	s_cmp_gt_u32 s52, 29
.LBB0_2138:
	ds_read_b128 v[152:155], v148
	ds_read_b128 v[156:159], v148 offset:1024
	ds_read_b128 v[160:163], v148 offset:2048
	ds_read_b128 v[164:167], v148 offset:3072
	ds_read_b128 v[168:171], v149
	ds_read_b128 v[172:175], v149 offset:1024
	ds_read_b128 v[176:179], v149 offset:2048
	ds_read_b128 v[180:183], v149 offset:3072
	s_add_u32 s28, s24, s26
	s_addc_u32 s29, s25, s27
	s_add_u32 s34, s28, 0x100
	s_addc_u32 s35, s29, 0
	s_add_u32 s28, s28, 0x180
	s_addc_u32 s29, s29, 0
	s_cmpk_eq_i32 s26, 0xf00
	s_cselect_b32 s29, s49, s29
	s_cselect_b32 s28, s48, s28
	s_cselect_b32 s31, s11, s51
	s_cselect_b32 s30, s13, s50
	s_cselect_b32 s35, s4, s35
	s_cselect_b32 s34, s5, s34
	s_mov_b32 m0, s47
	v_lshl_add_u64 v[216:217], v[142:143], 0, s[26:27]
	ds_read_b128 v[184:187], v150
	ds_read_b128 v[188:191], v150 offset:1024
	ds_read_b128 v[192:195], v150 offset:2048
	ds_read_b128 v[196:199], v150 offset:3072
	ds_read_b128 v[200:203], v150 offset:4096
	ds_read_b128 v[204:207], v150 offset:5120
	ds_read_b128 v[208:211], v150 offset:6144
	ds_read_b128 v[212:215], v150 offset:7168
	global_load_lds_dwordx4 v[216:217], off
	v_lshl_add_u64 v[216:217], v[144:145], 0, s[26:27]
	s_add_i32 m0, s21, 0xe000
	s_nop 0
	global_load_lds_dwordx4 v[216:217], off
	s_waitcnt vmcnt(8)
	s_barrier
; #define PG8_STAGE(bufoff, gbase, voff) do { _Pragma("unroll") for (int _i = 0; _i < 2; ++_i) \
;         __builtin_amdgcn_global_load_lds((const unsigned*)((const char*)(gbase) + (voff)[_i]), (LAS unsigned*)(lds + (bufoff) + ldsw + _i * 8192), 16, 0, 0); } while (0)
; #define PG8_LDA(dst, b, h) do { _Pragma("unroll") for (int m = 0; m < 4; ++m) _Pragma("unroll") for (int k = 0; k < 2; ++k) dst[m][k] = *(const LAS bf16x8*)(lds + PG8_SA(b, h) + aoff + m * 2048 + k * 1024); } while (0)
; #define PG8_MMA(ai, bj, At, Bt) do { __builtin_amdgcn_s_setprio(1); _Pragma("unroll") for (int m = 0; m < 4; ++m) _Pragma("unroll") for (int n = 0; n < 2; ++n) _Pragma("unroll") for (int k = 0; k < 2; ++k) \
;         acc[ai][bj][m][n] = __builtin_amdgcn_mfma_f32_16x16x32_bf16(Bt[n][k], At[m][k], acc[ai][bj][m][n], 0, 0, 0); __builtin_amdgcn_s_setprio(0); } while (0)
; #define PG8_WAIT_V(n) asm volatile("s_waitcnt vmcnt(" #n ")" ::: "memory")
; #define PG8_WAIT_L(n) asm volatile("s_waitcnt lgkmcnt(" #n ")" ::: "memory")
; #define PG8_BAR __builtin_amdgcn_s_barrier()
; #define PG8_SCHED __builtin_amdgcn_sched_barrier(0)
; template <class Epi, class Sched, bool ABLK = false, bool ALIGN_EPI = true, bool SP2 = true, bool BBLK = true>
; __device__ __forceinline__ void gemm_phase(LAS unsigned char* lds, const Gemm g, const Sched& S, const Epi& E) {
;     ...
;             PG8_WAIT_V(8); PG8_WAIT_L(0); PG8_BAR; PG8_MMA(0, 0, At, B0); PG8_MMA(0, 1, At, B1); PG8_BAR; PG8_SCHED;
;             PG8_LDA(At, 0, 1); PG8_STAGE(PG8_SB(0, 0), b2, voffB); PG8_STAGE(PG8_SB(0, 1), b2 + hstepB, voffB); PG8_STAGE(PG8_SA(0, 0), a2, voffA);
;             PG8_WAIT_V(8); PG8_WAIT_L(0); PG8_BAR; PG8_MMA(1, 0, At, B0); PG8_MMA(1, 1, At, B1); PG8_BAR; PG8_SCHED;
	s_waitcnt lgkmcnt(0)
	v_mfma_f32_16x16x32_bf16 v[122:125], v[152:155], v[184:187], v[122:125]
	v_mfma_f32_16x16x32_bf16 v[118:121], v[160:163], v[184:187], v[118:121]
	v_mfma_f32_16x16x32_bf16 v[106:109], v[152:155], v[192:195], v[106:109]
	v_mfma_f32_16x16x32_bf16 v[102:105], v[160:163], v[192:195], v[102:105]
	v_mfma_f32_16x16x32_bf16 v[90:93], v[152:155], v[200:203], v[90:93]
	v_mfma_f32_16x16x32_bf16 v[86:89], v[160:163], v[200:203], v[86:89]
	v_mfma_f32_16x16x32_bf16 v[74:77], v[152:155], v[208:211], v[74:77]
	v_mfma_f32_16x16x32_bf16 v[70:73], v[160:163], v[208:211], v[70:73]
	v_mfma_f32_16x16x32_bf16 v[122:125], v[156:159], v[188:191], v[122:125]
	v_mfma_f32_16x16x32_bf16 v[118:121], v[164:167], v[188:191], v[118:121]
	v_mfma_f32_16x16x32_bf16 v[106:109], v[156:159], v[196:199], v[106:109]
	v_mfma_f32_16x16x32_bf16 v[102:105], v[164:167], v[196:199], v[102:105]
	v_mfma_f32_16x16x32_bf16 v[90:93], v[156:159], v[204:207], v[90:93]
	v_mfma_f32_16x16x32_bf16 v[86:89], v[164:167], v[204:207], v[86:89]
	v_mfma_f32_16x16x32_bf16 v[74:77], v[156:159], v[212:215], v[74:77]
	v_mfma_f32_16x16x32_bf16 v[70:73], v[164:167], v[212:215], v[70:73]
	v_mfma_f32_16x16x32_bf16 v[126:129], v[168:171], v[184:187], v[126:129]
	v_mfma_f32_16x16x32_bf16 v[114:117], v[176:179], v[184:187], v[114:117]
	v_mfma_f32_16x16x32_bf16 v[110:113], v[168:171], v[192:195], v[110:113]
	v_mfma_f32_16x16x32_bf16 v[98:101], v[176:179], v[192:195], v[98:101]
	v_mfma_f32_16x16x32_bf16 v[94:97], v[168:171], v[200:203], v[94:97]
	v_mfma_f32_16x16x32_bf16 v[82:85], v[176:179], v[200:203], v[82:85]
	v_mfma_f32_16x16x32_bf16 v[78:81], v[168:171], v[208:211], v[78:81]
	v_mfma_f32_16x16x32_bf16 v[66:69], v[176:179], v[208:211], v[66:69]
	v_mfma_f32_16x16x32_bf16 v[126:129], v[172:175], v[188:191], v[126:129]
	v_mfma_f32_16x16x32_bf16 v[114:117], v[180:183], v[188:191], v[114:117]
	v_mfma_f32_16x16x32_bf16 v[110:113], v[172:175], v[196:199], v[110:113]
	v_mfma_f32_16x16x32_bf16 v[98:101], v[180:183], v[196:199], v[98:101]
	v_mfma_f32_16x16x32_bf16 v[94:97], v[172:175], v[204:207], v[94:97]
	v_mfma_f32_16x16x32_bf16 v[82:85], v[180:183], v[204:207], v[82:85]
	v_mfma_f32_16x16x32_bf16 v[78:81], v[172:175], v[212:215], v[78:81]
	v_mfma_f32_16x16x32_bf16 v[66:69], v[180:183], v[212:215], v[66:69]
	s_barrier
	s_add_i32 s53, s72, s36
	s_mov_b32 m0, s53
	ds_read_b128 v[184:187], v150 offset:16384
	ds_read_b128 v[188:191], v150 offset:17408
	ds_read_b128 v[192:195], v150 offset:18432
	ds_read_b128 v[196:199], v150 offset:19456
	ds_read_b128 v[200:203], v150 offset:20480
	ds_read_b128 v[204:207], v150 offset:21504
	ds_read_b128 v[208:211], v150 offset:22528
	ds_read_b128 v[212:215], v150 offset:23552
	global_load_lds_dwordx4 v134, s[30:31]
	s_add_i32 m0, s53, 0x2000
	s_add_u32 s54, s30, 0x4000
	s_addc_u32 s55, s31, 0
	s_add_i32 s53, s73, s36
	global_load_lds_dwordx4 v130, s[30:31]
	s_mov_b32 m0, s53
	s_nop 0
	global_load_lds_dwordx4 v134, s[54:55]
	s_add_i32 m0, s53, 0x2000
	s_nop 0
	global_load_lds_dwordx4 v130, s[54:55]
	s_mov_b32 m0, s21
	s_nop 0
	global_load_lds_dwordx4 v136, s[34:35]
	s_mov_b32 m0, s23
	s_nop 0
	global_load_lds_dwordx4 v132, s[34:35]
	s_waitcnt vmcnt(8)
	s_barrier
	s_waitcnt lgkmcnt(0)
	v_mfma_f32_16x16x32_bf16 v[58:61], v[152:155], v[184:187], v[58:61]
	v_mfma_f32_16x16x32_bf16 v[54:57], v[160:163], v[184:187], v[54:57]
	v_mfma_f32_16x16x32_bf16 v[42:45], v[152:155], v[192:195], v[42:45]
	v_mfma_f32_16x16x32_bf16 v[38:41], v[160:163], v[192:195], v[38:41]
	v_mfma_f32_16x16x32_bf16 v[26:29], v[152:155], v[200:203], v[26:29]
	v_mfma_f32_16x16x32_bf16 v[22:25], v[160:163], v[200:203], v[22:25]
	v_mfma_f32_16x16x32_bf16 v[10:13], v[152:155], v[208:211], v[10:13]
	v_mfma_f32_16x16x32_bf16 v[6:9], v[160:163], v[208:211], v[6:9]
	v_mfma_f32_16x16x32_bf16 v[58:61], v[156:159], v[188:191], v[58:61]
	v_mfma_f32_16x16x32_bf16 v[54:57], v[164:167], v[188:191], v[54:57]
	v_mfma_f32_16x16x32_bf16 v[42:45], v[156:159], v[196:199], v[42:45]
	v_mfma_f32_16x16x32_bf16 v[38:41], v[164:167], v[196:199], v[38:41]
	v_mfma_f32_16x16x32_bf16 v[26:29], v[156:159], v[204:207], v[26:29]
	v_mfma_f32_16x16x32_bf16 v[22:25], v[164:167], v[204:207], v[22:25]
	v_mfma_f32_16x16x32_bf16 v[10:13], v[156:159], v[212:215], v[10:13]
	v_mfma_f32_16x16x32_bf16 v[6:9], v[164:167], v[212:215], v[6:9]
	v_mfma_f32_16x16x32_bf16 v[62:65], v[168:171], v[184:187], v[62:65]
	v_mfma_f32_16x16x32_bf16 v[50:53], v[176:179], v[184:187], v[50:53]
	v_mfma_f32_16x16x32_bf16 v[46:49], v[168:171], v[192:195], v[46:49]
	v_mfma_f32_16x16x32_bf16 v[34:37], v[176:179], v[192:195], v[34:37]
	v_mfma_f32_16x16x32_bf16 v[30:33], v[168:171], v[200:203], v[30:33]
	v_mfma_f32_16x16x32_bf16 v[18:21], v[176:179], v[200:203], v[18:21]
	v_mfma_f32_16x16x32_bf16 v[14:17], v[168:171], v[208:211], v[14:17]
	v_mfma_f32_16x16x32_bf16 v[2:5], v[176:179], v[208:211], v[2:5]
	v_mfma_f32_16x16x32_bf16 v[62:65], v[172:175], v[188:191], v[62:65]
	v_mfma_f32_16x16x32_bf16 v[50:53], v[180:183], v[188:191], v[50:53]
	v_mfma_f32_16x16x32_bf16 v[46:49], v[172:175], v[196:199], v[46:49]
	v_mfma_f32_16x16x32_bf16 v[34:37], v[180:183], v[196:199], v[34:37]
	v_mfma_f32_16x16x32_bf16 v[30:33], v[172:175], v[204:207], v[30:33]
	v_mfma_f32_16x16x32_bf16 v[18:21], v[180:183], v[204:207], v[18:21]
	v_mfma_f32_16x16x32_bf16 v[14:17], v[172:175], v[212:215], v[14:17]
	v_mfma_f32_16x16x32_bf16 v[2:5], v[180:183], v[212:215], v[2:5]
	s_barrier
; #define PG8_STAGE(bufoff, gbase, voff) do { _Pragma("unroll") for (int _i = 0; _i < 2; ++_i) \
;         __builtin_amdgcn_global_load_lds((const unsigned*)((const char*)(gbase) + (voff)[_i]), (LAS unsigned*)(lds + (bufoff) + ldsw + _i * 8192), 16, 0, 0); } while (0)
; #define PG8_LDA(dst, b, h) do { _Pragma("unroll") for (int m = 0; m < 4; ++m) _Pragma("unroll") for (int k = 0; k < 2; ++k) dst[m][k] = *(const LAS bf16x8*)(lds + PG8_SA(b, h) + aoff + m * 2048 + k * 1024); } while (0)
; #define PG8_LDB(dst, b, h) do { _Pragma("unroll") for (int n = 0; n < 2; ++n) _Pragma("unroll") for (int k = 0; k < 2; ++k) dst[n][k] = *(const LAS bf16x8*)(lds + PG8_SB(b, h) + boff + n * 2048 + k * 1024); } while (0)
; #define PG8_MMA(ai, bj, At, Bt) do { __builtin_amdgcn_s_setprio(1); _Pragma("unroll") for (int m = 0; m < 4; ++m) _Pragma("unroll") for (int n = 0; n < 2; ++n) _Pragma("unroll") for (int k = 0; k < 2; ++k) \
;         acc[ai][bj][m][n] = __builtin_amdgcn_mfma_f32_16x16x32_bf16(Bt[n][k], At[m][k], acc[ai][bj][m][n], 0, 0, 0); __builtin_amdgcn_s_setprio(0); } while (0)
; #define PG8_WAIT_V(n) asm volatile("s_waitcnt vmcnt(" #n ")" ::: "memory")
; #define PG8_WAIT_L(n) asm volatile("s_waitcnt lgkmcnt(" #n ")" ::: "memory")
; #define PG8_BAR __builtin_amdgcn_s_barrier()
; #define PG8_SCHED __builtin_amdgcn_sched_barrier(0)
; template <class Epi, class Sched, bool ABLK = false, bool ALIGN_EPI = true, bool SP2 = true, bool BBLK = true>
; __device__ __forceinline__ void gemm_phase(LAS unsigned char* lds, const Gemm g, const Sched& S, const Epi& E) {
;     ...
;             PG8_LDB(B0, 1, 0); PG8_LDB(B1, 1, 1); PG8_SCHED; PG8_LDA(At, 1, 0); PG8_STAGE(PG8_SA(0, 1), a2 + hstepA, voffA);
;             PG8_WAIT_V(8); PG8_WAIT_L(0); PG8_BAR; PG8_MMA(0, 0, At, B0); PG8_MMA(0, 1, At, B1); PG8_BAR; PG8_SCHED;
;             PG8_LDA(At, 1, 1); PG8_STAGE(PG8_SB(1, 0), b3, voffB); PG8_STAGE(PG8_SB(1, 1), b3 + hstepB, voffB); PG8_STAGE(PG8_SA(1, 0), a3, voffA);
;             PG8_WAIT_V(8); PG8_WAIT_L(0); PG8_BAR; PG8_MMA(1, 0, At, B0); PG8_MMA(1, 1, At, B1); PG8_BAR; PG8_SCHED;
;     ...
;         if constexpr (ALIGN_EPI) { if (wr == 0) PG8_BAR; }
	v_add_u32_e32 v151, s60, v146
	ds_read_b128 v[152:155], v151
	ds_read_b128 v[156:159], v151 offset:1024
	ds_read_b128 v[160:163], v151 offset:2048
	ds_read_b128 v[164:167], v151 offset:3072
	v_add_u32_e32 v151, s61, v146
	ds_read_b128 v[168:171], v151
	ds_read_b128 v[172:175], v151 offset:1024
	ds_read_b128 v[176:179], v151 offset:2048
	ds_read_b128 v[180:183], v151 offset:3072
	s_add_u32 s34, s34, 0x80000
	s_addc_u32 s35, s35, 0
	s_mov_b32 m0, s39
	ds_read_b128 v[184:187], v150 offset:32768
	ds_read_b128 v[188:191], v150 offset:33792
	ds_read_b128 v[192:195], v150 offset:34816
	ds_read_b128 v[196:199], v150 offset:35840
	ds_read_b128 v[200:203], v150 offset:36864
	ds_read_b128 v[204:207], v150 offset:37888
	ds_read_b128 v[208:211], v150 offset:38912
	ds_read_b128 v[212:215], v150 offset:39936
	global_load_lds_dwordx4 v136, s[34:35]
	s_mov_b32 m0, s40
	s_nop 0
	global_load_lds_dwordx4 v132, s[34:35]
	s_waitcnt vmcnt(8)
	s_barrier
	s_waitcnt lgkmcnt(0)
	v_mfma_f32_16x16x32_bf16 v[122:125], v[152:155], v[184:187], v[122:125]
	v_mfma_f32_16x16x32_bf16 v[118:121], v[160:163], v[184:187], v[118:121]
	v_mfma_f32_16x16x32_bf16 v[106:109], v[152:155], v[192:195], v[106:109]
	v_mfma_f32_16x16x32_bf16 v[102:105], v[160:163], v[192:195], v[102:105]
	v_mfma_f32_16x16x32_bf16 v[90:93], v[152:155], v[200:203], v[90:93]
	v_mfma_f32_16x16x32_bf16 v[86:89], v[160:163], v[200:203], v[86:89]
	v_mfma_f32_16x16x32_bf16 v[74:77], v[152:155], v[208:211], v[74:77]
	v_mfma_f32_16x16x32_bf16 v[70:73], v[160:163], v[208:211], v[70:73]
	v_mfma_f32_16x16x32_bf16 v[122:125], v[156:159], v[188:191], v[122:125]
	v_mfma_f32_16x16x32_bf16 v[118:121], v[164:167], v[188:191], v[118:121]
	v_mfma_f32_16x16x32_bf16 v[106:109], v[156:159], v[196:199], v[106:109]
	v_mfma_f32_16x16x32_bf16 v[102:105], v[164:167], v[196:199], v[102:105]
	v_mfma_f32_16x16x32_bf16 v[90:93], v[156:159], v[204:207], v[90:93]
	v_mfma_f32_16x16x32_bf16 v[86:89], v[164:167], v[204:207], v[86:89]
	v_mfma_f32_16x16x32_bf16 v[74:77], v[156:159], v[212:215], v[74:77]
	v_mfma_f32_16x16x32_bf16 v[70:73], v[164:167], v[212:215], v[70:73]
	v_mfma_f32_16x16x32_bf16 v[126:129], v[168:171], v[184:187], v[126:129]
	v_mfma_f32_16x16x32_bf16 v[114:117], v[176:179], v[184:187], v[114:117]
	v_mfma_f32_16x16x32_bf16 v[110:113], v[168:171], v[192:195], v[110:113]
	v_mfma_f32_16x16x32_bf16 v[98:101], v[176:179], v[192:195], v[98:101]
	v_mfma_f32_16x16x32_bf16 v[94:97], v[168:171], v[200:203], v[94:97]
	v_mfma_f32_16x16x32_bf16 v[82:85], v[176:179], v[200:203], v[82:85]
	v_mfma_f32_16x16x32_bf16 v[78:81], v[168:171], v[208:211], v[78:81]
	v_mfma_f32_16x16x32_bf16 v[66:69], v[176:179], v[208:211], v[66:69]
	v_mfma_f32_16x16x32_bf16 v[126:129], v[172:175], v[188:191], v[126:129]
	v_mfma_f32_16x16x32_bf16 v[114:117], v[180:183], v[188:191], v[114:117]
	v_mfma_f32_16x16x32_bf16 v[110:113], v[172:175], v[196:199], v[110:113]
	v_mfma_f32_16x16x32_bf16 v[98:101], v[180:183], v[196:199], v[98:101]
	v_mfma_f32_16x16x32_bf16 v[94:97], v[172:175], v[204:207], v[94:97]
	v_mfma_f32_16x16x32_bf16 v[82:85], v[180:183], v[204:207], v[82:85]
	v_mfma_f32_16x16x32_bf16 v[78:81], v[172:175], v[212:215], v[78:81]
	v_mfma_f32_16x16x32_bf16 v[66:69], v[180:183], v[212:215], v[66:69]
	s_barrier
	s_add_u32 s34, s30, 0x8000
	s_addc_u32 s35, s31, 0
	s_add_i32 s53, s60, s36
	s_mov_b32 m0, s53
	ds_read_b128 v[184:187], v150 offset:49152
	ds_read_b128 v[188:191], v150 offset:50176
	ds_read_b128 v[192:195], v150 offset:51200
	ds_read_b128 v[196:199], v150 offset:52224
	ds_read_b128 v[200:203], v150 offset:53248
	ds_read_b128 v[204:207], v150 offset:54272
	ds_read_b128 v[208:211], v150 offset:55296
	ds_read_b128 v[212:215], v150 offset:56320
	global_load_lds_dwordx4 v134, s[34:35]
	s_add_i32 m0, s53, 0x2000
	s_add_u32 s30, s30, 0xc000
	v_lshl_add_u64 v[216:217], s[34:35], 0, v[130:131]
	s_addc_u32 s31, s31, 0
	s_add_i32 s34, s61, s36
	global_load_lds_dwordx4 v[216:217], off
	s_mov_b32 m0, s34
	s_nop 0
	global_load_lds_dwordx4 v134, s[30:31]
	s_add_i32 m0, s34, 0x2000
	s_nop 0
	global_load_lds_dwordx4 v130, s[30:31]
	s_mov_b32 m0, s42
	s_nop 0
	global_load_lds_dwordx4 v136, s[28:29]
	s_mov_b32 m0, s43
	s_nop 0
	global_load_lds_dwordx4 v132, s[28:29]
	s_waitcnt vmcnt(8)
	s_barrier
	s_waitcnt lgkmcnt(0)
	v_mfma_f32_16x16x32_bf16 v[58:61], v[152:155], v[184:187], v[58:61]
	v_mfma_f32_16x16x32_bf16 v[54:57], v[160:163], v[184:187], v[54:57]
	v_mfma_f32_16x16x32_bf16 v[42:45], v[152:155], v[192:195], v[42:45]
	v_mfma_f32_16x16x32_bf16 v[38:41], v[160:163], v[192:195], v[38:41]
	v_mfma_f32_16x16x32_bf16 v[26:29], v[152:155], v[200:203], v[26:29]
	v_mfma_f32_16x16x32_bf16 v[22:25], v[160:163], v[200:203], v[22:25]
	v_mfma_f32_16x16x32_bf16 v[10:13], v[152:155], v[208:211], v[10:13]
	v_mfma_f32_16x16x32_bf16 v[6:9], v[160:163], v[208:211], v[6:9]
	v_mfma_f32_16x16x32_bf16 v[58:61], v[156:159], v[188:191], v[58:61]
	v_mfma_f32_16x16x32_bf16 v[54:57], v[164:167], v[188:191], v[54:57]
	v_mfma_f32_16x16x32_bf16 v[42:45], v[156:159], v[196:199], v[42:45]
	v_mfma_f32_16x16x32_bf16 v[38:41], v[164:167], v[196:199], v[38:41]
	v_mfma_f32_16x16x32_bf16 v[26:29], v[156:159], v[204:207], v[26:29]
	v_mfma_f32_16x16x32_bf16 v[22:25], v[164:167], v[204:207], v[22:25]
	v_mfma_f32_16x16x32_bf16 v[10:13], v[156:159], v[212:215], v[10:13]
	v_mfma_f32_16x16x32_bf16 v[6:9], v[164:167], v[212:215], v[6:9]
	v_mfma_f32_16x16x32_bf16 v[62:65], v[168:171], v[184:187], v[62:65]
	v_mfma_f32_16x16x32_bf16 v[50:53], v[176:179], v[184:187], v[50:53]
	v_mfma_f32_16x16x32_bf16 v[46:49], v[168:171], v[192:195], v[46:49]
	v_mfma_f32_16x16x32_bf16 v[34:37], v[176:179], v[192:195], v[34:37]
	v_mfma_f32_16x16x32_bf16 v[30:33], v[168:171], v[200:203], v[30:33]
	v_mfma_f32_16x16x32_bf16 v[18:21], v[176:179], v[200:203], v[18:21]
	v_mfma_f32_16x16x32_bf16 v[14:17], v[168:171], v[208:211], v[14:17]
	v_mfma_f32_16x16x32_bf16 v[2:5], v[176:179], v[208:211], v[2:5]
	v_mfma_f32_16x16x32_bf16 v[62:65], v[172:175], v[188:191], v[62:65]
	v_mfma_f32_16x16x32_bf16 v[50:53], v[180:183], v[188:191], v[50:53]
	v_mfma_f32_16x16x32_bf16 v[46:49], v[172:175], v[196:199], v[46:49]
	v_mfma_f32_16x16x32_bf16 v[34:37], v[180:183], v[196:199], v[34:37]
	v_mfma_f32_16x16x32_bf16 v[30:33], v[172:175], v[204:207], v[30:33]
	v_mfma_f32_16x16x32_bf16 v[18:21], v[180:183], v[204:207], v[18:21]
	v_mfma_f32_16x16x32_bf16 v[14:17], v[172:175], v[212:215], v[14:17]
	v_mfma_f32_16x16x32_bf16 v[2:5], v[180:183], v[212:215], v[2:5]
	s_barrier
	s_add_i32 s52, s52, 2
	s_add_u32 s26, s26, 0x100
	s_addc_u32 s27, s27, 0
	s_add_u32 s50, s50, 0x10000
	s_addc_u32 s51, s51, 0
	s_cmp_gt_u32 s52, 29
	s_cbranch_scc0 .LBB0_2138
	s_and_b64 vcc, exec, s[6:7]
	s_cbranch_vccz .LBB0_2141
	s_barrier

; #define PG8_STAGE(bufoff, gbase, voff) do { _Pragma("unroll") for (int _i = 0; _i < 2; ++_i) \
;         __builtin_amdgcn_global_load_lds((const unsigned*)((const char*)(gbase) + (voff)[_i]), (LAS unsigned*)(lds + (bufoff) + ldsw + _i * 8192), 16, 0, 0); } while (0)
; #define PG8_LDA(dst, b, h) do { _Pragma("unroll") for (int m = 0; m < 4; ++m) _Pragma("unroll") for (int k = 0; k < 2; ++k) dst[m][k] = *(const LAS bf16x8*)(lds + PG8_SA(b, h) + aoff + m * 2048 + k * 1024); } while (0)
; #define PG8_LDB(dst, b, h) do { _Pragma("unroll") for (int n = 0; n < 2; ++n) _Pragma("unroll") for (int k = 0; k < 2; ++k) dst[n][k] = *(const LAS bf16x8*)(lds + PG8_SB(b, h) + boff + n * 2048 + k * 1024); } while (0)
; #define PG8_WAIT_V(n) asm volatile("s_waitcnt vmcnt(" #n ")" ::: "memory")
; #define PG8_WAIT_L(n) asm volatile("s_waitcnt lgkmcnt(" #n ")" ::: "memory")
; template <class Epi, class Sched, bool ABLK = false, bool ALIGN_EPI = true, bool SP2 = true, bool BBLK = true>
; __device__ __forceinline__ void gemm_phase(LAS unsigned char* lds, const Gemm g, const Sched& S, const Epi& E) {
;     ...
;         const bool has_next = S.next(ui + 1, nxt);
;         const int nt = cur.nt;
;         const char* nuA = has_next ? a_unit(nxt) : uA; const int ntbA = has_next ? nxt.k0 / BK : tbA; const char* nB = has_next ? (const char*)g.Bt + (size_t)nxt.pn * tstepB + b_k0(nxt.k0) : cB;
;         for (int t = 0; t < nt; t += 2) {
;             const bool last = (t == nt - 2);
;             const char* a1 = a_tile(uA, tbA + t + 1);
;             const char* a2 = last ? a_tile(nuA, ntbA) : a_tile(uA, tbA + t + 2); const char* b2 = last ? nB : cB + (size_t)(t + 2) * kstepB;
;             const char* a3 = last ? a_tile(nuA, ntbA + 1) : a_tile(uA, tbA + t + 3); const char* b3 = b2 + kstepB;
;             if (last && has_next) S.a_ready(nxt);
;             if constexpr (SP2) {
;             PG8_LDB(B0, 0, 0); PG8_LDB(B1, 0, 1); PG8_SCHED; PG8_LDA(At, 0, 0); PG8_STAGE(PG8_SA(1, 1), a1 + hstepA, voffA);
;             PG8_WAIT_V(8); PG8_WAIT_L(0); PG8_BAR; PG8_MMA(0, 0, At, B0); PG8_MMA(0, 1, At, B1); PG8_BAR; PG8_SCHED;
;             PG8_LDA(At, 0, 1); PG8_STAGE(PG8_SB(0, 0), b2, voffB); PG8_STAGE(PG8_SB(0, 1), b2 + hstepB, voffB); PG8_STAGE(PG8_SA(0, 0), a2, voffA);
;             PG8_WAIT_V(8); PG8_WAIT_L(0); PG8_BAR; PG8_MMA(1, 0, At, B0); PG8_MMA(1, 1, At, B1); PG8_BAR; PG8_SCHED;
.LBB0_2262:
	s_ashr_i32 s13, s12, 31
	s_lshl_b64 s[4:5], s[12:13], 20
	s_add_u32 s16, s41, s4
	s_addc_u32 s17, s42, s5
	s_and_b64 s[4:5], s[18:19], exec
	s_cselect_b32 s4, s17, s27
	s_cselect_b32 s5, s16, s26
	s_ashr_i32 s15, s14, 31
	s_lshl_b64 s[20:21], s[14:15], 20
	s_add_u32 s20, s38, s20
	s_addc_u32 s21, s39, s21
	s_and_b64 s[30:31], s[18:19], exec
	s_cselect_b32 s13, s21, s29
	s_cselect_b32 s15, s20, s28
	s_add_u32 s23, s5, 0x80
	s_addc_u32 s54, s4, 0
	s_add_u32 s55, s28, 0x10000
	v_mov_b32_e32 v2, 0
	s_addc_u32 s56, s29, 0
	v_lshl_add_u64 v[164:165], s[26:27], 0, v[160:161]
	v_lshl_add_u64 v[166:167], s[26:27], 0, v[162:163]
	s_mov_b32 s57, -2
	s_mov_b64 s[28:29], 0
	ds_read_b128 v[172:175], v168
	ds_read_b128 v[176:179], v168 offset:1024
	ds_read_b128 v[180:183], v168 offset:2048
	ds_read_b128 v[184:187], v168 offset:3072
	ds_read_b128 v[188:191], v169
	ds_read_b128 v[192:195], v169 offset:1024
	ds_read_b128 v[196:199], v169 offset:2048
	ds_read_b128 v[200:203], v169 offset:3072
	s_add_u32 s30, s26, s28
	s_addc_u32 s31, s27, s29
	s_add_u32 s36, s30, 0x100
	s_addc_u32 s37, s31, 0
	s_add_u32 s30, s30, 0x180
	s_addc_u32 s31, s31, 0
	s_cmpk_eq_i32 s28, 0xf00
	s_cselect_b32 s31, s54, s31
	s_cselect_b32 s30, s23, s30
	s_cselect_b32 s35, s13, s56
	s_cselect_b32 s34, s15, s55
	s_cselect_b32 s37, s4, s37
	s_cselect_b32 s36, s5, s36
	s_mov_b32 m0, s50
	v_lshl_add_u64 v[236:237], v[164:165], 0, s[28:29]
	ds_read_b128 v[204:207], v170
	ds_read_b128 v[208:211], v170 offset:1024
	ds_read_b128 v[212:215], v170 offset:2048
	ds_read_b128 v[216:219], v170 offset:3072
	ds_read_b128 v[220:223], v170 offset:4096
	ds_read_b128 v[224:227], v170 offset:5120
	ds_read_b128 v[228:231], v170 offset:6144
	ds_read_b128 v[232:235], v170 offset:7168
	global_load_lds_dwordx4 v[236:237], off
	v_lshl_add_u64 v[236:237], v[166:167], 0, s[28:29]
	s_mov_b32 m0, s51
	s_nop 0
	global_load_lds_dwordx4 v[236:237], off
	s_waitcnt vmcnt(8)
	s_barrier
	s_waitcnt lgkmcnt(0)
	v_mfma_f32_16x16x32_bf16 v[126:129], v[172:175], v[204:207], 0
	v_mfma_f32_16x16x32_bf16 v[122:125], v[180:183], v[204:207], 0
	v_mfma_f32_16x16x32_bf16 v[110:113], v[172:175], v[212:215], 0
	v_mfma_f32_16x16x32_bf16 v[106:109], v[180:183], v[212:215], 0
	v_mfma_f32_16x16x32_bf16 v[94:97], v[172:175], v[220:223], 0
	v_mfma_f32_16x16x32_bf16 v[90:93], v[180:183], v[220:223], 0
	v_mfma_f32_16x16x32_bf16 v[78:81], v[172:175], v[228:231], 0
	v_mfma_f32_16x16x32_bf16 v[74:77], v[180:183], v[228:231], 0
	v_mfma_f32_16x16x32_bf16 v[126:129], v[176:179], v[208:211], v[126:129]
	v_mfma_f32_16x16x32_bf16 v[122:125], v[184:187], v[208:211], v[122:125]
	v_mfma_f32_16x16x32_bf16 v[110:113], v[176:179], v[216:219], v[110:113]
	v_mfma_f32_16x16x32_bf16 v[106:109], v[184:187], v[216:219], v[106:109]
	v_mfma_f32_16x16x32_bf16 v[94:97], v[176:179], v[224:227], v[94:97]
	v_mfma_f32_16x16x32_bf16 v[90:93], v[184:187], v[224:227], v[90:93]
	v_mfma_f32_16x16x32_bf16 v[78:81], v[176:179], v[232:235], v[78:81]
	v_mfma_f32_16x16x32_bf16 v[74:77], v[184:187], v[232:235], v[74:77]
	v_mfma_f32_16x16x32_bf16 v[118:121], v[188:191], v[204:207], 0
	v_mfma_f32_16x16x32_bf16 v[114:117], v[196:199], v[204:207], 0
	v_mfma_f32_16x16x32_bf16 v[102:105], v[188:191], v[212:215], 0
	v_mfma_f32_16x16x32_bf16 v[98:101], v[196:199], v[212:215], 0
	v_mfma_f32_16x16x32_bf16 v[86:89], v[188:191], v[220:223], 0
	v_mfma_f32_16x16x32_bf16 v[82:85], v[196:199], v[220:223], 0
	v_mfma_f32_16x16x32_bf16 v[70:73], v[188:191], v[228:231], 0
	v_mfma_f32_16x16x32_bf16 v[66:69], v[196:199], v[228:231], 0
	v_mfma_f32_16x16x32_bf16 v[118:121], v[192:195], v[208:211], v[118:121]
	v_mfma_f32_16x16x32_bf16 v[114:117], v[200:203], v[208:211], v[114:117]
	v_mfma_f32_16x16x32_bf16 v[102:105], v[192:195], v[216:219], v[102:105]
	v_mfma_f32_16x16x32_bf16 v[98:101], v[200:203], v[216:219], v[98:101]
	v_mfma_f32_16x16x32_bf16 v[86:89], v[192:195], v[224:227], v[86:89]
	v_mfma_f32_16x16x32_bf16 v[82:85], v[200:203], v[224:227], v[82:85]
	v_mfma_f32_16x16x32_bf16 v[70:73], v[192:195], v[232:235], v[70:73]
	v_mfma_f32_16x16x32_bf16 v[66:69], v[200:203], v[232:235], v[66:69]
	s_barrier
	s_mov_b32 m0, s52
	s_add_u32 s58, s34, 0x4000
	ds_read_b128 v[204:207], v170 offset:16384
	ds_read_b128 v[208:211], v170 offset:17408
	ds_read_b128 v[212:215], v170 offset:18432
	ds_read_b128 v[216:219], v170 offset:19456
	ds_read_b128 v[220:223], v170 offset:20480
	ds_read_b128 v[224:227], v170 offset:21504
	ds_read_b128 v[228:231], v170 offset:22528
	ds_read_b128 v[232:235], v170 offset:23552
	global_load_lds_dwordx4 v134, s[34:35]
	s_mov_b32 m0, s53
	s_addc_u32 s59, s35, 0
	s_add_i32 s62, s73, s40
	global_load_lds_dwordx4 v130, s[34:35]
	s_mov_b32 m0, s62
	s_nop 0
	global_load_lds_dwordx4 v134, s[58:59]
	s_add_i32 m0, s62, 0x2000
	s_nop 0
	global_load_lds_dwordx4 v130, s[58:59]
	s_mov_b32 m0, s25
	s_nop 0
	global_load_lds_dwordx4 v136, s[36:37]
	s_mov_b32 m0, s43
	s_nop 0
	global_load_lds_dwordx4 v132, s[36:37]
	s_waitcnt vmcnt(8)
	s_barrier
; #define PG8_STAGE(bufoff, gbase, voff) do { _Pragma("unroll") for (int _i = 0; _i < 2; ++_i) \
;         __builtin_amdgcn_global_load_lds((const unsigned*)((const char*)(gbase) + (voff)[_i]), (LAS unsigned*)(lds + (bufoff) + ldsw + _i * 8192), 16, 0, 0); } while (0)
; #define PG8_LDA(dst, b, h) do { _Pragma("unroll") for (int m = 0; m < 4; ++m) _Pragma("unroll") for (int k = 0; k < 2; ++k) dst[m][k] = *(const LAS bf16x8*)(lds + PG8_SA(b, h) + aoff + m * 2048 + k * 1024); } while (0)
; #define PG8_LDB(dst, b, h) do { _Pragma("unroll") for (int n = 0; n < 2; ++n) _Pragma("unroll") for (int k = 0; k < 2; ++k) dst[n][k] = *(const LAS bf16x8*)(lds + PG8_SB(b, h) + boff + n * 2048 + k * 1024); } while (0)
; #define PG8_MMA(ai, bj, At, Bt) do { __builtin_amdgcn_s_setprio(1); _Pragma("unroll") for (int m = 0; m < 4; ++m) _Pragma("unroll") for (int n = 0; n < 2; ++n) _Pragma("unroll") for (int k = 0; k < 2; ++k) \
;         acc[ai][bj][m][n] = __builtin_amdgcn_mfma_f32_16x16x32_bf16(Bt[n][k], At[m][k], acc[ai][bj][m][n], 0, 0, 0); __builtin_amdgcn_s_setprio(0); } while (0)
; #define PG8_WAIT_V(n) asm volatile("s_waitcnt vmcnt(" #n ")" ::: "memory")
; #define PG8_WAIT_L(n) asm volatile("s_waitcnt lgkmcnt(" #n ")" ::: "memory")
; #define PG8_BAR __builtin_amdgcn_s_barrier()
; #define PG8_SCHED __builtin_amdgcn_sched_barrier(0)
; template <class Epi, class Sched, bool ABLK = false, bool ALIGN_EPI = true, bool SP2 = true, bool BBLK = true>
; __device__ __forceinline__ void gemm_phase(LAS unsigned char* lds, const Gemm g, const Sched& S, const Epi& E) {
;     ...
;             PG8_WAIT_V(8); PG8_WAIT_L(0); PG8_BAR; PG8_MMA(1, 0, At, B0); PG8_MMA(1, 1, At, B1); PG8_BAR; PG8_SCHED;
;             PG8_LDB(B0, 1, 0); PG8_LDB(B1, 1, 1); PG8_SCHED; PG8_LDA(At, 1, 0); PG8_STAGE(PG8_SA(0, 1), a2 + hstepA, voffA);
;             PG8_WAIT_V(8); PG8_WAIT_L(0); PG8_BAR; PG8_MMA(0, 0, At, B0); PG8_MMA(0, 1, At, B1); PG8_BAR; PG8_SCHED;
	s_waitcnt lgkmcnt(0)
	v_mfma_f32_16x16x32_bf16 v[62:65], v[172:175], v[204:207], 0
	v_mfma_f32_16x16x32_bf16 v[58:61], v[180:183], v[204:207], 0
	v_mfma_f32_16x16x32_bf16 v[46:49], v[172:175], v[212:215], 0
	v_mfma_f32_16x16x32_bf16 v[42:45], v[180:183], v[212:215], 0
	v_mfma_f32_16x16x32_bf16 v[30:33], v[172:175], v[220:223], 0
	v_mfma_f32_16x16x32_bf16 v[26:29], v[180:183], v[220:223], 0
	v_mfma_f32_16x16x32_bf16 v[14:17], v[172:175], v[228:231], 0
	v_mfma_f32_16x16x32_bf16 v[10:13], v[180:183], v[228:231], 0
	v_mfma_f32_16x16x32_bf16 v[62:65], v[176:179], v[208:211], v[62:65]
	v_mfma_f32_16x16x32_bf16 v[58:61], v[184:187], v[208:211], v[58:61]
	v_mfma_f32_16x16x32_bf16 v[46:49], v[176:179], v[216:219], v[46:49]
	v_mfma_f32_16x16x32_bf16 v[42:45], v[184:187], v[216:219], v[42:45]
	v_mfma_f32_16x16x32_bf16 v[30:33], v[176:179], v[224:227], v[30:33]
	v_mfma_f32_16x16x32_bf16 v[26:29], v[184:187], v[224:227], v[26:29]
	v_mfma_f32_16x16x32_bf16 v[14:17], v[176:179], v[232:235], v[14:17]
	v_mfma_f32_16x16x32_bf16 v[10:13], v[184:187], v[232:235], v[10:13]
	v_mfma_f32_16x16x32_bf16 v[54:57], v[188:191], v[204:207], 0
	v_mfma_f32_16x16x32_bf16 v[50:53], v[196:199], v[204:207], 0
	v_mfma_f32_16x16x32_bf16 v[38:41], v[188:191], v[212:215], 0
	v_mfma_f32_16x16x32_bf16 v[34:37], v[196:199], v[212:215], 0
	v_mfma_f32_16x16x32_bf16 v[22:25], v[188:191], v[220:223], 0
	v_mfma_f32_16x16x32_bf16 v[18:21], v[196:199], v[220:223], 0
	v_mfma_f32_16x16x32_bf16 v[6:9], v[188:191], v[228:231], 0
	v_mfma_f32_16x16x32_bf16 v[2:5], v[196:199], v[228:231], 0
	v_mfma_f32_16x16x32_bf16 v[54:57], v[192:195], v[208:211], v[54:57]
	v_mfma_f32_16x16x32_bf16 v[50:53], v[200:203], v[208:211], v[50:53]
	v_mfma_f32_16x16x32_bf16 v[38:41], v[192:195], v[216:219], v[38:41]
	v_mfma_f32_16x16x32_bf16 v[34:37], v[200:203], v[216:219], v[34:37]
	v_mfma_f32_16x16x32_bf16 v[22:25], v[192:195], v[224:227], v[22:25]
	v_mfma_f32_16x16x32_bf16 v[18:21], v[200:203], v[224:227], v[18:21]
	v_mfma_f32_16x16x32_bf16 v[6:9], v[192:195], v[232:235], v[6:9]
	v_mfma_f32_16x16x32_bf16 v[2:5], v[200:203], v[232:235], v[2:5]
	s_barrier
	v_add_u32_e32 v171, s60, v1
	ds_read_b128 v[172:175], v171
	ds_read_b128 v[176:179], v171 offset:1024
	ds_read_b128 v[180:183], v171 offset:2048
	ds_read_b128 v[184:187], v171 offset:3072
	v_add_u32_e32 v171, s61, v1
	ds_read_b128 v[188:191], v171
	ds_read_b128 v[192:195], v171 offset:1024
	ds_read_b128 v[196:199], v171 offset:2048
	ds_read_b128 v[200:203], v171 offset:3072
	s_add_u32 s36, s36, 0x80000
	s_addc_u32 s37, s37, 0
	s_mov_b32 m0, s44
	ds_read_b128 v[204:207], v170 offset:32768
	ds_read_b128 v[208:211], v170 offset:33792
	ds_read_b128 v[212:215], v170 offset:34816
	ds_read_b128 v[216:219], v170 offset:35840
	ds_read_b128 v[220:223], v170 offset:36864
	ds_read_b128 v[224:227], v170 offset:37888
	ds_read_b128 v[228:231], v170 offset:38912
	ds_read_b128 v[232:235], v170 offset:39936
	global_load_lds_dwordx4 v136, s[36:37]
	s_mov_b32 m0, s45
	s_nop 0
	global_load_lds_dwordx4 v132, s[36:37]
	s_waitcnt vmcnt(8)
	s_barrier
	s_waitcnt lgkmcnt(0)
	v_mfma_f32_16x16x32_bf16 v[126:129], v[172:175], v[204:207], v[126:129]
	v_mfma_f32_16x16x32_bf16 v[122:125], v[180:183], v[204:207], v[122:125]
	v_mfma_f32_16x16x32_bf16 v[110:113], v[172:175], v[212:215], v[110:113]
	v_mfma_f32_16x16x32_bf16 v[106:109], v[180:183], v[212:215], v[106:109]
	v_mfma_f32_16x16x32_bf16 v[94:97], v[172:175], v[220:223], v[94:97]
	v_mfma_f32_16x16x32_bf16 v[90:93], v[180:183], v[220:223], v[90:93]
	v_mfma_f32_16x16x32_bf16 v[78:81], v[172:175], v[228:231], v[78:81]
	v_mfma_f32_16x16x32_bf16 v[74:77], v[180:183], v[228:231], v[74:77]
	v_mfma_f32_16x16x32_bf16 v[126:129], v[176:179], v[208:211], v[126:129]
	v_mfma_f32_16x16x32_bf16 v[122:125], v[184:187], v[208:211], v[122:125]
	v_mfma_f32_16x16x32_bf16 v[110:113], v[176:179], v[216:219], v[110:113]
	v_mfma_f32_16x16x32_bf16 v[106:109], v[184:187], v[216:219], v[106:109]
	v_mfma_f32_16x16x32_bf16 v[94:97], v[176:179], v[224:227], v[94:97]
	v_mfma_f32_16x16x32_bf16 v[90:93], v[184:187], v[224:227], v[90:93]
	v_mfma_f32_16x16x32_bf16 v[78:81], v[176:179], v[232:235], v[78:81]
	v_mfma_f32_16x16x32_bf16 v[74:77], v[184:187], v[232:235], v[74:77]
	v_mfma_f32_16x16x32_bf16 v[118:121], v[188:191], v[204:207], v[118:121]
	v_mfma_f32_16x16x32_bf16 v[114:117], v[196:199], v[204:207], v[114:117]
	v_mfma_f32_16x16x32_bf16 v[102:105], v[188:191], v[212:215], v[102:105]
	v_mfma_f32_16x16x32_bf16 v[98:101], v[196:199], v[212:215], v[98:101]
	v_mfma_f32_16x16x32_bf16 v[86:89], v[188:191], v[220:223], v[86:89]
	v_mfma_f32_16x16x32_bf16 v[82:85], v[196:199], v[220:223], v[82:85]
	v_mfma_f32_16x16x32_bf16 v[70:73], v[188:191], v[228:231], v[70:73]
	v_mfma_f32_16x16x32_bf16 v[66:69], v[196:199], v[228:231], v[66:69]
	v_mfma_f32_16x16x32_bf16 v[118:121], v[192:195], v[208:211], v[118:121]
	v_mfma_f32_16x16x32_bf16 v[114:117], v[200:203], v[208:211], v[114:117]
	v_mfma_f32_16x16x32_bf16 v[102:105], v[192:195], v[216:219], v[102:105]
	v_mfma_f32_16x16x32_bf16 v[98:101], v[200:203], v[216:219], v[98:101]
	v_mfma_f32_16x16x32_bf16 v[86:89], v[192:195], v[224:227], v[86:89]
	v_mfma_f32_16x16x32_bf16 v[82:85], v[200:203], v[224:227], v[82:85]
	v_mfma_f32_16x16x32_bf16 v[70:73], v[192:195], v[232:235], v[70:73]
	v_mfma_f32_16x16x32_bf16 v[66:69], v[200:203], v[232:235], v[66:69]
	s_barrier
; #define PG8_STAGE(bufoff, gbase, voff) do { _Pragma("unroll") for (int _i = 0; _i < 2; ++_i) \
;         __builtin_amdgcn_global_load_lds((const unsigned*)((const char*)(gbase) + (voff)[_i]), (LAS unsigned*)(lds + (bufoff) + ldsw + _i * 8192), 16, 0, 0); } while (0)
; #define PG8_LDA(dst, b, h) do { _Pragma("unroll") for (int m = 0; m < 4; ++m) _Pragma("unroll") for (int k = 0; k < 2; ++k) dst[m][k] = *(const LAS bf16x8*)(lds + PG8_SA(b, h) + aoff + m * 2048 + k * 1024); } while (0)
; #define PG8_LDB(dst, b, h) do { _Pragma("unroll") for (int n = 0; n < 2; ++n) _Pragma("unroll") for (int k = 0; k < 2; ++k) dst[n][k] = *(const LAS bf16x8*)(lds + PG8_SB(b, h) + boff + n * 2048 + k * 1024); } while (0)
; #define PG8_WAIT_V(n) asm volatile("s_waitcnt vmcnt(" #n ")" ::: "memory")
; #define PG8_WAIT_L(n) asm volatile("s_waitcnt lgkmcnt(" #n ")" ::: "memory")
; #define PG8_BAR __builtin_amdgcn_s_barrier()
; #define PG8_SCHED __builtin_amdgcn_sched_barrier(0)
; template <class Epi, class Sched, bool ABLK = false, bool ALIGN_EPI = true, bool SP2 = true, bool BBLK = true>
; __device__ __forceinline__ void gemm_phase(LAS unsigned char* lds, const Gemm g, const Sched& S, const Epi& E) {
;     ...
;         for (int t = 0; t < nt; t += 2) {
;             const bool last = (t == nt - 2);
;             const char* a1 = a_tile(uA, tbA + t + 1);
;             const char* a2 = last ? a_tile(nuA, ntbA) : a_tile(uA, tbA + t + 2); const char* b2 = last ? nB : cB + (size_t)(t + 2) * kstepB;
;             const char* a3 = last ? a_tile(nuA, ntbA + 1) : a_tile(uA, tbA + t + 3); const char* b3 = b2 + kstepB;
;             if (last && has_next) S.a_ready(nxt);
;             if constexpr (SP2) {
;             PG8_LDB(B0, 0, 0); PG8_LDB(B1, 0, 1); PG8_SCHED; PG8_LDA(At, 0, 0); PG8_STAGE(PG8_SA(1, 1), a1 + hstepA, voffA);
;             PG8_WAIT_V(8); PG8_WAIT_L(0); PG8_BAR; PG8_MMA(0, 0, At, B0); PG8_MMA(0, 1, At, B1); PG8_BAR; PG8_SCHED;
;     ...
;             PG8_WAIT_V(8); PG8_WAIT_L(0); PG8_BAR; PG8_MMA(0, 0, At, B0); PG8_MMA(0, 1, At, B1); PG8_BAR; PG8_SCHED;
;             PG8_LDA(At, 1, 1); PG8_STAGE(PG8_SB(1, 0), b3, voffB); PG8_STAGE(PG8_SB(1, 1), b3 + hstepB, voffB); PG8_STAGE(PG8_SA(1, 0), a3, voffA);
;             PG8_WAIT_V(8); PG8_WAIT_L(0); PG8_BAR; PG8_MMA(1, 0, At, B0); PG8_MMA(1, 1, At, B1); PG8_BAR; PG8_SCHED;
	s_add_u32 s36, s34, 0x8000
	s_addc_u32 s37, s35, 0
	s_add_i32 s58, s60, s40
	s_mov_b32 m0, s58
	ds_read_b128 v[204:207], v170 offset:49152
	ds_read_b128 v[208:211], v170 offset:50176
	ds_read_b128 v[212:215], v170 offset:51200
	ds_read_b128 v[216:219], v170 offset:52224
	ds_read_b128 v[220:223], v170 offset:53248
	ds_read_b128 v[224:227], v170 offset:54272
	ds_read_b128 v[228:231], v170 offset:55296
	ds_read_b128 v[232:235], v170 offset:56320
	global_load_lds_dwordx4 v134, s[36:37]
	s_add_i32 m0, s58, 0x2000
	s_add_u32 s34, s34, 0xc000
	v_lshl_add_u64 v[236:237], s[36:37], 0, v[130:131]
	s_addc_u32 s35, s35, 0
	s_add_i32 s36, s61, s40
	global_load_lds_dwordx4 v[236:237], off
	s_mov_b32 m0, s36
	s_nop 0
	global_load_lds_dwordx4 v134, s[34:35]
	s_add_i32 m0, s36, 0x2000
	s_nop 0
	global_load_lds_dwordx4 v130, s[34:35]
	s_mov_b32 m0, s48
	s_nop 0
	global_load_lds_dwordx4 v136, s[30:31]
	s_mov_b32 m0, s49
	s_nop 0
	global_load_lds_dwordx4 v132, s[30:31]
	s_waitcnt vmcnt(8)
	s_barrier
	s_waitcnt lgkmcnt(0)
	v_mfma_f32_16x16x32_bf16 v[62:65], v[172:175], v[204:207], v[62:65]
	v_mfma_f32_16x16x32_bf16 v[58:61], v[180:183], v[204:207], v[58:61]
	v_mfma_f32_16x16x32_bf16 v[46:49], v[172:175], v[212:215], v[46:49]
	v_mfma_f32_16x16x32_bf16 v[42:45], v[180:183], v[212:215], v[42:45]
	v_mfma_f32_16x16x32_bf16 v[30:33], v[172:175], v[220:223], v[30:33]
	v_mfma_f32_16x16x32_bf16 v[26:29], v[180:183], v[220:223], v[26:29]
	v_mfma_f32_16x16x32_bf16 v[14:17], v[172:175], v[228:231], v[14:17]
	v_mfma_f32_16x16x32_bf16 v[10:13], v[180:183], v[228:231], v[10:13]
	v_mfma_f32_16x16x32_bf16 v[62:65], v[176:179], v[208:211], v[62:65]
	v_mfma_f32_16x16x32_bf16 v[58:61], v[184:187], v[208:211], v[58:61]
	v_mfma_f32_16x16x32_bf16 v[46:49], v[176:179], v[216:219], v[46:49]
	v_mfma_f32_16x16x32_bf16 v[42:45], v[184:187], v[216:219], v[42:45]
	v_mfma_f32_16x16x32_bf16 v[30:33], v[176:179], v[224:227], v[30:33]
	v_mfma_f32_16x16x32_bf16 v[26:29], v[184:187], v[224:227], v[26:29]
	v_mfma_f32_16x16x32_bf16 v[14:17], v[176:179], v[232:235], v[14:17]
	v_mfma_f32_16x16x32_bf16 v[10:13], v[184:187], v[232:235], v[10:13]
	v_mfma_f32_16x16x32_bf16 v[54:57], v[188:191], v[204:207], v[54:57]
	v_mfma_f32_16x16x32_bf16 v[50:53], v[196:199], v[204:207], v[50:53]
	v_mfma_f32_16x16x32_bf16 v[38:41], v[188:191], v[212:215], v[38:41]
	v_mfma_f32_16x16x32_bf16 v[34:37], v[196:199], v[212:215], v[34:37]
	v_mfma_f32_16x16x32_bf16 v[22:25], v[188:191], v[220:223], v[22:25]
	v_mfma_f32_16x16x32_bf16 v[18:21], v[196:199], v[220:223], v[18:21]
	v_mfma_f32_16x16x32_bf16 v[6:9], v[188:191], v[228:231], v[6:9]
	v_mfma_f32_16x16x32_bf16 v[2:5], v[196:199], v[228:231], v[2:5]
	v_mfma_f32_16x16x32_bf16 v[54:57], v[192:195], v[208:211], v[54:57]
	v_mfma_f32_16x16x32_bf16 v[50:53], v[200:203], v[208:211], v[50:53]
	v_mfma_f32_16x16x32_bf16 v[38:41], v[192:195], v[216:219], v[38:41]
	v_mfma_f32_16x16x32_bf16 v[34:37], v[200:203], v[216:219], v[34:37]
	v_mfma_f32_16x16x32_bf16 v[22:25], v[192:195], v[224:227], v[22:25]
	v_mfma_f32_16x16x32_bf16 v[18:21], v[200:203], v[224:227], v[18:21]
	v_mfma_f32_16x16x32_bf16 v[6:9], v[192:195], v[232:235], v[6:9]
	v_mfma_f32_16x16x32_bf16 v[2:5], v[200:203], v[232:235], v[2:5]
	s_barrier
	s_add_i32 s57, s57, 2
	s_add_u32 s28, s28, 0x100
	s_addc_u32 s29, s29, 0
	s_add_u32 s55, s55, 0x10000
	s_addc_u32 s56, s56, 0
	s_cmp_gt_u32 s57, 29
.LBB0_2263:
	ds_read_b128 v[172:175], v168
	ds_read_b128 v[176:179], v168 offset:1024
	ds_read_b128 v[180:183], v168 offset:2048
	ds_read_b128 v[184:187], v168 offset:3072
	ds_read_b128 v[188:191], v169
	ds_read_b128 v[192:195], v169 offset:1024
	ds_read_b128 v[196:199], v169 offset:2048
	ds_read_b128 v[200:203], v169 offset:3072
	s_add_u32 s30, s26, s28
	s_addc_u32 s31, s27, s29
	s_add_u32 s36, s30, 0x100
	s_addc_u32 s37, s31, 0
	s_add_u32 s30, s30, 0x180
	s_addc_u32 s31, s31, 0
	s_cmpk_eq_i32 s28, 0xf00
	s_cselect_b32 s31, s54, s31
	s_cselect_b32 s30, s23, s30
	s_cselect_b32 s35, s13, s56
	s_cselect_b32 s34, s15, s55
	s_cselect_b32 s37, s4, s37
	s_cselect_b32 s36, s5, s36
	s_mov_b32 m0, s50
	v_lshl_add_u64 v[236:237], v[164:165], 0, s[28:29]
	ds_read_b128 v[204:207], v170
	ds_read_b128 v[208:211], v170 offset:1024
	ds_read_b128 v[212:215], v170 offset:2048
	ds_read_b128 v[216:219], v170 offset:3072
	ds_read_b128 v[220:223], v170 offset:4096
	ds_read_b128 v[224:227], v170 offset:5120
	ds_read_b128 v[228:231], v170 offset:6144
	ds_read_b128 v[232:235], v170 offset:7168
	global_load_lds_dwordx4 v[236:237], off
	v_lshl_add_u64 v[236:237], v[166:167], 0, s[28:29]
	s_mov_b32 m0, s51
	s_nop 0
	global_load_lds_dwordx4 v[236:237], off
	s_waitcnt vmcnt(8)
	s_barrier
; #define PG8_STAGE(bufoff, gbase, voff) do { _Pragma("unroll") for (int _i = 0; _i < 2; ++_i) \
;         __builtin_amdgcn_global_load_lds((const unsigned*)((const char*)(gbase) + (voff)[_i]), (LAS unsigned*)(lds + (bufoff) + ldsw + _i * 8192), 16, 0, 0); } while (0)
; #define PG8_LDA(dst, b, h) do { _Pragma("unroll") for (int m = 0; m < 4; ++m) _Pragma("unroll") for (int k = 0; k < 2; ++k) dst[m][k] = *(const LAS bf16x8*)(lds + PG8_SA(b, h) + aoff + m * 2048 + k * 1024); } while (0)
; #define PG8_MMA(ai, bj, At, Bt) do { __builtin_amdgcn_s_setprio(1); _Pragma("unroll") for (int m = 0; m < 4; ++m) _Pragma("unroll") for (int n = 0; n < 2; ++n) _Pragma("unroll") for (int k = 0; k < 2; ++k) \
;         acc[ai][bj][m][n] = __builtin_amdgcn_mfma_f32_16x16x32_bf16(Bt[n][k], At[m][k], acc[ai][bj][m][n], 0, 0, 0); __builtin_amdgcn_s_setprio(0); } while (0)
; #define PG8_WAIT_V(n) asm volatile("s_waitcnt vmcnt(" #n ")" ::: "memory")
; #define PG8_WAIT_L(n) asm volatile("s_waitcnt lgkmcnt(" #n ")" ::: "memory")
; #define PG8_BAR __builtin_amdgcn_s_barrier()
; #define PG8_SCHED __builtin_amdgcn_sched_barrier(0)
; template <class Epi, class Sched, bool ABLK = false, bool ALIGN_EPI = true, bool SP2 = true, bool BBLK = true>
; __device__ __forceinline__ void gemm_phase(LAS unsigned char* lds, const Gemm g, const Sched& S, const Epi& E) {
;     ...
;             PG8_WAIT_V(8); PG8_WAIT_L(0); PG8_BAR; PG8_MMA(0, 0, At, B0); PG8_MMA(0, 1, At, B1); PG8_BAR; PG8_SCHED;
;             PG8_LDA(At, 0, 1); PG8_STAGE(PG8_SB(0, 0), b2, voffB); PG8_STAGE(PG8_SB(0, 1), b2 + hstepB, voffB); PG8_STAGE(PG8_SA(0, 0), a2, voffA);
;             PG8_WAIT_V(8); PG8_WAIT_L(0); PG8_BAR; PG8_MMA(1, 0, At, B0); PG8_MMA(1, 1, At, B1); PG8_BAR; PG8_SCHED;
	s_waitcnt lgkmcnt(0)
	v_mfma_f32_16x16x32_bf16 v[126:129], v[172:175], v[204:207], v[126:129]
	v_mfma_f32_16x16x32_bf16 v[122:125], v[180:183], v[204:207], v[122:125]
	v_mfma_f32_16x16x32_bf16 v[110:113], v[172:175], v[212:215], v[110:113]
	v_mfma_f32_16x16x32_bf16 v[106:109], v[180:183], v[212:215], v[106:109]
	v_mfma_f32_16x16x32_bf16 v[94:97], v[172:175], v[220:223], v[94:97]
	v_mfma_f32_16x16x32_bf16 v[90:93], v[180:183], v[220:223], v[90:93]
	v_mfma_f32_16x16x32_bf16 v[78:81], v[172:175], v[228:231], v[78:81]
	v_mfma_f32_16x16x32_bf16 v[74:77], v[180:183], v[228:231], v[74:77]
	v_mfma_f32_16x16x32_bf16 v[126:129], v[176:179], v[208:211], v[126:129]
	v_mfma_f32_16x16x32_bf16 v[122:125], v[184:187], v[208:211], v[122:125]
	v_mfma_f32_16x16x32_bf16 v[110:113], v[176:179], v[216:219], v[110:113]
	v_mfma_f32_16x16x32_bf16 v[106:109], v[184:187], v[216:219], v[106:109]
	v_mfma_f32_16x16x32_bf16 v[94:97], v[176:179], v[224:227], v[94:97]
	v_mfma_f32_16x16x32_bf16 v[90:93], v[184:187], v[224:227], v[90:93]
	v_mfma_f32_16x16x32_bf16 v[78:81], v[176:179], v[232:235], v[78:81]
	v_mfma_f32_16x16x32_bf16 v[74:77], v[184:187], v[232:235], v[74:77]
	v_mfma_f32_16x16x32_bf16 v[118:121], v[188:191], v[204:207], v[118:121]
	v_mfma_f32_16x16x32_bf16 v[114:117], v[196:199], v[204:207], v[114:117]
	v_mfma_f32_16x16x32_bf16 v[102:105], v[188:191], v[212:215], v[102:105]
	v_mfma_f32_16x16x32_bf16 v[98:101], v[196:199], v[212:215], v[98:101]
	v_mfma_f32_16x16x32_bf16 v[86:89], v[188:191], v[220:223], v[86:89]
	v_mfma_f32_16x16x32_bf16 v[82:85], v[196:199], v[220:223], v[82:85]
	v_mfma_f32_16x16x32_bf16 v[70:73], v[188:191], v[228:231], v[70:73]
	v_mfma_f32_16x16x32_bf16 v[66:69], v[196:199], v[228:231], v[66:69]
	v_mfma_f32_16x16x32_bf16 v[118:121], v[192:195], v[208:211], v[118:121]
	v_mfma_f32_16x16x32_bf16 v[114:117], v[200:203], v[208:211], v[114:117]
	v_mfma_f32_16x16x32_bf16 v[102:105], v[192:195], v[216:219], v[102:105]
	v_mfma_f32_16x16x32_bf16 v[98:101], v[200:203], v[216:219], v[98:101]
	v_mfma_f32_16x16x32_bf16 v[86:89], v[192:195], v[224:227], v[86:89]
	v_mfma_f32_16x16x32_bf16 v[82:85], v[200:203], v[224:227], v[82:85]
	v_mfma_f32_16x16x32_bf16 v[70:73], v[192:195], v[232:235], v[70:73]
	v_mfma_f32_16x16x32_bf16 v[66:69], v[200:203], v[232:235], v[66:69]
	s_barrier
	s_mov_b32 m0, s52
	s_add_u32 s58, s34, 0x4000
	ds_read_b128 v[204:207], v170 offset:16384
	ds_read_b128 v[208:211], v170 offset:17408
	ds_read_b128 v[212:215], v170 offset:18432
	ds_read_b128 v[216:219], v170 offset:19456
	ds_read_b128 v[220:223], v170 offset:20480
	ds_read_b128 v[224:227], v170 offset:21504
	ds_read_b128 v[228:231], v170 offset:22528
	ds_read_b128 v[232:235], v170 offset:23552
	global_load_lds_dwordx4 v134, s[34:35]
	s_mov_b32 m0, s53
	s_addc_u32 s59, s35, 0
	s_add_i32 s62, s73, s40
	global_load_lds_dwordx4 v130, s[34:35]
	s_mov_b32 m0, s62
	s_nop 0
	global_load_lds_dwordx4 v134, s[58:59]
	s_add_i32 m0, s62, 0x2000
	s_nop 0
	global_load_lds_dwordx4 v130, s[58:59]
	s_mov_b32 m0, s25
	s_nop 0
	global_load_lds_dwordx4 v136, s[36:37]
	s_mov_b32 m0, s43
	s_nop 0
	global_load_lds_dwordx4 v132, s[36:37]
	s_waitcnt vmcnt(8)
	s_barrier
	s_waitcnt lgkmcnt(0)
	v_mfma_f32_16x16x32_bf16 v[62:65], v[172:175], v[204:207], v[62:65]
	v_mfma_f32_16x16x32_bf16 v[58:61], v[180:183], v[204:207], v[58:61]
	v_mfma_f32_16x16x32_bf16 v[46:49], v[172:175], v[212:215], v[46:49]
	v_mfma_f32_16x16x32_bf16 v[42:45], v[180:183], v[212:215], v[42:45]
	v_mfma_f32_16x16x32_bf16 v[30:33], v[172:175], v[220:223], v[30:33]
	v_mfma_f32_16x16x32_bf16 v[26:29], v[180:183], v[220:223], v[26:29]
	v_mfma_f32_16x16x32_bf16 v[14:17], v[172:175], v[228:231], v[14:17]
	v_mfma_f32_16x16x32_bf16 v[10:13], v[180:183], v[228:231], v[10:13]
	v_mfma_f32_16x16x32_bf16 v[62:65], v[176:179], v[208:211], v[62:65]
	v_mfma_f32_16x16x32_bf16 v[58:61], v[184:187], v[208:211], v[58:61]
	v_mfma_f32_16x16x32_bf16 v[46:49], v[176:179], v[216:219], v[46:49]
	v_mfma_f32_16x16x32_bf16 v[42:45], v[184:187], v[216:219], v[42:45]
	v_mfma_f32_16x16x32_bf16 v[30:33], v[176:179], v[224:227], v[30:33]
	v_mfma_f32_16x16x32_bf16 v[26:29], v[184:187], v[224:227], v[26:29]
	v_mfma_f32_16x16x32_bf16 v[14:17], v[176:179], v[232:235], v[14:17]
	v_mfma_f32_16x16x32_bf16 v[10:13], v[184:187], v[232:235], v[10:13]
	v_mfma_f32_16x16x32_bf16 v[54:57], v[188:191], v[204:207], v[54:57]
	v_mfma_f32_16x16x32_bf16 v[50:53], v[196:199], v[204:207], v[50:53]
	v_mfma_f32_16x16x32_bf16 v[38:41], v[188:191], v[212:215], v[38:41]
	v_mfma_f32_16x16x32_bf16 v[34:37], v[196:199], v[212:215], v[34:37]
	v_mfma_f32_16x16x32_bf16 v[22:25], v[188:191], v[220:223], v[22:25]
	v_mfma_f32_16x16x32_bf16 v[18:21], v[196:199], v[220:223], v[18:21]
	v_mfma_f32_16x16x32_bf16 v[6:9], v[188:191], v[228:231], v[6:9]
	v_mfma_f32_16x16x32_bf16 v[2:5], v[196:199], v[228:231], v[2:5]
	v_mfma_f32_16x16x32_bf16 v[54:57], v[192:195], v[208:211], v[54:57]
	v_mfma_f32_16x16x32_bf16 v[50:53], v[200:203], v[208:211], v[50:53]
	v_mfma_f32_16x16x32_bf16 v[38:41], v[192:195], v[216:219], v[38:41]
	v_mfma_f32_16x16x32_bf16 v[34:37], v[200:203], v[216:219], v[34:37]
	v_mfma_f32_16x16x32_bf16 v[22:25], v[192:195], v[224:227], v[22:25]
	v_mfma_f32_16x16x32_bf16 v[18:21], v[200:203], v[224:227], v[18:21]
	v_mfma_f32_16x16x32_bf16 v[6:9], v[192:195], v[232:235], v[6:9]
	v_mfma_f32_16x16x32_bf16 v[2:5], v[200:203], v[232:235], v[2:5]
	s_barrier
; #define PG8_STAGE(bufoff, gbase, voff) do { _Pragma("unroll") for (int _i = 0; _i < 2; ++_i) \
;         __builtin_amdgcn_global_load_lds((const unsigned*)((const char*)(gbase) + (voff)[_i]), (LAS unsigned*)(lds + (bufoff) + ldsw + _i * 8192), 16, 0, 0); } while (0)
; #define PG8_LDA(dst, b, h) do { _Pragma("unroll") for (int m = 0; m < 4; ++m) _Pragma("unroll") for (int k = 0; k < 2; ++k) dst[m][k] = *(const LAS bf16x8*)(lds + PG8_SA(b, h) + aoff + m * 2048 + k * 1024); } while (0)
; #define PG8_LDB(dst, b, h) do { _Pragma("unroll") for (int n = 0; n < 2; ++n) _Pragma("unroll") for (int k = 0; k < 2; ++k) dst[n][k] = *(const LAS bf16x8*)(lds + PG8_SB(b, h) + boff + n * 2048 + k * 1024); } while (0)
; #define PG8_MMA(ai, bj, At, Bt) do { __builtin_amdgcn_s_setprio(1); _Pragma("unroll") for (int m = 0; m < 4; ++m) _Pragma("unroll") for (int n = 0; n < 2; ++n) _Pragma("unroll") for (int k = 0; k < 2; ++k) \
;         acc[ai][bj][m][n] = __builtin_amdgcn_mfma_f32_16x16x32_bf16(Bt[n][k], At[m][k], acc[ai][bj][m][n], 0, 0, 0); __builtin_amdgcn_s_setprio(0); } while (0)
; #define PG8_WAIT_V(n) asm volatile("s_waitcnt vmcnt(" #n ")" ::: "memory")
; #define PG8_WAIT_L(n) asm volatile("s_waitcnt lgkmcnt(" #n ")" ::: "memory")
; #define PG8_BAR __builtin_amdgcn_s_barrier()
; #define PG8_SCHED __builtin_amdgcn_sched_barrier(0)
; template <class Epi, class Sched, bool ABLK = false, bool ALIGN_EPI = true, bool SP2 = true, bool BBLK = true>
; __device__ __forceinline__ void gemm_phase(LAS unsigned char* lds, const Gemm g, const Sched& S, const Epi& E) {
;     ...
;             PG8_LDB(B0, 1, 0); PG8_LDB(B1, 1, 1); PG8_SCHED; PG8_LDA(At, 1, 0); PG8_STAGE(PG8_SA(0, 1), a2 + hstepA, voffA);
;             PG8_WAIT_V(8); PG8_WAIT_L(0); PG8_BAR; PG8_MMA(0, 0, At, B0); PG8_MMA(0, 1, At, B1); PG8_BAR; PG8_SCHED;
;             PG8_LDA(At, 1, 1); PG8_STAGE(PG8_SB(1, 0), b3, voffB); PG8_STAGE(PG8_SB(1, 1), b3 + hstepB, voffB); PG8_STAGE(PG8_SA(1, 0), a3, voffA);
;             PG8_WAIT_V(8); PG8_WAIT_L(0); PG8_BAR; PG8_MMA(1, 0, At, B0); PG8_MMA(1, 1, At, B1); PG8_BAR; PG8_SCHED;
;     ...
;         if constexpr (ALIGN_EPI) { if (wr == 0) PG8_BAR; }
	v_add_u32_e32 v171, s60, v1
	ds_read_b128 v[172:175], v171
	ds_read_b128 v[176:179], v171 offset:1024
	ds_read_b128 v[180:183], v171 offset:2048
	ds_read_b128 v[184:187], v171 offset:3072
	v_add_u32_e32 v171, s61, v1
	ds_read_b128 v[188:191], v171
	ds_read_b128 v[192:195], v171 offset:1024
	ds_read_b128 v[196:199], v171 offset:2048
	ds_read_b128 v[200:203], v171 offset:3072
	s_add_u32 s36, s36, 0x80000
	s_addc_u32 s37, s37, 0
	s_mov_b32 m0, s44
	ds_read_b128 v[204:207], v170 offset:32768
	ds_read_b128 v[208:211], v170 offset:33792
	ds_read_b128 v[212:215], v170 offset:34816
	ds_read_b128 v[216:219], v170 offset:35840
	ds_read_b128 v[220:223], v170 offset:36864
	ds_read_b128 v[224:227], v170 offset:37888
	ds_read_b128 v[228:231], v170 offset:38912
	ds_read_b128 v[232:235], v170 offset:39936
	global_load_lds_dwordx4 v136, s[36:37]
	s_mov_b32 m0, s45
	s_nop 0
	global_load_lds_dwordx4 v132, s[36:37]
	s_waitcnt vmcnt(8)
	s_barrier
	s_waitcnt lgkmcnt(0)
	v_mfma_f32_16x16x32_bf16 v[126:129], v[172:175], v[204:207], v[126:129]
	v_mfma_f32_16x16x32_bf16 v[122:125], v[180:183], v[204:207], v[122:125]
	v_mfma_f32_16x16x32_bf16 v[110:113], v[172:175], v[212:215], v[110:113]
	v_mfma_f32_16x16x32_bf16 v[106:109], v[180:183], v[212:215], v[106:109]
	v_mfma_f32_16x16x32_bf16 v[94:97], v[172:175], v[220:223], v[94:97]
	v_mfma_f32_16x16x32_bf16 v[90:93], v[180:183], v[220:223], v[90:93]
	v_mfma_f32_16x16x32_bf16 v[78:81], v[172:175], v[228:231], v[78:81]
	v_mfma_f32_16x16x32_bf16 v[74:77], v[180:183], v[228:231], v[74:77]
	v_mfma_f32_16x16x32_bf16 v[126:129], v[176:179], v[208:211], v[126:129]
	v_mfma_f32_16x16x32_bf16 v[122:125], v[184:187], v[208:211], v[122:125]
	v_mfma_f32_16x16x32_bf16 v[110:113], v[176:179], v[216:219], v[110:113]
	v_mfma_f32_16x16x32_bf16 v[106:109], v[184:187], v[216:219], v[106:109]
	v_mfma_f32_16x16x32_bf16 v[94:97], v[176:179], v[224:227], v[94:97]
	v_mfma_f32_16x16x32_bf16 v[90:93], v[184:187], v[224:227], v[90:93]
	v_mfma_f32_16x16x32_bf16 v[78:81], v[176:179], v[232:235], v[78:81]
	v_mfma_f32_16x16x32_bf16 v[74:77], v[184:187], v[232:235], v[74:77]
	v_mfma_f32_16x16x32_bf16 v[118:121], v[188:191], v[204:207], v[118:121]
	v_mfma_f32_16x16x32_bf16 v[114:117], v[196:199], v[204:207], v[114:117]
	v_mfma_f32_16x16x32_bf16 v[102:105], v[188:191], v[212:215], v[102:105]
	v_mfma_f32_16x16x32_bf16 v[98:101], v[196:199], v[212:215], v[98:101]
	v_mfma_f32_16x16x32_bf16 v[86:89], v[188:191], v[220:223], v[86:89]
	v_mfma_f32_16x16x32_bf16 v[82:85], v[196:199], v[220:223], v[82:85]
	v_mfma_f32_16x16x32_bf16 v[70:73], v[188:191], v[228:231], v[70:73]
	v_mfma_f32_16x16x32_bf16 v[66:69], v[196:199], v[228:231], v[66:69]
	v_mfma_f32_16x16x32_bf16 v[118:121], v[192:195], v[208:211], v[118:121]
	v_mfma_f32_16x16x32_bf16 v[114:117], v[200:203], v[208:211], v[114:117]
	v_mfma_f32_16x16x32_bf16 v[102:105], v[192:195], v[216:219], v[102:105]
	v_mfma_f32_16x16x32_bf16 v[98:101], v[200:203], v[216:219], v[98:101]
	v_mfma_f32_16x16x32_bf16 v[86:89], v[192:195], v[224:227], v[86:89]
	v_mfma_f32_16x16x32_bf16 v[82:85], v[200:203], v[224:227], v[82:85]
	v_mfma_f32_16x16x32_bf16 v[70:73], v[192:195], v[232:235], v[70:73]
	v_mfma_f32_16x16x32_bf16 v[66:69], v[200:203], v[232:235], v[66:69]
	s_barrier
	s_add_u32 s36, s34, 0x8000
	s_addc_u32 s37, s35, 0
	s_add_i32 s58, s60, s40
	s_mov_b32 m0, s58
	ds_read_b128 v[204:207], v170 offset:49152
	ds_read_b128 v[208:211], v170 offset:50176
	ds_read_b128 v[212:215], v170 offset:51200
	ds_read_b128 v[216:219], v170 offset:52224
	ds_read_b128 v[220:223], v170 offset:53248
	ds_read_b128 v[224:227], v170 offset:54272
	ds_read_b128 v[228:231], v170 offset:55296
	ds_read_b128 v[232:235], v170 offset:56320
	global_load_lds_dwordx4 v134, s[36:37]
	s_add_i32 m0, s58, 0x2000
	s_add_u32 s34, s34, 0xc000
	v_lshl_add_u64 v[236:237], s[36:37], 0, v[130:131]
	s_addc_u32 s35, s35, 0
	s_add_i32 s36, s61, s40
	global_load_lds_dwordx4 v[236:237], off
	s_mov_b32 m0, s36
	s_nop 0
	global_load_lds_dwordx4 v134, s[34:35]
	s_add_i32 m0, s36, 0x2000
	s_nop 0
	global_load_lds_dwordx4 v130, s[34:35]
	s_mov_b32 m0, s48
	s_nop 0
	global_load_lds_dwordx4 v136, s[30:31]
	s_mov_b32 m0, s49
	s_nop 0
	global_load_lds_dwordx4 v132, s[30:31]
	s_waitcnt vmcnt(8)
	s_barrier
	s_waitcnt lgkmcnt(0)
	v_mfma_f32_16x16x32_bf16 v[62:65], v[172:175], v[204:207], v[62:65]
	v_mfma_f32_16x16x32_bf16 v[58:61], v[180:183], v[204:207], v[58:61]
	v_mfma_f32_16x16x32_bf16 v[46:49], v[172:175], v[212:215], v[46:49]
	v_mfma_f32_16x16x32_bf16 v[42:45], v[180:183], v[212:215], v[42:45]
	v_mfma_f32_16x16x32_bf16 v[30:33], v[172:175], v[220:223], v[30:33]
	v_mfma_f32_16x16x32_bf16 v[26:29], v[180:183], v[220:223], v[26:29]
	v_mfma_f32_16x16x32_bf16 v[14:17], v[172:175], v[228:231], v[14:17]
	v_mfma_f32_16x16x32_bf16 v[10:13], v[180:183], v[228:231], v[10:13]
	v_mfma_f32_16x16x32_bf16 v[62:65], v[176:179], v[208:211], v[62:65]
	v_mfma_f32_16x16x32_bf16 v[58:61], v[184:187], v[208:211], v[58:61]
	v_mfma_f32_16x16x32_bf16 v[46:49], v[176:179], v[216:219], v[46:49]
	v_mfma_f32_16x16x32_bf16 v[42:45], v[184:187], v[216:219], v[42:45]
	v_mfma_f32_16x16x32_bf16 v[30:33], v[176:179], v[224:227], v[30:33]
	v_mfma_f32_16x16x32_bf16 v[26:29], v[184:187], v[224:227], v[26:29]
	v_mfma_f32_16x16x32_bf16 v[14:17], v[176:179], v[232:235], v[14:17]
	v_mfma_f32_16x16x32_bf16 v[10:13], v[184:187], v[232:235], v[10:13]
	v_mfma_f32_16x16x32_bf16 v[54:57], v[188:191], v[204:207], v[54:57]
	v_mfma_f32_16x16x32_bf16 v[50:53], v[196:199], v[204:207], v[50:53]
	v_mfma_f32_16x16x32_bf16 v[38:41], v[188:191], v[212:215], v[38:41]
	v_mfma_f32_16x16x32_bf16 v[34:37], v[196:199], v[212:215], v[34:37]
	v_mfma_f32_16x16x32_bf16 v[22:25], v[188:191], v[220:223], v[22:25]
	v_mfma_f32_16x16x32_bf16 v[18:21], v[196:199], v[220:223], v[18:21]
	v_mfma_f32_16x16x32_bf16 v[6:9], v[188:191], v[228:231], v[6:9]
	v_mfma_f32_16x16x32_bf16 v[2:5], v[196:199], v[228:231], v[2:5]
	v_mfma_f32_16x16x32_bf16 v[54:57], v[192:195], v[208:211], v[54:57]
	v_mfma_f32_16x16x32_bf16 v[50:53], v[200:203], v[208:211], v[50:53]
	v_mfma_f32_16x16x32_bf16 v[38:41], v[192:195], v[216:219], v[38:41]
	v_mfma_f32_16x16x32_bf16 v[34:37], v[200:203], v[216:219], v[34:37]
	v_mfma_f32_16x16x32_bf16 v[22:25], v[192:195], v[224:227], v[22:25]
	v_mfma_f32_16x16x32_bf16 v[18:21], v[200:203], v[224:227], v[18:21]
	v_mfma_f32_16x16x32_bf16 v[6:9], v[192:195], v[232:235], v[6:9]
	v_mfma_f32_16x16x32_bf16 v[2:5], v[200:203], v[232:235], v[2:5]
	s_barrier
	s_add_i32 s57, s57, 2
	s_add_u32 s28, s28, 0x100
	s_addc_u32 s29, s29, 0
	s_add_u32 s55, s55, 0x10000
	s_addc_u32 s56, s56, 0
	s_cmp_gt_u32 s57, 29
	s_cbranch_scc0 .LBB0_2263
	s_and_b64 vcc, exec, s[10:11]
	s_cbranch_vccz .LBB0_2266
	s_barrier

; #define PG8_STAGE(bufoff, gbase, voff) do { _Pragma("unroll") for (int _i = 0; _i < 2; ++_i) \
;         __builtin_amdgcn_global_load_lds((const unsigned*)((const char*)(gbase) + (voff)[_i]), (LAS unsigned*)(lds + (bufoff) + ldsw + _i * 8192), 16, 0, 0); } while (0)
; #define PG8_LDA(dst, b, h) do { _Pragma("unroll") for (int m = 0; m < 4; ++m) _Pragma("unroll") for (int k = 0; k < 2; ++k) dst[m][k] = *(const LAS bf16x8*)(lds + PG8_SA(b, h) + aoff + m * 2048 + k * 1024); } while (0)
; #define PG8_LDB(dst, b, h) do { _Pragma("unroll") for (int n = 0; n < 2; ++n) _Pragma("unroll") for (int k = 0; k < 2; ++k) dst[n][k] = *(const LAS bf16x8*)(lds + PG8_SB(b, h) + boff + n * 2048 + k * 1024); } while (0)
; #define PG8_WAIT_V(n) asm volatile("s_waitcnt vmcnt(" #n ")" ::: "memory")
; #define PG8_WAIT_L(n) asm volatile("s_waitcnt lgkmcnt(" #n ")" ::: "memory")
; template <class Epi, class Sched, bool ABLK = false, bool ALIGN_EPI = true, bool SP2 = true, bool BBLK = true>
; __device__ __forceinline__ void gemm_phase(LAS unsigned char* lds, const Gemm g, const Sched& S, const Epi& E) {
;     ...
;         const bool has_next = S.next(ui + 1, nxt);
;         const int nt = cur.nt;
;         const char* nuA = has_next ? a_unit(nxt) : uA; const int ntbA = has_next ? nxt.k0 / BK : tbA; const char* nB = has_next ? (const char*)g.Bt + (size_t)nxt.pn * tstepB + b_k0(nxt.k0) : cB;
;         for (int t = 0; t < nt; t += 2) {
;             const bool last = (t == nt - 2);
;             const char* a1 = a_tile(uA, tbA + t + 1);
;             const char* a2 = last ? a_tile(nuA, ntbA) : a_tile(uA, tbA + t + 2); const char* b2 = last ? nB : cB + (size_t)(t + 2) * kstepB;
;             const char* a3 = last ? a_tile(nuA, ntbA + 1) : a_tile(uA, tbA + t + 3); const char* b3 = b2 + kstepB;
;             if (last && has_next) S.a_ready(nxt);
;             if constexpr (SP2) {
;             PG8_LDB(B0, 0, 0); PG8_LDB(B1, 0, 1); PG8_SCHED; PG8_LDA(At, 0, 0); PG8_STAGE(PG8_SA(1, 1), a1 + hstepA, voffA);
;             PG8_WAIT_V(8); PG8_WAIT_L(0); PG8_BAR; PG8_MMA(0, 0, At, B0); PG8_MMA(0, 1, At, B1); PG8_BAR; PG8_SCHED;
;             PG8_LDA(At, 0, 1); PG8_STAGE(PG8_SB(0, 0), b2, voffB); PG8_STAGE(PG8_SB(0, 1), b2 + hstepB, voffB); PG8_STAGE(PG8_SA(0, 0), a2, voffA);
;             PG8_WAIT_V(8); PG8_WAIT_L(0); PG8_BAR; PG8_MMA(1, 0, At, B0); PG8_MMA(1, 1, At, B1); PG8_BAR; PG8_SCHED;
.LBB0_2327:
	s_ashr_i32 s81, s80, 31
	s_andn2_b64 vcc, exec, s[4:5]
	s_lshl_b64 s[30:31], s[80:81], 22
	s_add_u32 s30, s1, s30
	s_addc_u32 s31, s33, s31
	s_and_b64 s[34:35], s[4:5], exec
	s_cselect_b32 s43, s31, s41
	s_cselect_b32 s57, s30, s40
	s_ashr_i32 s34, s0, 31
	s_lshr_b32 s34, s34, 26
	s_add_i32 s34, s0, s34
	s_ashr_i32 s34, s34, 6
	s_and_b64 s[36:37], s[4:5], exec
	s_cselect_b32 s44, s34, s42
	s_ashr_i32 s79, s78, 31
	s_lshl_b64 s[36:37], s[78:79], 22
	s_add_u32 s45, s46, s36
	s_addc_u32 s58, s47, s37
	s_ashr_i32 s35, s34, 31
	s_lshl_b64 s[36:37], s[34:35], 15
	s_add_u32 s36, s45, s36
	s_addc_u32 s37, s58, s37
	v_cndmask_b32_e64 v2, 0, 1, s[4:5]
	s_and_b64 s[4:5], s[4:5], exec
	s_cselect_b32 s4, s37, s39
	s_cselect_b32 s5, s36, s38
	s_ashr_i32 s45, s44, 31
	s_lshl_b64 s[44:45], s[44:45], 15
	s_add_u32 s35, s57, s44
	s_addc_u32 s57, s43, s45
	s_add_u32 s58, s35, 0x8000
	s_addc_u32 s59, s57, 0
	s_add_u32 s62, s38, 0x10000
	s_addc_u32 s63, s39, 0
	s_ashr_i32 s43, s42, 31
	v_cmp_ne_u32_e64 s[6:7], 1, v2
	s_lshl_b64 s[38:39], s[42:43], 15
	v_lshl_add_u64 v[2:3], s[40:41], 0, v[138:139]
	s_add_u32 s64, s40, s38
	v_lshl_add_u64 v[142:143], v[2:3], 0, s[38:39]
	v_lshl_add_u64 v[2:3], s[40:41], 0, v[140:141]
	s_addc_u32 s65, s41, s39
	v_lshl_add_u64 v[144:145], v[2:3], 0, s[38:39]
	s_lshl_b32 s38, s56, 15
	s_add_i32 s38, s38, 0xfff00000
	v_mov_b32_e32 v2, 0
	s_add_u32 s66, s38, 0xf0000
	s_mov_b32 s67, 0
	s_mov_b64 s[38:39], 0
	ds_read_b128 v[152:155], v148
	ds_read_b128 v[156:159], v148 offset:1024
	ds_read_b128 v[160:163], v148 offset:2048
	ds_read_b128 v[164:167], v148 offset:3072
	ds_read_b128 v[168:171], v149
	ds_read_b128 v[172:175], v149 offset:1024
	ds_read_b128 v[176:179], v149 offset:2048
	ds_read_b128 v[180:183], v149 offset:3072
	s_add_u32 s40, s64, s38
	s_addc_u32 s41, s65, s39
	s_add_u32 s44, s40, 0x10000
	s_addc_u32 s45, s41, 0
	s_add_i32 s67, s67, 2
	s_add_u32 s42, s62, s38
	s_addc_u32 s43, s63, s39
	s_add_u32 s40, s40, 0x18000
	s_addc_u32 s41, s41, 0
	s_cmp_eq_u32 s66, s38
	s_cselect_b32 s41, s59, s41
	s_cselect_b32 s40, s58, s40
	s_cselect_b32 s43, s4, s43
	s_cselect_b32 s42, s5, s42
	s_cselect_b32 s45, s57, s45
	s_cselect_b32 s44, s35, s44
	v_lshl_add_u64 v[216:217], v[142:143], 0, s[38:39]
	s_add_i32 m0, s49, 0xc000
	ds_read_b128 v[184:187], v150
	ds_read_b128 v[188:191], v150 offset:1024
	ds_read_b128 v[192:195], v150 offset:2048
	ds_read_b128 v[196:199], v150 offset:3072
	ds_read_b128 v[200:203], v150 offset:4096
	ds_read_b128 v[204:207], v150 offset:5120
	ds_read_b128 v[208:211], v150 offset:6144
	ds_read_b128 v[212:215], v150 offset:7168
	global_load_lds_dwordx4 v[216:217], off
	v_lshl_add_u64 v[216:217], v[144:145], 0, s[38:39]
	s_add_i32 m0, s49, 0xe000
	s_nop 0
	global_load_lds_dwordx4 v[216:217], off
	s_waitcnt vmcnt(8)
	s_barrier
	s_waitcnt lgkmcnt(0)
	v_mfma_f32_16x16x32_bf16 v[126:129], v[152:155], v[184:187], 0
	v_mfma_f32_16x16x32_bf16 v[122:125], v[160:163], v[184:187], 0
	v_mfma_f32_16x16x32_bf16 v[110:113], v[152:155], v[192:195], 0
	v_mfma_f32_16x16x32_bf16 v[106:109], v[160:163], v[192:195], 0
	v_mfma_f32_16x16x32_bf16 v[94:97], v[152:155], v[200:203], 0
	v_mfma_f32_16x16x32_bf16 v[90:93], v[160:163], v[200:203], 0
	v_mfma_f32_16x16x32_bf16 v[78:81], v[152:155], v[208:211], 0
	v_mfma_f32_16x16x32_bf16 v[74:77], v[160:163], v[208:211], 0
	v_mfma_f32_16x16x32_bf16 v[126:129], v[156:159], v[188:191], v[126:129]
	v_mfma_f32_16x16x32_bf16 v[122:125], v[164:167], v[188:191], v[122:125]
	v_mfma_f32_16x16x32_bf16 v[110:113], v[156:159], v[196:199], v[110:113]
	v_mfma_f32_16x16x32_bf16 v[106:109], v[164:167], v[196:199], v[106:109]
	v_mfma_f32_16x16x32_bf16 v[94:97], v[156:159], v[204:207], v[94:97]
	v_mfma_f32_16x16x32_bf16 v[90:93], v[164:167], v[204:207], v[90:93]
	v_mfma_f32_16x16x32_bf16 v[78:81], v[156:159], v[212:215], v[78:81]
	v_mfma_f32_16x16x32_bf16 v[74:77], v[164:167], v[212:215], v[74:77]
	v_mfma_f32_16x16x32_bf16 v[118:121], v[168:171], v[184:187], 0
	v_mfma_f32_16x16x32_bf16 v[114:117], v[176:179], v[184:187], 0
	v_mfma_f32_16x16x32_bf16 v[102:105], v[168:171], v[192:195], 0
	v_mfma_f32_16x16x32_bf16 v[98:101], v[176:179], v[192:195], 0
	v_mfma_f32_16x16x32_bf16 v[86:89], v[168:171], v[200:203], 0
	v_mfma_f32_16x16x32_bf16 v[82:85], v[176:179], v[200:203], 0
	v_mfma_f32_16x16x32_bf16 v[70:73], v[168:171], v[208:211], 0
	v_mfma_f32_16x16x32_bf16 v[66:69], v[176:179], v[208:211], 0
	v_mfma_f32_16x16x32_bf16 v[118:121], v[172:175], v[188:191], v[118:121]
	v_mfma_f32_16x16x32_bf16 v[114:117], v[180:183], v[188:191], v[114:117]
	v_mfma_f32_16x16x32_bf16 v[102:105], v[172:175], v[196:199], v[102:105]
	v_mfma_f32_16x16x32_bf16 v[98:101], v[180:183], v[196:199], v[98:101]
	v_mfma_f32_16x16x32_bf16 v[86:89], v[172:175], v[204:207], v[86:89]
	v_mfma_f32_16x16x32_bf16 v[82:85], v[180:183], v[204:207], v[82:85]
	v_mfma_f32_16x16x32_bf16 v[70:73], v[172:175], v[212:215], v[70:73]
	v_mfma_f32_16x16x32_bf16 v[66:69], v[180:183], v[212:215], v[66:69]
	s_barrier
	s_add_i32 s70, s72, s48
	s_mov_b32 m0, s70
	ds_read_b128 v[184:187], v150 offset:16384
	ds_read_b128 v[188:191], v150 offset:17408
	ds_read_b128 v[192:195], v150 offset:18432
	ds_read_b128 v[196:199], v150 offset:19456
	ds_read_b128 v[200:203], v150 offset:20480
	ds_read_b128 v[204:207], v150 offset:21504
	ds_read_b128 v[208:211], v150 offset:22528
	ds_read_b128 v[212:215], v150 offset:23552
	global_load_lds_dwordx4 v130, s[42:43]
	s_add_i32 m0, s70, 0x2000
	s_add_u32 s76, s42, 0x4000
	s_addc_u32 s77, s43, 0
	s_add_i32 s70, s73, s48
	global_load_lds_dwordx4 v132, s[42:43]
	s_mov_b32 m0, s70
	s_nop 0
	global_load_lds_dwordx4 v130, s[76:77]
	s_add_i32 m0, s70, 0x2000
	s_nop 0
	global_load_lds_dwordx4 v132, s[76:77]
	s_mov_b32 m0, s49
	s_nop 0
	global_load_lds_dwordx4 v130, s[44:45]
	s_mov_b32 m0, s50
	s_nop 0
	global_load_lds_dwordx4 v132, s[44:45]
	s_waitcnt vmcnt(8)
	s_barrier
; #define PG8_STAGE(bufoff, gbase, voff) do { _Pragma("unroll") for (int _i = 0; _i < 2; ++_i) \
;         __builtin_amdgcn_global_load_lds((const unsigned*)((const char*)(gbase) + (voff)[_i]), (LAS unsigned*)(lds + (bufoff) + ldsw + _i * 8192), 16, 0, 0); } while (0)
; #define PG8_LDA(dst, b, h) do { _Pragma("unroll") for (int m = 0; m < 4; ++m) _Pragma("unroll") for (int k = 0; k < 2; ++k) dst[m][k] = *(const LAS bf16x8*)(lds + PG8_SA(b, h) + aoff + m * 2048 + k * 1024); } while (0)
; #define PG8_LDB(dst, b, h) do { _Pragma("unroll") for (int n = 0; n < 2; ++n) _Pragma("unroll") for (int k = 0; k < 2; ++k) dst[n][k] = *(const LAS bf16x8*)(lds + PG8_SB(b, h) + boff + n * 2048 + k * 1024); } while (0)
; #define PG8_MMA(ai, bj, At, Bt) do { __builtin_amdgcn_s_setprio(1); _Pragma("unroll") for (int m = 0; m < 4; ++m) _Pragma("unroll") for (int n = 0; n < 2; ++n) _Pragma("unroll") for (int k = 0; k < 2; ++k) \
;         acc[ai][bj][m][n] = __builtin_amdgcn_mfma_f32_16x16x32_bf16(Bt[n][k], At[m][k], acc[ai][bj][m][n], 0, 0, 0); __builtin_amdgcn_s_setprio(0); } while (0)
; #define PG8_WAIT_V(n) asm volatile("s_waitcnt vmcnt(" #n ")" ::: "memory")
; #define PG8_WAIT_L(n) asm volatile("s_waitcnt lgkmcnt(" #n ")" ::: "memory")
; #define PG8_BAR __builtin_amdgcn_s_barrier()
; #define PG8_SCHED __builtin_amdgcn_sched_barrier(0)
; template <class Epi, class Sched, bool ABLK = false, bool ALIGN_EPI = true, bool SP2 = true, bool BBLK = true>
; __device__ __forceinline__ void gemm_phase(LAS unsigned char* lds, const Gemm g, const Sched& S, const Epi& E) {
;     ...
;             PG8_WAIT_V(8); PG8_WAIT_L(0); PG8_BAR; PG8_MMA(1, 0, At, B0); PG8_MMA(1, 1, At, B1); PG8_BAR; PG8_SCHED;
;             PG8_LDB(B0, 1, 0); PG8_LDB(B1, 1, 1); PG8_SCHED; PG8_LDA(At, 1, 0); PG8_STAGE(PG8_SA(0, 1), a2 + hstepA, voffA);
;             PG8_WAIT_V(8); PG8_WAIT_L(0); PG8_BAR; PG8_MMA(0, 0, At, B0); PG8_MMA(0, 1, At, B1); PG8_BAR; PG8_SCHED;
	s_waitcnt lgkmcnt(0)
	v_mfma_f32_16x16x32_bf16 v[62:65], v[152:155], v[184:187], 0
	v_mfma_f32_16x16x32_bf16 v[58:61], v[160:163], v[184:187], 0
	v_mfma_f32_16x16x32_bf16 v[46:49], v[152:155], v[192:195], 0
	v_mfma_f32_16x16x32_bf16 v[42:45], v[160:163], v[192:195], 0
	v_mfma_f32_16x16x32_bf16 v[30:33], v[152:155], v[200:203], 0
	v_mfma_f32_16x16x32_bf16 v[26:29], v[160:163], v[200:203], 0
	v_mfma_f32_16x16x32_bf16 v[14:17], v[152:155], v[208:211], 0
	v_mfma_f32_16x16x32_bf16 v[10:13], v[160:163], v[208:211], 0
	v_mfma_f32_16x16x32_bf16 v[62:65], v[156:159], v[188:191], v[62:65]
	v_mfma_f32_16x16x32_bf16 v[58:61], v[164:167], v[188:191], v[58:61]
	v_mfma_f32_16x16x32_bf16 v[46:49], v[156:159], v[196:199], v[46:49]
	v_mfma_f32_16x16x32_bf16 v[42:45], v[164:167], v[196:199], v[42:45]
	v_mfma_f32_16x16x32_bf16 v[30:33], v[156:159], v[204:207], v[30:33]
	v_mfma_f32_16x16x32_bf16 v[26:29], v[164:167], v[204:207], v[26:29]
	v_mfma_f32_16x16x32_bf16 v[14:17], v[156:159], v[212:215], v[14:17]
	v_mfma_f32_16x16x32_bf16 v[10:13], v[164:167], v[212:215], v[10:13]
	v_mfma_f32_16x16x32_bf16 v[54:57], v[168:171], v[184:187], 0
	v_mfma_f32_16x16x32_bf16 v[50:53], v[176:179], v[184:187], 0
	v_mfma_f32_16x16x32_bf16 v[38:41], v[168:171], v[192:195], 0
	v_mfma_f32_16x16x32_bf16 v[34:37], v[176:179], v[192:195], 0
	v_mfma_f32_16x16x32_bf16 v[22:25], v[168:171], v[200:203], 0
	v_mfma_f32_16x16x32_bf16 v[18:21], v[176:179], v[200:203], 0
	v_mfma_f32_16x16x32_bf16 v[6:9], v[168:171], v[208:211], 0
	v_mfma_f32_16x16x32_bf16 v[2:5], v[176:179], v[208:211], 0
	v_mfma_f32_16x16x32_bf16 v[54:57], v[172:175], v[188:191], v[54:57]
	v_mfma_f32_16x16x32_bf16 v[50:53], v[180:183], v[188:191], v[50:53]
	v_mfma_f32_16x16x32_bf16 v[38:41], v[172:175], v[196:199], v[38:41]
	v_mfma_f32_16x16x32_bf16 v[34:37], v[180:183], v[196:199], v[34:37]
	v_mfma_f32_16x16x32_bf16 v[22:25], v[172:175], v[204:207], v[22:25]
	v_mfma_f32_16x16x32_bf16 v[18:21], v[180:183], v[204:207], v[18:21]
	v_mfma_f32_16x16x32_bf16 v[6:9], v[172:175], v[212:215], v[6:9]
	v_mfma_f32_16x16x32_bf16 v[2:5], v[180:183], v[212:215], v[2:5]
	s_barrier
	v_add_u32_e32 v151, s60, v146
	ds_read_b128 v[152:155], v151
	ds_read_b128 v[156:159], v151 offset:1024
	ds_read_b128 v[160:163], v151 offset:2048
	ds_read_b128 v[164:167], v151 offset:3072
	v_add_u32_e32 v151, s61, v146
	ds_read_b128 v[168:171], v151
	ds_read_b128 v[172:175], v151 offset:1024
	ds_read_b128 v[176:179], v151 offset:2048
	ds_read_b128 v[180:183], v151 offset:3072
	s_add_u32 s44, s44, 0x4000
	s_addc_u32 s45, s45, 0
	s_mov_b32 m0, s51
	ds_read_b128 v[184:187], v150 offset:32768
	ds_read_b128 v[188:191], v150 offset:33792
	ds_read_b128 v[192:195], v150 offset:34816
	ds_read_b128 v[196:199], v150 offset:35840
	ds_read_b128 v[200:203], v150 offset:36864
	ds_read_b128 v[204:207], v150 offset:37888
	ds_read_b128 v[208:211], v150 offset:38912
	ds_read_b128 v[212:215], v150 offset:39936
	global_load_lds_dwordx4 v130, s[44:45]
	s_mov_b32 m0, s52
	s_nop 0
	global_load_lds_dwordx4 v132, s[44:45]
	s_waitcnt vmcnt(8)
	s_barrier
	s_waitcnt lgkmcnt(0)
	v_mfma_f32_16x16x32_bf16 v[126:129], v[152:155], v[184:187], v[126:129]
	v_mfma_f32_16x16x32_bf16 v[122:125], v[160:163], v[184:187], v[122:125]
	v_mfma_f32_16x16x32_bf16 v[110:113], v[152:155], v[192:195], v[110:113]
	v_mfma_f32_16x16x32_bf16 v[106:109], v[160:163], v[192:195], v[106:109]
	v_mfma_f32_16x16x32_bf16 v[94:97], v[152:155], v[200:203], v[94:97]
	v_mfma_f32_16x16x32_bf16 v[90:93], v[160:163], v[200:203], v[90:93]
	v_mfma_f32_16x16x32_bf16 v[78:81], v[152:155], v[208:211], v[78:81]
	v_mfma_f32_16x16x32_bf16 v[74:77], v[160:163], v[208:211], v[74:77]
	v_mfma_f32_16x16x32_bf16 v[126:129], v[156:159], v[188:191], v[126:129]
	v_mfma_f32_16x16x32_bf16 v[122:125], v[164:167], v[188:191], v[122:125]
	v_mfma_f32_16x16x32_bf16 v[110:113], v[156:159], v[196:199], v[110:113]
	v_mfma_f32_16x16x32_bf16 v[106:109], v[164:167], v[196:199], v[106:109]
	v_mfma_f32_16x16x32_bf16 v[94:97], v[156:159], v[204:207], v[94:97]
	v_mfma_f32_16x16x32_bf16 v[90:93], v[164:167], v[204:207], v[90:93]
	v_mfma_f32_16x16x32_bf16 v[78:81], v[156:159], v[212:215], v[78:81]
	v_mfma_f32_16x16x32_bf16 v[74:77], v[164:167], v[212:215], v[74:77]
	v_mfma_f32_16x16x32_bf16 v[118:121], v[168:171], v[184:187], v[118:121]
	v_mfma_f32_16x16x32_bf16 v[114:117], v[176:179], v[184:187], v[114:117]
	v_mfma_f32_16x16x32_bf16 v[102:105], v[168:171], v[192:195], v[102:105]
	v_mfma_f32_16x16x32_bf16 v[98:101], v[176:179], v[192:195], v[98:101]
	v_mfma_f32_16x16x32_bf16 v[86:89], v[168:171], v[200:203], v[86:89]
	v_mfma_f32_16x16x32_bf16 v[82:85], v[176:179], v[200:203], v[82:85]
	v_mfma_f32_16x16x32_bf16 v[70:73], v[168:171], v[208:211], v[70:73]
	v_mfma_f32_16x16x32_bf16 v[66:69], v[176:179], v[208:211], v[66:69]
	v_mfma_f32_16x16x32_bf16 v[118:121], v[172:175], v[188:191], v[118:121]
	v_mfma_f32_16x16x32_bf16 v[114:117], v[180:183], v[188:191], v[114:117]
	v_mfma_f32_16x16x32_bf16 v[102:105], v[172:175], v[196:199], v[102:105]
	v_mfma_f32_16x16x32_bf16 v[98:101], v[180:183], v[196:199], v[98:101]
	v_mfma_f32_16x16x32_bf16 v[86:89], v[172:175], v[204:207], v[86:89]
	v_mfma_f32_16x16x32_bf16 v[82:85], v[180:183], v[204:207], v[82:85]
	v_mfma_f32_16x16x32_bf16 v[70:73], v[172:175], v[212:215], v[70:73]
	v_mfma_f32_16x16x32_bf16 v[66:69], v[180:183], v[212:215], v[66:69]
	s_barrier
; #define PG8_STAGE(bufoff, gbase, voff) do { _Pragma("unroll") for (int _i = 0; _i < 2; ++_i) \
;         __builtin_amdgcn_global_load_lds((const unsigned*)((const char*)(gbase) + (voff)[_i]), (LAS unsigned*)(lds + (bufoff) + ldsw + _i * 8192), 16, 0, 0); } while (0)
; #define PG8_LDA(dst, b, h) do { _Pragma("unroll") for (int m = 0; m < 4; ++m) _Pragma("unroll") for (int k = 0; k < 2; ++k) dst[m][k] = *(const LAS bf16x8*)(lds + PG8_SA(b, h) + aoff + m * 2048 + k * 1024); } while (0)
; #define PG8_LDB(dst, b, h) do { _Pragma("unroll") for (int n = 0; n < 2; ++n) _Pragma("unroll") for (int k = 0; k < 2; ++k) dst[n][k] = *(const LAS bf16x8*)(lds + PG8_SB(b, h) + boff + n * 2048 + k * 1024); } while (0)
; #define PG8_WAIT_V(n) asm volatile("s_waitcnt vmcnt(" #n ")" ::: "memory")
; #define PG8_WAIT_L(n) asm volatile("s_waitcnt lgkmcnt(" #n ")" ::: "memory")
; #define PG8_BAR __builtin_amdgcn_s_barrier()
; #define PG8_SCHED __builtin_amdgcn_sched_barrier(0)
; template <class Epi, class Sched, bool ABLK = false, bool ALIGN_EPI = true, bool SP2 = true, bool BBLK = true>
; __device__ __forceinline__ void gemm_phase(LAS unsigned char* lds, const Gemm g, const Sched& S, const Epi& E) {
;     ...
;         for (int t = 0; t < nt; t += 2) {
;             const bool last = (t == nt - 2);
;             const char* a1 = a_tile(uA, tbA + t + 1);
;             const char* a2 = last ? a_tile(nuA, ntbA) : a_tile(uA, tbA + t + 2); const char* b2 = last ? nB : cB + (size_t)(t + 2) * kstepB;
;             const char* a3 = last ? a_tile(nuA, ntbA + 1) : a_tile(uA, tbA + t + 3); const char* b3 = b2 + kstepB;
;             if (last && has_next) S.a_ready(nxt);
;             if constexpr (SP2) {
;             PG8_LDB(B0, 0, 0); PG8_LDB(B1, 0, 1); PG8_SCHED; PG8_LDA(At, 0, 0); PG8_STAGE(PG8_SA(1, 1), a1 + hstepA, voffA);
;             PG8_WAIT_V(8); PG8_WAIT_L(0); PG8_BAR; PG8_MMA(0, 0, At, B0); PG8_MMA(0, 1, At, B1); PG8_BAR; PG8_SCHED;
;     ...
;             PG8_WAIT_V(8); PG8_WAIT_L(0); PG8_BAR; PG8_MMA(0, 0, At, B0); PG8_MMA(0, 1, At, B1); PG8_BAR; PG8_SCHED;
;             PG8_LDA(At, 1, 1); PG8_STAGE(PG8_SB(1, 0), b3, voffB); PG8_STAGE(PG8_SB(1, 1), b3 + hstepB, voffB); PG8_STAGE(PG8_SA(1, 0), a3, voffA);
;             PG8_WAIT_V(8); PG8_WAIT_L(0); PG8_BAR; PG8_MMA(1, 0, At, B0); PG8_MMA(1, 1, At, B1); PG8_BAR; PG8_SCHED;
	s_add_u32 s44, s42, 0x8000
	s_addc_u32 s45, s43, 0
	s_add_i32 s70, s60, s48
	s_mov_b32 m0, s70
	ds_read_b128 v[184:187], v150 offset:49152
	ds_read_b128 v[188:191], v150 offset:50176
	ds_read_b128 v[192:195], v150 offset:51200
	ds_read_b128 v[196:199], v150 offset:52224
	ds_read_b128 v[200:203], v150 offset:53248
	ds_read_b128 v[204:207], v150 offset:54272
	ds_read_b128 v[208:211], v150 offset:55296
	ds_read_b128 v[212:215], v150 offset:56320
	global_load_lds_dwordx4 v130, s[44:45]
	s_add_i32 m0, s70, 0x2000
	s_add_u32 s42, s42, 0xc000
	v_lshl_add_u64 v[216:217], s[44:45], 0, v[132:133]
	s_addc_u32 s43, s43, 0
	s_add_i32 s44, s61, s48
	global_load_lds_dwordx4 v[216:217], off
	s_mov_b32 m0, s44
	s_nop 0
	global_load_lds_dwordx4 v130, s[42:43]
	s_add_i32 m0, s44, 0x2000
	s_nop 0
	global_load_lds_dwordx4 v132, s[42:43]
	s_mov_b32 m0, s53
	s_nop 0
	global_load_lds_dwordx4 v130, s[40:41]
	s_mov_b32 m0, s54
	s_nop 0
	global_load_lds_dwordx4 v132, s[40:41]
	s_waitcnt vmcnt(8)
	s_barrier
	s_waitcnt lgkmcnt(0)
	v_mfma_f32_16x16x32_bf16 v[62:65], v[152:155], v[184:187], v[62:65]
	v_mfma_f32_16x16x32_bf16 v[58:61], v[160:163], v[184:187], v[58:61]
	v_mfma_f32_16x16x32_bf16 v[46:49], v[152:155], v[192:195], v[46:49]
	v_mfma_f32_16x16x32_bf16 v[42:45], v[160:163], v[192:195], v[42:45]
	v_mfma_f32_16x16x32_bf16 v[30:33], v[152:155], v[200:203], v[30:33]
	v_mfma_f32_16x16x32_bf16 v[26:29], v[160:163], v[200:203], v[26:29]
	v_mfma_f32_16x16x32_bf16 v[14:17], v[152:155], v[208:211], v[14:17]
	v_mfma_f32_16x16x32_bf16 v[10:13], v[160:163], v[208:211], v[10:13]
	v_mfma_f32_16x16x32_bf16 v[62:65], v[156:159], v[188:191], v[62:65]
	v_mfma_f32_16x16x32_bf16 v[58:61], v[164:167], v[188:191], v[58:61]
	v_mfma_f32_16x16x32_bf16 v[46:49], v[156:159], v[196:199], v[46:49]
	v_mfma_f32_16x16x32_bf16 v[42:45], v[164:167], v[196:199], v[42:45]
	v_mfma_f32_16x16x32_bf16 v[30:33], v[156:159], v[204:207], v[30:33]
	v_mfma_f32_16x16x32_bf16 v[26:29], v[164:167], v[204:207], v[26:29]
	v_mfma_f32_16x16x32_bf16 v[14:17], v[156:159], v[212:215], v[14:17]
	v_mfma_f32_16x16x32_bf16 v[10:13], v[164:167], v[212:215], v[10:13]
	v_mfma_f32_16x16x32_bf16 v[54:57], v[168:171], v[184:187], v[54:57]
	v_mfma_f32_16x16x32_bf16 v[50:53], v[176:179], v[184:187], v[50:53]
	v_mfma_f32_16x16x32_bf16 v[38:41], v[168:171], v[192:195], v[38:41]
	v_mfma_f32_16x16x32_bf16 v[34:37], v[176:179], v[192:195], v[34:37]
	v_mfma_f32_16x16x32_bf16 v[22:25], v[168:171], v[200:203], v[22:25]
	v_mfma_f32_16x16x32_bf16 v[18:21], v[176:179], v[200:203], v[18:21]
	v_mfma_f32_16x16x32_bf16 v[6:9], v[168:171], v[208:211], v[6:9]
	v_mfma_f32_16x16x32_bf16 v[2:5], v[176:179], v[208:211], v[2:5]
	v_mfma_f32_16x16x32_bf16 v[54:57], v[172:175], v[188:191], v[54:57]
	v_mfma_f32_16x16x32_bf16 v[50:53], v[180:183], v[188:191], v[50:53]
	v_mfma_f32_16x16x32_bf16 v[38:41], v[172:175], v[196:199], v[38:41]
	v_mfma_f32_16x16x32_bf16 v[34:37], v[180:183], v[196:199], v[34:37]
	v_mfma_f32_16x16x32_bf16 v[22:25], v[172:175], v[204:207], v[22:25]
	v_mfma_f32_16x16x32_bf16 v[18:21], v[180:183], v[204:207], v[18:21]
	v_mfma_f32_16x16x32_bf16 v[6:9], v[172:175], v[212:215], v[6:9]
	v_mfma_f32_16x16x32_bf16 v[2:5], v[180:183], v[212:215], v[2:5]
	s_barrier
	s_add_u32 s38, s38, 0x10000
	s_addc_u32 s39, s39, 0
	s_cmp_ge_u32 s67, s56
.LBB0_2328:
	ds_read_b128 v[152:155], v148
	ds_read_b128 v[156:159], v148 offset:1024
	ds_read_b128 v[160:163], v148 offset:2048
	ds_read_b128 v[164:167], v148 offset:3072
	ds_read_b128 v[168:171], v149
	ds_read_b128 v[172:175], v149 offset:1024
	ds_read_b128 v[176:179], v149 offset:2048
	ds_read_b128 v[180:183], v149 offset:3072
	s_add_u32 s40, s64, s38
	s_addc_u32 s41, s65, s39
	s_add_u32 s44, s40, 0x10000
	s_addc_u32 s45, s41, 0
	s_add_i32 s67, s67, 2
	s_add_u32 s42, s62, s38
	s_addc_u32 s43, s63, s39
	s_add_u32 s40, s40, 0x18000
	s_addc_u32 s41, s41, 0
	s_cmp_eq_u32 s66, s38
	s_cselect_b32 s41, s59, s41
	s_cselect_b32 s40, s58, s40
	s_cselect_b32 s43, s4, s43
	s_cselect_b32 s42, s5, s42
	s_cselect_b32 s45, s57, s45
	s_cselect_b32 s44, s35, s44
	v_lshl_add_u64 v[216:217], v[142:143], 0, s[38:39]
	s_add_i32 m0, s49, 0xc000
	ds_read_b128 v[184:187], v150
	ds_read_b128 v[188:191], v150 offset:1024
	ds_read_b128 v[192:195], v150 offset:2048
	ds_read_b128 v[196:199], v150 offset:3072
	ds_read_b128 v[200:203], v150 offset:4096
	ds_read_b128 v[204:207], v150 offset:5120
	ds_read_b128 v[208:211], v150 offset:6144
	ds_read_b128 v[212:215], v150 offset:7168
	global_load_lds_dwordx4 v[216:217], off
	v_lshl_add_u64 v[216:217], v[144:145], 0, s[38:39]
	s_add_i32 m0, s49, 0xe000
	s_nop 0
	global_load_lds_dwordx4 v[216:217], off
	s_waitcnt vmcnt(8)
	s_barrier
; #define PG8_STAGE(bufoff, gbase, voff) do { _Pragma("unroll") for (int _i = 0; _i < 2; ++_i) \
;         __builtin_amdgcn_global_load_lds((const unsigned*)((const char*)(gbase) + (voff)[_i]), (LAS unsigned*)(lds + (bufoff) + ldsw + _i * 8192), 16, 0, 0); } while (0)
; #define PG8_LDA(dst, b, h) do { _Pragma("unroll") for (int m = 0; m < 4; ++m) _Pragma("unroll") for (int k = 0; k < 2; ++k) dst[m][k] = *(const LAS bf16x8*)(lds + PG8_SA(b, h) + aoff + m * 2048 + k * 1024); } while (0)
; #define PG8_MMA(ai, bj, At, Bt) do { __builtin_amdgcn_s_setprio(1); _Pragma("unroll") for (int m = 0; m < 4; ++m) _Pragma("unroll") for (int n = 0; n < 2; ++n) _Pragma("unroll") for (int k = 0; k < 2; ++k) \
;         acc[ai][bj][m][n] = __builtin_amdgcn_mfma_f32_16x16x32_bf16(Bt[n][k], At[m][k], acc[ai][bj][m][n], 0, 0, 0); __builtin_amdgcn_s_setprio(0); } while (0)
; #define PG8_WAIT_V(n) asm volatile("s_waitcnt vmcnt(" #n ")" ::: "memory")
; #define PG8_WAIT_L(n) asm volatile("s_waitcnt lgkmcnt(" #n ")" ::: "memory")
; #define PG8_BAR __builtin_amdgcn_s_barrier()
; #define PG8_SCHED __builtin_amdgcn_sched_barrier(0)
; template <class Epi, class Sched, bool ABLK = false, bool ALIGN_EPI = true, bool SP2 = true, bool BBLK = true>
; __device__ __forceinline__ void gemm_phase(LAS unsigned char* lds, const Gemm g, const Sched& S, const Epi& E) {
;     ...
;             PG8_WAIT_V(8); PG8_WAIT_L(0); PG8_BAR; PG8_MMA(0, 0, At, B0); PG8_MMA(0, 1, At, B1); PG8_BAR; PG8_SCHED;
;             PG8_LDA(At, 0, 1); PG8_STAGE(PG8_SB(0, 0), b2, voffB); PG8_STAGE(PG8_SB(0, 1), b2 + hstepB, voffB); PG8_STAGE(PG8_SA(0, 0), a2, voffA);
;             PG8_WAIT_V(8); PG8_WAIT_L(0); PG8_BAR; PG8_MMA(1, 0, At, B0); PG8_MMA(1, 1, At, B1); PG8_BAR; PG8_SCHED;
	s_waitcnt lgkmcnt(0)
	v_mfma_f32_16x16x32_bf16 v[126:129], v[152:155], v[184:187], v[126:129]
	v_mfma_f32_16x16x32_bf16 v[122:125], v[160:163], v[184:187], v[122:125]
	v_mfma_f32_16x16x32_bf16 v[110:113], v[152:155], v[192:195], v[110:113]
	v_mfma_f32_16x16x32_bf16 v[106:109], v[160:163], v[192:195], v[106:109]
	v_mfma_f32_16x16x32_bf16 v[94:97], v[152:155], v[200:203], v[94:97]
	v_mfma_f32_16x16x32_bf16 v[90:93], v[160:163], v[200:203], v[90:93]
	v_mfma_f32_16x16x32_bf16 v[78:81], v[152:155], v[208:211], v[78:81]
	v_mfma_f32_16x16x32_bf16 v[74:77], v[160:163], v[208:211], v[74:77]
	v_mfma_f32_16x16x32_bf16 v[126:129], v[156:159], v[188:191], v[126:129]
	v_mfma_f32_16x16x32_bf16 v[122:125], v[164:167], v[188:191], v[122:125]
	v_mfma_f32_16x16x32_bf16 v[110:113], v[156:159], v[196:199], v[110:113]
	v_mfma_f32_16x16x32_bf16 v[106:109], v[164:167], v[196:199], v[106:109]
	v_mfma_f32_16x16x32_bf16 v[94:97], v[156:159], v[204:207], v[94:97]
	v_mfma_f32_16x16x32_bf16 v[90:93], v[164:167], v[204:207], v[90:93]
	v_mfma_f32_16x16x32_bf16 v[78:81], v[156:159], v[212:215], v[78:81]
	v_mfma_f32_16x16x32_bf16 v[74:77], v[164:167], v[212:215], v[74:77]
	v_mfma_f32_16x16x32_bf16 v[118:121], v[168:171], v[184:187], v[118:121]
	v_mfma_f32_16x16x32_bf16 v[114:117], v[176:179], v[184:187], v[114:117]
	v_mfma_f32_16x16x32_bf16 v[102:105], v[168:171], v[192:195], v[102:105]
	v_mfma_f32_16x16x32_bf16 v[98:101], v[176:179], v[192:195], v[98:101]
	v_mfma_f32_16x16x32_bf16 v[86:89], v[168:171], v[200:203], v[86:89]
	v_mfma_f32_16x16x32_bf16 v[82:85], v[176:179], v[200:203], v[82:85]
	v_mfma_f32_16x16x32_bf16 v[70:73], v[168:171], v[208:211], v[70:73]
	v_mfma_f32_16x16x32_bf16 v[66:69], v[176:179], v[208:211], v[66:69]
	v_mfma_f32_16x16x32_bf16 v[118:121], v[172:175], v[188:191], v[118:121]
	v_mfma_f32_16x16x32_bf16 v[114:117], v[180:183], v[188:191], v[114:117]
	v_mfma_f32_16x16x32_bf16 v[102:105], v[172:175], v[196:199], v[102:105]
	v_mfma_f32_16x16x32_bf16 v[98:101], v[180:183], v[196:199], v[98:101]
	v_mfma_f32_16x16x32_bf16 v[86:89], v[172:175], v[204:207], v[86:89]
	v_mfma_f32_16x16x32_bf16 v[82:85], v[180:183], v[204:207], v[82:85]
	v_mfma_f32_16x16x32_bf16 v[70:73], v[172:175], v[212:215], v[70:73]
	v_mfma_f32_16x16x32_bf16 v[66:69], v[180:183], v[212:215], v[66:69]
	s_barrier
	s_add_i32 s70, s72, s48
	s_mov_b32 m0, s70
	ds_read_b128 v[184:187], v150 offset:16384
	ds_read_b128 v[188:191], v150 offset:17408
	ds_read_b128 v[192:195], v150 offset:18432
	ds_read_b128 v[196:199], v150 offset:19456
	ds_read_b128 v[200:203], v150 offset:20480
	ds_read_b128 v[204:207], v150 offset:21504
	ds_read_b128 v[208:211], v150 offset:22528
	ds_read_b128 v[212:215], v150 offset:23552
	global_load_lds_dwordx4 v130, s[42:43]
	s_add_i32 m0, s70, 0x2000
	s_add_u32 s76, s42, 0x4000
	s_addc_u32 s77, s43, 0
	s_add_i32 s70, s73, s48
	global_load_lds_dwordx4 v132, s[42:43]
	s_mov_b32 m0, s70
	s_nop 0
	global_load_lds_dwordx4 v130, s[76:77]
	s_add_i32 m0, s70, 0x2000
	s_nop 0
	global_load_lds_dwordx4 v132, s[76:77]
	s_mov_b32 m0, s49
	s_nop 0
	global_load_lds_dwordx4 v130, s[44:45]
	s_mov_b32 m0, s50
	s_nop 0
	global_load_lds_dwordx4 v132, s[44:45]
	s_waitcnt vmcnt(8)
	s_barrier
	s_waitcnt lgkmcnt(0)
	v_mfma_f32_16x16x32_bf16 v[62:65], v[152:155], v[184:187], v[62:65]
	v_mfma_f32_16x16x32_bf16 v[58:61], v[160:163], v[184:187], v[58:61]
	v_mfma_f32_16x16x32_bf16 v[46:49], v[152:155], v[192:195], v[46:49]
	v_mfma_f32_16x16x32_bf16 v[42:45], v[160:163], v[192:195], v[42:45]
	v_mfma_f32_16x16x32_bf16 v[30:33], v[152:155], v[200:203], v[30:33]
	v_mfma_f32_16x16x32_bf16 v[26:29], v[160:163], v[200:203], v[26:29]
	v_mfma_f32_16x16x32_bf16 v[14:17], v[152:155], v[208:211], v[14:17]
	v_mfma_f32_16x16x32_bf16 v[10:13], v[160:163], v[208:211], v[10:13]
	v_mfma_f32_16x16x32_bf16 v[62:65], v[156:159], v[188:191], v[62:65]
	v_mfma_f32_16x16x32_bf16 v[58:61], v[164:167], v[188:191], v[58:61]
	v_mfma_f32_16x16x32_bf16 v[46:49], v[156:159], v[196:199], v[46:49]
	v_mfma_f32_16x16x32_bf16 v[42:45], v[164:167], v[196:199], v[42:45]
	v_mfma_f32_16x16x32_bf16 v[30:33], v[156:159], v[204:207], v[30:33]
	v_mfma_f32_16x16x32_bf16 v[26:29], v[164:167], v[204:207], v[26:29]
	v_mfma_f32_16x16x32_bf16 v[14:17], v[156:159], v[212:215], v[14:17]
	v_mfma_f32_16x16x32_bf16 v[10:13], v[164:167], v[212:215], v[10:13]
	v_mfma_f32_16x16x32_bf16 v[54:57], v[168:171], v[184:187], v[54:57]
	v_mfma_f32_16x16x32_bf16 v[50:53], v[176:179], v[184:187], v[50:53]
	v_mfma_f32_16x16x32_bf16 v[38:41], v[168:171], v[192:195], v[38:41]
	v_mfma_f32_16x16x32_bf16 v[34:37], v[176:179], v[192:195], v[34:37]
	v_mfma_f32_16x16x32_bf16 v[22:25], v[168:171], v[200:203], v[22:25]
	v_mfma_f32_16x16x32_bf16 v[18:21], v[176:179], v[200:203], v[18:21]
	v_mfma_f32_16x16x32_bf16 v[6:9], v[168:171], v[208:211], v[6:9]
	v_mfma_f32_16x16x32_bf16 v[2:5], v[176:179], v[208:211], v[2:5]
	v_mfma_f32_16x16x32_bf16 v[54:57], v[172:175], v[188:191], v[54:57]
	v_mfma_f32_16x16x32_bf16 v[50:53], v[180:183], v[188:191], v[50:53]
	v_mfma_f32_16x16x32_bf16 v[38:41], v[172:175], v[196:199], v[38:41]
	v_mfma_f32_16x16x32_bf16 v[34:37], v[180:183], v[196:199], v[34:37]
	v_mfma_f32_16x16x32_bf16 v[22:25], v[172:175], v[204:207], v[22:25]
	v_mfma_f32_16x16x32_bf16 v[18:21], v[180:183], v[204:207], v[18:21]
	v_mfma_f32_16x16x32_bf16 v[6:9], v[172:175], v[212:215], v[6:9]
	v_mfma_f32_16x16x32_bf16 v[2:5], v[180:183], v[212:215], v[2:5]
	s_barrier
; #define PG8_STAGE(bufoff, gbase, voff) do { _Pragma("unroll") for (int _i = 0; _i < 2; ++_i) \
;         __builtin_amdgcn_global_load_lds((const unsigned*)((const char*)(gbase) + (voff)[_i]), (LAS unsigned*)(lds + (bufoff) + ldsw + _i * 8192), 16, 0, 0); } while (0)
; #define PG8_LDA(dst, b, h) do { _Pragma("unroll") for (int m = 0; m < 4; ++m) _Pragma("unroll") for (int k = 0; k < 2; ++k) dst[m][k] = *(const LAS bf16x8*)(lds + PG8_SA(b, h) + aoff + m * 2048 + k * 1024); } while (0)
; #define PG8_LDB(dst, b, h) do { _Pragma("unroll") for (int n = 0; n < 2; ++n) _Pragma("unroll") for (int k = 0; k < 2; ++k) dst[n][k] = *(const LAS bf16x8*)(lds + PG8_SB(b, h) + boff + n * 2048 + k * 1024); } while (0)
; #define PG8_MMA(ai, bj, At, Bt) do { __builtin_amdgcn_s_setprio(1); _Pragma("unroll") for (int m = 0; m < 4; ++m) _Pragma("unroll") for (int n = 0; n < 2; ++n) _Pragma("unroll") for (int k = 0; k < 2; ++k) \
;         acc[ai][bj][m][n] = __builtin_amdgcn_mfma_f32_16x16x32_bf16(Bt[n][k], At[m][k], acc[ai][bj][m][n], 0, 0, 0); __builtin_amdgcn_s_setprio(0); } while (0)
; #define PG8_WAIT_V(n) asm volatile("s_waitcnt vmcnt(" #n ")" ::: "memory")
; #define PG8_WAIT_L(n) asm volatile("s_waitcnt lgkmcnt(" #n ")" ::: "memory")
; #define PG8_BAR __builtin_amdgcn_s_barrier()
; #define PG8_SCHED __builtin_amdgcn_sched_barrier(0)
; template <class Epi, class Sched, bool ABLK = false, bool ALIGN_EPI = true, bool SP2 = true, bool BBLK = true>
; __device__ __forceinline__ void gemm_phase(LAS unsigned char* lds, const Gemm g, const Sched& S, const Epi& E) {
;     ...
;             PG8_LDB(B0, 1, 0); PG8_LDB(B1, 1, 1); PG8_SCHED; PG8_LDA(At, 1, 0); PG8_STAGE(PG8_SA(0, 1), a2 + hstepA, voffA);
;             PG8_WAIT_V(8); PG8_WAIT_L(0); PG8_BAR; PG8_MMA(0, 0, At, B0); PG8_MMA(0, 1, At, B1); PG8_BAR; PG8_SCHED;
;             PG8_LDA(At, 1, 1); PG8_STAGE(PG8_SB(1, 0), b3, voffB); PG8_STAGE(PG8_SB(1, 1), b3 + hstepB, voffB); PG8_STAGE(PG8_SA(1, 0), a3, voffA);
;             PG8_WAIT_V(8); PG8_WAIT_L(0); PG8_BAR; PG8_MMA(1, 0, At, B0); PG8_MMA(1, 1, At, B1); PG8_BAR; PG8_SCHED;
;     ...
;         if constexpr (ALIGN_EPI) { if (wr == 0) PG8_BAR; }
	v_add_u32_e32 v151, s60, v146
	ds_read_b128 v[152:155], v151
	ds_read_b128 v[156:159], v151 offset:1024
	ds_read_b128 v[160:163], v151 offset:2048
	ds_read_b128 v[164:167], v151 offset:3072
	v_add_u32_e32 v151, s61, v146
	ds_read_b128 v[168:171], v151
	ds_read_b128 v[172:175], v151 offset:1024
	ds_read_b128 v[176:179], v151 offset:2048
	ds_read_b128 v[180:183], v151 offset:3072
	s_add_u32 s44, s44, 0x4000
	s_addc_u32 s45, s45, 0
	s_mov_b32 m0, s51
	ds_read_b128 v[184:187], v150 offset:32768
	ds_read_b128 v[188:191], v150 offset:33792
	ds_read_b128 v[192:195], v150 offset:34816
	ds_read_b128 v[196:199], v150 offset:35840
	ds_read_b128 v[200:203], v150 offset:36864
	ds_read_b128 v[204:207], v150 offset:37888
	ds_read_b128 v[208:211], v150 offset:38912
	ds_read_b128 v[212:215], v150 offset:39936
	global_load_lds_dwordx4 v130, s[44:45]
	s_mov_b32 m0, s52
	s_nop 0
	global_load_lds_dwordx4 v132, s[44:45]
	s_waitcnt vmcnt(8)
	s_barrier
	s_waitcnt lgkmcnt(0)
	v_mfma_f32_16x16x32_bf16 v[126:129], v[152:155], v[184:187], v[126:129]
	v_mfma_f32_16x16x32_bf16 v[122:125], v[160:163], v[184:187], v[122:125]
	v_mfma_f32_16x16x32_bf16 v[110:113], v[152:155], v[192:195], v[110:113]
	v_mfma_f32_16x16x32_bf16 v[106:109], v[160:163], v[192:195], v[106:109]
	v_mfma_f32_16x16x32_bf16 v[94:97], v[152:155], v[200:203], v[94:97]
	v_mfma_f32_16x16x32_bf16 v[90:93], v[160:163], v[200:203], v[90:93]
	v_mfma_f32_16x16x32_bf16 v[78:81], v[152:155], v[208:211], v[78:81]
	v_mfma_f32_16x16x32_bf16 v[74:77], v[160:163], v[208:211], v[74:77]
	v_mfma_f32_16x16x32_bf16 v[126:129], v[156:159], v[188:191], v[126:129]
	v_mfma_f32_16x16x32_bf16 v[122:125], v[164:167], v[188:191], v[122:125]
	v_mfma_f32_16x16x32_bf16 v[110:113], v[156:159], v[196:199], v[110:113]
	v_mfma_f32_16x16x32_bf16 v[106:109], v[164:167], v[196:199], v[106:109]
	v_mfma_f32_16x16x32_bf16 v[94:97], v[156:159], v[204:207], v[94:97]
	v_mfma_f32_16x16x32_bf16 v[90:93], v[164:167], v[204:207], v[90:93]
	v_mfma_f32_16x16x32_bf16 v[78:81], v[156:159], v[212:215], v[78:81]
	v_mfma_f32_16x16x32_bf16 v[74:77], v[164:167], v[212:215], v[74:77]
	v_mfma_f32_16x16x32_bf16 v[118:121], v[168:171], v[184:187], v[118:121]
	v_mfma_f32_16x16x32_bf16 v[114:117], v[176:179], v[184:187], v[114:117]
	v_mfma_f32_16x16x32_bf16 v[102:105], v[168:171], v[192:195], v[102:105]
	v_mfma_f32_16x16x32_bf16 v[98:101], v[176:179], v[192:195], v[98:101]
	v_mfma_f32_16x16x32_bf16 v[86:89], v[168:171], v[200:203], v[86:89]
	v_mfma_f32_16x16x32_bf16 v[82:85], v[176:179], v[200:203], v[82:85]
	v_mfma_f32_16x16x32_bf16 v[70:73], v[168:171], v[208:211], v[70:73]
	v_mfma_f32_16x16x32_bf16 v[66:69], v[176:179], v[208:211], v[66:69]
	v_mfma_f32_16x16x32_bf16 v[118:121], v[172:175], v[188:191], v[118:121]
	v_mfma_f32_16x16x32_bf16 v[114:117], v[180:183], v[188:191], v[114:117]
	v_mfma_f32_16x16x32_bf16 v[102:105], v[172:175], v[196:199], v[102:105]
	v_mfma_f32_16x16x32_bf16 v[98:101], v[180:183], v[196:199], v[98:101]
	v_mfma_f32_16x16x32_bf16 v[86:89], v[172:175], v[204:207], v[86:89]
	v_mfma_f32_16x16x32_bf16 v[82:85], v[180:183], v[204:207], v[82:85]
	v_mfma_f32_16x16x32_bf16 v[70:73], v[172:175], v[212:215], v[70:73]
	v_mfma_f32_16x16x32_bf16 v[66:69], v[180:183], v[212:215], v[66:69]
	s_barrier
	s_add_u32 s44, s42, 0x8000
	s_addc_u32 s45, s43, 0
	s_add_i32 s70, s60, s48
	s_mov_b32 m0, s70
	ds_read_b128 v[184:187], v150 offset:49152
	ds_read_b128 v[188:191], v150 offset:50176
	ds_read_b128 v[192:195], v150 offset:51200
	ds_read_b128 v[196:199], v150 offset:52224
	ds_read_b128 v[200:203], v150 offset:53248
	ds_read_b128 v[204:207], v150 offset:54272
	ds_read_b128 v[208:211], v150 offset:55296
	ds_read_b128 v[212:215], v150 offset:56320
	global_load_lds_dwordx4 v130, s[44:45]
	s_add_i32 m0, s70, 0x2000
	s_add_u32 s42, s42, 0xc000
	v_lshl_add_u64 v[216:217], s[44:45], 0, v[132:133]
	s_addc_u32 s43, s43, 0
	s_add_i32 s44, s61, s48
	global_load_lds_dwordx4 v[216:217], off
	s_mov_b32 m0, s44
	s_nop 0
	global_load_lds_dwordx4 v130, s[42:43]
	s_add_i32 m0, s44, 0x2000
	s_nop 0
	global_load_lds_dwordx4 v132, s[42:43]
	s_mov_b32 m0, s53
	s_nop 0
	global_load_lds_dwordx4 v130, s[40:41]
	s_mov_b32 m0, s54
	s_nop 0
	global_load_lds_dwordx4 v132, s[40:41]
	s_waitcnt vmcnt(8)
	s_barrier
	s_waitcnt lgkmcnt(0)
	v_mfma_f32_16x16x32_bf16 v[62:65], v[152:155], v[184:187], v[62:65]
	v_mfma_f32_16x16x32_bf16 v[58:61], v[160:163], v[184:187], v[58:61]
	v_mfma_f32_16x16x32_bf16 v[46:49], v[152:155], v[192:195], v[46:49]
	v_mfma_f32_16x16x32_bf16 v[42:45], v[160:163], v[192:195], v[42:45]
	v_mfma_f32_16x16x32_bf16 v[30:33], v[152:155], v[200:203], v[30:33]
	v_mfma_f32_16x16x32_bf16 v[26:29], v[160:163], v[200:203], v[26:29]
	v_mfma_f32_16x16x32_bf16 v[14:17], v[152:155], v[208:211], v[14:17]
	v_mfma_f32_16x16x32_bf16 v[10:13], v[160:163], v[208:211], v[10:13]
	v_mfma_f32_16x16x32_bf16 v[62:65], v[156:159], v[188:191], v[62:65]
	v_mfma_f32_16x16x32_bf16 v[58:61], v[164:167], v[188:191], v[58:61]
	v_mfma_f32_16x16x32_bf16 v[46:49], v[156:159], v[196:199], v[46:49]
	v_mfma_f32_16x16x32_bf16 v[42:45], v[164:167], v[196:199], v[42:45]
	v_mfma_f32_16x16x32_bf16 v[30:33], v[156:159], v[204:207], v[30:33]
	v_mfma_f32_16x16x32_bf16 v[26:29], v[164:167], v[204:207], v[26:29]
	v_mfma_f32_16x16x32_bf16 v[14:17], v[156:159], v[212:215], v[14:17]
	v_mfma_f32_16x16x32_bf16 v[10:13], v[164:167], v[212:215], v[10:13]
	v_mfma_f32_16x16x32_bf16 v[54:57], v[168:171], v[184:187], v[54:57]
	v_mfma_f32_16x16x32_bf16 v[50:53], v[176:179], v[184:187], v[50:53]
	v_mfma_f32_16x16x32_bf16 v[38:41], v[168:171], v[192:195], v[38:41]
	v_mfma_f32_16x16x32_bf16 v[34:37], v[176:179], v[192:195], v[34:37]
	v_mfma_f32_16x16x32_bf16 v[22:25], v[168:171], v[200:203], v[22:25]
	v_mfma_f32_16x16x32_bf16 v[18:21], v[176:179], v[200:203], v[18:21]
	v_mfma_f32_16x16x32_bf16 v[6:9], v[168:171], v[208:211], v[6:9]
	v_mfma_f32_16x16x32_bf16 v[2:5], v[176:179], v[208:211], v[2:5]
	v_mfma_f32_16x16x32_bf16 v[54:57], v[172:175], v[188:191], v[54:57]
	v_mfma_f32_16x16x32_bf16 v[50:53], v[180:183], v[188:191], v[50:53]
	v_mfma_f32_16x16x32_bf16 v[38:41], v[172:175], v[196:199], v[38:41]
	v_mfma_f32_16x16x32_bf16 v[34:37], v[180:183], v[196:199], v[34:37]
	v_mfma_f32_16x16x32_bf16 v[22:25], v[172:175], v[204:207], v[22:25]
	v_mfma_f32_16x16x32_bf16 v[18:21], v[180:183], v[204:207], v[18:21]
	v_mfma_f32_16x16x32_bf16 v[6:9], v[172:175], v[212:215], v[6:9]
	v_mfma_f32_16x16x32_bf16 v[2:5], v[180:183], v[212:215], v[2:5]
	s_barrier
	s_add_u32 s38, s38, 0x10000
	s_addc_u32 s39, s39, 0
	s_cmp_ge_u32 s67, s56
	s_cbranch_scc0 .LBB0_2328
	s_and_b64 vcc, exec, s[14:15]
	s_cbranch_vccz .LBB0_2331
	s_barrier
